# T1 + mixer: kernel-arg pointers parked in v251 lanes (163 LDS reload round trips become v_readlane), K-norm xor-1/2/4 reductions via DPP adds instead of ds_bpermute
# speedup vs baseline: 1.0125x; 1.0125x over previous
; __device__ __forceinline__ int tid_of(int wv) { return wv * 64 + (int)__builtin_amdgcn_mbcnt_hi(~0u, __builtin_amdgcn_mbcnt_lo(~0u, 0u)); }
; #define LAS __attribute__((address_space(3)))
; #define PIN(i) ((const float*)ldq_(L, (i)))
; #define PREP_CONV(bit, SRC, Kd, Nd, DST, GK, MODE) if (mask & (bit)) { for (int it = gw; it < ((Kd) / 64) * ((Nd) / 64); it += NGW) transpose_item((SRC), (Kd), (Nd), (bf16_t*)(wl + (DST)), (GK), (MODE), scr, it, lane); }
; __device__ __forceinline__ unsigned xb_add(unsigned* p, unsigned v) { return __hip_atomic_fetch_add(p, v, __ATOMIC_RELAXED, __HIP_MEMORY_SCOPE_AGENT); }
; __device__ __forceinline__ unsigned xb_xcc_id() { return (unsigned)__builtin_amdgcn_s_getreg((3 << 11) | 20) & 0xFu; }
; __device__ __forceinline__ void prep(const Params& p, LAS unsigned char* L, int wv, int vb, int nvb, int l, int mask) {
;     int tid_ = tid_of(wv); asm volatile("" : "+v"(tid_));
;     const int tid = tid_, lane = tid & 63, wave = __builtin_amdgcn_readfirstlane(tid >> 6);
;     const int gw = vb * 8 + wave, NGW = nvb * 8; const int gt = vb * 512 + tid, NGT = nvb * 512;
;     LAS float* scr = (LAS float*)(L + wave * 16384);
;     unsigned char* ws = PWS; unsigned char* wl = ws + WS_W + (size_t)l * WL_STRIDE;
;     ...
;     PREP_CONV(PM_FFA_IN, PIN(I_WFFA_IN) + (size_t)l * DM * NFF2, DM, NFF2, WL_FFA_IN, PIN(I_NFFA) + l * DM, 1)
; __device__ __forceinline__ XcdBarrier xcd_barrier_post(unsigned* bar, volatile LAS unsigned* st) {
;     XcdBarrier b; b.bar = bar; b.x = xb_xcc_id(); b.st = st;
;     if (threadIdx.x == 0) (void)xb_add(&bar[XB_XCNT(b.x)], 1u);
.LBB0_8:
	s_or_b64 exec, exec, s[0:1]
	v_mov_b32_e32 v2, 0
	s_waitcnt lgkmcnt(0)
	s_barrier
	v_mbcnt_lo_u32_b32 v251, -1, 0
	v_mbcnt_hi_u32_b32 v251, -1, v251
	v_lshlrev_b32_e32 v251, 2, v251
	v_add_u32_e32 v251, 0x20100, v251
	ds_read_b32 v251, v251
	s_waitcnt lgkmcnt(0)
	s_nop 0
	v_add_u32_e32 v2, 0, v2
	v_add_u32_e32 v2, 0x201c0, v2
	s_nop 0
	s_getreg_b32 s11, hwreg(HW_REG_XCC_ID, 0, 4)
	s_waitcnt lgkmcnt(0)
	v_readlane_b32 s8, v251, 49
	v_readlane_b32 s9, v251, 48
	s_and_saveexec_b64 s[0:1], vcc
	s_cbranch_execz .LBB0_11
	s_mov_b64 s[6:7], exec
	v_mbcnt_lo_u32_b32 v2, s6, 0
	v_mbcnt_hi_u32_b32 v2, s7, v2
	v_cmp_eq_u32_e32 vcc, 0, v2
	s_and_b64 s[12:13], exec, vcc
	s_mov_b64 exec, s[12:13]
	s_cbranch_execz .LBB0_11
	s_lshl_b32 s11, s11, 8
	s_and_b32 s11, s11, 0xf00
	s_add_u32 s12, s9, s11
	s_addc_u32 s13, s8, 0
	s_bcnt1_i32_b64 s6, s[6:7]
	v_mov_b32_e32 v2, 0x28680000
	v_mov_b32_e32 v3, s6
	global_atomic_add v2, v3, s[12:13] offset:1024
.LBB0_11:
	s_or_b64 exec, exec, s[0:1]
	v_mbcnt_lo_u32_b32 v2, -1, 0
	s_andn2_b32 s10, s10, 63
	s_lshl_b32 s33, s2, 3
	v_mbcnt_hi_u32_b32 v182, -1, v2
	s_cmpk_lg_i32 s20, 0x100
	v_add_u32_e32 v183, s10, v182
	s_mov_b64 s[0:1], -1
	s_cbranch_scc0 .LBB0_660
	v_mov_b32_e32 v76, v183
	v_mov_b32_e32 v2, 0
	s_lshl_b32 s60, s20, 3
	v_add_u32_e32 v2, 0, v2
	v_add_u32_e32 v2, 0x201c0, v2
	v_readfirstlane_b32 s0, v76
	s_nop 0
	s_ashr_i32 s0, s0, 6
	s_add_i32 s64, s0, s33
	s_lshl_b32 s0, s0, 14
	s_add_i32 s22, s0, 0
	v_and_b32_e32 v26, 63, v76
	s_cmpk_lt_i32 s64, 0x580
	v_mov_b32_e32 v3, 0
	s_waitcnt lgkmcnt(0)
	v_readlane_b32 s9, v251, 49
	v_readlane_b32 s8, v251, 48
	s_cselect_b64 s[10:11], -1, 0
	s_cmpk_gt_i32 s64, 0x57f
	v_lshl_add_u32 v77, v26, 2, s22
	v_and_b32_e32 v27, 7, v76
	v_lshrrev_b32_e32 v78, 3, v26
	v_writelane_b32 v250, s84, 0
	s_cbranch_scc1 .LBB0_79
	v_lshlrev_b32_e32 v2, 4, v27
	v_mul_u32_u24_e32 v6, 0x410, v27
	v_lshl_add_u64 v[4:5], s[8:9], 0, v[2:3]
	v_lshlrev_b32_e32 v2, 2, v78
	v_add3_u32 v79, s22, v6, v2
	s_lshl_b32 s16, s64, 6
	s_lshl_b32 s17, s60, 6
	s_lshl_b32 s18, s64, 5
	s_lshl_b32 s19, s60, 5
	v_lshlrev_b32_e32 v2, 2, v26
	s_movk_i32 s23, 0x5000
	s_mov_b32 s24, 0xb000
	s_mov_b32 s25, 0x10000
	s_mov_b32 s26, 0x16000
	s_mov_b32 s27, 0x1b000
	s_mov_b32 s28, 0x21000
	s_mov_b32 s29, 0x26000
	s_mov_b32 s30, 0x2c000
	s_mov_b32 s31, 0x31000
	s_mov_b32 s34, 0x37000
	s_mov_b32 s35, 0x3c000
	s_mov_b32 s36, 0x42000
	s_mov_b32 s37, 0x47000
	s_mov_b32 s38, 0x4d000
	s_mov_b32 s39, 0x52000
	s_mov_b32 s40, 0x58000
	s_mov_b32 s41, 0x5d000
	s_mov_b32 s42, 0x63000
	s_mov_b32 s43, 0x68000
	s_mov_b32 s44, 0x6e000
	s_mov_b32 s45, 0x73000
	s_mov_b32 s46, 0x79000
	s_mov_b32 s47, 0x7e000
	s_mov_b32 s48, 0x84000
	s_mov_b32 s49, 0x89000
	s_mov_b32 s50, 0x8f000
	s_mov_b32 s51, 0x94000
	s_mov_b32 s52, 0x9a000
	s_mov_b32 s53, 0x9f000
	s_mov_b32 s54, 0xa5000
	s_mov_b32 s55, 0xaa000
	s_mov_b32 s56, 0xb0000
	s_mov_b32 s57, 0xb5000
	s_mov_b32 s58, 0xbb000
	s_mov_b32 s59, 0xc0000
	s_mov_b32 s61, 0xc6000
	s_mov_b32 s62, 0xcb000
	s_mov_b32 s63, 0xd1000
	s_mov_b32 s65, 0xd6000
	s_mov_b32 s66, 0xdc000
	s_mov_b32 s67, 0xe1000
	s_mov_b32 s68, 0xe7000
	s_mov_b32 s69, 0xec000
	s_mov_b32 s70, 0xf2000
	s_mov_b32 s71, 0xf7000
	s_mov_b32 s72, 0xfd000
	s_mov_b32 s73, 0x102000
	s_mov_b32 s74, 0x108000
	s_mov_b32 s75, 0x10d000
	s_mov_b32 s76, 0x113000
	s_mov_b32 s77, 0x118000
	s_mov_b32 s78, 0x11e000
	s_mov_b32 s79, 0x123000
	s_mov_b32 s80, 0x129000
	s_mov_b32 s81, 0x12e000
	s_mov_b32 s82, 0x134000
	s_mov_b32 s83, 0x139000
	s_mov_b32 s84, 0x13f000
	s_mov_b32 s85, 0x144000
	s_mov_b32 s86, 0x14a000
	s_mov_b32 s87, 0x14f000
	s_mov_b32 s88, s64
	s_branch .LBB0_15

; #define LAS __attribute__((address_space(3)))
; #define PIN(i) ((const float*)ldq_(L, (i)))
; __device__ __forceinline__ unsigned pk2(float lo, float hi) { f32x2 v = {lo, hi}; bf16x2_t b = __builtin_convertvector(v, bf16x2_t); return __builtin_bit_cast(unsigned, b); }
; #define PREP_CONV(bit, SRC, Kd, Nd, DST, GK, MODE) if (mask & (bit)) { for (int it = gw; it < ((Kd) / 64) * ((Nd) / 64); it += NGW) transpose_item((SRC), (Kd), (Nd), (bf16_t*)(wl + (DST)), (GK), (MODE), scr, it, lane); }
; __device__ __forceinline__ void transpose_item(const float* W, int K, int N, bf16_t* WT, const float* gk, int mode, LAS float* scr_, int item, int lane) {
;     LAS unsigned* scr = (LAS unsigned*)scr_;
;     const int nblk = N / 64, kb = item / nblk, nb = item % nblk, k0 = 64 * kb, n0 = 64 * nb;
;     const int sc = (mode == 1) ? (((n0 >> 7) & 1) * DFF + (n0 >> 8) * 128 + (n0 & 127)) : n0;
;     const float* src = W + (size_t)k0 * N + sc + lane;
;     float va[32], vb[32];
; #pragma unroll
;     for (int kp = 0; kp < 32; ++kp) { va[kp] = src[(size_t)(2 * kp) * N]; vb[kp] = src[(size_t)(2 * kp + 1) * N]; }
; #pragma unroll
;     for (int kp = 0; kp < 32; ++kp) {
;         float a = va[kp], b = vb[kp];
;         if (gk) { a *= gk[k0 + 2 * kp]; b *= gk[k0 + 2 * kp + 1]; }
;         scr[kp * 65 + lane] = pk2(a, b);
; __device__ __forceinline__ void prep(const Params& p, LAS unsigned char* L, int wv, int vb, int nvb, int l, int mask) {
;     ...
;     PREP_CONV(PM_FFA_IN, PIN(I_WFFA_IN) + (size_t)l * DM * NFF2, DM, NFF2, WL_FFA_IN, PIN(I_NFFA) + l * DM, 1)
.LBB0_15:
	v_mov_b32_e32 v6, 0
	s_mul_hi_i32 s0, s88, 0x2e8ba2e9
	v_add_u32_e32 v6, 0, v6
	v_add_u32_e32 v6, 0x20140, v6
	s_lshr_b32 s6, s0, 31
	s_ashr_i32 s0, s0, 4
	s_nop 0
	s_add_i32 s13, s0, s6
	s_mul_i32 s0, s13, 0xffffea00
	s_mul_i32 s7, s13, 0xfffff500
	s_add_i32 s89, s16, s0
	s_bfe_i32 s0, s88, 0x10001
	s_add_i32 s7, s18, s7
	s_and_b32 s0, s0, 0xb00
	s_and_b32 s7, s7, 0xffffff80
	s_lshl_b32 s6, s13, 6
	s_add_i32 s0, s0, s7
	s_and_b32 s7, s89, 64
	s_waitcnt lgkmcnt(0)
	v_readlane_b32 s12, v251, 16
	s_or_b32 s0, s0, s7
	s_ashr_i32 s7, s6, 31
	s_mul_i32 s13, s13, 0x160000
	v_readlane_b32 s1, v251, 17
	s_mul_hi_i32 s14, s6, 0x5800
	s_add_u32 s12, s12, s13
	v_mov_b32_e32 v8, 0
	s_addc_u32 s13, s1, s14
	s_ashr_i32 s1, s0, 31
	s_lshl_b64 s[0:1], s[0:1], 2
	v_add_u32_e32 v8, 0, v8
	s_add_u32 s0, s12, s0
	v_add_u32_e32 v6, 0x20138, v8
	s_addc_u32 s1, s13, s1
	ds_read_b64 v[68:69], v6
	v_lshl_add_u64 v[6:7], s[0:1], 0, v[2:3]
	v_add_co_u32_e32 v8, vcc, s23, v6
	s_waitcnt lgkmcnt(0)
	v_readfirstlane_b32 s13, v69
	v_addc_co_u32_e32 v9, vcc, 0, v7, vcc
	v_add_co_u32_e32 v10, vcc, s24, v6
	v_readfirstlane_b32 s12, v68
	s_nop 0
	v_addc_co_u32_e32 v11, vcc, 0, v7, vcc
	v_add_co_u32_e32 v12, vcc, s25, v6
	s_cmp_lg_u64 s[12:13], 0
	s_nop 0
	v_addc_co_u32_e32 v13, vcc, 0, v7, vcc
	v_add_co_u32_e32 v14, vcc, s26, v6
	s_cselect_b64 s[14:15], -1, 0
	s_nop 0
	v_addc_co_u32_e32 v15, vcc, 0, v7, vcc
	v_add_co_u32_e32 v16, vcc, s27, v6
	s_cmp_eq_u64 s[12:13], 0
	s_nop 0
	v_addc_co_u32_e32 v17, vcc, 0, v7, vcc
	v_add_co_u32_e32 v18, vcc, s28, v6
	s_nop 1
	v_addc_co_u32_e32 v19, vcc, 0, v7, vcc
	v_add_co_u32_e32 v20, vcc, s29, v6
	s_nop 1
	v_addc_co_u32_e32 v21, vcc, 0, v7, vcc
	v_add_co_u32_e32 v22, vcc, s30, v6
	s_nop 1
	v_addc_co_u32_e32 v23, vcc, 0, v7, vcc
	global_load_dword v73, v[8:9], off offset:2048
	global_load_dword v70, v[10:11], off
	global_load_dword v71, v[12:13], off offset:2048
	global_load_dword v64, v[14:15], off
	global_load_dword v65, v[16:17], off offset:2048
	global_load_dword v66, v[18:19], off
	global_load_dword v67, v[20:21], off offset:2048
	global_load_dword v60, v[22:23], off
	v_add_co_u32_e32 v8, vcc, s31, v6
	s_nop 1
	v_addc_co_u32_e32 v9, vcc, 0, v7, vcc
	v_add_co_u32_e32 v10, vcc, s34, v6
	s_nop 1
	v_addc_co_u32_e32 v11, vcc, 0, v7, vcc
	v_add_co_u32_e32 v12, vcc, s35, v6
	s_nop 1
	v_addc_co_u32_e32 v13, vcc, 0, v7, vcc
	v_add_co_u32_e32 v14, vcc, s36, v6
	s_nop 1
	v_addc_co_u32_e32 v15, vcc, 0, v7, vcc
	v_add_co_u32_e32 v16, vcc, s37, v6
	s_nop 1
	v_addc_co_u32_e32 v17, vcc, 0, v7, vcc
	v_add_co_u32_e32 v18, vcc, s38, v6
	s_nop 1
	v_addc_co_u32_e32 v19, vcc, 0, v7, vcc
	v_add_co_u32_e32 v20, vcc, s39, v6
	s_nop 1
	v_addc_co_u32_e32 v21, vcc, 0, v7, vcc
	v_add_co_u32_e32 v22, vcc, s40, v6
	s_nop 1
	v_addc_co_u32_e32 v23, vcc, 0, v7, vcc
	global_load_dword v61, v[8:9], off offset:2048
	global_load_dword v62, v[10:11], off
	global_load_dword v63, v[12:13], off offset:2048
	global_load_dword v56, v[14:15], off
	global_load_dword v57, v[16:17], off offset:2048
	global_load_dword v58, v[18:19], off
	global_load_dword v59, v[20:21], off offset:2048
	global_load_dword v52, v[22:23], off
	v_add_co_u32_e32 v8, vcc, s41, v6
	s_nop 1
	v_addc_co_u32_e32 v9, vcc, 0, v7, vcc
	v_add_co_u32_e32 v10, vcc, s42, v6
	s_nop 1
	v_addc_co_u32_e32 v11, vcc, 0, v7, vcc
	v_add_co_u32_e32 v12, vcc, s43, v6
	s_nop 1
	v_addc_co_u32_e32 v13, vcc, 0, v7, vcc
	v_add_co_u32_e32 v14, vcc, s44, v6
	s_nop 1
	v_addc_co_u32_e32 v15, vcc, 0, v7, vcc
	v_add_co_u32_e32 v16, vcc, s45, v6
	s_nop 1
	v_addc_co_u32_e32 v17, vcc, 0, v7, vcc
	v_add_co_u32_e32 v18, vcc, s46, v6
	s_nop 1
	v_addc_co_u32_e32 v19, vcc, 0, v7, vcc
	v_add_co_u32_e32 v20, vcc, s47, v6
	s_nop 1
	v_addc_co_u32_e32 v21, vcc, 0, v7, vcc
	v_add_co_u32_e32 v22, vcc, s48, v6
	s_nop 1
	v_addc_co_u32_e32 v23, vcc, 0, v7, vcc
	global_load_dword v53, v[8:9], off offset:2048
	global_load_dword v54, v[10:11], off
	global_load_dword v55, v[12:13], off offset:2048
	global_load_dword v48, v[14:15], off
	global_load_dword v49, v[16:17], off offset:2048
	global_load_dword v50, v[18:19], off
	global_load_dword v51, v[20:21], off offset:2048
	global_load_dword v44, v[22:23], off
	v_add_co_u32_e32 v8, vcc, s49, v6
	s_nop 1
	v_addc_co_u32_e32 v9, vcc, 0, v7, vcc
	v_add_co_u32_e32 v10, vcc, s50, v6
	s_nop 1
	v_addc_co_u32_e32 v11, vcc, 0, v7, vcc
	v_add_co_u32_e32 v12, vcc, s51, v6
	s_nop 1
	v_addc_co_u32_e32 v13, vcc, 0, v7, vcc
	v_add_co_u32_e32 v14, vcc, s52, v6
	s_nop 1
	v_addc_co_u32_e32 v15, vcc, 0, v7, vcc
	v_add_co_u32_e32 v16, vcc, s53, v6
	s_nop 1
	v_addc_co_u32_e32 v17, vcc, 0, v7, vcc
	v_add_co_u32_e32 v18, vcc, s54, v6
	s_nop 1
	v_addc_co_u32_e32 v19, vcc, 0, v7, vcc
	v_add_co_u32_e32 v20, vcc, s55, v6
	s_nop 1
	v_addc_co_u32_e32 v21, vcc, 0, v7, vcc
	v_add_co_u32_e32 v22, vcc, s56, v6
; __device__ __forceinline__ void transpose_item(const float* W, int K, int N, bf16_t* WT, const float* gk, int mode, LAS float* scr_, int item, int lane) {
;     ...
;     for (int kp = 0; kp < 32; ++kp) { va[kp] = src[(size_t)(2 * kp) * N]; vb[kp] = src[(size_t)(2 * kp + 1) * N]; }
; #pragma unroll
;     for (int kp = 0; kp < 32; ++kp) {
;         float a = va[kp], b = vb[kp];
;         if (gk) { a *= gk[k0 + 2 * kp]; b *= gk[k0 + 2 * kp + 1]; }
	s_nop 1
	v_addc_co_u32_e32 v23, vcc, 0, v7, vcc
	global_load_dword v45, v[8:9], off offset:2048
	global_load_dword v46, v[10:11], off
	global_load_dword v47, v[12:13], off offset:2048
	global_load_dword v40, v[14:15], off
	global_load_dword v41, v[16:17], off offset:2048
	global_load_dword v42, v[18:19], off
	global_load_dword v43, v[20:21], off offset:2048
	global_load_dword v36, v[22:23], off
	v_add_co_u32_e32 v8, vcc, s57, v6
	s_nop 1
	v_addc_co_u32_e32 v9, vcc, 0, v7, vcc
	v_add_co_u32_e32 v10, vcc, s58, v6
	s_nop 1
	v_addc_co_u32_e32 v11, vcc, 0, v7, vcc
	v_add_co_u32_e32 v12, vcc, s59, v6
	s_nop 1
	v_addc_co_u32_e32 v13, vcc, 0, v7, vcc
	v_add_co_u32_e32 v14, vcc, s61, v6
	s_nop 1
	v_addc_co_u32_e32 v15, vcc, 0, v7, vcc
	v_add_co_u32_e32 v16, vcc, s62, v6
	s_nop 1
	v_addc_co_u32_e32 v17, vcc, 0, v7, vcc
	v_add_co_u32_e32 v18, vcc, s63, v6
	s_nop 1
	v_addc_co_u32_e32 v19, vcc, 0, v7, vcc
	v_add_co_u32_e32 v20, vcc, s65, v6
	s_nop 1
	v_addc_co_u32_e32 v21, vcc, 0, v7, vcc
	v_add_co_u32_e32 v22, vcc, s66, v6
	s_nop 1
	v_addc_co_u32_e32 v23, vcc, 0, v7, vcc
	global_load_dword v37, v[8:9], off offset:2048
	global_load_dword v38, v[10:11], off
	global_load_dword v39, v[12:13], off offset:2048
	global_load_dword v32, v[14:15], off
	global_load_dword v33, v[16:17], off offset:2048
	global_load_dword v34, v[18:19], off
	global_load_dword v35, v[20:21], off offset:2048
	global_load_dword v28, v[22:23], off
	v_add_co_u32_e32 v8, vcc, s67, v6
	s_nop 1
	v_addc_co_u32_e32 v9, vcc, 0, v7, vcc
	v_add_co_u32_e32 v10, vcc, s68, v6
	s_nop 1
	v_addc_co_u32_e32 v11, vcc, 0, v7, vcc
	v_add_co_u32_e32 v12, vcc, s69, v6
	s_nop 1
	v_addc_co_u32_e32 v13, vcc, 0, v7, vcc
	v_add_co_u32_e32 v14, vcc, s70, v6
	s_nop 1
	v_addc_co_u32_e32 v15, vcc, 0, v7, vcc
	v_add_co_u32_e32 v16, vcc, s71, v6
	s_nop 1
	v_addc_co_u32_e32 v17, vcc, 0, v7, vcc
	v_add_co_u32_e32 v18, vcc, s72, v6
	s_nop 1
	v_addc_co_u32_e32 v19, vcc, 0, v7, vcc
	v_add_co_u32_e32 v20, vcc, s73, v6
	s_nop 1
	v_addc_co_u32_e32 v21, vcc, 0, v7, vcc
	v_add_co_u32_e32 v74, vcc, s74, v6
	s_nop 1
	v_addc_co_u32_e32 v75, vcc, 0, v7, vcc
	global_load_dword v29, v[8:9], off offset:2048
	global_load_dword v30, v[10:11], off
	global_load_dword v31, v[12:13], off offset:2048
	global_load_dword v22, v[14:15], off
	global_load_dword v23, v[16:17], off offset:2048
	global_load_dword v24, v[18:19], off
	global_load_dword v25, v[20:21], off offset:2048
	s_nop 0
	global_load_dword v18, v[74:75], off
	v_add_co_u32_e32 v8, vcc, s75, v6
	s_nop 1
	v_addc_co_u32_e32 v9, vcc, 0, v7, vcc
	v_add_co_u32_e32 v10, vcc, s76, v6
	s_nop 1
	v_addc_co_u32_e32 v11, vcc, 0, v7, vcc
	v_add_co_u32_e32 v12, vcc, s77, v6
	s_nop 1
	v_addc_co_u32_e32 v13, vcc, 0, v7, vcc
	v_add_co_u32_e32 v14, vcc, s78, v6
	s_nop 1
	v_addc_co_u32_e32 v15, vcc, 0, v7, vcc
	v_add_co_u32_e32 v16, vcc, s79, v6
	s_nop 1
	v_addc_co_u32_e32 v17, vcc, 0, v7, vcc
	v_add_co_u32_e32 v74, vcc, s80, v6
	s_nop 1
	v_addc_co_u32_e32 v75, vcc, 0, v7, vcc
	v_add_co_u32_e32 v80, vcc, s81, v6
	s_nop 1
	v_addc_co_u32_e32 v81, vcc, 0, v7, vcc
	v_add_co_u32_e32 v82, vcc, s82, v6
	s_nop 1
	v_addc_co_u32_e32 v83, vcc, 0, v7, vcc
	global_load_dword v19, v[8:9], off offset:2048
	global_load_dword v20, v[10:11], off
	global_load_dword v21, v[12:13], off offset:2048
	s_nop 0
	global_load_dword v14, v[14:15], off
	s_nop 0
	global_load_dword v15, v[16:17], off offset:2048
	s_nop 0
	global_load_dword v16, v[74:75], off
	global_load_dword v17, v[80:81], off offset:2048
	global_load_dword v10, v[82:83], off
	v_add_co_u32_e32 v8, vcc, s83, v6
	s_nop 1
	v_addc_co_u32_e32 v9, vcc, 0, v7, vcc
	v_add_co_u32_e32 v12, vcc, s84, v6
	s_nop 1
	v_addc_co_u32_e32 v13, vcc, 0, v7, vcc
	v_add_co_u32_e32 v74, vcc, s85, v6
	s_nop 1
	v_addc_co_u32_e32 v75, vcc, 0, v7, vcc
	v_add_co_u32_e32 v80, vcc, s86, v6
	s_nop 1
	v_addc_co_u32_e32 v81, vcc, 0, v7, vcc
	v_add_co_u32_e32 v82, vcc, s87, v6
	s_nop 1
	v_addc_co_u32_e32 v83, vcc, 0, v7, vcc
	v_add_co_u32_e32 v84, vcc, 0x155000, v6
	s_nop 1
	v_addc_co_u32_e32 v85, vcc, 0, v7, vcc
	v_add_co_u32_e32 v86, vcc, 0x15a000, v6
	s_nop 1
	v_addc_co_u32_e32 v87, vcc, 0, v7, vcc
	global_load_dword v72, v2, s[0:1]
	global_load_dword v11, v[8:9], off offset:2048
	s_nop 0
	global_load_dword v12, v[12:13], off
	s_nop 0
	global_load_dword v13, v[74:75], off offset:2048
	global_load_dword v6, v[80:81], off
	global_load_dword v7, v[82:83], off offset:2048
	global_load_dword v8, v[84:85], off
	global_load_dword v9, v[86:87], off offset:2048
	s_mov_b64 s[0:1], -1
	s_cbranch_scc1 .LBB0_17
	s_lshl_b64 s[0:1], s[6:7], 2
	s_add_u32 s0, s12, s0
	s_addc_u32 s1, s13, s1
	global_load_dwordx4 v[80:83], v3, s[0:1]
	s_mov_b64 s[0:1], 0
	s_waitcnt vmcnt(0)
	v_pk_mul_f32 v[68:69], v[72:73], v[80:81]
	v_pk_mul_f32 v[74:75], v[70:71], v[82:83]

; #define LAS __attribute__((address_space(3)))
; #define PIN(i) ((const float*)ldq_(L, (i)))
; __device__ __forceinline__ unsigned pk2(float lo, float hi) { f32x2 v = {lo, hi}; bf16x2_t b = __builtin_convertvector(v, bf16x2_t); return __builtin_bit_cast(unsigned, b); }
; #define PREP_CONV(bit, SRC, Kd, Nd, DST, GK, MODE) if (mask & (bit)) { for (int it = gw; it < ((Kd) / 64) * ((Nd) / 64); it += NGW) transpose_item((SRC), (Kd), (Nd), (bf16_t*)(wl + (DST)), (GK), (MODE), scr, it, lane); }
; __device__ __forceinline__ void transpose_item(const float* W, int K, int N, bf16_t* WT, const float* gk, int mode, LAS float* scr_, int item, int lane) {
;     LAS unsigned* scr = (LAS unsigned*)scr_;
;     const int nblk = N / 64, kb = item / nblk, nb = item % nblk, k0 = 64 * kb, n0 = 64 * nb;
;     const int sc = (mode == 1) ? (((n0 >> 7) & 1) * DFF + (n0 >> 8) * 128 + (n0 & 127)) : n0;
;     const float* src = W + (size_t)k0 * N + sc + lane;
;     float va[32], vb[32];
; #pragma unroll
;     for (int kp = 0; kp < 32; ++kp) { va[kp] = src[(size_t)(2 * kp) * N]; vb[kp] = src[(size_t)(2 * kp + 1) * N]; }
; #pragma unroll
;     for (int kp = 0; kp < 32; ++kp) {
;         float a = va[kp], b = vb[kp];
;         if (gk) { a *= gk[k0 + 2 * kp]; b *= gk[k0 + 2 * kp + 1]; }
;         scr[kp * 65 + lane] = pk2(a, b);
;     }
; __device__ __forceinline__ void prep(const Params& p, LAS unsigned char* L, int wv, int vb, int nvb, int l, int mask) {
;     ...
;     PREP_CONV(PM_FFA_OUT, PIN(I_WFFA_OUT) + (size_t)l * DFF * DM, DFF, DM, WL_FFA_OUT, nullptr, 0)
.LBB0_81:
	v_mov_b32_e32 v6, 0
	s_ashr_i32 s0, s56, 31
	v_add_u32_e32 v6, 0, v6
	v_add_u32_e32 v6, 0x20148, v6
	s_lshr_b32 s0, s0, 28
	s_nop 0
	s_add_i32 s0, s56, s0
	s_ashr_i32 s1, s0, 4
	s_lshl_b32 s0, s1, 6
	s_lshl_b32 s12, s1, 10
	s_mul_i32 s13, s1, 0xffd40000
	s_ashr_i32 s1, s0, 31
	s_sub_i32 s12, s17, s12
	s_lshl_b64 s[14:15], s[0:1], 12
	v_lshl_add_u64 v[20:21], s[0:1], 1, v[4:5]
	s_waitcnt lgkmcnt(0)
	v_readlane_b32 s1, v251, 18
	v_readlane_b32 s0, v251, 19
	s_add_u32 s14, s1, s14
	v_add_u32_e32 v18, s13, v9
	s_addc_u32 s15, s0, s15
	s_ashr_i32 s13, s12, 31
	s_lshl_b64 s[0:1], s[12:13], 2
	s_add_u32 s0, s14, s0
	s_addc_u32 s1, s15, s1
	v_ashrrev_i32_e32 v19, 31, v18
	v_lshl_add_u64 v[6:7], s[0:1], 0, v[2:3]
	v_add_u32_e32 v22, 0x5800, v18
	v_add_u32_e32 v24, 0xb000, v18
	v_add_u32_e32 v28, 0x10800, v18
	v_add_u32_e32 v30, 0x16000, v18
	v_add_u32_e32 v32, 0x1b800, v18
	v_add_u32_e32 v34, 0x21000, v18
	v_add_u32_e32 v36, 0x26800, v18
	v_lshl_add_u64 v[52:53], v[18:19], 1, v[20:21]
	v_add_co_u32_e32 v18, vcc, s19, v6
	v_ashrrev_i32_e32 v23, 31, v22
	v_ashrrev_i32_e32 v25, 31, v24
	v_ashrrev_i32_e32 v29, 31, v28
	v_ashrrev_i32_e32 v31, 31, v30
	v_ashrrev_i32_e32 v33, 31, v32
	v_ashrrev_i32_e32 v35, 31, v34
	v_ashrrev_i32_e32 v37, 31, v36
	v_addc_co_u32_e32 v19, vcc, 0, v7, vcc
	v_lshl_add_u64 v[54:55], v[22:23], 1, v[20:21]
	v_lshl_add_u64 v[56:57], v[24:25], 1, v[20:21]
	v_lshl_add_u64 v[58:59], v[28:29], 1, v[20:21]
	v_lshl_add_u64 v[60:61], v[30:31], 1, v[20:21]
	v_lshl_add_u64 v[62:63], v[32:33], 1, v[20:21]
	v_lshl_add_u64 v[64:65], v[34:35], 1, v[20:21]
	v_lshl_add_u64 v[66:67], v[36:37], 1, v[20:21]
	v_add_co_u32_e32 v20, vcc, s24, v6
	global_load_dword v17, v2, s[0:1]
	s_nop 0
	v_addc_co_u32_e32 v21, vcc, 0, v7, vcc
	v_add_co_u32_e32 v22, vcc, s25, v6
	s_add_i32 s56, s56, s60
	s_nop 0
	v_addc_co_u32_e32 v23, vcc, 0, v7, vcc
	v_add_co_u32_e32 v24, vcc, s26, v6
	s_add_i32 s17, s17, s18
	s_nop 0
	v_addc_co_u32_e32 v25, vcc, 0, v7, vcc
	v_add_co_u32_e32 v28, vcc, s27, v6
	s_cmpk_lt_i32 s56, 0x2c0
	s_nop 0
	v_addc_co_u32_e32 v29, vcc, 0, v7, vcc
	v_add_co_u32_e32 v30, vcc, s28, v6
	v_add_u32_e32 v9, s61, v9
	s_nop 0
	v_addc_co_u32_e32 v31, vcc, 0, v7, vcc
	v_add_co_u32_e32 v32, vcc, s29, v6
	s_nop 1
	v_addc_co_u32_e32 v33, vcc, 0, v7, vcc
	v_add_co_u32_e32 v34, vcc, s30, v6
	s_nop 1
	v_addc_co_u32_e32 v35, vcc, 0, v7, vcc
	v_add_co_u32_e32 v36, vcc, s31, v6
	s_nop 1
	v_addc_co_u32_e32 v37, vcc, 0, v7, vcc
	v_add_co_u32_e32 v38, vcc, s34, v6
	s_nop 1
	v_addc_co_u32_e32 v39, vcc, 0, v7, vcc
	v_add_co_u32_e32 v40, vcc, s35, v6
	s_nop 1
	v_addc_co_u32_e32 v41, vcc, 0, v7, vcc
	v_add_co_u32_e32 v42, vcc, s36, v6
	s_nop 1
	v_addc_co_u32_e32 v43, vcc, 0, v7, vcc
	v_add_co_u32_e32 v44, vcc, s37, v6
	s_nop 1
	v_addc_co_u32_e32 v45, vcc, 0, v7, vcc
	v_add_co_u32_e32 v46, vcc, s38, v6
	s_nop 1
	v_addc_co_u32_e32 v47, vcc, 0, v7, vcc
	v_add_co_u32_e32 v48, vcc, s39, v6
	s_nop 1
	v_addc_co_u32_e32 v49, vcc, 0, v7, vcc
	v_add_co_u32_e32 v50, vcc, s40, v6
	s_nop 1
	v_addc_co_u32_e32 v51, vcc, 0, v7, vcc
	v_add_co_u32_e32 v68, vcc, s41, v6
	s_nop 1
	v_addc_co_u32_e32 v69, vcc, 0, v7, vcc
	v_add_co_u32_e32 v70, vcc, s42, v6
	s_nop 1
	v_addc_co_u32_e32 v71, vcc, 0, v7, vcc
	v_add_co_u32_e32 v72, vcc, s43, v6
	s_nop 1
	v_addc_co_u32_e32 v73, vcc, 0, v7, vcc
	v_add_co_u32_e32 v74, vcc, s44, v6
	s_nop 1
	v_addc_co_u32_e32 v75, vcc, 0, v7, vcc
	v_add_co_u32_e32 v80, vcc, s45, v6
	s_nop 1
	v_addc_co_u32_e32 v81, vcc, 0, v7, vcc
	v_add_co_u32_e32 v82, vcc, s16, v6
	s_nop 1
	v_addc_co_u32_e32 v83, vcc, 0, v7, vcc
	v_add_co_u32_e32 v84, vcc, s46, v6
	s_nop 1
	v_addc_co_u32_e32 v85, vcc, 0, v7, vcc
	v_add_co_u32_e32 v86, vcc, s47, v6
	s_nop 1
	v_addc_co_u32_e32 v87, vcc, 0, v7, vcc
	v_add_co_u32_e32 v88, vcc, s48, v6
	s_nop 1
	v_addc_co_u32_e32 v89, vcc, 0, v7, vcc
	v_add_co_u32_e32 v90, vcc, s49, v6
	s_nop 1
	v_addc_co_u32_e32 v91, vcc, 0, v7, vcc
	v_add_co_u32_e32 v92, vcc, s50, v6
	s_nop 1
	v_addc_co_u32_e32 v93, vcc, 0, v7, vcc
	v_add_co_u32_e32 v94, vcc, s51, v6
	s_nop 1
	v_addc_co_u32_e32 v95, vcc, 0, v7, vcc
	v_add_co_u32_e32 v96, vcc, s52, v6
	s_nop 1
	v_addc_co_u32_e32 v97, vcc, 0, v7, vcc
	v_add_co_u32_e32 v98, vcc, s53, v6
	s_nop 1
	v_addc_co_u32_e32 v99, vcc, 0, v7, vcc
	v_add_co_u32_e32 v100, vcc, s54, v6
	s_nop 1
	v_addc_co_u32_e32 v101, vcc, 0, v7, vcc
	v_add_co_u32_e32 v6, vcc, s55, v6
	s_nop 1
	v_addc_co_u32_e32 v7, vcc, 0, v7, vcc
	global_load_dword v79, v[18:19], off offset:-4096
	s_nop 0
	global_load_dword v18, v[18:19], off
	s_nop 0
	global_load_dword v19, v[20:21], off offset:-4096
	s_nop 0
	global_load_dword v20, v[20:21], off
	s_nop 0
	global_load_dword v21, v[22:23], off offset:-4096
	s_nop 0
	global_load_dword v22, v[22:23], off
	s_nop 0
	global_load_dword v23, v[24:25], off offset:-4096
	s_nop 0
	global_load_dword v24, v[24:25], off
	s_nop 0
	global_load_dword v25, v[28:29], off offset:-4096
	s_nop 0
	global_load_dword v28, v[28:29], off
	s_nop 0
	global_load_dword v29, v[30:31], off offset:-4096
	s_nop 0
	global_load_dword v30, v[30:31], off
	s_nop 0
	global_load_dword v31, v[32:33], off offset:-4096
	s_nop 0
	global_load_dword v32, v[32:33], off
	s_nop 0
	global_load_dword v33, v[34:35], off offset:-4096
	s_nop 0
	global_load_dword v34, v[34:35], off
	s_nop 0
	global_load_dword v35, v[36:37], off offset:-4096
	s_nop 0
	global_load_dword v36, v[36:37], off
	s_nop 0
	global_load_dword v37, v[38:39], off offset:-4096
	s_nop 0
	global_load_dword v38, v[38:39], off
	s_nop 0
	global_load_dword v39, v[40:41], off offset:-4096
	s_nop 0
	global_load_dword v40, v[40:41], off
	s_nop 0
	global_load_dword v41, v[42:43], off offset:-4096
; #define LAS __attribute__((address_space(3)))
; __device__ __forceinline__ unsigned pk2(float lo, float hi) { f32x2 v = {lo, hi}; bf16x2_t b = __builtin_convertvector(v, bf16x2_t); return __builtin_bit_cast(unsigned, b); }
; __device__ __forceinline__ void transpose_item(const float* W, int K, int N, bf16_t* WT, const float* gk, int mode, LAS float* scr_, int item, int lane) {
;     ...
;     for (int kp = 0; kp < 32; ++kp) { va[kp] = src[(size_t)(2 * kp) * N]; vb[kp] = src[(size_t)(2 * kp + 1) * N]; }
; #pragma unroll
;     for (int kp = 0; kp < 32; ++kp) {
;         float a = va[kp], b = vb[kp];
;         if (gk) { a *= gk[k0 + 2 * kp]; b *= gk[k0 + 2 * kp + 1]; }
;         scr[kp * 65 + lane] = pk2(a, b);
;     }
;     asm volatile("s_waitcnt lgkmcnt(0)" ::: "memory");
;     const int c = lane & 7;
; #pragma unroll
;     for (int j = 0; j < 8; ++j) { const int r = (lane >> 3) + 8 * j; const LAS unsigned* q = scr + (4 * c) * 65 + r;
;         u32x4 o; o.x = q[0]; o.y = q[65]; o.z = q[130]; o.w = q[195];
;         *(u32x4*)(WT + (size_t)(n0 + r) * K + k0 + 8 * c) = o; }
;     asm volatile("s_waitcnt lgkmcnt(0)" ::: "memory");
	s_nop 0
	global_load_dword v42, v[42:43], off
	s_nop 0
	global_load_dword v43, v[44:45], off offset:-4096
	s_nop 0
	global_load_dword v44, v[44:45], off
	s_nop 0
	global_load_dword v45, v[46:47], off offset:-4096
	s_nop 0
	global_load_dword v46, v[46:47], off
	s_nop 0
	global_load_dword v47, v[48:49], off offset:-4096
	s_nop 0
	global_load_dword v48, v[48:49], off
	s_nop 0
	global_load_dword v49, v[50:51], off offset:-4096
	s_nop 0
	global_load_dword v50, v[50:51], off
	s_nop 0
	global_load_dword v51, v[68:69], off offset:-4096
	s_nop 0
	global_load_dword v68, v[68:69], off
	s_nop 0
	global_load_dword v69, v[70:71], off offset:-4096
	s_nop 0
	global_load_dword v70, v[70:71], off
	s_nop 0
	global_load_dword v71, v[72:73], off offset:-4096
	s_nop 0
	global_load_dword v72, v[72:73], off
	s_nop 0
	global_load_dword v73, v[74:75], off offset:-4096
	s_nop 0
	global_load_dword v74, v[74:75], off
	s_nop 0
	global_load_dword v75, v[80:81], off offset:-4096
	s_nop 0
	global_load_dword v80, v[80:81], off
	s_nop 0
	global_load_dword v81, v[82:83], off offset:-4096
	s_nop 0
	global_load_dword v82, v[82:83], off
	s_nop 0
	global_load_dword v83, v[84:85], off offset:-4096
	s_nop 0
	global_load_dword v84, v[84:85], off
	s_nop 0
	global_load_dword v85, v[86:87], off offset:-4096
	s_nop 0
	global_load_dword v86, v[86:87], off
	s_nop 0
	global_load_dword v87, v[88:89], off offset:-4096
	s_nop 0
	global_load_dword v88, v[88:89], off
	s_nop 0
	global_load_dword v89, v[90:91], off offset:-4096
	s_nop 0
	global_load_dword v90, v[90:91], off
	s_nop 0
	global_load_dword v91, v[92:93], off offset:-4096
	s_nop 0
	global_load_dword v92, v[92:93], off
	s_nop 0
	global_load_dword v93, v[94:95], off offset:-4096
	s_nop 0
	global_load_dword v94, v[94:95], off
	s_nop 0
	global_load_dword v95, v[96:97], off offset:-4096
	s_nop 0
	global_load_dword v96, v[96:97], off
	s_nop 0
	global_load_dword v97, v[98:99], off offset:-4096
	s_nop 0
	global_load_dword v98, v[98:99], off
	s_nop 0
	global_load_dword v99, v[100:101], off offset:-4096
	s_nop 0
	global_load_dword v100, v[100:101], off
	s_nop 0
	global_load_dword v6, v[6:7], off
	s_waitcnt vmcnt(62)
	v_cvt_pk_bf16_f32 v7, v17, v79
	s_waitcnt vmcnt(60)
	v_cvt_pk_bf16_f32 v17, v18, v19
	s_waitcnt vmcnt(58)
	v_cvt_pk_bf16_f32 v18, v20, v21
	s_waitcnt vmcnt(56)
	v_cvt_pk_bf16_f32 v19, v22, v23
	s_waitcnt vmcnt(54)
	v_cvt_pk_bf16_f32 v20, v24, v25
	s_waitcnt vmcnt(52)
	v_cvt_pk_bf16_f32 v21, v28, v29
	s_waitcnt vmcnt(50)
	v_cvt_pk_bf16_f32 v22, v30, v31
	s_waitcnt vmcnt(48)
	v_cvt_pk_bf16_f32 v23, v32, v33
	s_waitcnt vmcnt(46)
	v_cvt_pk_bf16_f32 v24, v34, v35
	s_waitcnt vmcnt(44)
	v_cvt_pk_bf16_f32 v25, v36, v37
	s_waitcnt vmcnt(42)
	v_cvt_pk_bf16_f32 v28, v38, v39
	s_waitcnt vmcnt(40)
	v_cvt_pk_bf16_f32 v29, v40, v41
	s_waitcnt vmcnt(38)
	v_cvt_pk_bf16_f32 v30, v42, v43
	s_waitcnt vmcnt(36)
	v_cvt_pk_bf16_f32 v31, v44, v45
	s_waitcnt vmcnt(34)
	v_cvt_pk_bf16_f32 v32, v46, v47
	s_waitcnt vmcnt(32)
	v_cvt_pk_bf16_f32 v33, v48, v49
	s_waitcnt vmcnt(30)
	v_cvt_pk_bf16_f32 v34, v50, v51
	s_waitcnt vmcnt(28)
	v_cvt_pk_bf16_f32 v35, v68, v69
	s_waitcnt vmcnt(26)
	v_cvt_pk_bf16_f32 v36, v70, v71
	s_waitcnt vmcnt(24)
	v_cvt_pk_bf16_f32 v37, v72, v73
	s_waitcnt vmcnt(22)
	v_cvt_pk_bf16_f32 v38, v74, v75
	s_waitcnt vmcnt(20)
	v_cvt_pk_bf16_f32 v39, v80, v81
	s_waitcnt vmcnt(18)
	v_cvt_pk_bf16_f32 v40, v82, v83
	s_waitcnt vmcnt(16)
	v_cvt_pk_bf16_f32 v41, v84, v85
	s_waitcnt vmcnt(14)
	v_cvt_pk_bf16_f32 v42, v86, v87
	s_waitcnt vmcnt(12)
	v_cvt_pk_bf16_f32 v43, v88, v89
	s_waitcnt vmcnt(10)
	v_cvt_pk_bf16_f32 v44, v90, v91
	s_waitcnt vmcnt(8)
	v_cvt_pk_bf16_f32 v45, v92, v93
	s_waitcnt vmcnt(6)
	v_cvt_pk_bf16_f32 v46, v94, v95
	s_waitcnt vmcnt(4)
	v_cvt_pk_bf16_f32 v47, v96, v97
	s_waitcnt vmcnt(2)
	v_cvt_pk_bf16_f32 v48, v98, v99
	s_waitcnt vmcnt(0)
	v_cvt_pk_bf16_f32 v6, v100, v6
	ds_write2_b32 v77, v7, v17 offset1:65
	ds_write2_b32 v77, v18, v19 offset0:130 offset1:195
	ds_write2_b32 v10, v20, v21 offset0:4 offset1:69
	ds_write2_b32 v10, v22, v23 offset0:134 offset1:199
	ds_write2_b32 v11, v24, v25 offset0:8 offset1:73
	ds_write2_b32 v11, v28, v29 offset0:138 offset1:203
	ds_write2_b32 v12, v30, v31 offset0:12 offset1:77
	ds_write2_b32 v12, v32, v33 offset0:142 offset1:207
	ds_write2_b32 v13, v34, v35 offset0:16 offset1:81
	ds_write2_b32 v13, v36, v37 offset0:146 offset1:211
	ds_write2_b32 v14, v38, v39 offset0:20 offset1:85
	ds_write2_b32 v14, v40, v41 offset0:150 offset1:215
	ds_write2_b32 v15, v42, v43 offset0:24 offset1:89
	ds_write2_b32 v15, v44, v45 offset0:154 offset1:219
	ds_write2_b32 v16, v46, v47 offset0:28 offset1:93
	ds_write2_b32 v16, v48, v6 offset0:158 offset1:223
	s_waitcnt lgkmcnt(0)
	ds_read2_b32 v[18:19], v8 offset0:65 offset1:73
	ds_read2_b32 v[6:7], v8 offset0:130 offset1:138
	ds_read2_b32 v[20:21], v8 offset0:195 offset1:203
	ds_read2_b32 v[40:41], v8 offset1:8
	ds_read2_b32 v[44:45], v8 offset0:16 offset1:24
	ds_read2_b32 v[22:23], v8 offset0:81 offset1:89
	ds_read2_b32 v[46:47], v8 offset0:146 offset1:154
	ds_read2_b32 v[24:25], v8 offset0:211 offset1:219
	ds_read2_b32 v[28:29], v8 offset0:97 offset1:105
	ds_read2_b32 v[48:49], v8 offset0:162 offset1:170
	ds_read2_b32 v[30:31], v8 offset0:227 offset1:235
	ds_read2_b32 v[50:51], v8 offset0:32 offset1:40
	ds_read2_b32 v[68:69], v8 offset0:48 offset1:56
	ds_read2_b32 v[32:33], v8 offset0:113 offset1:121
	ds_read2_b32 v[70:71], v8 offset0:178 offset1:186
	ds_read2_b32 v[34:35], v8 offset0:243 offset1:251
	s_waitcnt lgkmcnt(12)
	v_mov_b32_e32 v36, v40
	v_mov_b32_e32 v37, v18
	v_mov_b32_e32 v38, v6
	v_mov_b32_e32 v39, v20
	v_mov_b32_e32 v18, v41
	v_mov_b32_e32 v20, v7
	s_waitcnt lgkmcnt(11)
	v_mov_b32_e32 v40, v44
	s_waitcnt lgkmcnt(10)
	v_mov_b32_e32 v41, v22
	s_waitcnt lgkmcnt(9)
	v_mov_b32_e32 v42, v46
	s_waitcnt lgkmcnt(8)
	v_mov_b32_e32 v43, v24
	v_mov_b32_e32 v22, v45
	v_mov_b32_e32 v24, v47
	s_waitcnt lgkmcnt(4)
	v_mov_b32_e32 v44, v50
	v_mov_b32_e32 v45, v28
	v_mov_b32_e32 v46, v48
	v_mov_b32_e32 v47, v30
	v_mov_b32_e32 v28, v51
	v_mov_b32_e32 v30, v49
	s_waitcnt lgkmcnt(3)
	v_mov_b32_e32 v48, v68
	s_waitcnt lgkmcnt(2)
	v_mov_b32_e32 v49, v32
	s_waitcnt lgkmcnt(1)
	v_mov_b32_e32 v50, v70
	s_waitcnt lgkmcnt(0)
	v_mov_b32_e32 v51, v34
	v_mov_b32_e32 v32, v69
	v_mov_b32_e32 v34, v71
	global_store_dwordx4 v[52:53], v[36:39], off
	global_store_dwordx4 v[54:55], v[18:21], off
	global_store_dwordx4 v[56:57], v[40:43], off
	global_store_dwordx4 v[58:59], v[22:25], off
	global_store_dwordx4 v[60:61], v[44:47], off
	global_store_dwordx4 v[62:63], v[28:31], off
	global_store_dwordx4 v[64:65], v[48:51], off
	global_store_dwordx4 v[66:67], v[32:35], off
	s_waitcnt lgkmcnt(0)
	s_cbranch_scc1 .LBB0_81

; #define PIN(i) ((const float*)ldq_(L, (i)))
; #define PREP_CONV(bit, SRC, Kd, Nd, DST, GK, MODE) if (mask & (bit)) { for (int it = gw; it < ((Kd) / 64) * ((Nd) / 64); it += NGW) transpose_item((SRC), (Kd), (Nd), (bf16_t*)(wl + (DST)), (GK), (MODE), scr, it, lane); }
; __device__ __forceinline__ void transpose_item(const float* W, int K, int N, bf16_t* WT, const float* gk, int mode, LAS float* scr_, int item, int lane) {
;     ...
;     const int nblk = N / 64, kb = item / nblk, nb = item % nblk, k0 = 64 * kb, n0 = 64 * nb;
;     const int sc = (mode == 1) ? (((n0 >> 7) & 1) * DFF + (n0 >> 8) * 128 + (n0 & 127)) : n0;
;     const float* src = W + (size_t)k0 * N + sc + lane;
;     float va[32], vb[32];
; #pragma unroll
;     for (int kp = 0; kp < 32; ++kp) { va[kp] = src[(size_t)(2 * kp) * N]; vb[kp] = src[(size_t)(2 * kp + 1) * N]; }
; __device__ __forceinline__ void prep(const Params& p, LAS unsigned char* L, int wv, int vb, int nvb, int l, int mask) {
;     ...
;     PREP_CONV(PM_WIN, PIN(I_WIN) + (size_t)l * DM * NIN, DM, NIN, WL_IN, PIN(I_NMIX) + l * DM, 0)
.LBB0_85:
	v_mov_b32_e32 v6, 0
	s_mul_hi_i32 s12, s92, 0x66666667
	v_add_u32_e32 v6, 0, v6
	v_add_u32_e32 v6, 0x20158, v6
	s_nop 0
	s_lshr_b32 s13, s12, 31
	s_ashr_i32 s12, s12, 3
	s_add_i32 s13, s12, s13
	s_lshl_b32 s14, s13, 6
	s_mul_i32 s12, s13, 0xfffffb00
	s_waitcnt lgkmcnt(0)
	v_readlane_b32 s1, v251, 22
	s_add_i32 s12, s24, s12
	s_ashr_i32 s15, s14, 31
	s_mul_i32 s13, s13, 0x50000
	v_readlane_b32 s0, v251, 23
	s_mul_hi_i32 s16, s14, 0x1400
	s_add_u32 s17, s1, s13
	v_mov_b32_e32 v8, 0
	s_addc_u32 s16, s0, s16
	s_ashr_i32 s13, s12, 31
	s_lshl_b64 s[0:1], s[12:13], 2
	v_add_u32_e32 v8, 0, v8
	s_add_u32 s0, s17, s0
	v_add_u32_e32 v6, 0x20150, v8
	s_addc_u32 s1, s16, s1
	ds_read_b64 v[68:69], v6
	v_lshl_add_u64 v[6:7], s[0:1], 0, v[2:3]
	v_add_co_u32_e32 v8, vcc, s26, v6
	s_waitcnt lgkmcnt(0)
	v_readfirstlane_b32 s17, v69
	v_addc_co_u32_e32 v9, vcc, 0, v7, vcc
	v_add_co_u32_e32 v10, vcc, s27, v6
	v_readfirstlane_b32 s16, v68
	s_nop 0
	v_addc_co_u32_e32 v11, vcc, 0, v7, vcc
	v_add_co_u32_e32 v12, vcc, s28, v6
	s_cmp_lg_u64 s[16:17], 0
	s_nop 0
	v_addc_co_u32_e32 v13, vcc, 0, v7, vcc
	v_add_co_u32_e32 v14, vcc, s29, v6
	s_cselect_b64 s[18:19], -1, 0
	s_nop 0
	v_addc_co_u32_e32 v15, vcc, 0, v7, vcc
	v_add_co_u32_e32 v16, vcc, s30, v6
	s_cmp_eq_u64 s[16:17], 0
	s_nop 0
	v_addc_co_u32_e32 v17, vcc, 0, v7, vcc
	v_add_co_u32_e32 v18, vcc, s31, v6
	s_nop 1
	v_addc_co_u32_e32 v19, vcc, 0, v7, vcc
	v_add_co_u32_e32 v20, vcc, s34, v6
	s_nop 1
	v_addc_co_u32_e32 v21, vcc, 0, v7, vcc
	v_add_co_u32_e32 v22, vcc, s35, v6
	s_nop 1
	v_addc_co_u32_e32 v23, vcc, 0, v7, vcc
	global_load_dword v73, v[8:9], off offset:1024
	global_load_dword v70, v[10:11], off offset:2048
	global_load_dword v71, v[12:13], off offset:3072
	global_load_dword v64, v[14:15], off
	global_load_dword v65, v[16:17], off offset:1024
	global_load_dword v66, v[18:19], off offset:2048
	global_load_dword v67, v[20:21], off offset:3072
	global_load_dword v60, v[22:23], off
	v_add_co_u32_e32 v8, vcc, s36, v6
	s_nop 1
	v_addc_co_u32_e32 v9, vcc, 0, v7, vcc
	v_add_co_u32_e32 v10, vcc, s37, v6
	s_nop 1
	v_addc_co_u32_e32 v11, vcc, 0, v7, vcc
	v_add_co_u32_e32 v12, vcc, s38, v6
	s_nop 1
	v_addc_co_u32_e32 v13, vcc, 0, v7, vcc
	v_add_co_u32_e32 v14, vcc, s39, v6
	s_nop 1
	v_addc_co_u32_e32 v15, vcc, 0, v7, vcc
	v_add_co_u32_e32 v16, vcc, s40, v6
	s_nop 1
	v_addc_co_u32_e32 v17, vcc, 0, v7, vcc
	v_add_co_u32_e32 v18, vcc, s41, v6
	s_nop 1
	v_addc_co_u32_e32 v19, vcc, 0, v7, vcc
	v_add_co_u32_e32 v20, vcc, s42, v6
	s_nop 1
	v_addc_co_u32_e32 v21, vcc, 0, v7, vcc
	v_add_co_u32_e32 v22, vcc, s43, v6
	s_nop 1
	v_addc_co_u32_e32 v23, vcc, 0, v7, vcc
	global_load_dword v61, v[8:9], off offset:1024
	global_load_dword v62, v[10:11], off offset:2048
	global_load_dword v63, v[12:13], off offset:3072
	global_load_dword v56, v[14:15], off
	global_load_dword v57, v[16:17], off offset:1024
	global_load_dword v58, v[18:19], off offset:2048
	global_load_dword v59, v[20:21], off offset:3072
	global_load_dword v52, v[22:23], off
	v_add_co_u32_e32 v8, vcc, s44, v6
	s_nop 1
	v_addc_co_u32_e32 v9, vcc, 0, v7, vcc
	v_add_co_u32_e32 v10, vcc, s45, v6
	s_nop 1
	v_addc_co_u32_e32 v11, vcc, 0, v7, vcc
	v_add_co_u32_e32 v12, vcc, s46, v6
	s_nop 1
	v_addc_co_u32_e32 v13, vcc, 0, v7, vcc
	v_add_co_u32_e32 v14, vcc, s47, v6
	s_nop 1
	v_addc_co_u32_e32 v15, vcc, 0, v7, vcc
	v_add_co_u32_e32 v16, vcc, s48, v6
	s_nop 1
	v_addc_co_u32_e32 v17, vcc, 0, v7, vcc
	v_add_co_u32_e32 v18, vcc, s49, v6
	s_nop 1
	v_addc_co_u32_e32 v19, vcc, 0, v7, vcc
	v_add_co_u32_e32 v20, vcc, s50, v6
	s_nop 1
	v_addc_co_u32_e32 v21, vcc, 0, v7, vcc
	v_add_co_u32_e32 v22, vcc, s51, v6
	s_nop 1
	v_addc_co_u32_e32 v23, vcc, 0, v7, vcc
	global_load_dword v53, v[8:9], off offset:1024
	global_load_dword v54, v[10:11], off offset:2048
	global_load_dword v55, v[12:13], off offset:3072
	global_load_dword v48, v[14:15], off
	global_load_dword v49, v[16:17], off offset:1024
	global_load_dword v50, v[18:19], off offset:2048
	global_load_dword v51, v[20:21], off offset:3072
	global_load_dword v44, v[22:23], off
	v_add_co_u32_e32 v8, vcc, s52, v6
	s_nop 1
	v_addc_co_u32_e32 v9, vcc, 0, v7, vcc
	v_add_co_u32_e32 v10, vcc, s53, v6
	s_nop 1
	v_addc_co_u32_e32 v11, vcc, 0, v7, vcc
	v_add_co_u32_e32 v12, vcc, s54, v6
	s_nop 1
	v_addc_co_u32_e32 v13, vcc, 0, v7, vcc
	v_add_co_u32_e32 v14, vcc, s55, v6
	s_nop 1
	v_addc_co_u32_e32 v15, vcc, 0, v7, vcc
	v_add_co_u32_e32 v16, vcc, s56, v6
	s_nop 1
	v_addc_co_u32_e32 v17, vcc, 0, v7, vcc
	v_add_co_u32_e32 v18, vcc, s57, v6
	s_nop 1
	v_addc_co_u32_e32 v19, vcc, 0, v7, vcc
	v_add_co_u32_e32 v20, vcc, s58, v6
	s_nop 1
	v_addc_co_u32_e32 v21, vcc, 0, v7, vcc
	v_add_co_u32_e32 v22, vcc, s59, v6
	s_nop 1
	v_addc_co_u32_e32 v23, vcc, 0, v7, vcc
	global_load_dword v45, v[8:9], off offset:1024
; __device__ __forceinline__ void transpose_item(const float* W, int K, int N, bf16_t* WT, const float* gk, int mode, LAS float* scr_, int item, int lane) {
;     ...
;     for (int kp = 0; kp < 32; ++kp) { va[kp] = src[(size_t)(2 * kp) * N]; vb[kp] = src[(size_t)(2 * kp + 1) * N]; }
; #pragma unroll
;     for (int kp = 0; kp < 32; ++kp) {
;         float a = va[kp], b = vb[kp];
;         if (gk) { a *= gk[k0 + 2 * kp]; b *= gk[k0 + 2 * kp + 1]; }
	global_load_dword v46, v[10:11], off offset:2048
	global_load_dword v47, v[12:13], off offset:3072
	global_load_dword v40, v[14:15], off
	global_load_dword v41, v[16:17], off offset:1024
	global_load_dword v42, v[18:19], off offset:2048
	global_load_dword v43, v[20:21], off offset:3072
	global_load_dword v36, v[22:23], off
	v_add_co_u32_e32 v8, vcc, s62, v6
	s_nop 1
	v_addc_co_u32_e32 v9, vcc, 0, v7, vcc
	v_add_co_u32_e32 v10, vcc, s63, v6
	s_nop 1
	v_addc_co_u32_e32 v11, vcc, 0, v7, vcc
	v_add_co_u32_e32 v12, vcc, s65, v6
	s_nop 1
	v_addc_co_u32_e32 v13, vcc, 0, v7, vcc
	v_add_co_u32_e32 v14, vcc, s66, v6
	s_nop 1
	v_addc_co_u32_e32 v15, vcc, 0, v7, vcc
	v_add_co_u32_e32 v16, vcc, s67, v6
	s_nop 1
	v_addc_co_u32_e32 v17, vcc, 0, v7, vcc
	v_add_co_u32_e32 v18, vcc, s68, v6
	s_nop 1
	v_addc_co_u32_e32 v19, vcc, 0, v7, vcc
	v_add_co_u32_e32 v20, vcc, s69, v6
	s_nop 1
	v_addc_co_u32_e32 v21, vcc, 0, v7, vcc
	v_add_co_u32_e32 v22, vcc, s70, v6
	s_nop 1
	v_addc_co_u32_e32 v23, vcc, 0, v7, vcc
	global_load_dword v37, v[8:9], off offset:1024
	global_load_dword v38, v[10:11], off offset:2048
	global_load_dword v39, v[12:13], off offset:3072
	global_load_dword v32, v[14:15], off
	global_load_dword v33, v[16:17], off offset:1024
	global_load_dword v34, v[18:19], off offset:2048
	global_load_dword v35, v[20:21], off offset:3072
	global_load_dword v28, v[22:23], off
	v_add_co_u32_e32 v8, vcc, s71, v6
	s_nop 1
	v_addc_co_u32_e32 v9, vcc, 0, v7, vcc
	v_add_co_u32_e32 v10, vcc, s72, v6
	s_nop 1
	v_addc_co_u32_e32 v11, vcc, 0, v7, vcc
	v_add_co_u32_e32 v12, vcc, s73, v6
	s_nop 1
	v_addc_co_u32_e32 v13, vcc, 0, v7, vcc
	v_add_co_u32_e32 v14, vcc, s74, v6
	s_nop 1
	v_addc_co_u32_e32 v15, vcc, 0, v7, vcc
	v_add_co_u32_e32 v16, vcc, s75, v6
	s_nop 1
	v_addc_co_u32_e32 v17, vcc, 0, v7, vcc
	v_add_co_u32_e32 v18, vcc, s76, v6
	s_nop 1
	v_addc_co_u32_e32 v19, vcc, 0, v7, vcc
	v_add_co_u32_e32 v20, vcc, s77, v6
	s_nop 1
	v_addc_co_u32_e32 v21, vcc, 0, v7, vcc
	v_add_co_u32_e32 v74, vcc, s78, v6
	s_nop 1
	v_addc_co_u32_e32 v75, vcc, 0, v7, vcc
	global_load_dword v29, v[8:9], off offset:1024
	global_load_dword v30, v[10:11], off offset:2048
	global_load_dword v31, v[12:13], off offset:3072
	global_load_dword v22, v[14:15], off
	global_load_dword v23, v[16:17], off offset:1024
	global_load_dword v24, v[18:19], off offset:2048
	global_load_dword v25, v[20:21], off offset:3072
	s_nop 0
	global_load_dword v18, v[74:75], off
	v_add_co_u32_e32 v8, vcc, s79, v6
	s_nop 1
	v_addc_co_u32_e32 v9, vcc, 0, v7, vcc
	v_add_co_u32_e32 v10, vcc, s80, v6
	s_nop 1
	v_addc_co_u32_e32 v11, vcc, 0, v7, vcc
	v_add_co_u32_e32 v12, vcc, s81, v6
	s_nop 1
	v_addc_co_u32_e32 v13, vcc, 0, v7, vcc
	v_add_co_u32_e32 v14, vcc, s82, v6
	s_nop 1
	v_addc_co_u32_e32 v15, vcc, 0, v7, vcc
	v_add_co_u32_e32 v16, vcc, s83, v6
	s_nop 1
	v_addc_co_u32_e32 v17, vcc, 0, v7, vcc
	v_add_co_u32_e32 v74, vcc, s84, v6
	s_nop 1
	v_addc_co_u32_e32 v75, vcc, 0, v7, vcc
	v_add_co_u32_e32 v80, vcc, s85, v6
	s_nop 1
	v_addc_co_u32_e32 v81, vcc, 0, v7, vcc
	v_add_co_u32_e32 v82, vcc, s86, v6
	s_nop 1
	v_addc_co_u32_e32 v83, vcc, 0, v7, vcc
	global_load_dword v19, v[8:9], off offset:1024
	global_load_dword v20, v[10:11], off offset:2048
	global_load_dword v21, v[12:13], off offset:3072
	s_nop 0
	global_load_dword v14, v[14:15], off
	s_nop 0
	global_load_dword v15, v[16:17], off offset:1024
	s_nop 0
	global_load_dword v16, v[74:75], off offset:2048
	global_load_dword v17, v[80:81], off offset:3072
	global_load_dword v10, v[82:83], off
	v_add_co_u32_e32 v8, vcc, s87, v6
	s_nop 1
	v_addc_co_u32_e32 v9, vcc, 0, v7, vcc
	v_add_co_u32_e32 v12, vcc, s88, v6
	s_nop 1
	v_addc_co_u32_e32 v13, vcc, 0, v7, vcc
	v_add_co_u32_e32 v74, vcc, s89, v6
	s_nop 1
	v_addc_co_u32_e32 v75, vcc, 0, v7, vcc
	v_add_co_u32_e32 v80, vcc, s90, v6
	s_nop 1
	v_addc_co_u32_e32 v81, vcc, 0, v7, vcc
	v_add_co_u32_e32 v82, vcc, s91, v6
	s_nop 1
	v_addc_co_u32_e32 v83, vcc, 0, v7, vcc
	v_add_co_u32_e32 v84, vcc, 0x4d000, v6
	s_nop 1
	v_addc_co_u32_e32 v85, vcc, 0, v7, vcc
	v_add_co_u32_e32 v86, vcc, 0x4e000, v6
	s_nop 1
	v_addc_co_u32_e32 v87, vcc, 0, v7, vcc
	global_load_dword v72, v2, s[0:1]
	global_load_dword v11, v[8:9], off offset:1024
	s_nop 0
	global_load_dword v12, v[12:13], off offset:2048
	s_nop 0
	global_load_dword v13, v[74:75], off offset:3072
	global_load_dword v6, v[80:81], off
	global_load_dword v7, v[82:83], off offset:1024
	global_load_dword v8, v[84:85], off offset:2048
	global_load_dword v9, v[86:87], off offset:3072
	s_mov_b64 s[0:1], -1
	s_cbranch_scc1 .LBB0_87
	s_lshl_b64 s[0:1], s[14:15], 2
	s_add_u32 s0, s16, s0
	s_addc_u32 s1, s17, s1
	global_load_dwordx4 v[80:83], v3, s[0:1]
	s_mov_b64 s[0:1], 0
	s_waitcnt vmcnt(0)
	v_pk_mul_f32 v[68:69], v[72:73], v[80:81]
	v_pk_mul_f32 v[74:75], v[70:71], v[82:83]

; #define LAS __attribute__((address_space(3)))
; #define PIN(i) ((const float*)ldq_(L, (i)))
; __device__ __forceinline__ unsigned pk2(float lo, float hi) { f32x2 v = {lo, hi}; bf16x2_t b = __builtin_convertvector(v, bf16x2_t); return __builtin_bit_cast(unsigned, b); }
; #define PREP_CONV(bit, SRC, Kd, Nd, DST, GK, MODE) if (mask & (bit)) { for (int it = gw; it < ((Kd) / 64) * ((Nd) / 64); it += NGW) transpose_item((SRC), (Kd), (Nd), (bf16_t*)(wl + (DST)), (GK), (MODE), scr, it, lane); }
; __device__ __forceinline__ void transpose_item(const float* W, int K, int N, bf16_t* WT, const float* gk, int mode, LAS float* scr_, int item, int lane) {
;     ...
;     const int nblk = N / 64, kb = item / nblk, nb = item % nblk, k0 = 64 * kb, n0 = 64 * nb;
;     const int sc = (mode == 1) ? (((n0 >> 7) & 1) * DFF + (n0 >> 8) * 128 + (n0 & 127)) : n0;
;     const float* src = W + (size_t)k0 * N + sc + lane;
;     float va[32], vb[32];
; #pragma unroll
;     for (int kp = 0; kp < 32; ++kp) { va[kp] = src[(size_t)(2 * kp) * N]; vb[kp] = src[(size_t)(2 * kp + 1) * N]; }
; #pragma unroll
;     for (int kp = 0; kp < 32; ++kp) {
;         float a = va[kp], b = vb[kp];
;         if (gk) { a *= gk[k0 + 2 * kp]; b *= gk[k0 + 2 * kp + 1]; }
;         scr[kp * 65 + lane] = pk2(a, b);
;     }
;     asm volatile("s_waitcnt lgkmcnt(0)" ::: "memory");
;     const int c = lane & 7;
; #pragma unroll
;     for (int j = 0; j < 8; ++j) { const int r = (lane >> 3) + 8 * j; const LAS unsigned* q = scr + (4 * c) * 65 + r;
;         u32x4 o; o.x = q[0]; o.y = q[65]; o.z = q[130]; o.w = q[195];
;         *(u32x4*)(WT + (size_t)(n0 + r) * K + k0 + 8 * c) = o; }
; __device__ __forceinline__ void prep(const Params& p, LAS unsigned char* L, int wv, int vb, int nvb, int l, int mask) {
;     ...
;     PREP_CONV(PM_WOUT, PIN(I_WOUT) + (size_t)l * DM * DM, DM, DM, WL_OUT, nullptr, 0)
.LBB0_151:
	v_mov_b32_e32 v6, 0
	s_ashr_i32 s0, s58, 31
	v_add_u32_e32 v6, 0, v6
	v_add_u32_e32 v6, 0x20188, v6
	s_lshr_b32 s0, s0, 28
	s_nop 0
	s_add_i32 s0, s58, s0
	s_ashr_i32 s0, s0, 4
	s_lshl_b32 s16, s0, 6
	s_lshl_b32 s0, s0, 10
	s_ashr_i32 s17, s16, 31
	s_sub_i32 s0, s18, s0
	s_lshl_b64 s[14:15], s[16:17], 12
	v_lshl_add_u64 v[16:17], s[16:17], 1, v[4:5]
	s_waitcnt lgkmcnt(0)
	v_readlane_b32 s16, v251, 34
	v_readlane_b32 s1, v251, 35
	s_add_u32 s14, s16, s14
	v_add_u32_e32 v18, s0, v78
	s_addc_u32 s15, s1, s15
	s_ashr_i32 s1, s0, 31
	v_ashrrev_i32_e32 v19, 31, v18
	v_add_u32_e32 v20, 8, v18
	v_add_u32_e32 v22, 16, v18
	v_add_u32_e32 v24, 24, v18
	v_add_u32_e32 v28, 32, v18
	v_add_u32_e32 v30, 40, v18
	v_add_u32_e32 v32, 48, v18
	v_add_u32_e32 v34, 56, v18
	s_lshl_b64 s[0:1], s[0:1], 2
	v_lshlrev_b64 v[18:19], 11, v[18:19]
	v_ashrrev_i32_e32 v21, 31, v20
	v_ashrrev_i32_e32 v23, 31, v22
	v_ashrrev_i32_e32 v25, 31, v24
	v_ashrrev_i32_e32 v29, 31, v28
	v_ashrrev_i32_e32 v31, 31, v30
	v_ashrrev_i32_e32 v33, 31, v32
	v_ashrrev_i32_e32 v35, 31, v34
	s_add_u32 s0, s14, s0
	v_lshl_add_u64 v[6:7], v[16:17], 0, v[18:19]
	v_lshlrev_b64 v[18:19], 11, v[20:21]
	v_lshlrev_b64 v[20:21], 11, v[22:23]
	v_lshlrev_b64 v[22:23], 11, v[24:25]
	v_lshlrev_b64 v[24:25], 11, v[28:29]
	v_lshlrev_b64 v[28:29], 11, v[30:31]
	v_lshlrev_b64 v[30:31], 11, v[32:33]
	v_lshlrev_b64 v[32:33], 11, v[34:35]
	s_addc_u32 s1, s15, s1
	v_lshl_add_u64 v[52:53], v[16:17], 0, v[18:19]
	v_lshl_add_u64 v[54:55], v[16:17], 0, v[20:21]
	v_lshl_add_u64 v[56:57], v[16:17], 0, v[22:23]
	v_lshl_add_u64 v[24:25], v[16:17], 0, v[24:25]
	v_lshl_add_u64 v[58:59], v[16:17], 0, v[28:29]
	v_lshl_add_u64 v[60:61], v[16:17], 0, v[30:31]
	v_lshl_add_u64 v[62:63], v[16:17], 0, v[32:33]
	v_lshl_add_u64 v[16:17], s[0:1], 0, v[2:3]
	v_add_co_u32_e32 v18, vcc, s24, v16
	global_load_dword v79, v2, s[0:1]
	s_nop 0
	v_addc_co_u32_e32 v19, vcc, 0, v17, vcc
	v_add_co_u32_e32 v20, vcc, s25, v16
	s_add_i32 s58, s58, s60
	s_nop 0
	v_addc_co_u32_e32 v21, vcc, 0, v17, vcc
	v_add_co_u32_e32 v22, vcc, s26, v16
	s_add_i32 s18, s18, s19
	s_nop 0
	v_addc_co_u32_e32 v23, vcc, 0, v17, vcc
	v_add_co_u32_e32 v28, vcc, s27, v16
	s_cmpk_lt_i32 s58, 0x100
	s_nop 0
	v_addc_co_u32_e32 v29, vcc, 0, v17, vcc
	v_add_co_u32_e32 v30, vcc, s28, v16
	s_nop 1
	v_addc_co_u32_e32 v31, vcc, 0, v17, vcc
	v_add_co_u32_e32 v32, vcc, s29, v16
	s_nop 1
	v_addc_co_u32_e32 v33, vcc, 0, v17, vcc
	v_add_co_u32_e32 v34, vcc, s30, v16
	s_nop 1
	v_addc_co_u32_e32 v35, vcc, 0, v17, vcc
	v_add_co_u32_e32 v36, vcc, s31, v16
	s_nop 1
	v_addc_co_u32_e32 v37, vcc, 0, v17, vcc
	v_add_co_u32_e32 v38, vcc, s34, v16
	s_nop 1
	v_addc_co_u32_e32 v39, vcc, 0, v17, vcc
	v_add_co_u32_e32 v40, vcc, s35, v16
	s_nop 1
	v_addc_co_u32_e32 v41, vcc, 0, v17, vcc
	v_add_co_u32_e32 v42, vcc, s36, v16
	s_nop 1
	v_addc_co_u32_e32 v43, vcc, 0, v17, vcc
	v_add_co_u32_e32 v44, vcc, s37, v16
	s_nop 1
	v_addc_co_u32_e32 v45, vcc, 0, v17, vcc
	v_add_co_u32_e32 v46, vcc, s38, v16
	s_nop 1
	v_addc_co_u32_e32 v47, vcc, 0, v17, vcc
	v_add_co_u32_e32 v48, vcc, s39, v16
	s_nop 1
	v_addc_co_u32_e32 v49, vcc, 0, v17, vcc
	v_add_co_u32_e32 v50, vcc, s40, v16
	s_nop 1
	v_addc_co_u32_e32 v51, vcc, 0, v17, vcc
	v_add_co_u32_e32 v64, vcc, s41, v16
	s_nop 1
	v_addc_co_u32_e32 v65, vcc, 0, v17, vcc
	v_add_co_u32_e32 v66, vcc, s42, v16
	s_nop 1
	v_addc_co_u32_e32 v67, vcc, 0, v17, vcc
	v_add_co_u32_e32 v68, vcc, s43, v16
	s_nop 1
	v_addc_co_u32_e32 v69, vcc, 0, v17, vcc
	v_add_co_u32_e32 v70, vcc, s44, v16
	s_nop 1
	v_addc_co_u32_e32 v71, vcc, 0, v17, vcc
	v_add_co_u32_e32 v72, vcc, s45, v16
	s_nop 1
	v_addc_co_u32_e32 v73, vcc, 0, v17, vcc
	v_add_co_u32_e32 v74, vcc, s46, v16
	s_nop 1
	v_addc_co_u32_e32 v75, vcc, 0, v17, vcc
	v_add_co_u32_e32 v80, vcc, s47, v16
	s_nop 1
	v_addc_co_u32_e32 v81, vcc, 0, v17, vcc
	v_add_co_u32_e32 v82, vcc, s48, v16
	s_nop 1
	v_addc_co_u32_e32 v83, vcc, 0, v17, vcc
	v_add_co_u32_e32 v84, vcc, s49, v16
	s_nop 1
	v_addc_co_u32_e32 v85, vcc, 0, v17, vcc
	v_add_co_u32_e32 v86, vcc, s50, v16
	s_nop 1
	v_addc_co_u32_e32 v87, vcc, 0, v17, vcc
	v_add_co_u32_e32 v88, vcc, s51, v16
	s_nop 1
	v_addc_co_u32_e32 v89, vcc, 0, v17, vcc
	v_add_co_u32_e32 v90, vcc, s52, v16
	s_nop 1
	v_addc_co_u32_e32 v91, vcc, 0, v17, vcc
	v_add_co_u32_e32 v92, vcc, s53, v16
	s_nop 1
	v_addc_co_u32_e32 v93, vcc, 0, v17, vcc
	v_add_co_u32_e32 v94, vcc, s54, v16
	s_nop 1
	v_addc_co_u32_e32 v95, vcc, 0, v17, vcc
	v_add_co_u32_e32 v96, vcc, s55, v16
	s_nop 1
	v_addc_co_u32_e32 v97, vcc, 0, v17, vcc
	v_add_co_u32_e32 v98, vcc, s56, v16
	s_nop 1
	v_addc_co_u32_e32 v99, vcc, 0, v17, vcc
	v_add_co_u32_e32 v16, vcc, s57, v16
	s_nop 1
	v_addc_co_u32_e32 v17, vcc, 0, v17, vcc
	global_load_dword v100, v[18:19], off offset:-4096
	s_nop 0
	global_load_dword v18, v[18:19], off
	s_nop 0
	global_load_dword v19, v[20:21], off offset:-4096
	s_nop 0
	global_load_dword v20, v[20:21], off
	s_nop 0
	global_load_dword v21, v[22:23], off offset:-4096
	s_nop 0
	global_load_dword v22, v[22:23], off
	s_nop 0
	global_load_dword v23, v[28:29], off offset:-4096
	s_nop 0
	global_load_dword v28, v[28:29], off
	s_nop 0
	global_load_dword v29, v[30:31], off offset:-4096
	s_nop 0
	global_load_dword v30, v[30:31], off
	s_nop 0
	global_load_dword v31, v[32:33], off offset:-4096
	s_nop 0
	global_load_dword v32, v[32:33], off
	s_nop 0
	global_load_dword v33, v[34:35], off offset:-4096
	s_nop 0
	global_load_dword v34, v[34:35], off
	s_nop 0
	global_load_dword v35, v[36:37], off offset:-4096
	s_nop 0
	global_load_dword v36, v[36:37], off
	s_nop 0
	global_load_dword v37, v[38:39], off offset:-4096
	s_nop 0
	global_load_dword v38, v[38:39], off
; #define LAS __attribute__((address_space(3)))
; __device__ __forceinline__ unsigned pk2(float lo, float hi) { f32x2 v = {lo, hi}; bf16x2_t b = __builtin_convertvector(v, bf16x2_t); return __builtin_bit_cast(unsigned, b); }
; __device__ __forceinline__ void transpose_item(const float* W, int K, int N, bf16_t* WT, const float* gk, int mode, LAS float* scr_, int item, int lane) {
;     ...
;     for (int kp = 0; kp < 32; ++kp) { va[kp] = src[(size_t)(2 * kp) * N]; vb[kp] = src[(size_t)(2 * kp + 1) * N]; }
; #pragma unroll
;     for (int kp = 0; kp < 32; ++kp) {
;         float a = va[kp], b = vb[kp];
;         if (gk) { a *= gk[k0 + 2 * kp]; b *= gk[k0 + 2 * kp + 1]; }
;         scr[kp * 65 + lane] = pk2(a, b);
;     }
;     asm volatile("s_waitcnt lgkmcnt(0)" ::: "memory");
;     const int c = lane & 7;
; #pragma unroll
;     for (int j = 0; j < 8; ++j) { const int r = (lane >> 3) + 8 * j; const LAS unsigned* q = scr + (4 * c) * 65 + r;
;         u32x4 o; o.x = q[0]; o.y = q[65]; o.z = q[130]; o.w = q[195];
;         *(u32x4*)(WT + (size_t)(n0 + r) * K + k0 + 8 * c) = o; }
;     asm volatile("s_waitcnt lgkmcnt(0)" ::: "memory");
	s_nop 0
	global_load_dword v39, v[40:41], off offset:-4096
	s_nop 0
	global_load_dword v40, v[40:41], off
	s_nop 0
	global_load_dword v41, v[42:43], off offset:-4096
	s_nop 0
	global_load_dword v42, v[42:43], off
	s_nop 0
	global_load_dword v43, v[44:45], off offset:-4096
	s_nop 0
	global_load_dword v44, v[44:45], off
	s_nop 0
	global_load_dword v45, v[46:47], off offset:-4096
	s_nop 0
	global_load_dword v46, v[46:47], off
	s_nop 0
	global_load_dword v47, v[48:49], off offset:-4096
	s_nop 0
	global_load_dword v48, v[48:49], off
	s_nop 0
	global_load_dword v49, v[50:51], off offset:-4096
	s_nop 0
	global_load_dword v50, v[50:51], off
	s_nop 0
	global_load_dword v51, v[64:65], off offset:-4096
	s_nop 0
	global_load_dword v64, v[64:65], off
	s_nop 0
	global_load_dword v65, v[66:67], off offset:-4096
	s_nop 0
	global_load_dword v66, v[66:67], off
	s_nop 0
	global_load_dword v67, v[68:69], off offset:-4096
	s_nop 0
	global_load_dword v68, v[68:69], off
	s_nop 0
	global_load_dword v69, v[70:71], off offset:-4096
	s_nop 0
	global_load_dword v70, v[70:71], off
	s_nop 0
	global_load_dword v71, v[72:73], off offset:-4096
	s_nop 0
	global_load_dword v72, v[72:73], off
	s_nop 0
	global_load_dword v73, v[74:75], off offset:-4096
	s_nop 0
	global_load_dword v74, v[74:75], off
	s_nop 0
	global_load_dword v75, v[80:81], off offset:-4096
	s_nop 0
	global_load_dword v80, v[80:81], off
	s_nop 0
	global_load_dword v81, v[82:83], off offset:-4096
	s_nop 0
	global_load_dword v82, v[82:83], off
	s_nop 0
	global_load_dword v83, v[84:85], off offset:-4096
	s_nop 0
	global_load_dword v84, v[84:85], off
	s_nop 0
	global_load_dword v85, v[86:87], off offset:-4096
	s_nop 0
	global_load_dword v86, v[86:87], off
	s_nop 0
	global_load_dword v87, v[88:89], off offset:-4096
	s_nop 0
	global_load_dword v88, v[88:89], off
	s_nop 0
	global_load_dword v89, v[90:91], off offset:-4096
	s_nop 0
	global_load_dword v90, v[90:91], off
	s_nop 0
	global_load_dword v91, v[92:93], off offset:-4096
	s_nop 0
	global_load_dword v92, v[92:93], off
	s_nop 0
	global_load_dword v93, v[94:95], off offset:-4096
	s_nop 0
	global_load_dword v94, v[94:95], off
	s_nop 0
	global_load_dword v95, v[96:97], off offset:-4096
	s_nop 0
	global_load_dword v96, v[96:97], off
	s_nop 0
	global_load_dword v97, v[98:99], off offset:-4096
	s_nop 0
	global_load_dword v98, v[98:99], off
	s_nop 0
	global_load_dword v16, v[16:17], off
	s_waitcnt vmcnt(62)
	v_cvt_pk_bf16_f32 v17, v79, v100
	s_waitcnt vmcnt(60)
	v_cvt_pk_bf16_f32 v18, v18, v19
	s_waitcnt vmcnt(58)
	v_cvt_pk_bf16_f32 v19, v20, v21
	s_waitcnt vmcnt(56)
	v_cvt_pk_bf16_f32 v20, v22, v23
	s_waitcnt vmcnt(54)
	v_cvt_pk_bf16_f32 v21, v28, v29
	s_waitcnt vmcnt(52)
	v_cvt_pk_bf16_f32 v22, v30, v31
	s_waitcnt vmcnt(50)
	v_cvt_pk_bf16_f32 v23, v32, v33
	s_waitcnt vmcnt(48)
	v_cvt_pk_bf16_f32 v28, v34, v35
	s_waitcnt vmcnt(46)
	v_cvt_pk_bf16_f32 v29, v36, v37
	s_waitcnt vmcnt(44)
	v_cvt_pk_bf16_f32 v30, v38, v39
	s_waitcnt vmcnt(42)
	v_cvt_pk_bf16_f32 v31, v40, v41
	s_waitcnt vmcnt(40)
	v_cvt_pk_bf16_f32 v32, v42, v43
	s_waitcnt vmcnt(38)
	v_cvt_pk_bf16_f32 v33, v44, v45
	s_waitcnt vmcnt(36)
	v_cvt_pk_bf16_f32 v34, v46, v47
	s_waitcnt vmcnt(34)
	v_cvt_pk_bf16_f32 v35, v48, v49
	s_waitcnt vmcnt(32)
	v_cvt_pk_bf16_f32 v36, v50, v51
	s_waitcnt vmcnt(30)
	v_cvt_pk_bf16_f32 v37, v64, v65
	s_waitcnt vmcnt(28)
	v_cvt_pk_bf16_f32 v38, v66, v67
	s_waitcnt vmcnt(26)
	v_cvt_pk_bf16_f32 v39, v68, v69
	s_waitcnt vmcnt(24)
	v_cvt_pk_bf16_f32 v40, v70, v71
	s_waitcnt vmcnt(22)
	v_cvt_pk_bf16_f32 v41, v72, v73
	s_waitcnt vmcnt(20)
	v_cvt_pk_bf16_f32 v42, v74, v75
	s_waitcnt vmcnt(18)
	v_cvt_pk_bf16_f32 v43, v80, v81
	s_waitcnt vmcnt(16)
	v_cvt_pk_bf16_f32 v44, v82, v83
	s_waitcnt vmcnt(14)
	v_cvt_pk_bf16_f32 v45, v84, v85
	s_waitcnt vmcnt(12)
	v_cvt_pk_bf16_f32 v46, v86, v87
	s_waitcnt vmcnt(10)
	v_cvt_pk_bf16_f32 v47, v88, v89
	s_waitcnt vmcnt(8)
	v_cvt_pk_bf16_f32 v48, v90, v91
	s_waitcnt vmcnt(6)
	v_cvt_pk_bf16_f32 v49, v92, v93
	s_waitcnt vmcnt(4)
	v_cvt_pk_bf16_f32 v50, v94, v95
	s_waitcnt vmcnt(2)
	v_cvt_pk_bf16_f32 v51, v96, v97
	s_waitcnt vmcnt(0)
	v_cvt_pk_bf16_f32 v16, v98, v16
	ds_write2_b32 v77, v17, v18 offset1:65
	ds_write2_b32 v77, v19, v20 offset0:130 offset1:195
	ds_write2_b32 v9, v21, v22 offset0:4 offset1:69
	ds_write2_b32 v9, v23, v28 offset0:134 offset1:199
	ds_write2_b32 v10, v29, v30 offset0:8 offset1:73
	ds_write2_b32 v10, v31, v32 offset0:138 offset1:203
	ds_write2_b32 v11, v33, v34 offset0:12 offset1:77
	ds_write2_b32 v11, v35, v36 offset0:142 offset1:207
	ds_write2_b32 v12, v37, v38 offset0:16 offset1:81
	ds_write2_b32 v12, v39, v40 offset0:146 offset1:211
	ds_write2_b32 v13, v41, v42 offset0:20 offset1:85
	ds_write2_b32 v13, v43, v44 offset0:150 offset1:215
	ds_write2_b32 v14, v45, v46 offset0:24 offset1:89
	ds_write2_b32 v14, v47, v48 offset0:154 offset1:219
	ds_write2_b32 v15, v49, v50 offset0:28 offset1:93
	ds_write2_b32 v15, v51, v16 offset0:158 offset1:223
	s_waitcnt lgkmcnt(0)
	ds_read2_b32 v[16:17], v8 offset0:65 offset1:73
	ds_read2_b32 v[40:41], v8 offset0:130 offset1:138
	ds_read2_b32 v[18:19], v8 offset0:195 offset1:203
	ds_read2_b32 v[42:43], v8 offset1:8
	ds_read2_b32 v[44:45], v8 offset0:16 offset1:24
	ds_read2_b32 v[20:21], v8 offset0:81 offset1:89
	ds_read2_b32 v[46:47], v8 offset0:146 offset1:154
	ds_read2_b32 v[22:23], v8 offset0:211 offset1:219
	ds_read2_b32 v[28:29], v8 offset0:97 offset1:105
	ds_read2_b32 v[48:49], v8 offset0:162 offset1:170
	ds_read2_b32 v[30:31], v8 offset0:227 offset1:235
	ds_read2_b32 v[50:51], v8 offset0:32 offset1:40
	ds_read2_b32 v[64:65], v8 offset0:48 offset1:56
	ds_read2_b32 v[32:33], v8 offset0:113 offset1:121
	ds_read2_b32 v[66:67], v8 offset0:178 offset1:186
	ds_read2_b32 v[34:35], v8 offset0:243 offset1:251
	s_waitcnt lgkmcnt(12)
	v_mov_b32_e32 v36, v42
	v_mov_b32_e32 v37, v16
	v_mov_b32_e32 v38, v40
	v_mov_b32_e32 v39, v18
	v_mov_b32_e32 v16, v43
	v_mov_b32_e32 v18, v41
	s_waitcnt lgkmcnt(11)
	v_mov_b32_e32 v40, v44
	s_waitcnt lgkmcnt(10)
	v_mov_b32_e32 v41, v20
	s_waitcnt lgkmcnt(9)
	v_mov_b32_e32 v42, v46
	s_waitcnt lgkmcnt(8)
	v_mov_b32_e32 v43, v22
	v_mov_b32_e32 v20, v45
	v_mov_b32_e32 v22, v47
	s_waitcnt lgkmcnt(4)
	v_mov_b32_e32 v44, v50
	v_mov_b32_e32 v45, v28
	v_mov_b32_e32 v46, v48
	v_mov_b32_e32 v47, v30
	v_mov_b32_e32 v28, v51
	v_mov_b32_e32 v30, v49
	s_waitcnt lgkmcnt(3)
	v_mov_b32_e32 v48, v64
	s_waitcnt lgkmcnt(2)
	v_mov_b32_e32 v49, v32
	s_waitcnt lgkmcnt(1)
	v_mov_b32_e32 v50, v66
	s_waitcnt lgkmcnt(0)
	v_mov_b32_e32 v51, v34
	v_mov_b32_e32 v32, v65
	v_mov_b32_e32 v34, v67
	global_store_dwordx4 v[6:7], v[36:39], off
	global_store_dwordx4 v[52:53], v[16:19], off
	global_store_dwordx4 v[54:55], v[40:43], off
	global_store_dwordx4 v[56:57], v[20:23], off
	global_store_dwordx4 v[24:25], v[44:47], off
	global_store_dwordx4 v[58:59], v[28:31], off
	global_store_dwordx4 v[60:61], v[48:51], off
	global_store_dwordx4 v[62:63], v[32:35], off
	s_waitcnt lgkmcnt(0)
	s_cbranch_scc1 .LBB0_151

; #define PIN(i) ((const float*)ldq_(L, (i)))
; #define PREP_CONV(bit, SRC, Kd, Nd, DST, GK, MODE) if (mask & (bit)) { for (int it = gw; it < ((Kd) / 64) * ((Nd) / 64); it += NGW) transpose_item((SRC), (Kd), (Nd), (bf16_t*)(wl + (DST)), (GK), (MODE), scr, it, lane); }
; __device__ __forceinline__ void transpose_item(const float* W, int K, int N, bf16_t* WT, const float* gk, int mode, LAS float* scr_, int item, int lane) {
;     ...
;     const int nblk = N / 64, kb = item / nblk, nb = item % nblk, k0 = 64 * kb, n0 = 64 * nb;
;     const int sc = (mode == 1) ? (((n0 >> 7) & 1) * DFF + (n0 >> 8) * 128 + (n0 & 127)) : n0;
;     const float* src = W + (size_t)k0 * N + sc + lane;
;     float va[32], vb[32];
; #pragma unroll
;     for (int kp = 0; kp < 32; ++kp) { va[kp] = src[(size_t)(2 * kp) * N]; vb[kp] = src[(size_t)(2 * kp + 1) * N]; }
; __device__ __forceinline__ void prep(const Params& p, LAS unsigned char* L, int wv, int vb, int nvb, int l, int mask) {
;     ...
;     PREP_CONV(PM_FFB_IN, PIN(I_WFFB_IN) + (size_t)l * DM * NFF2, DM, NFF2, WL_FFB_IN, PIN(I_NFFB) + l * DM, 1)
.LBB0_155:
	v_mov_b32_e32 v6, 0
	s_mul_hi_i32 s0, s92, 0x2e8ba2e9
	v_add_u32_e32 v6, 0, v6
	v_add_u32_e32 v6, 0x20198, v6
	s_lshr_b32 s10, s0, 31
	s_ashr_i32 s0, s0, 4
	s_nop 0
	s_add_i32 s15, s0, s10
	s_mul_i32 s0, s15, 0xffffea00
	s_mul_i32 s11, s15, 0xfffff500
	s_add_i32 s93, s18, s0
	s_bfe_i32 s0, s92, 0x10001
	s_add_i32 s11, s24, s11
	s_and_b32 s0, s0, 0xb00
	s_and_b32 s11, s11, 0xffffff80
	s_lshl_b32 s10, s15, 6
	s_add_i32 s0, s0, s11
	s_and_b32 s11, s93, 64
	s_waitcnt lgkmcnt(0)
	v_readlane_b32 s14, v251, 38
	s_or_b32 s0, s0, s11
	s_ashr_i32 s11, s10, 31
	s_mul_i32 s15, s15, 0x160000
	v_readlane_b32 s1, v251, 39
	s_mul_hi_i32 s16, s10, 0x5800
	s_add_u32 s14, s14, s15
	v_mov_b32_e32 v8, 0
	s_addc_u32 s15, s1, s16
	s_ashr_i32 s1, s0, 31
	s_lshl_b64 s[0:1], s[0:1], 2
	v_add_u32_e32 v8, 0, v8
	s_add_u32 s0, s14, s0
	v_add_u32_e32 v6, 0x20190, v8
	s_addc_u32 s1, s15, s1
	ds_read_b64 v[68:69], v6
	v_lshl_add_u64 v[6:7], s[0:1], 0, v[2:3]
	v_add_co_u32_e32 v8, vcc, s26, v6
	s_waitcnt lgkmcnt(0)
	v_readfirstlane_b32 s15, v69
	v_addc_co_u32_e32 v9, vcc, 0, v7, vcc
	v_add_co_u32_e32 v10, vcc, s27, v6
	v_readfirstlane_b32 s14, v68
	s_nop 0
	v_addc_co_u32_e32 v11, vcc, 0, v7, vcc
	v_add_co_u32_e32 v12, vcc, s28, v6
	s_cmp_lg_u64 s[14:15], 0
	s_nop 0
	v_addc_co_u32_e32 v13, vcc, 0, v7, vcc
	v_add_co_u32_e32 v14, vcc, s29, v6
	s_cselect_b64 s[16:17], -1, 0
	s_nop 0
	v_addc_co_u32_e32 v15, vcc, 0, v7, vcc
	v_add_co_u32_e32 v16, vcc, s30, v6
	s_cmp_eq_u64 s[14:15], 0
	s_nop 0
	v_addc_co_u32_e32 v17, vcc, 0, v7, vcc
	v_add_co_u32_e32 v18, vcc, s31, v6
	s_nop 1
	v_addc_co_u32_e32 v19, vcc, 0, v7, vcc
	v_add_co_u32_e32 v20, vcc, s34, v6
	s_nop 1
	v_addc_co_u32_e32 v21, vcc, 0, v7, vcc
	v_add_co_u32_e32 v22, vcc, s35, v6
	s_nop 1
	v_addc_co_u32_e32 v23, vcc, 0, v7, vcc
	global_load_dword v73, v[8:9], off offset:2048
	global_load_dword v70, v[10:11], off
	global_load_dword v71, v[12:13], off offset:2048
	global_load_dword v64, v[14:15], off
	global_load_dword v65, v[16:17], off offset:2048
	global_load_dword v66, v[18:19], off
	global_load_dword v67, v[20:21], off offset:2048
	global_load_dword v60, v[22:23], off
	v_add_co_u32_e32 v8, vcc, s36, v6
	s_nop 1
	v_addc_co_u32_e32 v9, vcc, 0, v7, vcc
	v_add_co_u32_e32 v10, vcc, s37, v6
	s_nop 1
	v_addc_co_u32_e32 v11, vcc, 0, v7, vcc
	v_add_co_u32_e32 v12, vcc, s38, v6
	s_nop 1
	v_addc_co_u32_e32 v13, vcc, 0, v7, vcc
	v_add_co_u32_e32 v14, vcc, s39, v6
	s_nop 1
	v_addc_co_u32_e32 v15, vcc, 0, v7, vcc
	v_add_co_u32_e32 v16, vcc, s40, v6
	s_nop 1
	v_addc_co_u32_e32 v17, vcc, 0, v7, vcc
	v_add_co_u32_e32 v18, vcc, s41, v6
	s_nop 1
	v_addc_co_u32_e32 v19, vcc, 0, v7, vcc
	v_add_co_u32_e32 v20, vcc, s42, v6
	s_nop 1
	v_addc_co_u32_e32 v21, vcc, 0, v7, vcc
	v_add_co_u32_e32 v22, vcc, s43, v6
	s_nop 1
	v_addc_co_u32_e32 v23, vcc, 0, v7, vcc
	global_load_dword v61, v[8:9], off offset:2048
	global_load_dword v62, v[10:11], off
	global_load_dword v63, v[12:13], off offset:2048
	global_load_dword v56, v[14:15], off
	global_load_dword v57, v[16:17], off offset:2048
	global_load_dword v58, v[18:19], off
	global_load_dword v59, v[20:21], off offset:2048
	global_load_dword v52, v[22:23], off
	v_add_co_u32_e32 v8, vcc, s44, v6
	s_nop 1
	v_addc_co_u32_e32 v9, vcc, 0, v7, vcc
	v_add_co_u32_e32 v10, vcc, s45, v6
	s_nop 1
	v_addc_co_u32_e32 v11, vcc, 0, v7, vcc
	v_add_co_u32_e32 v12, vcc, s46, v6
	s_nop 1
	v_addc_co_u32_e32 v13, vcc, 0, v7, vcc
	v_add_co_u32_e32 v14, vcc, s47, v6
	s_nop 1
	v_addc_co_u32_e32 v15, vcc, 0, v7, vcc
	v_add_co_u32_e32 v16, vcc, s48, v6
	s_nop 1
	v_addc_co_u32_e32 v17, vcc, 0, v7, vcc
	v_add_co_u32_e32 v18, vcc, s49, v6
	s_nop 1
	v_addc_co_u32_e32 v19, vcc, 0, v7, vcc
	v_add_co_u32_e32 v20, vcc, s50, v6
	s_nop 1
	v_addc_co_u32_e32 v21, vcc, 0, v7, vcc
	v_add_co_u32_e32 v22, vcc, s51, v6
	s_nop 1
	v_addc_co_u32_e32 v23, vcc, 0, v7, vcc
	global_load_dword v53, v[8:9], off offset:2048
	global_load_dword v54, v[10:11], off
	global_load_dword v55, v[12:13], off offset:2048
	global_load_dword v48, v[14:15], off
	global_load_dword v49, v[16:17], off offset:2048
	global_load_dword v50, v[18:19], off
	global_load_dword v51, v[20:21], off offset:2048
	global_load_dword v44, v[22:23], off
	v_add_co_u32_e32 v8, vcc, s52, v6
	s_nop 1
	v_addc_co_u32_e32 v9, vcc, 0, v7, vcc
	v_add_co_u32_e32 v10, vcc, s53, v6
	s_nop 1
	v_addc_co_u32_e32 v11, vcc, 0, v7, vcc
	v_add_co_u32_e32 v12, vcc, s54, v6
	s_nop 1
	v_addc_co_u32_e32 v13, vcc, 0, v7, vcc
	v_add_co_u32_e32 v14, vcc, s55, v6
	s_nop 1
	v_addc_co_u32_e32 v15, vcc, 0, v7, vcc
	v_add_co_u32_e32 v16, vcc, s56, v6
	s_nop 1
	v_addc_co_u32_e32 v17, vcc, 0, v7, vcc
	v_add_co_u32_e32 v18, vcc, s57, v6
	s_nop 1
	v_addc_co_u32_e32 v19, vcc, 0, v7, vcc
	v_add_co_u32_e32 v20, vcc, s58, v6
	s_nop 1
	v_addc_co_u32_e32 v21, vcc, 0, v7, vcc
; __device__ __forceinline__ void transpose_item(const float* W, int K, int N, bf16_t* WT, const float* gk, int mode, LAS float* scr_, int item, int lane) {
;     ...
;     for (int kp = 0; kp < 32; ++kp) { va[kp] = src[(size_t)(2 * kp) * N]; vb[kp] = src[(size_t)(2 * kp + 1) * N]; }
; #pragma unroll
;     for (int kp = 0; kp < 32; ++kp) {
;         float a = va[kp], b = vb[kp];
;         if (gk) { a *= gk[k0 + 2 * kp]; b *= gk[k0 + 2 * kp + 1]; }
	v_add_co_u32_e32 v22, vcc, s59, v6
	s_nop 1
	v_addc_co_u32_e32 v23, vcc, 0, v7, vcc
	global_load_dword v45, v[8:9], off offset:2048
	global_load_dword v46, v[10:11], off
	global_load_dword v47, v[12:13], off offset:2048
	global_load_dword v40, v[14:15], off
	global_load_dword v41, v[16:17], off offset:2048
	global_load_dword v42, v[18:19], off
	global_load_dword v43, v[20:21], off offset:2048
	global_load_dword v36, v[22:23], off
	v_add_co_u32_e32 v8, vcc, s62, v6
	s_nop 1
	v_addc_co_u32_e32 v9, vcc, 0, v7, vcc
	v_add_co_u32_e32 v10, vcc, s63, v6
	s_nop 1
	v_addc_co_u32_e32 v11, vcc, 0, v7, vcc
	v_add_co_u32_e32 v12, vcc, s65, v6
	s_nop 1
	v_addc_co_u32_e32 v13, vcc, 0, v7, vcc
	v_add_co_u32_e32 v14, vcc, s66, v6
	s_nop 1
	v_addc_co_u32_e32 v15, vcc, 0, v7, vcc
	v_add_co_u32_e32 v16, vcc, s67, v6
	s_nop 1
	v_addc_co_u32_e32 v17, vcc, 0, v7, vcc
	v_add_co_u32_e32 v18, vcc, s68, v6
	s_nop 1
	v_addc_co_u32_e32 v19, vcc, 0, v7, vcc
	v_add_co_u32_e32 v20, vcc, s69, v6
	s_nop 1
	v_addc_co_u32_e32 v21, vcc, 0, v7, vcc
	v_add_co_u32_e32 v22, vcc, s70, v6
	s_nop 1
	v_addc_co_u32_e32 v23, vcc, 0, v7, vcc
	global_load_dword v37, v[8:9], off offset:2048
	global_load_dword v38, v[10:11], off
	global_load_dword v39, v[12:13], off offset:2048
	global_load_dword v32, v[14:15], off
	global_load_dword v33, v[16:17], off offset:2048
	global_load_dword v34, v[18:19], off
	global_load_dword v35, v[20:21], off offset:2048
	global_load_dword v28, v[22:23], off
	v_add_co_u32_e32 v8, vcc, s71, v6
	s_nop 1
	v_addc_co_u32_e32 v9, vcc, 0, v7, vcc
	v_add_co_u32_e32 v10, vcc, s72, v6
	s_nop 1
	v_addc_co_u32_e32 v11, vcc, 0, v7, vcc
	v_add_co_u32_e32 v12, vcc, s73, v6
	s_nop 1
	v_addc_co_u32_e32 v13, vcc, 0, v7, vcc
	v_add_co_u32_e32 v14, vcc, s74, v6
	s_nop 1
	v_addc_co_u32_e32 v15, vcc, 0, v7, vcc
	v_add_co_u32_e32 v16, vcc, s75, v6
	s_nop 1
	v_addc_co_u32_e32 v17, vcc, 0, v7, vcc
	v_add_co_u32_e32 v18, vcc, s76, v6
	s_nop 1
	v_addc_co_u32_e32 v19, vcc, 0, v7, vcc
	v_add_co_u32_e32 v20, vcc, s77, v6
	s_nop 1
	v_addc_co_u32_e32 v21, vcc, 0, v7, vcc
	v_add_co_u32_e32 v74, vcc, s78, v6
	s_nop 1
	v_addc_co_u32_e32 v75, vcc, 0, v7, vcc
	global_load_dword v29, v[8:9], off offset:2048
	global_load_dword v30, v[10:11], off
	global_load_dword v31, v[12:13], off offset:2048
	global_load_dword v22, v[14:15], off
	global_load_dword v23, v[16:17], off offset:2048
	global_load_dword v24, v[18:19], off
	global_load_dword v25, v[20:21], off offset:2048
	s_nop 0
	global_load_dword v18, v[74:75], off
	v_add_co_u32_e32 v8, vcc, s79, v6
	s_nop 1
	v_addc_co_u32_e32 v9, vcc, 0, v7, vcc
	v_add_co_u32_e32 v10, vcc, s80, v6
	s_nop 1
	v_addc_co_u32_e32 v11, vcc, 0, v7, vcc
	v_add_co_u32_e32 v12, vcc, s81, v6
	s_nop 1
	v_addc_co_u32_e32 v13, vcc, 0, v7, vcc
	v_add_co_u32_e32 v14, vcc, s82, v6
	s_nop 1
	v_addc_co_u32_e32 v15, vcc, 0, v7, vcc
	v_add_co_u32_e32 v16, vcc, s83, v6
	s_nop 1
	v_addc_co_u32_e32 v17, vcc, 0, v7, vcc
	v_add_co_u32_e32 v74, vcc, s84, v6
	s_nop 1
	v_addc_co_u32_e32 v75, vcc, 0, v7, vcc
	v_add_co_u32_e32 v80, vcc, s85, v6
	s_nop 1
	v_addc_co_u32_e32 v81, vcc, 0, v7, vcc
	v_add_co_u32_e32 v82, vcc, s86, v6
	s_nop 1
	v_addc_co_u32_e32 v83, vcc, 0, v7, vcc
	global_load_dword v19, v[8:9], off offset:2048
	global_load_dword v20, v[10:11], off
	global_load_dword v21, v[12:13], off offset:2048
	s_nop 0
	global_load_dword v14, v[14:15], off
	s_nop 0
	global_load_dword v15, v[16:17], off offset:2048
	s_nop 0
	global_load_dword v16, v[74:75], off
	global_load_dword v17, v[80:81], off offset:2048
	global_load_dword v10, v[82:83], off
	v_add_co_u32_e32 v8, vcc, s87, v6
	s_nop 1
	v_addc_co_u32_e32 v9, vcc, 0, v7, vcc
	v_add_co_u32_e32 v12, vcc, s88, v6
	s_nop 1
	v_addc_co_u32_e32 v13, vcc, 0, v7, vcc
	v_add_co_u32_e32 v74, vcc, s89, v6
	s_nop 1
	v_addc_co_u32_e32 v75, vcc, 0, v7, vcc
	v_add_co_u32_e32 v80, vcc, s90, v6
	s_nop 1
	v_addc_co_u32_e32 v81, vcc, 0, v7, vcc
	v_add_co_u32_e32 v82, vcc, s91, v6
	s_nop 1
	v_addc_co_u32_e32 v83, vcc, 0, v7, vcc
	v_add_co_u32_e32 v84, vcc, 0x155000, v6
	s_nop 1
	v_addc_co_u32_e32 v85, vcc, 0, v7, vcc
	v_add_co_u32_e32 v86, vcc, 0x15a000, v6
	s_nop 1
	v_addc_co_u32_e32 v87, vcc, 0, v7, vcc
	global_load_dword v72, v2, s[0:1]
	global_load_dword v11, v[8:9], off offset:2048
	s_nop 0
	global_load_dword v12, v[12:13], off
	s_nop 0
	global_load_dword v13, v[74:75], off offset:2048
	global_load_dword v6, v[80:81], off
	global_load_dword v7, v[82:83], off offset:2048
	global_load_dword v8, v[84:85], off
	global_load_dword v9, v[86:87], off offset:2048
	s_mov_b64 s[0:1], -1
	s_cbranch_scc1 .LBB0_157
	s_lshl_b64 s[0:1], s[10:11], 2
	s_add_u32 s0, s14, s0
	s_addc_u32 s1, s15, s1
	global_load_dwordx4 v[80:83], v3, s[0:1]
	s_mov_b64 s[0:1], 0
	s_waitcnt vmcnt(0)
	v_pk_mul_f32 v[68:69], v[72:73], v[80:81]
	v_pk_mul_f32 v[74:75], v[70:71], v[82:83]

; #define LAS __attribute__((address_space(3)))
; #define PIN(i) ((const float*)ldq_(L, (i)))
; __device__ __forceinline__ unsigned pk2(float lo, float hi) { f32x2 v = {lo, hi}; bf16x2_t b = __builtin_convertvector(v, bf16x2_t); return __builtin_bit_cast(unsigned, b); }
; #define PREP_CONV(bit, SRC, Kd, Nd, DST, GK, MODE) if (mask & (bit)) { for (int it = gw; it < ((Kd) / 64) * ((Nd) / 64); it += NGW) transpose_item((SRC), (Kd), (Nd), (bf16_t*)(wl + (DST)), (GK), (MODE), scr, it, lane); }
; __device__ __forceinline__ void transpose_item(const float* W, int K, int N, bf16_t* WT, const float* gk, int mode, LAS float* scr_, int item, int lane) {
;     ...
;     const int nblk = N / 64, kb = item / nblk, nb = item % nblk, k0 = 64 * kb, n0 = 64 * nb;
;     const int sc = (mode == 1) ? (((n0 >> 7) & 1) * DFF + (n0 >> 8) * 128 + (n0 & 127)) : n0;
;     const float* src = W + (size_t)k0 * N + sc + lane;
;     float va[32], vb[32];
; #pragma unroll
;     for (int kp = 0; kp < 32; ++kp) { va[kp] = src[(size_t)(2 * kp) * N]; vb[kp] = src[(size_t)(2 * kp + 1) * N]; }
; #pragma unroll
;     for (int kp = 0; kp < 32; ++kp) {
;         float a = va[kp], b = vb[kp];
;         if (gk) { a *= gk[k0 + 2 * kp]; b *= gk[k0 + 2 * kp + 1]; }
;         scr[kp * 65 + lane] = pk2(a, b);
;     }
;     asm volatile("s_waitcnt lgkmcnt(0)" ::: "memory");
;     const int c = lane & 7;
; #pragma unroll
;     for (int j = 0; j < 8; ++j) { const int r = (lane >> 3) + 8 * j; const LAS unsigned* q = scr + (4 * c) * 65 + r;
;         u32x4 o; o.x = q[0]; o.y = q[65]; o.z = q[130]; o.w = q[195];
;         *(u32x4*)(WT + (size_t)(n0 + r) * K + k0 + 8 * c) = o; }
; __device__ __forceinline__ void prep(const Params& p, LAS unsigned char* L, int wv, int vb, int nvb, int l, int mask) {
;     ...
;     PREP_CONV(PM_FFB_OUT, PIN(I_WFFB_OUT) + (size_t)l * DFF * DM, DFF, DM, WL_FFB_OUT, nullptr, 0)
.LBB0_221:
	v_mov_b32_e32 v6, 0
	s_ashr_i32 s0, s53, 31
	v_add_u32_e32 v6, 0, v6
	v_add_u32_e32 v6, 0x201a0, v6
	s_lshr_b32 s0, s0, 28
	s_nop 0
	s_add_i32 s0, s53, s0
	s_ashr_i32 s1, s0, 4
	s_lshl_b32 s0, s1, 6
	s_lshl_b32 s6, s1, 10
	s_mul_i32 s7, s1, 0xffd40000
	s_ashr_i32 s1, s0, 31
	s_sub_i32 s6, s15, s6
	s_lshl_b64 s[10:11], s[0:1], 12
	v_lshl_add_u64 v[20:21], s[0:1], 1, v[4:5]
	s_waitcnt lgkmcnt(0)
	v_readlane_b32 s1, v251, 40
	v_readlane_b32 s0, v251, 41
	s_add_u32 s10, s1, s10
	v_add_u32_e32 v18, s7, v9
	s_addc_u32 s11, s0, s11
	s_ashr_i32 s7, s6, 31
	s_lshl_b64 s[0:1], s[6:7], 2
	s_add_u32 s0, s10, s0
	s_addc_u32 s1, s11, s1
	v_ashrrev_i32_e32 v19, 31, v18
	v_lshl_add_u64 v[6:7], s[0:1], 0, v[2:3]
	v_add_u32_e32 v22, 0x5800, v18
	v_add_u32_e32 v24, 0xb000, v18
	v_add_u32_e32 v28, 0x10800, v18
	v_add_u32_e32 v30, 0x16000, v18
	v_add_u32_e32 v32, 0x1b800, v18
	v_add_u32_e32 v34, 0x21000, v18
	v_add_u32_e32 v36, 0x26800, v18
	v_lshl_add_u64 v[52:53], v[18:19], 1, v[20:21]
	v_add_co_u32_e32 v18, vcc, s17, v6
	v_ashrrev_i32_e32 v23, 31, v22
	v_ashrrev_i32_e32 v25, 31, v24
	v_ashrrev_i32_e32 v29, 31, v28
	v_ashrrev_i32_e32 v31, 31, v30
	v_ashrrev_i32_e32 v33, 31, v32
	v_ashrrev_i32_e32 v35, 31, v34
	v_ashrrev_i32_e32 v37, 31, v36
	v_addc_co_u32_e32 v19, vcc, 0, v7, vcc
	v_lshl_add_u64 v[54:55], v[22:23], 1, v[20:21]
	v_lshl_add_u64 v[56:57], v[24:25], 1, v[20:21]
	v_lshl_add_u64 v[58:59], v[28:29], 1, v[20:21]
	v_lshl_add_u64 v[60:61], v[30:31], 1, v[20:21]
	v_lshl_add_u64 v[62:63], v[32:33], 1, v[20:21]
	v_lshl_add_u64 v[64:65], v[34:35], 1, v[20:21]
	v_lshl_add_u64 v[66:67], v[36:37], 1, v[20:21]
	v_add_co_u32_e32 v20, vcc, s18, v6
	global_load_dword v17, v2, s[0:1]
	s_nop 0
	v_addc_co_u32_e32 v21, vcc, 0, v7, vcc
	v_add_co_u32_e32 v22, vcc, s19, v6
	s_add_i32 s53, s53, s60
	s_nop 0
	v_addc_co_u32_e32 v23, vcc, 0, v7, vcc
	v_add_co_u32_e32 v24, vcc, s23, v6
	s_add_i32 s15, s15, s16
	s_nop 0
	v_addc_co_u32_e32 v25, vcc, 0, v7, vcc
	v_add_co_u32_e32 v28, vcc, s24, v6
	s_cmpk_lt_i32 s53, 0x2c0
	s_nop 0
	v_addc_co_u32_e32 v29, vcc, 0, v7, vcc
	v_add_co_u32_e32 v30, vcc, s25, v6
	v_add_u32_e32 v9, s61, v9
	s_nop 0
	v_addc_co_u32_e32 v31, vcc, 0, v7, vcc
	v_add_co_u32_e32 v32, vcc, s26, v6
	s_nop 1
	v_addc_co_u32_e32 v33, vcc, 0, v7, vcc
	v_add_co_u32_e32 v34, vcc, s27, v6
	s_nop 1
	v_addc_co_u32_e32 v35, vcc, 0, v7, vcc
	v_add_co_u32_e32 v36, vcc, s28, v6
	s_nop 1
	v_addc_co_u32_e32 v37, vcc, 0, v7, vcc
	v_add_co_u32_e32 v38, vcc, s29, v6
	s_nop 1
	v_addc_co_u32_e32 v39, vcc, 0, v7, vcc
	v_add_co_u32_e32 v40, vcc, s30, v6
	s_nop 1
	v_addc_co_u32_e32 v41, vcc, 0, v7, vcc
	v_add_co_u32_e32 v42, vcc, s31, v6
	s_nop 1
	v_addc_co_u32_e32 v43, vcc, 0, v7, vcc
	v_add_co_u32_e32 v44, vcc, s34, v6
	s_nop 1
	v_addc_co_u32_e32 v45, vcc, 0, v7, vcc
	v_add_co_u32_e32 v46, vcc, s35, v6
	s_nop 1
	v_addc_co_u32_e32 v47, vcc, 0, v7, vcc
	v_add_co_u32_e32 v48, vcc, s36, v6
	s_nop 1
	v_addc_co_u32_e32 v49, vcc, 0, v7, vcc
	v_add_co_u32_e32 v50, vcc, s37, v6
	s_nop 1
	v_addc_co_u32_e32 v51, vcc, 0, v7, vcc
	v_add_co_u32_e32 v68, vcc, s38, v6
	s_nop 1
	v_addc_co_u32_e32 v69, vcc, 0, v7, vcc
	v_add_co_u32_e32 v70, vcc, s39, v6
	s_nop 1
	v_addc_co_u32_e32 v71, vcc, 0, v7, vcc
	v_add_co_u32_e32 v72, vcc, s40, v6
	s_nop 1
	v_addc_co_u32_e32 v73, vcc, 0, v7, vcc
	v_add_co_u32_e32 v74, vcc, s41, v6
	s_nop 1
	v_addc_co_u32_e32 v75, vcc, 0, v7, vcc
	v_add_co_u32_e32 v80, vcc, s42, v6
	s_nop 1
	v_addc_co_u32_e32 v81, vcc, 0, v7, vcc
	v_add_co_u32_e32 v82, vcc, s14, v6
	s_nop 1
	v_addc_co_u32_e32 v83, vcc, 0, v7, vcc
	v_add_co_u32_e32 v84, vcc, s43, v6
	s_nop 1
	v_addc_co_u32_e32 v85, vcc, 0, v7, vcc
	v_add_co_u32_e32 v86, vcc, s44, v6
	s_nop 1
	v_addc_co_u32_e32 v87, vcc, 0, v7, vcc
	v_add_co_u32_e32 v88, vcc, s45, v6
	s_nop 1
	v_addc_co_u32_e32 v89, vcc, 0, v7, vcc
	v_add_co_u32_e32 v90, vcc, s46, v6
	s_nop 1
	v_addc_co_u32_e32 v91, vcc, 0, v7, vcc
	v_add_co_u32_e32 v92, vcc, s47, v6
	s_nop 1
	v_addc_co_u32_e32 v93, vcc, 0, v7, vcc
	v_add_co_u32_e32 v94, vcc, s48, v6
	s_nop 1
	v_addc_co_u32_e32 v95, vcc, 0, v7, vcc
	v_add_co_u32_e32 v96, vcc, s49, v6
	s_nop 1
	v_addc_co_u32_e32 v97, vcc, 0, v7, vcc
	v_add_co_u32_e32 v98, vcc, s50, v6
	s_nop 1
	v_addc_co_u32_e32 v99, vcc, 0, v7, vcc
	v_add_co_u32_e32 v100, vcc, s51, v6
	s_nop 1
	v_addc_co_u32_e32 v101, vcc, 0, v7, vcc
	v_add_co_u32_e32 v6, vcc, s52, v6
	s_nop 1
	v_addc_co_u32_e32 v7, vcc, 0, v7, vcc
	global_load_dword v79, v[18:19], off offset:-4096
	s_nop 0
	global_load_dword v18, v[18:19], off
	s_nop 0
	global_load_dword v19, v[20:21], off offset:-4096
	s_nop 0
	global_load_dword v20, v[20:21], off
	s_nop 0
	global_load_dword v21, v[22:23], off offset:-4096
	s_nop 0
	global_load_dword v22, v[22:23], off
	s_nop 0
	global_load_dword v23, v[24:25], off offset:-4096
	s_nop 0
	global_load_dword v24, v[24:25], off
	s_nop 0
	global_load_dword v25, v[28:29], off offset:-4096
	s_nop 0
	global_load_dword v28, v[28:29], off
	s_nop 0
	global_load_dword v29, v[30:31], off offset:-4096
	s_nop 0
	global_load_dword v30, v[30:31], off
	s_nop 0
	global_load_dword v31, v[32:33], off offset:-4096
	s_nop 0
	global_load_dword v32, v[32:33], off
	s_nop 0
	global_load_dword v33, v[34:35], off offset:-4096
	s_nop 0
	global_load_dword v34, v[34:35], off
	s_nop 0
	global_load_dword v35, v[36:37], off offset:-4096
	s_nop 0
	global_load_dword v36, v[36:37], off
	s_nop 0
	global_load_dword v37, v[38:39], off offset:-4096
	s_nop 0
	global_load_dword v38, v[38:39], off
	s_nop 0
	global_load_dword v39, v[40:41], off offset:-4096
	s_nop 0
	global_load_dword v40, v[40:41], off
	s_nop 0
	global_load_dword v41, v[42:43], off offset:-4096
	s_nop 0
; #define LAS __attribute__((address_space(3)))
; __device__ __forceinline__ unsigned pk2(float lo, float hi) { f32x2 v = {lo, hi}; bf16x2_t b = __builtin_convertvector(v, bf16x2_t); return __builtin_bit_cast(unsigned, b); }
; __device__ __forceinline__ void transpose_item(const float* W, int K, int N, bf16_t* WT, const float* gk, int mode, LAS float* scr_, int item, int lane) {
;     ...
;     for (int kp = 0; kp < 32; ++kp) { va[kp] = src[(size_t)(2 * kp) * N]; vb[kp] = src[(size_t)(2 * kp + 1) * N]; }
; #pragma unroll
;     for (int kp = 0; kp < 32; ++kp) {
;         float a = va[kp], b = vb[kp];
;         if (gk) { a *= gk[k0 + 2 * kp]; b *= gk[k0 + 2 * kp + 1]; }
;         scr[kp * 65 + lane] = pk2(a, b);
;     }
;     asm volatile("s_waitcnt lgkmcnt(0)" ::: "memory");
;     const int c = lane & 7;
; #pragma unroll
;     for (int j = 0; j < 8; ++j) { const int r = (lane >> 3) + 8 * j; const LAS unsigned* q = scr + (4 * c) * 65 + r;
;         u32x4 o; o.x = q[0]; o.y = q[65]; o.z = q[130]; o.w = q[195];
;         *(u32x4*)(WT + (size_t)(n0 + r) * K + k0 + 8 * c) = o; }
;     asm volatile("s_waitcnt lgkmcnt(0)" ::: "memory");
	global_load_dword v42, v[42:43], off
	s_nop 0
	global_load_dword v43, v[44:45], off offset:-4096
	s_nop 0
	global_load_dword v44, v[44:45], off
	s_nop 0
	global_load_dword v45, v[46:47], off offset:-4096
	s_nop 0
	global_load_dword v46, v[46:47], off
	s_nop 0
	global_load_dword v47, v[48:49], off offset:-4096
	s_nop 0
	global_load_dword v48, v[48:49], off
	s_nop 0
	global_load_dword v49, v[50:51], off offset:-4096
	s_nop 0
	global_load_dword v50, v[50:51], off
	s_nop 0
	global_load_dword v51, v[68:69], off offset:-4096
	s_nop 0
	global_load_dword v68, v[68:69], off
	s_nop 0
	global_load_dword v69, v[70:71], off offset:-4096
	s_nop 0
	global_load_dword v70, v[70:71], off
	s_nop 0
	global_load_dword v71, v[72:73], off offset:-4096
	s_nop 0
	global_load_dword v72, v[72:73], off
	s_nop 0
	global_load_dword v73, v[74:75], off offset:-4096
	s_nop 0
	global_load_dword v74, v[74:75], off
	s_nop 0
	global_load_dword v75, v[80:81], off offset:-4096
	s_nop 0
	global_load_dword v80, v[80:81], off
	s_nop 0
	global_load_dword v81, v[82:83], off offset:-4096
	s_nop 0
	global_load_dword v82, v[82:83], off
	s_nop 0
	global_load_dword v83, v[84:85], off offset:-4096
	s_nop 0
	global_load_dword v84, v[84:85], off
	s_nop 0
	global_load_dword v85, v[86:87], off offset:-4096
	s_nop 0
	global_load_dword v86, v[86:87], off
	s_nop 0
	global_load_dword v87, v[88:89], off offset:-4096
	s_nop 0
	global_load_dword v88, v[88:89], off
	s_nop 0
	global_load_dword v89, v[90:91], off offset:-4096
	s_nop 0
	global_load_dword v90, v[90:91], off
	s_nop 0
	global_load_dword v91, v[92:93], off offset:-4096
	s_nop 0
	global_load_dword v92, v[92:93], off
	s_nop 0
	global_load_dword v93, v[94:95], off offset:-4096
	s_nop 0
	global_load_dword v94, v[94:95], off
	s_nop 0
	global_load_dword v95, v[96:97], off offset:-4096
	s_nop 0
	global_load_dword v96, v[96:97], off
	s_nop 0
	global_load_dword v97, v[98:99], off offset:-4096
	s_nop 0
	global_load_dword v98, v[98:99], off
	s_nop 0
	global_load_dword v99, v[100:101], off offset:-4096
	s_nop 0
	global_load_dword v100, v[100:101], off
	s_nop 0
	global_load_dword v6, v[6:7], off
	s_waitcnt vmcnt(62)
	v_cvt_pk_bf16_f32 v7, v17, v79
	s_waitcnt vmcnt(60)
	v_cvt_pk_bf16_f32 v17, v18, v19
	s_waitcnt vmcnt(58)
	v_cvt_pk_bf16_f32 v18, v20, v21
	s_waitcnt vmcnt(56)
	v_cvt_pk_bf16_f32 v19, v22, v23
	s_waitcnt vmcnt(54)
	v_cvt_pk_bf16_f32 v20, v24, v25
	s_waitcnt vmcnt(52)
	v_cvt_pk_bf16_f32 v21, v28, v29
	s_waitcnt vmcnt(50)
	v_cvt_pk_bf16_f32 v22, v30, v31
	s_waitcnt vmcnt(48)
	v_cvt_pk_bf16_f32 v23, v32, v33
	s_waitcnt vmcnt(46)
	v_cvt_pk_bf16_f32 v24, v34, v35
	s_waitcnt vmcnt(44)
	v_cvt_pk_bf16_f32 v25, v36, v37
	s_waitcnt vmcnt(42)
	v_cvt_pk_bf16_f32 v28, v38, v39
	s_waitcnt vmcnt(40)
	v_cvt_pk_bf16_f32 v29, v40, v41
	s_waitcnt vmcnt(38)
	v_cvt_pk_bf16_f32 v30, v42, v43
	s_waitcnt vmcnt(36)
	v_cvt_pk_bf16_f32 v31, v44, v45
	s_waitcnt vmcnt(34)
	v_cvt_pk_bf16_f32 v32, v46, v47
	s_waitcnt vmcnt(32)
	v_cvt_pk_bf16_f32 v33, v48, v49
	s_waitcnt vmcnt(30)
	v_cvt_pk_bf16_f32 v34, v50, v51
	s_waitcnt vmcnt(28)
	v_cvt_pk_bf16_f32 v35, v68, v69
	s_waitcnt vmcnt(26)
	v_cvt_pk_bf16_f32 v36, v70, v71
	s_waitcnt vmcnt(24)
	v_cvt_pk_bf16_f32 v37, v72, v73
	s_waitcnt vmcnt(22)
	v_cvt_pk_bf16_f32 v38, v74, v75
	s_waitcnt vmcnt(20)
	v_cvt_pk_bf16_f32 v39, v80, v81
	s_waitcnt vmcnt(18)
	v_cvt_pk_bf16_f32 v40, v82, v83
	s_waitcnt vmcnt(16)
	v_cvt_pk_bf16_f32 v41, v84, v85
	s_waitcnt vmcnt(14)
	v_cvt_pk_bf16_f32 v42, v86, v87
	s_waitcnt vmcnt(12)
	v_cvt_pk_bf16_f32 v43, v88, v89
	s_waitcnt vmcnt(10)
	v_cvt_pk_bf16_f32 v44, v90, v91
	s_waitcnt vmcnt(8)
	v_cvt_pk_bf16_f32 v45, v92, v93
	s_waitcnt vmcnt(6)
	v_cvt_pk_bf16_f32 v46, v94, v95
	s_waitcnt vmcnt(4)
	v_cvt_pk_bf16_f32 v47, v96, v97
	s_waitcnt vmcnt(2)
	v_cvt_pk_bf16_f32 v48, v98, v99
	s_waitcnt vmcnt(0)
	v_cvt_pk_bf16_f32 v6, v100, v6
	ds_write2_b32 v77, v7, v17 offset1:65
	ds_write2_b32 v77, v18, v19 offset0:130 offset1:195
	ds_write2_b32 v10, v20, v21 offset0:4 offset1:69
	ds_write2_b32 v10, v22, v23 offset0:134 offset1:199
	ds_write2_b32 v11, v24, v25 offset0:8 offset1:73
	ds_write2_b32 v11, v28, v29 offset0:138 offset1:203
	ds_write2_b32 v12, v30, v31 offset0:12 offset1:77
	ds_write2_b32 v12, v32, v33 offset0:142 offset1:207
	ds_write2_b32 v13, v34, v35 offset0:16 offset1:81
	ds_write2_b32 v13, v36, v37 offset0:146 offset1:211
	ds_write2_b32 v14, v38, v39 offset0:20 offset1:85
	ds_write2_b32 v14, v40, v41 offset0:150 offset1:215
	ds_write2_b32 v15, v42, v43 offset0:24 offset1:89
	ds_write2_b32 v15, v44, v45 offset0:154 offset1:219
	ds_write2_b32 v16, v46, v47 offset0:28 offset1:93
	ds_write2_b32 v16, v48, v6 offset0:158 offset1:223
	s_waitcnt lgkmcnt(0)
	ds_read2_b32 v[18:19], v8 offset0:65 offset1:73
	ds_read2_b32 v[6:7], v8 offset0:130 offset1:138
	ds_read2_b32 v[20:21], v8 offset0:195 offset1:203
	ds_read2_b32 v[40:41], v8 offset1:8
	ds_read2_b32 v[44:45], v8 offset0:16 offset1:24
	ds_read2_b32 v[22:23], v8 offset0:81 offset1:89
	ds_read2_b32 v[46:47], v8 offset0:146 offset1:154
	ds_read2_b32 v[24:25], v8 offset0:211 offset1:219
	ds_read2_b32 v[28:29], v8 offset0:97 offset1:105
	ds_read2_b32 v[48:49], v8 offset0:162 offset1:170
	ds_read2_b32 v[30:31], v8 offset0:227 offset1:235
	ds_read2_b32 v[50:51], v8 offset0:32 offset1:40
	ds_read2_b32 v[68:69], v8 offset0:48 offset1:56
	ds_read2_b32 v[32:33], v8 offset0:113 offset1:121
	ds_read2_b32 v[70:71], v8 offset0:178 offset1:186
	ds_read2_b32 v[34:35], v8 offset0:243 offset1:251
	s_waitcnt lgkmcnt(12)
	v_mov_b32_e32 v36, v40
	v_mov_b32_e32 v37, v18
	v_mov_b32_e32 v38, v6
	v_mov_b32_e32 v39, v20
	v_mov_b32_e32 v18, v41
	v_mov_b32_e32 v20, v7
	s_waitcnt lgkmcnt(11)
	v_mov_b32_e32 v40, v44
	s_waitcnt lgkmcnt(10)
	v_mov_b32_e32 v41, v22
	s_waitcnt lgkmcnt(9)
	v_mov_b32_e32 v42, v46
	s_waitcnt lgkmcnt(8)
	v_mov_b32_e32 v43, v24
	v_mov_b32_e32 v22, v45
	v_mov_b32_e32 v24, v47
	s_waitcnt lgkmcnt(4)
	v_mov_b32_e32 v44, v50
	v_mov_b32_e32 v45, v28
	v_mov_b32_e32 v46, v48
	v_mov_b32_e32 v47, v30
	v_mov_b32_e32 v28, v51
	v_mov_b32_e32 v30, v49
	s_waitcnt lgkmcnt(3)
	v_mov_b32_e32 v48, v68
	s_waitcnt lgkmcnt(2)
	v_mov_b32_e32 v49, v32
	s_waitcnt lgkmcnt(1)
	v_mov_b32_e32 v50, v70
	s_waitcnt lgkmcnt(0)
	v_mov_b32_e32 v51, v34
	v_mov_b32_e32 v32, v69
	v_mov_b32_e32 v34, v71
	global_store_dwordx4 v[52:53], v[36:39], off
	global_store_dwordx4 v[54:55], v[18:21], off
	global_store_dwordx4 v[56:57], v[40:43], off
	global_store_dwordx4 v[58:59], v[22:25], off
	global_store_dwordx4 v[60:61], v[44:47], off
	global_store_dwordx4 v[62:63], v[28:31], off
	global_store_dwordx4 v[64:65], v[48:51], off
	global_store_dwordx4 v[66:67], v[32:35], off
	s_waitcnt lgkmcnt(0)
	s_cbranch_scc1 .LBB0_221

; #define PIN(i) ((const float*)ldq_(L, (i)))
; #define PREP_CONV(bit, SRC, Kd, Nd, DST, GK, MODE) if (mask & (bit)) { for (int it = gw; it < ((Kd) / 64) * ((Nd) / 64); it += NGW) transpose_item((SRC), (Kd), (Nd), (bf16_t*)(wl + (DST)), (GK), (MODE), scr, it, lane); }
; __device__ __forceinline__ void transpose_item(const float* W, int K, int N, bf16_t* WT, const float* gk, int mode, LAS float* scr_, int item, int lane) {
;     ...
;     const int nblk = N / 64, kb = item / nblk, nb = item % nblk, k0 = 64 * kb, n0 = 64 * nb;
;     const int sc = (mode == 1) ? (((n0 >> 7) & 1) * DFF + (n0 >> 8) * 128 + (n0 & 127)) : n0;
;     const float* src = W + (size_t)k0 * N + sc + lane;
;     float va[32], vb[32];
; #pragma unroll
;     for (int kp = 0; kp < 32; ++kp) { va[kp] = src[(size_t)(2 * kp) * N]; vb[kp] = src[(size_t)(2 * kp + 1) * N]; }
; #pragma unroll
;     for (int kp = 0; kp < 32; ++kp) {
;         float a = va[kp], b = vb[kp];
;         if (gk) { a *= gk[k0 + 2 * kp]; b *= gk[k0 + 2 * kp + 1]; }
; __device__ __forceinline__ void prep(const Params& p, LAS unsigned char* L, int wv, int vb, int nvb, int l, int mask) {
;     ...
;     PREP_CONV(PM_PEG, PIN(I_WPEG) + (size_t)l * DM * DM, DM, DM, WL_PEG, PIN(I_NPE) + l * DM, 0)
.LBB0_225:
	v_mov_b32_e32 v6, 0
	s_ashr_i32 s0, s52, 31
	v_add_u32_e32 v6, 0, v6
	v_add_u32_e32 v6, 0x201b0, v6
	s_nop 0
	s_lshr_b32 s0, s0, 28
	s_add_i32 s0, s52, s0
	s_ashr_i32 s0, s0, 4
	s_lshl_b32 s6, s0, 6
	s_lshl_b32 s53, s0, 10
	s_ashr_i32 s7, s6, 31
	s_waitcnt lgkmcnt(0)
	v_readlane_b32 s12, v251, 44
	s_sub_i32 s0, s14, s53
	s_lshl_b64 s[10:11], s[6:7], 12
	v_readlane_b32 s1, v251, 45
	s_add_u32 s10, s12, s10
	s_addc_u32 s11, s1, s11
	s_ashr_i32 s1, s0, 31
	v_mov_b32_e32 v8, 0
	s_lshl_b64 s[0:1], s[0:1], 2
	s_add_u32 s0, s10, s0
	v_add_u32_e32 v8, 0, v8
	s_addc_u32 s1, s11, s1
	v_add_u32_e32 v6, 0x201a8, v8
	v_lshl_add_u64 v[8:9], s[0:1], 0, v[2:3]
	v_add_co_u32_e32 v72, vcc, s16, v8
	ds_read_b64 v[68:69], v6
	s_nop 0
	v_addc_co_u32_e32 v73, vcc, 0, v9, vcc
	v_add_co_u32_e32 v74, vcc, s17, v8
	s_waitcnt lgkmcnt(0)
	v_readfirstlane_b32 s11, v69
	v_addc_co_u32_e32 v75, vcc, 0, v9, vcc
	v_add_co_u32_e32 v6, vcc, s18, v8
	v_readfirstlane_b32 s10, v68
	s_nop 0
	v_addc_co_u32_e32 v7, vcc, 0, v9, vcc
	v_add_co_u32_e32 v10, vcc, s19, v8
	s_cmp_lg_u64 s[10:11], 0
	s_nop 0
	v_addc_co_u32_e32 v11, vcc, 0, v9, vcc
	v_add_co_u32_e32 v12, vcc, s23, v8
	s_cselect_b64 s[12:13], -1, 0
	s_nop 0
	v_addc_co_u32_e32 v13, vcc, 0, v9, vcc
	v_add_co_u32_e32 v14, vcc, s24, v8
	s_cmp_eq_u64 s[10:11], 0
	s_nop 0
	v_addc_co_u32_e32 v15, vcc, 0, v9, vcc
	global_load_dword v67, v[6:7], off offset:-4096
	global_load_dword v64, v[6:7], off
	global_load_dword v65, v[10:11], off offset:-4096
	global_load_dword v60, v[10:11], off
	global_load_dword v61, v[12:13], off offset:-4096
	global_load_dword v62, v[12:13], off
	global_load_dword v63, v[14:15], off offset:-4096
	global_load_dword v56, v[14:15], off
	v_add_co_u32_e32 v6, vcc, s25, v8
	s_nop 1
	v_addc_co_u32_e32 v7, vcc, 0, v9, vcc
	v_add_co_u32_e32 v10, vcc, s26, v8
	s_nop 1
	v_addc_co_u32_e32 v11, vcc, 0, v9, vcc
	v_add_co_u32_e32 v12, vcc, s27, v8
	s_nop 1
	v_addc_co_u32_e32 v13, vcc, 0, v9, vcc
	v_add_co_u32_e32 v14, vcc, s28, v8
	s_nop 1
	v_addc_co_u32_e32 v15, vcc, 0, v9, vcc
	global_load_dword v57, v[6:7], off offset:-4096
	global_load_dword v58, v[6:7], off
	global_load_dword v59, v[10:11], off offset:-4096
	global_load_dword v52, v[10:11], off
	global_load_dword v53, v[12:13], off offset:-4096
	global_load_dword v54, v[12:13], off
	global_load_dword v55, v[14:15], off offset:-4096
	global_load_dword v48, v[14:15], off
	v_add_co_u32_e32 v6, vcc, s29, v8
	s_nop 1
	v_addc_co_u32_e32 v7, vcc, 0, v9, vcc
	v_add_co_u32_e32 v10, vcc, s30, v8
	s_nop 1
	v_addc_co_u32_e32 v11, vcc, 0, v9, vcc
	v_add_co_u32_e32 v12, vcc, s31, v8
	s_nop 1
	v_addc_co_u32_e32 v13, vcc, 0, v9, vcc
	v_add_co_u32_e32 v14, vcc, s34, v8
	s_nop 1
	v_addc_co_u32_e32 v15, vcc, 0, v9, vcc
	global_load_dword v49, v[6:7], off offset:-4096
	global_load_dword v50, v[6:7], off
	global_load_dword v51, v[10:11], off offset:-4096
	global_load_dword v44, v[10:11], off
	global_load_dword v45, v[12:13], off offset:-4096
	global_load_dword v46, v[12:13], off
	global_load_dword v47, v[14:15], off offset:-4096
	global_load_dword v40, v[14:15], off
	v_add_co_u32_e32 v6, vcc, s35, v8
	s_nop 1
	v_addc_co_u32_e32 v7, vcc, 0, v9, vcc
	v_add_co_u32_e32 v10, vcc, s36, v8
	s_nop 1
	v_addc_co_u32_e32 v11, vcc, 0, v9, vcc
	v_add_co_u32_e32 v12, vcc, s37, v8
	s_nop 1
	v_addc_co_u32_e32 v13, vcc, 0, v9, vcc
	v_add_co_u32_e32 v14, vcc, s38, v8
	s_nop 1
	v_addc_co_u32_e32 v15, vcc, 0, v9, vcc
	global_load_dword v41, v[6:7], off offset:-4096
	global_load_dword v42, v[6:7], off
	global_load_dword v43, v[10:11], off offset:-4096
	global_load_dword v36, v[10:11], off
	global_load_dword v37, v[12:13], off offset:-4096
	global_load_dword v38, v[12:13], off
	global_load_dword v39, v[14:15], off offset:-4096
	global_load_dword v32, v[14:15], off
	v_add_co_u32_e32 v6, vcc, s39, v8
	s_nop 1
	v_addc_co_u32_e32 v7, vcc, 0, v9, vcc
	v_add_co_u32_e32 v10, vcc, s40, v8
	s_nop 1
	v_addc_co_u32_e32 v11, vcc, 0, v9, vcc
	v_add_co_u32_e32 v12, vcc, s41, v8
	s_nop 1
	v_addc_co_u32_e32 v13, vcc, 0, v9, vcc
	v_add_co_u32_e32 v14, vcc, s42, v8
	s_nop 1
	v_addc_co_u32_e32 v15, vcc, 0, v9, vcc
	global_load_dword v33, v[6:7], off offset:-4096
	global_load_dword v34, v[6:7], off
	global_load_dword v35, v[10:11], off offset:-4096
	global_load_dword v28, v[10:11], off
	global_load_dword v29, v[12:13], off offset:-4096
	global_load_dword v30, v[12:13], off
	global_load_dword v31, v[14:15], off offset:-4096
	global_load_dword v22, v[14:15], off
	v_add_co_u32_e32 v6, vcc, s43, v8
	s_nop 1
	v_addc_co_u32_e32 v7, vcc, 0, v9, vcc
	v_add_co_u32_e32 v10, vcc, s44, v8
	s_nop 1
	v_addc_co_u32_e32 v11, vcc, 0, v9, vcc
	v_add_co_u32_e32 v12, vcc, s45, v8
	s_nop 1
	v_addc_co_u32_e32 v13, vcc, 0, v9, vcc
	v_add_co_u32_e32 v14, vcc, s46, v8
	s_nop 1
	v_addc_co_u32_e32 v15, vcc, 0, v9, vcc
	global_load_dword v23, v[6:7], off offset:-4096
	global_load_dword v24, v[6:7], off
	global_load_dword v25, v[10:11], off offset:-4096
	global_load_dword v18, v[10:11], off
	global_load_dword v19, v[12:13], off offset:-4096
	global_load_dword v20, v[12:13], off
	global_load_dword v21, v[14:15], off offset:-4096
	s_nop 0
	global_load_dword v14, v[14:15], off
	v_add_co_u32_e32 v6, vcc, s47, v8
	s_nop 1
	v_addc_co_u32_e32 v7, vcc, 0, v9, vcc
	v_add_co_u32_e32 v10, vcc, s48, v8
	s_nop 1
	v_addc_co_u32_e32 v11, vcc, 0, v9, vcc
	v_add_co_u32_e32 v12, vcc, s49, v8
	s_nop 1
	v_addc_co_u32_e32 v13, vcc, 0, v9, vcc
	v_add_co_u32_e32 v70, vcc, s50, v8
	s_nop 1
	v_addc_co_u32_e32 v71, vcc, 0, v9, vcc
	v_add_co_u32_e32 v80, vcc, s51, v8
	global_load_dword v15, v[6:7], off offset:-4096
	global_load_dword v16, v[6:7], off
	global_load_dword v17, v[10:11], off offset:-4096
	s_nop 0
	global_load_dword v10, v[10:11], off
	s_nop 0
	global_load_dword v11, v[12:13], off offset:-4096
	s_nop 0
	global_load_dword v12, v[12:13], off
	s_nop 0
	global_load_dword v13, v[70:71], off offset:-4096
	global_load_dword v6, v[70:71], off
	v_addc_co_u32_e32 v81, vcc, 0, v9, vcc
	v_add_co_u32_e32 v82, vcc, 0x3e000, v8
	s_nop 1
	v_addc_co_u32_e32 v83, vcc, 0, v9, vcc
	v_add_co_u32_e32 v84, vcc, 0x3f000, v8
	s_nop 1
	v_addc_co_u32_e32 v85, vcc, 0, v9, vcc
	global_load_dword v70, v2, s[0:1]
	global_load_dword v71, v[72:73], off offset:-4096
	s_nop 0
	global_load_dword v72, v[72:73], off
	s_nop 0
	global_load_dword v73, v[74:75], off offset:-4096
	global_load_dword v66, v[74:75], off
	global_load_dword v7, v[80:81], off
	global_load_dword v8, v[82:83], off
	global_load_dword v9, v[84:85], off
	s_mov_b64 s[0:1], -1
	s_cbranch_scc1 .LBB0_227
	s_lshl_b64 s[0:1], s[6:7], 2
	s_add_u32 s0, s10, s0
	s_addc_u32 s1, s11, s1
	global_load_dwordx4 v[80:83], v3, s[0:1]
	s_mov_b64 s[0:1], 0
	s_waitcnt vmcnt(0)
	v_pk_mul_f32 v[68:69], v[70:71], v[80:81]
	v_pk_mul_f32 v[74:75], v[72:73], v[82:83]

; #define LAS __attribute__((address_space(3)))
; #define PIN(i) ((const float*)ldq_(L, (i)))
; __device__ __forceinline__ unsigned pk2(float lo, float hi) { f32x2 v = {lo, hi}; bf16x2_t b = __builtin_convertvector(v, bf16x2_t); return __builtin_bit_cast(unsigned, b); }
; #define PREP_CONV(bit, SRC, Kd, Nd, DST, GK, MODE) if (mask & (bit)) { for (int it = gw; it < ((Kd) / 64) * ((Nd) / 64); it += NGW) transpose_item((SRC), (Kd), (Nd), (bf16_t*)(wl + (DST)), (GK), (MODE), scr, it, lane); }
; __device__ __forceinline__ void transpose_item(const float* W, int K, int N, bf16_t* WT, const float* gk, int mode, LAS float* scr_, int item, int lane) {
;     ...
;     const int nblk = N / 64, kb = item / nblk, nb = item % nblk, k0 = 64 * kb, n0 = 64 * nb;
;     const int sc = (mode == 1) ? (((n0 >> 7) & 1) * DFF + (n0 >> 8) * 128 + (n0 & 127)) : n0;
;     const float* src = W + (size_t)k0 * N + sc + lane;
;     float va[32], vb[32];
; #pragma unroll
;     for (int kp = 0; kp < 32; ++kp) { va[kp] = src[(size_t)(2 * kp) * N]; vb[kp] = src[(size_t)(2 * kp + 1) * N]; }
; #pragma unroll
;     for (int kp = 0; kp < 32; ++kp) {
;         float a = va[kp], b = vb[kp];
;         if (gk) { a *= gk[k0 + 2 * kp]; b *= gk[k0 + 2 * kp + 1]; }
;         scr[kp * 65 + lane] = pk2(a, b);
;     }
;     asm volatile("s_waitcnt lgkmcnt(0)" ::: "memory");
;     const int c = lane & 7;
; #pragma unroll
;     for (int j = 0; j < 8; ++j) { const int r = (lane >> 3) + 8 * j; const LAS unsigned* q = scr + (4 * c) * 65 + r;
;         u32x4 o; o.x = q[0]; o.y = q[65]; o.z = q[130]; o.w = q[195];
;         *(u32x4*)(WT + (size_t)(n0 + r) * K + k0 + 8 * c) = o; }
; __device__ __forceinline__ void prep(const Params& p, LAS unsigned char* L, int wv, int vb, int nvb, int l, int mask) {
;     ...
;     PREP_CONV(PM_PEU, PIN(I_WPEU) + (size_t)l * PED * DM, PED, DM, WL_PEU, nullptr, 0)
.LBB0_291:
	v_mov_b32_e32 v6, 0
	s_ashr_i32 s0, s50, 31
	v_add_u32_e32 v6, 0, v6
	v_add_u32_e32 v6, 0x201b8, v6
	s_lshr_b32 s0, s0, 28
	s_nop 0
	s_add_i32 s0, s50, s0
	s_ashr_i32 s0, s0, 4
	s_lshl_b32 s10, s0, 6
	s_lshl_b32 s0, s0, 10
	s_ashr_i32 s11, s10, 31
	s_sub_i32 s0, s12, s0
	s_lshl_b64 s[6:7], s[10:11], 12
	v_lshl_add_u64 v[20:21], s[10:11], 1, v[4:5]
	s_waitcnt lgkmcnt(0)
	v_readlane_b32 s10, v251, 46
	v_readlane_b32 s1, v251, 47
	s_add_u32 s6, s10, s6
	v_add_u32_e32 v8, s0, v78
	s_addc_u32 s7, s1, s7
	s_ashr_i32 s1, s0, 31
	v_ashrrev_i32_e32 v9, 31, v8
	v_add_u32_e32 v10, 8, v8
	v_add_u32_e32 v12, 16, v8
	v_add_u32_e32 v14, 24, v8
	v_add_u32_e32 v16, 32, v8
	v_add_u32_e32 v18, 40, v8
	v_add_u32_e32 v32, 48, v8
	v_add_u32_e32 v34, 56, v8
	s_lshl_b64 s[0:1], s[0:1], 2
	v_lshlrev_b64 v[8:9], 9, v[8:9]
	v_ashrrev_i32_e32 v11, 31, v10
	v_ashrrev_i32_e32 v13, 31, v12
	v_ashrrev_i32_e32 v15, 31, v14
	v_ashrrev_i32_e32 v17, 31, v16
	v_ashrrev_i32_e32 v19, 31, v18
	v_ashrrev_i32_e32 v33, 31, v32
	v_ashrrev_i32_e32 v35, 31, v34
	s_add_u32 s0, s6, s0
	v_lshl_add_u64 v[6:7], v[20:21], 0, v[8:9]
	v_lshlrev_b64 v[8:9], 9, v[10:11]
	v_lshlrev_b64 v[10:11], 9, v[12:13]
	v_lshlrev_b64 v[12:13], 9, v[14:15]
	v_lshlrev_b64 v[14:15], 9, v[16:17]
	v_lshlrev_b64 v[16:17], 9, v[18:19]
	v_lshlrev_b64 v[18:19], 9, v[32:33]
	v_lshlrev_b64 v[32:33], 9, v[34:35]
	s_addc_u32 s1, s7, s1
	v_lshl_add_u64 v[8:9], v[20:21], 0, v[8:9]
	v_lshl_add_u64 v[10:11], v[20:21], 0, v[10:11]
	v_lshl_add_u64 v[12:13], v[20:21], 0, v[12:13]
	v_lshl_add_u64 v[14:15], v[20:21], 0, v[14:15]
	v_lshl_add_u64 v[16:17], v[20:21], 0, v[16:17]
	v_lshl_add_u64 v[18:19], v[20:21], 0, v[18:19]
	v_lshl_add_u64 v[20:21], v[20:21], 0, v[32:33]
	v_lshl_add_u64 v[32:33], s[0:1], 0, v[2:3]
	v_add_co_u32_e32 v34, vcc, s14, v32
	global_load_dword v79, v2, s[0:1]
	s_nop 0
	v_addc_co_u32_e32 v35, vcc, 0, v33, vcc
	v_add_co_u32_e32 v36, vcc, s15, v32
	s_add_i32 s50, s50, s60
	s_nop 0
	v_addc_co_u32_e32 v37, vcc, 0, v33, vcc
	v_add_co_u32_e32 v38, vcc, s16, v32
	s_add_i32 s12, s12, s13
	s_nop 0
	v_addc_co_u32_e32 v39, vcc, 0, v33, vcc
	v_add_co_u32_e32 v40, vcc, s17, v32
	s_cmp_lt_i32 s50, 64
	s_nop 0
	v_addc_co_u32_e32 v41, vcc, 0, v33, vcc
	v_add_co_u32_e32 v42, vcc, s18, v32
	s_nop 1
	v_addc_co_u32_e32 v43, vcc, 0, v33, vcc
	v_add_co_u32_e32 v44, vcc, s19, v32
	s_nop 1
	v_addc_co_u32_e32 v45, vcc, 0, v33, vcc
	v_add_co_u32_e32 v46, vcc, s22, v32
	s_nop 1
	v_addc_co_u32_e32 v47, vcc, 0, v33, vcc
	v_add_co_u32_e32 v48, vcc, s23, v32
	s_nop 1
	v_addc_co_u32_e32 v49, vcc, 0, v33, vcc
	v_add_co_u32_e32 v50, vcc, s24, v32
	s_nop 1
	v_addc_co_u32_e32 v51, vcc, 0, v33, vcc
	v_add_co_u32_e32 v52, vcc, s25, v32
	s_nop 1
	v_addc_co_u32_e32 v53, vcc, 0, v33, vcc
	v_add_co_u32_e32 v54, vcc, s26, v32
	s_nop 1
	v_addc_co_u32_e32 v55, vcc, 0, v33, vcc
	v_add_co_u32_e32 v56, vcc, s27, v32
	s_nop 1
	v_addc_co_u32_e32 v57, vcc, 0, v33, vcc
	v_add_co_u32_e32 v58, vcc, s28, v32
	s_nop 1
	v_addc_co_u32_e32 v59, vcc, 0, v33, vcc
	v_add_co_u32_e32 v60, vcc, s29, v32
	s_nop 1
	v_addc_co_u32_e32 v61, vcc, 0, v33, vcc
	v_add_co_u32_e32 v62, vcc, s30, v32
	s_nop 1
	v_addc_co_u32_e32 v63, vcc, 0, v33, vcc
	v_add_co_u32_e32 v64, vcc, s31, v32
	s_nop 1
	v_addc_co_u32_e32 v65, vcc, 0, v33, vcc
	v_add_co_u32_e32 v66, vcc, s34, v32
	s_nop 1
	v_addc_co_u32_e32 v67, vcc, 0, v33, vcc
	v_add_co_u32_e32 v68, vcc, s35, v32
	s_nop 1
	v_addc_co_u32_e32 v69, vcc, 0, v33, vcc
	v_add_co_u32_e32 v70, vcc, s36, v32
	s_nop 1
	v_addc_co_u32_e32 v71, vcc, 0, v33, vcc
	v_add_co_u32_e32 v72, vcc, s37, v32
	s_nop 1
	v_addc_co_u32_e32 v73, vcc, 0, v33, vcc
	v_add_co_u32_e32 v74, vcc, s38, v32
	s_nop 1
	v_addc_co_u32_e32 v75, vcc, 0, v33, vcc
	v_add_co_u32_e32 v80, vcc, s39, v32
	s_nop 1
	v_addc_co_u32_e32 v81, vcc, 0, v33, vcc
	v_add_co_u32_e32 v82, vcc, s40, v32
	s_nop 1
	v_addc_co_u32_e32 v83, vcc, 0, v33, vcc
	v_add_co_u32_e32 v84, vcc, s41, v32
	s_nop 1
	v_addc_co_u32_e32 v85, vcc, 0, v33, vcc
	v_add_co_u32_e32 v86, vcc, s42, v32
	s_nop 1
	v_addc_co_u32_e32 v87, vcc, 0, v33, vcc
	v_add_co_u32_e32 v88, vcc, s43, v32
	s_nop 1
	v_addc_co_u32_e32 v89, vcc, 0, v33, vcc
	v_add_co_u32_e32 v90, vcc, s44, v32
	s_nop 1
	v_addc_co_u32_e32 v91, vcc, 0, v33, vcc
	v_add_co_u32_e32 v92, vcc, s45, v32
	s_nop 1
	v_addc_co_u32_e32 v93, vcc, 0, v33, vcc
	v_add_co_u32_e32 v94, vcc, s46, v32
	s_nop 1
	v_addc_co_u32_e32 v95, vcc, 0, v33, vcc
	v_add_co_u32_e32 v96, vcc, s47, v32
	s_nop 1
	v_addc_co_u32_e32 v97, vcc, 0, v33, vcc
	v_add_co_u32_e32 v98, vcc, s48, v32
	s_nop 1
	v_addc_co_u32_e32 v99, vcc, 0, v33, vcc
	v_add_co_u32_e32 v32, vcc, s49, v32
	s_nop 1
	v_addc_co_u32_e32 v33, vcc, 0, v33, vcc
	global_load_dword v100, v[34:35], off offset:-4096
	global_load_dword v101, v[34:35], off
	global_load_dword v102, v[36:37], off offset:-4096
	global_load_dword v103, v[36:37], off
	global_load_dword v104, v[38:39], off offset:-4096
	global_load_dword v105, v[38:39], off
	global_load_dword v106, v[40:41], off offset:-4096
	global_load_dword v107, v[40:41], off
	global_load_dword v108, v[42:43], off offset:-4096
	global_load_dword v109, v[42:43], off
	global_load_dword v110, v[44:45], off offset:-4096
	global_load_dword v111, v[44:45], off
	global_load_dword v112, v[46:47], off offset:-4096
	global_load_dword v113, v[46:47], off
	global_load_dword v114, v[48:49], off offset:-4096
	global_load_dword v115, v[48:49], off
	global_load_dword v34, v[50:51], off offset:-4096
	global_load_dword v35, v[50:51], off
	global_load_dword v36, v[52:53], off offset:-4096
	global_load_dword v37, v[52:53], off
	global_load_dword v38, v[54:55], off offset:-4096
	global_load_dword v39, v[54:55], off
; #define LAS __attribute__((address_space(3)))
; __device__ __forceinline__ unsigned pk2(float lo, float hi) { f32x2 v = {lo, hi}; bf16x2_t b = __builtin_convertvector(v, bf16x2_t); return __builtin_bit_cast(unsigned, b); }
; __device__ __forceinline__ void transpose_item(const float* W, int K, int N, bf16_t* WT, const float* gk, int mode, LAS float* scr_, int item, int lane) {
;     ...
;     for (int kp = 0; kp < 32; ++kp) { va[kp] = src[(size_t)(2 * kp) * N]; vb[kp] = src[(size_t)(2 * kp + 1) * N]; }
; #pragma unroll
;     for (int kp = 0; kp < 32; ++kp) {
;         float a = va[kp], b = vb[kp];
;         if (gk) { a *= gk[k0 + 2 * kp]; b *= gk[k0 + 2 * kp + 1]; }
;         scr[kp * 65 + lane] = pk2(a, b);
;     }
;     asm volatile("s_waitcnt lgkmcnt(0)" ::: "memory");
;     const int c = lane & 7;
; #pragma unroll
;     for (int j = 0; j < 8; ++j) { const int r = (lane >> 3) + 8 * j; const LAS unsigned* q = scr + (4 * c) * 65 + r;
;         u32x4 o; o.x = q[0]; o.y = q[65]; o.z = q[130]; o.w = q[195];
;         *(u32x4*)(WT + (size_t)(n0 + r) * K + k0 + 8 * c) = o; }
;     asm volatile("s_waitcnt lgkmcnt(0)" ::: "memory");
	global_load_dword v40, v[56:57], off offset:-4096
	global_load_dword v41, v[56:57], off
	global_load_dword v42, v[58:59], off offset:-4096
	global_load_dword v43, v[58:59], off
	global_load_dword v44, v[60:61], off offset:-4096
	global_load_dword v45, v[60:61], off
	global_load_dword v46, v[62:63], off offset:-4096
	global_load_dword v47, v[62:63], off
	global_load_dword v48, v[64:65], off offset:-4096
	global_load_dword v49, v[64:65], off
	global_load_dword v50, v[66:67], off offset:-4096
	global_load_dword v51, v[66:67], off
	global_load_dword v52, v[68:69], off offset:-4096
	global_load_dword v53, v[68:69], off
	global_load_dword v54, v[70:71], off offset:-4096
	global_load_dword v55, v[70:71], off
	global_load_dword v56, v[72:73], off offset:-4096
	global_load_dword v57, v[72:73], off
	global_load_dword v58, v[74:75], off offset:-4096
	global_load_dword v59, v[74:75], off
	global_load_dword v60, v[80:81], off offset:-4096
	global_load_dword v61, v[80:81], off
	global_load_dword v62, v[82:83], off offset:-4096
	global_load_dword v63, v[82:83], off
	global_load_dword v64, v[84:85], off offset:-4096
	global_load_dword v65, v[84:85], off
	global_load_dword v66, v[86:87], off offset:-4096
	global_load_dword v67, v[86:87], off
	global_load_dword v68, v[88:89], off offset:-4096
	global_load_dword v69, v[88:89], off
	global_load_dword v70, v[90:91], off offset:-4096
	global_load_dword v71, v[90:91], off
	global_load_dword v72, v[92:93], off offset:-4096
	global_load_dword v73, v[92:93], off
	global_load_dword v74, v[94:95], off offset:-4096
	global_load_dword v75, v[94:95], off
	global_load_dword v80, v[96:97], off offset:-4096
	global_load_dword v81, v[96:97], off
	global_load_dword v82, v[98:99], off offset:-4096
	global_load_dword v83, v[98:99], off
	global_load_dword v84, v[32:33], off
	s_waitcnt vmcnt(62)
	v_cvt_pk_bf16_f32 v32, v79, v100
	s_waitcnt vmcnt(60)
	v_cvt_pk_bf16_f32 v33, v101, v102
	s_waitcnt vmcnt(58)
	v_cvt_pk_bf16_f32 v79, v103, v104
	s_waitcnt vmcnt(56)
	v_cvt_pk_bf16_f32 v85, v105, v106
	s_waitcnt vmcnt(54)
	v_cvt_pk_bf16_f32 v86, v107, v108
	s_waitcnt vmcnt(52)
	v_cvt_pk_bf16_f32 v87, v109, v110
	s_waitcnt vmcnt(50)
	v_cvt_pk_bf16_f32 v88, v111, v112
	s_waitcnt vmcnt(48)
	v_cvt_pk_bf16_f32 v89, v113, v114
	s_waitcnt vmcnt(46)
	v_cvt_pk_bf16_f32 v34, v115, v34
	s_waitcnt vmcnt(44)
	v_cvt_pk_bf16_f32 v35, v35, v36
	s_waitcnt vmcnt(42)
	v_cvt_pk_bf16_f32 v36, v37, v38
	s_waitcnt vmcnt(40)
	v_cvt_pk_bf16_f32 v37, v39, v40
	s_waitcnt vmcnt(38)
	v_cvt_pk_bf16_f32 v38, v41, v42
	s_waitcnt vmcnt(36)
	v_cvt_pk_bf16_f32 v39, v43, v44
	s_waitcnt vmcnt(34)
	v_cvt_pk_bf16_f32 v40, v45, v46
	s_waitcnt vmcnt(32)
	v_cvt_pk_bf16_f32 v41, v47, v48
	s_waitcnt vmcnt(30)
	v_cvt_pk_bf16_f32 v42, v49, v50
	s_waitcnt vmcnt(28)
	v_cvt_pk_bf16_f32 v43, v51, v52
	s_waitcnt vmcnt(26)
	v_cvt_pk_bf16_f32 v44, v53, v54
	s_waitcnt vmcnt(24)
	v_cvt_pk_bf16_f32 v45, v55, v56
	s_waitcnt vmcnt(22)
	v_cvt_pk_bf16_f32 v46, v57, v58
	s_waitcnt vmcnt(20)
	v_cvt_pk_bf16_f32 v47, v59, v60
	s_waitcnt vmcnt(18)
	v_cvt_pk_bf16_f32 v48, v61, v62
	s_waitcnt vmcnt(16)
	v_cvt_pk_bf16_f32 v49, v63, v64
	s_waitcnt vmcnt(14)
	v_cvt_pk_bf16_f32 v50, v65, v66
	s_waitcnt vmcnt(12)
	v_cvt_pk_bf16_f32 v51, v67, v68
	s_waitcnt vmcnt(10)
	v_cvt_pk_bf16_f32 v52, v69, v70
	s_waitcnt vmcnt(8)
	v_cvt_pk_bf16_f32 v53, v71, v72
	s_waitcnt vmcnt(6)
	v_cvt_pk_bf16_f32 v54, v73, v74
	s_waitcnt vmcnt(4)
	v_cvt_pk_bf16_f32 v55, v75, v80
	s_waitcnt vmcnt(2)
	v_cvt_pk_bf16_f32 v56, v81, v82
	s_waitcnt vmcnt(0)
	v_cvt_pk_bf16_f32 v57, v83, v84
	ds_write2_b32 v77, v32, v33 offset1:65
	ds_write2_b32 v77, v79, v85 offset0:130 offset1:195
	ds_write2_b32 v23, v86, v87 offset0:4 offset1:69
	ds_write2_b32 v23, v88, v89 offset0:134 offset1:199
	ds_write2_b32 v24, v34, v35 offset0:8 offset1:73
	ds_write2_b32 v24, v36, v37 offset0:138 offset1:203
	ds_write2_b32 v25, v38, v39 offset0:12 offset1:77
	ds_write2_b32 v25, v40, v41 offset0:142 offset1:207
	ds_write2_b32 v28, v42, v43 offset0:16 offset1:81
	ds_write2_b32 v28, v44, v45 offset0:146 offset1:211
	ds_write2_b32 v29, v46, v47 offset0:20 offset1:85
	ds_write2_b32 v29, v48, v49 offset0:150 offset1:215
	ds_write2_b32 v30, v50, v51 offset0:24 offset1:89
	ds_write2_b32 v30, v52, v53 offset0:154 offset1:219
	ds_write2_b32 v31, v54, v55 offset0:28 offset1:93
	ds_write2_b32 v31, v56, v57 offset0:158 offset1:223
	s_waitcnt lgkmcnt(0)
	ds_read2_b32 v[32:33], v22 offset0:65 offset1:73
	ds_read2_b32 v[52:53], v22 offset0:130 offset1:138
	ds_read2_b32 v[34:35], v22 offset0:195 offset1:203
	ds_read2_b32 v[54:55], v22 offset1:8
	ds_read2_b32 v[56:57], v22 offset0:16 offset1:24
	ds_read2_b32 v[36:37], v22 offset0:81 offset1:89
	ds_read2_b32 v[58:59], v22 offset0:146 offset1:154
	ds_read2_b32 v[38:39], v22 offset0:211 offset1:219
	ds_read2_b32 v[40:41], v22 offset0:97 offset1:105
	ds_read2_b32 v[60:61], v22 offset0:162 offset1:170
	ds_read2_b32 v[42:43], v22 offset0:227 offset1:235
	ds_read2_b32 v[62:63], v22 offset0:32 offset1:40
	ds_read2_b32 v[64:65], v22 offset0:48 offset1:56
	ds_read2_b32 v[44:45], v22 offset0:113 offset1:121
	ds_read2_b32 v[66:67], v22 offset0:178 offset1:186
	ds_read2_b32 v[46:47], v22 offset0:243 offset1:251
	s_waitcnt lgkmcnt(12)
	v_mov_b32_e32 v48, v54
	v_mov_b32_e32 v49, v32
	v_mov_b32_e32 v50, v52
	v_mov_b32_e32 v51, v34
	v_mov_b32_e32 v32, v55
	v_mov_b32_e32 v34, v53
	s_waitcnt lgkmcnt(11)
	v_mov_b32_e32 v52, v56
	s_waitcnt lgkmcnt(10)
	v_mov_b32_e32 v53, v36
	s_waitcnt lgkmcnt(9)
	v_mov_b32_e32 v54, v58
	s_waitcnt lgkmcnt(8)
	v_mov_b32_e32 v55, v38
	v_mov_b32_e32 v36, v57
	v_mov_b32_e32 v38, v59
	s_waitcnt lgkmcnt(4)
	v_mov_b32_e32 v56, v62
	v_mov_b32_e32 v57, v40
	v_mov_b32_e32 v58, v60
	v_mov_b32_e32 v59, v42
	v_mov_b32_e32 v40, v63
	v_mov_b32_e32 v42, v61
	s_waitcnt lgkmcnt(3)
	v_mov_b32_e32 v60, v64
	s_waitcnt lgkmcnt(2)
	v_mov_b32_e32 v61, v44
	s_waitcnt lgkmcnt(1)
	v_mov_b32_e32 v62, v66
	s_waitcnt lgkmcnt(0)
	v_mov_b32_e32 v63, v46
	v_mov_b32_e32 v44, v65
	v_mov_b32_e32 v46, v67
	global_store_dwordx4 v[6:7], v[48:51], off
	global_store_dwordx4 v[8:9], v[32:35], off
	global_store_dwordx4 v[10:11], v[52:55], off
	global_store_dwordx4 v[12:13], v[36:39], off
	global_store_dwordx4 v[14:15], v[56:59], off
	global_store_dwordx4 v[16:17], v[40:43], off
	global_store_dwordx4 v[18:19], v[60:63], off
	global_store_dwordx4 v[20:21], v[44:47], off
	s_waitcnt lgkmcnt(0)
	s_cbranch_scc1 .LBB0_291

; #define PIN(i) ((const float*)ldq_(L, (i)))
; __device__ __forceinline__ unsigned pk2(float lo, float hi) { f32x2 v = {lo, hi}; bf16x2_t b = __builtin_convertvector(v, bf16x2_t); return __builtin_bit_cast(unsigned, b); }
; __device__ __forceinline__ void prep(const Params& p, LAS unsigned char* L, int wv, int vb, int nvb, int l, int mask) {
;     ...
;     if (mask & PM_POOL) {
;         for (int t = gt; t < 4 * 128 * 16; t += NGT) {
;             const int ko = t & 15, n = (t >> 4) & 127, g = (t >> 11) & 3;
;             const float* src = PIN(I_WPOOL) + ((size_t)(l * 4 + g) * 128 + 8 * ko) * 128 + n; const float sc = PIN(I_PSCALE)[l * 512 + g * 128 + n];
;             u32x4 o; o.x = pk2(src[0] * sc, src[128] * sc); o.y = pk2(src[256] * sc, src[384] * sc); o.z = pk2(src[512] * sc, src[640] * sc); o.w = pk2(src[768] * sc, src[896] * sc);
;             *(u32x4*)((bf16_t*)(wl + WL_POOL) + ((size_t)g * 128 + n) * 128 + 8 * ko) = o;
;         }
;     }
.LBB0_294:
	v_mov_b32_e32 v8, 0
	v_mov_b32_e32 v10, v3
	v_add_u32_e32 v8, 0, v8
	v_add_u32_e32 v8, 0x20178, v8
	s_nop 0
	v_bfe_u32 v20, v6, 11, 2
	v_add_u32_e32 v10, 0, v10
	v_add_u32_e32 v10, 0x20180, v10
	s_nop 0
	v_and_b32_e32 v21, 0x78, v5
	v_lshlrev_b32_e32 v2, 16, v20
	s_waitcnt lgkmcnt(1)
	v_readlane_b32 s17, v251, 31
	v_readlane_b32 s16, v251, 30
	v_bfe_u32 v7, v6, 4, 7
	v_add_u32_e32 v6, s6, v6
	v_lshl_add_u64 v[8:9], s[16:17], 0, v[2:3]
	v_lshlrev_b32_e32 v2, 9, v21
	v_lshl_add_u64 v[8:9], v[8:9], 0, v[2:3]
	v_lshlrev_b32_e32 v2, 2, v7
	v_lshl_add_u64 v[8:9], v[8:9], 0, v[2:3]
	s_waitcnt lgkmcnt(0)
	v_readlane_b32 s17, v251, 33
	v_readlane_b32 s16, v251, 32
	v_lshl_or_b32 v2, v20, 9, v2
	s_nop 3
	global_load_dword v10, v2, s[16:17]
	global_load_dword v12, v[8:9], off
	global_load_dword v13, v[8:9], off offset:512
	global_load_dword v14, v[8:9], off offset:1024
	global_load_dword v15, v[8:9], off offset:1536
	global_load_dword v16, v[8:9], off offset:2048
	global_load_dword v17, v[8:9], off offset:2560
	global_load_dword v18, v[8:9], off offset:3072
	global_load_dword v19, v[8:9], off offset:3584
	v_lshlrev_b32_e32 v2, 8, v7
	v_lshl_or_b32 v2, v20, 15, v2
	v_lshl_add_u64 v[8:9], s[10:11], 0, v[2:3]
	v_lshlrev_b32_e32 v2, 1, v21
	v_cmp_lt_i32_e32 vcc, s14, v6
	v_lshl_add_u64 v[20:21], v[8:9], 0, v[2:3]
	v_add_u32_e32 v5, s7, v5
	s_or_b64 s[12:13], vcc, s[12:13]
	s_waitcnt vmcnt(6)
	v_pk_mul_f32 v[8:9], v[10:11], v[12:13] op_sel_hi:[0,1]
	v_cvt_pk_bf16_f32 v8, v8, v9
	s_waitcnt vmcnt(4)
	v_pk_mul_f32 v[12:13], v[10:11], v[14:15] op_sel_hi:[0,1]
	v_cvt_pk_bf16_f32 v9, v12, v13
	s_waitcnt vmcnt(2)
	v_pk_mul_f32 v[14:15], v[10:11], v[16:17] op_sel_hi:[0,1]
	s_waitcnt vmcnt(0)
	v_pk_mul_f32 v[16:17], v[10:11], v[18:19] op_sel_hi:[0,1]
	v_cvt_pk_bf16_f32 v10, v14, v15
	v_cvt_pk_bf16_f32 v11, v16, v17
	global_store_dwordx4 v[20:21], v[8:11], off
	s_andn2_b64 exec, exec, s[12:13]
	s_cbranch_execnz .LBB0_294

; #define PIN(i) ((const float*)ldq_(L, (i)))
; __device__ __forceinline__ void prep(const Params& p, LAS unsigned char* L, int wv, int vb, int nvb, int l, int mask) {
;     ...
;         for (int t0 = gt; t0 < MT * 32; t0 += 4 * NGT) {
;             f32x4 a[4], b[4]; size_t dsto[4];
; #pragma unroll
;             for (int u = 0; u < 4; ++u) {
;                 const int t = min(t0 + u * NGT, MT * 32 - 1);
;                 const int o8 = t & 31, m = t >> 5;
;                 const float* src = ((m < MP) ? PIN(I_PP) + ((size_t)l * MP + m) * PED : PIN(I_PS) + ((size_t)l * MS + (m - MP)) * PED) + 8 * o8;
;                 a[u] = *(const f32x4*)src; b[u] = *(const f32x4*)(src + 4); dsto[u] = (size_t)m * PED + 8 * o8;
;             }
.LBB0_298:
	v_ashrrev_i32_e32 v30, 5, v36
	v_cmp_lt_i32_e32 vcc, s17, v30
	s_and_saveexec_b64 s[14:15], vcc
	s_xor_b64 s[14:15], exec, s[14:15]
	s_cbranch_execz .LBB0_300
	v_mov_b32_e32 v2, v29
	v_add_u32_e32 v28, 0xffff0000, v30
	v_add_u32_e32 v2, 0, v2
	v_add_u32_e32 v2, 0x20118, v2
	s_nop 0
	v_lshlrev_b64 v[4:5], 10, v[28:29]
	v_mov_b32_e32 v31, v29
	s_waitcnt lgkmcnt(0)
	v_readlane_b32 s23, v251, 7
	v_readlane_b32 s22, v251, 6
	s_nop 1
	v_lshl_add_u64 v[2:3], s[22:23], 0, v[4:5]
.LBB0_300:
	s_andn2_saveexec_b64 s[14:15], s[14:15]
	s_cbranch_execz .LBB0_302
	v_mov_b32_e32 v2, v29
	v_ashrrev_i32_e32 v31, 31, v30
	v_add_u32_e32 v2, 0, v2
	v_add_u32_e32 v2, 0x20110, v2
	s_nop 0
	s_waitcnt lgkmcnt(0)
	v_readlane_b32 s23, v251, 5
	v_readlane_b32 s22, v251, 4
	v_lshlrev_b64 v[2:3], 10, v[30:31]
	s_nop 0
	v_lshl_add_u64 v[2:3], s[22:23], 0, v[2:3]
.LBB0_302:
	s_or_b64 exec, exec, s[14:15]
	v_and_b32_e32 v41, 0xf8, v40
	v_lshlrev_b32_e32 v28, 2, v41
	v_lshl_add_u64 v[10:11], v[2:3], 0, v[28:29]
	global_load_dwordx4 v[2:5], v[10:11], off offset:16
	global_load_dwordx4 v[6:9], v[10:11], off
	v_add_u32_e32 v42, s6, v36
	v_min_i32_e32 v12, 0x20ffff, v42
	v_ashrrev_i32_e32 v32, 5, v12
	v_cmp_lt_i32_e32 vcc, s17, v32
	s_and_saveexec_b64 s[14:15], vcc
	s_xor_b64 s[14:15], exec, s[14:15]
	s_cbranch_execz .LBB0_304
	v_mov_b32_e32 v10, v29
	v_add_u32_e32 v28, 0xffff0000, v32
	v_add_u32_e32 v10, 0, v10
	v_add_u32_e32 v10, 0x20118, v10
	s_nop 0
	v_lshlrev_b64 v[14:15], 10, v[28:29]
	v_mov_b32_e32 v33, v29
	s_waitcnt lgkmcnt(0)
	v_readlane_b32 s23, v251, 7
	v_readlane_b32 s22, v251, 6
	s_nop 1
	v_lshl_add_u64 v[10:11], s[22:23], 0, v[14:15]
.LBB0_304:
	s_andn2_saveexec_b64 s[14:15], s[14:15]
	s_cbranch_execz .LBB0_306
	v_mov_b32_e32 v10, v29
	v_ashrrev_i32_e32 v33, 31, v32
	v_add_u32_e32 v10, 0, v10
	v_add_u32_e32 v10, 0x20110, v10
	s_nop 0
	s_waitcnt lgkmcnt(0)
	v_readlane_b32 s23, v251, 5
	v_readlane_b32 s22, v251, 4
	v_lshlrev_b64 v[10:11], 10, v[32:33]
	s_nop 0
	v_lshl_add_u64 v[10:11], s[22:23], 0, v[10:11]
.LBB0_306:
	s_or_b64 exec, exec, s[14:15]
	v_lshlrev_b32_e32 v12, 3, v12
	v_and_b32_e32 v43, 0xf8, v12
	v_lshlrev_b32_e32 v28, 2, v43
	v_lshl_add_u64 v[18:19], v[10:11], 0, v[28:29]
	global_load_dwordx4 v[10:13], v[18:19], off offset:16
	global_load_dwordx4 v[14:17], v[18:19], off
	v_add_u32_e32 v18, s7, v36
	v_min_i32_e32 v20, 0x20ffff, v18
	v_ashrrev_i32_e32 v34, 5, v20
	v_cmp_lt_i32_e32 vcc, s17, v34
	s_and_saveexec_b64 s[14:15], vcc
	s_xor_b64 s[14:15], exec, s[14:15]
	s_cbranch_execz .LBB0_308
	v_mov_b32_e32 v18, v29
	v_add_u32_e32 v28, 0xffff0000, v34
	v_add_u32_e32 v18, 0, v18
	v_add_u32_e32 v18, 0x20118, v18
	s_nop 0
	v_lshlrev_b64 v[22:23], 10, v[28:29]
	v_mov_b32_e32 v35, v29
	s_waitcnt lgkmcnt(0)
	v_readlane_b32 s23, v251, 7
	v_readlane_b32 s22, v251, 6
	s_nop 1
	v_lshl_add_u64 v[18:19], s[22:23], 0, v[22:23]
.LBB0_308:
	s_andn2_saveexec_b64 s[14:15], s[14:15]
	s_cbranch_execz .LBB0_310
	v_mov_b32_e32 v18, v29
	v_ashrrev_i32_e32 v35, 31, v34
	v_add_u32_e32 v18, 0, v18
	v_add_u32_e32 v18, 0x20110, v18
	s_nop 0
	s_waitcnt lgkmcnt(0)
	v_readlane_b32 s23, v251, 5
	v_readlane_b32 s22, v251, 4
	v_lshlrev_b64 v[18:19], 10, v[34:35]
	s_nop 0
	v_lshl_add_u64 v[18:19], s[22:23], 0, v[18:19]
.LBB0_310:
	s_or_b64 exec, exec, s[14:15]
	v_lshlrev_b32_e32 v20, 3, v20
	v_and_b32_e32 v44, 0xf8, v20
	v_lshlrev_b32_e32 v28, 2, v44
	v_lshl_add_u64 v[38:39], v[18:19], 0, v[28:29]
	global_load_dwordx4 v[18:21], v[38:39], off offset:16
	global_load_dwordx4 v[22:25], v[38:39], off
	v_add_u32_e32 v28, s62, v36
	v_min_i32_e32 v45, 0x20ffff, v28
	v_ashrrev_i32_e32 v36, 5, v45
	v_cmp_lt_i32_e32 vcc, s17, v36
	s_and_saveexec_b64 s[14:15], vcc
	s_xor_b64 s[14:15], exec, s[14:15]
	s_cbranch_execz .LBB0_312
	v_mov_b32_e32 v28, v29
	v_mov_b32_e32 v37, v29
	v_add_u32_e32 v28, 0, v28
	v_add_u32_e32 v28, 0x20118, v28
	s_nop 0
	v_add_u32_e32 v28, 0xffff0000, v36
	v_lshlrev_b64 v[46:47], 10, v[28:29]
	s_waitcnt lgkmcnt(0)
	v_readlane_b32 s23, v251, 7
	v_readlane_b32 s22, v251, 6
	s_nop 1
	v_lshl_add_u64 v[38:39], s[22:23], 0, v[46:47]
.LBB0_312:
	s_andn2_saveexec_b64 s[14:15], s[14:15]
	s_cbranch_execz .LBB0_297
	v_mov_b32_e32 v28, v29
	v_ashrrev_i32_e32 v37, 31, v36
	v_add_u32_e32 v28, 0, v28
	v_add_u32_e32 v28, 0x20110, v28
	s_nop 0
	s_waitcnt lgkmcnt(0)
	v_readlane_b32 s23, v251, 5
	v_readlane_b32 s22, v251, 4
	v_lshlrev_b64 v[38:39], 10, v[36:37]
	s_nop 0
	v_lshl_add_u64 v[38:39], s[22:23], 0, v[38:39]
	s_branch .LBB0_297

; #define PIN(i) ((const float*)ldq_(L, (i)))
; __device__ __forceinline__ void prep(const Params& p, LAS unsigned char* L, int wv, int vb, int nvb, int l, int mask) {
;     ...
;         for (int m0 = 4 * gw; m0 < MT; m0 += 4 * NGW) {
;             const float* xr = (m0 < MP) ? PIN(I_XP) + (size_t)m0 * DM : PIN(I_XS) + (size_t)(m0 - MP) * DM;
.LBB0_342:
	s_cmp_gt_i32 s10, 0xffff
	s_mov_b64 s[34:35], -1
	s_cbranch_scc0 .LBB0_344
	v_mov_b32_e32 v2, 0
	s_add_i32 s12, s10, 0xffff0000
	v_add_u32_e32 v2, 0, v2
	v_add_u32_e32 v2, 0x20108, v2
	s_nop 0
	s_lshl_b64 s[28:29], s[12:13], 12
	s_mov_b32 s12, s10
	s_mov_b64 s[34:35], 0
	s_waitcnt lgkmcnt(0)
	v_readlane_b32 s30, v251, 2
	v_readlane_b32 s31, v251, 3
	s_add_u32 s30, s30, s28
	s_addc_u32 s31, s31, s29
	s_mov_b64 s[28:29], s[12:13]
.LBB0_344:
	s_andn2_b64 vcc, exec, s[34:35]
	s_cbranch_vccnz .LBB0_346
	v_mov_b32_e32 v2, 0
	s_nop 0
	v_add_u32_e32 v2, 0, v2
	v_add_u32_e32 v2, 0x20100, v2
	s_nop 0
	s_waitcnt lgkmcnt(0)
	v_readlane_b32 s28, v251, 0
	v_readlane_b32 s12, v251, 1
	s_add_u32 s30, s28, s16
	s_addc_u32 s31, s12, s17
	s_mov_b64 s[28:29], s[10:11]

; __device__ __forceinline__ int tid_of(int wv) { return wv * 64 + (int)__builtin_amdgcn_mbcnt_hi(~0u, __builtin_amdgcn_mbcnt_lo(~0u, 0u)); }
; #define LAS __attribute__((address_space(3)))
; #define PIN(i) ((const float*)ldq_(L, (i)))
; #define PREP_CONV(bit, SRC, Kd, Nd, DST, GK, MODE) if (mask & (bit)) { for (int it = gw; it < ((Kd) / 64) * ((Nd) / 64); it += NGW) transpose_item((SRC), (Kd), (Nd), (bf16_t*)(wl + (DST)), (GK), (MODE), scr, it, lane); }
; __device__ __forceinline__ void prep(const Params& p, LAS unsigned char* L, int wv, int vb, int nvb, int l, int mask) {
;     int tid_ = tid_of(wv); asm volatile("" : "+v"(tid_));
;     const int tid = tid_, lane = tid & 63, wave = __builtin_amdgcn_readfirstlane(tid >> 6);
;     const int gw = vb * 8 + wave, NGW = nvb * 8; const int gt = vb * 512 + tid, NGT = nvb * 512;
;     LAS float* scr = (LAS float*)(L + wave * 16384);
;     unsigned char* ws = PWS; unsigned char* wl = ws + WS_W + (size_t)l * WL_STRIDE;
;     ...
;     PREP_CONV(PM_FFA_IN, PIN(I_WFFA_IN) + (size_t)l * DM * NFF2, DM, NFF2, WL_FFA_IN, PIN(I_NFFA) + l * DM, 1)
.LBB0_357:
	s_or_b64 exec, exec, s[0:1]
	v_mov_b32_e32 v76, v183
	v_mov_b32_e32 v3, 0
	v_mov_b32_e32 v5, 0
	v_add_u32_e32 v3, 0, v3
	v_add_u32_e32 v3, 0x201c0, v3
	v_readfirstlane_b32 s0, v76
	s_nop 0
	s_ashr_i32 s0, s0, 6
	s_add_i32 s7, s0, s33
	s_lshl_b32 s0, s0, 14
	s_add_i32 s22, s0, 0
	v_and_b32_e32 v2, 63, v76
	s_cmpk_lt_i32 s7, 0x580
	s_waitcnt lgkmcnt(0)
	v_readlane_b32 s9, v251, 49
	v_readlane_b32 s8, v251, 48
	s_cselect_b64 s[10:11], -1, 0
	s_cmpk_gt_i32 s7, 0x57f
	v_lshl_add_u32 v77, v2, 2, s22
	v_and_b32_e32 v3, 7, v76
	v_lshrrev_b32_e32 v78, 3, v2
	s_cbranch_scc1 .LBB0_424
	v_lshlrev_b32_e32 v4, 4, v3
	v_mul_u32_u24_e32 v8, 0x410, v3
	v_lshl_add_u64 v[6:7], s[8:9], 0, v[4:5]
	s_mov_b64 s[0:1], 0x2900000
	v_lshlrev_b32_e32 v4, 2, v78
	v_lshl_add_u64 v[6:7], v[6:7], 0, s[0:1]
	v_add3_u32 v79, s22, v8, v4
	s_lshl_b32 s16, s7, 6
	s_lshl_b32 s17, s60, 6
	s_lshl_b32 s18, s7, 5
	s_lshl_b32 s19, s60, 5
	v_lshlrev_b32_e32 v4, 2, v2
	s_mov_b32 s23, 0x1600000
	s_mov_b32 s24, 0x1605000
	s_mov_b32 s25, 0x160b000
	s_mov_b32 s26, 0x1610000
	s_mov_b32 s27, 0x1616000
	s_mov_b32 s28, 0x161b000
	s_mov_b32 s29, 0x1621000
	s_mov_b32 s30, 0x1626000
	s_mov_b32 s31, 0x162c000
	s_mov_b32 s34, 0x1631000
	s_mov_b32 s35, 0x1637000
	s_mov_b32 s36, 0x163c000
	s_mov_b32 s37, 0x1642000
	s_mov_b32 s38, 0x1647000
	s_mov_b32 s39, 0x164d000
	s_mov_b32 s40, 0x1652000
	s_mov_b32 s41, 0x1658000
	s_mov_b32 s42, 0x165d000
	s_mov_b32 s43, 0x1663000
	s_mov_b32 s44, 0x1668000
	s_mov_b32 s45, 0x166e000
	s_mov_b32 s46, 0x1673000
	s_mov_b32 s47, 0x1679000
	s_mov_b32 s48, 0x167e000
	s_mov_b32 s49, 0x1684000
	s_mov_b32 s50, 0x1689000
	s_mov_b32 s51, 0x168f000
	s_mov_b32 s52, 0x1694000
	s_mov_b32 s53, 0x169a000
	s_mov_b32 s54, 0x169f000
	s_mov_b32 s55, 0x16a5000
	s_mov_b32 s56, 0x16aa000
	s_mov_b32 s57, 0x16b0000
	s_mov_b32 s58, 0x16b5000
	s_mov_b32 s59, 0x16bb000
	s_mov_b32 s64, 0x16c0000
	s_mov_b32 s65, 0x16c6000
	s_mov_b32 s66, 0x16cb000
	s_mov_b32 s67, 0x16d1000
	s_mov_b32 s68, 0x16d6000
	s_mov_b32 s69, 0x16dc000
	s_mov_b32 s70, 0x16e1000
	s_mov_b32 s71, 0x16e7000
	s_mov_b32 s72, 0x16ec000
	s_mov_b32 s73, 0x16f2000
	s_mov_b32 s74, 0x16f7000
	s_mov_b32 s75, 0x16fd000
	s_mov_b32 s76, 0x1702000
	s_mov_b32 s77, 0x1708000
	s_mov_b32 s78, 0x170d000
	s_mov_b32 s79, 0x1713000
	s_mov_b32 s80, 0x1718000
	s_mov_b32 s81, 0x171e000
	s_mov_b32 s82, 0x1723000
	s_mov_b32 s83, 0x1729000
	s_mov_b32 s84, 0x172e000
	s_mov_b32 s85, 0x1734000
	s_mov_b32 s86, 0x1739000
	s_mov_b32 s87, 0x173f000
	s_mov_b32 s88, 0x1744000
	s_mov_b32 s89, 0x174a000
	s_mov_b32 s90, 0x174f000
	s_mov_b32 s91, s7
	s_branch .LBB0_360

; #define PIN(i) ((const float*)ldq_(L, (i)))
; #define PREP_CONV(bit, SRC, Kd, Nd, DST, GK, MODE) if (mask & (bit)) { for (int it = gw; it < ((Kd) / 64) * ((Nd) / 64); it += NGW) transpose_item((SRC), (Kd), (Nd), (bf16_t*)(wl + (DST)), (GK), (MODE), scr, it, lane); }
; __device__ __forceinline__ void transpose_item(const float* W, int K, int N, bf16_t* WT, const float* gk, int mode, LAS float* scr_, int item, int lane) {
;     ...
;     const int nblk = N / 64, kb = item / nblk, nb = item % nblk, k0 = 64 * kb, n0 = 64 * nb;
;     const int sc = (mode == 1) ? (((n0 >> 7) & 1) * DFF + (n0 >> 8) * 128 + (n0 & 127)) : n0;
;     const float* src = W + (size_t)k0 * N + sc + lane;
;     float va[32], vb[32];
; #pragma unroll
;     for (int kp = 0; kp < 32; ++kp) { va[kp] = src[(size_t)(2 * kp) * N]; vb[kp] = src[(size_t)(2 * kp + 1) * N]; }
; __device__ __forceinline__ void prep(const Params& p, LAS unsigned char* L, int wv, int vb, int nvb, int l, int mask) {
;     ...
;     PREP_CONV(PM_FFA_IN, PIN(I_WFFA_IN) + (size_t)l * DM * NFF2, DM, NFF2, WL_FFA_IN, PIN(I_NFFA) + l * DM, 1)
.LBB0_360:
	v_mov_b32_e32 v8, 0
	v_mov_b32_e32 v10, 0
	v_add_u32_e32 v8, 0, v8
	v_add_u32_e32 v8, 0x20140, v8
	s_nop 0
	s_mul_hi_i32 s12, s91, 0x2e8ba2e9
	v_add_u32_e32 v10, 0, v10
	v_add_u32_e32 v10, 0x20138, v10
	s_nop 0
	s_waitcnt lgkmcnt(1)
	v_readlane_b32 s95, v251, 16
	v_readlane_b32 s15, v251, 17
	s_waitcnt lgkmcnt(0)
	v_readlane_b32 s0, v251, 14
	v_readlane_b32 s1, v251, 15
	s_add_u32 s93, s0, 0x1000
	s_addc_u32 s94, s1, 0
	s_lshr_b32 s13, s12, 31
	s_ashr_i32 s12, s12, 4
	s_add_i32 s96, s12, s13
	s_mul_i32 s13, s96, 0xffffea00
	s_mul_i32 s14, s96, 0xfffff500
	s_add_i32 s92, s16, s13
	s_bfe_i32 s13, s91, 0x10001
	s_add_i32 s14, s18, s14
	s_and_b32 s13, s13, 0xb00
	s_and_b32 s14, s14, 0xffffff80
	s_lshl_b32 s12, s96, 6
	s_add_i32 s13, s13, s14
	s_and_b32 s14, s92, 64
	s_or_b32 s14, s13, s14
	s_ashr_i32 s13, s12, 31
	s_mul_i32 s96, s96, 0x160000
	s_mul_hi_i32 s97, s12, 0x5800
	s_add_u32 s95, s95, s96
	s_addc_u32 s96, s15, s97
	s_ashr_i32 s15, s14, 31
	s_lshl_b64 s[14:15], s[14:15], 2
	s_add_u32 s14, s95, s14
	s_addc_u32 s15, s96, s15
	v_lshl_add_u64 v[8:9], s[14:15], 0, v[4:5]
	v_add_co_u32_e32 v10, vcc, s23, v8
	s_cmp_lg_u64 s[0:1], 0
	s_nop 0
	v_addc_co_u32_e32 v11, vcc, 0, v9, vcc
	v_add_co_u32_e32 v12, vcc, s24, v8
	s_cselect_b64 s[14:15], -1, 0
	s_nop 0
	v_addc_co_u32_e32 v13, vcc, 0, v9, vcc
	v_add_co_u32_e32 v14, vcc, s25, v8
	s_cmp_eq_u64 s[0:1], 0
	s_nop 0
	v_addc_co_u32_e32 v15, vcc, 0, v9, vcc
	v_add_co_u32_e32 v16, vcc, s26, v8
	s_mov_b64 s[0:1], -1
	s_nop 0
	v_addc_co_u32_e32 v17, vcc, 0, v9, vcc
	v_add_co_u32_e32 v18, vcc, s27, v8
	s_nop 1
	v_addc_co_u32_e32 v19, vcc, 0, v9, vcc
	v_add_co_u32_e32 v20, vcc, s28, v8
	s_nop 1
	v_addc_co_u32_e32 v21, vcc, 0, v9, vcc
	v_add_co_u32_e32 v22, vcc, s29, v8
	s_nop 1
	v_addc_co_u32_e32 v23, vcc, 0, v9, vcc
	v_add_co_u32_e32 v24, vcc, s30, v8
	s_nop 1
	v_addc_co_u32_e32 v25, vcc, 0, v9, vcc
	global_load_dword v68, v[10:11], off
	global_load_dword v69, v[12:13], off offset:2048
	global_load_dword v70, v[14:15], off
	global_load_dword v71, v[16:17], off offset:2048
	global_load_dword v64, v[18:19], off
	global_load_dword v65, v[20:21], off offset:2048
	global_load_dword v66, v[22:23], off
	global_load_dword v67, v[24:25], off offset:2048
	v_add_co_u32_e32 v10, vcc, s31, v8
	s_nop 1
	v_addc_co_u32_e32 v11, vcc, 0, v9, vcc
	v_add_co_u32_e32 v12, vcc, s34, v8
	s_nop 1
	v_addc_co_u32_e32 v13, vcc, 0, v9, vcc
	v_add_co_u32_e32 v14, vcc, s35, v8
	s_nop 1
	v_addc_co_u32_e32 v15, vcc, 0, v9, vcc
	v_add_co_u32_e32 v16, vcc, s36, v8
	s_nop 1
	v_addc_co_u32_e32 v17, vcc, 0, v9, vcc
	v_add_co_u32_e32 v18, vcc, s37, v8
	s_nop 1
	v_addc_co_u32_e32 v19, vcc, 0, v9, vcc
	v_add_co_u32_e32 v20, vcc, s38, v8
	s_nop 1
	v_addc_co_u32_e32 v21, vcc, 0, v9, vcc
	v_add_co_u32_e32 v22, vcc, s39, v8
	s_nop 1
	v_addc_co_u32_e32 v23, vcc, 0, v9, vcc
	v_add_co_u32_e32 v24, vcc, s40, v8
	s_nop 1
	v_addc_co_u32_e32 v25, vcc, 0, v9, vcc
	global_load_dword v60, v[10:11], off
	global_load_dword v61, v[12:13], off offset:2048
	global_load_dword v62, v[14:15], off
	global_load_dword v63, v[16:17], off offset:2048
	global_load_dword v56, v[18:19], off
	global_load_dword v57, v[20:21], off offset:2048
	global_load_dword v58, v[22:23], off
	global_load_dword v59, v[24:25], off offset:2048
	v_add_co_u32_e32 v10, vcc, s41, v8
	s_nop 1
	v_addc_co_u32_e32 v11, vcc, 0, v9, vcc
	v_add_co_u32_e32 v12, vcc, s42, v8
	s_nop 1
	v_addc_co_u32_e32 v13, vcc, 0, v9, vcc
	v_add_co_u32_e32 v14, vcc, s43, v8
	s_nop 1
	v_addc_co_u32_e32 v15, vcc, 0, v9, vcc
	v_add_co_u32_e32 v16, vcc, s44, v8
	s_nop 1
	v_addc_co_u32_e32 v17, vcc, 0, v9, vcc
	v_add_co_u32_e32 v18, vcc, s45, v8
	s_nop 1
	v_addc_co_u32_e32 v19, vcc, 0, v9, vcc
	v_add_co_u32_e32 v20, vcc, s46, v8
	s_nop 1
	v_addc_co_u32_e32 v21, vcc, 0, v9, vcc
	v_add_co_u32_e32 v22, vcc, s47, v8
	s_nop 1
	v_addc_co_u32_e32 v23, vcc, 0, v9, vcc
	v_add_co_u32_e32 v24, vcc, s48, v8
	s_nop 1
	v_addc_co_u32_e32 v25, vcc, 0, v9, vcc
	global_load_dword v52, v[10:11], off
	global_load_dword v53, v[12:13], off offset:2048
	global_load_dword v54, v[14:15], off
	global_load_dword v55, v[16:17], off offset:2048
	global_load_dword v48, v[18:19], off
	global_load_dword v49, v[20:21], off offset:2048
	global_load_dword v50, v[22:23], off
	global_load_dword v51, v[24:25], off offset:2048
	v_add_co_u32_e32 v10, vcc, s49, v8
	s_nop 1
	v_addc_co_u32_e32 v11, vcc, 0, v9, vcc
	v_add_co_u32_e32 v12, vcc, s50, v8
	s_nop 1
	v_addc_co_u32_e32 v13, vcc, 0, v9, vcc
	v_add_co_u32_e32 v14, vcc, s51, v8
	s_nop 1
	v_addc_co_u32_e32 v15, vcc, 0, v9, vcc
	v_add_co_u32_e32 v16, vcc, s52, v8
	s_nop 1
	v_addc_co_u32_e32 v17, vcc, 0, v9, vcc
	v_add_co_u32_e32 v18, vcc, s53, v8
	s_nop 1
	v_addc_co_u32_e32 v19, vcc, 0, v9, vcc
	v_add_co_u32_e32 v20, vcc, s54, v8
	s_nop 1
	v_addc_co_u32_e32 v21, vcc, 0, v9, vcc
	v_add_co_u32_e32 v22, vcc, s55, v8
	s_nop 1
	v_addc_co_u32_e32 v23, vcc, 0, v9, vcc
; __device__ __forceinline__ void transpose_item(const float* W, int K, int N, bf16_t* WT, const float* gk, int mode, LAS float* scr_, int item, int lane) {
;     ...
;     for (int kp = 0; kp < 32; ++kp) { va[kp] = src[(size_t)(2 * kp) * N]; vb[kp] = src[(size_t)(2 * kp + 1) * N]; }
; #pragma unroll
;     for (int kp = 0; kp < 32; ++kp) {
;         float a = va[kp], b = vb[kp];
;         if (gk) { a *= gk[k0 + 2 * kp]; b *= gk[k0 + 2 * kp + 1]; }
	v_add_co_u32_e32 v24, vcc, s56, v8
	s_nop 1
	v_addc_co_u32_e32 v25, vcc, 0, v9, vcc
	global_load_dword v44, v[10:11], off
	global_load_dword v45, v[12:13], off offset:2048
	global_load_dword v46, v[14:15], off
	global_load_dword v47, v[16:17], off offset:2048
	global_load_dword v40, v[18:19], off
	global_load_dword v41, v[20:21], off offset:2048
	global_load_dword v42, v[22:23], off
	global_load_dword v43, v[24:25], off offset:2048
	v_add_co_u32_e32 v10, vcc, s57, v8
	s_nop 1
	v_addc_co_u32_e32 v11, vcc, 0, v9, vcc
	v_add_co_u32_e32 v12, vcc, s58, v8
	s_nop 1
	v_addc_co_u32_e32 v13, vcc, 0, v9, vcc
	v_add_co_u32_e32 v14, vcc, s59, v8
	s_nop 1
	v_addc_co_u32_e32 v15, vcc, 0, v9, vcc
	v_add_co_u32_e32 v16, vcc, s64, v8
	s_nop 1
	v_addc_co_u32_e32 v17, vcc, 0, v9, vcc
	v_add_co_u32_e32 v18, vcc, s65, v8
	s_nop 1
	v_addc_co_u32_e32 v19, vcc, 0, v9, vcc
	v_add_co_u32_e32 v20, vcc, s66, v8
	s_nop 1
	v_addc_co_u32_e32 v21, vcc, 0, v9, vcc
	v_add_co_u32_e32 v22, vcc, s67, v8
	s_nop 1
	v_addc_co_u32_e32 v23, vcc, 0, v9, vcc
	v_add_co_u32_e32 v24, vcc, s68, v8
	s_nop 1
	v_addc_co_u32_e32 v25, vcc, 0, v9, vcc
	global_load_dword v36, v[10:11], off
	global_load_dword v37, v[12:13], off offset:2048
	global_load_dword v38, v[14:15], off
	global_load_dword v39, v[16:17], off offset:2048
	global_load_dword v32, v[18:19], off
	global_load_dword v33, v[20:21], off offset:2048
	global_load_dword v34, v[22:23], off
	global_load_dword v35, v[24:25], off offset:2048
	v_add_co_u32_e32 v10, vcc, s69, v8
	s_nop 1
	v_addc_co_u32_e32 v11, vcc, 0, v9, vcc
	v_add_co_u32_e32 v12, vcc, s70, v8
	s_nop 1
	v_addc_co_u32_e32 v13, vcc, 0, v9, vcc
	v_add_co_u32_e32 v14, vcc, s71, v8
	s_nop 1
	v_addc_co_u32_e32 v15, vcc, 0, v9, vcc
	v_add_co_u32_e32 v16, vcc, s72, v8
	s_nop 1
	v_addc_co_u32_e32 v17, vcc, 0, v9, vcc
	v_add_co_u32_e32 v18, vcc, s73, v8
	s_nop 1
	v_addc_co_u32_e32 v19, vcc, 0, v9, vcc
	v_add_co_u32_e32 v20, vcc, s74, v8
	s_nop 1
	v_addc_co_u32_e32 v21, vcc, 0, v9, vcc
	v_add_co_u32_e32 v22, vcc, s75, v8
	s_nop 1
	v_addc_co_u32_e32 v23, vcc, 0, v9, vcc
	v_add_co_u32_e32 v72, vcc, s76, v8
	s_nop 1
	v_addc_co_u32_e32 v73, vcc, 0, v9, vcc
	global_load_dword v28, v[10:11], off
	global_load_dword v29, v[12:13], off offset:2048
	global_load_dword v30, v[14:15], off
	global_load_dword v31, v[16:17], off offset:2048
	global_load_dword v24, v[18:19], off
	global_load_dword v25, v[20:21], off offset:2048
	global_load_dword v26, v[22:23], off
	global_load_dword v27, v[72:73], off offset:2048
	v_add_co_u32_e32 v10, vcc, s77, v8
	s_nop 1
	v_addc_co_u32_e32 v11, vcc, 0, v9, vcc
	v_add_co_u32_e32 v12, vcc, s78, v8
	s_nop 1
	v_addc_co_u32_e32 v13, vcc, 0, v9, vcc
	v_add_co_u32_e32 v14, vcc, s79, v8
	s_nop 1
	v_addc_co_u32_e32 v15, vcc, 0, v9, vcc
	v_add_co_u32_e32 v16, vcc, s80, v8
	s_nop 1
	v_addc_co_u32_e32 v17, vcc, 0, v9, vcc
	v_add_co_u32_e32 v18, vcc, s81, v8
	s_nop 1
	v_addc_co_u32_e32 v19, vcc, 0, v9, vcc
	v_add_co_u32_e32 v72, vcc, s82, v8
	s_nop 1
	v_addc_co_u32_e32 v73, vcc, 0, v9, vcc
	v_add_co_u32_e32 v74, vcc, s83, v8
	s_nop 1
	v_addc_co_u32_e32 v75, vcc, 0, v9, vcc
	v_add_co_u32_e32 v80, vcc, s84, v8
	s_nop 1
	v_addc_co_u32_e32 v81, vcc, 0, v9, vcc
	global_load_dword v20, v[10:11], off
	global_load_dword v21, v[12:13], off offset:2048
	global_load_dword v22, v[14:15], off
	global_load_dword v23, v[16:17], off offset:2048
	s_nop 0
	global_load_dword v16, v[18:19], off
	global_load_dword v17, v[72:73], off offset:2048
	s_nop 0
	global_load_dword v18, v[74:75], off
	global_load_dword v19, v[80:81], off offset:2048
	v_add_co_u32_e32 v10, vcc, s85, v8
	s_nop 1
	v_addc_co_u32_e32 v11, vcc, 0, v9, vcc
	v_add_co_u32_e32 v14, vcc, s86, v8
	s_nop 1
	v_addc_co_u32_e32 v15, vcc, 0, v9, vcc
	v_add_co_u32_e32 v72, vcc, s87, v8
	s_nop 1
	v_addc_co_u32_e32 v73, vcc, 0, v9, vcc
	v_add_co_u32_e32 v74, vcc, s88, v8
	s_nop 1
	v_addc_co_u32_e32 v75, vcc, 0, v9, vcc
	v_add_co_u32_e32 v80, vcc, s89, v8
	s_nop 1
	v_addc_co_u32_e32 v81, vcc, 0, v9, vcc
	v_add_co_u32_e32 v82, vcc, s90, v8
	s_nop 1
	v_addc_co_u32_e32 v83, vcc, 0, v9, vcc
	v_add_co_u32_e32 v84, vcc, 0x1755000, v8
	s_nop 1
	v_addc_co_u32_e32 v85, vcc, 0, v9, vcc
	v_add_co_u32_e32 v86, vcc, 0x175a000, v8
	s_nop 1
	v_addc_co_u32_e32 v87, vcc, 0, v9, vcc
	global_load_dword v12, v[10:11], off
	global_load_dword v13, v[14:15], off offset:2048
	s_nop 0
	global_load_dword v14, v[72:73], off
	global_load_dword v15, v[74:75], off offset:2048
	global_load_dword v8, v[80:81], off
	global_load_dword v9, v[82:83], off offset:2048
	global_load_dword v10, v[84:85], off
	global_load_dword v11, v[86:87], off offset:2048
	s_cbranch_scc1 .LBB0_362
	s_lshl_b64 s[0:1], s[12:13], 2
	s_add_u32 s0, s93, s0
	s_addc_u32 s1, s94, s1
	global_load_dwordx4 v[72:75], v5, s[0:1]
	s_mov_b64 s[0:1], 0
	s_waitcnt vmcnt(0)
	v_pk_mul_f32 v[72:73], v[68:69], v[72:73]
	v_pk_mul_f32 v[74:75], v[70:71], v[74:75]

; #define LAS __attribute__((address_space(3)))
; #define PIN(i) ((const float*)ldq_(L, (i)))
; __device__ __forceinline__ unsigned pk2(float lo, float hi) { f32x2 v = {lo, hi}; bf16x2_t b = __builtin_convertvector(v, bf16x2_t); return __builtin_bit_cast(unsigned, b); }
; #define PREP_CONV(bit, SRC, Kd, Nd, DST, GK, MODE) if (mask & (bit)) { for (int it = gw; it < ((Kd) / 64) * ((Nd) / 64); it += NGW) transpose_item((SRC), (Kd), (Nd), (bf16_t*)(wl + (DST)), (GK), (MODE), scr, it, lane); }
; __device__ __forceinline__ void transpose_item(const float* W, int K, int N, bf16_t* WT, const float* gk, int mode, LAS float* scr_, int item, int lane) {
;     ...
;     const int nblk = N / 64, kb = item / nblk, nb = item % nblk, k0 = 64 * kb, n0 = 64 * nb;
;     const int sc = (mode == 1) ? (((n0 >> 7) & 1) * DFF + (n0 >> 8) * 128 + (n0 & 127)) : n0;
;     const float* src = W + (size_t)k0 * N + sc + lane;
;     float va[32], vb[32];
; #pragma unroll
;     for (int kp = 0; kp < 32; ++kp) { va[kp] = src[(size_t)(2 * kp) * N]; vb[kp] = src[(size_t)(2 * kp + 1) * N]; }
; #pragma unroll
;     for (int kp = 0; kp < 32; ++kp) {
;         float a = va[kp], b = vb[kp];
;         if (gk) { a *= gk[k0 + 2 * kp]; b *= gk[k0 + 2 * kp + 1]; }
;         scr[kp * 65 + lane] = pk2(a, b);
;     }
;     asm volatile("s_waitcnt lgkmcnt(0)" ::: "memory");
;     const int c = lane & 7;
; #pragma unroll
;     for (int j = 0; j < 8; ++j) { const int r = (lane >> 3) + 8 * j; const LAS unsigned* q = scr + (4 * c) * 65 + r;
;         u32x4 o; o.x = q[0]; o.y = q[65]; o.z = q[130]; o.w = q[195];
;         *(u32x4*)(WT + (size_t)(n0 + r) * K + k0 + 8 * c) = o; }
; __device__ __forceinline__ void prep(const Params& p, LAS unsigned char* L, int wv, int vb, int nvb, int l, int mask) {
;     ...
;     PREP_CONV(PM_FFA_OUT, PIN(I_WFFA_OUT) + (size_t)l * DFF * DM, DFF, DM, WL_FFA_OUT, nullptr, 0)
.LBB0_426:
	v_mov_b32_e32 v8, 0
	s_ashr_i32 s0, s58, 31
	v_add_u32_e32 v8, 0, v8
	v_add_u32_e32 v8, 0x20148, v8
	s_lshr_b32 s0, s0, 28
	s_nop 0
	s_add_i32 s0, s58, s0
	s_ashr_i32 s1, s0, 4
	s_lshl_b32 s0, s1, 6
	s_lshl_b32 s14, s1, 10
	s_mul_i32 s15, s1, 0xffd40000
	s_ashr_i32 s1, s0, 31
	s_sub_i32 s14, s18, s14
	s_lshl_b64 s[16:17], s[0:1], 12
	v_lshl_add_u64 v[22:23], s[0:1], 1, v[6:7]
	s_waitcnt lgkmcnt(0)
	v_readlane_b32 s1, v251, 18
	v_readlane_b32 s0, v251, 19
	s_add_u32 s16, s1, s16
	v_add_u32_e32 v20, s15, v11
	s_addc_u32 s17, s0, s17
	s_ashr_i32 s15, s14, 31
	s_lshl_b64 s[0:1], s[14:15], 2
	s_add_u32 s0, s16, s0
	s_addc_u32 s1, s17, s1
	v_ashrrev_i32_e32 v21, 31, v20
	v_lshl_add_u64 v[8:9], s[0:1], 0, v[4:5]
	v_add_u32_e32 v24, 0x5800, v20
	v_add_u32_e32 v26, 0xb000, v20
	v_add_u32_e32 v28, 0x10800, v20
	v_add_u32_e32 v30, 0x16000, v20
	v_add_u32_e32 v32, 0x1b800, v20
	v_add_u32_e32 v34, 0x21000, v20
	v_add_u32_e32 v36, 0x26800, v20
	v_lshl_add_u64 v[52:53], v[20:21], 1, v[22:23]
	v_add_co_u32_e32 v20, vcc, s24, v8
	v_ashrrev_i32_e32 v25, 31, v24
	v_ashrrev_i32_e32 v27, 31, v26
	v_ashrrev_i32_e32 v29, 31, v28
	v_ashrrev_i32_e32 v31, 31, v30
	v_ashrrev_i32_e32 v33, 31, v32
	v_ashrrev_i32_e32 v35, 31, v34
	v_ashrrev_i32_e32 v37, 31, v36
	v_addc_co_u32_e32 v21, vcc, 0, v9, vcc
	v_lshl_add_u64 v[54:55], v[24:25], 1, v[22:23]
	v_lshl_add_u64 v[56:57], v[26:27], 1, v[22:23]
	v_lshl_add_u64 v[58:59], v[28:29], 1, v[22:23]
	v_lshl_add_u64 v[60:61], v[30:31], 1, v[22:23]
	v_lshl_add_u64 v[62:63], v[32:33], 1, v[22:23]
	v_lshl_add_u64 v[64:65], v[34:35], 1, v[22:23]
	v_lshl_add_u64 v[66:67], v[36:37], 1, v[22:23]
	v_add_co_u32_e32 v22, vcc, s25, v8
	s_add_i32 s58, s58, s60
	s_nop 0
	v_addc_co_u32_e32 v23, vcc, 0, v9, vcc
	v_add_co_u32_e32 v24, vcc, s26, v8
	s_add_i32 s18, s18, s19
	s_nop 0
	v_addc_co_u32_e32 v25, vcc, 0, v9, vcc
	v_add_co_u32_e32 v26, vcc, s27, v8
	s_cmpk_lt_i32 s58, 0x2c0
	s_nop 0
	v_addc_co_u32_e32 v27, vcc, 0, v9, vcc
	v_add_co_u32_e32 v28, vcc, s28, v8
	v_add_u32_e32 v11, s61, v11
	s_nop 0
	v_addc_co_u32_e32 v29, vcc, 0, v9, vcc
	v_add_co_u32_e32 v30, vcc, s29, v8
	s_nop 1
	v_addc_co_u32_e32 v31, vcc, 0, v9, vcc
	v_add_co_u32_e32 v32, vcc, s30, v8
	s_nop 1
	v_addc_co_u32_e32 v33, vcc, 0, v9, vcc
	v_add_co_u32_e32 v34, vcc, s31, v8
	s_nop 1
	v_addc_co_u32_e32 v35, vcc, 0, v9, vcc
	v_add_co_u32_e32 v36, vcc, s34, v8
	s_nop 1
	v_addc_co_u32_e32 v37, vcc, 0, v9, vcc
	v_add_co_u32_e32 v38, vcc, s35, v8
	s_nop 1
	v_addc_co_u32_e32 v39, vcc, 0, v9, vcc
	v_add_co_u32_e32 v40, vcc, s36, v8
	s_nop 1
	v_addc_co_u32_e32 v41, vcc, 0, v9, vcc
	v_add_co_u32_e32 v42, vcc, s37, v8
	s_nop 1
	v_addc_co_u32_e32 v43, vcc, 0, v9, vcc
	v_add_co_u32_e32 v44, vcc, s38, v8
	s_nop 1
	v_addc_co_u32_e32 v45, vcc, 0, v9, vcc
	v_add_co_u32_e32 v46, vcc, s39, v8
	s_nop 1
	v_addc_co_u32_e32 v47, vcc, 0, v9, vcc
	v_add_co_u32_e32 v48, vcc, s40, v8
	s_nop 1
	v_addc_co_u32_e32 v49, vcc, 0, v9, vcc
	v_add_co_u32_e32 v50, vcc, s41, v8
	s_nop 1
	v_addc_co_u32_e32 v51, vcc, 0, v9, vcc
	v_add_co_u32_e32 v68, vcc, s42, v8
	s_nop 1
	v_addc_co_u32_e32 v69, vcc, 0, v9, vcc
	v_add_co_u32_e32 v70, vcc, s43, v8
	s_nop 1
	v_addc_co_u32_e32 v71, vcc, 0, v9, vcc
	v_add_co_u32_e32 v72, vcc, s44, v8
	s_nop 1
	v_addc_co_u32_e32 v73, vcc, 0, v9, vcc
	v_add_co_u32_e32 v74, vcc, s45, v8
	s_nop 1
	v_addc_co_u32_e32 v75, vcc, 0, v9, vcc
	v_add_co_u32_e32 v80, vcc, s46, v8
	s_nop 1
	v_addc_co_u32_e32 v81, vcc, 0, v9, vcc
	v_add_co_u32_e32 v82, vcc, s47, v8
	s_nop 1
	v_addc_co_u32_e32 v83, vcc, 0, v9, vcc
	v_add_co_u32_e32 v84, vcc, s48, v8
	s_nop 1
	v_addc_co_u32_e32 v85, vcc, 0, v9, vcc
	v_add_co_u32_e32 v86, vcc, s49, v8
	s_nop 1
	v_addc_co_u32_e32 v87, vcc, 0, v9, vcc
	v_add_co_u32_e32 v88, vcc, s50, v8
	s_nop 1
	v_addc_co_u32_e32 v89, vcc, 0, v9, vcc
	v_add_co_u32_e32 v90, vcc, s51, v8
	s_nop 1
	v_addc_co_u32_e32 v91, vcc, 0, v9, vcc
	v_add_co_u32_e32 v92, vcc, s52, v8
	s_nop 1
	v_addc_co_u32_e32 v93, vcc, 0, v9, vcc
	v_add_co_u32_e32 v94, vcc, s53, v8
	s_nop 1
	v_addc_co_u32_e32 v95, vcc, 0, v9, vcc
	v_add_co_u32_e32 v96, vcc, s54, v8
	s_nop 1
	v_addc_co_u32_e32 v97, vcc, 0, v9, vcc
	v_add_co_u32_e32 v98, vcc, s55, v8
	s_nop 1
	v_addc_co_u32_e32 v99, vcc, 0, v9, vcc
	v_add_co_u32_e32 v100, vcc, s56, v8
	s_nop 1
	v_addc_co_u32_e32 v101, vcc, 0, v9, vcc
	v_add_co_u32_e32 v8, vcc, s57, v8
	s_nop 1
	v_addc_co_u32_e32 v9, vcc, 0, v9, vcc
	global_load_dword v19, v[20:21], off offset:-4096
	s_nop 0
	global_load_dword v20, v[20:21], off
	s_nop 0
	global_load_dword v21, v[22:23], off offset:-4096
	s_nop 0
	global_load_dword v22, v[22:23], off
	s_nop 0
	global_load_dword v23, v[24:25], off offset:-4096
	s_nop 0
	global_load_dword v24, v[24:25], off
	s_nop 0
	global_load_dword v25, v[26:27], off offset:-4096
	s_nop 0
	global_load_dword v26, v[26:27], off
	s_nop 0
	global_load_dword v27, v[28:29], off offset:-4096
	s_nop 0
	global_load_dword v28, v[28:29], off
	s_nop 0
	global_load_dword v29, v[30:31], off offset:-4096
	s_nop 0
	global_load_dword v30, v[30:31], off
	s_nop 0
	global_load_dword v31, v[32:33], off offset:-4096
	s_nop 0
	global_load_dword v32, v[32:33], off
	s_nop 0
	global_load_dword v33, v[34:35], off offset:-4096
	s_nop 0
	global_load_dword v34, v[34:35], off
	s_nop 0
	global_load_dword v35, v[36:37], off offset:-4096
	s_nop 0
	global_load_dword v36, v[36:37], off
	s_nop 0
	global_load_dword v37, v[38:39], off offset:-4096
	s_nop 0
	global_load_dword v38, v[38:39], off
	s_nop 0
	global_load_dword v39, v[40:41], off offset:-4096
	s_nop 0
	global_load_dword v40, v[40:41], off
	s_nop 0
	global_load_dword v41, v[42:43], off offset:-4096
	s_nop 0
	global_load_dword v42, v[42:43], off
; #define LAS __attribute__((address_space(3)))
; __device__ __forceinline__ unsigned pk2(float lo, float hi) { f32x2 v = {lo, hi}; bf16x2_t b = __builtin_convertvector(v, bf16x2_t); return __builtin_bit_cast(unsigned, b); }
; __device__ __forceinline__ void transpose_item(const float* W, int K, int N, bf16_t* WT, const float* gk, int mode, LAS float* scr_, int item, int lane) {
;     ...
;     for (int kp = 0; kp < 32; ++kp) { va[kp] = src[(size_t)(2 * kp) * N]; vb[kp] = src[(size_t)(2 * kp + 1) * N]; }
; #pragma unroll
;     for (int kp = 0; kp < 32; ++kp) {
;         float a = va[kp], b = vb[kp];
;         if (gk) { a *= gk[k0 + 2 * kp]; b *= gk[k0 + 2 * kp + 1]; }
;         scr[kp * 65 + lane] = pk2(a, b);
;     }
;     asm volatile("s_waitcnt lgkmcnt(0)" ::: "memory");
;     const int c = lane & 7;
; #pragma unroll
;     for (int j = 0; j < 8; ++j) { const int r = (lane >> 3) + 8 * j; const LAS unsigned* q = scr + (4 * c) * 65 + r;
;         u32x4 o; o.x = q[0]; o.y = q[65]; o.z = q[130]; o.w = q[195];
;         *(u32x4*)(WT + (size_t)(n0 + r) * K + k0 + 8 * c) = o; }
;     asm volatile("s_waitcnt lgkmcnt(0)" ::: "memory");
	s_nop 0
	global_load_dword v43, v[44:45], off offset:-4096
	s_nop 0
	global_load_dword v44, v[44:45], off
	s_nop 0
	global_load_dword v45, v[46:47], off offset:-4096
	s_nop 0
	global_load_dword v46, v[46:47], off
	s_nop 0
	global_load_dword v47, v[48:49], off offset:-4096
	s_nop 0
	global_load_dword v48, v[48:49], off
	s_nop 0
	global_load_dword v49, v[50:51], off offset:-4096
	s_nop 0
	global_load_dword v50, v[50:51], off
	s_nop 0
	global_load_dword v51, v[68:69], off offset:-4096
	s_nop 0
	global_load_dword v68, v[68:69], off
	s_nop 0
	global_load_dword v69, v[70:71], off offset:-4096
	s_nop 0
	global_load_dword v70, v[70:71], off
	s_nop 0
	global_load_dword v71, v[72:73], off offset:-4096
	s_nop 0
	global_load_dword v72, v[72:73], off
	s_nop 0
	global_load_dword v73, v[74:75], off offset:-4096
	s_nop 0
	global_load_dword v74, v[74:75], off
	s_nop 0
	global_load_dword v75, v[80:81], off offset:-4096
	global_load_dword v79, v[80:81], off
	s_nop 0
	global_load_dword v80, v[82:83], off offset:-4096
	global_load_dword v81, v[82:83], off
	s_nop 0
	global_load_dword v82, v[84:85], off offset:-4096
	global_load_dword v83, v[84:85], off
	s_nop 0
	global_load_dword v84, v[86:87], off offset:-4096
	global_load_dword v85, v[86:87], off
	s_nop 0
	global_load_dword v86, v[88:89], off offset:-4096
	global_load_dword v87, v[88:89], off
	s_nop 0
	global_load_dword v88, v[90:91], off offset:-4096
	global_load_dword v89, v[90:91], off
	s_nop 0
	global_load_dword v90, v[92:93], off offset:-4096
	global_load_dword v91, v[92:93], off
	s_nop 0
	global_load_dword v92, v[94:95], off offset:-4096
	global_load_dword v93, v[94:95], off
	s_nop 0
	global_load_dword v94, v[96:97], off offset:-4096
	global_load_dword v95, v[96:97], off
	s_nop 0
	global_load_dword v96, v[98:99], off offset:-4096
	global_load_dword v97, v[98:99], off
	s_nop 0
	global_load_dword v98, v[100:101], off offset:-4096
	global_load_dword v99, v[100:101], off
	s_nop 0
	global_load_dword v100, v[8:9], off offset:-4096
	s_nop 0
	global_load_dword v8, v[8:9], off
	s_waitcnt vmcnt(62)
	v_cvt_pk_bf16_f32 v9, v19, v20
	s_waitcnt vmcnt(60)
	v_cvt_pk_bf16_f32 v19, v21, v22
	s_waitcnt vmcnt(58)
	v_cvt_pk_bf16_f32 v20, v23, v24
	s_waitcnt vmcnt(56)
	v_cvt_pk_bf16_f32 v21, v25, v26
	s_waitcnt vmcnt(54)
	v_cvt_pk_bf16_f32 v22, v27, v28
	s_waitcnt vmcnt(52)
	v_cvt_pk_bf16_f32 v23, v29, v30
	s_waitcnt vmcnt(50)
	v_cvt_pk_bf16_f32 v24, v31, v32
	s_waitcnt vmcnt(48)
	v_cvt_pk_bf16_f32 v25, v33, v34
	s_waitcnt vmcnt(46)
	v_cvt_pk_bf16_f32 v26, v35, v36
	s_waitcnt vmcnt(44)
	v_cvt_pk_bf16_f32 v27, v37, v38
	s_waitcnt vmcnt(42)
	v_cvt_pk_bf16_f32 v28, v39, v40
	s_waitcnt vmcnt(40)
	v_cvt_pk_bf16_f32 v29, v41, v42
	s_waitcnt vmcnt(38)
	v_cvt_pk_bf16_f32 v30, v43, v44
	s_waitcnt vmcnt(36)
	v_cvt_pk_bf16_f32 v31, v45, v46
	s_waitcnt vmcnt(34)
	v_cvt_pk_bf16_f32 v32, v47, v48
	s_waitcnt vmcnt(32)
	v_cvt_pk_bf16_f32 v33, v49, v50
	s_waitcnt vmcnt(30)
	v_cvt_pk_bf16_f32 v34, v51, v68
	s_waitcnt vmcnt(28)
	v_cvt_pk_bf16_f32 v35, v69, v70
	s_waitcnt vmcnt(26)
	v_cvt_pk_bf16_f32 v36, v71, v72
	s_waitcnt vmcnt(24)
	v_cvt_pk_bf16_f32 v37, v73, v74
	s_waitcnt vmcnt(22)
	v_cvt_pk_bf16_f32 v38, v75, v79
	s_waitcnt vmcnt(20)
	v_cvt_pk_bf16_f32 v39, v80, v81
	s_waitcnt vmcnt(18)
	v_cvt_pk_bf16_f32 v40, v82, v83
	s_waitcnt vmcnt(16)
	v_cvt_pk_bf16_f32 v41, v84, v85
	s_waitcnt vmcnt(14)
	v_cvt_pk_bf16_f32 v42, v86, v87
	s_waitcnt vmcnt(12)
	v_cvt_pk_bf16_f32 v43, v88, v89
	s_waitcnt vmcnt(10)
	v_cvt_pk_bf16_f32 v44, v90, v91
	s_waitcnt vmcnt(8)
	v_cvt_pk_bf16_f32 v45, v92, v93
	s_waitcnt vmcnt(6)
	v_cvt_pk_bf16_f32 v46, v94, v95
	s_waitcnt vmcnt(4)
	v_cvt_pk_bf16_f32 v47, v96, v97
	s_waitcnt vmcnt(2)
	v_cvt_pk_bf16_f32 v48, v98, v99
	s_waitcnt vmcnt(0)
	v_cvt_pk_bf16_f32 v8, v100, v8
	ds_write2_b32 v77, v9, v19 offset1:65
	ds_write2_b32 v77, v20, v21 offset0:130 offset1:195
	ds_write2_b32 v12, v22, v23 offset0:4 offset1:69
	ds_write2_b32 v12, v24, v25 offset0:134 offset1:199
	ds_write2_b32 v13, v26, v27 offset0:8 offset1:73
	ds_write2_b32 v13, v28, v29 offset0:138 offset1:203
	ds_write2_b32 v14, v30, v31 offset0:12 offset1:77
	ds_write2_b32 v14, v32, v33 offset0:142 offset1:207
	ds_write2_b32 v15, v34, v35 offset0:16 offset1:81
	ds_write2_b32 v15, v36, v37 offset0:146 offset1:211
	ds_write2_b32 v16, v38, v39 offset0:20 offset1:85
	ds_write2_b32 v16, v40, v41 offset0:150 offset1:215
	ds_write2_b32 v17, v42, v43 offset0:24 offset1:89
	ds_write2_b32 v17, v44, v45 offset0:154 offset1:219
	ds_write2_b32 v18, v46, v47 offset0:28 offset1:93
	ds_write2_b32 v18, v48, v8 offset0:158 offset1:223
	s_waitcnt lgkmcnt(0)
	ds_read2_b32 v[20:21], v10 offset0:65 offset1:73
	ds_read2_b32 v[8:9], v10 offset0:130 offset1:138
	ds_read2_b32 v[22:23], v10 offset0:195 offset1:203
	ds_read2_b32 v[40:41], v10 offset1:8
	ds_read2_b32 v[44:45], v10 offset0:16 offset1:24
	ds_read2_b32 v[24:25], v10 offset0:81 offset1:89
	ds_read2_b32 v[46:47], v10 offset0:146 offset1:154
	ds_read2_b32 v[26:27], v10 offset0:211 offset1:219
	ds_read2_b32 v[28:29], v10 offset0:97 offset1:105
	ds_read2_b32 v[48:49], v10 offset0:162 offset1:170
	ds_read2_b32 v[30:31], v10 offset0:227 offset1:235
	ds_read2_b32 v[50:51], v10 offset0:32 offset1:40
	ds_read2_b32 v[68:69], v10 offset0:48 offset1:56
	ds_read2_b32 v[32:33], v10 offset0:113 offset1:121
	ds_read2_b32 v[70:71], v10 offset0:178 offset1:186
	ds_read2_b32 v[34:35], v10 offset0:243 offset1:251
	s_waitcnt lgkmcnt(12)
	v_mov_b32_e32 v36, v40
	v_mov_b32_e32 v37, v20
	v_mov_b32_e32 v38, v8
	v_mov_b32_e32 v39, v22
	v_mov_b32_e32 v20, v41
	v_mov_b32_e32 v22, v9
	s_waitcnt lgkmcnt(11)
	v_mov_b32_e32 v40, v44
	s_waitcnt lgkmcnt(10)
	v_mov_b32_e32 v41, v24
	s_waitcnt lgkmcnt(9)
	v_mov_b32_e32 v42, v46
	s_waitcnt lgkmcnt(8)
	v_mov_b32_e32 v43, v26
	v_mov_b32_e32 v24, v45
	v_mov_b32_e32 v26, v47
	s_waitcnt lgkmcnt(4)
	v_mov_b32_e32 v44, v50
	v_mov_b32_e32 v45, v28
	v_mov_b32_e32 v46, v48
	v_mov_b32_e32 v47, v30
	v_mov_b32_e32 v28, v51
	v_mov_b32_e32 v30, v49
	s_waitcnt lgkmcnt(3)
	v_mov_b32_e32 v48, v68
	s_waitcnt lgkmcnt(2)
	v_mov_b32_e32 v49, v32
	s_waitcnt lgkmcnt(1)
	v_mov_b32_e32 v50, v70
	s_waitcnt lgkmcnt(0)
	v_mov_b32_e32 v51, v34
	v_mov_b32_e32 v32, v69
	v_mov_b32_e32 v34, v71
	global_store_dwordx4 v[52:53], v[36:39], off
	global_store_dwordx4 v[54:55], v[20:23], off
	global_store_dwordx4 v[56:57], v[40:43], off
	global_store_dwordx4 v[58:59], v[24:27], off
	global_store_dwordx4 v[60:61], v[44:47], off
	global_store_dwordx4 v[62:63], v[28:31], off
	global_store_dwordx4 v[64:65], v[48:51], off
	global_store_dwordx4 v[66:67], v[32:35], off
	s_waitcnt lgkmcnt(0)
	s_cbranch_scc1 .LBB0_426

; #define PIN(i) ((const float*)ldq_(L, (i)))
; #define PREP_CONV(bit, SRC, Kd, Nd, DST, GK, MODE) if (mask & (bit)) { for (int it = gw; it < ((Kd) / 64) * ((Nd) / 64); it += NGW) transpose_item((SRC), (Kd), (Nd), (bf16_t*)(wl + (DST)), (GK), (MODE), scr, it, lane); }
; __device__ __forceinline__ void transpose_item(const float* W, int K, int N, bf16_t* WT, const float* gk, int mode, LAS float* scr_, int item, int lane) {
;     ...
;     const int nblk = N / 64, kb = item / nblk, nb = item % nblk, k0 = 64 * kb, n0 = 64 * nb;
;     const int sc = (mode == 1) ? (((n0 >> 7) & 1) * DFF + (n0 >> 8) * 128 + (n0 & 127)) : n0;
;     const float* src = W + (size_t)k0 * N + sc + lane;
;     float va[32], vb[32];
; #pragma unroll
;     for (int kp = 0; kp < 32; ++kp) { va[kp] = src[(size_t)(2 * kp) * N]; vb[kp] = src[(size_t)(2 * kp + 1) * N]; }
; __device__ __forceinline__ void prep(const Params& p, LAS unsigned char* L, int wv, int vb, int nvb, int l, int mask) {
;     ...
;     PREP_CONV(PM_WIN, PIN(I_WIN) + (size_t)l * DM * NIN, DM, NIN, WL_IN, PIN(I_NMIX) + l * DM, 0)
.LBB0_430:
	v_mov_b32_e32 v8, 0
	v_mov_b32_e32 v10, 0
	v_add_u32_e32 v8, 0, v8
	v_add_u32_e32 v8, 0x20158, v8
	s_nop 0
	s_mul_hi_i32 s14, s94, 0x66666667
	v_add_u32_e32 v10, 0, v10
	v_add_u32_e32 v10, 0x20150, v10
	s_nop 0
	s_waitcnt lgkmcnt(1)
	v_readlane_b32 s18, v251, 22
	v_readlane_b32 s15, v251, 23
	s_waitcnt lgkmcnt(0)
	v_readlane_b32 s0, v251, 20
	v_readlane_b32 s1, v251, 21
	s_add_u32 s95, s0, 0x1000
	s_addc_u32 s96, s1, 0
	s_lshr_b32 s16, s14, 31
	s_ashr_i32 s14, s14, 3
	s_add_i32 s19, s14, s16
	s_lshl_b32 s16, s19, 6
	s_mul_i32 s14, s19, 0xfffffb00
	s_add_i32 s14, s24, s14
	s_ashr_i32 s17, s16, 31
	s_mul_i32 s19, s19, 0x50000
	s_mul_hi_i32 s97, s16, 0x1400
	s_add_u32 vcc_lo, s18, s19
	s_addc_u32 s97, s15, s97
	s_ashr_i32 s15, s14, 31
	s_lshl_b64 s[18:19], s[14:15], 2
	s_add_u32 s18, vcc_lo, s18
	s_addc_u32 s19, s97, s19
	v_lshl_add_u64 v[8:9], s[18:19], 0, v[4:5]
	v_add_co_u32_e32 v10, vcc, s26, v8
	s_cmp_lg_u64 s[0:1], 0
	s_nop 0
	v_addc_co_u32_e32 v11, vcc, 0, v9, vcc
	v_add_co_u32_e32 v12, vcc, s27, v8
	s_cselect_b64 s[18:19], -1, 0
	s_nop 0
	v_addc_co_u32_e32 v13, vcc, 0, v9, vcc
	v_add_co_u32_e32 v14, vcc, s28, v8
	s_cmp_eq_u64 s[0:1], 0
	s_nop 0
	v_addc_co_u32_e32 v15, vcc, 0, v9, vcc
	v_add_co_u32_e32 v16, vcc, s29, v8
	s_mov_b64 s[0:1], -1
	s_nop 0
	v_addc_co_u32_e32 v17, vcc, 0, v9, vcc
	v_add_co_u32_e32 v18, vcc, s30, v8
	s_nop 1
	v_addc_co_u32_e32 v19, vcc, 0, v9, vcc
	v_add_co_u32_e32 v20, vcc, s31, v8
	s_nop 1
	v_addc_co_u32_e32 v21, vcc, 0, v9, vcc
	v_add_co_u32_e32 v22, vcc, s34, v8
	s_nop 1
	v_addc_co_u32_e32 v23, vcc, 0, v9, vcc
	v_add_co_u32_e32 v24, vcc, s35, v8
	s_nop 1
	v_addc_co_u32_e32 v25, vcc, 0, v9, vcc
	global_load_dword v68, v[10:11], off
	global_load_dword v69, v[12:13], off offset:1024
	global_load_dword v70, v[14:15], off offset:2048
	global_load_dword v71, v[16:17], off offset:3072
	global_load_dword v64, v[18:19], off
	global_load_dword v65, v[20:21], off offset:1024
	global_load_dword v66, v[22:23], off offset:2048
	global_load_dword v67, v[24:25], off offset:3072
	v_add_co_u32_e32 v10, vcc, s36, v8
	s_nop 1
	v_addc_co_u32_e32 v11, vcc, 0, v9, vcc
	v_add_co_u32_e32 v12, vcc, s37, v8
	s_nop 1
	v_addc_co_u32_e32 v13, vcc, 0, v9, vcc
	v_add_co_u32_e32 v14, vcc, s38, v8
	s_nop 1
	v_addc_co_u32_e32 v15, vcc, 0, v9, vcc
	v_add_co_u32_e32 v16, vcc, s39, v8
	s_nop 1
	v_addc_co_u32_e32 v17, vcc, 0, v9, vcc
	v_add_co_u32_e32 v18, vcc, s40, v8
	s_nop 1
	v_addc_co_u32_e32 v19, vcc, 0, v9, vcc
	v_add_co_u32_e32 v20, vcc, s41, v8
	s_nop 1
	v_addc_co_u32_e32 v21, vcc, 0, v9, vcc
	v_add_co_u32_e32 v22, vcc, s42, v8
	s_nop 1
	v_addc_co_u32_e32 v23, vcc, 0, v9, vcc
	v_add_co_u32_e32 v24, vcc, s43, v8
	s_nop 1
	v_addc_co_u32_e32 v25, vcc, 0, v9, vcc
	global_load_dword v60, v[10:11], off
	global_load_dword v61, v[12:13], off offset:1024
	global_load_dword v62, v[14:15], off offset:2048
	global_load_dword v63, v[16:17], off offset:3072
	global_load_dword v56, v[18:19], off
	global_load_dword v57, v[20:21], off offset:1024
	global_load_dword v58, v[22:23], off offset:2048
	global_load_dword v59, v[24:25], off offset:3072
	v_add_co_u32_e32 v10, vcc, s44, v8
	s_nop 1
	v_addc_co_u32_e32 v11, vcc, 0, v9, vcc
	v_add_co_u32_e32 v12, vcc, s45, v8
	s_nop 1
	v_addc_co_u32_e32 v13, vcc, 0, v9, vcc
	v_add_co_u32_e32 v14, vcc, s46, v8
	s_nop 1
	v_addc_co_u32_e32 v15, vcc, 0, v9, vcc
	v_add_co_u32_e32 v16, vcc, s47, v8
	s_nop 1
	v_addc_co_u32_e32 v17, vcc, 0, v9, vcc
	v_add_co_u32_e32 v18, vcc, s48, v8
	s_nop 1
	v_addc_co_u32_e32 v19, vcc, 0, v9, vcc
	v_add_co_u32_e32 v20, vcc, s49, v8
	s_nop 1
	v_addc_co_u32_e32 v21, vcc, 0, v9, vcc
	v_add_co_u32_e32 v22, vcc, s50, v8
	s_nop 1
	v_addc_co_u32_e32 v23, vcc, 0, v9, vcc
	v_add_co_u32_e32 v24, vcc, s51, v8
	s_nop 1
	v_addc_co_u32_e32 v25, vcc, 0, v9, vcc
	global_load_dword v52, v[10:11], off
	global_load_dword v53, v[12:13], off offset:1024
	global_load_dword v54, v[14:15], off offset:2048
	global_load_dword v55, v[16:17], off offset:3072
	global_load_dword v48, v[18:19], off
	global_load_dword v49, v[20:21], off offset:1024
	global_load_dword v50, v[22:23], off offset:2048
	global_load_dword v51, v[24:25], off offset:3072
	v_add_co_u32_e32 v10, vcc, s52, v8
	s_nop 1
	v_addc_co_u32_e32 v11, vcc, 0, v9, vcc
	v_add_co_u32_e32 v12, vcc, s53, v8
	s_nop 1
	v_addc_co_u32_e32 v13, vcc, 0, v9, vcc
	v_add_co_u32_e32 v14, vcc, s54, v8
	s_nop 1
	v_addc_co_u32_e32 v15, vcc, 0, v9, vcc
	v_add_co_u32_e32 v16, vcc, s55, v8
	s_nop 1
	v_addc_co_u32_e32 v17, vcc, 0, v9, vcc
	v_add_co_u32_e32 v18, vcc, s56, v8
	s_nop 1
	v_addc_co_u32_e32 v19, vcc, 0, v9, vcc
	v_add_co_u32_e32 v20, vcc, s57, v8
	s_nop 1
	v_addc_co_u32_e32 v21, vcc, 0, v9, vcc
	v_add_co_u32_e32 v22, vcc, s58, v8
	s_nop 1
	v_addc_co_u32_e32 v23, vcc, 0, v9, vcc
	v_add_co_u32_e32 v24, vcc, s59, v8
	s_nop 1
	v_addc_co_u32_e32 v25, vcc, 0, v9, vcc
	global_load_dword v44, v[10:11], off
; __device__ __forceinline__ void transpose_item(const float* W, int K, int N, bf16_t* WT, const float* gk, int mode, LAS float* scr_, int item, int lane) {
;     ...
;     for (int kp = 0; kp < 32; ++kp) { va[kp] = src[(size_t)(2 * kp) * N]; vb[kp] = src[(size_t)(2 * kp + 1) * N]; }
; #pragma unroll
;     for (int kp = 0; kp < 32; ++kp) {
;         float a = va[kp], b = vb[kp];
;         if (gk) { a *= gk[k0 + 2 * kp]; b *= gk[k0 + 2 * kp + 1]; }
	global_load_dword v45, v[12:13], off offset:1024
	global_load_dword v46, v[14:15], off offset:2048
	global_load_dword v47, v[16:17], off offset:3072
	global_load_dword v40, v[18:19], off
	global_load_dword v41, v[20:21], off offset:1024
	global_load_dword v42, v[22:23], off offset:2048
	global_load_dword v43, v[24:25], off offset:3072
	v_add_co_u32_e32 v10, vcc, s64, v8
	s_nop 1
	v_addc_co_u32_e32 v11, vcc, 0, v9, vcc
	v_add_co_u32_e32 v12, vcc, s65, v8
	s_nop 1
	v_addc_co_u32_e32 v13, vcc, 0, v9, vcc
	v_add_co_u32_e32 v14, vcc, s66, v8
	s_nop 1
	v_addc_co_u32_e32 v15, vcc, 0, v9, vcc
	v_add_co_u32_e32 v16, vcc, s67, v8
	s_nop 1
	v_addc_co_u32_e32 v17, vcc, 0, v9, vcc
	v_add_co_u32_e32 v18, vcc, s68, v8
	s_nop 1
	v_addc_co_u32_e32 v19, vcc, 0, v9, vcc
	v_add_co_u32_e32 v20, vcc, s69, v8
	s_nop 1
	v_addc_co_u32_e32 v21, vcc, 0, v9, vcc
	v_add_co_u32_e32 v22, vcc, s70, v8
	s_nop 1
	v_addc_co_u32_e32 v23, vcc, 0, v9, vcc
	v_add_co_u32_e32 v24, vcc, s71, v8
	s_nop 1
	v_addc_co_u32_e32 v25, vcc, 0, v9, vcc
	global_load_dword v36, v[10:11], off
	global_load_dword v37, v[12:13], off offset:1024
	global_load_dword v38, v[14:15], off offset:2048
	global_load_dword v39, v[16:17], off offset:3072
	global_load_dword v32, v[18:19], off
	global_load_dword v33, v[20:21], off offset:1024
	global_load_dword v34, v[22:23], off offset:2048
	global_load_dword v35, v[24:25], off offset:3072
	v_add_co_u32_e32 v10, vcc, s72, v8
	s_nop 1
	v_addc_co_u32_e32 v11, vcc, 0, v9, vcc
	v_add_co_u32_e32 v12, vcc, s73, v8
	s_nop 1
	v_addc_co_u32_e32 v13, vcc, 0, v9, vcc
	v_add_co_u32_e32 v14, vcc, s74, v8
	s_nop 1
	v_addc_co_u32_e32 v15, vcc, 0, v9, vcc
	v_add_co_u32_e32 v16, vcc, s75, v8
	s_nop 1
	v_addc_co_u32_e32 v17, vcc, 0, v9, vcc
	v_add_co_u32_e32 v18, vcc, s76, v8
	s_nop 1
	v_addc_co_u32_e32 v19, vcc, 0, v9, vcc
	v_add_co_u32_e32 v20, vcc, s77, v8
	s_nop 1
	v_addc_co_u32_e32 v21, vcc, 0, v9, vcc
	v_add_co_u32_e32 v22, vcc, s78, v8
	s_nop 1
	v_addc_co_u32_e32 v23, vcc, 0, v9, vcc
	v_add_co_u32_e32 v72, vcc, s79, v8
	s_nop 1
	v_addc_co_u32_e32 v73, vcc, 0, v9, vcc
	global_load_dword v28, v[10:11], off
	global_load_dword v29, v[12:13], off offset:1024
	global_load_dword v30, v[14:15], off offset:2048
	global_load_dword v31, v[16:17], off offset:3072
	global_load_dword v24, v[18:19], off
	global_load_dword v25, v[20:21], off offset:1024
	global_load_dword v26, v[22:23], off offset:2048
	global_load_dword v27, v[72:73], off offset:3072
	v_add_co_u32_e32 v10, vcc, s80, v8
	s_nop 1
	v_addc_co_u32_e32 v11, vcc, 0, v9, vcc
	v_add_co_u32_e32 v12, vcc, s81, v8
	s_nop 1
	v_addc_co_u32_e32 v13, vcc, 0, v9, vcc
	v_add_co_u32_e32 v14, vcc, s82, v8
	s_nop 1
	v_addc_co_u32_e32 v15, vcc, 0, v9, vcc
	v_add_co_u32_e32 v16, vcc, s83, v8
	s_nop 1
	v_addc_co_u32_e32 v17, vcc, 0, v9, vcc
	v_add_co_u32_e32 v18, vcc, s84, v8
	s_nop 1
	v_addc_co_u32_e32 v19, vcc, 0, v9, vcc
	v_add_co_u32_e32 v72, vcc, s85, v8
	s_nop 1
	v_addc_co_u32_e32 v73, vcc, 0, v9, vcc
	v_add_co_u32_e32 v74, vcc, s86, v8
	s_nop 1
	v_addc_co_u32_e32 v75, vcc, 0, v9, vcc
	v_add_co_u32_e32 v80, vcc, s87, v8
	s_nop 1
	v_addc_co_u32_e32 v81, vcc, 0, v9, vcc
	global_load_dword v20, v[10:11], off
	global_load_dword v21, v[12:13], off offset:1024
	global_load_dword v22, v[14:15], off offset:2048
	global_load_dword v23, v[16:17], off offset:3072
	s_nop 0
	global_load_dword v16, v[18:19], off
	global_load_dword v17, v[72:73], off offset:1024
	s_nop 0
	global_load_dword v18, v[74:75], off offset:2048
	global_load_dword v19, v[80:81], off offset:3072
	v_add_co_u32_e32 v10, vcc, s88, v8
	s_nop 1
	v_addc_co_u32_e32 v11, vcc, 0, v9, vcc
	v_add_co_u32_e32 v14, vcc, s89, v8
	s_nop 1
	v_addc_co_u32_e32 v15, vcc, 0, v9, vcc
	v_add_co_u32_e32 v72, vcc, s90, v8
	s_nop 1
	v_addc_co_u32_e32 v73, vcc, 0, v9, vcc
	v_add_co_u32_e32 v74, vcc, s91, v8
	s_nop 1
	v_addc_co_u32_e32 v75, vcc, 0, v9, vcc
	v_add_co_u32_e32 v80, vcc, s92, v8
	s_nop 1
	v_addc_co_u32_e32 v81, vcc, 0, v9, vcc
	v_add_co_u32_e32 v82, vcc, s93, v8
	s_nop 1
	v_addc_co_u32_e32 v83, vcc, 0, v9, vcc
	v_add_co_u32_e32 v84, vcc, 0x54d000, v8
	s_nop 1
	v_addc_co_u32_e32 v85, vcc, 0, v9, vcc
	v_add_co_u32_e32 v86, vcc, 0x54e000, v8
	s_nop 1
	v_addc_co_u32_e32 v87, vcc, 0, v9, vcc
	global_load_dword v12, v[10:11], off
	global_load_dword v13, v[14:15], off offset:1024
	s_nop 0
	global_load_dword v14, v[72:73], off offset:2048
	global_load_dword v15, v[74:75], off offset:3072
	global_load_dword v8, v[80:81], off
	global_load_dword v9, v[82:83], off offset:1024
	global_load_dword v10, v[84:85], off offset:2048
	global_load_dword v11, v[86:87], off offset:3072
	s_cbranch_scc1 .LBB0_432
	s_lshl_b64 s[0:1], s[16:17], 2
	s_add_u32 s0, s95, s0
	s_addc_u32 s1, s96, s1
	global_load_dwordx4 v[72:75], v5, s[0:1]
	s_mov_b64 s[0:1], 0
	s_waitcnt vmcnt(0)
	v_pk_mul_f32 v[72:73], v[68:69], v[72:73]
	v_pk_mul_f32 v[74:75], v[70:71], v[74:75]

; #define LAS __attribute__((address_space(3)))
; #define PIN(i) ((const float*)ldq_(L, (i)))
; __device__ __forceinline__ unsigned pk2(float lo, float hi) { f32x2 v = {lo, hi}; bf16x2_t b = __builtin_convertvector(v, bf16x2_t); return __builtin_bit_cast(unsigned, b); }
; #define PREP_CONV(bit, SRC, Kd, Nd, DST, GK, MODE) if (mask & (bit)) { for (int it = gw; it < ((Kd) / 64) * ((Nd) / 64); it += NGW) transpose_item((SRC), (Kd), (Nd), (bf16_t*)(wl + (DST)), (GK), (MODE), scr, it, lane); }
; __device__ __forceinline__ void transpose_item(const float* W, int K, int N, bf16_t* WT, const float* gk, int mode, LAS float* scr_, int item, int lane) {
;     ...
;     const int nblk = N / 64, kb = item / nblk, nb = item % nblk, k0 = 64 * kb, n0 = 64 * nb;
;     const int sc = (mode == 1) ? (((n0 >> 7) & 1) * DFF + (n0 >> 8) * 128 + (n0 & 127)) : n0;
;     const float* src = W + (size_t)k0 * N + sc + lane;
;     float va[32], vb[32];
; #pragma unroll
;     for (int kp = 0; kp < 32; ++kp) { va[kp] = src[(size_t)(2 * kp) * N]; vb[kp] = src[(size_t)(2 * kp + 1) * N]; }
; #pragma unroll
;     for (int kp = 0; kp < 32; ++kp) {
;         float a = va[kp], b = vb[kp];
;         if (gk) { a *= gk[k0 + 2 * kp]; b *= gk[k0 + 2 * kp + 1]; }
;         scr[kp * 65 + lane] = pk2(a, b);
;     }
;     asm volatile("s_waitcnt lgkmcnt(0)" ::: "memory");
;     const int c = lane & 7;
; #pragma unroll
;     for (int j = 0; j < 8; ++j) { const int r = (lane >> 3) + 8 * j; const LAS unsigned* q = scr + (4 * c) * 65 + r;
;         u32x4 o; o.x = q[0]; o.y = q[65]; o.z = q[130]; o.w = q[195];
;         *(u32x4*)(WT + (size_t)(n0 + r) * K + k0 + 8 * c) = o; }
; __device__ __forceinline__ void prep(const Params& p, LAS unsigned char* L, int wv, int vb, int nvb, int l, int mask) {
;     ...
;     PREP_CONV(PM_WOUT, PIN(I_WOUT) + (size_t)l * DM * DM, DM, DM, WL_OUT, nullptr, 0)
.LBB0_496:
	v_mov_b32_e32 v8, 0
	s_ashr_i32 s0, s64, 31
	v_add_u32_e32 v8, 0, v8
	v_add_u32_e32 v8, 0x20188, v8
	s_lshr_b32 s0, s0, 28
	s_nop 0
	s_add_i32 s0, s64, s0
	s_ashr_i32 s0, s0, 4
	s_lshl_b32 s18, s0, 6
	s_lshl_b32 s0, s0, 10
	s_ashr_i32 s19, s18, 31
	s_sub_i32 s0, s24, s0
	s_lshl_b64 s[16:17], s[18:19], 12
	v_lshl_add_u64 v[18:19], s[18:19], 1, v[6:7]
	s_waitcnt lgkmcnt(0)
	v_readlane_b32 s18, v251, 34
	v_readlane_b32 s1, v251, 35
	s_add_u32 s16, s18, s16
	v_add_u32_e32 v20, s0, v78
	s_addc_u32 s17, s1, s17
	s_ashr_i32 s1, s0, 31
	v_ashrrev_i32_e32 v21, 31, v20
	v_add_u32_e32 v22, 8, v20
	v_add_u32_e32 v24, 16, v20
	v_add_u32_e32 v26, 24, v20
	v_add_u32_e32 v28, 32, v20
	v_add_u32_e32 v30, 40, v20
	v_add_u32_e32 v32, 48, v20
	v_add_u32_e32 v34, 56, v20
	s_lshl_b64 s[0:1], s[0:1], 2
	v_lshlrev_b64 v[20:21], 11, v[20:21]
	v_ashrrev_i32_e32 v23, 31, v22
	v_ashrrev_i32_e32 v25, 31, v24
	v_ashrrev_i32_e32 v27, 31, v26
	v_ashrrev_i32_e32 v29, 31, v28
	v_ashrrev_i32_e32 v31, 31, v30
	v_ashrrev_i32_e32 v33, 31, v32
	v_ashrrev_i32_e32 v35, 31, v34
	s_add_u32 s0, s16, s0
	v_lshl_add_u64 v[8:9], v[18:19], 0, v[20:21]
	v_lshlrev_b64 v[20:21], 11, v[22:23]
	v_lshlrev_b64 v[22:23], 11, v[24:25]
	v_lshlrev_b64 v[24:25], 11, v[26:27]
	v_lshlrev_b64 v[26:27], 11, v[28:29]
	v_lshlrev_b64 v[28:29], 11, v[30:31]
	v_lshlrev_b64 v[30:31], 11, v[32:33]
	v_lshlrev_b64 v[32:33], 11, v[34:35]
	s_addc_u32 s1, s17, s1
	v_lshl_add_u64 v[50:51], v[18:19], 0, v[20:21]
	v_lshl_add_u64 v[52:53], v[18:19], 0, v[22:23]
	v_lshl_add_u64 v[54:55], v[18:19], 0, v[24:25]
	v_lshl_add_u64 v[56:57], v[18:19], 0, v[26:27]
	v_lshl_add_u64 v[58:59], v[18:19], 0, v[28:29]
	v_lshl_add_u64 v[60:61], v[18:19], 0, v[30:31]
	v_lshl_add_u64 v[62:63], v[18:19], 0, v[32:33]
	v_lshl_add_u64 v[18:19], s[0:1], 0, v[4:5]
	v_add_co_u32_e32 v20, vcc, s26, v18
	s_add_i32 s64, s64, s60
	s_nop 0
	v_addc_co_u32_e32 v21, vcc, 0, v19, vcc
	v_add_co_u32_e32 v22, vcc, s27, v18
	s_add_i32 s24, s24, s25
	s_nop 0
	v_addc_co_u32_e32 v23, vcc, 0, v19, vcc
	v_add_co_u32_e32 v24, vcc, s28, v18
	s_cmpk_lt_i32 s64, 0x100
	s_nop 0
	v_addc_co_u32_e32 v25, vcc, 0, v19, vcc
	v_add_co_u32_e32 v26, vcc, s29, v18
	s_nop 1
	v_addc_co_u32_e32 v27, vcc, 0, v19, vcc
	v_add_co_u32_e32 v28, vcc, s30, v18
	s_nop 1
	v_addc_co_u32_e32 v29, vcc, 0, v19, vcc
	v_add_co_u32_e32 v30, vcc, s31, v18
	s_nop 1
	v_addc_co_u32_e32 v31, vcc, 0, v19, vcc
	v_add_co_u32_e32 v32, vcc, s34, v18
	s_nop 1
	v_addc_co_u32_e32 v33, vcc, 0, v19, vcc
	v_add_co_u32_e32 v34, vcc, s35, v18
	s_nop 1
	v_addc_co_u32_e32 v35, vcc, 0, v19, vcc
	v_add_co_u32_e32 v36, vcc, s36, v18
	s_nop 1
	v_addc_co_u32_e32 v37, vcc, 0, v19, vcc
	v_add_co_u32_e32 v38, vcc, s37, v18
	s_nop 1
	v_addc_co_u32_e32 v39, vcc, 0, v19, vcc
	v_add_co_u32_e32 v40, vcc, s38, v18
	s_nop 1
	v_addc_co_u32_e32 v41, vcc, 0, v19, vcc
	v_add_co_u32_e32 v42, vcc, s39, v18
	s_nop 1
	v_addc_co_u32_e32 v43, vcc, 0, v19, vcc
	v_add_co_u32_e32 v44, vcc, s40, v18
	s_nop 1
	v_addc_co_u32_e32 v45, vcc, 0, v19, vcc
	v_add_co_u32_e32 v46, vcc, s41, v18
	s_nop 1
	v_addc_co_u32_e32 v47, vcc, 0, v19, vcc
	v_add_co_u32_e32 v48, vcc, s42, v18
	s_nop 1
	v_addc_co_u32_e32 v49, vcc, 0, v19, vcc
	v_add_co_u32_e32 v64, vcc, s43, v18
	s_nop 1
	v_addc_co_u32_e32 v65, vcc, 0, v19, vcc
	v_add_co_u32_e32 v66, vcc, s44, v18
	s_nop 1
	v_addc_co_u32_e32 v67, vcc, 0, v19, vcc
	v_add_co_u32_e32 v68, vcc, s45, v18
	s_nop 1
	v_addc_co_u32_e32 v69, vcc, 0, v19, vcc
	v_add_co_u32_e32 v70, vcc, s46, v18
	s_nop 1
	v_addc_co_u32_e32 v71, vcc, 0, v19, vcc
	v_add_co_u32_e32 v72, vcc, s47, v18
	s_nop 1
	v_addc_co_u32_e32 v73, vcc, 0, v19, vcc
	v_add_co_u32_e32 v74, vcc, s48, v18
	s_nop 1
	v_addc_co_u32_e32 v75, vcc, 0, v19, vcc
	v_add_co_u32_e32 v80, vcc, s49, v18
	s_nop 1
	v_addc_co_u32_e32 v81, vcc, 0, v19, vcc
	v_add_co_u32_e32 v82, vcc, s50, v18
	s_nop 1
	v_addc_co_u32_e32 v83, vcc, 0, v19, vcc
	v_add_co_u32_e32 v84, vcc, s51, v18
	s_nop 1
	v_addc_co_u32_e32 v85, vcc, 0, v19, vcc
	v_add_co_u32_e32 v86, vcc, s52, v18
	s_nop 1
	v_addc_co_u32_e32 v87, vcc, 0, v19, vcc
	v_add_co_u32_e32 v88, vcc, s53, v18
	s_nop 1
	v_addc_co_u32_e32 v89, vcc, 0, v19, vcc
	v_add_co_u32_e32 v90, vcc, s54, v18
	s_nop 1
	v_addc_co_u32_e32 v91, vcc, 0, v19, vcc
	v_add_co_u32_e32 v92, vcc, s55, v18
	s_nop 1
	v_addc_co_u32_e32 v93, vcc, 0, v19, vcc
	v_add_co_u32_e32 v94, vcc, s56, v18
	s_nop 1
	v_addc_co_u32_e32 v95, vcc, 0, v19, vcc
	v_add_co_u32_e32 v96, vcc, s57, v18
	s_nop 1
	v_addc_co_u32_e32 v97, vcc, 0, v19, vcc
	v_add_co_u32_e32 v98, vcc, s58, v18
	s_nop 1
	v_addc_co_u32_e32 v99, vcc, 0, v19, vcc
	v_add_co_u32_e32 v18, vcc, s59, v18
	s_nop 1
	v_addc_co_u32_e32 v19, vcc, 0, v19, vcc
	global_load_dword v79, v[20:21], off offset:-4096
	s_nop 0
	global_load_dword v20, v[20:21], off
	s_nop 0
	global_load_dword v21, v[22:23], off offset:-4096
	s_nop 0
	global_load_dword v22, v[22:23], off
	s_nop 0
	global_load_dword v23, v[24:25], off offset:-4096
	s_nop 0
	global_load_dword v24, v[24:25], off
	s_nop 0
	global_load_dword v25, v[26:27], off offset:-4096
	s_nop 0
	global_load_dword v26, v[26:27], off
	s_nop 0
	global_load_dword v27, v[28:29], off offset:-4096
	s_nop 0
	global_load_dword v28, v[28:29], off
	s_nop 0
	global_load_dword v29, v[30:31], off offset:-4096
	s_nop 0
	global_load_dword v30, v[30:31], off
	s_nop 0
	global_load_dword v31, v[32:33], off offset:-4096
	s_nop 0
	global_load_dword v32, v[32:33], off
	s_nop 0
	global_load_dword v33, v[34:35], off offset:-4096
	s_nop 0
	global_load_dword v34, v[34:35], off
	s_nop 0
	global_load_dword v35, v[36:37], off offset:-4096
	s_nop 0
	global_load_dword v36, v[36:37], off
	s_nop 0
; #define LAS __attribute__((address_space(3)))
; __device__ __forceinline__ unsigned pk2(float lo, float hi) { f32x2 v = {lo, hi}; bf16x2_t b = __builtin_convertvector(v, bf16x2_t); return __builtin_bit_cast(unsigned, b); }
; __device__ __forceinline__ void transpose_item(const float* W, int K, int N, bf16_t* WT, const float* gk, int mode, LAS float* scr_, int item, int lane) {
;     ...
;     for (int kp = 0; kp < 32; ++kp) { va[kp] = src[(size_t)(2 * kp) * N]; vb[kp] = src[(size_t)(2 * kp + 1) * N]; }
; #pragma unroll
;     for (int kp = 0; kp < 32; ++kp) {
;         float a = va[kp], b = vb[kp];
;         if (gk) { a *= gk[k0 + 2 * kp]; b *= gk[k0 + 2 * kp + 1]; }
;         scr[kp * 65 + lane] = pk2(a, b);
;     }
;     asm volatile("s_waitcnt lgkmcnt(0)" ::: "memory");
;     const int c = lane & 7;
; #pragma unroll
;     for (int j = 0; j < 8; ++j) { const int r = (lane >> 3) + 8 * j; const LAS unsigned* q = scr + (4 * c) * 65 + r;
;         u32x4 o; o.x = q[0]; o.y = q[65]; o.z = q[130]; o.w = q[195];
;         *(u32x4*)(WT + (size_t)(n0 + r) * K + k0 + 8 * c) = o; }
;     asm volatile("s_waitcnt lgkmcnt(0)" ::: "memory");
	global_load_dword v37, v[38:39], off offset:-4096
	s_nop 0
	global_load_dword v38, v[38:39], off
	s_nop 0
	global_load_dword v39, v[40:41], off offset:-4096
	s_nop 0
	global_load_dword v40, v[40:41], off
	s_nop 0
	global_load_dword v41, v[42:43], off offset:-4096
	s_nop 0
	global_load_dword v42, v[42:43], off
	s_nop 0
	global_load_dword v43, v[44:45], off offset:-4096
	s_nop 0
	global_load_dword v44, v[44:45], off
	s_nop 0
	global_load_dword v45, v[46:47], off offset:-4096
	s_nop 0
	global_load_dword v46, v[46:47], off
	s_nop 0
	global_load_dword v47, v[48:49], off offset:-4096
	s_nop 0
	global_load_dword v48, v[48:49], off
	s_nop 0
	global_load_dword v49, v[64:65], off offset:-4096
	s_nop 0
	global_load_dword v64, v[64:65], off
	s_nop 0
	global_load_dword v65, v[66:67], off offset:-4096
	s_nop 0
	global_load_dword v66, v[66:67], off
	s_nop 0
	global_load_dword v67, v[68:69], off offset:-4096
	s_nop 0
	global_load_dword v68, v[68:69], off
	s_nop 0
	global_load_dword v69, v[70:71], off offset:-4096
	s_nop 0
	global_load_dword v70, v[70:71], off
	s_nop 0
	global_load_dword v71, v[72:73], off offset:-4096
	s_nop 0
	global_load_dword v72, v[72:73], off
	s_nop 0
	global_load_dword v73, v[74:75], off offset:-4096
	s_nop 0
	global_load_dword v74, v[74:75], off
	s_nop 0
	global_load_dword v75, v[80:81], off offset:-4096
	s_nop 0
	global_load_dword v80, v[80:81], off
	s_nop 0
	global_load_dword v81, v[82:83], off offset:-4096
	s_nop 0
	global_load_dword v82, v[82:83], off
	s_nop 0
	global_load_dword v83, v[84:85], off offset:-4096
	s_nop 0
	global_load_dword v84, v[84:85], off
	s_nop 0
	global_load_dword v85, v[86:87], off offset:-4096
	s_nop 0
	global_load_dword v86, v[86:87], off
	s_nop 0
	global_load_dword v87, v[88:89], off offset:-4096
	s_nop 0
	global_load_dword v88, v[88:89], off
	s_nop 0
	global_load_dword v89, v[90:91], off offset:-4096
	s_nop 0
	global_load_dword v90, v[90:91], off
	s_nop 0
	global_load_dword v91, v[92:93], off offset:-4096
	s_nop 0
	global_load_dword v92, v[92:93], off
	s_nop 0
	global_load_dword v93, v[94:95], off offset:-4096
	s_nop 0
	global_load_dword v94, v[94:95], off
	s_nop 0
	global_load_dword v95, v[96:97], off offset:-4096
	s_nop 0
	global_load_dword v96, v[96:97], off
	s_nop 0
	global_load_dword v97, v[98:99], off offset:-4096
	s_nop 0
	global_load_dword v98, v[98:99], off
	s_nop 0
	global_load_dword v99, v[18:19], off offset:-4096
	s_nop 0
	global_load_dword v18, v[18:19], off
	s_waitcnt vmcnt(62)
	v_cvt_pk_bf16_f32 v19, v79, v20
	s_waitcnt vmcnt(60)
	v_cvt_pk_bf16_f32 v20, v21, v22
	s_waitcnt vmcnt(58)
	v_cvt_pk_bf16_f32 v21, v23, v24
	s_waitcnt vmcnt(56)
	v_cvt_pk_bf16_f32 v22, v25, v26
	s_waitcnt vmcnt(54)
	v_cvt_pk_bf16_f32 v23, v27, v28
	s_waitcnt vmcnt(52)
	v_cvt_pk_bf16_f32 v24, v29, v30
	s_waitcnt vmcnt(50)
	v_cvt_pk_bf16_f32 v25, v31, v32
	s_waitcnt vmcnt(48)
	v_cvt_pk_bf16_f32 v26, v33, v34
	s_waitcnt vmcnt(46)
	v_cvt_pk_bf16_f32 v27, v35, v36
	s_waitcnt vmcnt(44)
	v_cvt_pk_bf16_f32 v28, v37, v38
	s_waitcnt vmcnt(42)
	v_cvt_pk_bf16_f32 v29, v39, v40
	s_waitcnt vmcnt(40)
	v_cvt_pk_bf16_f32 v30, v41, v42
	s_waitcnt vmcnt(38)
	v_cvt_pk_bf16_f32 v31, v43, v44
	s_waitcnt vmcnt(36)
	v_cvt_pk_bf16_f32 v32, v45, v46
	s_waitcnt vmcnt(34)
	v_cvt_pk_bf16_f32 v33, v47, v48
	s_waitcnt vmcnt(32)
	v_cvt_pk_bf16_f32 v34, v49, v64
	s_waitcnt vmcnt(30)
	v_cvt_pk_bf16_f32 v35, v65, v66
	s_waitcnt vmcnt(28)
	v_cvt_pk_bf16_f32 v36, v67, v68
	s_waitcnt vmcnt(26)
	v_cvt_pk_bf16_f32 v37, v69, v70
	s_waitcnt vmcnt(24)
	v_cvt_pk_bf16_f32 v38, v71, v72
	s_waitcnt vmcnt(22)
	v_cvt_pk_bf16_f32 v39, v73, v74
	s_waitcnt vmcnt(20)
	v_cvt_pk_bf16_f32 v40, v75, v80
	s_waitcnt vmcnt(18)
	v_cvt_pk_bf16_f32 v41, v81, v82
	s_waitcnt vmcnt(16)
	v_cvt_pk_bf16_f32 v42, v83, v84
	s_waitcnt vmcnt(14)
	v_cvt_pk_bf16_f32 v43, v85, v86
	s_waitcnt vmcnt(12)
	v_cvt_pk_bf16_f32 v44, v87, v88
	s_waitcnt vmcnt(10)
	v_cvt_pk_bf16_f32 v45, v89, v90
	s_waitcnt vmcnt(8)
	v_cvt_pk_bf16_f32 v46, v91, v92
	s_waitcnt vmcnt(6)
	v_cvt_pk_bf16_f32 v47, v93, v94
	s_waitcnt vmcnt(4)
	v_cvt_pk_bf16_f32 v48, v95, v96
	s_waitcnt vmcnt(2)
	v_cvt_pk_bf16_f32 v49, v97, v98
	s_waitcnt vmcnt(0)
	v_cvt_pk_bf16_f32 v18, v99, v18
	ds_write2_b32 v77, v19, v20 offset1:65
	ds_write2_b32 v77, v21, v22 offset0:130 offset1:195
	ds_write2_b32 v11, v23, v24 offset0:4 offset1:69
	ds_write2_b32 v11, v25, v26 offset0:134 offset1:199
	ds_write2_b32 v12, v27, v28 offset0:8 offset1:73
	ds_write2_b32 v12, v29, v30 offset0:138 offset1:203
	ds_write2_b32 v13, v31, v32 offset0:12 offset1:77
	ds_write2_b32 v13, v33, v34 offset0:142 offset1:207
	ds_write2_b32 v14, v35, v36 offset0:16 offset1:81
	ds_write2_b32 v14, v37, v38 offset0:146 offset1:211
	ds_write2_b32 v15, v39, v40 offset0:20 offset1:85
	ds_write2_b32 v15, v41, v42 offset0:150 offset1:215
	ds_write2_b32 v16, v43, v44 offset0:24 offset1:89
	ds_write2_b32 v16, v45, v46 offset0:154 offset1:219
	ds_write2_b32 v17, v47, v48 offset0:28 offset1:93
	ds_write2_b32 v17, v49, v18 offset0:158 offset1:223
	s_waitcnt lgkmcnt(0)
	ds_read2_b32 v[18:19], v10 offset0:65 offset1:73
	ds_read2_b32 v[38:39], v10 offset0:130 offset1:138
	ds_read2_b32 v[20:21], v10 offset0:195 offset1:203
	ds_read2_b32 v[40:41], v10 offset1:8
	ds_read2_b32 v[42:43], v10 offset0:16 offset1:24
	ds_read2_b32 v[22:23], v10 offset0:81 offset1:89
	ds_read2_b32 v[44:45], v10 offset0:146 offset1:154
	ds_read2_b32 v[24:25], v10 offset0:211 offset1:219
	ds_read2_b32 v[26:27], v10 offset0:97 offset1:105
	ds_read2_b32 v[46:47], v10 offset0:162 offset1:170
	ds_read2_b32 v[28:29], v10 offset0:227 offset1:235
	ds_read2_b32 v[48:49], v10 offset0:32 offset1:40
	ds_read2_b32 v[64:65], v10 offset0:48 offset1:56
	ds_read2_b32 v[30:31], v10 offset0:113 offset1:121
	ds_read2_b32 v[66:67], v10 offset0:178 offset1:186
	ds_read2_b32 v[32:33], v10 offset0:243 offset1:251
	s_waitcnt lgkmcnt(12)
	v_mov_b32_e32 v34, v40
	v_mov_b32_e32 v35, v18
	v_mov_b32_e32 v36, v38
	v_mov_b32_e32 v37, v20
	v_mov_b32_e32 v18, v41
	v_mov_b32_e32 v20, v39
	s_waitcnt lgkmcnt(11)
	v_mov_b32_e32 v38, v42
	s_waitcnt lgkmcnt(10)
	v_mov_b32_e32 v39, v22
	s_waitcnt lgkmcnt(9)
	v_mov_b32_e32 v40, v44
	s_waitcnt lgkmcnt(8)
	v_mov_b32_e32 v41, v24
	v_mov_b32_e32 v22, v43
	v_mov_b32_e32 v24, v45
	s_waitcnt lgkmcnt(4)
	v_mov_b32_e32 v42, v48
	v_mov_b32_e32 v43, v26
	v_mov_b32_e32 v44, v46
	v_mov_b32_e32 v45, v28
	v_mov_b32_e32 v26, v49
	v_mov_b32_e32 v28, v47
	s_waitcnt lgkmcnt(3)
	v_mov_b32_e32 v46, v64
	s_waitcnt lgkmcnt(2)
	v_mov_b32_e32 v47, v30
	s_waitcnt lgkmcnt(1)
	v_mov_b32_e32 v48, v66
	s_waitcnt lgkmcnt(0)
	v_mov_b32_e32 v49, v32
	v_mov_b32_e32 v30, v65
	v_mov_b32_e32 v32, v67
	global_store_dwordx4 v[8:9], v[34:37], off
	global_store_dwordx4 v[50:51], v[18:21], off
	global_store_dwordx4 v[52:53], v[38:41], off
	global_store_dwordx4 v[54:55], v[22:25], off
	global_store_dwordx4 v[56:57], v[42:45], off
	global_store_dwordx4 v[58:59], v[26:29], off
	global_store_dwordx4 v[60:61], v[46:49], off
	global_store_dwordx4 v[62:63], v[30:33], off
	s_waitcnt lgkmcnt(0)
	s_cbranch_scc1 .LBB0_496

; #define LAS __attribute__((address_space(3)))
; #define PIN(i) ((const float*)ldq_(L, (i)))
; #define PREP_CONV(bit, SRC, Kd, Nd, DST, GK, MODE) if (mask & (bit)) { for (int it = gw; it < ((Kd) / 64) * ((Nd) / 64); it += NGW) transpose_item((SRC), (Kd), (Nd), (bf16_t*)(wl + (DST)), (GK), (MODE), scr, it, lane); }
; __device__ __forceinline__ void transpose_item(const float* W, int K, int N, bf16_t* WT, const float* gk, int mode, LAS float* scr_, int item, int lane) {
;     LAS unsigned* scr = (LAS unsigned*)scr_;
;     const int nblk = N / 64, kb = item / nblk, nb = item % nblk, k0 = 64 * kb, n0 = 64 * nb;
;     const int sc = (mode == 1) ? (((n0 >> 7) & 1) * DFF + (n0 >> 8) * 128 + (n0 & 127)) : n0;
;     const float* src = W + (size_t)k0 * N + sc + lane;
;     float va[32], vb[32];
; #pragma unroll
;     for (int kp = 0; kp < 32; ++kp) { va[kp] = src[(size_t)(2 * kp) * N]; vb[kp] = src[(size_t)(2 * kp + 1) * N]; }
; #pragma unroll
;     for (int kp = 0; kp < 32; ++kp) {
;         float a = va[kp], b = vb[kp];
;         if (gk) { a *= gk[k0 + 2 * kp]; b *= gk[k0 + 2 * kp + 1]; }
; __device__ __forceinline__ void prep(const Params& p, LAS unsigned char* L, int wv, int vb, int nvb, int l, int mask) {
;     ...
;     PREP_CONV(PM_FFB_IN, PIN(I_WFFB_IN) + (size_t)l * DM * NFF2, DM, NFF2, WL_FFB_IN, PIN(I_NFFB) + l * DM, 1)
.LBB0_500:
	v_mov_b32_e32 v8, 0
	v_mov_b32_e32 v10, 0
	v_add_u32_e32 v8, 0, v8
	v_add_u32_e32 v8, 0x20198, v8
	ds_read_b64 v[8:9], v8
	s_mul_hi_i32 s10, s94, 0x2e8ba2e9
	v_add_u32_e32 v10, 0, v10
	v_add_u32_e32 v10, 0x20190, v10
	s_nop 0
	s_waitcnt lgkmcnt(1)
	v_readfirstlane_b32 vcc_lo, v8
	v_readfirstlane_b32 s17, v9
	s_waitcnt lgkmcnt(0)
	v_readlane_b32 s0, v251, 36
	v_readlane_b32 s1, v251, 37
	s_add_u32 s96, s0, 0x1000
	s_addc_u32 s97, s1, 0
	s_lshr_b32 s11, s10, 31
	s_ashr_i32 s10, s10, 4
	s_add_i32 vcc_hi, s10, s11
	s_mul_i32 s11, vcc_hi, 0xffffea00
	s_mul_i32 s16, vcc_hi, 0xfffff500
	s_add_i32 s95, s18, s11
	s_bfe_i32 s11, s94, 0x10001
	s_add_i32 s16, s24, s16
	s_and_b32 s11, s11, 0xb00
	s_and_b32 s16, s16, 0xffffff80
	s_lshl_b32 s10, vcc_hi, 6
	s_add_i32 s11, s11, s16
	s_and_b32 s16, s95, 64
	s_or_b32 s16, s11, s16
	s_ashr_i32 s11, s10, 31
	s_mul_i32 vcc_hi, vcc_hi, 0x160000
	s_mul_hi_i32 s3, s10, 0x5800
	s_add_u32 vcc_lo, vcc_lo, vcc_hi
	s_addc_u32 s3, s17, s3
	s_ashr_i32 s17, s16, 31
	s_lshl_b64 s[16:17], s[16:17], 2
	s_add_u32 s16, vcc_lo, s16
	s_addc_u32 s17, s3, s17
	v_lshl_add_u64 v[8:9], s[16:17], 0, v[4:5]
	v_add_co_u32_e32 v10, vcc, s26, v8
	s_cmp_lg_u64 s[0:1], 0
	s_nop 0
	v_addc_co_u32_e32 v11, vcc, 0, v9, vcc
	v_add_co_u32_e32 v12, vcc, s27, v8
	s_cselect_b64 s[16:17], -1, 0
	s_nop 0
	v_addc_co_u32_e32 v13, vcc, 0, v9, vcc
	v_add_co_u32_e32 v14, vcc, s28, v8
	s_cmp_eq_u64 s[0:1], 0
	s_nop 0
	v_addc_co_u32_e32 v15, vcc, 0, v9, vcc
	v_add_co_u32_e32 v16, vcc, s29, v8
	s_mov_b64 s[0:1], -1
	s_nop 0
	v_addc_co_u32_e32 v17, vcc, 0, v9, vcc
	v_add_co_u32_e32 v18, vcc, s30, v8
	s_nop 1
	v_addc_co_u32_e32 v19, vcc, 0, v9, vcc
	v_add_co_u32_e32 v20, vcc, s31, v8
	s_nop 1
	v_addc_co_u32_e32 v21, vcc, 0, v9, vcc
	v_add_co_u32_e32 v22, vcc, s34, v8
	s_nop 1
	v_addc_co_u32_e32 v23, vcc, 0, v9, vcc
	v_add_co_u32_e32 v24, vcc, s35, v8
	s_nop 1
	v_addc_co_u32_e32 v25, vcc, 0, v9, vcc
	global_load_dword v68, v[10:11], off
	global_load_dword v69, v[12:13], off offset:2048
	global_load_dword v70, v[14:15], off
	global_load_dword v71, v[16:17], off offset:2048
	global_load_dword v64, v[18:19], off
	global_load_dword v65, v[20:21], off offset:2048
	global_load_dword v66, v[22:23], off
	global_load_dword v67, v[24:25], off offset:2048
	v_add_co_u32_e32 v10, vcc, s36, v8
	s_nop 1
	v_addc_co_u32_e32 v11, vcc, 0, v9, vcc
	v_add_co_u32_e32 v12, vcc, s37, v8
	s_nop 1
	v_addc_co_u32_e32 v13, vcc, 0, v9, vcc
	v_add_co_u32_e32 v14, vcc, s38, v8
	s_nop 1
	v_addc_co_u32_e32 v15, vcc, 0, v9, vcc
	v_add_co_u32_e32 v16, vcc, s39, v8
	s_nop 1
	v_addc_co_u32_e32 v17, vcc, 0, v9, vcc
	v_add_co_u32_e32 v18, vcc, s40, v8
	s_nop 1
	v_addc_co_u32_e32 v19, vcc, 0, v9, vcc
	v_add_co_u32_e32 v20, vcc, s41, v8
	s_nop 1
	v_addc_co_u32_e32 v21, vcc, 0, v9, vcc
	v_add_co_u32_e32 v22, vcc, s42, v8
	s_nop 1
	v_addc_co_u32_e32 v23, vcc, 0, v9, vcc
	v_add_co_u32_e32 v24, vcc, s43, v8
	s_nop 1
	v_addc_co_u32_e32 v25, vcc, 0, v9, vcc
	global_load_dword v60, v[10:11], off
	global_load_dword v61, v[12:13], off offset:2048
	global_load_dword v62, v[14:15], off
	global_load_dword v63, v[16:17], off offset:2048
	global_load_dword v56, v[18:19], off
	global_load_dword v57, v[20:21], off offset:2048
	global_load_dword v58, v[22:23], off
	global_load_dword v59, v[24:25], off offset:2048
	v_add_co_u32_e32 v10, vcc, s44, v8
	s_nop 1
	v_addc_co_u32_e32 v11, vcc, 0, v9, vcc
	v_add_co_u32_e32 v12, vcc, s45, v8
	s_nop 1
	v_addc_co_u32_e32 v13, vcc, 0, v9, vcc
	v_add_co_u32_e32 v14, vcc, s46, v8
	s_nop 1
	v_addc_co_u32_e32 v15, vcc, 0, v9, vcc
	v_add_co_u32_e32 v16, vcc, s47, v8
	s_nop 1
	v_addc_co_u32_e32 v17, vcc, 0, v9, vcc
	v_add_co_u32_e32 v18, vcc, s48, v8
	s_nop 1
	v_addc_co_u32_e32 v19, vcc, 0, v9, vcc
	v_add_co_u32_e32 v20, vcc, s49, v8
	s_nop 1
	v_addc_co_u32_e32 v21, vcc, 0, v9, vcc
	v_add_co_u32_e32 v22, vcc, s50, v8
	s_nop 1
	v_addc_co_u32_e32 v23, vcc, 0, v9, vcc
	v_add_co_u32_e32 v24, vcc, s51, v8
	s_nop 1
	v_addc_co_u32_e32 v25, vcc, 0, v9, vcc
	global_load_dword v52, v[10:11], off
	global_load_dword v53, v[12:13], off offset:2048
	global_load_dword v54, v[14:15], off
	global_load_dword v55, v[16:17], off offset:2048
	global_load_dword v48, v[18:19], off
	global_load_dword v49, v[20:21], off offset:2048
	global_load_dword v50, v[22:23], off
	global_load_dword v51, v[24:25], off offset:2048
	v_add_co_u32_e32 v10, vcc, s52, v8
	s_nop 1
	v_addc_co_u32_e32 v11, vcc, 0, v9, vcc
	v_add_co_u32_e32 v12, vcc, s53, v8
	s_nop 1
	v_addc_co_u32_e32 v13, vcc, 0, v9, vcc
	v_add_co_u32_e32 v14, vcc, s54, v8
	s_nop 1
	v_addc_co_u32_e32 v15, vcc, 0, v9, vcc
	v_add_co_u32_e32 v16, vcc, s55, v8
	s_nop 1
	v_addc_co_u32_e32 v17, vcc, 0, v9, vcc
	v_add_co_u32_e32 v18, vcc, s56, v8
	s_nop 1
	v_addc_co_u32_e32 v19, vcc, 0, v9, vcc
	v_add_co_u32_e32 v20, vcc, s57, v8
	s_nop 1
	v_addc_co_u32_e32 v21, vcc, 0, v9, vcc
	v_add_co_u32_e32 v22, vcc, s58, v8
	s_nop 1
; __device__ __forceinline__ void transpose_item(const float* W, int K, int N, bf16_t* WT, const float* gk, int mode, LAS float* scr_, int item, int lane) {
;     ...
;     for (int kp = 0; kp < 32; ++kp) { va[kp] = src[(size_t)(2 * kp) * N]; vb[kp] = src[(size_t)(2 * kp + 1) * N]; }
; #pragma unroll
;     for (int kp = 0; kp < 32; ++kp) {
;         float a = va[kp], b = vb[kp];
;         if (gk) { a *= gk[k0 + 2 * kp]; b *= gk[k0 + 2 * kp + 1]; }
	v_addc_co_u32_e32 v23, vcc, 0, v9, vcc
	v_add_co_u32_e32 v24, vcc, s59, v8
	s_nop 1
	v_addc_co_u32_e32 v25, vcc, 0, v9, vcc
	global_load_dword v44, v[10:11], off
	global_load_dword v45, v[12:13], off offset:2048
	global_load_dword v46, v[14:15], off
	global_load_dword v47, v[16:17], off offset:2048
	global_load_dword v40, v[18:19], off
	global_load_dword v41, v[20:21], off offset:2048
	global_load_dword v42, v[22:23], off
	global_load_dword v43, v[24:25], off offset:2048
	v_add_co_u32_e32 v10, vcc, s64, v8
	s_nop 1
	v_addc_co_u32_e32 v11, vcc, 0, v9, vcc
	v_add_co_u32_e32 v12, vcc, s65, v8
	s_nop 1
	v_addc_co_u32_e32 v13, vcc, 0, v9, vcc
	v_add_co_u32_e32 v14, vcc, s66, v8
	s_nop 1
	v_addc_co_u32_e32 v15, vcc, 0, v9, vcc
	v_add_co_u32_e32 v16, vcc, s67, v8
	s_nop 1
	v_addc_co_u32_e32 v17, vcc, 0, v9, vcc
	v_add_co_u32_e32 v18, vcc, s68, v8
	s_nop 1
	v_addc_co_u32_e32 v19, vcc, 0, v9, vcc
	v_add_co_u32_e32 v20, vcc, s69, v8
	s_nop 1
	v_addc_co_u32_e32 v21, vcc, 0, v9, vcc
	v_add_co_u32_e32 v22, vcc, s70, v8
	s_nop 1
	v_addc_co_u32_e32 v23, vcc, 0, v9, vcc
	v_add_co_u32_e32 v24, vcc, s71, v8
	s_nop 1
	v_addc_co_u32_e32 v25, vcc, 0, v9, vcc
	global_load_dword v36, v[10:11], off
	global_load_dword v37, v[12:13], off offset:2048
	global_load_dword v38, v[14:15], off
	global_load_dword v39, v[16:17], off offset:2048
	global_load_dword v32, v[18:19], off
	global_load_dword v33, v[20:21], off offset:2048
	global_load_dword v34, v[22:23], off
	global_load_dword v35, v[24:25], off offset:2048
	v_add_co_u32_e32 v10, vcc, s72, v8
	s_nop 1
	v_addc_co_u32_e32 v11, vcc, 0, v9, vcc
	v_add_co_u32_e32 v12, vcc, s73, v8
	s_nop 1
	v_addc_co_u32_e32 v13, vcc, 0, v9, vcc
	v_add_co_u32_e32 v14, vcc, s74, v8
	s_nop 1
	v_addc_co_u32_e32 v15, vcc, 0, v9, vcc
	v_add_co_u32_e32 v16, vcc, s75, v8
	s_nop 1
	v_addc_co_u32_e32 v17, vcc, 0, v9, vcc
	v_add_co_u32_e32 v18, vcc, s76, v8
	s_nop 1
	v_addc_co_u32_e32 v19, vcc, 0, v9, vcc
	v_add_co_u32_e32 v20, vcc, s77, v8
	s_nop 1
	v_addc_co_u32_e32 v21, vcc, 0, v9, vcc
	v_add_co_u32_e32 v22, vcc, s78, v8
	s_nop 1
	v_addc_co_u32_e32 v23, vcc, 0, v9, vcc
	v_add_co_u32_e32 v72, vcc, s79, v8
	s_nop 1
	v_addc_co_u32_e32 v73, vcc, 0, v9, vcc
	global_load_dword v28, v[10:11], off
	global_load_dword v29, v[12:13], off offset:2048
	global_load_dword v30, v[14:15], off
	global_load_dword v31, v[16:17], off offset:2048
	global_load_dword v24, v[18:19], off
	global_load_dword v25, v[20:21], off offset:2048
	global_load_dword v26, v[22:23], off
	global_load_dword v27, v[72:73], off offset:2048
	v_add_co_u32_e32 v10, vcc, s80, v8
	s_nop 1
	v_addc_co_u32_e32 v11, vcc, 0, v9, vcc
	v_add_co_u32_e32 v12, vcc, s81, v8
	s_nop 1
	v_addc_co_u32_e32 v13, vcc, 0, v9, vcc
	v_add_co_u32_e32 v14, vcc, s82, v8
	s_nop 1
	v_addc_co_u32_e32 v15, vcc, 0, v9, vcc
	v_add_co_u32_e32 v16, vcc, s83, v8
	s_nop 1
	v_addc_co_u32_e32 v17, vcc, 0, v9, vcc
	v_add_co_u32_e32 v18, vcc, s84, v8
	s_nop 1
	v_addc_co_u32_e32 v19, vcc, 0, v9, vcc
	v_add_co_u32_e32 v72, vcc, s85, v8
	s_nop 1
	v_addc_co_u32_e32 v73, vcc, 0, v9, vcc
	v_add_co_u32_e32 v74, vcc, s86, v8
	s_nop 1
	v_addc_co_u32_e32 v75, vcc, 0, v9, vcc
	v_add_co_u32_e32 v80, vcc, s87, v8
	s_nop 1
	v_addc_co_u32_e32 v81, vcc, 0, v9, vcc
	global_load_dword v20, v[10:11], off
	global_load_dword v21, v[12:13], off offset:2048
	global_load_dword v22, v[14:15], off
	global_load_dword v23, v[16:17], off offset:2048
	s_nop 0
	global_load_dword v16, v[18:19], off
	global_load_dword v17, v[72:73], off offset:2048
	s_nop 0
	global_load_dword v18, v[74:75], off
	global_load_dword v19, v[80:81], off offset:2048
	v_add_co_u32_e32 v10, vcc, s88, v8
	s_nop 1
	v_addc_co_u32_e32 v11, vcc, 0, v9, vcc
	v_add_co_u32_e32 v14, vcc, s89, v8
	s_nop 1
	v_addc_co_u32_e32 v15, vcc, 0, v9, vcc
	v_add_co_u32_e32 v72, vcc, s90, v8
	s_nop 1
	v_addc_co_u32_e32 v73, vcc, 0, v9, vcc
	v_add_co_u32_e32 v74, vcc, s91, v8
	s_nop 1
	v_addc_co_u32_e32 v75, vcc, 0, v9, vcc
	v_add_co_u32_e32 v80, vcc, s92, v8
	s_nop 1
	v_addc_co_u32_e32 v81, vcc, 0, v9, vcc
	v_add_co_u32_e32 v82, vcc, s93, v8
	s_nop 1
	v_addc_co_u32_e32 v83, vcc, 0, v9, vcc
	v_add_co_u32_e32 v84, vcc, 0x1755000, v8
	s_nop 1
	v_addc_co_u32_e32 v85, vcc, 0, v9, vcc
	v_add_co_u32_e32 v86, vcc, 0x175a000, v8
	s_nop 1
	v_addc_co_u32_e32 v87, vcc, 0, v9, vcc
	global_load_dword v12, v[10:11], off
	global_load_dword v13, v[14:15], off offset:2048
	s_nop 0
	global_load_dword v14, v[72:73], off
	global_load_dword v15, v[74:75], off offset:2048
	global_load_dword v8, v[80:81], off
	global_load_dword v9, v[82:83], off offset:2048
	global_load_dword v10, v[84:85], off
	global_load_dword v11, v[86:87], off offset:2048
	s_cbranch_scc1 .LBB0_502
	s_lshl_b64 s[0:1], s[10:11], 2
	s_add_u32 s0, s96, s0
	s_addc_u32 s1, s97, s1
	global_load_dwordx4 v[72:75], v5, s[0:1]
	s_mov_b64 s[0:1], 0
	s_waitcnt vmcnt(0)
	v_pk_mul_f32 v[72:73], v[68:69], v[72:73]
	v_pk_mul_f32 v[74:75], v[70:71], v[74:75]

; #define LAS __attribute__((address_space(3)))
; #define PIN(i) ((const float*)ldq_(L, (i)))
; __device__ __forceinline__ unsigned pk2(float lo, float hi) { f32x2 v = {lo, hi}; bf16x2_t b = __builtin_convertvector(v, bf16x2_t); return __builtin_bit_cast(unsigned, b); }
; #define PREP_CONV(bit, SRC, Kd, Nd, DST, GK, MODE) if (mask & (bit)) { for (int it = gw; it < ((Kd) / 64) * ((Nd) / 64); it += NGW) transpose_item((SRC), (Kd), (Nd), (bf16_t*)(wl + (DST)), (GK), (MODE), scr, it, lane); }
; __device__ __forceinline__ void transpose_item(const float* W, int K, int N, bf16_t* WT, const float* gk, int mode, LAS float* scr_, int item, int lane) {
;     LAS unsigned* scr = (LAS unsigned*)scr_;
;     const int nblk = N / 64, kb = item / nblk, nb = item % nblk, k0 = 64 * kb, n0 = 64 * nb;
;     const int sc = (mode == 1) ? (((n0 >> 7) & 1) * DFF + (n0 >> 8) * 128 + (n0 & 127)) : n0;
;     const float* src = W + (size_t)k0 * N + sc + lane;
;     float va[32], vb[32];
; #pragma unroll
;     for (int kp = 0; kp < 32; ++kp) { va[kp] = src[(size_t)(2 * kp) * N]; vb[kp] = src[(size_t)(2 * kp + 1) * N]; }
; #pragma unroll
;     for (int kp = 0; kp < 32; ++kp) {
;         float a = va[kp], b = vb[kp];
;         if (gk) { a *= gk[k0 + 2 * kp]; b *= gk[k0 + 2 * kp + 1]; }
;         scr[kp * 65 + lane] = pk2(a, b);
;     }
;     asm volatile("s_waitcnt lgkmcnt(0)" ::: "memory");
;     const int c = lane & 7;
; #pragma unroll
;     for (int j = 0; j < 8; ++j) { const int r = (lane >> 3) + 8 * j; const LAS unsigned* q = scr + (4 * c) * 65 + r;
;         u32x4 o; o.x = q[0]; o.y = q[65]; o.z = q[130]; o.w = q[195];
;         *(u32x4*)(WT + (size_t)(n0 + r) * K + k0 + 8 * c) = o; }
; __device__ __forceinline__ void prep(const Params& p, LAS unsigned char* L, int wv, int vb, int nvb, int l, int mask) {
;     ...
;     PREP_CONV(PM_FFB_OUT, PIN(I_WFFB_OUT) + (size_t)l * DFF * DM, DFF, DM, WL_FFB_OUT, nullptr, 0)
.LBB0_566:
	v_mov_b32_e32 v8, 0
	s_ashr_i32 s0, s55, 31
	v_add_u32_e32 v8, 0, v8
	v_add_u32_e32 v8, 0x201a0, v8
	s_lshr_b32 s0, s0, 28
	s_nop 0
	s_add_i32 s0, s55, s0
	s_ashr_i32 s1, s0, 4
	s_lshl_b32 s0, s1, 6
	s_lshl_b32 s10, s1, 10
	s_mul_i32 s3, s1, 0xffd40000
	s_ashr_i32 s1, s0, 31
	s_sub_i32 s10, s16, s10
	s_lshl_b64 s[12:13], s[0:1], 12
	v_lshl_add_u64 v[22:23], s[0:1], 1, v[6:7]
	s_waitcnt lgkmcnt(0)
	v_readlane_b32 s1, v251, 40
	v_add_u32_e32 v20, s3, v11
	v_readlane_b32 s0, v251, 41
	s_add_u32 s3, s1, s12
	s_addc_u32 s12, s0, s13
	s_ashr_i32 s11, s10, 31
	s_lshl_b64 s[0:1], s[10:11], 2
	s_add_u32 s0, s3, s0
	s_addc_u32 s1, s12, s1
	v_ashrrev_i32_e32 v21, 31, v20
	v_lshl_add_u64 v[8:9], s[0:1], 0, v[4:5]
	v_add_u32_e32 v24, 0x5800, v20
	v_add_u32_e32 v26, 0xb000, v20
	v_add_u32_e32 v28, 0x10800, v20
	v_add_u32_e32 v30, 0x16000, v20
	v_add_u32_e32 v32, 0x1b800, v20
	v_add_u32_e32 v34, 0x21000, v20
	v_add_u32_e32 v36, 0x26800, v20
	v_lshl_add_u64 v[52:53], v[20:21], 1, v[22:23]
	v_add_co_u32_e32 v20, vcc, s18, v8
	v_ashrrev_i32_e32 v25, 31, v24
	v_ashrrev_i32_e32 v27, 31, v26
	v_ashrrev_i32_e32 v29, 31, v28
	v_ashrrev_i32_e32 v31, 31, v30
	v_ashrrev_i32_e32 v33, 31, v32
	v_ashrrev_i32_e32 v35, 31, v34
	v_ashrrev_i32_e32 v37, 31, v36
	v_addc_co_u32_e32 v21, vcc, 0, v9, vcc
	v_lshl_add_u64 v[54:55], v[24:25], 1, v[22:23]
	v_lshl_add_u64 v[56:57], v[26:27], 1, v[22:23]
	v_lshl_add_u64 v[58:59], v[28:29], 1, v[22:23]
	v_lshl_add_u64 v[60:61], v[30:31], 1, v[22:23]
	v_lshl_add_u64 v[62:63], v[32:33], 1, v[22:23]
	v_lshl_add_u64 v[64:65], v[34:35], 1, v[22:23]
	v_lshl_add_u64 v[66:67], v[36:37], 1, v[22:23]
	v_add_co_u32_e32 v22, vcc, s19, v8
	s_add_i32 s55, s55, s60
	s_nop 0
	v_addc_co_u32_e32 v23, vcc, 0, v9, vcc
	v_add_co_u32_e32 v24, vcc, s23, v8
	s_add_i32 s16, s16, s17
	s_nop 0
	v_addc_co_u32_e32 v25, vcc, 0, v9, vcc
	v_add_co_u32_e32 v26, vcc, s24, v8
	s_cmpk_lt_i32 s55, 0x2c0
	s_nop 0
	v_addc_co_u32_e32 v27, vcc, 0, v9, vcc
	v_add_co_u32_e32 v28, vcc, s25, v8
	v_add_u32_e32 v11, s61, v11
	s_nop 0
	v_addc_co_u32_e32 v29, vcc, 0, v9, vcc
	v_add_co_u32_e32 v30, vcc, s26, v8
	s_nop 1
	v_addc_co_u32_e32 v31, vcc, 0, v9, vcc
	v_add_co_u32_e32 v32, vcc, s27, v8
	s_nop 1
	v_addc_co_u32_e32 v33, vcc, 0, v9, vcc
	v_add_co_u32_e32 v34, vcc, s28, v8
	s_nop 1
	v_addc_co_u32_e32 v35, vcc, 0, v9, vcc
	v_add_co_u32_e32 v36, vcc, s29, v8
	s_nop 1
	v_addc_co_u32_e32 v37, vcc, 0, v9, vcc
	v_add_co_u32_e32 v38, vcc, s30, v8
	s_nop 1
	v_addc_co_u32_e32 v39, vcc, 0, v9, vcc
	v_add_co_u32_e32 v40, vcc, s31, v8
	s_nop 1
	v_addc_co_u32_e32 v41, vcc, 0, v9, vcc
	v_add_co_u32_e32 v42, vcc, s34, v8
	s_nop 1
	v_addc_co_u32_e32 v43, vcc, 0, v9, vcc
	v_add_co_u32_e32 v44, vcc, s35, v8
	s_nop 1
	v_addc_co_u32_e32 v45, vcc, 0, v9, vcc
	v_add_co_u32_e32 v46, vcc, s36, v8
	s_nop 1
	v_addc_co_u32_e32 v47, vcc, 0, v9, vcc
	v_add_co_u32_e32 v48, vcc, s37, v8
	s_nop 1
	v_addc_co_u32_e32 v49, vcc, 0, v9, vcc
	v_add_co_u32_e32 v50, vcc, s38, v8
	s_nop 1
	v_addc_co_u32_e32 v51, vcc, 0, v9, vcc
	v_add_co_u32_e32 v68, vcc, s39, v8
	s_nop 1
	v_addc_co_u32_e32 v69, vcc, 0, v9, vcc
	v_add_co_u32_e32 v70, vcc, s40, v8
	s_nop 1
	v_addc_co_u32_e32 v71, vcc, 0, v9, vcc
	v_add_co_u32_e32 v72, vcc, s41, v8
	s_nop 1
	v_addc_co_u32_e32 v73, vcc, 0, v9, vcc
	v_add_co_u32_e32 v74, vcc, s42, v8
	s_nop 1
	v_addc_co_u32_e32 v75, vcc, 0, v9, vcc
	v_add_co_u32_e32 v80, vcc, s43, v8
	s_nop 1
	v_addc_co_u32_e32 v81, vcc, 0, v9, vcc
	v_add_co_u32_e32 v82, vcc, s44, v8
	s_nop 1
	v_addc_co_u32_e32 v83, vcc, 0, v9, vcc
	v_add_co_u32_e32 v84, vcc, s45, v8
	s_nop 1
	v_addc_co_u32_e32 v85, vcc, 0, v9, vcc
	v_add_co_u32_e32 v86, vcc, s46, v8
	s_nop 1
	v_addc_co_u32_e32 v87, vcc, 0, v9, vcc
	v_add_co_u32_e32 v88, vcc, s47, v8
	s_nop 1
	v_addc_co_u32_e32 v89, vcc, 0, v9, vcc
	v_add_co_u32_e32 v90, vcc, s48, v8
	s_nop 1
	v_addc_co_u32_e32 v91, vcc, 0, v9, vcc
	v_add_co_u32_e32 v92, vcc, s49, v8
	s_nop 1
	v_addc_co_u32_e32 v93, vcc, 0, v9, vcc
	v_add_co_u32_e32 v94, vcc, s50, v8
	s_nop 1
	v_addc_co_u32_e32 v95, vcc, 0, v9, vcc
	v_add_co_u32_e32 v96, vcc, s51, v8
	s_nop 1
	v_addc_co_u32_e32 v97, vcc, 0, v9, vcc
	v_add_co_u32_e32 v98, vcc, s52, v8
	s_nop 1
	v_addc_co_u32_e32 v99, vcc, 0, v9, vcc
	v_add_co_u32_e32 v100, vcc, s53, v8
	s_nop 1
	v_addc_co_u32_e32 v101, vcc, 0, v9, vcc
	v_add_co_u32_e32 v8, vcc, s54, v8
	s_nop 1
	v_addc_co_u32_e32 v9, vcc, 0, v9, vcc
	global_load_dword v19, v[20:21], off offset:-4096
	s_nop 0
	global_load_dword v20, v[20:21], off
	s_nop 0
	global_load_dword v21, v[22:23], off offset:-4096
	s_nop 0
	global_load_dword v22, v[22:23], off
	s_nop 0
	global_load_dword v23, v[24:25], off offset:-4096
	s_nop 0
	global_load_dword v24, v[24:25], off
	s_nop 0
	global_load_dword v25, v[26:27], off offset:-4096
	s_nop 0
	global_load_dword v26, v[26:27], off
	s_nop 0
	global_load_dword v27, v[28:29], off offset:-4096
	s_nop 0
	global_load_dword v28, v[28:29], off
	s_nop 0
	global_load_dword v29, v[30:31], off offset:-4096
	s_nop 0
	global_load_dword v30, v[30:31], off
	s_nop 0
	global_load_dword v31, v[32:33], off offset:-4096
	s_nop 0
	global_load_dword v32, v[32:33], off
	s_nop 0
	global_load_dword v33, v[34:35], off offset:-4096
	s_nop 0
	global_load_dword v34, v[34:35], off
	s_nop 0
	global_load_dword v35, v[36:37], off offset:-4096
	s_nop 0
	global_load_dword v36, v[36:37], off
	s_nop 0
	global_load_dword v37, v[38:39], off offset:-4096
	s_nop 0
	global_load_dword v38, v[38:39], off
	s_nop 0
	global_load_dword v39, v[40:41], off offset:-4096
	s_nop 0
	global_load_dword v40, v[40:41], off
	s_nop 0
	global_load_dword v41, v[42:43], off offset:-4096
	s_nop 0
	global_load_dword v42, v[42:43], off
; #define LAS __attribute__((address_space(3)))
; __device__ __forceinline__ unsigned pk2(float lo, float hi) { f32x2 v = {lo, hi}; bf16x2_t b = __builtin_convertvector(v, bf16x2_t); return __builtin_bit_cast(unsigned, b); }
; __device__ __forceinline__ void transpose_item(const float* W, int K, int N, bf16_t* WT, const float* gk, int mode, LAS float* scr_, int item, int lane) {
;     ...
; #pragma unroll
;     for (int kp = 0; kp < 32; ++kp) { va[kp] = src[(size_t)(2 * kp) * N]; vb[kp] = src[(size_t)(2 * kp + 1) * N]; }
; #pragma unroll
;     for (int kp = 0; kp < 32; ++kp) {
;         float a = va[kp], b = vb[kp];
;         if (gk) { a *= gk[k0 + 2 * kp]; b *= gk[k0 + 2 * kp + 1]; }
;         scr[kp * 65 + lane] = pk2(a, b);
;     }
;     asm volatile("s_waitcnt lgkmcnt(0)" ::: "memory");
;     const int c = lane & 7;
; #pragma unroll
;     for (int j = 0; j < 8; ++j) { const int r = (lane >> 3) + 8 * j; const LAS unsigned* q = scr + (4 * c) * 65 + r;
;         u32x4 o; o.x = q[0]; o.y = q[65]; o.z = q[130]; o.w = q[195];
;         *(u32x4*)(WT + (size_t)(n0 + r) * K + k0 + 8 * c) = o; }
	s_nop 0
	global_load_dword v43, v[44:45], off offset:-4096
	s_nop 0
	global_load_dword v44, v[44:45], off
	s_nop 0
	global_load_dword v45, v[46:47], off offset:-4096
	s_nop 0
	global_load_dword v46, v[46:47], off
	s_nop 0
	global_load_dword v47, v[48:49], off offset:-4096
	s_nop 0
	global_load_dword v48, v[48:49], off
	s_nop 0
	global_load_dword v49, v[50:51], off offset:-4096
	s_nop 0
	global_load_dword v50, v[50:51], off
	s_nop 0
	global_load_dword v51, v[68:69], off offset:-4096
	s_nop 0
	global_load_dword v68, v[68:69], off
	s_nop 0
	global_load_dword v69, v[70:71], off offset:-4096
	s_nop 0
	global_load_dword v70, v[70:71], off
	s_nop 0
	global_load_dword v71, v[72:73], off offset:-4096
	s_nop 0
	global_load_dword v72, v[72:73], off
	s_nop 0
	global_load_dword v73, v[74:75], off offset:-4096
	s_nop 0
	global_load_dword v74, v[74:75], off
	s_nop 0
	global_load_dword v75, v[80:81], off offset:-4096
	global_load_dword v79, v[80:81], off
	s_nop 0
	global_load_dword v80, v[82:83], off offset:-4096
	global_load_dword v81, v[82:83], off
	s_nop 0
	global_load_dword v82, v[84:85], off offset:-4096
	global_load_dword v83, v[84:85], off
	s_nop 0
	global_load_dword v84, v[86:87], off offset:-4096
	global_load_dword v85, v[86:87], off
	s_nop 0
	global_load_dword v86, v[88:89], off offset:-4096
	global_load_dword v87, v[88:89], off
	s_nop 0
	global_load_dword v88, v[90:91], off offset:-4096
	global_load_dword v89, v[90:91], off
	s_nop 0
	global_load_dword v90, v[92:93], off offset:-4096
	global_load_dword v91, v[92:93], off
	s_nop 0
	global_load_dword v92, v[94:95], off offset:-4096
	global_load_dword v93, v[94:95], off
	s_nop 0
	global_load_dword v94, v[96:97], off offset:-4096
	global_load_dword v95, v[96:97], off
	s_nop 0
	global_load_dword v96, v[98:99], off offset:-4096
	global_load_dword v97, v[98:99], off
	s_nop 0
	global_load_dword v98, v[100:101], off offset:-4096
	global_load_dword v99, v[100:101], off
	s_nop 0
	global_load_dword v100, v[8:9], off offset:-4096
	s_nop 0
	global_load_dword v8, v[8:9], off
	s_waitcnt vmcnt(62)
	v_cvt_pk_bf16_f32 v9, v19, v20
	s_waitcnt vmcnt(60)
	v_cvt_pk_bf16_f32 v19, v21, v22
	s_waitcnt vmcnt(58)
	v_cvt_pk_bf16_f32 v20, v23, v24
	s_waitcnt vmcnt(56)
	v_cvt_pk_bf16_f32 v21, v25, v26
	s_waitcnt vmcnt(54)
	v_cvt_pk_bf16_f32 v22, v27, v28
	s_waitcnt vmcnt(52)
	v_cvt_pk_bf16_f32 v23, v29, v30
	s_waitcnt vmcnt(50)
	v_cvt_pk_bf16_f32 v24, v31, v32
	s_waitcnt vmcnt(48)
	v_cvt_pk_bf16_f32 v25, v33, v34
	s_waitcnt vmcnt(46)
	v_cvt_pk_bf16_f32 v26, v35, v36
	s_waitcnt vmcnt(44)
	v_cvt_pk_bf16_f32 v27, v37, v38
	s_waitcnt vmcnt(42)
	v_cvt_pk_bf16_f32 v28, v39, v40
	s_waitcnt vmcnt(40)
	v_cvt_pk_bf16_f32 v29, v41, v42
	s_waitcnt vmcnt(38)
	v_cvt_pk_bf16_f32 v30, v43, v44
	s_waitcnt vmcnt(36)
	v_cvt_pk_bf16_f32 v31, v45, v46
	s_waitcnt vmcnt(34)
	v_cvt_pk_bf16_f32 v32, v47, v48
	s_waitcnt vmcnt(32)
	v_cvt_pk_bf16_f32 v33, v49, v50
	s_waitcnt vmcnt(30)
	v_cvt_pk_bf16_f32 v34, v51, v68
	s_waitcnt vmcnt(28)
	v_cvt_pk_bf16_f32 v35, v69, v70
	s_waitcnt vmcnt(26)
	v_cvt_pk_bf16_f32 v36, v71, v72
	s_waitcnt vmcnt(24)
	v_cvt_pk_bf16_f32 v37, v73, v74
	s_waitcnt vmcnt(22)
	v_cvt_pk_bf16_f32 v38, v75, v79
	s_waitcnt vmcnt(20)
	v_cvt_pk_bf16_f32 v39, v80, v81
	s_waitcnt vmcnt(18)
	v_cvt_pk_bf16_f32 v40, v82, v83
	s_waitcnt vmcnt(16)
	v_cvt_pk_bf16_f32 v41, v84, v85
	s_waitcnt vmcnt(14)
	v_cvt_pk_bf16_f32 v42, v86, v87
	s_waitcnt vmcnt(12)
	v_cvt_pk_bf16_f32 v43, v88, v89
	s_waitcnt vmcnt(10)
	v_cvt_pk_bf16_f32 v44, v90, v91
	s_waitcnt vmcnt(8)
	v_cvt_pk_bf16_f32 v45, v92, v93
	s_waitcnt vmcnt(6)
	v_cvt_pk_bf16_f32 v46, v94, v95
	s_waitcnt vmcnt(4)
	v_cvt_pk_bf16_f32 v47, v96, v97
	s_waitcnt vmcnt(2)
	v_cvt_pk_bf16_f32 v48, v98, v99
	s_waitcnt vmcnt(0)
	v_cvt_pk_bf16_f32 v8, v100, v8
	ds_write2_b32 v77, v9, v19 offset1:65
	ds_write2_b32 v77, v20, v21 offset0:130 offset1:195
	ds_write2_b32 v12, v22, v23 offset0:4 offset1:69
	ds_write2_b32 v12, v24, v25 offset0:134 offset1:199
	ds_write2_b32 v13, v26, v27 offset0:8 offset1:73
	ds_write2_b32 v13, v28, v29 offset0:138 offset1:203
	ds_write2_b32 v14, v30, v31 offset0:12 offset1:77
	ds_write2_b32 v14, v32, v33 offset0:142 offset1:207
	ds_write2_b32 v15, v34, v35 offset0:16 offset1:81
	ds_write2_b32 v15, v36, v37 offset0:146 offset1:211
	ds_write2_b32 v16, v38, v39 offset0:20 offset1:85
	ds_write2_b32 v16, v40, v41 offset0:150 offset1:215
	ds_write2_b32 v17, v42, v43 offset0:24 offset1:89
	ds_write2_b32 v17, v44, v45 offset0:154 offset1:219
	ds_write2_b32 v18, v46, v47 offset0:28 offset1:93
	ds_write2_b32 v18, v48, v8 offset0:158 offset1:223
	s_waitcnt lgkmcnt(0)
	ds_read2_b32 v[20:21], v10 offset0:65 offset1:73
	ds_read2_b32 v[8:9], v10 offset0:130 offset1:138
	ds_read2_b32 v[22:23], v10 offset0:195 offset1:203
	ds_read2_b32 v[40:41], v10 offset1:8
	ds_read2_b32 v[44:45], v10 offset0:16 offset1:24
	ds_read2_b32 v[24:25], v10 offset0:81 offset1:89
	ds_read2_b32 v[46:47], v10 offset0:146 offset1:154
	ds_read2_b32 v[26:27], v10 offset0:211 offset1:219
	ds_read2_b32 v[28:29], v10 offset0:97 offset1:105
	ds_read2_b32 v[48:49], v10 offset0:162 offset1:170
	ds_read2_b32 v[30:31], v10 offset0:227 offset1:235
	ds_read2_b32 v[50:51], v10 offset0:32 offset1:40
	ds_read2_b32 v[68:69], v10 offset0:48 offset1:56
	ds_read2_b32 v[32:33], v10 offset0:113 offset1:121
	ds_read2_b32 v[70:71], v10 offset0:178 offset1:186
	ds_read2_b32 v[34:35], v10 offset0:243 offset1:251
	s_waitcnt lgkmcnt(12)
	v_mov_b32_e32 v36, v40
	v_mov_b32_e32 v37, v20
	v_mov_b32_e32 v38, v8
	v_mov_b32_e32 v39, v22
	v_mov_b32_e32 v20, v41
	v_mov_b32_e32 v22, v9
	s_waitcnt lgkmcnt(11)
	v_mov_b32_e32 v40, v44
	s_waitcnt lgkmcnt(10)
	v_mov_b32_e32 v41, v24
	s_waitcnt lgkmcnt(9)
	v_mov_b32_e32 v42, v46
	s_waitcnt lgkmcnt(8)
	v_mov_b32_e32 v43, v26
	v_mov_b32_e32 v24, v45
	v_mov_b32_e32 v26, v47
	s_waitcnt lgkmcnt(4)
	v_mov_b32_e32 v44, v50
	v_mov_b32_e32 v45, v28
	v_mov_b32_e32 v46, v48
	v_mov_b32_e32 v47, v30
	v_mov_b32_e32 v28, v51
	v_mov_b32_e32 v30, v49
	s_waitcnt lgkmcnt(3)
	v_mov_b32_e32 v48, v68
	s_waitcnt lgkmcnt(2)
	v_mov_b32_e32 v49, v32
	s_waitcnt lgkmcnt(1)
	v_mov_b32_e32 v50, v70
	s_waitcnt lgkmcnt(0)
	v_mov_b32_e32 v51, v34
	v_mov_b32_e32 v32, v69
	v_mov_b32_e32 v34, v71
	global_store_dwordx4 v[52:53], v[36:39], off
	global_store_dwordx4 v[54:55], v[20:23], off
	global_store_dwordx4 v[56:57], v[40:43], off
	global_store_dwordx4 v[58:59], v[24:27], off
	global_store_dwordx4 v[60:61], v[44:47], off
	global_store_dwordx4 v[62:63], v[28:31], off
	global_store_dwordx4 v[64:65], v[48:51], off
	global_store_dwordx4 v[66:67], v[32:35], off
	s_waitcnt lgkmcnt(0)
	s_cbranch_scc1 .LBB0_566

; #define LAS __attribute__((address_space(3)))
; #define PIN(i) ((const float*)ldq_(L, (i)))
; #define PREP_CONV(bit, SRC, Kd, Nd, DST, GK, MODE) if (mask & (bit)) { for (int it = gw; it < ((Kd) / 64) * ((Nd) / 64); it += NGW) transpose_item((SRC), (Kd), (Nd), (bf16_t*)(wl + (DST)), (GK), (MODE), scr, it, lane); }
; __device__ __forceinline__ void transpose_item(const float* W, int K, int N, bf16_t* WT, const float* gk, int mode, LAS float* scr_, int item, int lane) {
;     LAS unsigned* scr = (LAS unsigned*)scr_;
;     const int nblk = N / 64, kb = item / nblk, nb = item % nblk, k0 = 64 * kb, n0 = 64 * nb;
;     const int sc = (mode == 1) ? (((n0 >> 7) & 1) * DFF + (n0 >> 8) * 128 + (n0 & 127)) : n0;
;     const float* src = W + (size_t)k0 * N + sc + lane;
;     float va[32], vb[32];
; #pragma unroll
;     for (int kp = 0; kp < 32; ++kp) { va[kp] = src[(size_t)(2 * kp) * N]; vb[kp] = src[(size_t)(2 * kp + 1) * N]; }
; #pragma unroll
;     for (int kp = 0; kp < 32; ++kp) {
;         float a = va[kp], b = vb[kp];
;         if (gk) { a *= gk[k0 + 2 * kp]; b *= gk[k0 + 2 * kp + 1]; }
; __device__ __forceinline__ void prep(const Params& p, LAS unsigned char* L, int wv, int vb, int nvb, int l, int mask) {
;     ...
;     PREP_CONV(PM_PEG, PIN(I_WPEG) + (size_t)l * DM * DM, DM, DM, WL_PEG, PIN(I_NPE) + l * DM, 0)
.LBB0_570:
	v_mov_b32_e32 v8, 0
	v_mov_b32_e32 v10, 0
	v_add_u32_e32 v8, 0, v8
	v_add_u32_e32 v8, 0x201b0, v8
	s_nop 0
	s_waitcnt lgkmcnt(0)
	v_readlane_b32 s13, v251, 44
	v_add_u32_e32 v10, 0, v10
	v_add_u32_e32 v10, 0x201a8, v10
	s_nop 0
	v_readlane_b32 s3, v251, 45
	s_waitcnt lgkmcnt(0)
	v_readlane_b32 s0, v251, 42
	v_readlane_b32 s1, v251, 43
	s_add_u32 s54, s0, 0x1000
	s_addc_u32 s55, s1, 0
	s_ashr_i32 s10, s52, 31
	s_lshr_b32 s10, s10, 28
	s_add_i32 s10, s52, s10
	s_ashr_i32 s11, s10, 4
	s_lshl_b32 s10, s11, 6
	s_lshl_b32 s53, s11, 10
	s_ashr_i32 s11, s10, 31
	s_sub_i32 s12, s14, s53
	s_lshl_b64 s[56:57], s[10:11], 12
	s_add_u32 s56, s13, s56
	s_addc_u32 s3, s3, s57
	s_ashr_i32 s13, s12, 31
	s_lshl_b64 s[12:13], s[12:13], 2
	s_add_u32 s12, s56, s12
	s_addc_u32 s13, s3, s13
	v_lshl_add_u64 v[10:11], s[12:13], 0, v[4:5]
	v_add_co_u32_e32 v66, vcc, s16, v10
	s_cmp_lg_u64 s[0:1], 0
	s_nop 0
	v_addc_co_u32_e32 v67, vcc, 0, v11, vcc
	v_add_co_u32_e32 v72, vcc, s17, v10
	s_cselect_b64 s[12:13], -1, 0
	s_nop 0
	v_addc_co_u32_e32 v73, vcc, 0, v11, vcc
	v_add_co_u32_e32 v74, vcc, s18, v10
	s_cmp_eq_u64 s[0:1], 0
	s_nop 0
	v_addc_co_u32_e32 v75, vcc, 0, v11, vcc
	v_add_co_u32_e32 v8, vcc, s19, v10
	s_mov_b64 s[0:1], -1
	s_nop 0
	v_addc_co_u32_e32 v9, vcc, 0, v11, vcc
	v_add_co_u32_e32 v12, vcc, s23, v10
	s_nop 1
	v_addc_co_u32_e32 v13, vcc, 0, v11, vcc
	v_add_co_u32_e32 v14, vcc, s24, v10
	s_nop 1
	v_addc_co_u32_e32 v15, vcc, 0, v11, vcc
	v_add_co_u32_e32 v16, vcc, s25, v10
	s_nop 1
	v_addc_co_u32_e32 v17, vcc, 0, v11, vcc
	global_load_dword v64, v[8:9], off offset:-4096
	global_load_dword v65, v[8:9], off
	global_load_dword v60, v[12:13], off offset:-4096
	global_load_dword v61, v[12:13], off
	global_load_dword v62, v[14:15], off offset:-4096
	global_load_dword v63, v[14:15], off
	global_load_dword v56, v[16:17], off offset:-4096
	global_load_dword v57, v[16:17], off
	v_add_co_u32_e32 v8, vcc, s26, v10
	s_nop 1
	v_addc_co_u32_e32 v9, vcc, 0, v11, vcc
	v_add_co_u32_e32 v12, vcc, s27, v10
	s_nop 1
	v_addc_co_u32_e32 v13, vcc, 0, v11, vcc
	v_add_co_u32_e32 v14, vcc, s28, v10
	s_nop 1
	v_addc_co_u32_e32 v15, vcc, 0, v11, vcc
	v_add_co_u32_e32 v16, vcc, s29, v10
	s_nop 1
	v_addc_co_u32_e32 v17, vcc, 0, v11, vcc
	global_load_dword v58, v[8:9], off offset:-4096
	global_load_dword v59, v[8:9], off
	global_load_dword v52, v[12:13], off offset:-4096
	global_load_dword v53, v[12:13], off
	global_load_dword v54, v[14:15], off offset:-4096
	global_load_dword v55, v[14:15], off
	global_load_dword v48, v[16:17], off offset:-4096
	global_load_dword v49, v[16:17], off
	v_add_co_u32_e32 v8, vcc, s30, v10
	s_nop 1
	v_addc_co_u32_e32 v9, vcc, 0, v11, vcc
	v_add_co_u32_e32 v12, vcc, s31, v10
	s_nop 1
	v_addc_co_u32_e32 v13, vcc, 0, v11, vcc
	v_add_co_u32_e32 v14, vcc, s34, v10
	s_nop 1
	v_addc_co_u32_e32 v15, vcc, 0, v11, vcc
	v_add_co_u32_e32 v16, vcc, s35, v10
	s_nop 1
	v_addc_co_u32_e32 v17, vcc, 0, v11, vcc
	global_load_dword v50, v[8:9], off offset:-4096
	global_load_dword v51, v[8:9], off
	global_load_dword v44, v[12:13], off offset:-4096
	global_load_dword v45, v[12:13], off
	global_load_dword v46, v[14:15], off offset:-4096
	global_load_dword v47, v[14:15], off
	global_load_dword v40, v[16:17], off offset:-4096
	global_load_dword v41, v[16:17], off
	v_add_co_u32_e32 v8, vcc, s36, v10
	s_nop 1
	v_addc_co_u32_e32 v9, vcc, 0, v11, vcc
	v_add_co_u32_e32 v12, vcc, s37, v10
	s_nop 1
	v_addc_co_u32_e32 v13, vcc, 0, v11, vcc
	v_add_co_u32_e32 v14, vcc, s38, v10
	s_nop 1
	v_addc_co_u32_e32 v15, vcc, 0, v11, vcc
	v_add_co_u32_e32 v16, vcc, s39, v10
	s_nop 1
	v_addc_co_u32_e32 v17, vcc, 0, v11, vcc
	global_load_dword v42, v[8:9], off offset:-4096
	global_load_dword v43, v[8:9], off
	global_load_dword v36, v[12:13], off offset:-4096
	global_load_dword v37, v[12:13], off
	global_load_dword v38, v[14:15], off offset:-4096
	global_load_dword v39, v[14:15], off
	global_load_dword v32, v[16:17], off offset:-4096
	global_load_dword v33, v[16:17], off
	v_add_co_u32_e32 v8, vcc, s40, v10
	s_nop 1
	v_addc_co_u32_e32 v9, vcc, 0, v11, vcc
	v_add_co_u32_e32 v12, vcc, s41, v10
	s_nop 1
	v_addc_co_u32_e32 v13, vcc, 0, v11, vcc
	v_add_co_u32_e32 v14, vcc, s42, v10
	s_nop 1
	v_addc_co_u32_e32 v15, vcc, 0, v11, vcc
	v_add_co_u32_e32 v16, vcc, s43, v10
	s_nop 1
	v_addc_co_u32_e32 v17, vcc, 0, v11, vcc
	global_load_dword v34, v[8:9], off offset:-4096
	global_load_dword v35, v[8:9], off
	global_load_dword v28, v[12:13], off offset:-4096
	global_load_dword v29, v[12:13], off
	global_load_dword v30, v[14:15], off offset:-4096
	global_load_dword v31, v[14:15], off
	global_load_dword v24, v[16:17], off offset:-4096
	global_load_dword v25, v[16:17], off
	v_add_co_u32_e32 v8, vcc, s44, v10
	s_nop 1
	v_addc_co_u32_e32 v9, vcc, 0, v11, vcc
	v_add_co_u32_e32 v12, vcc, s45, v10
	s_nop 1
	v_addc_co_u32_e32 v13, vcc, 0, v11, vcc
	v_add_co_u32_e32 v14, vcc, s46, v10
	s_nop 1
	v_addc_co_u32_e32 v15, vcc, 0, v11, vcc
	v_add_co_u32_e32 v18, vcc, s47, v10
	s_nop 1
	v_addc_co_u32_e32 v19, vcc, 0, v11, vcc
	global_load_dword v26, v[8:9], off offset:-4096
	global_load_dword v27, v[8:9], off
	global_load_dword v20, v[12:13], off offset:-4096
	global_load_dword v21, v[12:13], off
	global_load_dword v22, v[14:15], off offset:-4096
	global_load_dword v23, v[14:15], off
	global_load_dword v16, v[18:19], off offset:-4096
	global_load_dword v17, v[18:19], off
	v_add_co_u32_e32 v8, vcc, s48, v10
	s_nop 1
	v_addc_co_u32_e32 v9, vcc, 0, v11, vcc
	v_add_co_u32_e32 v14, vcc, s49, v10
	s_nop 1
	v_addc_co_u32_e32 v15, vcc, 0, v11, vcc
	v_add_co_u32_e32 v68, vcc, s50, v10
	s_nop 1
	v_addc_co_u32_e32 v69, vcc, 0, v11, vcc
	v_add_co_u32_e32 v70, vcc, s51, v10
	s_nop 1
	v_addc_co_u32_e32 v71, vcc, 0, v11, vcc
	v_add_co_u32_e32 v80, vcc, 0x43e000, v10
	global_load_dword v18, v[8:9], off offset:-4096
	global_load_dword v19, v[8:9], off
	global_load_dword v12, v[14:15], off offset:-4096
	global_load_dword v13, v[14:15], off
	s_nop 0
	global_load_dword v14, v[68:69], off offset:-4096
	global_load_dword v15, v[68:69], off
	global_load_dword v8, v[70:71], off offset:-4096
	global_load_dword v9, v[70:71], off
	v_addc_co_u32_e32 v81, vcc, 0, v11, vcc
	v_add_co_u32_e32 v82, vcc, 0x43f000, v10
	s_nop 1
	v_addc_co_u32_e32 v83, vcc, 0, v11, vcc
	global_load_dword v68, v[66:67], off offset:-4096
	global_load_dword v69, v[66:67], off
	global_load_dword v70, v[72:73], off offset:-4096
	global_load_dword v71, v[72:73], off
	s_nop 0
	global_load_dword v66, v[74:75], off offset:-4096
	global_load_dword v67, v[74:75], off
	global_load_dword v10, v[80:81], off
	global_load_dword v11, v[82:83], off
	s_cbranch_scc1 .LBB0_572
	s_lshl_b64 s[0:1], s[10:11], 2
	s_add_u32 s0, s54, s0
	s_addc_u32 s1, s55, s1
	global_load_dwordx4 v[72:75], v5, s[0:1]
	s_mov_b64 s[0:1], 0
	s_waitcnt vmcnt(0)
	v_pk_mul_f32 v[72:73], v[68:69], v[72:73]
	v_pk_mul_f32 v[74:75], v[70:71], v[74:75]

; #define LAS __attribute__((address_space(3)))
; #define PIN(i) ((const float*)ldq_(L, (i)))
; __device__ __forceinline__ unsigned pk2(float lo, float hi) { f32x2 v = {lo, hi}; bf16x2_t b = __builtin_convertvector(v, bf16x2_t); return __builtin_bit_cast(unsigned, b); }
; #define PREP_CONV(bit, SRC, Kd, Nd, DST, GK, MODE) if (mask & (bit)) { for (int it = gw; it < ((Kd) / 64) * ((Nd) / 64); it += NGW) transpose_item((SRC), (Kd), (Nd), (bf16_t*)(wl + (DST)), (GK), (MODE), scr, it, lane); }
; __device__ __forceinline__ void transpose_item(const float* W, int K, int N, bf16_t* WT, const float* gk, int mode, LAS float* scr_, int item, int lane) {
;     LAS unsigned* scr = (LAS unsigned*)scr_;
;     const int nblk = N / 64, kb = item / nblk, nb = item % nblk, k0 = 64 * kb, n0 = 64 * nb;
;     const int sc = (mode == 1) ? (((n0 >> 7) & 1) * DFF + (n0 >> 8) * 128 + (n0 & 127)) : n0;
;     const float* src = W + (size_t)k0 * N + sc + lane;
;     float va[32], vb[32];
; #pragma unroll
;     for (int kp = 0; kp < 32; ++kp) { va[kp] = src[(size_t)(2 * kp) * N]; vb[kp] = src[(size_t)(2 * kp + 1) * N]; }
; #pragma unroll
;     for (int kp = 0; kp < 32; ++kp) {
;         float a = va[kp], b = vb[kp];
;         if (gk) { a *= gk[k0 + 2 * kp]; b *= gk[k0 + 2 * kp + 1]; }
;         scr[kp * 65 + lane] = pk2(a, b);
;     }
;     asm volatile("s_waitcnt lgkmcnt(0)" ::: "memory");
;     const int c = lane & 7;
; #pragma unroll
;     for (int j = 0; j < 8; ++j) { const int r = (lane >> 3) + 8 * j; const LAS unsigned* q = scr + (4 * c) * 65 + r;
;         u32x4 o; o.x = q[0]; o.y = q[65]; o.z = q[130]; o.w = q[195];
;         *(u32x4*)(WT + (size_t)(n0 + r) * K + k0 + 8 * c) = o; }
; __device__ __forceinline__ void prep(const Params& p, LAS unsigned char* L, int wv, int vb, int nvb, int l, int mask) {
;     ...
;     PREP_CONV(PM_PEU, PIN(I_WPEU) + (size_t)l * PED * DM, PED, DM, WL_PEU, nullptr, 0)
.LBB0_636:
	v_mov_b32_e32 v2, 0
	s_ashr_i32 s0, s7, 31
	v_add_u32_e32 v2, 0, v2
	v_add_u32_e32 v2, 0x201b8, v2
	s_lshr_b32 s0, s0, 28
	s_nop 0
	s_add_i32 s0, s7, s0
	s_ashr_i32 s0, s0, 4
	s_lshl_b32 s12, s0, 6
	s_lshl_b32 s0, s0, 10
	s_ashr_i32 s13, s12, 31
	s_sub_i32 s0, s14, s0
	s_lshl_b64 s[10:11], s[12:13], 12
	s_waitcnt lgkmcnt(0)
	v_readlane_b32 s3, v251, 46
	v_readlane_b32 s1, v251, 47
	s_add_u32 s3, s3, s10
	v_add_u32_e32 v8, s0, v78
	s_addc_u32 s10, s1, s11
	s_ashr_i32 s1, s0, 31
	v_ashrrev_i32_e32 v9, 31, v8
	v_add_u32_e32 v10, 8, v8
	v_add_u32_e32 v12, 16, v8
	v_add_u32_e32 v14, 24, v8
	v_add_u32_e32 v16, 32, v8
	v_add_u32_e32 v18, 40, v8
	v_add_u32_e32 v30, 48, v8
	v_add_u32_e32 v32, 56, v8
	s_lshl_b64 s[0:1], s[0:1], 2
	v_lshl_add_u64 v[20:21], s[12:13], 1, v[6:7]
	v_lshlrev_b64 v[8:9], 9, v[8:9]
	v_ashrrev_i32_e32 v11, 31, v10
	v_ashrrev_i32_e32 v13, 31, v12
	v_ashrrev_i32_e32 v15, 31, v14
	v_ashrrev_i32_e32 v17, 31, v16
	v_ashrrev_i32_e32 v19, 31, v18
	v_ashrrev_i32_e32 v31, 31, v30
	v_ashrrev_i32_e32 v33, 31, v32
	s_add_u32 s0, s3, s0
	v_lshl_add_u64 v[2:3], v[20:21], 0, v[8:9]
	v_lshlrev_b64 v[8:9], 9, v[10:11]
	v_lshlrev_b64 v[10:11], 9, v[12:13]
	v_lshlrev_b64 v[12:13], 9, v[14:15]
	v_lshlrev_b64 v[14:15], 9, v[16:17]
	v_lshlrev_b64 v[16:17], 9, v[18:19]
	v_lshlrev_b64 v[18:19], 9, v[30:31]
	v_lshlrev_b64 v[30:31], 9, v[32:33]
	s_addc_u32 s1, s10, s1
	v_lshl_add_u64 v[8:9], v[20:21], 0, v[8:9]
	v_lshl_add_u64 v[10:11], v[20:21], 0, v[10:11]
	v_lshl_add_u64 v[12:13], v[20:21], 0, v[12:13]
	v_lshl_add_u64 v[14:15], v[20:21], 0, v[14:15]
	v_lshl_add_u64 v[16:17], v[20:21], 0, v[16:17]
	v_lshl_add_u64 v[18:19], v[20:21], 0, v[18:19]
	v_lshl_add_u64 v[20:21], v[20:21], 0, v[30:31]
	v_lshl_add_u64 v[30:31], s[0:1], 0, v[4:5]
	v_add_co_u32_e32 v32, vcc, s16, v30
	s_add_i32 s7, s7, s60
	s_nop 0
	v_addc_co_u32_e32 v33, vcc, 0, v31, vcc
	v_add_co_u32_e32 v34, vcc, s17, v30
	s_add_i32 s14, s14, s15
	s_nop 0
	v_addc_co_u32_e32 v35, vcc, 0, v31, vcc
	v_add_co_u32_e32 v36, vcc, s18, v30
	s_cmp_lt_i32 s7, 64
	s_nop 0
	v_addc_co_u32_e32 v37, vcc, 0, v31, vcc
	v_add_co_u32_e32 v38, vcc, s19, v30
	s_nop 1
	v_addc_co_u32_e32 v39, vcc, 0, v31, vcc
	v_add_co_u32_e32 v40, vcc, s22, v30
	s_nop 1
	v_addc_co_u32_e32 v41, vcc, 0, v31, vcc
	v_add_co_u32_e32 v42, vcc, s23, v30
	s_nop 1
	v_addc_co_u32_e32 v43, vcc, 0, v31, vcc
	v_add_co_u32_e32 v44, vcc, s24, v30
	s_nop 1
	v_addc_co_u32_e32 v45, vcc, 0, v31, vcc
	v_add_co_u32_e32 v46, vcc, s25, v30
	s_nop 1
	v_addc_co_u32_e32 v47, vcc, 0, v31, vcc
	v_add_co_u32_e32 v48, vcc, s26, v30
	s_nop 1
	v_addc_co_u32_e32 v49, vcc, 0, v31, vcc
	v_add_co_u32_e32 v50, vcc, s27, v30
	s_nop 1
	v_addc_co_u32_e32 v51, vcc, 0, v31, vcc
	v_add_co_u32_e32 v52, vcc, s28, v30
	s_nop 1
	v_addc_co_u32_e32 v53, vcc, 0, v31, vcc
	v_add_co_u32_e32 v54, vcc, s29, v30
	s_nop 1
	v_addc_co_u32_e32 v55, vcc, 0, v31, vcc
	v_add_co_u32_e32 v56, vcc, s30, v30
	s_nop 1
	v_addc_co_u32_e32 v57, vcc, 0, v31, vcc
	v_add_co_u32_e32 v58, vcc, s31, v30
	s_nop 1
	v_addc_co_u32_e32 v59, vcc, 0, v31, vcc
	v_add_co_u32_e32 v60, vcc, s34, v30
	s_nop 1
	v_addc_co_u32_e32 v61, vcc, 0, v31, vcc
	v_add_co_u32_e32 v62, vcc, s35, v30
	s_nop 1
	v_addc_co_u32_e32 v63, vcc, 0, v31, vcc
	v_add_co_u32_e32 v64, vcc, s36, v30
	s_nop 1
	v_addc_co_u32_e32 v65, vcc, 0, v31, vcc
	v_add_co_u32_e32 v66, vcc, s37, v30
	s_nop 1
	v_addc_co_u32_e32 v67, vcc, 0, v31, vcc
	v_add_co_u32_e32 v68, vcc, s38, v30
	s_nop 1
	v_addc_co_u32_e32 v69, vcc, 0, v31, vcc
	v_add_co_u32_e32 v70, vcc, s39, v30
	s_nop 1
	v_addc_co_u32_e32 v71, vcc, 0, v31, vcc
	v_add_co_u32_e32 v72, vcc, s40, v30
	s_nop 1
	v_addc_co_u32_e32 v73, vcc, 0, v31, vcc
	v_add_co_u32_e32 v74, vcc, s41, v30
	s_nop 1
	v_addc_co_u32_e32 v75, vcc, 0, v31, vcc
	v_add_co_u32_e32 v80, vcc, s42, v30
	s_nop 1
	v_addc_co_u32_e32 v81, vcc, 0, v31, vcc
	v_add_co_u32_e32 v82, vcc, s43, v30
	s_nop 1
	v_addc_co_u32_e32 v83, vcc, 0, v31, vcc
	v_add_co_u32_e32 v84, vcc, s44, v30
	s_nop 1
	v_addc_co_u32_e32 v85, vcc, 0, v31, vcc
	v_add_co_u32_e32 v86, vcc, s45, v30
	s_nop 1
	v_addc_co_u32_e32 v87, vcc, 0, v31, vcc
	v_add_co_u32_e32 v88, vcc, s46, v30
	s_nop 1
	v_addc_co_u32_e32 v89, vcc, 0, v31, vcc
	v_add_co_u32_e32 v90, vcc, s47, v30
	s_nop 1
	v_addc_co_u32_e32 v91, vcc, 0, v31, vcc
	v_add_co_u32_e32 v92, vcc, s48, v30
	s_nop 1
	v_addc_co_u32_e32 v93, vcc, 0, v31, vcc
	v_add_co_u32_e32 v94, vcc, s49, v30
	s_nop 1
	v_addc_co_u32_e32 v95, vcc, 0, v31, vcc
	v_add_co_u32_e32 v96, vcc, s50, v30
	s_nop 1
	v_addc_co_u32_e32 v97, vcc, 0, v31, vcc
	v_add_co_u32_e32 v30, vcc, s51, v30
	s_nop 1
	v_addc_co_u32_e32 v31, vcc, 0, v31, vcc
	global_load_dword v79, v[32:33], off offset:-4096
	global_load_dword v98, v[32:33], off
	global_load_dword v99, v[34:35], off offset:-4096
	global_load_dword v100, v[34:35], off
	global_load_dword v101, v[36:37], off offset:-4096
	global_load_dword v102, v[36:37], off
	global_load_dword v103, v[38:39], off offset:-4096
	global_load_dword v104, v[38:39], off
	global_load_dword v105, v[40:41], off offset:-4096
	global_load_dword v106, v[40:41], off
	global_load_dword v107, v[42:43], off offset:-4096
	global_load_dword v108, v[42:43], off
	global_load_dword v109, v[44:45], off offset:-4096
	global_load_dword v110, v[44:45], off
	global_load_dword v111, v[46:47], off offset:-4096
	global_load_dword v32, v[46:47], off
	global_load_dword v33, v[48:49], off offset:-4096
	global_load_dword v34, v[48:49], off
	global_load_dword v35, v[50:51], off offset:-4096
	global_load_dword v36, v[50:51], off
	global_load_dword v37, v[52:53], off offset:-4096
	global_load_dword v38, v[52:53], off
	global_load_dword v39, v[54:55], off offset:-4096
; #define LAS __attribute__((address_space(3)))
; __device__ __forceinline__ unsigned pk2(float lo, float hi) { f32x2 v = {lo, hi}; bf16x2_t b = __builtin_convertvector(v, bf16x2_t); return __builtin_bit_cast(unsigned, b); }
; __device__ __forceinline__ void transpose_item(const float* W, int K, int N, bf16_t* WT, const float* gk, int mode, LAS float* scr_, int item, int lane) {
;     ...
; #pragma unroll
;     for (int kp = 0; kp < 32; ++kp) { va[kp] = src[(size_t)(2 * kp) * N]; vb[kp] = src[(size_t)(2 * kp + 1) * N]; }
; #pragma unroll
;     for (int kp = 0; kp < 32; ++kp) {
;         float a = va[kp], b = vb[kp];
;         if (gk) { a *= gk[k0 + 2 * kp]; b *= gk[k0 + 2 * kp + 1]; }
;         scr[kp * 65 + lane] = pk2(a, b);
;     }
;     asm volatile("s_waitcnt lgkmcnt(0)" ::: "memory");
;     const int c = lane & 7;
; #pragma unroll
;     for (int j = 0; j < 8; ++j) { const int r = (lane >> 3) + 8 * j; const LAS unsigned* q = scr + (4 * c) * 65 + r;
;         u32x4 o; o.x = q[0]; o.y = q[65]; o.z = q[130]; o.w = q[195];
;         *(u32x4*)(WT + (size_t)(n0 + r) * K + k0 + 8 * c) = o; }
	global_load_dword v40, v[54:55], off
	global_load_dword v41, v[56:57], off offset:-4096
	global_load_dword v42, v[56:57], off
	global_load_dword v43, v[58:59], off offset:-4096
	global_load_dword v44, v[58:59], off
	global_load_dword v45, v[60:61], off offset:-4096
	global_load_dword v112, v[60:61], off
	global_load_dword v46, v[62:63], off offset:-4096
	global_load_dword v47, v[62:63], off
	global_load_dword v48, v[64:65], off offset:-4096
	global_load_dword v49, v[64:65], off
	global_load_dword v50, v[66:67], off offset:-4096
	global_load_dword v51, v[66:67], off
	global_load_dword v52, v[68:69], off offset:-4096
	global_load_dword v53, v[68:69], off
	global_load_dword v54, v[70:71], off offset:-4096
	global_load_dword v55, v[70:71], off
	global_load_dword v56, v[72:73], off offset:-4096
	global_load_dword v57, v[72:73], off
	global_load_dword v58, v[74:75], off offset:-4096
	global_load_dword v59, v[74:75], off
	global_load_dword v60, v[80:81], off offset:-4096
	global_load_dword v61, v[80:81], off
	global_load_dword v62, v[82:83], off offset:-4096
	global_load_dword v63, v[82:83], off
	global_load_dword v64, v[84:85], off offset:-4096
	global_load_dword v65, v[84:85], off
	global_load_dword v66, v[86:87], off offset:-4096
	global_load_dword v67, v[86:87], off
	global_load_dword v68, v[88:89], off offset:-4096
	global_load_dword v69, v[88:89], off
	global_load_dword v70, v[90:91], off offset:-4096
	global_load_dword v71, v[90:91], off
	global_load_dword v72, v[92:93], off offset:-4096
	global_load_dword v73, v[92:93], off
	global_load_dword v74, v[94:95], off offset:-4096
	global_load_dword v75, v[94:95], off
	global_load_dword v80, v[96:97], off offset:-4096
	global_load_dword v81, v[96:97], off
	global_load_dword v82, v[30:31], off offset:-4096
	global_load_dword v83, v[30:31], off
	s_waitcnt vmcnt(62)
	v_cvt_pk_bf16_f32 v30, v79, v98
	s_waitcnt vmcnt(60)
	v_cvt_pk_bf16_f32 v31, v99, v100
	s_waitcnt vmcnt(58)
	v_cvt_pk_bf16_f32 v79, v101, v102
	s_waitcnt vmcnt(56)
	v_cvt_pk_bf16_f32 v84, v103, v104
	s_waitcnt vmcnt(54)
	v_cvt_pk_bf16_f32 v85, v105, v106
	s_waitcnt vmcnt(52)
	v_cvt_pk_bf16_f32 v86, v107, v108
	s_waitcnt vmcnt(50)
	v_cvt_pk_bf16_f32 v87, v109, v110
	s_waitcnt vmcnt(48)
	v_cvt_pk_bf16_f32 v32, v111, v32
	s_waitcnt vmcnt(46)
	v_cvt_pk_bf16_f32 v33, v33, v34
	s_waitcnt vmcnt(44)
	v_cvt_pk_bf16_f32 v34, v35, v36
	s_waitcnt vmcnt(42)
	v_cvt_pk_bf16_f32 v35, v37, v38
	s_waitcnt vmcnt(40)
	v_cvt_pk_bf16_f32 v36, v39, v40
	s_waitcnt vmcnt(38)
	v_cvt_pk_bf16_f32 v37, v41, v42
	s_waitcnt vmcnt(36)
	v_cvt_pk_bf16_f32 v38, v43, v44
	s_waitcnt vmcnt(34)
	v_cvt_pk_bf16_f32 v39, v45, v112
	s_waitcnt vmcnt(32)
	v_cvt_pk_bf16_f32 v40, v46, v47
	s_waitcnt vmcnt(30)
	v_cvt_pk_bf16_f32 v41, v48, v49
	s_waitcnt vmcnt(28)
	v_cvt_pk_bf16_f32 v42, v50, v51
	s_waitcnt vmcnt(26)
	v_cvt_pk_bf16_f32 v43, v52, v53
	s_waitcnt vmcnt(24)
	v_cvt_pk_bf16_f32 v44, v54, v55
	s_waitcnt vmcnt(22)
	v_cvt_pk_bf16_f32 v45, v56, v57
	s_waitcnt vmcnt(20)
	v_cvt_pk_bf16_f32 v46, v58, v59
	s_waitcnt vmcnt(18)
	v_cvt_pk_bf16_f32 v47, v60, v61
	s_waitcnt vmcnt(16)
	v_cvt_pk_bf16_f32 v48, v62, v63
	s_waitcnt vmcnt(14)
	v_cvt_pk_bf16_f32 v49, v64, v65
	s_waitcnt vmcnt(12)
	v_cvt_pk_bf16_f32 v50, v66, v67
	s_waitcnt vmcnt(10)
	v_cvt_pk_bf16_f32 v51, v68, v69
	s_waitcnt vmcnt(8)
	v_cvt_pk_bf16_f32 v52, v70, v71
	s_waitcnt vmcnt(6)
	v_cvt_pk_bf16_f32 v53, v72, v73
	s_waitcnt vmcnt(4)
	v_cvt_pk_bf16_f32 v54, v74, v75
	s_waitcnt vmcnt(2)
	v_cvt_pk_bf16_f32 v55, v80, v81
	s_waitcnt vmcnt(0)
	v_cvt_pk_bf16_f32 v56, v82, v83
	ds_write2_b32 v77, v30, v31 offset1:65
	ds_write2_b32 v77, v79, v84 offset0:130 offset1:195
	ds_write2_b32 v23, v85, v86 offset0:4 offset1:69
	ds_write2_b32 v23, v87, v32 offset0:134 offset1:199
	ds_write2_b32 v24, v33, v34 offset0:8 offset1:73
	ds_write2_b32 v24, v35, v36 offset0:138 offset1:203
	ds_write2_b32 v25, v37, v38 offset0:12 offset1:77
	ds_write2_b32 v25, v39, v40 offset0:142 offset1:207
	ds_write2_b32 v26, v41, v42 offset0:16 offset1:81
	ds_write2_b32 v26, v43, v44 offset0:146 offset1:211
	ds_write2_b32 v27, v45, v46 offset0:20 offset1:85
	ds_write2_b32 v27, v47, v48 offset0:150 offset1:215
	ds_write2_b32 v28, v49, v50 offset0:24 offset1:89
	ds_write2_b32 v28, v51, v52 offset0:154 offset1:219
	ds_write2_b32 v29, v53, v54 offset0:28 offset1:93
	ds_write2_b32 v29, v55, v56 offset0:158 offset1:223
	s_waitcnt lgkmcnt(0)
	ds_read2_b32 v[30:31], v22 offset0:65 offset1:73
	ds_read2_b32 v[50:51], v22 offset0:130 offset1:138
	ds_read2_b32 v[32:33], v22 offset0:195 offset1:203
	ds_read2_b32 v[52:53], v22 offset1:8
	ds_read2_b32 v[54:55], v22 offset0:16 offset1:24
	ds_read2_b32 v[34:35], v22 offset0:81 offset1:89
	ds_read2_b32 v[56:57], v22 offset0:146 offset1:154
	ds_read2_b32 v[36:37], v22 offset0:211 offset1:219
	ds_read2_b32 v[38:39], v22 offset0:97 offset1:105
	ds_read2_b32 v[58:59], v22 offset0:162 offset1:170
	ds_read2_b32 v[40:41], v22 offset0:227 offset1:235
	ds_read2_b32 v[60:61], v22 offset0:32 offset1:40
	ds_read2_b32 v[62:63], v22 offset0:48 offset1:56
	ds_read2_b32 v[42:43], v22 offset0:113 offset1:121
	ds_read2_b32 v[64:65], v22 offset0:178 offset1:186
	ds_read2_b32 v[44:45], v22 offset0:243 offset1:251
	s_waitcnt lgkmcnt(12)
	v_mov_b32_e32 v46, v52
	v_mov_b32_e32 v47, v30
	v_mov_b32_e32 v48, v50
	v_mov_b32_e32 v49, v32
	v_mov_b32_e32 v30, v53
	v_mov_b32_e32 v32, v51
	s_waitcnt lgkmcnt(11)
	v_mov_b32_e32 v50, v54
	s_waitcnt lgkmcnt(10)
	v_mov_b32_e32 v51, v34
	s_waitcnt lgkmcnt(9)
	v_mov_b32_e32 v52, v56
	s_waitcnt lgkmcnt(8)
	v_mov_b32_e32 v53, v36
	v_mov_b32_e32 v34, v55
	v_mov_b32_e32 v36, v57
	s_waitcnt lgkmcnt(4)
	v_mov_b32_e32 v54, v60
	v_mov_b32_e32 v55, v38
	v_mov_b32_e32 v56, v58
	v_mov_b32_e32 v57, v40
	v_mov_b32_e32 v38, v61
	v_mov_b32_e32 v40, v59
	s_waitcnt lgkmcnt(3)
	v_mov_b32_e32 v58, v62
	s_waitcnt lgkmcnt(2)
	v_mov_b32_e32 v59, v42
	s_waitcnt lgkmcnt(1)
	v_mov_b32_e32 v60, v64
	s_waitcnt lgkmcnt(0)
	v_mov_b32_e32 v61, v44
	v_mov_b32_e32 v42, v63
	v_mov_b32_e32 v44, v65
	global_store_dwordx4 v[2:3], v[46:49], off
	global_store_dwordx4 v[8:9], v[30:33], off
	global_store_dwordx4 v[10:11], v[50:53], off
	global_store_dwordx4 v[12:13], v[34:37], off
	global_store_dwordx4 v[14:15], v[54:57], off
	global_store_dwordx4 v[16:17], v[38:41], off
	global_store_dwordx4 v[18:19], v[58:61], off
	global_store_dwordx4 v[20:21], v[42:45], off
	s_waitcnt lgkmcnt(0)
	s_cbranch_scc1 .LBB0_636

; #define PIN(i) ((const float*)ldq_(L, (i)))
; __device__ __forceinline__ unsigned pk2(float lo, float hi) { f32x2 v = {lo, hi}; bf16x2_t b = __builtin_convertvector(v, bf16x2_t); return __builtin_bit_cast(unsigned, b); }
; __device__ __forceinline__ void prep(const Params& p, LAS unsigned char* L, int wv, int vb, int nvb, int l, int mask) {
;     ...
;     if (mask & PM_POOL) {
;         for (int t = gt; t < 4 * 128 * 16; t += NGT) {
;             const int ko = t & 15, n = (t >> 4) & 127, g = (t >> 11) & 3;
;             const float* src = PIN(I_WPOOL) + ((size_t)(l * 4 + g) * 128 + 8 * ko) * 128 + n; const float sc = PIN(I_PSCALE)[l * 512 + g * 128 + n];
;             u32x4 o; o.x = pk2(src[0] * sc, src[128] * sc); o.y = pk2(src[256] * sc, src[384] * sc); o.z = pk2(src[512] * sc, src[640] * sc); o.w = pk2(src[768] * sc, src[896] * sc);
;             *(u32x4*)((bf16_t*)(wl + WL_POOL) + ((size_t)g * 128 + n) * 128 + 8 * ko) = o;
;         }
.LBB0_639:
	v_mov_b32_e32 v8, 0
	v_mov_b32_e32 v10, v3
	v_add_u32_e32 v8, 0, v8
	v_add_u32_e32 v8, 0x20178, v8
	s_nop 0
	v_bfe_u32 v13, v6, 11, 2
	v_add_u32_e32 v10, 0, v10
	v_add_u32_e32 v10, 0x20180, v10
	s_nop 0
	v_and_b32_e32 v22, 0x78, v5
	v_lshlrev_b32_e32 v2, 16, v13
	s_waitcnt lgkmcnt(1)
	v_readlane_b32 s19, v251, 31
	v_readlane_b32 s18, v251, 30
	v_bfe_u32 v7, v6, 4, 7
	v_add_u32_e32 v6, s6, v6
	v_lshl_add_u64 v[8:9], s[18:19], 0, v[2:3]
	v_lshlrev_b32_e32 v2, 9, v22
	v_lshl_add_u64 v[8:9], v[8:9], 0, v[2:3]
	v_lshlrev_b32_e32 v2, 2, v7
	v_lshl_add_u64 v[8:9], v[8:9], 0, v[2:3]
	s_waitcnt lgkmcnt(0)
	v_readlane_b32 s19, v251, 33
	v_readlane_b32 s18, v251, 32
	v_lshl_add_u64 v[10:11], v[8:9], 0, s[14:15]
	v_add_co_u32_e32 v8, vcc, s16, v8
	v_lshl_or_b32 v2, v13, 9, v2
	s_nop 0
	v_addc_co_u32_e32 v9, vcc, 0, v9, vcc
	global_load_dword v12, v2, s[18:19] offset:2048
	global_load_dword v14, v[8:9], off
	global_load_dword v15, v[10:11], off offset:512
	global_load_dword v16, v[10:11], off offset:1024
	global_load_dword v17, v[10:11], off offset:1536
	global_load_dword v18, v[10:11], off offset:2048
	global_load_dword v19, v[10:11], off offset:2560
	global_load_dword v20, v[10:11], off offset:3072
	global_load_dword v21, v[10:11], off offset:3584
	v_lshlrev_b32_e32 v2, 8, v7
	v_lshl_or_b32 v2, v13, 15, v2
	v_lshl_add_u64 v[8:9], s[10:11], 0, v[2:3]
	v_lshlrev_b32_e32 v2, 1, v22
	v_cmp_lt_i32_e32 vcc, s17, v6
	v_lshl_add_u64 v[22:23], v[8:9], 0, v[2:3]
	v_add_u32_e32 v5, s7, v5
	s_or_b64 s[12:13], vcc, s[12:13]
	s_waitcnt vmcnt(6)
	v_pk_mul_f32 v[8:9], v[12:13], v[14:15] op_sel_hi:[0,1]
	s_waitcnt vmcnt(4)
	v_pk_mul_f32 v[10:11], v[12:13], v[16:17] op_sel_hi:[0,1]
	s_waitcnt vmcnt(2)
	v_pk_mul_f32 v[14:15], v[12:13], v[18:19] op_sel_hi:[0,1]
	s_waitcnt vmcnt(0)
	v_pk_mul_f32 v[12:13], v[12:13], v[20:21] op_sel_hi:[0,1]
	v_cvt_pk_bf16_f32 v8, v8, v9
	v_cvt_pk_bf16_f32 v9, v10, v11
	v_cvt_pk_bf16_f32 v10, v14, v15
	v_cvt_pk_bf16_f32 v11, v12, v13
	global_store_dwordx4 v[22:23], v[8:11], off
	s_andn2_b64 exec, exec, s[12:13]
	s_cbranch_execnz .LBB0_639

; #define PIN(i) ((const float*)ldq_(L, (i)))
; __device__ __forceinline__ void prep(const Params& p, LAS unsigned char* L, int wv, int vb, int nvb, int l, int mask) {
;     ...
;         for (int t0 = gt; t0 < MT * 32; t0 += 4 * NGT) {
;             f32x4 a[4], b[4]; size_t dsto[4];
; #pragma unroll
;             for (int u = 0; u < 4; ++u) {
;                 const int t = min(t0 + u * NGT, MT * 32 - 1);
;                 const int o8 = t & 31, m = t >> 5;
;                 const float* src = ((m < MP) ? PIN(I_PP) + ((size_t)l * MP + m) * PED : PIN(I_PS) + ((size_t)l * MS + (m - MP)) * PED) + 8 * o8;
;                 a[u] = *(const f32x4*)src; b[u] = *(const f32x4*)(src + 4); dsto[u] = (size_t)m * PED + 8 * o8;
.LBB0_643:
	v_ashrrev_i32_e32 v28, 5, v34
	v_cmp_lt_i32_e32 vcc, s19, v28
	s_and_saveexec_b64 s[16:17], vcc
	s_xor_b64 s[16:17], exec, s[16:17]
	s_cbranch_execz .LBB0_645
	v_mov_b32_e32 v2, v27
	v_add_u32_e32 v26, 0xffff0000, v28
	v_add_u32_e32 v2, 0, v2
	v_add_u32_e32 v2, 0x20118, v2
	s_nop 0
	v_lshlrev_b64 v[4:5], 10, v[26:27]
	v_mov_b32_e32 v29, v27
	s_waitcnt lgkmcnt(0)
	v_readlane_b32 s25, v251, 7
	v_readlane_b32 s24, v251, 6
	s_nop 1
	v_lshl_add_u64 v[2:3], s[24:25], 0, v[4:5]
	v_lshl_add_u64 v[2:3], v[2:3], 0, s[12:13]
.LBB0_645:
	s_andn2_saveexec_b64 s[16:17], s[16:17]
	s_cbranch_execz .LBB0_647
	v_mov_b32_e32 v2, v27
	v_ashrrev_i32_e32 v29, 31, v28
	v_add_u32_e32 v2, 0, v2
	v_add_u32_e32 v2, 0x20110, v2
	s_nop 0
	s_waitcnt lgkmcnt(0)
	v_readlane_b32 s25, v251, 5
	v_readlane_b32 s24, v251, 4
	v_lshlrev_b64 v[2:3], 10, v[28:29]
	s_nop 0
	v_lshl_add_u64 v[2:3], s[24:25], 0, v[2:3]
	v_lshl_add_u64 v[2:3], v[2:3], 0, s[14:15]
.LBB0_647:
	s_or_b64 exec, exec, s[16:17]
	v_and_b32_e32 v39, 0xf8, v38
	v_lshlrev_b32_e32 v26, 2, v39
	v_lshl_add_u64 v[10:11], v[2:3], 0, v[26:27]
	global_load_dwordx4 v[2:5], v[10:11], off offset:16
	global_load_dwordx4 v[6:9], v[10:11], off
	v_add_u32_e32 v40, s6, v34
	v_min_i32_e32 v12, 0x20ffff, v40
	v_ashrrev_i32_e32 v30, 5, v12
	v_cmp_lt_i32_e32 vcc, s19, v30
	s_and_saveexec_b64 s[16:17], vcc
	s_xor_b64 s[16:17], exec, s[16:17]
	s_cbranch_execz .LBB0_649
	v_mov_b32_e32 v10, v27
	v_add_u32_e32 v26, 0xffff0000, v30
	v_add_u32_e32 v10, 0, v10
	v_add_u32_e32 v10, 0x20118, v10
	s_nop 0
	v_lshlrev_b64 v[14:15], 10, v[26:27]
	v_mov_b32_e32 v31, v27
	s_waitcnt lgkmcnt(0)
	v_readlane_b32 s25, v251, 7
	v_readlane_b32 s24, v251, 6
	s_nop 1
	v_lshl_add_u64 v[10:11], s[24:25], 0, v[14:15]
	v_lshl_add_u64 v[10:11], v[10:11], 0, s[12:13]
.LBB0_649:
	s_andn2_saveexec_b64 s[16:17], s[16:17]
	s_cbranch_execz .LBB0_651
	v_mov_b32_e32 v10, v27
	v_ashrrev_i32_e32 v31, 31, v30
	v_add_u32_e32 v10, 0, v10
	v_add_u32_e32 v10, 0x20110, v10
	s_nop 0
	s_waitcnt lgkmcnt(0)
	v_readlane_b32 s25, v251, 5
	v_readlane_b32 s24, v251, 4
	v_lshlrev_b64 v[10:11], 10, v[30:31]
	s_nop 0
	v_lshl_add_u64 v[10:11], s[24:25], 0, v[10:11]
	v_lshl_add_u64 v[10:11], v[10:11], 0, s[14:15]
.LBB0_651:
	s_or_b64 exec, exec, s[16:17]
	v_lshlrev_b32_e32 v12, 3, v12
	v_and_b32_e32 v41, 0xf8, v12
	v_lshlrev_b32_e32 v26, 2, v41
	v_lshl_add_u64 v[18:19], v[10:11], 0, v[26:27]
	global_load_dwordx4 v[10:13], v[18:19], off offset:16
	global_load_dwordx4 v[14:17], v[18:19], off
	v_add_u32_e32 v18, s7, v34
	v_min_i32_e32 v20, 0x20ffff, v18
	v_ashrrev_i32_e32 v32, 5, v20
	v_cmp_lt_i32_e32 vcc, s19, v32
	s_and_saveexec_b64 s[16:17], vcc
	s_xor_b64 s[16:17], exec, s[16:17]
	s_cbranch_execz .LBB0_653
	v_mov_b32_e32 v18, v27
	v_add_u32_e32 v26, 0xffff0000, v32
	v_add_u32_e32 v18, 0, v18
	v_add_u32_e32 v18, 0x20118, v18
	s_nop 0
	v_lshlrev_b64 v[22:23], 10, v[26:27]
	v_mov_b32_e32 v33, v27
	s_waitcnt lgkmcnt(0)
	v_readlane_b32 s25, v251, 7
	v_readlane_b32 s24, v251, 6
	s_nop 1
	v_lshl_add_u64 v[18:19], s[24:25], 0, v[22:23]
	v_lshl_add_u64 v[18:19], v[18:19], 0, s[12:13]
.LBB0_653:
	s_andn2_saveexec_b64 s[16:17], s[16:17]
	s_cbranch_execz .LBB0_655
	v_mov_b32_e32 v18, v27
	v_ashrrev_i32_e32 v33, 31, v32
	v_add_u32_e32 v18, 0, v18
	v_add_u32_e32 v18, 0x20110, v18
	s_nop 0
	s_waitcnt lgkmcnt(0)
	v_readlane_b32 s25, v251, 5
	v_readlane_b32 s24, v251, 4
	v_lshlrev_b64 v[18:19], 10, v[32:33]
	s_nop 0
	v_lshl_add_u64 v[18:19], s[24:25], 0, v[18:19]
	v_lshl_add_u64 v[18:19], v[18:19], 0, s[14:15]
.LBB0_655:
	s_or_b64 exec, exec, s[16:17]
	v_lshlrev_b32_e32 v20, 3, v20
	v_and_b32_e32 v42, 0xf8, v20
	v_lshlrev_b32_e32 v26, 2, v42
	v_lshl_add_u64 v[36:37], v[18:19], 0, v[26:27]
	global_load_dwordx4 v[18:21], v[36:37], off offset:16
	global_load_dwordx4 v[22:25], v[36:37], off
	v_add_u32_e32 v26, s62, v34
	v_min_i32_e32 v43, 0x20ffff, v26
	v_ashrrev_i32_e32 v34, 5, v43
	v_cmp_lt_i32_e32 vcc, s19, v34
	s_and_saveexec_b64 s[16:17], vcc
	s_xor_b64 s[16:17], exec, s[16:17]
	s_cbranch_execz .LBB0_657
	v_mov_b32_e32 v26, v27
	v_mov_b32_e32 v35, v27
	v_add_u32_e32 v26, 0, v26
	v_add_u32_e32 v26, 0x20118, v26
	s_nop 0
	v_add_u32_e32 v26, 0xffff0000, v34
	v_lshlrev_b64 v[44:45], 10, v[26:27]
	s_waitcnt lgkmcnt(0)
	v_readlane_b32 s25, v251, 7
	v_readlane_b32 s24, v251, 6
	s_nop 1
	v_lshl_add_u64 v[36:37], s[24:25], 0, v[44:45]
	v_lshl_add_u64 v[36:37], v[36:37], 0, s[12:13]
.LBB0_657:
	s_andn2_saveexec_b64 s[16:17], s[16:17]
	s_cbranch_execz .LBB0_642
	v_mov_b32_e32 v26, v27
	v_ashrrev_i32_e32 v35, 31, v34
	v_add_u32_e32 v26, 0, v26
	v_add_u32_e32 v26, 0x20110, v26
	s_nop 0
	s_waitcnt lgkmcnt(0)
	v_readlane_b32 s25, v251, 5
	v_readlane_b32 s24, v251, 4
	v_lshlrev_b64 v[36:37], 10, v[34:35]
	s_nop 0
	v_lshl_add_u64 v[36:37], s[24:25], 0, v[36:37]
	v_lshl_add_u64 v[36:37], v[36:37], 0, s[14:15]
	s_branch .LBB0_642

; __device__ __forceinline__ int tid_of(int wv) { return wv * 64 + (int)__builtin_amdgcn_mbcnt_hi(~0u, __builtin_amdgcn_mbcnt_lo(~0u, 0u)); }
; #define LAS __attribute__((address_space(3)))
; #define PIN(i) ((const float*)ldq_(L, (i)))
; #define PREP_CONV(bit, SRC, Kd, Nd, DST, GK, MODE) if (mask & (bit)) { for (int it = gw; it < ((Kd) / 64) * ((Nd) / 64); it += NGW) transpose_item((SRC), (Kd), (Nd), (bf16_t*)(wl + (DST)), (GK), (MODE), scr, it, lane); }
; __device__ __forceinline__ void prep(const Params& p, LAS unsigned char* L, int wv, int vb, int nvb, int l, int mask) {
;     int tid_ = tid_of(wv); asm volatile("" : "+v"(tid_));
;     const int tid = tid_, lane = tid & 63, wave = __builtin_amdgcn_readfirstlane(tid >> 6);
;     const int gw = vb * 8 + wave, NGW = nvb * 8; const int gt = vb * 512 + tid, NGT = nvb * 512;
;     LAS float* scr = (LAS float*)(L + wave * 16384);
;     unsigned char* ws = PWS; unsigned char* wl = ws + WS_W + (size_t)l * WL_STRIDE;
;     ...
;     PREP_CONV(PM_FFA_IN, PIN(I_WFFA_IN) + (size_t)l * DM * NFF2, DM, NFF2, WL_FFA_IN, PIN(I_NFFA) + l * DM, 1)
.LBB0_660:
	s_and_b64 vcc, exec, s[0:1]
	s_cbranch_vccz .LBB0_750
	v_mov_b32_e32 v104, v183
	v_mov_b32_e32 v3, 0
	v_mov_b32_e32 v5, 0
	v_add_u32_e32 v3, 0, v3
	v_add_u32_e32 v3, 0x201c0, v3
	s_nop 0
	v_readfirstlane_b32 s0, v104
	s_ashr_i32 s0, s0, 6
	s_add_i32 s14, s0, s33
	s_lshl_b32 s0, s0, 14
	v_and_b32_e32 v2, 63, v104
	s_add_i32 s15, s0, 0
	s_waitcnt lgkmcnt(0)
	v_readlane_b32 s7, v251, 49
	v_readlane_b32 s6, v251, 48
	s_cmpk_gt_i32 s14, 0x57f
	v_lshl_add_u32 v3, v2, 2, s15
	v_and_b32_e32 v106, 7, v104
	v_lshrrev_b32_e32 v105, 3, v2
	s_cbranch_scc1 .LBB0_728
	v_lshlrev_b32_e32 v4, 4, v106
	v_mul_u32_u24_e32 v8, 0x410, v106
	v_lshl_add_u64 v[6:7], s[6:7], 0, v[4:5]
	v_lshlrev_b32_e32 v4, 2, v105
	v_add3_u32 v107, s15, v8, v4
	s_lshl_b32 s16, s14, 6
	s_lshl_b32 s17, s14, 5
	v_lshlrev_b32_e32 v4, 2, v2
	s_movk_i32 s18, 0x5000
	s_mov_b32 s19, 0xb000
	s_mov_b32 s22, 0x10000
	s_mov_b32 s23, 0x16000
	s_mov_b32 s24, 0x1b000
	s_mov_b32 s25, 0x21000
	s_mov_b32 s26, 0x26000
	s_mov_b32 s27, 0x2c000
	s_mov_b32 s28, 0x31000
	s_mov_b32 s29, 0x37000
	s_mov_b32 s30, 0x3c000
	s_mov_b32 s31, 0x42000
	s_mov_b32 s33, 0x47000
	s_mov_b32 s34, 0x4d000
	s_mov_b32 s35, 0x52000
	s_mov_b32 s36, 0x58000
	s_mov_b32 s37, 0x5d000
	s_mov_b32 s38, 0x63000
	s_mov_b32 s39, 0x68000
	s_mov_b32 s40, 0x6e000
	s_mov_b32 s41, 0x73000
	s_mov_b32 s42, 0x79000
	s_mov_b32 s43, 0x7e000
	s_mov_b32 s44, 0x84000
	s_mov_b32 s45, 0x89000
	s_mov_b32 s46, 0x8f000
	s_mov_b32 s47, 0x94000
	s_mov_b32 s48, 0x9a000
	s_mov_b32 s49, 0x9f000
	s_mov_b32 s50, 0xa5000
	s_mov_b32 s51, 0xaa000
	s_mov_b32 s52, 0xb0000
	s_mov_b32 s53, 0xb5000
	s_mov_b32 s54, 0xbb000
	s_mov_b32 s55, 0xc0000
	s_mov_b32 s56, 0xc6000
	s_mov_b32 s57, 0xcb000
	s_mov_b32 s58, 0xd1000
	s_mov_b32 s59, 0xd6000
	s_mov_b32 s60, 0xdc000
	s_mov_b32 s61, 0xe1000
	s_mov_b32 s62, 0xe7000
	s_mov_b32 s63, 0xec000
	s_mov_b32 s64, 0xf2000
	s_mov_b32 s65, 0xf7000
	s_mov_b32 s66, 0xfd000
	s_mov_b32 s67, 0x102000
	s_mov_b32 s68, 0x108000
	s_mov_b32 s69, 0x10d000
	s_mov_b32 s70, 0x113000
	s_mov_b32 s71, 0x118000
	s_mov_b32 s72, 0x11e000
	s_mov_b32 s73, 0x123000
	s_mov_b32 s74, 0x129000
	s_mov_b32 s75, 0x12e000
	s_mov_b32 s76, 0x134000
	s_mov_b32 s77, 0x139000
	s_mov_b32 s78, 0x13f000
	s_mov_b32 s79, 0x144000
	s_mov_b32 s80, 0x14a000
	s_mov_b32 s81, 0x14f000
	s_mov_b32 s82, s14
	s_branch .LBB0_664

; #define LAS __attribute__((address_space(3)))
; __device__ __forceinline__ void transpose_item(const float* W, int K, int N, bf16_t* WT, const float* gk, int mode, LAS float* scr_, int item, int lane) {
;     LAS unsigned* scr = (LAS unsigned*)scr_;
;     const int nblk = N / 64, kb = item / nblk, nb = item % nblk, k0 = 64 * kb, n0 = 64 * nb;
;     const int sc = (mode == 1) ? (((n0 >> 7) & 1) * DFF + (n0 >> 8) * 128 + (n0 & 127)) : n0;
;     const float* src = W + (size_t)k0 * N + sc + lane;
;     float va[32], vb[32];
; #pragma unroll
;     for (int kp = 0; kp < 32; ++kp) { va[kp] = src[(size_t)(2 * kp) * N]; vb[kp] = src[(size_t)(2 * kp + 1) * N]; }
; #pragma unroll
;     for (int kp = 0; kp < 32; ++kp) {
;         float a = va[kp], b = vb[kp];
;         if (gk) { a *= gk[k0 + 2 * kp]; b *= gk[k0 + 2 * kp + 1]; }
.LBB0_664:
	v_mov_b32_e32 v8, 0
	s_mul_hi_i32 s0, s82, 0x2e8ba2e9
	v_add_u32_e32 v8, 0, v8
	v_add_u32_e32 v8, 0x20140, v8
	s_lshr_b32 s8, s0, 31
	s_ashr_i32 s0, s0, 4
	s_nop 0
	s_add_i32 s11, s0, s8
	s_mul_i32 s0, s11, 0xffffea00
	s_mul_i32 s9, s11, 0xfffff500
	s_add_i32 s83, s16, s0
	s_bfe_i32 s0, s82, 0x10001
	s_add_i32 s9, s17, s9
	s_and_b32 s0, s0, 0xb00
	s_and_b32 s9, s9, 0xffffff80
	s_lshl_b32 s8, s11, 6
	s_add_i32 s0, s0, s9
	s_and_b32 s9, s83, 64
	s_waitcnt lgkmcnt(0)
	v_readlane_b32 s10, v251, 16
	s_or_b32 s0, s0, s9
	s_ashr_i32 s9, s8, 31
	s_mul_i32 s11, s11, 0x160000
	v_readlane_b32 s1, v251, 17
	s_mul_hi_i32 s12, s8, 0x5800
	s_add_u32 s10, s10, s11
	s_addc_u32 s11, s1, s12
	s_ashr_i32 s1, s0, 31
	s_lshl_b64 s[0:1], s[0:1], 2
	s_add_u32 s0, s10, s0
	s_addc_u32 s1, s11, s1
	v_lshl_add_u64 v[8:9], s[0:1], 0, v[4:5]
	v_add_co_u32_e32 v46, vcc, s18, v8
	v_mov_b32_e32 v10, 0
	s_nop 0
	v_addc_co_u32_e32 v47, vcc, 0, v9, vcc
	v_add_co_u32_e32 v48, vcc, s19, v8
	s_waitcnt vmcnt(12)
	s_nop 0
	v_addc_co_u32_e32 v49, vcc, 0, v9, vcc
	s_waitcnt vmcnt(11)
	v_add_co_u32_e32 v50, vcc, s22, v8
	v_add_u32_e32 v10, 0, v10
	s_waitcnt vmcnt(10)
	v_addc_co_u32_e32 v51, vcc, 0, v9, vcc
	v_add_co_u32_e32 v52, vcc, s23, v8
	v_add_u32_e32 v10, 0x20138, v10
	s_nop 0
	v_addc_co_u32_e32 v53, vcc, 0, v9, vcc
	v_add_co_u32_e32 v54, vcc, s24, v8
	s_nop 0
	s_nop 0
	v_addc_co_u32_e32 v55, vcc, 0, v9, vcc
	v_add_co_u32_e32 v56, vcc, s25, v8
	s_waitcnt lgkmcnt(0)
	v_readlane_b32 s11, v251, 15
	v_addc_co_u32_e32 v57, vcc, 0, v9, vcc
	v_add_co_u32_e32 v58, vcc, s26, v8
	v_readlane_b32 s10, v251, 14
	s_nop 0
	v_addc_co_u32_e32 v59, vcc, 0, v9, vcc
	v_add_co_u32_e32 v60, vcc, s27, v8
	s_cmp_lg_u64 s[10:11], 0
	s_nop 0
	v_addc_co_u32_e32 v61, vcc, 0, v9, vcc
	s_waitcnt vmcnt(9)
	v_add_co_u32_e32 v66, vcc, s28, v8
	s_cselect_b64 s[12:13], -1, 0
	s_nop 0
	v_addc_co_u32_e32 v67, vcc, 0, v9, vcc
	v_add_co_u32_e32 v68, vcc, s29, v8
	s_cmp_eq_u64 s[10:11], 0
	s_nop 0
	v_addc_co_u32_e32 v69, vcc, 0, v9, vcc
	v_add_co_u32_e32 v70, vcc, s30, v8
	s_nop 1
	v_addc_co_u32_e32 v71, vcc, 0, v9, vcc
	v_add_co_u32_e32 v72, vcc, s31, v8
	s_nop 1
	v_addc_co_u32_e32 v73, vcc, 0, v9, vcc
	v_add_co_u32_e32 v74, vcc, s33, v8
	s_nop 1
	v_addc_co_u32_e32 v75, vcc, 0, v9, vcc
	v_add_co_u32_e32 v76, vcc, s34, v8
	s_nop 1
	v_addc_co_u32_e32 v77, vcc, 0, v9, vcc
	v_add_co_u32_e32 v78, vcc, s35, v8
	s_nop 1
	v_addc_co_u32_e32 v79, vcc, 0, v9, vcc
	v_add_co_u32_e32 v80, vcc, s36, v8
	s_nop 1
	v_addc_co_u32_e32 v81, vcc, 0, v9, vcc
	v_add_co_u32_e32 v84, vcc, s37, v8
	s_nop 1
	v_addc_co_u32_e32 v85, vcc, 0, v9, vcc
	v_add_co_u32_e32 v82, vcc, s38, v8
	s_nop 1
	v_addc_co_u32_e32 v83, vcc, 0, v9, vcc
	v_add_co_u32_e32 v86, vcc, s39, v8
	s_nop 1
	v_addc_co_u32_e32 v87, vcc, 0, v9, vcc
	v_add_co_u32_e32 v88, vcc, s40, v8
	s_nop 1
	v_addc_co_u32_e32 v89, vcc, 0, v9, vcc
	v_add_co_u32_e32 v90, vcc, s41, v8
	s_nop 1
	v_addc_co_u32_e32 v91, vcc, 0, v9, vcc
	v_add_co_u32_e32 v92, vcc, s42, v8
	s_nop 1
	v_addc_co_u32_e32 v93, vcc, 0, v9, vcc
	v_add_co_u32_e32 v94, vcc, s43, v8
	s_nop 1
	v_addc_co_u32_e32 v95, vcc, 0, v9, vcc
	v_add_co_u32_e32 v96, vcc, s44, v8
	s_nop 1
	v_addc_co_u32_e32 v97, vcc, 0, v9, vcc
	v_add_co_u32_e32 v42, vcc, s46, v8
	s_nop 1
	v_addc_co_u32_e32 v43, vcc, 0, v9, vcc
	v_add_co_u32_e32 v44, vcc, s47, v8
	s_nop 1
	v_addc_co_u32_e32 v45, vcc, 0, v9, vcc
	v_add_co_u32_e32 v64, vcc, s48, v8
	s_nop 1
	v_addc_co_u32_e32 v65, vcc, 0, v9, vcc
	v_add_co_u32_e32 v98, vcc, s49, v8
	s_nop 1
	v_addc_co_u32_e32 v99, vcc, 0, v9, vcc
	v_add_co_u32_e32 v100, vcc, s50, v8
	s_nop 1
	v_addc_co_u32_e32 v101, vcc, 0, v9, vcc
	v_add_co_u32_e32 v108, vcc, s51, v8
	s_nop 1
	v_addc_co_u32_e32 v109, vcc, 0, v9, vcc
	v_add_co_u32_e32 v32, vcc, s54, v8
	s_nop 1
	v_addc_co_u32_e32 v33, vcc, 0, v9, vcc
	v_add_co_u32_e32 v34, vcc, s55, v8
	s_nop 1
	v_addc_co_u32_e32 v35, vcc, 0, v9, vcc
	v_add_co_u32_e32 v38, vcc, s56, v8
	s_nop 1
	v_addc_co_u32_e32 v39, vcc, 0, v9, vcc
	v_add_co_u32_e32 v62, vcc, s57, v8
	s_nop 1
	v_addc_co_u32_e32 v63, vcc, 0, v9, vcc
	v_add_co_u32_e32 v110, vcc, s58, v8
	s_nop 1
	v_addc_co_u32_e32 v111, vcc, 0, v9, vcc
	v_add_co_u32_e32 v112, vcc, s59, v8
	s_nop 1
	v_addc_co_u32_e32 v113, vcc, 0, v9, vcc
	v_add_co_u32_e32 v24, vcc, s62, v8
	s_nop 1
	v_addc_co_u32_e32 v25, vcc, 0, v9, vcc
	v_add_co_u32_e32 v26, vcc, s63, v8
	s_nop 1
	v_addc_co_u32_e32 v27, vcc, 0, v9, vcc
	v_add_co_u32_e32 v30, vcc, s64, v8
	s_nop 1
	v_addc_co_u32_e32 v31, vcc, 0, v9, vcc
	v_add_co_u32_e32 v36, vcc, s65, v8
	s_nop 1
	v_addc_co_u32_e32 v37, vcc, 0, v9, vcc
	v_add_co_u32_e32 v114, vcc, s66, v8
	s_nop 1
	v_addc_co_u32_e32 v115, vcc, 0, v9, vcc
	v_add_co_u32_e32 v116, vcc, s67, v8
	s_nop 1
	v_addc_co_u32_e32 v117, vcc, 0, v9, vcc
	v_add_co_u32_e32 v16, vcc, s70, v8
	s_nop 1
	v_addc_co_u32_e32 v17, vcc, 0, v9, vcc
	v_add_co_u32_e32 v18, vcc, s71, v8
	s_nop 1
	v_addc_co_u32_e32 v19, vcc, 0, v9, vcc
	v_add_co_u32_e32 v22, vcc, s72, v8
	s_nop 1
	v_addc_co_u32_e32 v23, vcc, 0, v9, vcc
	v_add_co_u32_e32 v28, vcc, s73, v8
	s_nop 1
	v_addc_co_u32_e32 v29, vcc, 0, v9, vcc
	v_add_co_u32_e32 v118, vcc, s74, v8
	s_nop 1
	v_addc_co_u32_e32 v119, vcc, 0, v9, vcc
	v_add_co_u32_e32 v120, vcc, s75, v8
	s_nop 1
	v_addc_co_u32_e32 v121, vcc, 0, v9, vcc
	v_add_co_u32_e32 v122, vcc, s45, v8
	s_nop 1
	v_addc_co_u32_e32 v123, vcc, 0, v9, vcc
	v_add_co_u32_e32 v124, vcc, s52, v8
	s_nop 1
	v_addc_co_u32_e32 v125, vcc, 0, v9, vcc
	v_add_co_u32_e32 v126, vcc, s53, v8
	s_nop 1
	v_addc_co_u32_e32 v127, vcc, 0, v9, vcc
	v_add_co_u32_e32 v128, vcc, s60, v8
	s_nop 1
	v_addc_co_u32_e32 v129, vcc, 0, v9, vcc
	v_add_co_u32_e32 v130, vcc, s61, v8
	s_nop 1
	v_addc_co_u32_e32 v131, vcc, 0, v9, vcc
	v_add_co_u32_e32 v132, vcc, s68, v8
	s_nop 1
	v_addc_co_u32_e32 v133, vcc, 0, v9, vcc
	v_add_co_u32_e32 v134, vcc, s69, v8
	s_nop 1
	v_addc_co_u32_e32 v135, vcc, 0, v9, vcc
	v_add_co_u32_e32 v136, vcc, s76, v8
	s_nop 1
	v_addc_co_u32_e32 v137, vcc, 0, v9, vcc
	v_add_co_u32_e32 v14, vcc, s77, v8
	s_nop 1
	v_addc_co_u32_e32 v15, vcc, 0, v9, vcc
	v_add_co_u32_e32 v10, vcc, s78, v8
	s_nop 1
	v_addc_co_u32_e32 v11, vcc, 0, v9, vcc
	v_add_co_u32_e32 v20, vcc, s79, v8
	s_nop 1
	v_addc_co_u32_e32 v21, vcc, 0, v9, vcc
	v_add_co_u32_e32 v102, vcc, s80, v8
	s_waitcnt vmcnt(8)
; __device__ __forceinline__ void transpose_item(const float* W, int K, int N, bf16_t* WT, const float* gk, int mode, LAS float* scr_, int item, int lane) {
;     ...
; #pragma unroll
;     for (int kp = 0; kp < 32; ++kp) { va[kp] = src[(size_t)(2 * kp) * N]; vb[kp] = src[(size_t)(2 * kp + 1) * N]; }
; #pragma unroll
;     for (int kp = 0; kp < 32; ++kp) {
;         float a = va[kp], b = vb[kp];
;         if (gk) { a *= gk[k0 + 2 * kp]; b *= gk[k0 + 2 * kp + 1]; }
	s_nop 0
	v_addc_co_u32_e32 v103, vcc, 0, v9, vcc
	v_add_co_u32_e32 v138, vcc, s81, v8
	s_nop 1
	v_addc_co_u32_e32 v139, vcc, 0, v9, vcc
	v_add_co_u32_e32 v140, vcc, 0x155000, v8
	s_nop 1
	v_addc_co_u32_e32 v141, vcc, 0, v9, vcc
	v_add_co_u32_e32 v142, vcc, 0x15a000, v8
	s_nop 1
	v_addc_co_u32_e32 v143, vcc, 0, v9, vcc
	global_load_dword v12, v[10:11], off
	global_load_dword v13, v[20:21], off offset:2048
	global_load_dword v8, v[102:103], off
	global_load_dword v9, v[138:139], off offset:2048
	s_nop 0
	global_load_dword v10, v[140:141], off
	global_load_dword v11, v[142:143], off offset:2048
	global_load_dword v102, v4, s[0:1]
	s_nop 0
	global_load_dword v15, v[14:15], off offset:2048
	s_nop 0
	global_load_dword v20, v[16:17], off
	global_load_dword v21, v[18:19], off offset:2048
	s_nop 0
	global_load_dword v16, v[22:23], off
	global_load_dword v17, v[28:29], off offset:2048
	global_load_dword v18, v[118:119], off
	global_load_dword v19, v[120:121], off offset:2048
	global_load_dword v14, v[136:137], off
	s_nop 0
	global_load_dword v23, v[134:135], off offset:2048
	global_load_dword v28, v[24:25], off
	global_load_dword v29, v[26:27], off offset:2048
	s_nop 0
	global_load_dword v24, v[30:31], off
	global_load_dword v25, v[36:37], off offset:2048
	global_load_dword v26, v[114:115], off
	global_load_dword v27, v[116:117], off offset:2048
	global_load_dword v22, v[132:133], off
	s_nop 0
	global_load_dword v31, v[130:131], off offset:2048
	global_load_dword v36, v[32:33], off
	global_load_dword v37, v[34:35], off offset:2048
	s_nop 0
	global_load_dword v32, v[38:39], off
	global_load_dword v33, v[62:63], off offset:2048
	global_load_dword v34, v[110:111], off
	global_load_dword v35, v[112:113], off offset:2048
	global_load_dword v30, v[128:129], off
	s_nop 0
	global_load_dword v39, v[126:127], off offset:2048
	global_load_dword v62, v[42:43], off
	global_load_dword v63, v[44:45], off offset:2048
	s_nop 0
	global_load_dword v42, v[64:65], off
	global_load_dword v43, v[98:99], off offset:2048
	global_load_dword v44, v[100:101], off
	global_load_dword v45, v[108:109], off offset:2048
	global_load_dword v38, v[124:125], off
	s_nop 0
	global_load_dword v65, v[122:123], off offset:2048
	global_load_dword v98, v[82:83], off
	global_load_dword v99, v[86:87], off offset:2048
	s_nop 0
	global_load_dword v82, v[88:89], off
	global_load_dword v83, v[90:91], off offset:2048
	global_load_dword v86, v[92:93], off
	global_load_dword v87, v[94:95], off offset:2048
	global_load_dword v64, v[96:97], off
	s_nop 0
	global_load_dword v85, v[84:85], off offset:2048
	s_nop 0
	global_load_dword v88, v[68:69], off
	global_load_dword v89, v[70:71], off offset:2048
	s_nop 0
	global_load_dword v68, v[72:73], off
	global_load_dword v69, v[74:75], off offset:2048
	global_load_dword v70, v[76:77], off
	global_load_dword v71, v[78:79], off offset:2048
	global_load_dword v84, v[80:81], off
	s_nop 0
	global_load_dword v67, v[66:67], off offset:2048
	s_nop 0
	global_load_dword v72, v[48:49], off
	global_load_dword v73, v[50:51], off offset:2048
	s_nop 0
	global_load_dword v48, v[52:53], off
	global_load_dword v49, v[54:55], off offset:2048
	global_load_dword v50, v[56:57], off
	global_load_dword v51, v[58:59], off offset:2048
	global_load_dword v66, v[60:61], off
	global_load_dword v103, v[46:47], off offset:2048
	s_mov_b64 s[0:1], -1
	s_cbranch_scc1 .LBB0_666
	s_lshl_b64 s[0:1], s[8:9], 2
	s_add_u32 s0, s10, s0
	s_addc_u32 s1, s11, s1
	global_load_dwordx4 v[52:55], v5, s[0:1]
	s_mov_b64 s[0:1], 0
	s_waitcnt vmcnt(0)
	v_pk_mul_f32 v[40:41], v[102:103], v[52:53]
	v_pk_mul_f32 v[46:47], v[72:73], v[54:55]

; #define LAS __attribute__((address_space(3)))
; #define PIN(i) ((const float*)ldq_(L, (i)))
; __device__ __forceinline__ unsigned pk2(float lo, float hi) { f32x2 v = {lo, hi}; bf16x2_t b = __builtin_convertvector(v, bf16x2_t); return __builtin_bit_cast(unsigned, b); }
; #define PREP_CONV(bit, SRC, Kd, Nd, DST, GK, MODE) if (mask & (bit)) { for (int it = gw; it < ((Kd) / 64) * ((Nd) / 64); it += NGW) transpose_item((SRC), (Kd), (Nd), (bf16_t*)(wl + (DST)), (GK), (MODE), scr, it, lane); }
; __device__ __forceinline__ void transpose_item(const float* W, int K, int N, bf16_t* WT, const float* gk, int mode, LAS float* scr_, int item, int lane) {
;     LAS unsigned* scr = (LAS unsigned*)scr_;
;     const int nblk = N / 64, kb = item / nblk, nb = item % nblk, k0 = 64 * kb, n0 = 64 * nb;
;     const int sc = (mode == 1) ? (((n0 >> 7) & 1) * DFF + (n0 >> 8) * 128 + (n0 & 127)) : n0;
;     const float* src = W + (size_t)k0 * N + sc + lane;
;     float va[32], vb[32];
; #pragma unroll
;     for (int kp = 0; kp < 32; ++kp) { va[kp] = src[(size_t)(2 * kp) * N]; vb[kp] = src[(size_t)(2 * kp + 1) * N]; }
; #pragma unroll
;     for (int kp = 0; kp < 32; ++kp) {
;         float a = va[kp], b = vb[kp];
;         if (gk) { a *= gk[k0 + 2 * kp]; b *= gk[k0 + 2 * kp + 1]; }
;         scr[kp * 65 + lane] = pk2(a, b);
;     }
;     asm volatile("s_waitcnt lgkmcnt(0)" ::: "memory");
;     const int c = lane & 7;
; #pragma unroll
;     for (int j = 0; j < 8; ++j) { const int r = (lane >> 3) + 8 * j; const LAS unsigned* q = scr + (4 * c) * 65 + r;
;         u32x4 o; o.x = q[0]; o.y = q[65]; o.z = q[130]; o.w = q[195];
;         *(u32x4*)(WT + (size_t)(n0 + r) * K + k0 + 8 * c) = o; }
; __device__ __forceinline__ void prep(const Params& p, LAS unsigned char* L, int wv, int vb, int nvb, int l, int mask) {
;     ...
;     PREP_CONV(PM_FFA_OUT, PIN(I_WFFA_OUT) + (size_t)l * DFF * DM, DFF, DM, WL_FFA_OUT, nullptr, 0)
.LBB0_730:
	v_mov_b32_e32 v8, 0
	s_ashr_i32 s0, s47, 31
	v_add_u32_e32 v8, 0, v8
	v_add_u32_e32 v8, 0x20148, v8
	s_lshr_b32 s0, s0, 28
	s_nop 0
	s_add_i32 s0, s47, s0
	s_ashr_i32 s1, s0, 4
	s_lshl_b32 s0, s1, 6
	s_lshl_b32 s8, s1, 10
	s_mul_i32 s9, s1, 0xffd40000
	s_ashr_i32 s1, s0, 31
	s_sub_i32 s8, s11, s8
	s_lshl_b64 s[48:49], s[0:1], 12
	v_lshl_add_u64 v[24:25], s[0:1], 1, v[6:7]
	s_waitcnt lgkmcnt(0)
	v_readlane_b32 s1, v251, 18
	v_readlane_b32 s0, v251, 19
	s_add_u32 s48, s1, s48
	v_add_u32_e32 v10, s9, v27
	s_addc_u32 s49, s0, s49
	s_ashr_i32 s9, s8, 31
	s_lshl_b64 s[0:1], s[8:9], 2
	s_add_u32 s8, s48, s0
	v_add_u32_e32 v12, 0x5800, v10
	v_add_u32_e32 v14, 0xb000, v10
	v_add_u32_e32 v16, 0x10800, v10
	v_add_u32_e32 v18, 0x16000, v10
	v_add_u32_e32 v20, 0x1b800, v10
	v_add_u32_e32 v22, 0x21000, v10
	v_add_u32_e32 v36, 0x26800, v10
	s_addc_u32 s9, s49, s1
	v_ashrrev_i32_e32 v11, 31, v10
	v_ashrrev_i32_e32 v13, 31, v12
	v_ashrrev_i32_e32 v15, 31, v14
	v_ashrrev_i32_e32 v17, 31, v16
	v_ashrrev_i32_e32 v19, 31, v18
	v_ashrrev_i32_e32 v21, 31, v20
	v_ashrrev_i32_e32 v23, 31, v22
	v_ashrrev_i32_e32 v37, 31, v36
	v_lshl_add_u64 v[8:9], s[8:9], 0, v[4:5]
	v_lshl_add_u64 v[10:11], v[10:11], 1, v[24:25]
	v_lshl_add_u64 v[12:13], v[12:13], 1, v[24:25]
	v_lshl_add_u64 v[14:15], v[14:15], 1, v[24:25]
	v_lshl_add_u64 v[16:17], v[16:17], 1, v[24:25]
	v_lshl_add_u64 v[18:19], v[18:19], 1, v[24:25]
	v_lshl_add_u64 v[20:21], v[20:21], 1, v[24:25]
	v_lshl_add_u64 v[22:23], v[22:23], 1, v[24:25]
	v_lshl_add_u64 v[24:25], v[36:37], 1, v[24:25]
	v_add_co_u32_e32 v36, vcc, s12, v8
	global_load_dword v35, v4, s[8:9]
	s_nop 0
	v_addc_co_u32_e32 v37, vcc, 0, v9, vcc
	v_add_co_u32_e32 v38, vcc, s13, v8
	s_add_i32 s0, s47, 0x800
	s_nop 0
	v_addc_co_u32_e32 v39, vcc, 0, v9, vcc
	v_add_co_u32_e32 v40, vcc, s15, v8
	s_add_i32 s11, s11, 0x20000
	s_nop 0
	v_addc_co_u32_e32 v41, vcc, 0, v9, vcc
	v_add_co_u32_e32 v42, vcc, s16, v8
	v_add_u32_e32 v27, 0x16000000, v27
	s_nop 0
	v_addc_co_u32_e32 v43, vcc, 0, v9, vcc
	v_add_co_u32_e32 v44, vcc, s17, v8
	s_cmpk_lt_i32 s47, 0xfac0
	s_nop 0
	v_addc_co_u32_e32 v45, vcc, 0, v9, vcc
	v_add_co_u32_e32 v46, vcc, s18, v8
	s_mov_b32 s47, s0
	s_nop 0
	v_addc_co_u32_e32 v47, vcc, 0, v9, vcc
	v_add_co_u32_e32 v48, vcc, s19, v8
	s_waitcnt vmcnt(13)
	s_nop 0
	v_addc_co_u32_e32 v49, vcc, 0, v9, vcc
	s_waitcnt vmcnt(12)
	v_add_co_u32_e32 v50, vcc, s22, v8
	s_waitcnt vmcnt(11)
	s_nop 0
	v_addc_co_u32_e32 v51, vcc, 0, v9, vcc
	v_add_co_u32_e32 v52, vcc, s23, v8
	s_nop 1
	v_addc_co_u32_e32 v53, vcc, 0, v9, vcc
	v_add_co_u32_e32 v54, vcc, s24, v8
	s_nop 1
	v_addc_co_u32_e32 v55, vcc, 0, v9, vcc
	v_add_co_u32_e32 v56, vcc, s25, v8
	s_nop 1
	v_addc_co_u32_e32 v57, vcc, 0, v9, vcc
	v_add_co_u32_e32 v58, vcc, s26, v8
	s_nop 1
	v_addc_co_u32_e32 v59, vcc, 0, v9, vcc
	v_add_co_u32_e32 v60, vcc, s27, v8
	s_nop 1
	v_addc_co_u32_e32 v61, vcc, 0, v9, vcc
	v_add_co_u32_e32 v62, vcc, s28, v8
	s_nop 1
	v_addc_co_u32_e32 v63, vcc, 0, v9, vcc
	v_add_co_u32_e32 v64, vcc, s29, v8
	s_nop 1
	v_addc_co_u32_e32 v65, vcc, 0, v9, vcc
	s_waitcnt vmcnt(10)
	v_add_co_u32_e32 v66, vcc, s30, v8
	s_nop 1
	v_addc_co_u32_e32 v67, vcc, 0, v9, vcc
	v_add_co_u32_e32 v68, vcc, s31, v8
	s_nop 1
	v_addc_co_u32_e32 v69, vcc, 0, v9, vcc
	v_add_co_u32_e32 v70, vcc, s33, v8
	s_nop 1
	v_addc_co_u32_e32 v71, vcc, 0, v9, vcc
	v_add_co_u32_e32 v72, vcc, s34, v8
	s_nop 1
	v_addc_co_u32_e32 v73, vcc, 0, v9, vcc
	v_add_co_u32_e32 v74, vcc, s35, v8
	s_nop 1
	v_addc_co_u32_e32 v75, vcc, 0, v9, vcc
	v_add_co_u32_e32 v76, vcc, s36, v8
	s_nop 1
	v_addc_co_u32_e32 v77, vcc, 0, v9, vcc
	v_add_co_u32_e32 v78, vcc, s10, v8
	s_nop 1
	v_addc_co_u32_e32 v79, vcc, 0, v9, vcc
	v_add_co_u32_e32 v80, vcc, s37, v8
	s_nop 1
	v_addc_co_u32_e32 v81, vcc, 0, v9, vcc
	v_add_co_u32_e32 v82, vcc, s38, v8
	s_nop 1
	v_addc_co_u32_e32 v83, vcc, 0, v9, vcc
	v_add_co_u32_e32 v84, vcc, s39, v8
	s_nop 1
	v_addc_co_u32_e32 v85, vcc, 0, v9, vcc
	v_add_co_u32_e32 v86, vcc, s40, v8
	s_nop 1
	v_addc_co_u32_e32 v87, vcc, 0, v9, vcc
	v_add_co_u32_e32 v88, vcc, s41, v8
	s_nop 1
	v_addc_co_u32_e32 v89, vcc, 0, v9, vcc
	v_add_co_u32_e32 v90, vcc, s42, v8
	s_nop 1
	v_addc_co_u32_e32 v91, vcc, 0, v9, vcc
	v_add_co_u32_e32 v92, vcc, s43, v8
	s_nop 1
	v_addc_co_u32_e32 v93, vcc, 0, v9, vcc
	v_add_co_u32_e32 v94, vcc, s44, v8
	s_nop 1
	v_addc_co_u32_e32 v95, vcc, 0, v9, vcc
	v_add_co_u32_e32 v96, vcc, s45, v8
	s_nop 1
	v_addc_co_u32_e32 v97, vcc, 0, v9, vcc
	v_add_co_u32_e32 v8, vcc, s46, v8
	s_nop 1
	v_addc_co_u32_e32 v9, vcc, 0, v9, vcc
	global_load_dword v98, v[36:37], off offset:-4096
	global_load_dword v99, v[36:37], off
	global_load_dword v100, v[38:39], off offset:-4096
	global_load_dword v101, v[38:39], off
	global_load_dword v102, v[40:41], off offset:-4096
	global_load_dword v103, v[40:41], off
	global_load_dword v105, v[42:43], off offset:-4096
	global_load_dword v106, v[42:43], off
	global_load_dword v107, v[44:45], off offset:-4096
	global_load_dword v108, v[44:45], off
	global_load_dword v109, v[46:47], off offset:-4096
	global_load_dword v110, v[46:47], off
	global_load_dword v111, v[48:49], off offset:-4096
	global_load_dword v112, v[48:49], off
	global_load_dword v113, v[50:51], off offset:-4096
	global_load_dword v36, v[50:51], off
	global_load_dword v37, v[52:53], off offset:-4096
	global_load_dword v38, v[52:53], off
	global_load_dword v39, v[54:55], off offset:-4096
	global_load_dword v40, v[54:55], off
	global_load_dword v41, v[56:57], off offset:-4096
	global_load_dword v42, v[56:57], off
	global_load_dword v43, v[58:59], off offset:-4096
	global_load_dword v44, v[58:59], off
	global_load_dword v45, v[60:61], off offset:-4096
; #define LAS __attribute__((address_space(3)))
; __device__ __forceinline__ unsigned pk2(float lo, float hi) { f32x2 v = {lo, hi}; bf16x2_t b = __builtin_convertvector(v, bf16x2_t); return __builtin_bit_cast(unsigned, b); }
; __device__ __forceinline__ void transpose_item(const float* W, int K, int N, bf16_t* WT, const float* gk, int mode, LAS float* scr_, int item, int lane) {
;     ...
; #pragma unroll
;     for (int kp = 0; kp < 32; ++kp) { va[kp] = src[(size_t)(2 * kp) * N]; vb[kp] = src[(size_t)(2 * kp + 1) * N]; }
; #pragma unroll
;     for (int kp = 0; kp < 32; ++kp) {
;         float a = va[kp], b = vb[kp];
;         if (gk) { a *= gk[k0 + 2 * kp]; b *= gk[k0 + 2 * kp + 1]; }
;         scr[kp * 65 + lane] = pk2(a, b);
;     }
;     asm volatile("s_waitcnt lgkmcnt(0)" ::: "memory");
;     const int c = lane & 7;
; #pragma unroll
;     for (int j = 0; j < 8; ++j) { const int r = (lane >> 3) + 8 * j; const LAS unsigned* q = scr + (4 * c) * 65 + r;
;         u32x4 o; o.x = q[0]; o.y = q[65]; o.z = q[130]; o.w = q[195];
;         *(u32x4*)(WT + (size_t)(n0 + r) * K + k0 + 8 * c) = o; }
	global_load_dword v46, v[60:61], off
	global_load_dword v47, v[62:63], off offset:-4096
	global_load_dword v48, v[62:63], off
	global_load_dword v49, v[64:65], off offset:-4096
	global_load_dword v114, v[64:65], off
	global_load_dword v50, v[66:67], off offset:-4096
	global_load_dword v51, v[66:67], off
	global_load_dword v52, v[68:69], off offset:-4096
	global_load_dword v53, v[68:69], off
	global_load_dword v54, v[70:71], off offset:-4096
	global_load_dword v55, v[70:71], off
	global_load_dword v56, v[72:73], off offset:-4096
	global_load_dword v57, v[72:73], off
	global_load_dword v58, v[74:75], off offset:-4096
	global_load_dword v59, v[74:75], off
	global_load_dword v60, v[76:77], off offset:-4096
	global_load_dword v61, v[76:77], off
	global_load_dword v62, v[78:79], off offset:-4096
	global_load_dword v63, v[78:79], off
	global_load_dword v64, v[80:81], off offset:-4096
	global_load_dword v65, v[80:81], off
	global_load_dword v66, v[82:83], off offset:-4096
	global_load_dword v67, v[82:83], off
	global_load_dword v68, v[84:85], off offset:-4096
	global_load_dword v69, v[84:85], off
	global_load_dword v70, v[86:87], off offset:-4096
	global_load_dword v71, v[86:87], off
	global_load_dword v72, v[88:89], off offset:-4096
	global_load_dword v73, v[88:89], off
	global_load_dword v74, v[90:91], off offset:-4096
	global_load_dword v75, v[90:91], off
	global_load_dword v76, v[92:93], off offset:-4096
	global_load_dword v77, v[92:93], off
	global_load_dword v78, v[94:95], off offset:-4096
	global_load_dword v79, v[94:95], off
	global_load_dword v80, v[96:97], off offset:-4096
	global_load_dword v81, v[96:97], off
	global_load_dword v82, v[8:9], off
	s_waitcnt vmcnt(62)
	v_cvt_pk_bf16_f32 v8, v35, v98
	s_waitcnt vmcnt(60)
	v_cvt_pk_bf16_f32 v9, v99, v100
	s_waitcnt vmcnt(58)
	v_cvt_pk_bf16_f32 v35, v101, v102
	s_waitcnt vmcnt(56)
	v_cvt_pk_bf16_f32 v83, v103, v105
	s_waitcnt vmcnt(54)
	v_cvt_pk_bf16_f32 v84, v106, v107
	s_waitcnt vmcnt(52)
	v_cvt_pk_bf16_f32 v85, v108, v109
	s_waitcnt vmcnt(50)
	v_cvt_pk_bf16_f32 v86, v110, v111
	s_waitcnt vmcnt(48)
	v_cvt_pk_bf16_f32 v87, v112, v113
	s_waitcnt vmcnt(46)
	v_cvt_pk_bf16_f32 v36, v36, v37
	s_waitcnt vmcnt(44)
	v_cvt_pk_bf16_f32 v37, v38, v39
	s_waitcnt vmcnt(42)
	v_cvt_pk_bf16_f32 v38, v40, v41
	s_waitcnt vmcnt(40)
	v_cvt_pk_bf16_f32 v39, v42, v43
	s_waitcnt vmcnt(38)
	v_cvt_pk_bf16_f32 v40, v44, v45
	s_waitcnt vmcnt(36)
	v_cvt_pk_bf16_f32 v41, v46, v47
	s_waitcnt vmcnt(34)
	v_cvt_pk_bf16_f32 v42, v48, v49
	s_waitcnt vmcnt(32)
	v_cvt_pk_bf16_f32 v43, v114, v50
	s_waitcnt vmcnt(30)
	v_cvt_pk_bf16_f32 v44, v51, v52
	s_waitcnt vmcnt(28)
	v_cvt_pk_bf16_f32 v45, v53, v54
	s_waitcnt vmcnt(26)
	v_cvt_pk_bf16_f32 v46, v55, v56
	s_waitcnt vmcnt(24)
	v_cvt_pk_bf16_f32 v47, v57, v58
	s_waitcnt vmcnt(22)
	v_cvt_pk_bf16_f32 v48, v59, v60
	s_waitcnt vmcnt(20)
	v_cvt_pk_bf16_f32 v49, v61, v62
	s_waitcnt vmcnt(18)
	v_cvt_pk_bf16_f32 v50, v63, v64
	s_waitcnt vmcnt(16)
	v_cvt_pk_bf16_f32 v51, v65, v66
	s_waitcnt vmcnt(14)
	v_cvt_pk_bf16_f32 v52, v67, v68
	s_waitcnt vmcnt(12)
	v_cvt_pk_bf16_f32 v53, v69, v70
	s_waitcnt vmcnt(10)
	v_cvt_pk_bf16_f32 v54, v71, v72
	s_waitcnt vmcnt(8)
	v_cvt_pk_bf16_f32 v55, v73, v74
	s_waitcnt vmcnt(6)
	v_cvt_pk_bf16_f32 v56, v75, v76
	s_waitcnt vmcnt(4)
	v_cvt_pk_bf16_f32 v57, v77, v78
	s_waitcnt vmcnt(2)
	v_cvt_pk_bf16_f32 v58, v79, v80
	s_waitcnt vmcnt(0)
	v_cvt_pk_bf16_f32 v59, v81, v82
	ds_write2_b32 v3, v8, v9 offset1:65
	ds_write2_b32 v3, v35, v83 offset0:130 offset1:195
	ds_write2_b32 v28, v84, v85 offset0:4 offset1:69
	ds_write2_b32 v28, v86, v87 offset0:134 offset1:199
	ds_write2_b32 v29, v36, v37 offset0:8 offset1:73
	ds_write2_b32 v29, v38, v39 offset0:138 offset1:203
	ds_write2_b32 v30, v40, v41 offset0:12 offset1:77
	ds_write2_b32 v30, v42, v43 offset0:142 offset1:207
	ds_write2_b32 v31, v44, v45 offset0:16 offset1:81
	ds_write2_b32 v31, v46, v47 offset0:146 offset1:211
	ds_write2_b32 v32, v48, v49 offset0:20 offset1:85
	ds_write2_b32 v32, v50, v51 offset0:150 offset1:215
	ds_write2_b32 v33, v52, v53 offset0:24 offset1:89
	ds_write2_b32 v33, v54, v55 offset0:154 offset1:219
	ds_write2_b32 v34, v56, v57 offset0:28 offset1:93
	ds_write2_b32 v34, v58, v59 offset0:158 offset1:223
	s_waitcnt lgkmcnt(0)
	ds_read2_b32 v[36:37], v26 offset0:65 offset1:73
	ds_read2_b32 v[8:9], v26 offset0:130 offset1:138
	ds_read2_b32 v[38:39], v26 offset0:195 offset1:203
	ds_read2_b32 v[56:57], v26 offset1:8
	ds_read2_b32 v[60:61], v26 offset0:16 offset1:24
	ds_read2_b32 v[40:41], v26 offset0:81 offset1:89
	ds_read2_b32 v[62:63], v26 offset0:146 offset1:154
	ds_read2_b32 v[42:43], v26 offset0:211 offset1:219
	ds_read2_b32 v[44:45], v26 offset0:97 offset1:105
	ds_read2_b32 v[64:65], v26 offset0:162 offset1:170
	ds_read2_b32 v[46:47], v26 offset0:227 offset1:235
	ds_read2_b32 v[66:67], v26 offset0:32 offset1:40
	ds_read2_b32 v[68:69], v26 offset0:48 offset1:56
	ds_read2_b32 v[48:49], v26 offset0:113 offset1:121
	ds_read2_b32 v[70:71], v26 offset0:178 offset1:186
	ds_read2_b32 v[50:51], v26 offset0:243 offset1:251
	s_waitcnt lgkmcnt(12)
	v_mov_b32_e32 v52, v56
	v_mov_b32_e32 v53, v36
	v_mov_b32_e32 v54, v8
	v_mov_b32_e32 v55, v38
	v_mov_b32_e32 v36, v57
	v_mov_b32_e32 v38, v9
	s_waitcnt lgkmcnt(11)
	v_mov_b32_e32 v56, v60
	s_waitcnt lgkmcnt(10)
	v_mov_b32_e32 v57, v40
	s_waitcnt lgkmcnt(9)
	v_mov_b32_e32 v58, v62
	s_waitcnt lgkmcnt(8)
	v_mov_b32_e32 v59, v42
	v_mov_b32_e32 v40, v61
	v_mov_b32_e32 v42, v63
	s_waitcnt lgkmcnt(4)
	v_mov_b32_e32 v60, v66
	v_mov_b32_e32 v61, v44
	v_mov_b32_e32 v62, v64
	v_mov_b32_e32 v63, v46
	v_mov_b32_e32 v44, v67
	v_mov_b32_e32 v46, v65
	s_waitcnt lgkmcnt(3)
	v_mov_b32_e32 v64, v68
	s_waitcnt lgkmcnt(2)
	v_mov_b32_e32 v65, v48
	s_waitcnt lgkmcnt(1)
	v_mov_b32_e32 v66, v70
	s_waitcnt lgkmcnt(0)
	v_mov_b32_e32 v67, v50
	v_mov_b32_e32 v48, v69
	v_mov_b32_e32 v50, v71
	global_store_dwordx4 v[10:11], v[52:55], off
	global_store_dwordx4 v[12:13], v[36:39], off
	global_store_dwordx4 v[14:15], v[56:59], off
	global_store_dwordx4 v[16:17], v[40:43], off
	global_store_dwordx4 v[18:19], v[60:63], off
	global_store_dwordx4 v[20:21], v[44:47], off
	global_store_dwordx4 v[22:23], v[64:67], off
	global_store_dwordx4 v[24:25], v[48:51], off
	s_waitcnt lgkmcnt(0)
	s_cbranch_scc1 .LBB0_730

; #define PIN(i) ((const float*)ldq_(L, (i)))
; __device__ __forceinline__ void prep(const Params& p, LAS unsigned char* L, int wv, int vb, int nvb, int l, int mask) {
;     ...
;         for (int m0 = 4 * gw; m0 < MT; m0 += 4 * NGW) {
;             const float* xr = (m0 < MP) ? PIN(I_XP) + (size_t)m0 * DM : PIN(I_XS) + (size_t)(m0 - MP) * DM;
.LBB0_734:
	s_cmp_gt_i32 s8, 0xffff
	s_mov_b64 s[24:25], -1
	s_cbranch_scc0 .LBB0_736
	v_mov_b32_e32 v2, 0
	s_add_i32 s10, s8, 0xffff0000
	v_add_u32_e32 v2, 0, v2
	v_add_u32_e32 v2, 0x20108, v2
	s_nop 0
	s_lshl_b64 s[18:19], s[10:11], 12
	s_mov_b32 s10, s8
	s_mov_b64 s[24:25], 0
	s_waitcnt lgkmcnt(0)
	v_readlane_b32 s22, v251, 2
	v_readlane_b32 s23, v251, 3
	s_add_u32 s22, s22, s18
	s_addc_u32 s23, s23, s19
	s_mov_b64 s[18:19], s[10:11]
.LBB0_736:
	s_andn2_b64 vcc, exec, s[24:25]
	s_cbranch_vccnz .LBB0_738
	v_mov_b32_e32 v2, 0
	s_nop 0
	v_add_u32_e32 v2, 0, v2
	v_add_u32_e32 v2, 0x20100, v2
	s_nop 0
	s_waitcnt lgkmcnt(0)
	v_readlane_b32 s18, v251, 0
	v_readlane_b32 s10, v251, 1
	s_add_u32 s22, s18, s12
	s_addc_u32 s23, s10, s13
	s_mov_b64 s[18:19], s[8:9]

; __device__ __forceinline__ unsigned xb_ld(unsigned* p)              { return __hip_atomic_load(p, __ATOMIC_RELAXED, __HIP_MEMORY_SCOPE_AGENT); }
; __device__ __forceinline__ void xcd_barrier_complete(unsigned* bar, unsigned x, unsigned& nloc, unsigned& nx) {
;     const unsigned G = gridDim.x * gridDim.y * gridDim.z;
;     unsigned sum, cnt, mine, sp = 0u;
;     for (;;) {
;         sum = 0u; cnt = 0u; mine = 0u;
; #pragma unroll
;         for (unsigned j = 0; j < 16; ++j) { const unsigned c = xb_ld(&bar[XB_XCNT(j)]); sum += c; cnt += (c > 0u) ? 1u : 0u; mine = (j == x) ? c : mine; }
;         if (sum == G) break;
; __device__ __forceinline__ void xcd_barrier(const XcdBarrier& b, bool t0) {
;     asm volatile("s_waitcnt vmcnt(0)" ::: "memory");
;     __syncthreads();
;     if (t0) {
;         unsigned* bar = b.bar;
;         __builtin_amdgcn_s_waitcnt(0);
;         unsigned nloc = b.st[0], nx = b.st[1];
;         if (nloc == 0u) { xcd_barrier_complete(bar, b.x, nloc, nx); b.st[0] = nloc; b.st[1] = nx; }
.LBB0_780:
	s_waitcnt lgkmcnt(0)
	v_mov_b32_e32 v0, v161
	v_mov_b32_e32 v2, v183
	v_add_u32_e32 v0, 0, v0
	v_add_u32_e32 v0, 0x201c0, v0
	s_nop 0
	s_getreg_b32 s8, hwreg(HW_REG_XCC_ID, 0, 4)
	s_waitcnt vmcnt(0)
	s_waitcnt lgkmcnt(0)
	v_readlane_b32 s7, v251, 49
	v_readlane_b32 s6, v251, 48
	v_cmp_eq_u32_e32 vcc, 0, v2
	s_barrier
	s_and_saveexec_b64 s[4:5], vcc
	s_cbranch_execz .LBB0_832
	v_readlane_b32 s9, v250, 17
	s_waitcnt vmcnt(0) expcnt(0) lgkmcnt(0)
	s_and_b32 s16, s8, 15
	v_mov_b32_e32 v0, s9
	ds_read_b32 v2, v0
	v_readlane_b32 s9, v250, 18
	s_waitcnt lgkmcnt(0)
	v_cmp_ne_u32_e32 vcc, 0, v2
	v_mov_b32_e32 v0, s9
	ds_read_b32 v0, v0
	s_cbranch_vccnz .LBB0_796
	s_add_u32 s8, s6, 0x28680200
	s_addc_u32 s9, s7, 0
	s_add_u32 s10, s6, 0x28680400
	s_addc_u32 s11, s7, 0
	s_add_u32 s12, s6, 0x28680500
	s_addc_u32 s13, s7, 0
	s_add_u32 s14, s6, 0x28680600
	s_addc_u32 s15, s7, 0
	s_add_u32 s18, s6, 0x28680700
	s_addc_u32 s19, s7, 0
	s_add_u32 s34, s6, 0x28680800
	s_addc_u32 s35, s7, 0
	s_add_u32 s40, s6, 0x28680900
	s_addc_u32 s41, s7, 0
	s_add_u32 s42, s6, 0x28680a00
	s_addc_u32 s43, s7, 0
	s_add_u32 s44, s6, 0x28680b00
	s_addc_u32 s45, s7, 0
	s_add_u32 s48, s6, 0x28680c00
	s_addc_u32 s49, s7, 0
	s_add_u32 s50, s6, 0x28680d00
	s_addc_u32 s51, s7, 0
	s_add_u32 s52, s6, 0x28680e00
	s_addc_u32 s53, s7, 0
	s_add_u32 s56, s6, 0x28680f00
	s_addc_u32 s57, s7, 0
	s_add_u32 s60, s6, 0x28681000
	s_addc_u32 s61, s7, 0
	s_add_u32 s62, s6, 0x28681100
	s_addc_u32 s63, s7, 0
	s_add_u32 s64, s6, 0x28681200
	s_addc_u32 s65, s7, 0
	s_add_u32 s66, s6, 0x28681300
	s_addc_u32 s67, s7, 0
	s_mov_b32 s21, 1
	s_branch .LBB0_784

; __device__ __forceinline__ int tid_of(int wv) { return wv * 64 + (int)__builtin_amdgcn_mbcnt_hi(~0u, __builtin_amdgcn_mbcnt_lo(~0u, 0u)); }
; #define LAS __attribute__((address_space(3)))
; #define PIN(i) ((const float*)ldq_(L, (i)))
; #define PREP_CONV(bit, SRC, Kd, Nd, DST, GK, MODE) if (mask & (bit)) { for (int it = gw; it < ((Kd) / 64) * ((Nd) / 64); it += NGW) transpose_item((SRC), (Kd), (Nd), (bf16_t*)(wl + (DST)), (GK), (MODE), scr, it, lane); }
; __device__ __forceinline__ void prep(const Params& p, LAS unsigned char* L, int wv, int vb, int nvb, int l, int mask) {
;     int tid_ = tid_of(wv); asm volatile("" : "+v"(tid_));
;     const int tid = tid_, lane = tid & 63, wave = __builtin_amdgcn_readfirstlane(tid >> 6);
;     const int gw = vb * 8 + wave, NGW = nvb * 8; const int gt = vb * 512 + tid, NGT = nvb * 512;
;     LAS float* scr = (LAS float*)(L + wave * 16384);
;     unsigned char* ws = PWS; unsigned char* wl = ws + WS_W + (size_t)l * WL_STRIDE;
;     ...
;     PREP_CONV(PM_FFA_IN, PIN(I_WFFA_IN) + (size_t)l * DM * NFF2, DM, NFF2, WL_FFA_IN, PIN(I_NFFA) + l * DM, 1)
;     PREP_CONV(PM_FFA_OUT, PIN(I_WFFA_OUT) + (size_t)l * DFF * DM, DFF, DM, WL_FFA_OUT, nullptr, 0)
;     PREP_CONV(PM_WIN, PIN(I_WIN) + (size_t)l * DM * NIN, DM, NIN, WL_IN, PIN(I_NMIX) + l * DM, 0)
.LBB0_868:
	v_readlane_b32 s4, v250, 31
	v_readlane_b32 s5, v250, 32
	s_and_b64 s[4:5], s[4:5], exec
	s_cselect_b32 s6, 0, 2
	s_mov_b32 s35, s2
	s_mov_b32 s4, s20
	s_cmpk_eq_i32 s4, 0x100
	s_cselect_b64 s[4:5], -1, 0
	s_cmp_gt_i32 s35, 31
	s_cselect_b64 s[8:9], -1, 0
	s_and_b64 s[4:5], s[4:5], s[8:9]
	s_cmp_lt_i32 s6, 2
	s_cselect_b64 s[8:9], -1, 0
	s_and_b64 s[4:5], s[4:5], s[8:9]
	s_andn2_b64 vcc, exec, s[4:5]
	s_cbranch_vccnz .LBB0_1127
	v_mov_b32_e32 v75, v183
	s_waitcnt lgkmcnt(0)
	v_mov_b32_e32 v1, v161
	s_sub_i32 s40, s35, 32
	v_add_u32_e32 v1, 0, v1
	v_add_u32_e32 v1, 0x201c0, v1
	s_nop 0
	v_readfirstlane_b32 s4, v75
	s_ashr_i32 s4, s4, 6
	s_lshl_b32 s5, s40, 3
	s_add_i32 s41, s4, s5
	s_lshl_b32 s4, s4, 14
	s_add_i32 s14, s4, 0
	s_waitcnt lgkmcnt(0)
	v_readlane_b32 s34, v251, 48
	s_ashr_i32 s7, s6, 31
	s_mul_i32 s5, s6, 0x2900000
	v_and_b32_e32 v0, 63, v75
	v_readlane_b32 s16, v251, 49
	s_mul_hi_i32 s4, s6, 0x2900000
	s_add_u32 s8, s34, s5
	s_addc_u32 s9, s16, s4
	v_and_b32_e32 v74, 7, v75
	v_lshrrev_b32_e32 v76, 3, v0
	s_cmpk_gt_i32 s41, 0x13f
	v_lshl_add_u32 v77, v0, 2, s14
	v_mul_u32_u24_e32 v1, 0x410, v74
	v_lshlrev_b32_e32 v2, 4, v74
	v_lshlrev_b32_e32 v78, 2, v76
	s_cbranch_scc1 .LBB0_936
	s_lshl_b32 s4, s6, 10
	v_mov_b32_e32 v3, v161
	s_ashr_i32 s5, s4, 31
	v_lshl_add_u64 v[4:5], s[8:9], 0, v[2:3]
	s_mov_b64 s[10:11], 0x1080000
	v_lshl_add_u64 v[4:5], v[4:5], 0, s[10:11]
	v_add3_u32 v3, s14, v1, v78
	s_lshl_b32 s15, s41, 6
	s_lshl_b64 s[10:11], s[4:5], 2
	v_lshlrev_b32_e32 v160, 2, v0
	s_mov_b32 s29, s41
	s_branch .LBB0_872

; #define LAS __attribute__((address_space(3)))
; #define PIN(i) ((const float*)ldq_(L, (i)))
; #define PREP_CONV(bit, SRC, Kd, Nd, DST, GK, MODE) if (mask & (bit)) { for (int it = gw; it < ((Kd) / 64) * ((Nd) / 64); it += NGW) transpose_item((SRC), (Kd), (Nd), (bf16_t*)(wl + (DST)), (GK), (MODE), scr, it, lane); }
; __device__ __forceinline__ void transpose_item(const float* W, int K, int N, bf16_t* WT, const float* gk, int mode, LAS float* scr_, int item, int lane) {
;     LAS unsigned* scr = (LAS unsigned*)scr_;
;     const int nblk = N / 64, kb = item / nblk, nb = item % nblk, k0 = 64 * kb, n0 = 64 * nb;
;     const int sc = (mode == 1) ? (((n0 >> 7) & 1) * DFF + (n0 >> 8) * 128 + (n0 & 127)) : n0;
;     const float* src = W + (size_t)k0 * N + sc + lane;
;     float va[32], vb[32];
; #pragma unroll
;     for (int kp = 0; kp < 32; ++kp) { va[kp] = src[(size_t)(2 * kp) * N]; vb[kp] = src[(size_t)(2 * kp + 1) * N]; }
; #pragma unroll
;     for (int kp = 0; kp < 32; ++kp) {
;         float a = va[kp], b = vb[kp];
;         if (gk) { a *= gk[k0 + 2 * kp]; b *= gk[k0 + 2 * kp + 1]; }
; __device__ __forceinline__ void prep(const Params& p, LAS unsigned char* L, int wv, int vb, int nvb, int l, int mask) {
;     ...
;     PREP_CONV(PM_WIN, PIN(I_WIN) + (size_t)l * DM * NIN, DM, NIN, WL_IN, PIN(I_NMIX) + l * DM, 0)
.LBB0_872:
	v_mov_b32_e32 v6, v161
	s_mul_i32 s12, s6, 0x500000
	v_add_u32_e32 v6, 0, v6
	v_add_u32_e32 v6, 0x20158, v6
	ds_read_b64 v[6:7], v6
	s_mov_b64 s[30:31], -1
	s_waitcnt lgkmcnt(0)
	v_readfirstlane_b32 s5, v6
	v_mov_b32_e32 v6, v161
	v_readfirstlane_b32 s4, v7
	v_add_u32_e32 v6, 0, v6
	v_add_u32_e32 v6, 0x20150, v6
	s_nop 0
	s_add_u32 s13, s5, s12
	s_mul_hi_i32 s5, s6, 0x500000
	s_addc_u32 s21, s4, s5
	s_mul_hi_i32 s12, s29, 0x66666667
	s_waitcnt lgkmcnt(0)
	v_readlane_b32 s4, v251, 20
	v_readlane_b32 s5, v251, 21
	s_add_u32 s42, s4, s10
	s_addc_u32 s43, s5, s11
	s_lshr_b32 s18, s12, 31
	s_ashr_i32 s12, s12, 3
	s_add_i32 s24, s12, s18
	s_lshl_b32 s18, s24, 6
	s_mul_i32 s12, s24, 0xfffffb00
	s_add_i32 s12, s15, s12
	s_ashr_i32 s19, s18, 31
	s_mul_i32 s24, s24, 0x50000
	s_mul_hi_i32 s25, s18, 0x1400
	s_add_u32 s26, s13, s24
	s_addc_u32 s21, s21, s25
	s_ashr_i32 s13, s12, 31
	s_lshl_b64 s[24:25], s[12:13], 2
	s_add_u32 s24, s26, s24
	s_addc_u32 s25, s21, s25
	v_lshl_add_u64 v[70:71], s[24:25], 0, v[160:161]
	s_movk_i32 s13, 0x1000
	v_add_co_u32_e32 v6, vcc, s13, v70
	s_movk_i32 s13, 0x3000
	s_nop 0
	v_addc_co_u32_e32 v7, vcc, 0, v71, vcc
	global_load_dword v67, v[6:7], off offset:1024
	v_add_co_u32_e32 v6, vcc, s79, v70
	global_load_dword v66, v160, s[24:25]
	s_nop 0
	v_addc_co_u32_e32 v7, vcc, 0, v71, vcc
	global_load_dword v68, v[6:7], off offset:2048
	v_add_co_u32_e32 v6, vcc, s13, v70
	s_movk_i32 s13, 0x5000
	s_nop 0
	v_addc_co_u32_e32 v7, vcc, 0, v71, vcc
	global_load_dword v69, v[6:7], off offset:3072
	v_add_co_u32_e32 v6, vcc, s13, v70
	s_movk_i32 s13, 0x7000
	s_nop 0
	v_addc_co_u32_e32 v7, vcc, 0, v71, vcc
	global_load_dword v58, v[6:7], off
	v_add_co_u32_e32 v6, vcc, s80, v70
	s_cmp_lg_u64 s[4:5], 0
	s_nop 0
	v_addc_co_u32_e32 v7, vcc, 0, v71, vcc
	global_load_dword v59, v[6:7], off offset:1024
	v_add_co_u32_e32 v6, vcc, s13, v70
	s_mov_b32 s13, 0xb000
	s_nop 0
	v_addc_co_u32_e32 v7, vcc, 0, v71, vcc
	global_load_dword v64, v[6:7], off offset:2048
	v_add_co_u32_e32 v6, vcc, s70, v70
	s_cselect_b64 s[24:25], -1, 0
	s_nop 0
	v_addc_co_u32_e32 v7, vcc, 0, v71, vcc
	global_load_dword v65, v[6:7], off offset:3072
	v_add_co_u32_e32 v6, vcc, s71, v70
	s_cmp_eq_u64 s[4:5], 0
	s_nop 0
	v_addc_co_u32_e32 v7, vcc, 0, v71, vcc
	global_load_dword v60, v[6:7], off
	v_add_co_u32_e32 v6, vcc, s13, v70
	s_mov_b32 s13, 0xd000
	s_nop 0
	v_addc_co_u32_e32 v7, vcc, 0, v71, vcc
	global_load_dword v61, v[6:7], off offset:1024
	v_add_co_u32_e32 v6, vcc, s91, v70
	s_nop 1
	v_addc_co_u32_e32 v7, vcc, 0, v71, vcc
	global_load_dword v62, v[6:7], off offset:2048
	v_add_co_u32_e32 v6, vcc, s13, v70
	s_mov_b32 s13, 0xf000
	s_nop 0
	v_addc_co_u32_e32 v7, vcc, 0, v71, vcc
	global_load_dword v63, v[6:7], off offset:3072
	v_add_co_u32_e32 v6, vcc, s13, v70
	s_mov_b32 s13, 0x11000
	s_nop 0
	v_addc_co_u32_e32 v7, vcc, 0, v71, vcc
	global_load_dword v50, v[6:7], off
	v_add_co_u32_e32 v6, vcc, s37, v70
	s_nop 1
	v_addc_co_u32_e32 v7, vcc, 0, v71, vcc
	global_load_dword v51, v[6:7], off offset:1024
	v_add_co_u32_e32 v6, vcc, s13, v70
	s_mov_b32 s13, 0x15000
	s_nop 0
	v_addc_co_u32_e32 v7, vcc, 0, v71, vcc
	global_load_dword v56, v[6:7], off offset:2048
	v_add_co_u32_e32 v6, vcc, s94, v70
	s_nop 1
	v_addc_co_u32_e32 v7, vcc, 0, v71, vcc
	global_load_dword v57, v[6:7], off offset:3072
	v_add_co_u32_e32 v6, vcc, s46, v70
	s_nop 1
	v_addc_co_u32_e32 v7, vcc, 0, v71, vcc
	global_load_dword v52, v[6:7], off
	v_add_co_u32_e32 v6, vcc, s13, v70
	s_mov_b32 s13, 0x17000
	s_nop 0
	v_addc_co_u32_e32 v7, vcc, 0, v71, vcc
	global_load_dword v53, v[6:7], off offset:1024
	v_add_co_u32_e32 v6, vcc, s47, v70
	s_nop 1
	v_addc_co_u32_e32 v7, vcc, 0, v71, vcc
	global_load_dword v54, v[6:7], off offset:2048
	v_add_co_u32_e32 v6, vcc, s13, v70
	s_mov_b32 s13, 0x19000
	s_nop 0
	v_addc_co_u32_e32 v7, vcc, 0, v71, vcc
	global_load_dword v55, v[6:7], off offset:3072
	v_add_co_u32_e32 v6, vcc, s13, v70
	s_mov_b32 s13, 0x1b000
	s_nop 0
	v_addc_co_u32_e32 v7, vcc, 0, v71, vcc
	global_load_dword v42, v[6:7], off
	v_add_co_u32_e32 v6, vcc, s81, v70
	s_nop 1
	v_addc_co_u32_e32 v7, vcc, 0, v71, vcc
	global_load_dword v43, v[6:7], off offset:1024
	v_add_co_u32_e32 v6, vcc, s13, v70
	s_mov_b32 s13, 0x1f000
	s_nop 0
	v_addc_co_u32_e32 v7, vcc, 0, v71, vcc
	global_load_dword v48, v[6:7], off offset:2048
	v_add_co_u32_e32 v6, vcc, s83, v70
	s_nop 1
	v_addc_co_u32_e32 v7, vcc, 0, v71, vcc
	global_load_dword v49, v[6:7], off offset:3072
	v_add_co_u32_e32 v6, vcc, s27, v70
	s_nop 1
	v_addc_co_u32_e32 v7, vcc, 0, v71, vcc
	global_load_dword v44, v[6:7], off
	v_add_co_u32_e32 v6, vcc, s13, v70
	s_mov_b32 s13, 0x21000
	s_nop 0
	v_addc_co_u32_e32 v7, vcc, 0, v71, vcc
	global_load_dword v45, v[6:7], off offset:1024
	v_add_co_u32_e32 v6, vcc, s50, v70
	s_nop 1
	v_addc_co_u32_e32 v7, vcc, 0, v71, vcc
	global_load_dword v46, v[6:7], off offset:2048
	v_add_co_u32_e32 v6, vcc, s13, v70
	s_mov_b32 s13, 0x23000
	s_nop 0
	v_addc_co_u32_e32 v7, vcc, 0, v71, vcc
	global_load_dword v47, v[6:7], off offset:3072
	v_add_co_u32_e32 v6, vcc, s13, v70
	s_mov_b32 s13, 0x25000
	s_nop 0
	v_addc_co_u32_e32 v7, vcc, 0, v71, vcc
	global_load_dword v34, v[6:7], off
	v_add_co_u32_e32 v6, vcc, s0, v70
	s_nop 1
; __device__ __forceinline__ void transpose_item(const float* W, int K, int N, bf16_t* WT, const float* gk, int mode, LAS float* scr_, int item, int lane) {
;     ...
; #pragma unroll
;     for (int kp = 0; kp < 32; ++kp) { va[kp] = src[(size_t)(2 * kp) * N]; vb[kp] = src[(size_t)(2 * kp + 1) * N]; }
; #pragma unroll
;     for (int kp = 0; kp < 32; ++kp) {
;         float a = va[kp], b = vb[kp];
;         if (gk) { a *= gk[k0 + 2 * kp]; b *= gk[k0 + 2 * kp + 1]; }
	v_addc_co_u32_e32 v7, vcc, 0, v71, vcc
	global_load_dword v35, v[6:7], off offset:1024
	v_add_co_u32_e32 v6, vcc, s13, v70
	s_mov_b32 s13, 0x29000
	s_nop 0
	v_addc_co_u32_e32 v7, vcc, 0, v71, vcc
	global_load_dword v40, v[6:7], off offset:2048
	v_add_co_u32_e32 v6, vcc, s73, v70
	s_nop 1
	v_addc_co_u32_e32 v7, vcc, 0, v71, vcc
	global_load_dword v41, v[6:7], off offset:3072
	v_add_co_u32_e32 v6, vcc, s1, v70
	s_nop 1
	v_addc_co_u32_e32 v7, vcc, 0, v71, vcc
	global_load_dword v36, v[6:7], off
	v_add_co_u32_e32 v6, vcc, s13, v70
	s_mov_b32 s13, 0x2b000
	s_nop 0
	v_addc_co_u32_e32 v7, vcc, 0, v71, vcc
	global_load_dword v37, v[6:7], off offset:1024
	v_add_co_u32_e32 v6, vcc, s72, v70
	s_nop 1
	v_addc_co_u32_e32 v7, vcc, 0, v71, vcc
	global_load_dword v38, v[6:7], off offset:2048
	v_add_co_u32_e32 v6, vcc, s13, v70
	s_mov_b32 s13, 0x2d000
	s_nop 0
	v_addc_co_u32_e32 v7, vcc, 0, v71, vcc
	global_load_dword v39, v[6:7], off offset:3072
	v_add_co_u32_e32 v6, vcc, s13, v70
	s_mov_b32 s13, 0x2f000
	s_nop 0
	v_addc_co_u32_e32 v7, vcc, 0, v71, vcc
	global_load_dword v26, v[6:7], off
	v_add_co_u32_e32 v6, vcc, s33, v70
	s_nop 1
	v_addc_co_u32_e32 v7, vcc, 0, v71, vcc
	global_load_dword v27, v[6:7], off offset:1024
	v_add_co_u32_e32 v6, vcc, s13, v70
	s_mov_b32 s13, 0x33000
	s_nop 0
	v_addc_co_u32_e32 v7, vcc, 0, v71, vcc
	global_load_dword v32, v[6:7], off offset:2048
	v_add_co_u32_e32 v6, vcc, s22, v70
	s_nop 1
	v_addc_co_u32_e32 v7, vcc, 0, v71, vcc
	global_load_dword v33, v[6:7], off offset:3072
	v_add_co_u32_e32 v6, vcc, s38, v70
	s_nop 1
	v_addc_co_u32_e32 v7, vcc, 0, v71, vcc
	global_load_dword v28, v[6:7], off
	v_add_co_u32_e32 v6, vcc, s13, v70
	s_mov_b32 s13, 0x35000
	s_nop 0
	v_addc_co_u32_e32 v7, vcc, 0, v71, vcc
	global_load_dword v29, v[6:7], off offset:1024
	v_add_co_u32_e32 v6, vcc, s39, v70
	s_nop 1
	v_addc_co_u32_e32 v7, vcc, 0, v71, vcc
	global_load_dword v30, v[6:7], off offset:2048
	v_add_co_u32_e32 v6, vcc, s13, v70
	s_mov_b32 s13, 0x37000
	s_nop 0
	v_addc_co_u32_e32 v7, vcc, 0, v71, vcc
	global_load_dword v31, v[6:7], off offset:3072
	v_add_co_u32_e32 v6, vcc, s13, v70
	s_mov_b32 s13, 0x39000
	s_nop 0
	v_addc_co_u32_e32 v7, vcc, 0, v71, vcc
	global_load_dword v18, v[6:7], off
	v_add_co_u32_e32 v6, vcc, s69, v70
	s_nop 1
	v_addc_co_u32_e32 v7, vcc, 0, v71, vcc
	global_load_dword v19, v[6:7], off offset:1024
	v_add_co_u32_e32 v6, vcc, s13, v70
	s_mov_b32 s13, 0x3d000
	s_nop 0
	v_addc_co_u32_e32 v7, vcc, 0, v71, vcc
	global_load_dword v24, v[6:7], off offset:2048
	v_add_co_u32_e32 v6, vcc, s87, v70
	s_nop 1
	v_addc_co_u32_e32 v7, vcc, 0, v71, vcc
	global_load_dword v25, v[6:7], off offset:3072
	v_add_co_u32_e32 v6, vcc, s90, v70
	s_nop 1
	v_addc_co_u32_e32 v7, vcc, 0, v71, vcc
	global_load_dword v20, v[6:7], off
	v_add_co_u32_e32 v6, vcc, s13, v70
	s_mov_b32 s13, 0x41000
	s_nop 0
	v_addc_co_u32_e32 v7, vcc, 0, v71, vcc
	global_load_dword v21, v[6:7], off offset:1024
	v_add_co_u32_e32 v6, vcc, s51, v70
	s_nop 1
	v_addc_co_u32_e32 v7, vcc, 0, v71, vcc
	global_load_dword v22, v[6:7], off offset:2048
	v_add_co_u32_e32 v6, vcc, s52, v70
	s_nop 1
	v_addc_co_u32_e32 v7, vcc, 0, v71, vcc
	global_load_dword v23, v[6:7], off offset:3072
	v_add_co_u32_e32 v6, vcc, s13, v70
	s_mov_b32 s13, 0x43000
	s_nop 0
	v_addc_co_u32_e32 v7, vcc, 0, v71, vcc
	global_load_dword v8, v[6:7], off
	v_add_co_u32_e32 v6, vcc, s93, v70
	s_nop 1
	v_addc_co_u32_e32 v7, vcc, 0, v71, vcc
	global_load_dword v9, v[6:7], off offset:1024
	v_add_co_u32_e32 v6, vcc, s13, v70
	s_mov_b32 s13, 0x44000
	s_nop 0
	v_addc_co_u32_e32 v7, vcc, 0, v71, vcc
	global_load_dword v14, v[6:7], off offset:2048
	v_add_co_u32_e32 v6, vcc, s13, v70
	s_mov_b32 s13, 0x46000
	s_nop 0
	v_addc_co_u32_e32 v7, vcc, 0, v71, vcc
	global_load_dword v15, v[6:7], off offset:3072
	v_add_co_u32_e32 v6, vcc, s13, v70
	s_mov_b32 s13, 0x47000
	s_nop 0
	v_addc_co_u32_e32 v7, vcc, 0, v71, vcc
	global_load_dword v10, v[6:7], off
	v_add_co_u32_e32 v6, vcc, s13, v70
	s_mov_b32 s13, 0x48000
	s_nop 0
	v_addc_co_u32_e32 v7, vcc, 0, v71, vcc
	global_load_dword v11, v[6:7], off offset:1024
	v_add_co_u32_e32 v6, vcc, s13, v70
	s_mov_b32 s13, 0x49000
	s_nop 0
	v_addc_co_u32_e32 v7, vcc, 0, v71, vcc
	global_load_dword v16, v[6:7], off offset:2048
	v_add_co_u32_e32 v6, vcc, s13, v70
	s_mov_b32 s13, 0x4b000
	s_nop 0
	v_addc_co_u32_e32 v7, vcc, 0, v71, vcc
	global_load_dword v17, v[6:7], off offset:3072
	v_add_co_u32_e32 v6, vcc, s13, v70
	s_mov_b32 s13, 0x4c000
	s_nop 0
	v_addc_co_u32_e32 v7, vcc, 0, v71, vcc
	v_add_co_u32_e32 v12, vcc, s13, v70
	global_load_dword v6, v[6:7], off
	s_nop 0
	v_addc_co_u32_e32 v13, vcc, 0, v71, vcc
	global_load_dword v7, v[12:13], off offset:1024
	v_add_co_u32_e32 v12, vcc, 0x4d000, v70
	s_nop 1
	v_addc_co_u32_e32 v13, vcc, 0, v71, vcc
	v_add_co_u32_e32 v70, vcc, 0x4e000, v70
	global_load_dword v12, v[12:13], off offset:2048
	s_nop 0
	v_addc_co_u32_e32 v71, vcc, 0, v71, vcc
	global_load_dword v13, v[70:71], off offset:3072
	s_cbranch_scc1 .LBB0_874
	s_lshl_b64 s[4:5], s[18:19], 2
	s_add_u32 s4, s42, s4
	s_addc_u32 s5, s43, s5
	global_load_dwordx4 v[70:73], v161, s[4:5]
	s_mov_b64 s[30:31], 0
	s_waitcnt vmcnt(0)
	v_pk_mul_f32 v[70:71], v[66:67], v[70:71]
	v_pk_mul_f32 v[72:73], v[68:69], v[72:73]

; #define LAS __attribute__((address_space(3)))
; #define PIN(i) ((const float*)ldq_(L, (i)))
; __device__ __forceinline__ unsigned pk2(float lo, float hi) { f32x2 v = {lo, hi}; bf16x2_t b = __builtin_convertvector(v, bf16x2_t); return __builtin_bit_cast(unsigned, b); }
; #define PREP_CONV(bit, SRC, Kd, Nd, DST, GK, MODE) if (mask & (bit)) { for (int it = gw; it < ((Kd) / 64) * ((Nd) / 64); it += NGW) transpose_item((SRC), (Kd), (Nd), (bf16_t*)(wl + (DST)), (GK), (MODE), scr, it, lane); }
; __device__ __forceinline__ void transpose_item(const float* W, int K, int N, bf16_t* WT, const float* gk, int mode, LAS float* scr_, int item, int lane) {
;     LAS unsigned* scr = (LAS unsigned*)scr_;
;     const int nblk = N / 64, kb = item / nblk, nb = item % nblk, k0 = 64 * kb, n0 = 64 * nb;
;     const int sc = (mode == 1) ? (((n0 >> 7) & 1) * DFF + (n0 >> 8) * 128 + (n0 & 127)) : n0;
;     const float* src = W + (size_t)k0 * N + sc + lane;
;     float va[32], vb[32];
; #pragma unroll
;     for (int kp = 0; kp < 32; ++kp) { va[kp] = src[(size_t)(2 * kp) * N]; vb[kp] = src[(size_t)(2 * kp + 1) * N]; }
; #pragma unroll
;     for (int kp = 0; kp < 32; ++kp) {
;         float a = va[kp], b = vb[kp];
;         if (gk) { a *= gk[k0 + 2 * kp]; b *= gk[k0 + 2 * kp + 1]; }
;         scr[kp * 65 + lane] = pk2(a, b);
;     }
;     asm volatile("s_waitcnt lgkmcnt(0)" ::: "memory");
;     const int c = lane & 7;
; #pragma unroll
;     for (int j = 0; j < 8; ++j) { const int r = (lane >> 3) + 8 * j; const LAS unsigned* q = scr + (4 * c) * 65 + r;
;         u32x4 o; o.x = q[0]; o.y = q[65]; o.z = q[130]; o.w = q[195];
;         *(u32x4*)(WT + (size_t)(n0 + r) * K + k0 + 8 * c) = o; }
; __device__ __forceinline__ void prep(const Params& p, LAS unsigned char* L, int wv, int vb, int nvb, int l, int mask) {
;     ...
;     PREP_CONV(PM_WOUT, PIN(I_WOUT) + (size_t)l * DM * DM, DM, DM, WL_OUT, nullptr, 0)
.LBB0_938:
	v_mov_b32_e32 v6, v161
	v_add_u32_e32 v79, 0x400, v77
	v_add_u32_e32 v6, 0, v6
	v_add_u32_e32 v6, 0x20188, v6
	s_nop 0
	v_add_u32_e32 v92, 0x800, v77
	v_add_u32_e32 v93, 0xc00, v77
	v_add_u32_e32 v94, 0x1000, v77
	v_add_u32_e32 v95, 0x1400, v77
	s_waitcnt lgkmcnt(0)
	v_readlane_b32 s13, v251, 34
	v_readlane_b32 s12, v251, 35
	s_add_u32 s13, s13, s4
	s_addc_u32 s21, s12, s5
	s_ashr_i32 s12, s24, 31
	s_lshr_b32 s12, s12, 28
	s_add_i32 s12, s24, s12
	s_ashr_i32 s12, s12, 4
	s_lshl_b32 s28, s12, 6
	s_lshl_b32 s12, s12, 10
	s_ashr_i32 s29, s28, 31
	s_sub_i32 s12, s15, s12
	s_lshl_b64 s[18:19], s[28:29], 12
	s_add_u32 s18, s13, s18
	v_add_u32_e32 v6, s12, v76
	s_addc_u32 s19, s21, s19
	s_ashr_i32 s13, s12, 31
	v_add_u32_e32 v8, 8, v6
	v_add_u32_e32 v10, 16, v6
	v_add_u32_e32 v12, 24, v6
	v_add_u32_e32 v14, 32, v6
	v_add_u32_e32 v16, 40, v6
	v_add_u32_e32 v18, 48, v6
	v_add_u32_e32 v22, 56, v6
	s_lshl_b64 s[12:13], s[12:13], 2
	v_ashrrev_i32_e32 v7, 31, v6
	v_ashrrev_i32_e32 v9, 31, v8
	v_ashrrev_i32_e32 v11, 31, v10
	v_ashrrev_i32_e32 v13, 31, v12
	v_ashrrev_i32_e32 v15, 31, v14
	v_ashrrev_i32_e32 v17, 31, v16
	v_ashrrev_i32_e32 v19, 31, v18
	v_ashrrev_i32_e32 v23, 31, v22
	s_add_u32 s18, s18, s12
	v_lshl_add_u64 v[20:21], s[28:29], 1, v[4:5]
	v_lshlrev_b64 v[6:7], 11, v[6:7]
	v_lshlrev_b64 v[8:9], 11, v[8:9]
	v_lshlrev_b64 v[10:11], 11, v[10:11]
	v_lshlrev_b64 v[12:13], 11, v[12:13]
	v_lshlrev_b64 v[14:15], 11, v[14:15]
	v_lshlrev_b64 v[16:17], 11, v[16:17]
	v_lshlrev_b64 v[18:19], 11, v[18:19]
	v_lshlrev_b64 v[22:23], 11, v[22:23]
	s_addc_u32 s19, s19, s13
	v_lshl_add_u64 v[6:7], v[20:21], 0, v[6:7]
	v_lshl_add_u64 v[8:9], v[20:21], 0, v[8:9]
	v_lshl_add_u64 v[10:11], v[20:21], 0, v[10:11]
	v_lshl_add_u64 v[12:13], v[20:21], 0, v[12:13]
	v_lshl_add_u64 v[14:15], v[20:21], 0, v[14:15]
	v_lshl_add_u64 v[16:17], v[20:21], 0, v[16:17]
	v_lshl_add_u64 v[18:19], v[20:21], 0, v[18:19]
	v_lshl_add_u64 v[20:21], v[20:21], 0, v[22:23]
	v_lshl_add_u64 v[22:23], s[18:19], 0, v[160:161]
	v_add_co_u32_e32 v24, vcc, s79, v22
	global_load_dword v98, v160, s[18:19]
	s_nop 0
	v_addc_co_u32_e32 v25, vcc, 0, v23, vcc
	v_add_co_u32_e32 v26, vcc, s88, v22
	v_add_u32_e32 v96, 0x1800, v77
	s_nop 0
	v_addc_co_u32_e32 v27, vcc, 0, v23, vcc
	v_add_co_u32_e32 v28, vcc, s80, v22
	v_add_u32_e32 v97, 0x1c00, v77
	s_nop 0
	v_addc_co_u32_e32 v29, vcc, 0, v23, vcc
	v_add_co_u32_e32 v30, vcc, s70, v22
	s_add_i32 s12, s24, 0x700
	s_nop 0
	v_addc_co_u32_e32 v31, vcc, 0, v23, vcc
	v_add_co_u32_e32 v32, vcc, s71, v22
	s_add_i32 s15, s15, 0x1c000
	s_nop 0
	v_addc_co_u32_e32 v33, vcc, 0, v23, vcc
	v_add_co_u32_e32 v34, vcc, s91, v22
	s_cmpk_lt_i32 s24, 0xfa00
	s_nop 0
	v_addc_co_u32_e32 v35, vcc, 0, v23, vcc
	v_add_co_u32_e32 v36, vcc, s92, v22
	s_mov_b32 s24, s12
	s_nop 0
	v_addc_co_u32_e32 v37, vcc, 0, v23, vcc
	v_add_co_u32_e32 v38, vcc, s37, v22
	s_nop 1
	v_addc_co_u32_e32 v39, vcc, 0, v23, vcc
	v_add_co_u32_e32 v40, vcc, s94, v22
	s_nop 1
	v_addc_co_u32_e32 v41, vcc, 0, v23, vcc
	v_add_co_u32_e32 v42, vcc, s46, v22
	s_nop 1
	v_addc_co_u32_e32 v43, vcc, 0, v23, vcc
	v_add_co_u32_e32 v44, vcc, s47, v22
	s_nop 1
	v_addc_co_u32_e32 v45, vcc, 0, v23, vcc
	v_add_co_u32_e32 v46, vcc, s59, v22
	s_nop 1
	v_addc_co_u32_e32 v47, vcc, 0, v23, vcc
	v_add_co_u32_e32 v48, vcc, s81, v22
	s_waitcnt vmcnt(13)
	s_nop 0
	v_addc_co_u32_e32 v49, vcc, 0, v23, vcc
	s_waitcnt vmcnt(12)
	v_add_co_u32_e32 v50, vcc, s83, v22
	s_waitcnt vmcnt(11)
	s_nop 0
	v_addc_co_u32_e32 v51, vcc, 0, v23, vcc
	v_add_co_u32_e32 v52, vcc, s27, v22
	s_nop 1
	v_addc_co_u32_e32 v53, vcc, 0, v23, vcc
	v_add_co_u32_e32 v54, vcc, s50, v22
	s_nop 1
	v_addc_co_u32_e32 v55, vcc, 0, v23, vcc
	v_add_co_u32_e32 v56, vcc, s53, v22
	s_nop 1
	v_addc_co_u32_e32 v57, vcc, 0, v23, vcc
	v_add_co_u32_e32 v58, vcc, s0, v22
	s_nop 1
	v_addc_co_u32_e32 v59, vcc, 0, v23, vcc
	v_add_co_u32_e32 v60, vcc, s73, v22
	s_nop 1
	v_addc_co_u32_e32 v61, vcc, 0, v23, vcc
	v_add_co_u32_e32 v62, vcc, s1, v22
	s_nop 1
	v_addc_co_u32_e32 v63, vcc, 0, v23, vcc
	v_add_co_u32_e32 v64, vcc, s72, v22
	s_nop 1
	v_addc_co_u32_e32 v65, vcc, 0, v23, vcc
	s_waitcnt vmcnt(10)
	v_add_co_u32_e32 v66, vcc, s82, v22
	s_nop 1
	v_addc_co_u32_e32 v67, vcc, 0, v23, vcc
	v_add_co_u32_e32 v68, vcc, s33, v22
	s_nop 1
	v_addc_co_u32_e32 v69, vcc, 0, v23, vcc
	v_add_co_u32_e32 v70, vcc, s22, v22
	s_nop 1
	v_addc_co_u32_e32 v71, vcc, 0, v23, vcc
	v_add_co_u32_e32 v72, vcc, s38, v22
	s_nop 1
	v_addc_co_u32_e32 v73, vcc, 0, v23, vcc
	v_add_co_u32_e32 v80, vcc, s39, v22
	s_nop 1
	v_addc_co_u32_e32 v81, vcc, 0, v23, vcc
	v_add_co_u32_e32 v82, vcc, s56, v22
	s_nop 1
	v_addc_co_u32_e32 v83, vcc, 0, v23, vcc
	v_add_co_u32_e32 v84, vcc, s69, v22
	s_nop 1
	v_addc_co_u32_e32 v85, vcc, 0, v23, vcc
	v_add_co_u32_e32 v86, vcc, s87, v22
	s_nop 1
	v_addc_co_u32_e32 v87, vcc, 0, v23, vcc
	v_add_co_u32_e32 v88, vcc, s90, v22
	s_nop 1
	v_addc_co_u32_e32 v89, vcc, 0, v23, vcc
	v_add_co_u32_e32 v90, vcc, s51, v22
	s_nop 1
	v_addc_co_u32_e32 v91, vcc, 0, v23, vcc
	v_add_co_u32_e32 v22, vcc, s52, v22
	s_nop 1
	v_addc_co_u32_e32 v23, vcc, 0, v23, vcc
	global_load_dword v99, v[24:25], off offset:-4096
	s_nop 0
	global_load_dword v24, v[24:25], off
	s_nop 0
	global_load_dword v25, v[26:27], off offset:-4096
	s_nop 0
	global_load_dword v26, v[26:27], off
	s_nop 0
	global_load_dword v27, v[28:29], off offset:-4096
	s_nop 0
	global_load_dword v28, v[28:29], off
	s_nop 0
	global_load_dword v29, v[30:31], off offset:-4096
	s_nop 0
	global_load_dword v30, v[30:31], off
	s_nop 0
	global_load_dword v31, v[32:33], off offset:-4096
	s_nop 0
	global_load_dword v32, v[32:33], off
	s_nop 0
; __device__ __forceinline__ unsigned pk2(float lo, float hi) { f32x2 v = {lo, hi}; bf16x2_t b = __builtin_convertvector(v, bf16x2_t); return __builtin_bit_cast(unsigned, b); }
; __device__ __forceinline__ void transpose_item(const float* W, int K, int N, bf16_t* WT, const float* gk, int mode, LAS float* scr_, int item, int lane) {
;     ...
; #pragma unroll
;     for (int kp = 0; kp < 32; ++kp) { va[kp] = src[(size_t)(2 * kp) * N]; vb[kp] = src[(size_t)(2 * kp + 1) * N]; }
; #pragma unroll
;     for (int kp = 0; kp < 32; ++kp) {
;         float a = va[kp], b = vb[kp];
;         if (gk) { a *= gk[k0 + 2 * kp]; b *= gk[k0 + 2 * kp + 1]; }
;         scr[kp * 65 + lane] = pk2(a, b);
;     }
	global_load_dword v33, v[34:35], off offset:-4096
	s_nop 0
	global_load_dword v34, v[34:35], off
	s_nop 0
	global_load_dword v35, v[36:37], off offset:-4096
	s_nop 0
	global_load_dword v36, v[36:37], off
	s_nop 0
	global_load_dword v37, v[38:39], off offset:-4096
	s_nop 0
	global_load_dword v38, v[38:39], off
	s_nop 0
	global_load_dword v39, v[40:41], off offset:-4096
	s_nop 0
	global_load_dword v40, v[40:41], off
	s_nop 0
	global_load_dword v41, v[42:43], off offset:-4096
	s_nop 0
	global_load_dword v42, v[42:43], off
	s_nop 0
	global_load_dword v43, v[44:45], off offset:-4096
	s_nop 0
	global_load_dword v44, v[44:45], off
	s_nop 0
	global_load_dword v45, v[46:47], off offset:-4096
	s_nop 0
	global_load_dword v46, v[46:47], off
	s_nop 0
	global_load_dword v47, v[48:49], off offset:-4096
	s_nop 0
	global_load_dword v48, v[48:49], off
	s_nop 0
	global_load_dword v49, v[50:51], off offset:-4096
	s_nop 0
	global_load_dword v50, v[50:51], off
	s_nop 0
	global_load_dword v51, v[52:53], off offset:-4096
	s_nop 0
	global_load_dword v52, v[52:53], off
	s_nop 0
	global_load_dword v53, v[54:55], off offset:-4096
	s_nop 0
	global_load_dword v54, v[54:55], off
	s_nop 0
	global_load_dword v55, v[56:57], off offset:-4096
	s_nop 0
	global_load_dword v56, v[56:57], off
	s_nop 0
	global_load_dword v57, v[58:59], off offset:-4096
	s_nop 0
	global_load_dword v58, v[58:59], off
	s_nop 0
	global_load_dword v59, v[60:61], off offset:-4096
	s_nop 0
	global_load_dword v60, v[60:61], off
	s_nop 0
	global_load_dword v61, v[62:63], off offset:-4096
	s_nop 0
	global_load_dword v62, v[62:63], off
	s_nop 0
	global_load_dword v63, v[64:65], off offset:-4096
	s_nop 0
	global_load_dword v64, v[64:65], off
	s_nop 0
	global_load_dword v65, v[66:67], off offset:-4096
	s_nop 0
	global_load_dword v66, v[66:67], off
	s_nop 0
	global_load_dword v67, v[68:69], off offset:-4096
	s_nop 0
	global_load_dword v68, v[68:69], off
	s_nop 0
	global_load_dword v69, v[70:71], off offset:-4096
	s_nop 0
	global_load_dword v70, v[70:71], off
	s_nop 0
	global_load_dword v71, v[72:73], off offset:-4096
	s_nop 0
	global_load_dword v72, v[72:73], off
	s_nop 0
	global_load_dword v73, v[80:81], off offset:-4096
	s_nop 0
	global_load_dword v80, v[80:81], off
	s_nop 0
	global_load_dword v81, v[82:83], off offset:-4096
	s_nop 0
	global_load_dword v82, v[82:83], off
	s_nop 0
	global_load_dword v83, v[84:85], off offset:-4096
	s_nop 0
	global_load_dword v84, v[84:85], off
	s_nop 0
	global_load_dword v85, v[86:87], off offset:-4096
	s_nop 0
	global_load_dword v86, v[86:87], off
	s_nop 0
	global_load_dword v87, v[88:89], off offset:-4096
	s_nop 0
	global_load_dword v88, v[88:89], off
	s_nop 0
	global_load_dword v89, v[90:91], off offset:-4096
	s_nop 0
	global_load_dword v90, v[90:91], off
	s_nop 0
	global_load_dword v22, v[22:23], off
	s_waitcnt vmcnt(62)
	v_cvt_pk_bf16_f32 v23, v98, v99
	s_waitcnt vmcnt(60)
	v_cvt_pk_bf16_f32 v24, v24, v25
	s_waitcnt vmcnt(58)
	v_cvt_pk_bf16_f32 v25, v26, v27
	s_waitcnt vmcnt(56)
	v_cvt_pk_bf16_f32 v26, v28, v29
	s_waitcnt vmcnt(54)
	v_cvt_pk_bf16_f32 v27, v30, v31
	s_waitcnt vmcnt(52)
	v_cvt_pk_bf16_f32 v28, v32, v33
	s_waitcnt vmcnt(50)
	v_cvt_pk_bf16_f32 v29, v34, v35
	s_waitcnt vmcnt(48)
	v_cvt_pk_bf16_f32 v30, v36, v37
	s_waitcnt vmcnt(46)
	v_cvt_pk_bf16_f32 v31, v38, v39
	s_waitcnt vmcnt(44)
	v_cvt_pk_bf16_f32 v32, v40, v41
	s_waitcnt vmcnt(42)
	v_cvt_pk_bf16_f32 v33, v42, v43
	s_waitcnt vmcnt(40)
	v_cvt_pk_bf16_f32 v34, v44, v45
	s_waitcnt vmcnt(38)
	v_cvt_pk_bf16_f32 v35, v46, v47
	s_waitcnt vmcnt(36)
	v_cvt_pk_bf16_f32 v36, v48, v49
	s_waitcnt vmcnt(34)
	v_cvt_pk_bf16_f32 v37, v50, v51
	s_waitcnt vmcnt(32)
	v_cvt_pk_bf16_f32 v38, v52, v53
	s_waitcnt vmcnt(30)
; #define LAS __attribute__((address_space(3)))
; __device__ __forceinline__ unsigned pk2(float lo, float hi) { f32x2 v = {lo, hi}; bf16x2_t b = __builtin_convertvector(v, bf16x2_t); return __builtin_bit_cast(unsigned, b); }
; __device__ __forceinline__ void transpose_item(const float* W, int K, int N, bf16_t* WT, const float* gk, int mode, LAS float* scr_, int item, int lane) {
;     ...
;         scr[kp * 65 + lane] = pk2(a, b);
;     }
;     asm volatile("s_waitcnt lgkmcnt(0)" ::: "memory");
;     const int c = lane & 7;
; #pragma unroll
;     for (int j = 0; j < 8; ++j) { const int r = (lane >> 3) + 8 * j; const LAS unsigned* q = scr + (4 * c) * 65 + r;
;         u32x4 o; o.x = q[0]; o.y = q[65]; o.z = q[130]; o.w = q[195];
;         *(u32x4*)(WT + (size_t)(n0 + r) * K + k0 + 8 * c) = o; }
	v_cvt_pk_bf16_f32 v39, v54, v55
	s_waitcnt vmcnt(28)
	v_cvt_pk_bf16_f32 v40, v56, v57
	s_waitcnt vmcnt(26)
	v_cvt_pk_bf16_f32 v41, v58, v59
	s_waitcnt vmcnt(24)
	v_cvt_pk_bf16_f32 v42, v60, v61
	s_waitcnt vmcnt(22)
	v_cvt_pk_bf16_f32 v43, v62, v63
	s_waitcnt vmcnt(20)
	v_cvt_pk_bf16_f32 v44, v64, v65
	s_waitcnt vmcnt(18)
	v_cvt_pk_bf16_f32 v45, v66, v67
	s_waitcnt vmcnt(16)
	v_cvt_pk_bf16_f32 v46, v68, v69
	s_waitcnt vmcnt(14)
	v_cvt_pk_bf16_f32 v47, v70, v71
	s_waitcnt vmcnt(12)
	v_cvt_pk_bf16_f32 v48, v72, v73
	s_waitcnt vmcnt(10)
	v_cvt_pk_bf16_f32 v49, v80, v81
	s_waitcnt vmcnt(8)
	v_cvt_pk_bf16_f32 v50, v82, v83
	s_waitcnt vmcnt(6)
	v_cvt_pk_bf16_f32 v51, v84, v85
	s_waitcnt vmcnt(4)
	v_cvt_pk_bf16_f32 v52, v86, v87
	s_waitcnt vmcnt(2)
	v_cvt_pk_bf16_f32 v53, v88, v89
	s_waitcnt vmcnt(0)
	v_cvt_pk_bf16_f32 v22, v90, v22
	ds_write2_b32 v77, v23, v24 offset1:65
	ds_write2_b32 v77, v25, v26 offset0:130 offset1:195
	ds_write2_b32 v79, v27, v28 offset0:4 offset1:69
	ds_write2_b32 v79, v29, v30 offset0:134 offset1:199
	ds_write2_b32 v92, v31, v32 offset0:8 offset1:73
	ds_write2_b32 v92, v33, v34 offset0:138 offset1:203
	ds_write2_b32 v93, v35, v36 offset0:12 offset1:77
	ds_write2_b32 v93, v37, v38 offset0:142 offset1:207
	ds_write2_b32 v94, v39, v40 offset0:16 offset1:81
	ds_write2_b32 v94, v41, v42 offset0:146 offset1:211
	ds_write2_b32 v95, v43, v44 offset0:20 offset1:85
	ds_write2_b32 v95, v45, v46 offset0:150 offset1:215
	ds_write2_b32 v96, v47, v48 offset0:24 offset1:89
	ds_write2_b32 v96, v49, v50 offset0:154 offset1:219
	ds_write2_b32 v97, v51, v52 offset0:28 offset1:93
	ds_write2_b32 v97, v53, v22 offset0:158 offset1:223
	s_waitcnt lgkmcnt(0)
	ds_read2_b32 v[22:23], v3 offset0:65 offset1:73
	ds_read2_b32 v[42:43], v3 offset0:130 offset1:138
	ds_read2_b32 v[24:25], v3 offset0:195 offset1:203
	ds_read2_b32 v[44:45], v3 offset1:8
	ds_read2_b32 v[46:47], v3 offset0:16 offset1:24
	ds_read2_b32 v[26:27], v3 offset0:81 offset1:89
	ds_read2_b32 v[48:49], v3 offset0:146 offset1:154
	ds_read2_b32 v[28:29], v3 offset0:211 offset1:219
	ds_read2_b32 v[30:31], v3 offset0:97 offset1:105
	ds_read2_b32 v[50:51], v3 offset0:162 offset1:170
	ds_read2_b32 v[32:33], v3 offset0:227 offset1:235
	ds_read2_b32 v[52:53], v3 offset0:32 offset1:40
	ds_read2_b32 v[54:55], v3 offset0:48 offset1:56
	ds_read2_b32 v[34:35], v3 offset0:113 offset1:121
	ds_read2_b32 v[56:57], v3 offset0:178 offset1:186
	ds_read2_b32 v[36:37], v3 offset0:243 offset1:251
	s_waitcnt lgkmcnt(12)
	v_mov_b32_e32 v38, v44
	v_mov_b32_e32 v39, v22
	v_mov_b32_e32 v40, v42
	v_mov_b32_e32 v41, v24
	v_mov_b32_e32 v22, v45
	v_mov_b32_e32 v24, v43
	s_waitcnt lgkmcnt(11)
	v_mov_b32_e32 v42, v46
	s_waitcnt lgkmcnt(10)
	v_mov_b32_e32 v43, v26
	s_waitcnt lgkmcnt(9)
	v_mov_b32_e32 v44, v48
	s_waitcnt lgkmcnt(8)
	v_mov_b32_e32 v45, v28
	v_mov_b32_e32 v26, v47
	v_mov_b32_e32 v28, v49
	s_waitcnt lgkmcnt(4)
	v_mov_b32_e32 v46, v52
	v_mov_b32_e32 v47, v30
	v_mov_b32_e32 v48, v50
	v_mov_b32_e32 v49, v32
	v_mov_b32_e32 v30, v53
	v_mov_b32_e32 v32, v51
	s_waitcnt lgkmcnt(3)
	v_mov_b32_e32 v50, v54
	s_waitcnt lgkmcnt(2)
	v_mov_b32_e32 v51, v34
	s_waitcnt lgkmcnt(1)
	v_mov_b32_e32 v52, v56
	s_waitcnt lgkmcnt(0)
	v_mov_b32_e32 v53, v36
	v_mov_b32_e32 v34, v55
	v_mov_b32_e32 v36, v57
	global_store_dwordx4 v[6:7], v[38:41], off
	global_store_dwordx4 v[8:9], v[22:25], off
	global_store_dwordx4 v[10:11], v[42:45], off
	global_store_dwordx4 v[12:13], v[26:29], off
	global_store_dwordx4 v[14:15], v[46:49], off
	global_store_dwordx4 v[16:17], v[30:33], off
	global_store_dwordx4 v[18:19], v[50:53], off
	global_store_dwordx4 v[20:21], v[34:37], off
	s_waitcnt lgkmcnt(0)
	s_cbranch_scc1 .LBB0_938

; #define LAS __attribute__((address_space(3)))
; #define PIN(i) ((const float*)ldq_(L, (i)))
; #define PREP_CONV(bit, SRC, Kd, Nd, DST, GK, MODE) if (mask & (bit)) { for (int it = gw; it < ((Kd) / 64) * ((Nd) / 64); it += NGW) transpose_item((SRC), (Kd), (Nd), (bf16_t*)(wl + (DST)), (GK), (MODE), scr, it, lane); }
; __device__ __forceinline__ void transpose_item(const float* W, int K, int N, bf16_t* WT, const float* gk, int mode, LAS float* scr_, int item, int lane) {
;     LAS unsigned* scr = (LAS unsigned*)scr_;
;     const int nblk = N / 64, kb = item / nblk, nb = item % nblk, k0 = 64 * kb, n0 = 64 * nb;
;     const int sc = (mode == 1) ? (((n0 >> 7) & 1) * DFF + (n0 >> 8) * 128 + (n0 & 127)) : n0;
;     const float* src = W + (size_t)k0 * N + sc + lane;
;     float va[32], vb[32];
; #pragma unroll
;     for (int kp = 0; kp < 32; ++kp) { va[kp] = src[(size_t)(2 * kp) * N]; vb[kp] = src[(size_t)(2 * kp + 1) * N]; }
; #pragma unroll
;     for (int kp = 0; kp < 32; ++kp) {
;         float a = va[kp], b = vb[kp];
;         if (gk) { a *= gk[k0 + 2 * kp]; b *= gk[k0 + 2 * kp + 1]; }
; __device__ __forceinline__ void prep(const Params& p, LAS unsigned char* L, int wv, int vb, int nvb, int l, int mask) {
;     ...
;     PREP_CONV(PM_FFB_IN, PIN(I_WFFB_IN) + (size_t)l * DM * NFF2, DM, NFF2, WL_FFB_IN, PIN(I_NFFB) + l * DM, 1)
.LBB0_942:
	v_mov_b32_e32 v6, v161
	s_mul_i32 s18, s6, 0x1600000
	v_add_u32_e32 v6, 0, v6
	v_add_u32_e32 v6, 0x20198, v6
	ds_read_b64 v[6:7], v6
	s_mov_b64 s[30:31], -1
	s_waitcnt lgkmcnt(0)
	v_readfirstlane_b32 s5, v6
	v_mov_b32_e32 v6, v161
	v_readfirstlane_b32 s4, v7
	v_add_u32_e32 v6, 0, v6
	v_add_u32_e32 v6, 0x20190, v6
	s_nop 0
	s_add_u32 s21, s5, s18
	s_mul_hi_i32 s5, s6, 0x1600000
	s_addc_u32 s25, s4, s5
	s_mul_hi_i32 s18, s42, 0x2e8ba2e9
	s_waitcnt lgkmcnt(0)
	v_readlane_b32 s4, v251, 36
	v_readlane_b32 s5, v251, 37
	s_add_u32 s44, s4, s12
	s_addc_u32 s45, s5, s13
	s_lshr_b32 s19, s18, 31
	s_ashr_i32 s18, s18, 4
	s_add_i32 s26, s18, s19
	s_mul_i32 s19, s26, 0xffffea00
	s_mul_i32 s24, s26, 0xfffff500
	s_add_i32 s43, s15, s19
	s_bfe_i32 s19, s42, 0x10001
	s_add_i32 s24, s29, s24
	s_and_b32 s19, s19, 0xb00
	s_and_b32 s24, s24, 0xffffff80
	s_lshl_b32 s18, s26, 6
	s_add_i32 s19, s19, s24
	s_and_b32 s24, s43, 64
	s_or_b32 s24, s19, s24
	s_ashr_i32 s19, s18, 31
	s_mul_i32 s26, s26, 0x160000
	s_mul_hi_i32 s28, s18, 0x5800
	s_add_u32 s21, s21, s26
	s_addc_u32 s26, s25, s28
	s_ashr_i32 s25, s24, 31
	s_lshl_b64 s[24:25], s[24:25], 2
	s_add_u32 s24, s21, s24
	s_addc_u32 s25, s26, s25
	v_lshl_add_u64 v[70:71], s[24:25], 0, v[160:161]
	s_movk_i32 s21, 0x5000
	v_add_co_u32_e32 v6, vcc, s21, v70
	s_mov_b32 s21, 0xb000
	s_nop 0
	v_addc_co_u32_e32 v7, vcc, 0, v71, vcc
	global_load_dword v67, v[6:7], off offset:2048
	v_add_co_u32_e32 v6, vcc, s21, v70
	global_load_dword v66, v160, s[24:25]
	s_nop 0
	v_addc_co_u32_e32 v7, vcc, 0, v71, vcc
	global_load_dword v68, v[6:7], off
	v_add_co_u32_e32 v6, vcc, s37, v70
	s_mov_b32 s21, 0x1b000
	s_nop 0
	v_addc_co_u32_e32 v7, vcc, 0, v71, vcc
	global_load_dword v69, v[6:7], off offset:2048
	v_add_co_u32_e32 v6, vcc, s47, v70
	s_cmp_lg_u64 s[4:5], 0
	s_nop 0
	v_addc_co_u32_e32 v7, vcc, 0, v71, vcc
	global_load_dword v58, v[6:7], off
	v_add_co_u32_e32 v6, vcc, s21, v70
	s_mov_b32 s21, 0x21000
	s_nop 0
	v_addc_co_u32_e32 v7, vcc, 0, v71, vcc
	global_load_dword v59, v[6:7], off offset:2048
	v_add_co_u32_e32 v6, vcc, s21, v70
	s_mov_b32 s21, 0x31000
	s_nop 0
	v_addc_co_u32_e32 v7, vcc, 0, v71, vcc
	global_load_dword v64, v[6:7], off
	v_add_co_u32_e32 v6, vcc, s73, v70
	s_cselect_b64 s[24:25], -1, 0
	s_nop 0
	v_addc_co_u32_e32 v7, vcc, 0, v71, vcc
	global_load_dword v65, v[6:7], off offset:2048
	v_add_co_u32_e32 v6, vcc, s82, v70
	s_cmp_eq_u64 s[4:5], 0
	s_nop 0
	v_addc_co_u32_e32 v7, vcc, 0, v71, vcc
	global_load_dword v60, v[6:7], off
	v_add_co_u32_e32 v6, vcc, s21, v70
	s_mov_b32 s21, 0x37000
	s_nop 0
	v_addc_co_u32_e32 v7, vcc, 0, v71, vcc
	global_load_dword v61, v[6:7], off offset:2048
	v_add_co_u32_e32 v6, vcc, s21, v70
	s_mov_b32 s21, 0x47000
	s_nop 0
	v_addc_co_u32_e32 v7, vcc, 0, v71, vcc
	global_load_dword v62, v[6:7], off
	v_add_co_u32_e32 v6, vcc, s90, v70
	s_nop 1
	v_addc_co_u32_e32 v7, vcc, 0, v71, vcc
	global_load_dword v63, v[6:7], off offset:2048
	v_add_co_u32_e32 v6, vcc, s93, v70
	s_nop 1
	v_addc_co_u32_e32 v7, vcc, 0, v71, vcc
	global_load_dword v48, v[6:7], off
	v_add_co_u32_e32 v6, vcc, s21, v70
	s_mov_b32 s21, 0x4d000
	s_nop 0
	v_addc_co_u32_e32 v7, vcc, 0, v71, vcc
	global_load_dword v49, v[6:7], off offset:2048
	v_add_co_u32_e32 v6, vcc, s21, v70
	s_mov_b32 s21, 0x52000
	s_nop 0
	v_addc_co_u32_e32 v7, vcc, 0, v71, vcc
	global_load_dword v54, v[6:7], off
	v_add_co_u32_e32 v6, vcc, s21, v70
	s_mov_b32 s21, 0x58000
	s_nop 0
	v_addc_co_u32_e32 v7, vcc, 0, v71, vcc
	global_load_dword v55, v[6:7], off offset:2048
	v_add_co_u32_e32 v6, vcc, s21, v70
	s_mov_b32 s21, 0x5d000
	s_nop 0
	v_addc_co_u32_e32 v7, vcc, 0, v71, vcc
	global_load_dword v52, v[6:7], off
	v_add_co_u32_e32 v6, vcc, s21, v70
	s_mov_b32 s21, 0x63000
	s_nop 0
	v_addc_co_u32_e32 v7, vcc, 0, v71, vcc
	global_load_dword v53, v[6:7], off offset:2048
	v_add_co_u32_e32 v6, vcc, s21, v70
	s_mov_b32 s21, 0x68000
	s_nop 0
	v_addc_co_u32_e32 v7, vcc, 0, v71, vcc
	global_load_dword v56, v[6:7], off
	v_add_co_u32_e32 v6, vcc, s21, v70
	s_mov_b32 s21, 0x6e000
	s_nop 0
	v_addc_co_u32_e32 v7, vcc, 0, v71, vcc
	global_load_dword v57, v[6:7], off offset:2048
	v_add_co_u32_e32 v6, vcc, s21, v70
	s_mov_b32 s21, 0x73000
	s_nop 0
	v_addc_co_u32_e32 v7, vcc, 0, v71, vcc
	global_load_dword v42, v[6:7], off
	v_add_co_u32_e32 v6, vcc, s21, v70
	s_mov_b32 s21, 0x79000
	s_nop 0
	v_addc_co_u32_e32 v7, vcc, 0, v71, vcc
	global_load_dword v43, v[6:7], off offset:2048
	v_add_co_u32_e32 v6, vcc, s21, v70
	s_mov_b32 s21, 0x7e000
	s_nop 0
	v_addc_co_u32_e32 v7, vcc, 0, v71, vcc
	global_load_dword v46, v[6:7], off
	v_add_co_u32_e32 v6, vcc, s21, v70
	s_mov_b32 s21, 0x84000
	s_nop 0
	v_addc_co_u32_e32 v7, vcc, 0, v71, vcc
	global_load_dword v47, v[6:7], off offset:2048
	v_add_co_u32_e32 v6, vcc, s21, v70
	s_mov_b32 s21, 0x89000
	s_nop 0
	v_addc_co_u32_e32 v7, vcc, 0, v71, vcc
	global_load_dword v44, v[6:7], off
	v_add_co_u32_e32 v6, vcc, s21, v70
	s_mov_b32 s21, 0x8f000
	s_nop 0
	v_addc_co_u32_e32 v7, vcc, 0, v71, vcc
	global_load_dword v45, v[6:7], off offset:2048
	v_add_co_u32_e32 v6, vcc, s21, v70
	s_mov_b32 s21, 0x94000
	s_nop 0
	v_addc_co_u32_e32 v7, vcc, 0, v71, vcc
	global_load_dword v50, v[6:7], off
	v_add_co_u32_e32 v6, vcc, s21, v70
	s_mov_b32 s21, 0x9a000
	s_nop 0
	v_addc_co_u32_e32 v7, vcc, 0, v71, vcc
	global_load_dword v51, v[6:7], off offset:2048
	v_add_co_u32_e32 v6, vcc, s21, v70
	s_mov_b32 s21, 0x9f000
	s_nop 0
	v_addc_co_u32_e32 v7, vcc, 0, v71, vcc
	global_load_dword v34, v[6:7], off
; __device__ __forceinline__ void transpose_item(const float* W, int K, int N, bf16_t* WT, const float* gk, int mode, LAS float* scr_, int item, int lane) {
;     ...
; #pragma unroll
;     for (int kp = 0; kp < 32; ++kp) { va[kp] = src[(size_t)(2 * kp) * N]; vb[kp] = src[(size_t)(2 * kp + 1) * N]; }
; #pragma unroll
;     for (int kp = 0; kp < 32; ++kp) {
;         float a = va[kp], b = vb[kp];
;         if (gk) { a *= gk[k0 + 2 * kp]; b *= gk[k0 + 2 * kp + 1]; }
	v_add_co_u32_e32 v6, vcc, s21, v70
	s_mov_b32 s21, 0xa5000
	s_nop 0
	v_addc_co_u32_e32 v7, vcc, 0, v71, vcc
	global_load_dword v35, v[6:7], off offset:2048
	v_add_co_u32_e32 v6, vcc, s21, v70
	s_mov_b32 s21, 0xaa000
	s_nop 0
	v_addc_co_u32_e32 v7, vcc, 0, v71, vcc
	global_load_dword v40, v[6:7], off
	v_add_co_u32_e32 v6, vcc, s21, v70
	s_mov_b32 s21, 0xb5000
	s_nop 0
	v_addc_co_u32_e32 v7, vcc, 0, v71, vcc
	global_load_dword v41, v[6:7], off offset:2048
	v_add_co_u32_e32 v6, vcc, s95, v70
	s_nop 1
	v_addc_co_u32_e32 v7, vcc, 0, v71, vcc
	global_load_dword v36, v[6:7], off
	v_add_co_u32_e32 v6, vcc, s21, v70
	s_mov_b32 s21, 0xbb000
	s_nop 0
	v_addc_co_u32_e32 v7, vcc, 0, v71, vcc
	global_load_dword v37, v[6:7], off offset:2048
	v_add_co_u32_e32 v6, vcc, s21, v70
	s_mov_b32 s21, 0xc0000
	s_nop 0
	v_addc_co_u32_e32 v7, vcc, 0, v71, vcc
	global_load_dword v38, v[6:7], off
	v_add_co_u32_e32 v6, vcc, s21, v70
	s_mov_b32 s21, 0xcb000
	s_nop 0
	v_addc_co_u32_e32 v7, vcc, 0, v71, vcc
	global_load_dword v39, v[6:7], off offset:2048
	v_add_co_u32_e32 v6, vcc, s89, v70
	s_nop 1
	v_addc_co_u32_e32 v7, vcc, 0, v71, vcc
	global_load_dword v24, v[6:7], off
	v_add_co_u32_e32 v6, vcc, s21, v70
	s_mov_b32 s21, 0xd1000
	s_nop 0
	v_addc_co_u32_e32 v7, vcc, 0, v71, vcc
	global_load_dword v25, v[6:7], off offset:2048
	v_add_co_u32_e32 v6, vcc, s21, v70
	s_mov_b32 s21, 0xd6000
	s_nop 0
	v_addc_co_u32_e32 v7, vcc, 0, v71, vcc
	global_load_dword v30, v[6:7], off
	v_add_co_u32_e32 v6, vcc, s21, v70
	s_mov_b32 s21, 0xdc000
	s_nop 0
	v_addc_co_u32_e32 v7, vcc, 0, v71, vcc
	global_load_dword v31, v[6:7], off offset:2048
	v_add_co_u32_e32 v6, vcc, s21, v70
	s_mov_b32 s21, 0xe1000
	s_nop 0
	v_addc_co_u32_e32 v7, vcc, 0, v71, vcc
	global_load_dword v28, v[6:7], off
	v_add_co_u32_e32 v6, vcc, s21, v70
	s_mov_b32 s21, 0xe7000
	s_nop 0
	v_addc_co_u32_e32 v7, vcc, 0, v71, vcc
	global_load_dword v29, v[6:7], off offset:2048
	v_add_co_u32_e32 v6, vcc, s21, v70
	s_mov_b32 s21, 0xec000
	s_nop 0
	v_addc_co_u32_e32 v7, vcc, 0, v71, vcc
	global_load_dword v32, v[6:7], off
	v_add_co_u32_e32 v6, vcc, s21, v70
	s_mov_b32 s21, 0xf2000
	s_nop 0
	v_addc_co_u32_e32 v7, vcc, 0, v71, vcc
	global_load_dword v33, v[6:7], off offset:2048
	v_add_co_u32_e32 v6, vcc, s21, v70
	s_mov_b32 s21, 0xf7000
	s_nop 0
	v_addc_co_u32_e32 v7, vcc, 0, v71, vcc
	global_load_dword v16, v[6:7], off
	v_add_co_u32_e32 v6, vcc, s21, v70
	s_mov_b32 s21, 0xfd000
	s_nop 0
	v_addc_co_u32_e32 v7, vcc, 0, v71, vcc
	global_load_dword v17, v[6:7], off offset:2048
	v_add_co_u32_e32 v6, vcc, s21, v70
	s_mov_b32 s21, 0x102000
	s_nop 0
	v_addc_co_u32_e32 v7, vcc, 0, v71, vcc
	global_load_dword v22, v[6:7], off
	v_add_co_u32_e32 v6, vcc, s21, v70
	s_mov_b32 s21, 0x108000
	s_nop 0
	v_addc_co_u32_e32 v7, vcc, 0, v71, vcc
	global_load_dword v23, v[6:7], off offset:2048
	v_add_co_u32_e32 v6, vcc, s21, v70
	s_mov_b32 s21, 0x10d000
	s_nop 0
	v_addc_co_u32_e32 v7, vcc, 0, v71, vcc
	global_load_dword v20, v[6:7], off
	v_add_co_u32_e32 v6, vcc, s21, v70
	s_mov_b32 s21, 0x113000
	s_nop 0
	v_addc_co_u32_e32 v7, vcc, 0, v71, vcc
	global_load_dword v21, v[6:7], off offset:2048
	v_add_co_u32_e32 v6, vcc, s21, v70
	s_mov_b32 s21, 0x118000
	s_nop 0
	v_addc_co_u32_e32 v7, vcc, 0, v71, vcc
	global_load_dword v26, v[6:7], off
	v_add_co_u32_e32 v6, vcc, s21, v70
	s_mov_b32 s21, 0x11e000
	s_nop 0
	v_addc_co_u32_e32 v7, vcc, 0, v71, vcc
	global_load_dword v27, v[6:7], off offset:2048
	v_add_co_u32_e32 v6, vcc, s21, v70
	s_mov_b32 s21, 0x123000
	s_nop 0
	v_addc_co_u32_e32 v7, vcc, 0, v71, vcc
	global_load_dword v8, v[6:7], off
	v_add_co_u32_e32 v6, vcc, s21, v70
	s_mov_b32 s21, 0x129000
	s_nop 0
	v_addc_co_u32_e32 v7, vcc, 0, v71, vcc
	global_load_dword v9, v[6:7], off offset:2048
	v_add_co_u32_e32 v6, vcc, s21, v70
	s_mov_b32 s21, 0x12e000
	s_nop 0
	v_addc_co_u32_e32 v7, vcc, 0, v71, vcc
	global_load_dword v14, v[6:7], off
	v_add_co_u32_e32 v6, vcc, s21, v70
	s_mov_b32 s21, 0x134000
	s_nop 0
	v_addc_co_u32_e32 v7, vcc, 0, v71, vcc
	global_load_dword v15, v[6:7], off offset:2048
	v_add_co_u32_e32 v6, vcc, s21, v70
	s_mov_b32 s21, 0x139000
	s_nop 0
	v_addc_co_u32_e32 v7, vcc, 0, v71, vcc
	global_load_dword v10, v[6:7], off
	v_add_co_u32_e32 v6, vcc, s21, v70
	s_mov_b32 s21, 0x13f000
	s_nop 0
	v_addc_co_u32_e32 v7, vcc, 0, v71, vcc
	global_load_dword v11, v[6:7], off offset:2048
	v_add_co_u32_e32 v6, vcc, s21, v70
	s_mov_b32 s21, 0x144000
	s_nop 0
	v_addc_co_u32_e32 v7, vcc, 0, v71, vcc
	global_load_dword v18, v[6:7], off
	v_add_co_u32_e32 v6, vcc, s21, v70
	s_mov_b32 s21, 0x14a000
	s_nop 0
	v_addc_co_u32_e32 v7, vcc, 0, v71, vcc
	global_load_dword v19, v[6:7], off offset:2048
	v_add_co_u32_e32 v6, vcc, s21, v70
	s_mov_b32 s21, 0x14f000
	s_nop 0
	v_addc_co_u32_e32 v7, vcc, 0, v71, vcc
	v_add_co_u32_e32 v12, vcc, s21, v70
	global_load_dword v6, v[6:7], off
	s_nop 0
	v_addc_co_u32_e32 v13, vcc, 0, v71, vcc
	global_load_dword v7, v[12:13], off offset:2048
	v_add_co_u32_e32 v12, vcc, 0x155000, v70
	s_nop 1
	v_addc_co_u32_e32 v13, vcc, 0, v71, vcc
	v_add_co_u32_e32 v70, vcc, 0x15a000, v70
	global_load_dword v12, v[12:13], off
	s_nop 0
	v_addc_co_u32_e32 v71, vcc, 0, v71, vcc
	global_load_dword v13, v[70:71], off offset:2048
	s_cbranch_scc1 .LBB0_944
	s_lshl_b64 s[4:5], s[18:19], 2
	s_add_u32 s4, s44, s4
	s_addc_u32 s5, s45, s5
	global_load_dwordx4 v[70:73], v161, s[4:5]
	s_mov_b64 s[30:31], 0
	s_waitcnt vmcnt(0)
	v_pk_mul_f32 v[70:71], v[66:67], v[70:71]
	v_pk_mul_f32 v[72:73], v[68:69], v[72:73]

; #define LAS __attribute__((address_space(3)))
; #define PIN(i) ((const float*)ldq_(L, (i)))
; __device__ __forceinline__ unsigned pk2(float lo, float hi) { f32x2 v = {lo, hi}; bf16x2_t b = __builtin_convertvector(v, bf16x2_t); return __builtin_bit_cast(unsigned, b); }
; #define PREP_CONV(bit, SRC, Kd, Nd, DST, GK, MODE) if (mask & (bit)) { for (int it = gw; it < ((Kd) / 64) * ((Nd) / 64); it += NGW) transpose_item((SRC), (Kd), (Nd), (bf16_t*)(wl + (DST)), (GK), (MODE), scr, it, lane); }
; __device__ __forceinline__ void transpose_item(const float* W, int K, int N, bf16_t* WT, const float* gk, int mode, LAS float* scr_, int item, int lane) {
;     LAS unsigned* scr = (LAS unsigned*)scr_;
;     const int nblk = N / 64, kb = item / nblk, nb = item % nblk, k0 = 64 * kb, n0 = 64 * nb;
;     const int sc = (mode == 1) ? (((n0 >> 7) & 1) * DFF + (n0 >> 8) * 128 + (n0 & 127)) : n0;
;     const float* src = W + (size_t)k0 * N + sc + lane;
;     float va[32], vb[32];
; #pragma unroll
;     for (int kp = 0; kp < 32; ++kp) { va[kp] = src[(size_t)(2 * kp) * N]; vb[kp] = src[(size_t)(2 * kp + 1) * N]; }
; #pragma unroll
;     for (int kp = 0; kp < 32; ++kp) {
;         float a = va[kp], b = vb[kp];
;         if (gk) { a *= gk[k0 + 2 * kp]; b *= gk[k0 + 2 * kp + 1]; }
;         scr[kp * 65 + lane] = pk2(a, b);
;     }
;     asm volatile("s_waitcnt lgkmcnt(0)" ::: "memory");
;     const int c = lane & 7;
; #pragma unroll
;     for (int j = 0; j < 8; ++j) { const int r = (lane >> 3) + 8 * j; const LAS unsigned* q = scr + (4 * c) * 65 + r;
;         u32x4 o; o.x = q[0]; o.y = q[65]; o.z = q[130]; o.w = q[195];
;         *(u32x4*)(WT + (size_t)(n0 + r) * K + k0 + 8 * c) = o; }
; __device__ __forceinline__ void prep(const Params& p, LAS unsigned char* L, int wv, int vb, int nvb, int l, int mask) {
;     ...
;     PREP_CONV(PM_FFB_OUT, PIN(I_WFFB_OUT) + (size_t)l * DFF * DM, DFF, DM, WL_FFB_OUT, nullptr, 0)
.LBB0_1008:
	v_mov_b32_e32 v6, v161
	s_mul_i32 s12, s6, 0xb00000
	v_add_u32_e32 v6, 0, v6
	v_add_u32_e32 v6, 0x201a0, v6
	s_nop 0
	v_add_u32_e32 v23, 0x400, v77
	v_add_u32_e32 v79, 0x800, v77
	v_add_u32_e32 v94, 0xc00, v77
	v_add_u32_e32 v95, 0x1000, v77
	s_waitcnt lgkmcnt(0)
	v_readlane_b32 s5, v251, 40
	v_readlane_b32 s4, v251, 41
	s_add_u32 s5, s5, s12
	s_mul_hi_i32 s12, s6, 0xb00000
	s_addc_u32 s19, s4, s12
	s_ashr_i32 s4, s18, 31
	s_lshr_b32 s4, s4, 28
	s_add_i32 s4, s18, s4
	s_ashr_i32 s4, s4, 4
	s_lshl_b32 s12, s4, 6
	s_lshl_b32 s13, s4, 10
	s_mul_i32 s21, s4, 0xffd40000
	s_sub_i32 s4, s15, s13
	s_ashr_i32 s13, s12, 31
	s_lshl_b64 s[24:25], s[12:13], 12
	v_lshl_add_u64 v[20:21], s[12:13], 1, v[4:5]
	s_add_u32 s12, s5, s24
	s_addc_u32 s13, s19, s25
	s_ashr_i32 s5, s4, 31
	v_add_u32_e32 v6, s21, v22
	s_lshl_b64 s[4:5], s[4:5], 2
	v_add_u32_e32 v8, 0x5800, v6
	v_add_u32_e32 v10, 0xb000, v6
	v_add_u32_e32 v12, 0x10800, v6
	v_add_u32_e32 v14, 0x16000, v6
	v_add_u32_e32 v16, 0x1b800, v6
	v_add_u32_e32 v18, 0x21000, v6
	v_add_u32_e32 v24, 0x26800, v6
	s_add_u32 s12, s12, s4
	v_ashrrev_i32_e32 v7, 31, v6
	v_ashrrev_i32_e32 v9, 31, v8
	v_ashrrev_i32_e32 v11, 31, v10
	v_ashrrev_i32_e32 v13, 31, v12
	v_ashrrev_i32_e32 v15, 31, v14
	v_ashrrev_i32_e32 v17, 31, v16
	v_ashrrev_i32_e32 v19, 31, v18
	v_ashrrev_i32_e32 v25, 31, v24
	s_addc_u32 s13, s13, s5
	v_lshl_add_u64 v[6:7], v[6:7], 1, v[20:21]
	v_lshl_add_u64 v[8:9], v[8:9], 1, v[20:21]
	v_lshl_add_u64 v[10:11], v[10:11], 1, v[20:21]
	v_lshl_add_u64 v[12:13], v[12:13], 1, v[20:21]
	v_lshl_add_u64 v[14:15], v[14:15], 1, v[20:21]
	v_lshl_add_u64 v[16:17], v[16:17], 1, v[20:21]
	v_lshl_add_u64 v[18:19], v[18:19], 1, v[20:21]
	v_lshl_add_u64 v[20:21], v[24:25], 1, v[20:21]
	v_lshl_add_u64 v[24:25], s[12:13], 0, v[160:161]
	v_add_co_u32_e32 v26, vcc, s79, v24
	global_load_dword v99, v160, s[12:13]
	s_nop 0
	v_addc_co_u32_e32 v27, vcc, 0, v25, vcc
	v_add_co_u32_e32 v28, vcc, s88, v24
	v_add_u32_e32 v96, 0x1400, v77
	s_nop 0
	v_addc_co_u32_e32 v29, vcc, 0, v25, vcc
	v_add_co_u32_e32 v30, vcc, s80, v24
	v_add_u32_e32 v97, 0x1800, v77
	s_nop 0
	v_addc_co_u32_e32 v31, vcc, 0, v25, vcc
	v_add_co_u32_e32 v32, vcc, s70, v24
	v_add_u32_e32 v98, 0x1c00, v77
	s_nop 0
	v_addc_co_u32_e32 v33, vcc, 0, v25, vcc
	v_add_co_u32_e32 v34, vcc, s71, v24
	s_add_i32 s4, s18, 0x700
	s_nop 0
	v_addc_co_u32_e32 v35, vcc, 0, v25, vcc
	v_add_co_u32_e32 v36, vcc, s91, v24
	s_add_i32 s15, s15, 0x1c000
	s_nop 0
	v_addc_co_u32_e32 v37, vcc, 0, v25, vcc
	v_add_co_u32_e32 v38, vcc, s92, v24
	v_add_u32_e32 v22, 0x13400000, v22
	s_nop 0
	v_addc_co_u32_e32 v39, vcc, 0, v25, vcc
	v_add_co_u32_e32 v40, vcc, s37, v24
	s_cmpk_lt_i32 s18, 0xfbc0
	s_nop 0
	v_addc_co_u32_e32 v41, vcc, 0, v25, vcc
	v_add_co_u32_e32 v42, vcc, s94, v24
	s_mov_b32 s18, s4
	s_nop 0
	v_addc_co_u32_e32 v43, vcc, 0, v25, vcc
	v_add_co_u32_e32 v44, vcc, s46, v24
	s_nop 1
	v_addc_co_u32_e32 v45, vcc, 0, v25, vcc
	v_add_co_u32_e32 v46, vcc, s47, v24
	s_nop 1
	v_addc_co_u32_e32 v47, vcc, 0, v25, vcc
	v_add_co_u32_e32 v48, vcc, s59, v24
	s_waitcnt vmcnt(13)
	s_nop 0
	v_addc_co_u32_e32 v49, vcc, 0, v25, vcc
	s_waitcnt vmcnt(12)
	v_add_co_u32_e32 v50, vcc, s81, v24
	s_waitcnt vmcnt(11)
	s_nop 0
	v_addc_co_u32_e32 v51, vcc, 0, v25, vcc
	v_add_co_u32_e32 v52, vcc, s83, v24
	s_nop 1
	v_addc_co_u32_e32 v53, vcc, 0, v25, vcc
	v_add_co_u32_e32 v54, vcc, s27, v24
	s_nop 1
	v_addc_co_u32_e32 v55, vcc, 0, v25, vcc
	v_add_co_u32_e32 v56, vcc, s50, v24
	s_nop 1
	v_addc_co_u32_e32 v57, vcc, 0, v25, vcc
	v_add_co_u32_e32 v58, vcc, s53, v24
	s_nop 1
	v_addc_co_u32_e32 v59, vcc, 0, v25, vcc
	v_add_co_u32_e32 v60, vcc, s0, v24
	s_nop 1
	v_addc_co_u32_e32 v61, vcc, 0, v25, vcc
	v_add_co_u32_e32 v62, vcc, s73, v24
	s_nop 1
	v_addc_co_u32_e32 v63, vcc, 0, v25, vcc
	v_add_co_u32_e32 v64, vcc, s1, v24
	s_nop 1
	v_addc_co_u32_e32 v65, vcc, 0, v25, vcc
	s_waitcnt vmcnt(10)
	v_add_co_u32_e32 v66, vcc, s72, v24
	s_nop 1
	v_addc_co_u32_e32 v67, vcc, 0, v25, vcc
	v_add_co_u32_e32 v68, vcc, s82, v24
	s_nop 1
	v_addc_co_u32_e32 v69, vcc, 0, v25, vcc
	v_add_co_u32_e32 v70, vcc, s33, v24
	s_nop 1
	v_addc_co_u32_e32 v71, vcc, 0, v25, vcc
	v_add_co_u32_e32 v72, vcc, s22, v24
	s_nop 1
	v_addc_co_u32_e32 v73, vcc, 0, v25, vcc
	v_add_co_u32_e32 v80, vcc, s38, v24
	s_nop 1
	v_addc_co_u32_e32 v81, vcc, 0, v25, vcc
	v_add_co_u32_e32 v82, vcc, s39, v24
	s_nop 1
	v_addc_co_u32_e32 v83, vcc, 0, v25, vcc
	v_add_co_u32_e32 v84, vcc, s56, v24
	s_nop 1
	v_addc_co_u32_e32 v85, vcc, 0, v25, vcc
	v_add_co_u32_e32 v86, vcc, s69, v24
	s_nop 1
	v_addc_co_u32_e32 v87, vcc, 0, v25, vcc
	v_add_co_u32_e32 v88, vcc, s87, v24
	s_nop 1
	v_addc_co_u32_e32 v89, vcc, 0, v25, vcc
	v_add_co_u32_e32 v90, vcc, s90, v24
	s_nop 1
	v_addc_co_u32_e32 v91, vcc, 0, v25, vcc
	v_add_co_u32_e32 v92, vcc, s51, v24
	s_nop 1
	v_addc_co_u32_e32 v93, vcc, 0, v25, vcc
	v_add_co_u32_e32 v24, vcc, s52, v24
	s_nop 1
	v_addc_co_u32_e32 v25, vcc, 0, v25, vcc
	global_load_dword v100, v[26:27], off offset:-4096
	s_nop 0
	global_load_dword v26, v[26:27], off
	s_nop 0
	global_load_dword v27, v[28:29], off offset:-4096
	s_nop 0
	global_load_dword v28, v[28:29], off
	s_nop 0
	global_load_dword v29, v[30:31], off offset:-4096
	s_nop 0
	global_load_dword v30, v[30:31], off
	s_nop 0
	global_load_dword v31, v[32:33], off offset:-4096
	s_nop 0
	global_load_dword v32, v[32:33], off
	s_nop 0
	global_load_dword v33, v[34:35], off offset:-4096
	s_nop 0
	global_load_dword v34, v[34:35], off
	s_nop 0
	global_load_dword v35, v[36:37], off offset:-4096
	s_nop 0
	global_load_dword v36, v[36:37], off
	s_nop 0
	global_load_dword v37, v[38:39], off offset:-4096
	s_nop 0
; __device__ __forceinline__ unsigned pk2(float lo, float hi) { f32x2 v = {lo, hi}; bf16x2_t b = __builtin_convertvector(v, bf16x2_t); return __builtin_bit_cast(unsigned, b); }
; __device__ __forceinline__ void transpose_item(const float* W, int K, int N, bf16_t* WT, const float* gk, int mode, LAS float* scr_, int item, int lane) {
;     ...
; #pragma unroll
;     for (int kp = 0; kp < 32; ++kp) { va[kp] = src[(size_t)(2 * kp) * N]; vb[kp] = src[(size_t)(2 * kp + 1) * N]; }
; #pragma unroll
;     for (int kp = 0; kp < 32; ++kp) {
;         float a = va[kp], b = vb[kp];
;         if (gk) { a *= gk[k0 + 2 * kp]; b *= gk[k0 + 2 * kp + 1]; }
;         scr[kp * 65 + lane] = pk2(a, b);
;     }
	global_load_dword v38, v[38:39], off
	s_nop 0
	global_load_dword v39, v[40:41], off offset:-4096
	s_nop 0
	global_load_dword v40, v[40:41], off
	s_nop 0
	global_load_dword v41, v[42:43], off offset:-4096
	s_nop 0
	global_load_dword v42, v[42:43], off
	s_nop 0
	global_load_dword v43, v[44:45], off offset:-4096
	s_nop 0
	global_load_dword v44, v[44:45], off
	s_nop 0
	global_load_dword v45, v[46:47], off offset:-4096
	s_nop 0
	global_load_dword v46, v[46:47], off
	s_nop 0
	global_load_dword v47, v[48:49], off offset:-4096
	s_nop 0
	global_load_dword v48, v[48:49], off
	s_nop 0
	global_load_dword v49, v[50:51], off offset:-4096
	s_nop 0
	global_load_dword v50, v[50:51], off
	s_nop 0
	global_load_dword v51, v[52:53], off offset:-4096
	s_nop 0
	global_load_dword v52, v[52:53], off
	s_nop 0
	global_load_dword v53, v[54:55], off offset:-4096
	s_nop 0
	global_load_dword v54, v[54:55], off
	s_nop 0
	global_load_dword v55, v[56:57], off offset:-4096
	s_nop 0
	global_load_dword v56, v[56:57], off
	s_nop 0
	global_load_dword v57, v[58:59], off offset:-4096
	s_nop 0
	global_load_dword v58, v[58:59], off
	s_nop 0
	global_load_dword v59, v[60:61], off offset:-4096
	s_nop 0
	global_load_dword v60, v[60:61], off
	s_nop 0
	global_load_dword v61, v[62:63], off offset:-4096
	s_nop 0
	global_load_dword v62, v[62:63], off
	s_nop 0
	global_load_dword v63, v[64:65], off offset:-4096
	s_nop 0
	global_load_dword v64, v[64:65], off
	s_nop 0
	global_load_dword v65, v[66:67], off offset:-4096
	s_nop 0
	global_load_dword v66, v[66:67], off
	s_nop 0
	global_load_dword v67, v[68:69], off offset:-4096
	s_nop 0
	global_load_dword v68, v[68:69], off
	s_nop 0
	global_load_dword v69, v[70:71], off offset:-4096
	s_nop 0
	global_load_dword v70, v[70:71], off
	s_nop 0
	global_load_dword v71, v[72:73], off offset:-4096
	s_nop 0
	global_load_dword v72, v[72:73], off
	s_nop 0
	global_load_dword v73, v[80:81], off offset:-4096
	s_nop 0
	global_load_dword v80, v[80:81], off
	s_nop 0
	global_load_dword v81, v[82:83], off offset:-4096
	s_nop 0
	global_load_dword v82, v[82:83], off
	s_nop 0
	global_load_dword v83, v[84:85], off offset:-4096
	s_nop 0
	global_load_dword v84, v[84:85], off
	s_nop 0
	global_load_dword v85, v[86:87], off offset:-4096
	s_nop 0
	global_load_dword v86, v[86:87], off
	s_nop 0
	global_load_dword v87, v[88:89], off offset:-4096
	s_nop 0
	global_load_dword v88, v[88:89], off
	s_nop 0
	global_load_dword v89, v[90:91], off offset:-4096
	s_nop 0
	global_load_dword v90, v[90:91], off
	s_nop 0
	global_load_dword v91, v[92:93], off offset:-4096
	s_nop 0
	global_load_dword v92, v[92:93], off
	s_nop 0
	global_load_dword v24, v[24:25], off
	s_waitcnt vmcnt(62)
	v_cvt_pk_bf16_f32 v25, v99, v100
	s_waitcnt vmcnt(60)
	v_cvt_pk_bf16_f32 v26, v26, v27
	s_waitcnt vmcnt(58)
	v_cvt_pk_bf16_f32 v27, v28, v29
	s_waitcnt vmcnt(56)
	v_cvt_pk_bf16_f32 v28, v30, v31
	s_waitcnt vmcnt(54)
	v_cvt_pk_bf16_f32 v29, v32, v33
	s_waitcnt vmcnt(52)
	v_cvt_pk_bf16_f32 v30, v34, v35
	s_waitcnt vmcnt(50)
	v_cvt_pk_bf16_f32 v31, v36, v37
	s_waitcnt vmcnt(48)
	v_cvt_pk_bf16_f32 v32, v38, v39
	s_waitcnt vmcnt(46)
	v_cvt_pk_bf16_f32 v33, v40, v41
	s_waitcnt vmcnt(44)
	v_cvt_pk_bf16_f32 v34, v42, v43
	s_waitcnt vmcnt(42)
	v_cvt_pk_bf16_f32 v35, v44, v45
	s_waitcnt vmcnt(40)
	v_cvt_pk_bf16_f32 v36, v46, v47
	s_waitcnt vmcnt(38)
	v_cvt_pk_bf16_f32 v37, v48, v49
	s_waitcnt vmcnt(36)
	v_cvt_pk_bf16_f32 v38, v50, v51
	s_waitcnt vmcnt(34)
	v_cvt_pk_bf16_f32 v39, v52, v53
	s_waitcnt vmcnt(32)
	v_cvt_pk_bf16_f32 v40, v54, v55
	s_waitcnt vmcnt(30)
	v_cvt_pk_bf16_f32 v41, v56, v57
	s_waitcnt vmcnt(28)
; #define LAS __attribute__((address_space(3)))
; __device__ __forceinline__ unsigned pk2(float lo, float hi) { f32x2 v = {lo, hi}; bf16x2_t b = __builtin_convertvector(v, bf16x2_t); return __builtin_bit_cast(unsigned, b); }
; __device__ __forceinline__ void transpose_item(const float* W, int K, int N, bf16_t* WT, const float* gk, int mode, LAS float* scr_, int item, int lane) {
;     ...
; #pragma unroll
;     for (int kp = 0; kp < 32; ++kp) {
;         float a = va[kp], b = vb[kp];
;         if (gk) { a *= gk[k0 + 2 * kp]; b *= gk[k0 + 2 * kp + 1]; }
;         scr[kp * 65 + lane] = pk2(a, b);
;     }
;     asm volatile("s_waitcnt lgkmcnt(0)" ::: "memory");
;     const int c = lane & 7;
; #pragma unroll
;     for (int j = 0; j < 8; ++j) { const int r = (lane >> 3) + 8 * j; const LAS unsigned* q = scr + (4 * c) * 65 + r;
;         u32x4 o; o.x = q[0]; o.y = q[65]; o.z = q[130]; o.w = q[195];
;         *(u32x4*)(WT + (size_t)(n0 + r) * K + k0 + 8 * c) = o; }
;     asm volatile("s_waitcnt lgkmcnt(0)" ::: "memory");
	v_cvt_pk_bf16_f32 v42, v58, v59
	s_waitcnt vmcnt(26)
	v_cvt_pk_bf16_f32 v43, v60, v61
	s_waitcnt vmcnt(24)
	v_cvt_pk_bf16_f32 v44, v62, v63
	s_waitcnt vmcnt(22)
	v_cvt_pk_bf16_f32 v45, v64, v65
	s_waitcnt vmcnt(20)
	v_cvt_pk_bf16_f32 v46, v66, v67
	s_waitcnt vmcnt(18)
	v_cvt_pk_bf16_f32 v47, v68, v69
	s_waitcnt vmcnt(16)
	v_cvt_pk_bf16_f32 v48, v70, v71
	s_waitcnt vmcnt(14)
	v_cvt_pk_bf16_f32 v49, v72, v73
	s_waitcnt vmcnt(12)
	v_cvt_pk_bf16_f32 v50, v80, v81
	s_waitcnt vmcnt(10)
	v_cvt_pk_bf16_f32 v51, v82, v83
	s_waitcnt vmcnt(8)
	v_cvt_pk_bf16_f32 v52, v84, v85
	s_waitcnt vmcnt(6)
	v_cvt_pk_bf16_f32 v53, v86, v87
	s_waitcnt vmcnt(4)
	v_cvt_pk_bf16_f32 v54, v88, v89
	s_waitcnt vmcnt(2)
	v_cvt_pk_bf16_f32 v55, v90, v91
	s_waitcnt vmcnt(0)
	v_cvt_pk_bf16_f32 v24, v92, v24
	ds_write2_b32 v77, v25, v26 offset1:65
	ds_write2_b32 v77, v27, v28 offset0:130 offset1:195
	ds_write2_b32 v23, v29, v30 offset0:4 offset1:69
	ds_write2_b32 v23, v31, v32 offset0:134 offset1:199
	ds_write2_b32 v79, v33, v34 offset0:8 offset1:73
	ds_write2_b32 v79, v35, v36 offset0:138 offset1:203
	ds_write2_b32 v94, v37, v38 offset0:12 offset1:77
	ds_write2_b32 v94, v39, v40 offset0:142 offset1:207
	ds_write2_b32 v95, v41, v42 offset0:16 offset1:81
	ds_write2_b32 v95, v43, v44 offset0:146 offset1:211
	ds_write2_b32 v96, v45, v46 offset0:20 offset1:85
	ds_write2_b32 v96, v47, v48 offset0:150 offset1:215
	ds_write2_b32 v97, v49, v50 offset0:24 offset1:89
	ds_write2_b32 v97, v51, v52 offset0:154 offset1:219
	ds_write2_b32 v98, v53, v54 offset0:28 offset1:93
	ds_write2_b32 v98, v55, v24 offset0:158 offset1:223
	s_waitcnt lgkmcnt(0)
	ds_read2_b32 v[24:25], v3 offset0:65 offset1:73
	ds_read2_b32 v[44:45], v3 offset0:130 offset1:138
	ds_read2_b32 v[26:27], v3 offset0:195 offset1:203
	ds_read2_b32 v[46:47], v3 offset1:8
	ds_read2_b32 v[48:49], v3 offset0:16 offset1:24
	ds_read2_b32 v[28:29], v3 offset0:81 offset1:89
	ds_read2_b32 v[50:51], v3 offset0:146 offset1:154
	ds_read2_b32 v[30:31], v3 offset0:211 offset1:219
	ds_read2_b32 v[32:33], v3 offset0:97 offset1:105
	ds_read2_b32 v[52:53], v3 offset0:162 offset1:170
	ds_read2_b32 v[34:35], v3 offset0:227 offset1:235
	ds_read2_b32 v[54:55], v3 offset0:32 offset1:40
	ds_read2_b32 v[56:57], v3 offset0:48 offset1:56
	ds_read2_b32 v[36:37], v3 offset0:113 offset1:121
	ds_read2_b32 v[58:59], v3 offset0:178 offset1:186
	ds_read2_b32 v[38:39], v3 offset0:243 offset1:251
	s_waitcnt lgkmcnt(12)
	v_mov_b32_e32 v40, v46
	v_mov_b32_e32 v41, v24
	v_mov_b32_e32 v42, v44
	v_mov_b32_e32 v43, v26
	v_mov_b32_e32 v24, v47
	v_mov_b32_e32 v26, v45
	s_waitcnt lgkmcnt(11)
	v_mov_b32_e32 v44, v48
	s_waitcnt lgkmcnt(10)
	v_mov_b32_e32 v45, v28
	s_waitcnt lgkmcnt(9)
	v_mov_b32_e32 v46, v50
	s_waitcnt lgkmcnt(8)
	v_mov_b32_e32 v47, v30
	v_mov_b32_e32 v28, v49
	v_mov_b32_e32 v30, v51
	s_waitcnt lgkmcnt(4)
	v_mov_b32_e32 v48, v54
	v_mov_b32_e32 v49, v32
	v_mov_b32_e32 v50, v52
	v_mov_b32_e32 v51, v34
	v_mov_b32_e32 v32, v55
	v_mov_b32_e32 v34, v53
	s_waitcnt lgkmcnt(3)
	v_mov_b32_e32 v52, v56
	s_waitcnt lgkmcnt(2)
	v_mov_b32_e32 v53, v36
	s_waitcnt lgkmcnt(1)
	v_mov_b32_e32 v54, v58
	s_waitcnt lgkmcnt(0)
	v_mov_b32_e32 v55, v38
	v_mov_b32_e32 v36, v57
	v_mov_b32_e32 v38, v59
	global_store_dwordx4 v[6:7], v[40:43], off
	global_store_dwordx4 v[8:9], v[24:27], off
	global_store_dwordx4 v[10:11], v[44:47], off
	global_store_dwordx4 v[12:13], v[28:31], off
	global_store_dwordx4 v[14:15], v[48:51], off
	global_store_dwordx4 v[16:17], v[32:35], off
	global_store_dwordx4 v[18:19], v[52:55], off
	global_store_dwordx4 v[20:21], v[36:39], off
	s_waitcnt lgkmcnt(0)
	s_cbranch_scc1 .LBB0_1008

; #define LAS __attribute__((address_space(3)))
; #define PIN(i) ((const float*)ldq_(L, (i)))
; __device__ __forceinline__ unsigned pk2(float lo, float hi) { f32x2 v = {lo, hi}; bf16x2_t b = __builtin_convertvector(v, bf16x2_t); return __builtin_bit_cast(unsigned, b); }
; #define PREP_CONV(bit, SRC, Kd, Nd, DST, GK, MODE) if (mask & (bit)) { for (int it = gw; it < ((Kd) / 64) * ((Nd) / 64); it += NGW) transpose_item((SRC), (Kd), (Nd), (bf16_t*)(wl + (DST)), (GK), (MODE), scr, it, lane); }
; __device__ __forceinline__ void transpose_item(const float* W, int K, int N, bf16_t* WT, const float* gk, int mode, LAS float* scr_, int item, int lane) {
;     LAS unsigned* scr = (LAS unsigned*)scr_;
;     const int nblk = N / 64, kb = item / nblk, nb = item % nblk, k0 = 64 * kb, n0 = 64 * nb;
;     const int sc = (mode == 1) ? (((n0 >> 7) & 1) * DFF + (n0 >> 8) * 128 + (n0 & 127)) : n0;
;     const float* src = W + (size_t)k0 * N + sc + lane;
;     float va[32], vb[32];
; #pragma unroll
;     for (int kp = 0; kp < 32; ++kp) { va[kp] = src[(size_t)(2 * kp) * N]; vb[kp] = src[(size_t)(2 * kp + 1) * N]; }
; #pragma unroll
;     for (int kp = 0; kp < 32; ++kp) {
;         float a = va[kp], b = vb[kp];
;         if (gk) { a *= gk[k0 + 2 * kp]; b *= gk[k0 + 2 * kp + 1]; }
;         scr[kp * 65 + lane] = pk2(a, b);
;     }
; __device__ __forceinline__ void prep(const Params& p, LAS unsigned char* L, int wv, int vb, int nvb, int l, int mask) {
;     ...
;     PREP_CONV(PM_PEG, PIN(I_WPEG) + (size_t)l * DM * DM, DM, DM, WL_PEG, PIN(I_NPE) + l * DM, 0)
.LBB0_1012:
	v_mov_b32_e32 v6, v161
	s_nop 0
	v_add_u32_e32 v6, 0, v6
	v_add_u32_e32 v6, 0x201b0, v6
	ds_read_b64 v[6:7], v6
	s_waitcnt lgkmcnt(0)
	v_readfirstlane_b32 s5, v6
	v_mov_b32_e32 v6, v161
	v_readfirstlane_b32 s4, v7
	v_add_u32_e32 v6, 0, v6
	v_add_u32_e32 v6, 0x201a8, v6
	s_nop 0
	s_add_u32 s21, s5, s10
	s_addc_u32 s25, s4, s11
	s_waitcnt lgkmcnt(0)
	v_readlane_b32 s4, v251, 42
	v_readlane_b32 s5, v251, 43
	s_add_u32 s43, s4, s12
	s_addc_u32 s44, s5, s13
	s_ashr_i32 s18, s29, 31
	s_lshr_b32 s18, s18, 28
	s_add_i32 s18, s29, s18
	s_ashr_i32 s19, s18, 4
	s_lshl_b32 s18, s19, 6
	s_lshl_b32 s42, s19, 10
	s_ashr_i32 s19, s18, 31
	s_sub_i32 s24, s15, s42
	s_lshl_b64 s[30:31], s[18:19], 12
	s_add_u32 s21, s21, s30
	s_addc_u32 s26, s25, s31
	s_ashr_i32 s25, s24, 31
	s_lshl_b64 s[24:25], s[24:25], 2
	s_add_u32 s24, s21, s24
	s_addc_u32 s25, s26, s25
	v_lshl_add_u64 v[70:71], s[24:25], 0, v[160:161]
	v_add_co_u32_e32 v6, vcc, s79, v70
	global_load_dword v66, v160, s[24:25]
	s_nop 0
	v_addc_co_u32_e32 v7, vcc, 0, v71, vcc
	global_load_dword v67, v[6:7], off offset:-4096
	global_load_dword v68, v[6:7], off
	v_add_co_u32_e32 v6, vcc, s88, v70
	s_mov_b32 s21, 0x3d000
	s_nop 0
	v_addc_co_u32_e32 v7, vcc, 0, v71, vcc
	global_load_dword v69, v[6:7], off offset:-4096
	global_load_dword v62, v[6:7], off
	v_add_co_u32_e32 v6, vcc, s80, v70
	s_cmp_lg_u64 s[4:5], 0
	s_nop 0
	v_addc_co_u32_e32 v7, vcc, 0, v71, vcc
	global_load_dword v63, v[6:7], off offset:-4096
	global_load_dword v64, v[6:7], off
	v_add_co_u32_e32 v6, vcc, s70, v70
	s_mov_b64 s[30:31], -1
	s_nop 0
	v_addc_co_u32_e32 v7, vcc, 0, v71, vcc
	global_load_dword v65, v[6:7], off offset:-4096
	global_load_dword v58, v[6:7], off
	v_add_co_u32_e32 v6, vcc, s71, v70
	s_cselect_b64 s[24:25], -1, 0
	s_nop 0
	v_addc_co_u32_e32 v7, vcc, 0, v71, vcc
	global_load_dword v59, v[6:7], off offset:-4096
	global_load_dword v60, v[6:7], off
	v_add_co_u32_e32 v6, vcc, s91, v70
	s_cmp_eq_u64 s[4:5], 0
	s_nop 0
	v_addc_co_u32_e32 v7, vcc, 0, v71, vcc
	global_load_dword v61, v[6:7], off offset:-4096
	global_load_dword v54, v[6:7], off
	v_add_co_u32_e32 v6, vcc, s92, v70
	s_nop 1
	v_addc_co_u32_e32 v7, vcc, 0, v71, vcc
	global_load_dword v55, v[6:7], off offset:-4096
	global_load_dword v56, v[6:7], off
	v_add_co_u32_e32 v6, vcc, s37, v70
	s_nop 1
	v_addc_co_u32_e32 v7, vcc, 0, v71, vcc
	global_load_dword v57, v[6:7], off offset:-4096
	global_load_dword v50, v[6:7], off
	v_add_co_u32_e32 v6, vcc, s94, v70
	s_nop 1
	v_addc_co_u32_e32 v7, vcc, 0, v71, vcc
	global_load_dword v51, v[6:7], off offset:-4096
	global_load_dword v52, v[6:7], off
	v_add_co_u32_e32 v6, vcc, s46, v70
	s_nop 1
	v_addc_co_u32_e32 v7, vcc, 0, v71, vcc
	global_load_dword v53, v[6:7], off offset:-4096
	global_load_dword v46, v[6:7], off
	v_add_co_u32_e32 v6, vcc, s47, v70
	s_nop 1
	v_addc_co_u32_e32 v7, vcc, 0, v71, vcc
	global_load_dword v47, v[6:7], off offset:-4096
	global_load_dword v48, v[6:7], off
	v_add_co_u32_e32 v6, vcc, s59, v70
	s_nop 1
	v_addc_co_u32_e32 v7, vcc, 0, v71, vcc
	global_load_dword v49, v[6:7], off offset:-4096
	global_load_dword v42, v[6:7], off
	v_add_co_u32_e32 v6, vcc, s81, v70
	s_nop 1
	v_addc_co_u32_e32 v7, vcc, 0, v71, vcc
	global_load_dword v43, v[6:7], off offset:-4096
	global_load_dword v44, v[6:7], off
	v_add_co_u32_e32 v6, vcc, s83, v70
	s_nop 1
	v_addc_co_u32_e32 v7, vcc, 0, v71, vcc
	global_load_dword v45, v[6:7], off offset:-4096
	global_load_dword v38, v[6:7], off
	v_add_co_u32_e32 v6, vcc, s27, v70
	s_nop 1
	v_addc_co_u32_e32 v7, vcc, 0, v71, vcc
	global_load_dword v39, v[6:7], off offset:-4096
	global_load_dword v40, v[6:7], off
	v_add_co_u32_e32 v6, vcc, s50, v70
	s_nop 1
	v_addc_co_u32_e32 v7, vcc, 0, v71, vcc
	global_load_dword v41, v[6:7], off offset:-4096
	global_load_dword v34, v[6:7], off
	v_add_co_u32_e32 v6, vcc, s53, v70
	s_nop 1
	v_addc_co_u32_e32 v7, vcc, 0, v71, vcc
	global_load_dword v35, v[6:7], off offset:-4096
	global_load_dword v36, v[6:7], off
	v_add_co_u32_e32 v6, vcc, s0, v70
	s_nop 1
	v_addc_co_u32_e32 v7, vcc, 0, v71, vcc
	global_load_dword v37, v[6:7], off offset:-4096
	global_load_dword v30, v[6:7], off
	v_add_co_u32_e32 v6, vcc, s73, v70
	s_nop 1
	v_addc_co_u32_e32 v7, vcc, 0, v71, vcc
	global_load_dword v31, v[6:7], off offset:-4096
	global_load_dword v32, v[6:7], off
	v_add_co_u32_e32 v6, vcc, s1, v70
	s_nop 1
	v_addc_co_u32_e32 v7, vcc, 0, v71, vcc
	global_load_dword v33, v[6:7], off offset:-4096
	global_load_dword v26, v[6:7], off
	v_add_co_u32_e32 v6, vcc, s72, v70
	s_nop 1
	v_addc_co_u32_e32 v7, vcc, 0, v71, vcc
	global_load_dword v27, v[6:7], off offset:-4096
	global_load_dword v28, v[6:7], off
	v_add_co_u32_e32 v6, vcc, s82, v70
	s_nop 1
	v_addc_co_u32_e32 v7, vcc, 0, v71, vcc
	global_load_dword v29, v[6:7], off offset:-4096
	global_load_dword v22, v[6:7], off
	v_add_co_u32_e32 v6, vcc, s33, v70
	s_nop 1
	v_addc_co_u32_e32 v7, vcc, 0, v71, vcc
	global_load_dword v23, v[6:7], off offset:-4096
	global_load_dword v24, v[6:7], off
	v_add_co_u32_e32 v6, vcc, s22, v70
	s_nop 1
	v_addc_co_u32_e32 v7, vcc, 0, v71, vcc
	global_load_dword v25, v[6:7], off offset:-4096
	global_load_dword v18, v[6:7], off
	v_add_co_u32_e32 v6, vcc, s38, v70
	s_nop 1
	v_addc_co_u32_e32 v7, vcc, 0, v71, vcc
	global_load_dword v19, v[6:7], off offset:-4096
	global_load_dword v20, v[6:7], off
	v_add_co_u32_e32 v6, vcc, s39, v70
	s_nop 1
	v_addc_co_u32_e32 v7, vcc, 0, v71, vcc
	global_load_dword v21, v[6:7], off offset:-4096
	global_load_dword v14, v[6:7], off
	v_add_co_u32_e32 v6, vcc, s56, v70
	s_nop 1
	v_addc_co_u32_e32 v7, vcc, 0, v71, vcc
	global_load_dword v15, v[6:7], off offset:-4096
	global_load_dword v16, v[6:7], off
	v_add_co_u32_e32 v6, vcc, s69, v70
	s_nop 1
	v_addc_co_u32_e32 v7, vcc, 0, v71, vcc
	v_add_co_u32_e32 v8, vcc, s87, v70
	global_load_dword v17, v[6:7], off offset:-4096
	s_nop 0
	global_load_dword v6, v[6:7], off
	v_addc_co_u32_e32 v9, vcc, 0, v71, vcc
	global_load_dword v7, v[8:9], off offset:-4096
	global_load_dword v12, v[8:9], off
	v_add_co_u32_e32 v8, vcc, 0x3b000, v70
	s_nop 1
	v_addc_co_u32_e32 v9, vcc, 0, v71, vcc
	v_add_co_u32_e32 v10, vcc, s21, v70
	global_load_dword v13, v[8:9], off
	s_nop 0
	v_addc_co_u32_e32 v11, vcc, 0, v71, vcc
	global_load_dword v8, v[10:11], off offset:-4096
	global_load_dword v9, v[10:11], off
	v_add_co_u32_e32 v10, vcc, 0x3e000, v70
	s_nop 1
	v_addc_co_u32_e32 v11, vcc, 0, v71, vcc
	v_add_co_u32_e32 v70, vcc, 0x3f000, v70
	global_load_dword v10, v[10:11], off
	s_nop 0
	v_addc_co_u32_e32 v71, vcc, 0, v71, vcc
	global_load_dword v11, v[70:71], off
	s_cbranch_scc1 .LBB0_1014
	s_lshl_b64 s[4:5], s[18:19], 2
	s_add_u32 s4, s43, s4
	s_addc_u32 s5, s44, s5
	global_load_dwordx4 v[70:73], v161, s[4:5]
	s_mov_b64 s[30:31], 0
	s_waitcnt vmcnt(0)
	v_pk_mul_f32 v[70:71], v[66:67], v[70:71]
	v_pk_mul_f32 v[72:73], v[68:69], v[72:73]

; #define LAS __attribute__((address_space(3)))
; #define PIN(i) ((const float*)ldq_(L, (i)))
; #define PREP_CONV(bit, SRC, Kd, Nd, DST, GK, MODE) if (mask & (bit)) { for (int it = gw; it < ((Kd) / 64) * ((Nd) / 64); it += NGW) transpose_item((SRC), (Kd), (Nd), (bf16_t*)(wl + (DST)), (GK), (MODE), scr, it, lane); }
; __device__ __forceinline__ void transpose_item(const float* W, int K, int N, bf16_t* WT, const float* gk, int mode, LAS float* scr_, int item, int lane) {
;     LAS unsigned* scr = (LAS unsigned*)scr_;
;     const int nblk = N / 64, kb = item / nblk, nb = item % nblk, k0 = 64 * kb, n0 = 64 * nb;
;     const int sc = (mode == 1) ? (((n0 >> 7) & 1) * DFF + (n0 >> 8) * 128 + (n0 & 127)) : n0;
;     const float* src = W + (size_t)k0 * N + sc + lane;
;     float va[32], vb[32];
; #pragma unroll
;     for (int kp = 0; kp < 32; ++kp) { va[kp] = src[(size_t)(2 * kp) * N]; vb[kp] = src[(size_t)(2 * kp + 1) * N]; }
; __device__ __forceinline__ void prep(const Params& p, LAS unsigned char* L, int wv, int vb, int nvb, int l, int mask) {
;     ...
;     PREP_CONV(PM_PEU, PIN(I_WPEU) + (size_t)l * PED * DM, PED, DM, WL_PEU, nullptr, 0)
.LBB0_1078:
	v_mov_b32_e32 v0, v161
	v_add_u32_e32 v19, 0x400, v77
	v_add_u32_e32 v0, 0, v0
	v_add_u32_e32 v0, 0x201b8, v0
	s_nop 0
	v_add_u32_e32 v88, 0x800, v77
	v_add_u32_e32 v89, 0xc00, v77
	v_add_u32_e32 v90, 0x1000, v77
	v_add_u32_e32 v91, 0x1400, v77
	s_waitcnt lgkmcnt(0)
	v_readlane_b32 s11, v251, 46
	v_readlane_b32 s10, v251, 47
	s_add_u32 s11, s11, s4
	s_addc_u32 s15, s10, s5
	s_ashr_i32 s10, s41, 31
	s_lshr_b32 s10, s10, 28
	s_add_i32 s10, s41, s10
	s_ashr_i32 s10, s10, 4
	s_lshl_b32 s18, s10, 6
	s_lshl_b32 s10, s10, 10
	s_ashr_i32 s19, s18, 31
	s_sub_i32 s10, s14, s10
	s_lshl_b64 s[12:13], s[18:19], 12
	s_add_u32 s12, s11, s12
	v_add_u32_e32 v0, s10, v76
	s_addc_u32 s13, s15, s13
	s_ashr_i32 s11, s10, 31
	v_add_u32_e32 v4, 8, v0
	v_add_u32_e32 v6, 16, v0
	v_add_u32_e32 v8, 24, v0
	v_add_u32_e32 v10, 32, v0
	v_add_u32_e32 v12, 40, v0
	v_add_u32_e32 v14, 48, v0
	v_add_u32_e32 v20, 56, v0
	s_lshl_b64 s[10:11], s[10:11], 2
	v_ashrrev_i32_e32 v1, 31, v0
	v_ashrrev_i32_e32 v5, 31, v4
	v_ashrrev_i32_e32 v7, 31, v6
	v_ashrrev_i32_e32 v9, 31, v8
	v_ashrrev_i32_e32 v11, 31, v10
	v_ashrrev_i32_e32 v13, 31, v12
	v_ashrrev_i32_e32 v15, 31, v14
	v_ashrrev_i32_e32 v21, 31, v20
	s_add_u32 s12, s12, s10
	v_lshl_add_u64 v[16:17], s[18:19], 1, v[2:3]
	v_lshlrev_b64 v[0:1], 9, v[0:1]
	v_lshlrev_b64 v[4:5], 9, v[4:5]
	v_lshlrev_b64 v[6:7], 9, v[6:7]
	v_lshlrev_b64 v[8:9], 9, v[8:9]
	v_lshlrev_b64 v[10:11], 9, v[10:11]
	v_lshlrev_b64 v[12:13], 9, v[12:13]
	v_lshlrev_b64 v[14:15], 9, v[14:15]
	v_lshlrev_b64 v[20:21], 9, v[20:21]
	s_addc_u32 s13, s13, s11
	v_lshl_add_u64 v[0:1], v[16:17], 0, v[0:1]
	v_lshl_add_u64 v[4:5], v[16:17], 0, v[4:5]
	v_lshl_add_u64 v[6:7], v[16:17], 0, v[6:7]
	v_lshl_add_u64 v[8:9], v[16:17], 0, v[8:9]
	v_lshl_add_u64 v[10:11], v[16:17], 0, v[10:11]
	v_lshl_add_u64 v[12:13], v[16:17], 0, v[12:13]
	v_lshl_add_u64 v[14:15], v[16:17], 0, v[14:15]
	v_lshl_add_u64 v[16:17], v[16:17], 0, v[20:21]
	v_lshl_add_u64 v[20:21], s[12:13], 0, v[160:161]
	v_add_co_u32_e32 v22, vcc, s79, v20
	global_load_dword v94, v160, s[12:13]
	s_nop 0
	v_addc_co_u32_e32 v23, vcc, 0, v21, vcc
	v_add_co_u32_e32 v24, vcc, s88, v20
	v_add_u32_e32 v92, 0x1800, v77
	s_nop 0
	v_addc_co_u32_e32 v25, vcc, 0, v21, vcc
	v_add_co_u32_e32 v26, vcc, s80, v20
	v_add_u32_e32 v93, 0x1c00, v77
	s_nop 0
	v_addc_co_u32_e32 v27, vcc, 0, v21, vcc
	v_add_co_u32_e32 v28, vcc, s70, v20
	s_add_i32 s10, s41, 0x700
	s_nop 0
	v_addc_co_u32_e32 v29, vcc, 0, v21, vcc
	v_add_co_u32_e32 v30, vcc, s71, v20
	s_add_i32 s14, s14, 0x1c000
	s_nop 0
	v_addc_co_u32_e32 v31, vcc, 0, v21, vcc
	v_add_co_u32_e32 v32, vcc, s91, v20
	s_cmpk_lt_i32 s41, 0xf940
	s_nop 0
	v_addc_co_u32_e32 v33, vcc, 0, v21, vcc
	v_add_co_u32_e32 v34, vcc, s92, v20
	s_mov_b32 s41, s10
	s_nop 0
	v_addc_co_u32_e32 v35, vcc, 0, v21, vcc
	v_add_co_u32_e32 v36, vcc, s37, v20
	s_nop 1
	v_addc_co_u32_e32 v37, vcc, 0, v21, vcc
	v_add_co_u32_e32 v38, vcc, s94, v20
	s_nop 1
	v_addc_co_u32_e32 v39, vcc, 0, v21, vcc
	v_add_co_u32_e32 v40, vcc, s46, v20
	s_nop 1
	v_addc_co_u32_e32 v41, vcc, 0, v21, vcc
	v_add_co_u32_e32 v42, vcc, s47, v20
	s_nop 1
	v_addc_co_u32_e32 v43, vcc, 0, v21, vcc
	v_add_co_u32_e32 v44, vcc, s59, v20
	s_nop 1
	v_addc_co_u32_e32 v45, vcc, 0, v21, vcc
	v_add_co_u32_e32 v46, vcc, s81, v20
	s_nop 1
	v_addc_co_u32_e32 v47, vcc, 0, v21, vcc
	v_add_co_u32_e32 v48, vcc, s83, v20
	s_waitcnt vmcnt(13)
	s_nop 0
	v_addc_co_u32_e32 v49, vcc, 0, v21, vcc
	s_waitcnt vmcnt(12)
	v_add_co_u32_e32 v50, vcc, s27, v20
	s_waitcnt vmcnt(11)
	s_nop 0
	v_addc_co_u32_e32 v51, vcc, 0, v21, vcc
	v_add_co_u32_e32 v52, vcc, s50, v20
	s_nop 1
	v_addc_co_u32_e32 v53, vcc, 0, v21, vcc
	v_add_co_u32_e32 v54, vcc, s53, v20
	s_nop 1
	v_addc_co_u32_e32 v55, vcc, 0, v21, vcc
	v_add_co_u32_e32 v56, vcc, s0, v20
	s_nop 1
	v_addc_co_u32_e32 v57, vcc, 0, v21, vcc
	v_add_co_u32_e32 v58, vcc, s73, v20
	s_nop 1
	v_addc_co_u32_e32 v59, vcc, 0, v21, vcc
	v_add_co_u32_e32 v60, vcc, s1, v20
	s_nop 1
	v_addc_co_u32_e32 v61, vcc, 0, v21, vcc
	v_add_co_u32_e32 v62, vcc, s72, v20
	s_nop 1
	v_addc_co_u32_e32 v63, vcc, 0, v21, vcc
	v_add_co_u32_e32 v64, vcc, s82, v20
	s_nop 1
	v_addc_co_u32_e32 v65, vcc, 0, v21, vcc
	s_waitcnt vmcnt(10)
	v_add_co_u32_e32 v66, vcc, s33, v20
	s_nop 1
	v_addc_co_u32_e32 v67, vcc, 0, v21, vcc
	v_add_co_u32_e32 v68, vcc, s22, v20
	s_nop 1
	v_addc_co_u32_e32 v69, vcc, 0, v21, vcc
	v_add_co_u32_e32 v70, vcc, s38, v20
	s_nop 1
	v_addc_co_u32_e32 v71, vcc, 0, v21, vcc
	v_add_co_u32_e32 v72, vcc, s39, v20
	s_nop 1
	v_addc_co_u32_e32 v73, vcc, 0, v21, vcc
	v_add_co_u32_e32 v78, vcc, s56, v20
	s_nop 1
	v_addc_co_u32_e32 v79, vcc, 0, v21, vcc
	v_add_co_u32_e32 v80, vcc, s69, v20
	s_nop 1
	v_addc_co_u32_e32 v81, vcc, 0, v21, vcc
	v_add_co_u32_e32 v82, vcc, s87, v20
	s_nop 1
	v_addc_co_u32_e32 v83, vcc, 0, v21, vcc
	v_add_co_u32_e32 v84, vcc, s90, v20
	s_nop 1
	v_addc_co_u32_e32 v85, vcc, 0, v21, vcc
	v_add_co_u32_e32 v86, vcc, s51, v20
	s_nop 1
	v_addc_co_u32_e32 v87, vcc, 0, v21, vcc
	v_add_co_u32_e32 v20, vcc, s52, v20
	s_nop 1
	v_addc_co_u32_e32 v21, vcc, 0, v21, vcc
	global_load_dword v95, v[22:23], off offset:-4096
	s_nop 0
	global_load_dword v22, v[22:23], off
	s_nop 0
	global_load_dword v23, v[24:25], off offset:-4096
	s_nop 0
	global_load_dword v24, v[24:25], off
	s_nop 0
	global_load_dword v25, v[26:27], off offset:-4096
	s_nop 0
	global_load_dword v26, v[26:27], off
	s_nop 0
	global_load_dword v27, v[28:29], off offset:-4096
	s_nop 0
	global_load_dword v28, v[28:29], off
	s_nop 0
	global_load_dword v29, v[30:31], off offset:-4096
	s_nop 0
	global_load_dword v30, v[30:31], off
	s_nop 0
	global_load_dword v31, v[32:33], off offset:-4096
; __device__ __forceinline__ unsigned pk2(float lo, float hi) { f32x2 v = {lo, hi}; bf16x2_t b = __builtin_convertvector(v, bf16x2_t); return __builtin_bit_cast(unsigned, b); }
; __device__ __forceinline__ void transpose_item(const float* W, int K, int N, bf16_t* WT, const float* gk, int mode, LAS float* scr_, int item, int lane) {
;     ...
;     for (int kp = 0; kp < 32; ++kp) { va[kp] = src[(size_t)(2 * kp) * N]; vb[kp] = src[(size_t)(2 * kp + 1) * N]; }
; #pragma unroll
;     for (int kp = 0; kp < 32; ++kp) {
;         float a = va[kp], b = vb[kp];
;         if (gk) { a *= gk[k0 + 2 * kp]; b *= gk[k0 + 2 * kp + 1]; }
;         scr[kp * 65 + lane] = pk2(a, b);
	s_nop 0
	global_load_dword v32, v[32:33], off
	s_nop 0
	global_load_dword v33, v[34:35], off offset:-4096
	s_nop 0
	global_load_dword v34, v[34:35], off
	s_nop 0
	global_load_dword v35, v[36:37], off offset:-4096
	s_nop 0
	global_load_dword v36, v[36:37], off
	s_nop 0
	global_load_dword v37, v[38:39], off offset:-4096
	s_nop 0
	global_load_dword v38, v[38:39], off
	s_nop 0
	global_load_dword v39, v[40:41], off offset:-4096
	s_nop 0
	global_load_dword v40, v[40:41], off
	s_nop 0
	global_load_dword v41, v[42:43], off offset:-4096
	s_nop 0
	global_load_dword v42, v[42:43], off
	s_nop 0
	global_load_dword v43, v[44:45], off offset:-4096
	s_nop 0
	global_load_dword v44, v[44:45], off
	s_nop 0
	global_load_dword v45, v[46:47], off offset:-4096
	s_nop 0
	global_load_dword v46, v[46:47], off
	s_nop 0
	global_load_dword v47, v[48:49], off offset:-4096
	s_nop 0
	global_load_dword v48, v[48:49], off
	s_nop 0
	global_load_dword v49, v[50:51], off offset:-4096
	s_nop 0
	global_load_dword v50, v[50:51], off
	s_nop 0
	global_load_dword v51, v[52:53], off offset:-4096
	s_nop 0
	global_load_dword v52, v[52:53], off
	s_nop 0
	global_load_dword v53, v[54:55], off offset:-4096
	s_nop 0
	global_load_dword v54, v[54:55], off
	s_nop 0
	global_load_dword v55, v[56:57], off offset:-4096
	s_nop 0
	global_load_dword v56, v[56:57], off
	s_nop 0
	global_load_dword v57, v[58:59], off offset:-4096
	s_nop 0
	global_load_dword v58, v[58:59], off
	s_nop 0
	global_load_dword v59, v[60:61], off offset:-4096
	s_nop 0
	global_load_dword v60, v[60:61], off
	s_nop 0
	global_load_dword v61, v[62:63], off offset:-4096
	s_nop 0
	global_load_dword v62, v[62:63], off
	s_nop 0
	global_load_dword v63, v[64:65], off offset:-4096
	s_nop 0
	global_load_dword v64, v[64:65], off
	s_nop 0
	global_load_dword v65, v[66:67], off offset:-4096
	s_nop 0
	global_load_dword v66, v[66:67], off
	s_nop 0
	global_load_dword v67, v[68:69], off offset:-4096
	s_nop 0
	global_load_dword v68, v[68:69], off
	s_nop 0
	global_load_dword v69, v[70:71], off offset:-4096
	s_nop 0
	global_load_dword v70, v[70:71], off
	s_nop 0
	global_load_dword v71, v[72:73], off offset:-4096
	s_nop 0
	global_load_dword v72, v[72:73], off
	s_nop 0
	global_load_dword v73, v[78:79], off offset:-4096
	s_nop 0
	global_load_dword v78, v[78:79], off
	s_nop 0
	global_load_dword v79, v[80:81], off offset:-4096
	s_nop 0
	global_load_dword v80, v[80:81], off
	s_nop 0
	global_load_dword v81, v[82:83], off offset:-4096
	s_nop 0
	global_load_dword v82, v[82:83], off
	s_nop 0
	global_load_dword v83, v[84:85], off offset:-4096
	s_nop 0
	global_load_dword v84, v[84:85], off
	s_nop 0
	global_load_dword v85, v[86:87], off offset:-4096
	s_nop 0
	global_load_dword v86, v[86:87], off
	s_nop 0
	global_load_dword v20, v[20:21], off
	s_waitcnt vmcnt(62)
	v_cvt_pk_bf16_f32 v21, v94, v95
	s_waitcnt vmcnt(60)
	v_cvt_pk_bf16_f32 v22, v22, v23
	s_waitcnt vmcnt(58)
	v_cvt_pk_bf16_f32 v23, v24, v25
	s_waitcnt vmcnt(56)
	v_cvt_pk_bf16_f32 v24, v26, v27
	s_waitcnt vmcnt(54)
	v_cvt_pk_bf16_f32 v25, v28, v29
	s_waitcnt vmcnt(52)
	v_cvt_pk_bf16_f32 v26, v30, v31
	s_waitcnt vmcnt(50)
	v_cvt_pk_bf16_f32 v27, v32, v33
	s_waitcnt vmcnt(48)
	v_cvt_pk_bf16_f32 v28, v34, v35
	s_waitcnt vmcnt(46)
	v_cvt_pk_bf16_f32 v29, v36, v37
	s_waitcnt vmcnt(44)
	v_cvt_pk_bf16_f32 v30, v38, v39
	s_waitcnt vmcnt(42)
	v_cvt_pk_bf16_f32 v31, v40, v41
	s_waitcnt vmcnt(40)
	v_cvt_pk_bf16_f32 v32, v42, v43
	s_waitcnt vmcnt(38)
	v_cvt_pk_bf16_f32 v33, v44, v45
	s_waitcnt vmcnt(36)
	v_cvt_pk_bf16_f32 v34, v46, v47
	s_waitcnt vmcnt(34)
	v_cvt_pk_bf16_f32 v35, v48, v49
	s_waitcnt vmcnt(32)
	v_cvt_pk_bf16_f32 v36, v50, v51
	s_waitcnt vmcnt(30)
; #define LAS __attribute__((address_space(3)))
; __device__ __forceinline__ unsigned pk2(float lo, float hi) { f32x2 v = {lo, hi}; bf16x2_t b = __builtin_convertvector(v, bf16x2_t); return __builtin_bit_cast(unsigned, b); }
; __device__ __forceinline__ void transpose_item(const float* W, int K, int N, bf16_t* WT, const float* gk, int mode, LAS float* scr_, int item, int lane) {
;     ...
; #pragma unroll
;     for (int kp = 0; kp < 32; ++kp) {
;         float a = va[kp], b = vb[kp];
;         if (gk) { a *= gk[k0 + 2 * kp]; b *= gk[k0 + 2 * kp + 1]; }
;         scr[kp * 65 + lane] = pk2(a, b);
;     }
;     asm volatile("s_waitcnt lgkmcnt(0)" ::: "memory");
;     const int c = lane & 7;
; #pragma unroll
;     for (int j = 0; j < 8; ++j) { const int r = (lane >> 3) + 8 * j; const LAS unsigned* q = scr + (4 * c) * 65 + r;
;         u32x4 o; o.x = q[0]; o.y = q[65]; o.z = q[130]; o.w = q[195];
;         *(u32x4*)(WT + (size_t)(n0 + r) * K + k0 + 8 * c) = o; }
;     asm volatile("s_waitcnt lgkmcnt(0)" ::: "memory");
	v_cvt_pk_bf16_f32 v37, v52, v53
	s_waitcnt vmcnt(28)
	v_cvt_pk_bf16_f32 v38, v54, v55
	s_waitcnt vmcnt(26)
	v_cvt_pk_bf16_f32 v39, v56, v57
	s_waitcnt vmcnt(24)
	v_cvt_pk_bf16_f32 v40, v58, v59
	s_waitcnt vmcnt(22)
	v_cvt_pk_bf16_f32 v41, v60, v61
	s_waitcnt vmcnt(20)
	v_cvt_pk_bf16_f32 v42, v62, v63
	s_waitcnt vmcnt(18)
	v_cvt_pk_bf16_f32 v43, v64, v65
	s_waitcnt vmcnt(16)
	v_cvt_pk_bf16_f32 v44, v66, v67
	s_waitcnt vmcnt(14)
	v_cvt_pk_bf16_f32 v45, v68, v69
	s_waitcnt vmcnt(12)
	v_cvt_pk_bf16_f32 v46, v70, v71
	s_waitcnt vmcnt(10)
	v_cvt_pk_bf16_f32 v47, v72, v73
	s_waitcnt vmcnt(8)
	v_cvt_pk_bf16_f32 v48, v78, v79
	s_waitcnt vmcnt(6)
	v_cvt_pk_bf16_f32 v49, v80, v81
	s_waitcnt vmcnt(4)
	v_cvt_pk_bf16_f32 v50, v82, v83
	s_waitcnt vmcnt(2)
	v_cvt_pk_bf16_f32 v51, v84, v85
	s_waitcnt vmcnt(0)
	v_cvt_pk_bf16_f32 v20, v86, v20
	ds_write2_b32 v77, v21, v22 offset1:65
	ds_write2_b32 v77, v23, v24 offset0:130 offset1:195
	ds_write2_b32 v19, v25, v26 offset0:4 offset1:69
	ds_write2_b32 v19, v27, v28 offset0:134 offset1:199
	ds_write2_b32 v88, v29, v30 offset0:8 offset1:73
	ds_write2_b32 v88, v31, v32 offset0:138 offset1:203
	ds_write2_b32 v89, v33, v34 offset0:12 offset1:77
	ds_write2_b32 v89, v35, v36 offset0:142 offset1:207
	ds_write2_b32 v90, v37, v38 offset0:16 offset1:81
	ds_write2_b32 v90, v39, v40 offset0:146 offset1:211
	ds_write2_b32 v91, v41, v42 offset0:20 offset1:85
	ds_write2_b32 v91, v43, v44 offset0:150 offset1:215
	ds_write2_b32 v92, v45, v46 offset0:24 offset1:89
	ds_write2_b32 v92, v47, v48 offset0:154 offset1:219
	ds_write2_b32 v93, v49, v50 offset0:28 offset1:93
	ds_write2_b32 v93, v51, v20 offset0:158 offset1:223
	s_waitcnt lgkmcnt(0)
	ds_read2_b32 v[20:21], v18 offset0:65 offset1:73
	ds_read2_b32 v[40:41], v18 offset0:130 offset1:138
	ds_read2_b32 v[22:23], v18 offset0:195 offset1:203
	ds_read2_b32 v[42:43], v18 offset1:8
	ds_read2_b32 v[44:45], v18 offset0:16 offset1:24
	ds_read2_b32 v[24:25], v18 offset0:81 offset1:89
	ds_read2_b32 v[46:47], v18 offset0:146 offset1:154
	ds_read2_b32 v[26:27], v18 offset0:211 offset1:219
	ds_read2_b32 v[28:29], v18 offset0:97 offset1:105
	ds_read2_b32 v[48:49], v18 offset0:162 offset1:170
	ds_read2_b32 v[30:31], v18 offset0:227 offset1:235
	ds_read2_b32 v[50:51], v18 offset0:32 offset1:40
	ds_read2_b32 v[52:53], v18 offset0:48 offset1:56
	ds_read2_b32 v[32:33], v18 offset0:113 offset1:121
	ds_read2_b32 v[54:55], v18 offset0:178 offset1:186
	ds_read2_b32 v[34:35], v18 offset0:243 offset1:251
	s_waitcnt lgkmcnt(12)
	v_mov_b32_e32 v36, v42
	v_mov_b32_e32 v37, v20
	v_mov_b32_e32 v38, v40
	v_mov_b32_e32 v39, v22
	v_mov_b32_e32 v20, v43
	v_mov_b32_e32 v22, v41
	s_waitcnt lgkmcnt(11)
	v_mov_b32_e32 v40, v44
	s_waitcnt lgkmcnt(10)
	v_mov_b32_e32 v41, v24
	s_waitcnt lgkmcnt(9)
	v_mov_b32_e32 v42, v46
	s_waitcnt lgkmcnt(8)
	v_mov_b32_e32 v43, v26
	v_mov_b32_e32 v24, v45
	v_mov_b32_e32 v26, v47
	s_waitcnt lgkmcnt(4)
	v_mov_b32_e32 v44, v50
	v_mov_b32_e32 v45, v28
	v_mov_b32_e32 v46, v48
	v_mov_b32_e32 v47, v30
	v_mov_b32_e32 v28, v51
	v_mov_b32_e32 v30, v49
	s_waitcnt lgkmcnt(3)
	v_mov_b32_e32 v48, v52
	s_waitcnt lgkmcnt(2)
	v_mov_b32_e32 v49, v32
	s_waitcnt lgkmcnt(1)
	v_mov_b32_e32 v50, v54
	s_waitcnt lgkmcnt(0)
	v_mov_b32_e32 v51, v34
	v_mov_b32_e32 v32, v53
	v_mov_b32_e32 v34, v55
	global_store_dwordx4 v[0:1], v[36:39], off
	global_store_dwordx4 v[4:5], v[20:23], off
	global_store_dwordx4 v[6:7], v[40:43], off
	global_store_dwordx4 v[8:9], v[24:27], off
	global_store_dwordx4 v[10:11], v[44:47], off
	global_store_dwordx4 v[12:13], v[28:31], off
	global_store_dwordx4 v[14:15], v[48:51], off
	global_store_dwordx4 v[16:17], v[32:35], off
	s_waitcnt lgkmcnt(0)
	s_cbranch_scc1 .LBB0_1078

; #define PIN(i) ((const float*)ldq_(L, (i)))
; __device__ __forceinline__ unsigned pk2(float lo, float hi) { f32x2 v = {lo, hi}; bf16x2_t b = __builtin_convertvector(v, bf16x2_t); return __builtin_bit_cast(unsigned, b); }
; __device__ __forceinline__ void prep(const Params& p, LAS unsigned char* L, int wv, int vb, int nvb, int l, int mask) {
;     ...
;     if (mask & PM_POOL) {
;         for (int t = gt; t < 4 * 128 * 16; t += NGT) {
;             const int ko = t & 15, n = (t >> 4) & 127, g = (t >> 11) & 3;
;             const float* src = PIN(I_WPOOL) + ((size_t)(l * 4 + g) * 128 + 8 * ko) * 128 + n; const float sc = PIN(I_PSCALE)[l * 512 + g * 128 + n];
;             u32x4 o; o.x = pk2(src[0] * sc, src[128] * sc); o.y = pk2(src[256] * sc, src[384] * sc); o.z = pk2(src[512] * sc, src[640] * sc); o.w = pk2(src[768] * sc, src[896] * sc);
;             *(u32x4*)((bf16_t*)(wl + WL_POOL) + ((size_t)g * 128 + n) * 128 + 8 * ko) = o;
;         }
.LBB0_1081:
	v_mov_b32_e32 v2, v161
	v_add_u32_e32 v0, 0x1c000, v0
	v_add_u32_e32 v2, 0, v2
	v_add_u32_e32 v2, 0x20178, v2
	ds_read_b64 v[2:3], v2
	v_bfe_u32 v12, v0, 11, 2
	v_and_b32_e32 v13, 0x78, v1
	v_bfe_u32 v9, v0, 4, 7
	v_lshlrev_b32_e32 v160, 9, v13
	s_waitcnt lgkmcnt(0)
	v_readfirstlane_b32 s14, v2
	v_or_b32_e32 v2, s12, v12
	v_readfirstlane_b32 s15, v3
	v_ashrrev_i32_e32 v3, 31, v2
	v_lshlrev_b64 v[2:3], 16, v[2:3]
	v_lshl_add_u64 v[2:3], s[14:15], 0, v[2:3]
	v_lshl_add_u64 v[2:3], v[2:3], 0, v[160:161]
	v_lshlrev_b32_e32 v160, 2, v9
	v_lshl_add_u64 v[6:7], v[2:3], 0, v[160:161]
	v_mov_b32_e32 v2, v161
	v_lshlrev_b32_e32 v4, 7, v12
	v_add_u32_e32 v2, 0, v2
	v_add_u32_e32 v2, 0x20180, v2
	s_nop 0
	v_or3_b32 v4, v4, s13, v9
	v_ashrrev_i32_e32 v5, 31, v4
	v_cmp_lt_i32_e32 vcc, s18, v0
	v_add_u32_e32 v1, 0xe0000, v1
	s_waitcnt lgkmcnt(0)
	v_readlane_b32 s14, v251, 33
	v_readlane_b32 s15, v251, 32
	s_or_b64 s[10:11], vcc, s[10:11]
	v_mov_b32_e32 v3, s14
	v_mov_b32_e32 v2, s15
	v_lshl_add_u64 v[2:3], v[4:5], 2, v[2:3]
	global_load_dword v8, v[2:3], off
	s_nop 0
	global_load_dword v2, v[6:7], off
	global_load_dword v3, v[6:7], off offset:512
	global_load_dword v4, v[6:7], off offset:1024
	global_load_dword v5, v[6:7], off offset:1536
	s_waitcnt vmcnt(2)
	v_pk_mul_f32 v[2:3], v[8:9], v[2:3] op_sel_hi:[0,1]
	s_waitcnt vmcnt(0)
	v_pk_mul_f32 v[4:5], v[8:9], v[4:5] op_sel_hi:[0,1]
	v_cvt_pk_bf16_f32 v2, v2, v3
	v_cvt_pk_bf16_f32 v3, v4, v5
	global_load_dword v4, v[6:7], off offset:2048
	global_load_dword v5, v[6:7], off offset:2560
	global_load_dword v10, v[6:7], off offset:3072
	global_load_dword v11, v[6:7], off offset:3584
	s_waitcnt vmcnt(2)
	v_pk_mul_f32 v[4:5], v[8:9], v[4:5] op_sel_hi:[0,1]
	s_waitcnt vmcnt(0)
	v_pk_mul_f32 v[6:7], v[8:9], v[10:11] op_sel_hi:[0,1]
	v_cvt_pk_bf16_f32 v4, v4, v5
	v_cvt_pk_bf16_f32 v5, v6, v7
	v_lshlrev_b32_e32 v6, 8, v9
	v_lshl_or_b32 v160, v12, 15, v6
	v_lshl_add_u64 v[6:7], s[8:9], 0, v[160:161]
	v_lshlrev_b32_e32 v160, 1, v13
	v_lshl_add_u64 v[6:7], v[6:7], 0, v[160:161]
	global_store_dwordx4 v[6:7], v[2:5], off
	s_andn2_b64 exec, exec, s[10:11]
	s_cbranch_execnz .LBB0_1081

; #define PIN(i) ((const float*)ldq_(L, (i)))
; __device__ __forceinline__ void prep(const Params& p, LAS unsigned char* L, int wv, int vb, int nvb, int l, int mask) {
;     ...
;         for (int t0 = gt; t0 < MT * 32; t0 += 4 * NGT) {
;             f32x4 a[4], b[4]; size_t dsto[4];
; #pragma unroll
;             for (int u = 0; u < 4; ++u) {
;                 const int t = min(t0 + u * NGT, MT * 32 - 1);
;                 const int o8 = t & 31, m = t >> 5;
;                 const float* src = ((m < MP) ? PIN(I_PP) + ((size_t)l * MP + m) * PED : PIN(I_PS) + ((size_t)l * MS + (m - MP)) * PED) + 8 * o8;
;                 a[u] = *(const f32x4*)src; b[u] = *(const f32x4*)(src + 4); dsto[u] = (size_t)m * PED + 8 * o8;
;             }
.LBB0_1085:
	v_add_u32_e32 v37, 0x70000, v37
	v_ashrrev_i32_e32 v24, 5, v37
	v_cmp_lt_i32_e32 vcc, s57, v24
	s_and_saveexec_b64 s[14:15], vcc
	s_xor_b64 s[18:19], exec, s[14:15]
	s_cbranch_execz .LBB0_1087
	v_mov_b32_e32 v0, v161
	v_add_u32_e32 v160, 0xffff0000, v24
	v_add_u32_e32 v0, 0, v0
	v_add_u32_e32 v0, 0x20118, v0
	s_nop 0
	v_mov_b32_e32 v25, v161
	s_waitcnt lgkmcnt(0)
	v_readlane_b32 s14, v251, 6
	v_readlane_b32 s15, v251, 7
	s_add_u32 s14, s14, s10
	s_addc_u32 s15, s15, s11
	v_lshlrev_b64 v[0:1], 10, v[160:161]
	v_lshl_add_u64 v[0:1], s[14:15], 0, v[0:1]
.LBB0_1087:
	s_andn2_saveexec_b64 s[18:19], s[18:19]
	s_cbranch_execz .LBB0_1089
	v_mov_b32_e32 v0, v161
	v_ashrrev_i32_e32 v25, 31, v24
	v_add_u32_e32 v0, 0, v0
	v_add_u32_e32 v0, 0x20110, v0
	s_nop 0
	s_waitcnt lgkmcnt(0)
	v_readlane_b32 s14, v251, 4
	v_readlane_b32 s15, v251, 5
	s_add_u32 s14, s14, s6
	s_addc_u32 s15, s15, s7
	v_lshlrev_b64 v[0:1], 10, v[24:25]
	v_lshl_add_u64 v[0:1], s[14:15], 0, v[0:1]
.LBB0_1089:
	s_or_b64 exec, exec, s[18:19]
	v_and_b32_e32 v38, 0xf8, v36
	v_lshlrev_b32_e32 v160, 2, v38
	v_lshl_add_u64 v[4:5], v[0:1], 0, v[160:161]
	global_load_dwordx4 v[0:3], v[4:5], off offset:16
	s_nop 0
	global_load_dwordx4 v[4:7], v[4:5], off
	v_min_i32_e32 v10, 0x1f3fff, v37
	v_add_u32_e32 v8, 0x1c000, v10
	v_ashrrev_i32_e32 v26, 5, v8
	v_cmp_lt_i32_e32 vcc, s57, v26
	s_and_saveexec_b64 s[14:15], vcc
	s_xor_b64 s[18:19], exec, s[14:15]
	s_cbranch_execz .LBB0_1091
	v_mov_b32_e32 v8, v161
	v_add_u32_e32 v160, 0xffff0000, v26
	v_add_u32_e32 v8, 0, v8
	v_add_u32_e32 v8, 0x20118, v8
	s_nop 0
	v_mov_b32_e32 v27, v161
	s_waitcnt lgkmcnt(0)
	v_readlane_b32 s14, v251, 6
	v_readlane_b32 s15, v251, 7
	s_add_u32 s14, s14, s10
	s_addc_u32 s15, s15, s11
	v_lshlrev_b64 v[8:9], 10, v[160:161]
	v_lshl_add_u64 v[8:9], s[14:15], 0, v[8:9]
.LBB0_1091:
	s_andn2_saveexec_b64 s[18:19], s[18:19]
	s_cbranch_execz .LBB0_1093
	v_mov_b32_e32 v8, v161
	v_ashrrev_i32_e32 v27, 31, v26
	v_add_u32_e32 v8, 0, v8
	v_add_u32_e32 v8, 0x20110, v8
	s_nop 0
	s_waitcnt lgkmcnt(0)
	v_readlane_b32 s14, v251, 4
	v_readlane_b32 s15, v251, 5
	s_add_u32 s14, s14, s6
	s_addc_u32 s15, s15, s7
	v_lshlrev_b64 v[8:9], 10, v[26:27]
	v_lshl_add_u64 v[8:9], s[14:15], 0, v[8:9]
.LBB0_1093:
	s_or_b64 exec, exec, s[18:19]
	v_lshlrev_b32_e32 v10, 3, v10
	v_and_b32_e32 v39, 0xf8, v10
	v_lshlrev_b32_e32 v160, 2, v39
	v_lshl_add_u64 v[12:13], v[8:9], 0, v[160:161]
	global_load_dwordx4 v[8:11], v[12:13], off offset:16
	s_nop 0
	global_load_dwordx4 v[12:15], v[12:13], off
	v_min_i32_e32 v18, 0x1d7fff, v37
	v_add_u32_e32 v16, 0x38000, v18
	v_ashrrev_i32_e32 v28, 5, v16
	v_cmp_lt_i32_e32 vcc, s57, v28
	s_and_saveexec_b64 s[14:15], vcc
	s_xor_b64 s[18:19], exec, s[14:15]
	s_cbranch_execz .LBB0_1095
	v_mov_b32_e32 v16, v161
	v_add_u32_e32 v160, 0xffff0000, v28
	v_add_u32_e32 v16, 0, v16
	v_add_u32_e32 v16, 0x20118, v16
	s_nop 0
	v_mov_b32_e32 v29, v161
	s_waitcnt lgkmcnt(0)
	v_readlane_b32 s14, v251, 6
	v_readlane_b32 s15, v251, 7
	s_add_u32 s14, s14, s10
	s_addc_u32 s15, s15, s11
	v_lshlrev_b64 v[16:17], 10, v[160:161]
	v_lshl_add_u64 v[16:17], s[14:15], 0, v[16:17]
.LBB0_1095:
	s_andn2_saveexec_b64 s[18:19], s[18:19]
	s_cbranch_execz .LBB0_1097
	v_mov_b32_e32 v16, v161
	v_ashrrev_i32_e32 v29, 31, v28
	v_add_u32_e32 v16, 0, v16
	v_add_u32_e32 v16, 0x20110, v16
	s_nop 0
	s_waitcnt lgkmcnt(0)
	v_readlane_b32 s14, v251, 4
	v_readlane_b32 s15, v251, 5
	s_add_u32 s14, s14, s6
	s_addc_u32 s15, s15, s7
	v_lshlrev_b64 v[16:17], 10, v[28:29]
	v_lshl_add_u64 v[16:17], s[14:15], 0, v[16:17]
.LBB0_1097:
	s_or_b64 exec, exec, s[18:19]
	v_lshlrev_b32_e32 v18, 3, v18
	v_and_b32_e32 v40, 0xf8, v18
	v_lshlrev_b32_e32 v160, 2, v40
	v_lshl_add_u64 v[20:21], v[16:17], 0, v[160:161]
	global_load_dwordx4 v[16:19], v[20:21], off offset:16
	s_nop 0
	global_load_dwordx4 v[20:23], v[20:21], off
	v_min_i32_e32 v41, 0x1bbfff, v37
	v_add_u32_e32 v30, 0x54000, v41
	v_ashrrev_i32_e32 v30, 5, v30
	v_cmp_lt_i32_e32 vcc, s57, v30
	s_and_saveexec_b64 s[14:15], vcc
	s_xor_b64 s[18:19], exec, s[14:15]
	s_cbranch_execz .LBB0_1099
	v_mov_b32_e32 v31, v161
	v_add_u32_e32 v160, 0xffff0000, v30
	v_add_u32_e32 v31, 0, v31
	v_add_u32_e32 v31, 0x20118, v31
	s_nop 0
	v_mov_b32_e32 v31, v161
	s_waitcnt lgkmcnt(0)
	v_readlane_b32 s14, v251, 6
	v_readlane_b32 s15, v251, 7
	s_add_u32 s14, s14, s10
	s_addc_u32 s15, s15, s11
	v_lshlrev_b64 v[32:33], 10, v[160:161]
	v_lshl_add_u64 v[32:33], s[14:15], 0, v[32:33]
.LBB0_1099:
	s_andn2_saveexec_b64 s[18:19], s[18:19]
	s_cbranch_execz .LBB0_1084
	v_mov_b32_e32 v31, v161
	s_nop 0
	v_add_u32_e32 v31, 0, v31
	v_add_u32_e32 v31, 0x20110, v31
	s_nop 0
	v_ashrrev_i32_e32 v31, 31, v30
	s_waitcnt lgkmcnt(0)
	v_readlane_b32 s14, v251, 4
	v_readlane_b32 s15, v251, 5
	s_add_u32 s14, s14, s6
	s_addc_u32 s15, s15, s7
	v_lshlrev_b64 v[32:33], 10, v[30:31]
	v_lshl_add_u64 v[32:33], s[14:15], 0, v[32:33]
	s_branch .LBB0_1084

; __device__ __forceinline__ unsigned xb_ld(unsigned* p)              { return __hip_atomic_load(p, __ATOMIC_RELAXED, __HIP_MEMORY_SCOPE_AGENT); }
; __device__ __forceinline__ unsigned xb_add(unsigned* p, unsigned v) { return __hip_atomic_fetch_add(p, v, __ATOMIC_RELAXED, __HIP_MEMORY_SCOPE_AGENT); }
; __device__ __forceinline__ void xcd_barrier_complete(unsigned* bar, unsigned x, unsigned& nloc, unsigned& nx) {
;     const unsigned G = gridDim.x * gridDim.y * gridDim.z;
;     unsigned sum, cnt, mine, sp = 0u;
;     for (;;) {
;         sum = 0u; cnt = 0u; mine = 0u;
; #pragma unroll
;         for (unsigned j = 0; j < 16; ++j) { const unsigned c = xb_ld(&bar[XB_XCNT(j)]); sum += c; cnt += (c > 0u) ? 1u : 0u; mine = (j == x) ? c : mine; }
;         if (sum == G) break;
; __device__ __forceinline__ void xcd_barrier(const XcdBarrier& b, bool t0) {
;     asm volatile("s_waitcnt vmcnt(0)" ::: "memory");
;     __syncthreads();
;     if (t0) {
;         unsigned* bar = b.bar;
;         __builtin_amdgcn_s_waitcnt(0);
;         unsigned nloc = b.st[0], nx = b.st[1];
;         if (nloc == 0u) { xcd_barrier_complete(bar, b.x, nloc, nx); b.st[0] = nloc; b.st[1] = nx; }
;         const unsigned old = xb_add(&bar[XB_XSUB(b.x)], 1u);
.LBB0_1127:
	v_mov_b32_e32 v0, v161
	v_mov_b32_e32 v2, v183
	v_add_u32_e32 v0, 0, v0
	v_add_u32_e32 v0, 0x201c0, v0
	s_waitcnt lgkmcnt(0)
	s_nop 0
	s_getreg_b32 s8, hwreg(HW_REG_XCC_ID, 0, 4)
	s_waitcnt vmcnt(0)
	s_waitcnt lgkmcnt(0)
	v_readlane_b32 s7, v251, 49
	v_readlane_b32 s6, v251, 48
	v_cmp_eq_u32_e32 vcc, 0, v2
	s_barrier
	s_and_saveexec_b64 s[4:5], vcc
	s_cbranch_execz .LBB0_1179
	v_readlane_b32 s9, v250, 17
	s_waitcnt vmcnt(0) expcnt(0) lgkmcnt(0)
	s_and_b32 s14, s8, 15
	v_mov_b32_e32 v0, s9
	ds_read_b32 v2, v0
	v_readlane_b32 s9, v250, 18
	s_waitcnt lgkmcnt(0)
	v_cmp_ne_u32_e32 vcc, 0, v2
	v_mov_b32_e32 v0, s9
	ds_read_b32 v0, v0
	s_cbranch_vccnz .LBB0_1143
	s_add_u32 s8, s6, 0x28680200
	s_addc_u32 s9, s7, 0
	s_add_u32 s10, s6, 0x28680400
	s_addc_u32 s11, s7, 0
	s_add_u32 s12, s6, 0x28680500
	s_addc_u32 s13, s7, 0
	s_add_u32 s18, s6, 0x28680600
	s_addc_u32 s19, s7, 0
	s_add_u32 s34, s6, 0x28680700
	s_addc_u32 s35, s7, 0
	s_add_u32 s40, s6, 0x28680800
	s_addc_u32 s41, s7, 0
	s_add_u32 s42, s6, 0x28680900
	s_addc_u32 s43, s7, 0
	s_add_u32 s44, s6, 0x28680a00
	s_addc_u32 s45, s7, 0
	s_add_u32 s48, s6, 0x28680b00
	s_addc_u32 s49, s7, 0
	s_add_u32 s50, s6, 0x28680c00
	s_addc_u32 s51, s7, 0
	s_add_u32 s52, s6, 0x28680d00
	s_addc_u32 s53, s7, 0
	s_add_u32 s56, s6, 0x28680e00
	s_addc_u32 s57, s7, 0
	s_add_u32 s60, s6, 0x28680f00
	s_addc_u32 s61, s7, 0
	s_add_u32 s62, s6, 0x28681000
	s_addc_u32 s63, s7, 0
	s_add_u32 s64, s6, 0x28681100
	s_addc_u32 s65, s7, 0
	s_add_u32 s88, s6, 0x28681200
	s_addc_u32 s89, s7, 0
	s_add_u32 s66, s6, 0x28681300
	s_addc_u32 s67, s7, 0
	s_mov_b32 s15, 1
	s_branch .LBB0_1131

; __device__ __forceinline__ int tid_of(int wv) { return wv * 64 + (int)__builtin_amdgcn_mbcnt_hi(~0u, __builtin_amdgcn_mbcnt_lo(~0u, 0u)); }
; #define LAS __attribute__((address_space(3)))
; #define PIN(i) ((const float*)ldq_(L, (i)))
; #define PREP_CONV(bit, SRC, Kd, Nd, DST, GK, MODE) if (mask & (bit)) { for (int it = gw; it < ((Kd) / 64) * ((Nd) / 64); it += NGW) transpose_item((SRC), (Kd), (Nd), (bf16_t*)(wl + (DST)), (GK), (MODE), scr, it, lane); }
; __device__ __forceinline__ void prep(const Params& p, LAS unsigned char* L, int wv, int vb, int nvb, int l, int mask) {
;     int tid_ = tid_of(wv); asm volatile("" : "+v"(tid_));
;     const int tid = tid_, lane = tid & 63, wave = __builtin_amdgcn_readfirstlane(tid >> 6);
;     const int gw = vb * 8 + wave, NGW = nvb * 8; const int gt = vb * 512 + tid, NGT = nvb * 512;
;     LAS float* scr = (LAS float*)(L + wave * 16384);
;     unsigned char* ws = PWS; unsigned char* wl = ws + WS_W + (size_t)l * WL_STRIDE;
;     ...
;     PREP_CONV(PM_FFA_IN, PIN(I_WFFA_IN) + (size_t)l * DM * NFF2, DM, NFF2, WL_FFA_IN, PIN(I_NFFA) + l * DM, 1)
.LBB0_1195:
	v_readlane_b32 s4, v250, 0
	s_add_i32 s60, s4, 1
	s_mov_b32 s4, s60
	s_mov_b32 s5, s2
	s_mov_b32 s6, s20
	s_cmpk_eq_i32 s6, 0x100
	s_cselect_b64 s[6:7], -1, 0
	s_cmp_gt_i32 s5, 39
	s_cselect_b64 s[8:9], -1, 0
	s_and_b64 s[6:7], s[6:7], s[8:9]
	s_cmp_lt_i32 s4, 2
	s_cselect_b64 s[8:9], -1, 0
	s_and_b64 s[6:7], s[6:7], s[8:9]
	s_andn2_b64 vcc, exec, s[6:7]
	s_cbranch_vccnz .LBB0_1263
	s_waitcnt lgkmcnt(0)
	v_mov_b32_e32 v0, v183
	v_mov_b32_e32 v1, v161
	s_lshl_b32 s5, s5, 3
	v_add_u32_e32 v1, 0, v1
	v_add_u32_e32 v1, 0x201c0, v1
	s_nop 0
	v_readfirstlane_b32 s6, v0
	s_ashr_i32 s6, s6, 6
	s_add_i32 s5, s5, s6
	s_add_i32 s14, s5, 0xfffffec0
	s_waitcnt lgkmcnt(0)
	v_readlane_b32 s5, v251, 49
	s_cmpk_gt_i32 s14, 0x57f
	v_readlane_b32 s7, v251, 48
	s_cbranch_scc1 .LBB0_1263
	s_mul_i32 s8, s4, 0x2900000
	s_mul_hi_i32 s9, s4, 0x2900000
	s_add_u32 s8, s7, s8
	s_addc_u32 s9, s5, s9
	s_lshl_b32 s5, s6, 14
	s_mul_hi_i32 s15, s4, 0x1600000
	s_mul_i32 s16, s4, 0x1600000
	s_lshl_b32 s4, s4, 10
	v_and_b32_e32 v1, 7, v0
	v_bfe_u32 v71, v0, 3, 3
	s_add_i32 s6, s5, 0
	v_and_b32_e32 v2, 63, v0
	s_ashr_i32 s5, s4, 31
	v_mul_u32_u24_e32 v3, 0x410, v1
	v_lshlrev_b32_e32 v160, 4, v1
	v_lshlrev_b32_e32 v4, 2, v71
	v_lshl_add_u32 v70, v2, 2, s6
	v_lshl_add_u64 v[0:1], s[8:9], 0, v[160:161]
	v_add3_u32 v72, s6, v3, v4
	s_lshl_b32 s18, s14, 6
	s_lshl_b32 s19, s14, 5
	s_lshl_b64 s[6:7], s[4:5], 2
	v_lshlrev_b32_e32 v160, 2, v2
	s_branch .LBB0_1199

; #define LAS __attribute__((address_space(3)))
; #define PIN(i) ((const float*)ldq_(L, (i)))
; #define PREP_CONV(bit, SRC, Kd, Nd, DST, GK, MODE) if (mask & (bit)) { for (int it = gw; it < ((Kd) / 64) * ((Nd) / 64); it += NGW) transpose_item((SRC), (Kd), (Nd), (bf16_t*)(wl + (DST)), (GK), (MODE), scr, it, lane); }
; __device__ __forceinline__ void transpose_item(const float* W, int K, int N, bf16_t* WT, const float* gk, int mode, LAS float* scr_, int item, int lane) {
;     LAS unsigned* scr = (LAS unsigned*)scr_;
;     const int nblk = N / 64, kb = item / nblk, nb = item % nblk, k0 = 64 * kb, n0 = 64 * nb;
;     const int sc = (mode == 1) ? (((n0 >> 7) & 1) * DFF + (n0 >> 8) * 128 + (n0 & 127)) : n0;
;     const float* src = W + (size_t)k0 * N + sc + lane;
;     float va[32], vb[32];
; #pragma unroll
;     for (int kp = 0; kp < 32; ++kp) { va[kp] = src[(size_t)(2 * kp) * N]; vb[kp] = src[(size_t)(2 * kp + 1) * N]; }
; __device__ __forceinline__ void prep(const Params& p, LAS unsigned char* L, int wv, int vb, int nvb, int l, int mask) {
;     ...
;     PREP_CONV(PM_FFA_IN, PIN(I_WFFA_IN) + (size_t)l * DM * NFF2, DM, NFF2, WL_FFA_IN, PIN(I_NFFA) + l * DM, 1)
.LBB0_1199:
	v_mov_b32_e32 v2, v161
	s_mul_hi_i32 s8, s14, 0x2e8ba2e9
	v_add_u32_e32 v2, 0, v2
	v_add_u32_e32 v2, 0x20140, v2
	ds_read_b64 v[2:3], v2
	s_waitcnt lgkmcnt(0)
	v_readfirstlane_b32 s5, v2
	v_mov_b32_e32 v2, v161
	v_readfirstlane_b32 s4, v3
	v_add_u32_e32 v2, 0, v2
	v_add_u32_e32 v2, 0x20138, v2
	s_nop 0
	s_add_u32 s11, s5, s16
	s_addc_u32 s12, s4, s15
	s_waitcnt lgkmcnt(0)
	v_readlane_b32 s4, v251, 14
	v_readlane_b32 s5, v251, 15
	s_add_u32 s25, s4, s6
	s_addc_u32 s29, s5, s7
	s_lshr_b32 s9, s8, 31
	s_ashr_i32 s8, s8, 4
	s_add_i32 s13, s8, s9
	s_mul_i32 s9, s13, 0xffffea00
	s_mul_i32 s10, s13, 0xfffff500
	s_add_i32 s24, s18, s9
	s_bfe_i32 s9, s14, 0x10001
	s_add_i32 s10, s19, s10
	s_and_b32 s9, s9, 0xb00
	s_and_b32 s10, s10, 0xffffff80
	s_lshl_b32 s8, s13, 6
	s_add_i32 s9, s9, s10
	s_and_b32 s10, s24, 64
	s_or_b32 s10, s9, s10
	s_ashr_i32 s9, s8, 31
	s_mul_i32 s13, s13, 0x160000
	s_mul_hi_i32 s21, s8, 0x5800
	s_add_u32 s13, s11, s13
	s_addc_u32 s12, s12, s21
	s_ashr_i32 s11, s10, 31
	s_lshl_b64 s[10:11], s[10:11], 2
	s_add_u32 s10, s13, s10
	s_addc_u32 s11, s12, s11
	s_waitcnt vmcnt(9)
	v_lshl_add_u64 v[66:67], s[10:11], 0, v[160:161]
	global_load_dword v62, v160, s[10:11]
	s_movk_i32 s10, 0x5000
	v_add_co_u32_e32 v2, vcc, s10, v66
	s_mov_b32 s10, 0xb000
	s_nop 0
	v_addc_co_u32_e32 v3, vcc, 0, v67, vcc
	global_load_dword v63, v[2:3], off offset:2048
	v_add_co_u32_e32 v2, vcc, s10, v66
	s_mov_b32 s10, 0x1b000
	s_nop 0
	v_addc_co_u32_e32 v3, vcc, 0, v67, vcc
	global_load_dword v64, v[2:3], off
	v_add_co_u32_e32 v2, vcc, s37, v66
	s_cmp_lg_u64 s[4:5], 0
	s_nop 0
	v_addc_co_u32_e32 v3, vcc, 0, v67, vcc
	global_load_dword v65, v[2:3], off offset:2048
	v_add_co_u32_e32 v2, vcc, s47, v66
	s_mov_b64 s[12:13], -1
	s_nop 0
	v_addc_co_u32_e32 v3, vcc, 0, v67, vcc
	global_load_dword v54, v[2:3], off
	v_add_co_u32_e32 v2, vcc, s10, v66
	s_mov_b32 s10, 0x21000
	s_nop 0
	v_addc_co_u32_e32 v3, vcc, 0, v67, vcc
	global_load_dword v55, v[2:3], off offset:2048
	v_add_co_u32_e32 v2, vcc, s10, v66
	s_mov_b32 s10, 0x31000
	s_nop 0
	v_addc_co_u32_e32 v3, vcc, 0, v67, vcc
	global_load_dword v60, v[2:3], off
	v_add_co_u32_e32 v2, vcc, s73, v66
	s_nop 1
	v_addc_co_u32_e32 v3, vcc, 0, v67, vcc
	global_load_dword v61, v[2:3], off offset:2048
	v_add_co_u32_e32 v2, vcc, s82, v66
	s_nop 1
	v_addc_co_u32_e32 v3, vcc, 0, v67, vcc
	global_load_dword v56, v[2:3], off
	v_add_co_u32_e32 v2, vcc, s10, v66
	s_mov_b32 s10, 0x37000
	s_nop 0
	v_addc_co_u32_e32 v3, vcc, 0, v67, vcc
	global_load_dword v57, v[2:3], off offset:2048
	v_add_co_u32_e32 v2, vcc, s10, v66
	s_mov_b32 s10, 0x47000
	s_nop 0
	v_addc_co_u32_e32 v3, vcc, 0, v67, vcc
	global_load_dword v58, v[2:3], off
	v_add_co_u32_e32 v2, vcc, s90, v66
	s_nop 1
	v_addc_co_u32_e32 v3, vcc, 0, v67, vcc
	global_load_dword v59, v[2:3], off offset:2048
	v_add_co_u32_e32 v2, vcc, s93, v66
	s_nop 1
	v_addc_co_u32_e32 v3, vcc, 0, v67, vcc
	global_load_dword v44, v[2:3], off
	v_add_co_u32_e32 v2, vcc, s10, v66
	s_mov_b32 s10, 0x4d000
	s_nop 0
	v_addc_co_u32_e32 v3, vcc, 0, v67, vcc
	global_load_dword v45, v[2:3], off offset:2048
	v_add_co_u32_e32 v2, vcc, s10, v66
	s_mov_b32 s10, 0x52000
	s_nop 0
	v_addc_co_u32_e32 v3, vcc, 0, v67, vcc
	global_load_dword v50, v[2:3], off
	v_add_co_u32_e32 v2, vcc, s10, v66
	s_mov_b32 s10, 0x58000
	s_nop 0
	v_addc_co_u32_e32 v3, vcc, 0, v67, vcc
	global_load_dword v51, v[2:3], off offset:2048
	v_add_co_u32_e32 v2, vcc, s10, v66
	s_mov_b32 s10, 0x5d000
	s_nop 0
	v_addc_co_u32_e32 v3, vcc, 0, v67, vcc
	global_load_dword v48, v[2:3], off
	v_add_co_u32_e32 v2, vcc, s10, v66
	s_mov_b32 s10, 0x63000
	s_nop 0
	v_addc_co_u32_e32 v3, vcc, 0, v67, vcc
	global_load_dword v49, v[2:3], off offset:2048
	v_add_co_u32_e32 v2, vcc, s10, v66
	s_mov_b32 s10, 0x68000
	s_nop 0
	v_addc_co_u32_e32 v3, vcc, 0, v67, vcc
	global_load_dword v52, v[2:3], off
	v_add_co_u32_e32 v2, vcc, s10, v66
	s_mov_b32 s10, 0x6e000
	s_nop 0
	v_addc_co_u32_e32 v3, vcc, 0, v67, vcc
	global_load_dword v53, v[2:3], off offset:2048
	v_add_co_u32_e32 v2, vcc, s10, v66
	s_mov_b32 s10, 0x73000
	s_nop 0
	v_addc_co_u32_e32 v3, vcc, 0, v67, vcc
	global_load_dword v38, v[2:3], off
	v_add_co_u32_e32 v2, vcc, s10, v66
	s_mov_b32 s10, 0x79000
	s_nop 0
	v_addc_co_u32_e32 v3, vcc, 0, v67, vcc
	global_load_dword v39, v[2:3], off offset:2048
	v_add_co_u32_e32 v2, vcc, s10, v66
	s_mov_b32 s10, 0x7e000
	s_nop 0
	v_addc_co_u32_e32 v3, vcc, 0, v67, vcc
	global_load_dword v42, v[2:3], off
	v_add_co_u32_e32 v2, vcc, s10, v66
	s_mov_b32 s10, 0x84000
	s_nop 0
	v_addc_co_u32_e32 v3, vcc, 0, v67, vcc
	global_load_dword v43, v[2:3], off offset:2048
	v_add_co_u32_e32 v2, vcc, s10, v66
	s_mov_b32 s10, 0x89000
	s_nop 0
	v_addc_co_u32_e32 v3, vcc, 0, v67, vcc
	global_load_dword v40, v[2:3], off
	v_add_co_u32_e32 v2, vcc, s10, v66
	s_mov_b32 s10, 0x8f000
	s_nop 0
	v_addc_co_u32_e32 v3, vcc, 0, v67, vcc
	global_load_dword v41, v[2:3], off offset:2048
	v_add_co_u32_e32 v2, vcc, s10, v66
	s_mov_b32 s10, 0x94000
	s_nop 0
	v_addc_co_u32_e32 v3, vcc, 0, v67, vcc
	global_load_dword v46, v[2:3], off
	v_add_co_u32_e32 v2, vcc, s10, v66
	s_mov_b32 s10, 0x9a000
	s_nop 0
	v_addc_co_u32_e32 v3, vcc, 0, v67, vcc
	global_load_dword v47, v[2:3], off offset:2048
	v_add_co_u32_e32 v2, vcc, s10, v66
	s_mov_b32 s10, 0x9f000
	s_nop 0
	v_addc_co_u32_e32 v3, vcc, 0, v67, vcc
	global_load_dword v30, v[2:3], off
	v_add_co_u32_e32 v2, vcc, s10, v66
	s_mov_b32 s10, 0xa5000
	s_nop 0
; __device__ __forceinline__ void transpose_item(const float* W, int K, int N, bf16_t* WT, const float* gk, int mode, LAS float* scr_, int item, int lane) {
;     ...
;     for (int kp = 0; kp < 32; ++kp) { va[kp] = src[(size_t)(2 * kp) * N]; vb[kp] = src[(size_t)(2 * kp + 1) * N]; }
; #pragma unroll
;     for (int kp = 0; kp < 32; ++kp) {
;         float a = va[kp], b = vb[kp];
;         if (gk) { a *= gk[k0 + 2 * kp]; b *= gk[k0 + 2 * kp + 1]; }
	v_addc_co_u32_e32 v3, vcc, 0, v67, vcc
	global_load_dword v31, v[2:3], off offset:2048
	v_add_co_u32_e32 v2, vcc, s10, v66
	s_mov_b32 s10, 0xaa000
	s_nop 0
	v_addc_co_u32_e32 v3, vcc, 0, v67, vcc
	global_load_dword v36, v[2:3], off
	v_add_co_u32_e32 v2, vcc, s10, v66
	s_mov_b32 s10, 0xb5000
	s_nop 0
	v_addc_co_u32_e32 v3, vcc, 0, v67, vcc
	global_load_dword v37, v[2:3], off offset:2048
	v_add_co_u32_e32 v2, vcc, s95, v66
	s_nop 1
	v_addc_co_u32_e32 v3, vcc, 0, v67, vcc
	global_load_dword v32, v[2:3], off
	v_add_co_u32_e32 v2, vcc, s10, v66
	s_mov_b32 s10, 0xbb000
	s_nop 0
	v_addc_co_u32_e32 v3, vcc, 0, v67, vcc
	global_load_dword v33, v[2:3], off offset:2048
	v_add_co_u32_e32 v2, vcc, s10, v66
	s_mov_b32 s10, 0xc0000
	s_nop 0
	v_addc_co_u32_e32 v3, vcc, 0, v67, vcc
	global_load_dword v34, v[2:3], off
	v_add_co_u32_e32 v2, vcc, s10, v66
	s_mov_b32 s10, 0xcb000
	s_nop 0
	v_addc_co_u32_e32 v3, vcc, 0, v67, vcc
	global_load_dword v35, v[2:3], off offset:2048
	v_add_co_u32_e32 v2, vcc, s89, v66
	s_nop 1
	v_addc_co_u32_e32 v3, vcc, 0, v67, vcc
	global_load_dword v20, v[2:3], off
	v_add_co_u32_e32 v2, vcc, s10, v66
	s_mov_b32 s10, 0xd1000
	s_nop 0
	v_addc_co_u32_e32 v3, vcc, 0, v67, vcc
	global_load_dword v21, v[2:3], off offset:2048
	v_add_co_u32_e32 v2, vcc, s10, v66
	s_mov_b32 s10, 0xd6000
	s_nop 0
	v_addc_co_u32_e32 v3, vcc, 0, v67, vcc
	global_load_dword v26, v[2:3], off
	v_add_co_u32_e32 v2, vcc, s10, v66
	s_mov_b32 s10, 0xdc000
	s_nop 0
	v_addc_co_u32_e32 v3, vcc, 0, v67, vcc
	global_load_dword v27, v[2:3], off offset:2048
	v_add_co_u32_e32 v2, vcc, s10, v66
	s_mov_b32 s10, 0xe1000
	s_nop 0
	v_addc_co_u32_e32 v3, vcc, 0, v67, vcc
	global_load_dword v24, v[2:3], off
	v_add_co_u32_e32 v2, vcc, s10, v66
	s_mov_b32 s10, 0xe7000
	s_nop 0
	v_addc_co_u32_e32 v3, vcc, 0, v67, vcc
	global_load_dword v25, v[2:3], off offset:2048
	v_add_co_u32_e32 v2, vcc, s10, v66
	s_mov_b32 s10, 0xec000
	s_nop 0
	v_addc_co_u32_e32 v3, vcc, 0, v67, vcc
	global_load_dword v28, v[2:3], off
	v_add_co_u32_e32 v2, vcc, s10, v66
	s_mov_b32 s10, 0xf2000
	s_nop 0
	v_addc_co_u32_e32 v3, vcc, 0, v67, vcc
	global_load_dword v29, v[2:3], off offset:2048
	v_add_co_u32_e32 v2, vcc, s10, v66
	s_mov_b32 s10, 0xf7000
	s_nop 0
	v_addc_co_u32_e32 v3, vcc, 0, v67, vcc
	global_load_dword v12, v[2:3], off
	v_add_co_u32_e32 v2, vcc, s10, v66
	s_mov_b32 s10, 0xfd000
	s_nop 0
	v_addc_co_u32_e32 v3, vcc, 0, v67, vcc
	global_load_dword v13, v[2:3], off offset:2048
	v_add_co_u32_e32 v2, vcc, s10, v66
	s_mov_b32 s10, 0x102000
	s_nop 0
	v_addc_co_u32_e32 v3, vcc, 0, v67, vcc
	global_load_dword v18, v[2:3], off
	v_add_co_u32_e32 v2, vcc, s10, v66
	s_mov_b32 s10, 0x108000
	s_nop 0
	v_addc_co_u32_e32 v3, vcc, 0, v67, vcc
	global_load_dword v19, v[2:3], off offset:2048
	v_add_co_u32_e32 v2, vcc, s10, v66
	s_mov_b32 s10, 0x10d000
	s_nop 0
	v_addc_co_u32_e32 v3, vcc, 0, v67, vcc
	global_load_dword v16, v[2:3], off
	v_add_co_u32_e32 v2, vcc, s10, v66
	s_mov_b32 s10, 0x113000
	s_nop 0
	v_addc_co_u32_e32 v3, vcc, 0, v67, vcc
	global_load_dword v17, v[2:3], off offset:2048
	v_add_co_u32_e32 v2, vcc, s10, v66
	s_mov_b32 s10, 0x118000
	s_nop 0
	v_addc_co_u32_e32 v3, vcc, 0, v67, vcc
	global_load_dword v22, v[2:3], off
	v_add_co_u32_e32 v2, vcc, s10, v66
	s_mov_b32 s10, 0x11e000
	s_nop 0
	v_addc_co_u32_e32 v3, vcc, 0, v67, vcc
	global_load_dword v23, v[2:3], off offset:2048
	v_add_co_u32_e32 v2, vcc, s10, v66
	s_mov_b32 s10, 0x123000
	s_nop 0
	v_addc_co_u32_e32 v3, vcc, 0, v67, vcc
	global_load_dword v4, v[2:3], off
	v_add_co_u32_e32 v2, vcc, s10, v66
	s_mov_b32 s10, 0x129000
	s_nop 0
	v_addc_co_u32_e32 v3, vcc, 0, v67, vcc
	global_load_dword v5, v[2:3], off offset:2048
	v_add_co_u32_e32 v2, vcc, s10, v66
	s_mov_b32 s10, 0x12e000
	s_nop 0
	v_addc_co_u32_e32 v3, vcc, 0, v67, vcc
	global_load_dword v10, v[2:3], off
	v_add_co_u32_e32 v2, vcc, s10, v66
	s_mov_b32 s10, 0x134000
	s_nop 0
	v_addc_co_u32_e32 v3, vcc, 0, v67, vcc
	global_load_dword v11, v[2:3], off offset:2048
	v_add_co_u32_e32 v2, vcc, s10, v66
	s_mov_b32 s10, 0x139000
	s_nop 0
	v_addc_co_u32_e32 v3, vcc, 0, v67, vcc
	global_load_dword v6, v[2:3], off
	v_add_co_u32_e32 v2, vcc, s10, v66
	s_mov_b32 s10, 0x13f000
	s_nop 0
	v_addc_co_u32_e32 v3, vcc, 0, v67, vcc
	global_load_dword v7, v[2:3], off offset:2048
	v_add_co_u32_e32 v2, vcc, s10, v66
	s_mov_b32 s10, 0x144000
	s_nop 0
	v_addc_co_u32_e32 v3, vcc, 0, v67, vcc
	global_load_dword v14, v[2:3], off
	v_add_co_u32_e32 v2, vcc, s10, v66
	s_mov_b32 s10, 0x14a000
	s_nop 0
	v_addc_co_u32_e32 v3, vcc, 0, v67, vcc
	global_load_dword v15, v[2:3], off offset:2048
	v_add_co_u32_e32 v2, vcc, s10, v66
	s_mov_b32 s10, 0x14f000
	s_nop 0
	v_addc_co_u32_e32 v3, vcc, 0, v67, vcc
	v_add_co_u32_e32 v8, vcc, s10, v66
	global_load_dword v2, v[2:3], off
	s_nop 0
	v_addc_co_u32_e32 v9, vcc, 0, v67, vcc
	global_load_dword v3, v[8:9], off offset:2048
	v_add_co_u32_e32 v8, vcc, 0x155000, v66
	s_cselect_b64 s[10:11], -1, 0
	s_nop 0
	v_addc_co_u32_e32 v9, vcc, 0, v67, vcc
	v_add_co_u32_e32 v66, vcc, 0x15a000, v66
	global_load_dword v8, v[8:9], off
	s_nop 0
	v_addc_co_u32_e32 v67, vcc, 0, v67, vcc
	global_load_dword v9, v[66:67], off offset:2048
	s_cmp_eq_u64 s[4:5], 0
	s_cbranch_scc1 .LBB0_1201
	s_lshl_b64 s[4:5], s[8:9], 2
	s_add_u32 s4, s25, s4
	s_addc_u32 s5, s29, s5
	global_load_dwordx4 v[66:69], v161, s[4:5]
	s_mov_b64 s[12:13], 0
	s_waitcnt vmcnt(0)
	v_pk_mul_f32 v[66:67], v[62:63], v[66:67]
	v_pk_mul_f32 v[68:69], v[64:65], v[68:69]

; __device__ __forceinline__ unsigned xb_ld(unsigned* p)              { return __hip_atomic_load(p, __ATOMIC_RELAXED, __HIP_MEMORY_SCOPE_AGENT); }
; __device__ __forceinline__ unsigned xb_add(unsigned* p, unsigned v) { return __hip_atomic_fetch_add(p, v, __ATOMIC_RELAXED, __HIP_MEMORY_SCOPE_AGENT); }
; __device__ __forceinline__ void xcd_barrier_complete(unsigned* bar, unsigned x, unsigned& nloc, unsigned& nx) {
;     const unsigned G = gridDim.x * gridDim.y * gridDim.z;
;     unsigned sum, cnt, mine, sp = 0u;
;     for (;;) {
;         sum = 0u; cnt = 0u; mine = 0u;
; #pragma unroll
;         for (unsigned j = 0; j < 16; ++j) { const unsigned c = xb_ld(&bar[XB_XCNT(j)]); sum += c; cnt += (c > 0u) ? 1u : 0u; mine = (j == x) ? c : mine; }
;         if (sum == G) break;
; __device__ __forceinline__ void xcd_barrier(const XcdBarrier& b, bool t0) {
;     asm volatile("s_waitcnt vmcnt(0)" ::: "memory");
;     __syncthreads();
;     if (t0) {
;         unsigned* bar = b.bar;
;         __builtin_amdgcn_s_waitcnt(0);
;         unsigned nloc = b.st[0], nx = b.st[1];
;         if (nloc == 0u) { xcd_barrier_complete(bar, b.x, nloc, nx); b.st[0] = nloc; b.st[1] = nx; }
;         const unsigned old = xb_add(&bar[XB_XSUB(b.x)], 1u);
.LBB0_1263:
	s_waitcnt lgkmcnt(0)
	v_mov_b32_e32 v0, v161
	v_mov_b32_e32 v2, v183
	v_add_u32_e32 v0, 0, v0
	v_add_u32_e32 v0, 0x201c0, v0
	s_nop 0
	s_getreg_b32 s8, hwreg(HW_REG_XCC_ID, 0, 4)
	s_waitcnt vmcnt(0)
	s_waitcnt lgkmcnt(0)
	v_readlane_b32 s7, v251, 49
	v_readlane_b32 s6, v251, 48
	v_cmp_eq_u32_e32 vcc, 0, v2
	s_barrier
	s_and_saveexec_b64 s[4:5], vcc
	s_mov_b32 s0, s60
	s_cbranch_execz .LBB0_1315
	v_readlane_b32 s9, v250, 17
	s_waitcnt vmcnt(0) expcnt(0) lgkmcnt(0)
	s_and_b32 s14, s8, 15
	v_mov_b32_e32 v0, s9
	ds_read_b32 v2, v0
	v_readlane_b32 s9, v250, 18
	s_waitcnt lgkmcnt(0)
	v_cmp_ne_u32_e32 vcc, 0, v2
	v_mov_b32_e32 v0, s9
	ds_read_b32 v0, v0
	s_cbranch_vccnz .LBB0_1279
	s_add_u32 s8, s6, 0x28680200
	s_addc_u32 s9, s7, 0
	s_add_u32 s10, s6, 0x28680400
	s_addc_u32 s11, s7, 0
	s_add_u32 s12, s6, 0x28680500
	s_addc_u32 s13, s7, 0
	s_add_u32 s18, s6, 0x28680600
	s_addc_u32 s19, s7, 0
	s_add_u32 s34, s6, 0x28680700
	s_addc_u32 s35, s7, 0
	s_add_u32 s40, s6, 0x28680800
	s_addc_u32 s41, s7, 0
	s_add_u32 s42, s6, 0x28680900
	s_addc_u32 s43, s7, 0
	s_add_u32 s44, s6, 0x28680a00
	s_addc_u32 s45, s7, 0
	s_add_u32 s48, s6, 0x28680b00
	s_addc_u32 s49, s7, 0
	s_add_u32 s50, s6, 0x28680c00
	s_addc_u32 s51, s7, 0
	s_add_u32 s52, s6, 0x28680d00
	s_addc_u32 s53, s7, 0
	s_add_u32 s56, s6, 0x28680e00
	s_addc_u32 s57, s7, 0
	s_add_u32 s60, s6, 0x28680f00
	s_addc_u32 s61, s7, 0
	s_add_u32 s62, s6, 0x28681000
	s_addc_u32 s63, s7, 0
	s_add_u32 s64, s6, 0x28681100
	s_addc_u32 s65, s7, 0
	s_add_u32 s66, s6, 0x28681200
	s_addc_u32 s67, s7, 0
	s_add_u32 s24, s6, 0x28681300
	s_addc_u32 s25, s7, 0
	s_mov_b32 s15, 1
	s_branch .LBB0_1267

; #define LAS __attribute__((address_space(3)))
; __device__ __forceinline__ unsigned pk2(float lo, float hi) { f32x2 v = {lo, hi}; bf16x2_t b = __builtin_convertvector(v, bf16x2_t); return __builtin_bit_cast(unsigned, b); }
; #define GAS __attribute__((address_space(1)))
; __device__ __forceinline__ void mixer_unit(const Params& p, int layer, int cu, LAS unsigned char* L, int wv) {
;     ...
;     {
;         const int g = wave >> 1, th = wave & 1;
;         bf16x8 dfr[2][4];
; #pragma unroll
;         for (int tb = 0; tb < 2; ++tb)
; #pragma unroll
;             for (int ks = 0; ks < 4; ++ks) dfr[tb][ks] = *(const LAS bf16x8*)(L + ((32 * th + 16 * tb + q16) * DROW + 128 * g + 32 * ks + 8 * quad) * 2);
;         const bf16_t* wp = (const bf16_t*)(PWS + WS_W + (size_t)layer * WL_STRIDE + WL_POOL) + (size_t)g * 128 * 128;
;         u32x2 res[8][2];
; #pragma unroll
;         for (int nt = 0; nt < 8; ++nt) {
;             bf16x8 wf[4];
; #pragma unroll
;             for (int ks = 0; ks < 4; ++ks) wf[ks] = *(const GAS bf16x8*)((const GAS bf16_t*)wp + (16 * nt + q16) * 128 + 32 * ks + 8 * quad);
; #pragma unroll
;             for (int tb = 0; tb < 2; ++tb) {
;                 f32x4 o = (f32x4){0.f, 0.f, 0.f, 0.f};
; #pragma unroll
;                 for (int ks = 0; ks < 4; ++ks) o = __builtin_amdgcn_mfma_f32_16x16x32_bf16(wf[ks], dfr[tb][ks], o, 0, 0, 0);
;                 res[nt][tb].x = pk2(o[0], o[1]); res[nt][tb].y = pk2(o[2], o[3]);
;             }
;             if ((nt & 3) == 3) asm volatile("" ::: "memory");
;         }
; #pragma unroll
;         for (int nt = 0; nt < 8; ++nt)
; #pragma unroll
;             for (int tb = 0; tb < 2; ++tb) *(GAS u32x2*)((GAS bf16_t*)mix + (size_t)(tok0 + 32 * th + 16 * tb + q16) * DM + 512 + 128 * g + 16 * nt + 4 * quad) = res[nt][tb];
;     }
;     __syncthreads();
.LBB0_1318:
	s_or_b64 exec, exec, s[4:5]
	s_and_b32 s4, s66, 0x7fffff80
	v_lshl_or_b32 v82, s9, 5, v179
	v_or_b32_e32 v0, s4, v180
	s_movk_i32 s4, 0x208
	v_mad_u32_u24 v0, v82, s4, v0
	v_lshl_add_u32 v0, v0, 1, 0
	s_waitcnt lgkmcnt(0)
	s_barrier
	ds_read_b128 v[40:43], v0
	ds_read_b128 v[36:39], v0 offset:64
	ds_read_b128 v[28:31], v0 offset:128
	ds_read_b128 v[8:11], v0 offset:192
	ds_read_b128 v[12:15], v0 offset:16640
	ds_read_b128 v[16:19], v0 offset:16704
	ds_read_b128 v[20:23], v0 offset:16768
	ds_read_b128 v[24:27], v0 offset:16832
	v_mov_b32_e32 v0, v161
	v_readlane_b32 s6, v250, 0
	v_add_u32_e32 v0, 0, v0
	v_add_u32_e32 v0, 0x201c0, v0
	s_nop 0
	s_mul_i32 s6, s6, 0x2900000
	v_lshlrev_b32_e32 v160, 1, v180
	v_mov_b32_e32 v113, v161
	s_waitcnt lgkmcnt(0)
	v_readlane_b32 s5, v251, 48
	v_readlane_b32 s4, v251, 49
	s_add_u32 s6, s5, s6
	s_addc_u32 s7, s4, 0
	s_ashr_i32 s9, s8, 31
	s_lshl_b64 s[4:5], s[8:9], 15
	s_add_u32 s4, s6, s4
	s_addc_u32 s5, s7, s5
	v_lshl_add_u64 v[0:1], s[4:5], 0, v[160:161]
	v_lshlrev_b32_e32 v160, 8, v179
	v_lshl_add_u64 v[80:81], v[0:1], 0, v[160:161]
	s_mov_b64 s[4:5], 0x2800000
	v_lshl_add_u64 v[0:1], v[80:81], 0, s[4:5]
	s_mov_b32 s4, 0x2801000
	v_add_co_u32_e32 v56, vcc, s4, v80
	s_mov_b32 s4, 0x2802000
	s_nop 0
	v_addc_co_u32_e32 v57, vcc, 0, v81, vcc
	global_load_dwordx4 v[4:7], v[56:57], off offset:-4096
	global_load_dwordx4 v[32:35], v[0:1], off offset:64
	global_load_dwordx4 v[44:47], v[0:1], off offset:128
	global_load_dwordx4 v[48:51], v[0:1], off offset:192
	s_add_i32 s65, s65, s20
	s_waitcnt vmcnt(3)
	v_mfma_f32_16x16x32_bf16 v[0:3], v[4:7], v[40:43], 0
	v_mfma_f32_16x16x32_bf16 v[4:7], v[4:7], v[12:15], 0
	s_waitcnt vmcnt(2)
	v_mfma_f32_16x16x32_bf16 v[0:3], v[32:35], v[36:39], v[0:3]
	v_mfma_f32_16x16x32_bf16 v[4:7], v[32:35], v[16:19], v[4:7]
	s_waitcnt vmcnt(1)
	v_mfma_f32_16x16x32_bf16 v[0:3], v[44:47], v[28:31], v[0:3]
	v_mfma_f32_16x16x32_bf16 v[4:7], v[44:47], v[20:23], v[4:7]
	s_waitcnt vmcnt(0)
	v_mfma_f32_16x16x32_bf16 v[0:3], v[48:51], v[8:11], v[0:3]
	v_mfma_f32_16x16x32_bf16 v[4:7], v[48:51], v[24:27], v[4:7]
	global_load_dwordx4 v[44:47], v[56:57], off
	global_load_dwordx4 v[48:51], v[56:57], off offset:64
	global_load_dwordx4 v[52:55], v[56:57], off offset:128
	s_nop 0
	global_load_dwordx4 v[56:59], v[56:57], off offset:192
	s_nop 1
	v_cvt_pk_bf16_f32 v0, v0, v1
	v_cvt_pk_bf16_f32 v1, v2, v3
	v_add_u32_e32 v2, s67, v82
	v_ashrrev_i32_e32 v3, 31, v2
	v_cvt_pk_bf16_f32 v4, v4, v5
	v_cvt_pk_bf16_f32 v5, v6, v7
	v_lshlrev_b64 v[6:7], 11, v[2:3]
	v_lshl_add_u64 v[6:7], s[12:13], 0, v[6:7]
	s_waitcnt vmcnt(3)
	v_mfma_f32_16x16x32_bf16 v[32:35], v[44:47], v[40:43], 0
	v_mfma_f32_16x16x32_bf16 v[44:47], v[44:47], v[12:15], 0
	s_waitcnt vmcnt(2)
	v_mfma_f32_16x16x32_bf16 v[32:35], v[48:51], v[36:39], v[32:35]
	v_mfma_f32_16x16x32_bf16 v[44:47], v[48:51], v[16:19], v[44:47]
	v_add_co_u32_e32 v48, vcc, s4, v80
	s_mov_b32 s4, 0x2803000
	s_waitcnt vmcnt(1)
	v_mfma_f32_16x16x32_bf16 v[32:35], v[52:55], v[28:31], v[32:35]
	v_addc_co_u32_e32 v49, vcc, 0, v81, vcc
	v_add_co_u32_e32 v72, vcc, s4, v80
	v_mfma_f32_16x16x32_bf16 v[44:47], v[52:55], v[20:23], v[44:47]
	s_nop 0
	v_addc_co_u32_e32 v73, vcc, 0, v81, vcc
	s_mov_b32 s4, 0x2804000
	s_waitcnt vmcnt(0)
	v_mfma_f32_16x16x32_bf16 v[32:35], v[56:59], v[8:11], v[32:35]
	v_mfma_f32_16x16x32_bf16 v[44:47], v[56:59], v[24:27], v[44:47]
	global_load_dwordx4 v[52:55], v[72:73], off offset:-4096
	global_load_dwordx4 v[56:59], v[48:49], off offset:64
	global_load_dwordx4 v[60:63], v[48:49], off offset:128
	global_load_dwordx4 v[64:67], v[48:49], off offset:192
	s_nop 2
	v_cvt_pk_bf16_f32 v32, v32, v33
	v_cvt_pk_bf16_f32 v33, v34, v35
	s_waitcnt vmcnt(3)
	v_mfma_f32_16x16x32_bf16 v[48:51], v[52:55], v[40:43], 0
	v_mfma_f32_16x16x32_bf16 v[52:55], v[52:55], v[12:15], 0
	s_waitcnt vmcnt(2)
	v_mfma_f32_16x16x32_bf16 v[48:51], v[56:59], v[36:39], v[48:51]
	v_mfma_f32_16x16x32_bf16 v[52:55], v[56:59], v[16:19], v[52:55]
	s_waitcnt vmcnt(1)
	v_mfma_f32_16x16x32_bf16 v[48:51], v[60:63], v[28:31], v[48:51]
	v_mfma_f32_16x16x32_bf16 v[52:55], v[60:63], v[20:23], v[52:55]
	s_waitcnt vmcnt(0)
	v_mfma_f32_16x16x32_bf16 v[48:51], v[64:67], v[8:11], v[48:51]
	v_mfma_f32_16x16x32_bf16 v[52:55], v[64:67], v[24:27], v[52:55]
	global_load_dwordx4 v[60:63], v[72:73], off
	global_load_dwordx4 v[64:67], v[72:73], off offset:64
	global_load_dwordx4 v[68:71], v[72:73], off offset:128
	s_nop 0
	global_load_dwordx4 v[72:75], v[72:73], off offset:192
	s_waitcnt vmcnt(3)
	v_mfma_f32_16x16x32_bf16 v[56:59], v[60:63], v[40:43], 0
	v_mfma_f32_16x16x32_bf16 v[60:63], v[60:63], v[12:15], 0
	s_waitcnt vmcnt(2)
	v_mfma_f32_16x16x32_bf16 v[56:59], v[64:67], v[36:39], v[56:59]
	v_mfma_f32_16x16x32_bf16 v[60:63], v[64:67], v[16:19], v[60:63]
	v_add_co_u32_e32 v64, vcc, s4, v80
	s_mov_b32 s4, 0x2805000
	s_waitcnt vmcnt(1)
	v_mfma_f32_16x16x32_bf16 v[56:59], v[68:71], v[28:31], v[56:59]
	v_addc_co_u32_e32 v65, vcc, 0, v81, vcc
	v_add_co_u32_e32 v92, vcc, s4, v80
	v_mfma_f32_16x16x32_bf16 v[60:63], v[68:71], v[20:23], v[60:63]
	s_nop 0
	v_addc_co_u32_e32 v93, vcc, 0, v81, vcc
	s_mov_b32 s4, 0x2806000
	s_waitcnt vmcnt(0)
	v_mfma_f32_16x16x32_bf16 v[56:59], v[72:75], v[8:11], v[56:59]
	v_add_co_u32_e32 v96, vcc, s4, v80
	s_mov_b32 s4, 0x2807000
	v_mfma_f32_16x16x32_bf16 v[60:63], v[72:75], v[24:27], v[60:63]
	global_load_dwordx4 v[68:71], v[92:93], off offset:-4096
	global_load_dwordx4 v[72:75], v[64:65], off offset:64
	global_load_dwordx4 v[76:79], v[64:65], off offset:128
	global_load_dwordx4 v[84:87], v[64:65], off offset:192
	v_addc_co_u32_e32 v97, vcc, 0, v81, vcc
	s_waitcnt vmcnt(3)
; __device__ __forceinline__ unsigned pk2(float lo, float hi) { f32x2 v = {lo, hi}; bf16x2_t b = __builtin_convertvector(v, bf16x2_t); return __builtin_bit_cast(unsigned, b); }
; #define GAS __attribute__((address_space(1)))
; __device__ __forceinline__ void mixer_unit(const Params& p, int layer, int cu, LAS unsigned char* L, int wv) {
;     ...
;         for (int nt = 0; nt < 8; ++nt) {
;             bf16x8 wf[4];
; #pragma unroll
;             for (int ks = 0; ks < 4; ++ks) wf[ks] = *(const GAS bf16x8*)((const GAS bf16_t*)wp + (16 * nt + q16) * 128 + 32 * ks + 8 * quad);
; #pragma unroll
;             for (int tb = 0; tb < 2; ++tb) {
;                 f32x4 o = (f32x4){0.f, 0.f, 0.f, 0.f};
; #pragma unroll
;                 for (int ks = 0; ks < 4; ++ks) o = __builtin_amdgcn_mfma_f32_16x16x32_bf16(wf[ks], dfr[tb][ks], o, 0, 0, 0);
;                 res[nt][tb].x = pk2(o[0], o[1]); res[nt][tb].y = pk2(o[2], o[3]);
;             }
;             if ((nt & 3) == 3) asm volatile("" ::: "memory");
;         }
; #pragma unroll
;         for (int nt = 0; nt < 8; ++nt)
; #pragma unroll
;             for (int tb = 0; tb < 2; ++tb) *(GAS u32x2*)((GAS bf16_t*)mix + (size_t)(tok0 + 32 * th + 16 * tb + q16) * DM + 512 + 128 * g + 16 * nt + 4 * quad) = res[nt][tb];
;     }
;     __syncthreads();
	v_mfma_f32_16x16x32_bf16 v[64:67], v[68:71], v[40:43], 0
	v_add_co_u32_e32 v80, vcc, s4, v80
	s_and_b32 s4, s66, 0xffffff80
	v_mfma_f32_16x16x32_bf16 v[68:71], v[68:71], v[12:15], 0
	v_addc_co_u32_e32 v81, vcc, 0, v81, vcc
	s_ashr_i32 s5, s4, 31
	s_waitcnt vmcnt(2)
	v_mfma_f32_16x16x32_bf16 v[64:67], v[72:75], v[36:39], v[64:67]
	s_lshl_b64 s[4:5], s[4:5], 1
	v_lshl_add_u64 v[6:7], v[6:7], 0, s[4:5]
	v_lshl_add_u64 v[6:7], v[6:7], 0, v[112:113]
	v_mfma_f32_16x16x32_bf16 v[68:71], v[72:75], v[16:19], v[68:71]
	s_cmpk_gt_i32 s65, 0x41f
	s_waitcnt vmcnt(1)
	v_mfma_f32_16x16x32_bf16 v[64:67], v[76:79], v[28:31], v[64:67]
	v_mfma_f32_16x16x32_bf16 v[68:71], v[76:79], v[20:23], v[68:71]
	s_waitcnt vmcnt(0)
	v_mfma_f32_16x16x32_bf16 v[64:67], v[84:87], v[8:11], v[64:67]
	v_mfma_f32_16x16x32_bf16 v[68:71], v[84:87], v[24:27], v[68:71]
	global_load_dwordx4 v[76:79], v[92:93], off
	global_load_dwordx4 v[84:87], v[92:93], off offset:64
	global_load_dwordx4 v[88:91], v[92:93], off offset:128
	s_nop 0
	global_load_dwordx4 v[92:95], v[92:93], off offset:192
	s_waitcnt vmcnt(3)
	v_mfma_f32_16x16x32_bf16 v[72:75], v[76:79], v[40:43], 0
	v_mfma_f32_16x16x32_bf16 v[76:79], v[76:79], v[12:15], 0
	s_waitcnt vmcnt(2)
	v_mfma_f32_16x16x32_bf16 v[72:75], v[84:87], v[36:39], v[72:75]
	v_mfma_f32_16x16x32_bf16 v[76:79], v[84:87], v[16:19], v[76:79]
	s_waitcnt vmcnt(1)
	v_mfma_f32_16x16x32_bf16 v[72:75], v[88:91], v[28:31], v[72:75]
	v_mfma_f32_16x16x32_bf16 v[76:79], v[88:91], v[20:23], v[76:79]
	s_waitcnt vmcnt(0)
	v_mfma_f32_16x16x32_bf16 v[72:75], v[92:95], v[8:11], v[72:75]
	v_mfma_f32_16x16x32_bf16 v[76:79], v[92:95], v[24:27], v[76:79]
	global_load_dwordx4 v[84:87], v[80:81], off offset:-4096
	global_load_dwordx4 v[88:91], v[96:97], off offset:64
	global_load_dwordx4 v[92:95], v[96:97], off offset:128
	s_nop 0
	global_load_dwordx4 v[96:99], v[96:97], off offset:192
	s_waitcnt vmcnt(3)
	v_mfma_f32_16x16x32_bf16 v[100:103], v[84:87], v[40:43], 0
	v_mfma_f32_16x16x32_bf16 v[84:87], v[84:87], v[12:15], 0
	s_waitcnt vmcnt(2)
	v_mfma_f32_16x16x32_bf16 v[100:103], v[88:91], v[36:39], v[100:103]
	v_mfma_f32_16x16x32_bf16 v[84:87], v[88:91], v[16:19], v[84:87]
	s_waitcnt vmcnt(1)
	v_mfma_f32_16x16x32_bf16 v[100:103], v[92:95], v[28:31], v[100:103]
	v_mfma_f32_16x16x32_bf16 v[84:87], v[92:95], v[20:23], v[84:87]
	s_waitcnt vmcnt(0)
	v_mfma_f32_16x16x32_bf16 v[100:103], v[96:99], v[8:11], v[100:103]
	v_mfma_f32_16x16x32_bf16 v[84:87], v[96:99], v[24:27], v[84:87]
	global_load_dwordx4 v[88:91], v[80:81], off
	global_load_dwordx4 v[92:95], v[80:81], off offset:64
	global_load_dwordx4 v[96:99], v[80:81], off offset:128
	global_load_dwordx4 v[104:107], v[80:81], off offset:192
	global_store_dwordx2 v[6:7], v[0:1], off offset:1024
	s_waitcnt vmcnt(4)
	v_mfma_f32_16x16x32_bf16 v[40:43], v[88:91], v[40:43], 0
	v_add_u32_e32 v0, 16, v2
	v_ashrrev_i32_e32 v1, 31, v0
	v_lshlrev_b64 v[0:1], 11, v[0:1]
	v_mfma_f32_16x16x32_bf16 v[12:15], v[88:91], v[12:15], 0
	v_lshl_add_u64 v[0:1], s[12:13], 0, v[0:1]
	v_lshl_add_u64 v[0:1], v[0:1], 0, s[4:5]
	v_lshl_add_u64 v[0:1], v[0:1], 0, v[112:113]
	s_waitcnt vmcnt(3)
	v_mfma_f32_16x16x32_bf16 v[36:39], v[92:95], v[36:39], v[40:43]
	v_mfma_f32_16x16x32_bf16 v[12:15], v[92:95], v[16:19], v[12:15]
	v_cvt_pk_bf16_f32 v16, v76, v77
	v_cvt_pk_bf16_f32 v17, v78, v79
	v_cvt_pk_bf16_f32 v18, v72, v73
	s_waitcnt vmcnt(2)
	v_mfma_f32_16x16x32_bf16 v[28:31], v[96:99], v[28:31], v[36:39]
	v_cvt_pk_bf16_f32 v19, v74, v75
	v_mfma_f32_16x16x32_bf16 v[12:15], v[96:99], v[20:23], v[12:15]
	v_cvt_pk_bf16_f32 v20, v68, v69
	v_cvt_pk_bf16_f32 v21, v70, v71
	v_cvt_pk_bf16_f32 v22, v64, v65
	s_waitcnt vmcnt(1)
	v_mfma_f32_16x16x32_bf16 v[8:11], v[104:107], v[8:11], v[28:31]
	v_cvt_pk_bf16_f32 v23, v66, v67
	v_cvt_pk_bf16_f32 v36, v44, v45
	v_cvt_pk_bf16_f32 v37, v46, v47
	v_mfma_f32_16x16x32_bf16 v[12:15], v[104:107], v[24:27], v[12:15]
	v_cvt_pk_bf16_f32 v24, v60, v61
	s_nop 2
	v_cvt_pk_bf16_f32 v8, v8, v9
	v_cvt_pk_bf16_f32 v9, v10, v11
	v_cvt_pk_bf16_f32 v10, v84, v85
	v_cvt_pk_bf16_f32 v11, v86, v87
	v_cvt_pk_bf16_f32 v12, v12, v13
	v_cvt_pk_bf16_f32 v13, v14, v15
	v_cvt_pk_bf16_f32 v14, v100, v101
	v_cvt_pk_bf16_f32 v15, v102, v103
	v_cvt_pk_bf16_f32 v25, v62, v63
	v_cvt_pk_bf16_f32 v26, v56, v57
	v_cvt_pk_bf16_f32 v27, v58, v59
	v_cvt_pk_bf16_f32 v28, v52, v53
	v_cvt_pk_bf16_f32 v29, v54, v55
	v_cvt_pk_bf16_f32 v30, v48, v49
	v_cvt_pk_bf16_f32 v31, v50, v51
	global_store_dwordx2 v[0:1], v[4:5], off offset:1024
	global_store_dwordx2 v[6:7], v[32:33], off offset:1056
	global_store_dwordx2 v[0:1], v[36:37], off offset:1056
	global_store_dwordx2 v[6:7], v[30:31], off offset:1088
	global_store_dwordx2 v[0:1], v[28:29], off offset:1088
	global_store_dwordx2 v[6:7], v[26:27], off offset:1120
	global_store_dwordx2 v[0:1], v[24:25], off offset:1120
	global_store_dwordx2 v[6:7], v[22:23], off offset:1152
	global_store_dwordx2 v[0:1], v[20:21], off offset:1152
	global_store_dwordx2 v[6:7], v[18:19], off offset:1184
	global_store_dwordx2 v[0:1], v[16:17], off offset:1184
	global_store_dwordx2 v[6:7], v[14:15], off offset:1216
	global_store_dwordx2 v[0:1], v[10:11], off offset:1216
	global_store_dwordx2 v[6:7], v[8:9], off offset:1248
	global_store_dwordx2 v[0:1], v[12:13], off offset:1248
	s_barrier
	s_cbranch_scc1 .LBB0_1801

; #define LAS __attribute__((address_space(3)))
; #define PIN(i) ((const float*)ldq_(L, (i)))
; __device__ __forceinline__ bf16x8 pack8(const float* v) { u32x4 w; w.x = pk2(v[0], v[1]); w.y = pk2(v[2], v[3]); w.z = pk2(v[4], v[5]); w.w = pk2(v[6], v[7]); return __builtin_bit_cast(bf16x8, w); }
; __device__ __forceinline__ void mixer_unit(const Params& p, int layer, int cu, LAS unsigned char* L, int wv) {
;     ...
;         for (int ps = 0; ps < 8; ++ps) {
;             const int kk = 16 * ps + rsub; const size_t o = ((((size_t)layer * NB + b) * 128 + kk) * 2 + kvh) * 64 + sub * 8;
;             const float* src = (isK ? PIN(I_CK) : PIN(I_CV)) + o;
;             const f32x4 a0 = *(const f32x4*)src, a1 = *(const f32x4*)(src + 4);
;             float v[8] = {a0[0], a0[1], a0[2], a0[3], a1[0], a1[1], a1[2], a1[3]};
;             *(LAS bf16x8*)(L + (isK ? LK_OFF : LV_OFF) + ((kvh * 192 + kk) * KROW + sub * 8) * 2) = pack8(v);
;             if (kk >= 64) { float* dst = POUT + (isK ? O_KS : O_VS) + ((((size_t)layer * NB + b) * 128 + (kk - 64)) * 2 + kvh) * 64 + sub * 8; *(f32x4*)dst = a0; *(f32x4*)(dst + 4) = a1; }
;         }
.LBB0_1341:
	s_and_saveexec_b64 s[24:25], s[12:13]
	s_xor_b64 s[24:25], exec, s[24:25]
	s_cbranch_execz .LBB0_1343
	v_mov_b32_e32 v48, 0
	s_nop 0
	v_add_u32_e32 v48, 0, v48
	v_add_u32_e32 v48, 0x20128, v48
	s_nop 0
	s_waitcnt lgkmcnt(0)
	v_readlane_b32 s31, v251, 11
	v_readlane_b32 s30, v251, 10
.LBB0_1343:
	s_or_saveexec_b64 s[24:25], s[24:25]
	v_mov_b32_e32 v57, 0xd800
	v_mov_b64_e32 v[48:49], s[30:31]
	s_xor_b64 exec, exec, s[24:25]
	s_cbranch_execz .LBB0_1345
	v_mov_b32_e32 v48, 0
	v_mov_b32_e32 v57, 0
	v_add_u32_e32 v48, 0, v48
	v_add_u32_e32 v48, 0x20120, v48
	s_nop 0
	s_waitcnt lgkmcnt(0)
	v_readlane_b32 s31, v251, 9
	v_readlane_b32 s30, v251, 8
	s_nop 1
	v_mov_b64_e32 v[48:49], s[30:31]
.LBB0_1345:
	s_or_b64 exec, exec, s[24:25]
	v_lshl_add_u64 v[48:49], v[48:49], 0, v[62:63]
	global_load_dwordx4 v[52:55], v[48:49], off offset:-16
	s_nop 0
	global_load_dwordx4 v[48:51], v[48:49], off
	v_add3_u32 v57, v66, v57, s21
	v_cmp_lt_i32_e32 vcc, 63, v56
	s_waitcnt vmcnt(1)
	v_cvt_pk_bf16_f32 v70, v52, v53
	v_cvt_pk_bf16_f32 v71, v54, v55
	s_waitcnt vmcnt(0)
	v_cvt_pk_bf16_f32 v72, v48, v49
	v_cvt_pk_bf16_f32 v73, v50, v51
	ds_write_b128 v57, v[70:73]
	s_and_saveexec_b64 s[24:25], vcc
	s_cbranch_execz .LBB0_1340
	v_mov_b32_e32 v57, 0
	v_subrev_u32_e32 v72, 64, v56
	v_add_u32_e32 v57, 0, v57
	v_add_u32_e32 v57, 0x201c8, v57
	s_nop 0
	v_mov_b32_e32 v73, v161
	v_lshl_add_u64 v[72:73], s[18:19], 0, v[72:73]
	v_lshlrev_b64 v[72:73], 9, v[72:73]
	s_waitcnt lgkmcnt(0)
	v_readlane_b32 s31, v251, 51
	v_readlane_b32 s30, v251, 50
	s_nop 1
	v_lshl_add_u64 v[70:71], s[30:31], 0, v[160:161]
	v_lshl_add_u64 v[70:71], v[70:71], 0, v[72:73]
	v_lshl_add_u64 v[70:71], v[70:71], 0, v[60:61]
	v_lshlrev_b32_e32 v72, 2, v58
	v_mov_b32_e32 v73, v161
	v_lshl_add_u64 v[70:71], v[70:71], 0, v[72:73]
	global_store_dwordx4 v[70:71], v[52:55], off
	global_store_dwordx4 v[70:71], v[48:51], off offset:16
	s_branch .LBB0_1340

; #define LAS __attribute__((address_space(3)))
; #define PIN(i) ((const float*)ldq_(L, (i)))
; __device__ __forceinline__ bf16x8 pack8(const float* v) { u32x4 w; w.x = pk2(v[0], v[1]); w.y = pk2(v[2], v[3]); w.z = pk2(v[4], v[5]); w.w = pk2(v[6], v[7]); return __builtin_bit_cast(bf16x8, w); }
; __device__ __forceinline__ void unpack8(u32x4 w, float* v) { v[0] = bflo(w.x); v[1] = bfhi(w.x); v[2] = bflo(w.y); v[3] = bfhi(w.y); v[4] = bflo(w.z); v[5] = bfhi(w.z); v[6] = bflo(w.w); v[7] = bfhi(w.w); }
; __device__ __forceinline__ void mixer_unit(const Params& p, int layer, int cu, LAS unsigned char* L, int wv) {
;     ...
;         float kn[8];
; #pragma unroll
;         for (int i = 0; i < 8; ++i) kn[i] = PIN(I_KN)[layer * 64 + sub * 8 + i];
; #pragma unroll
;         for (int ps = 0; ps < 12; ++ps) if (ps < npass) {
;             const int kk = klo + 16 * ps + rsub;
;             float v[8]; unpack8(raw[ps], v);
;             float ss = 0.f;
; #pragma unroll
;             for (int i = 0; i < 8; ++i) ss += v[i] * v[i];
;             ss += __shfl_xor(ss, 1); ss += __shfl_xor(ss, 2); ss += __shfl_xor(ss, 4);
;             const float rs = __builtin_amdgcn_rsqf(ss * (1.0f / 64.0f) + EPS);
; #pragma unroll
;             for (int i = 0; i < 8; ++i) { if (isK) v[i] = v[i] * rs * kn[i]; }
;             *(LAS bf16x8*)(L + (isK ? LK_OFF : LV_OFF) + ((kvh * 192 + kk) * KROW + sub * 8) * 2) = pack8(v);
;             int orow = -1;
;             if (is_s) orow = kk - 64; else if (c >= 30 && kk >= 128) orow = (c - 30) * 64 + (kk - 128);
;             if (orow >= 0 && !(isK && sub < 2)) {
;                 float* dst = POUT + (isK ? (is_s ? O_KS : O_KP) : (is_s ? O_VS : O_VP)) + ((((size_t)layer * NB + b) * 128 + orow) * 2 + kvh) * 64 + sub * 8;
;                 *(f32x4*)dst = (f32x4){v[0], v[1], v[2], v[3]}; *(f32x4*)(dst + 4) = (f32x4){v[4], v[5], v[6], v[7]};
;             }
;         }
.LBB0_1348:
	v_mov_b32_e32 v48, v161
	v_or_b32_e32 v160, s63, v54
	v_add_u32_e32 v48, s85, v48
	s_waitcnt vmcnt(16)
	s_nop 0
	s_cmp_gt_u32 s76, 29
	s_mov_b64 s[60:61], -1
	s_waitcnt lgkmcnt(0)
	v_readlane_b32 s19, v251, 27
	v_readlane_b32 s18, v251, 26
	v_lshlrev_b64 v[48:49], 2, v[160:161]
	s_waitcnt vmcnt(14)
	v_lshl_add_u64 v[50:51], s[18:19], 0, v[48:49]
	global_load_dword v58, v[50:51], off
	v_mov_b32_e32 v50, v161
	s_nop 0
	v_add_u32_e32 v50, s85, v50
	s_nop 0
	s_waitcnt lgkmcnt(0)
	v_readlane_b32 s19, v251, 27
	v_readlane_b32 s18, v251, 26
	s_nop 1
	v_lshl_add_u64 v[50:51], s[18:19], 0, v[48:49]
	global_load_dword v59, v[50:51], off offset:4
	v_mov_b32_e32 v50, v161
	s_nop 0
	v_add_u32_e32 v50, s85, v50
	s_nop 0
	s_waitcnt lgkmcnt(0)
	v_readlane_b32 s19, v251, 27
	v_readlane_b32 s18, v251, 26
	s_nop 1
	v_lshl_add_u64 v[50:51], s[18:19], 0, v[48:49]
	global_load_dword v60, v[50:51], off offset:8
	v_mov_b32_e32 v50, v161
	s_nop 0
	v_add_u32_e32 v50, s85, v50
	s_nop 0
	s_waitcnt lgkmcnt(0)
	v_readlane_b32 s19, v251, 27
	v_readlane_b32 s18, v251, 26
	s_nop 1
	v_lshl_add_u64 v[50:51], s[18:19], 0, v[48:49]
	global_load_dword v61, v[50:51], off offset:12
	v_mov_b32_e32 v50, v161
	s_nop 0
	v_add_u32_e32 v50, s85, v50
	s_nop 0
	s_waitcnt lgkmcnt(0)
	v_readlane_b32 s19, v251, 27
	v_readlane_b32 s18, v251, 26
	s_nop 1
	v_lshl_add_u64 v[50:51], s[18:19], 0, v[48:49]
	global_load_dword v62, v[50:51], off offset:16
	v_mov_b32_e32 v50, v161
	s_nop 0
	v_add_u32_e32 v50, s85, v50
	s_nop 0
	s_waitcnt lgkmcnt(0)
	v_readlane_b32 s19, v251, 27
	v_readlane_b32 s18, v251, 26
	s_nop 1
	v_lshl_add_u64 v[50:51], s[18:19], 0, v[48:49]
	global_load_dword v63, v[50:51], off offset:20
	v_mov_b32_e32 v50, v161
	s_nop 0
	v_add_u32_e32 v50, s85, v50
	s_nop 0
	s_waitcnt lgkmcnt(0)
	v_readlane_b32 s19, v251, 27
	v_readlane_b32 s18, v251, 26
	s_nop 1
	v_lshl_add_u64 v[50:51], s[18:19], 0, v[48:49]
	global_load_dword v65, v[50:51], off offset:24
	v_mov_b32_e32 v50, v161
	s_nop 0
	v_add_u32_e32 v50, s85, v50
	s_nop 0
	s_waitcnt lgkmcnt(0)
	v_readlane_b32 s19, v251, 27
	v_readlane_b32 s18, v251, 26
	s_waitcnt vmcnt(10)
	v_lshlrev_b32_e32 v50, 16, v45
	v_and_b32_e32 v51, 0xffff0000, v45
	v_lshl_add_u64 v[48:49], s[18:19], 0, v[48:49]
	global_load_dword v67, v[48:49], off offset:28
	v_cndmask_b32_e64 v48, v198, 0, s[8:9]
	v_and_b32_e32 v49, 0xffff0000, v44
	v_add_u32_e32 v66, 0, v48
	v_lshlrev_b32_e32 v48, 16, v44
	v_mul_f32_e32 v70, v49, v49
	v_fmac_f32_e32 v70, v48, v48
	v_fmac_f32_e32 v70, v50, v50
	v_and_b32_e32 v44, 0xffff0000, v46
	v_lshlrev_b32_e32 v45, 16, v46
	v_fmac_f32_e32 v70, v51, v51
	v_pk_mov_b32 v[56:57], v[44:45], v[44:45] op_sel:[1,0]
	v_pk_mul_f32 v[44:45], v[44:45], v[44:45]
	s_cselect_b64 s[18:19], -1, 0
	v_add_f32_e32 v45, v45, v70
	v_add_f32_e32 v70, v44, v45
	v_and_b32_e32 v44, 0xffff0000, v47
	v_lshlrev_b32_e32 v45, 16, v47
	v_pk_mov_b32 v[46:47], v[44:45], v[44:45] op_sel:[1,0]
	v_pk_mul_f32 v[44:45], v[44:45], v[44:45]
	s_or_b32 s13, s77, 0xfffff800
	v_add_f32_e32 v45, v45, v70
	v_add_f32_e32 v44, v44, v45
	s_and_b64 vcc, exec, s[40:41]
	s_nop 1
	v_add_f32_dpp v44, v44, v44 quad_perm:[1,0,3,2] row_mask:0xf bank_mask:0xf
	s_nop 1
	v_add_f32_dpp v44, v44, v44 quad_perm:[2,3,0,1] row_mask:0xf bank_mask:0xf
	s_nop 1
	v_add_f32_dpp v44, v44, v44 row_half_mirror row_mask:0xf bank_mask:0xf
	s_nop 0
	v_fmamk_f32 v44, v44, 0x3c800000, v189
	v_rsq_f32_e32 v44, v44
	s_nop 0
	v_mul_f32_e32 v73, v44, v56
	v_mul_f32_e32 v45, v44, v48
	v_mul_f32_e32 v70, v44, v49
	v_mul_f32_e32 v71, v44, v50
	v_mul_f32_e32 v72, v44, v51
	s_waitcnt vmcnt(3)
	v_mul_f32_e32 v73, v62, v73
	v_mul_f32_e32 v74, v44, v57
	v_mul_f32_e32 v75, v44, v46
	v_mul_f32_e32 v44, v44, v47
	v_mul_f32_e32 v45, v58, v45
	v_mul_f32_e32 v70, v59, v70
	v_mul_f32_e32 v71, v60, v71
	v_mul_f32_e32 v72, v61, v72
	s_waitcnt vmcnt(2)
	v_mul_f32_e32 v74, v63, v74
	v_cndmask_b32_e64 v49, v49, v70, s[8:9]
	v_cndmask_b32_e64 v48, v48, v45, s[8:9]
	v_cndmask_b32_e64 v50, v50, v71, s[8:9]
	v_cndmask_b32_e64 v51, v51, v72, s[8:9]
	v_cndmask_b32_e64 v45, v57, v74, s[8:9]
	s_waitcnt vmcnt(1)
	v_mul_f32_e32 v75, v65, v75
	v_cndmask_b32_e64 v46, v46, v75, s[8:9]
	v_cvt_pk_bf16_f32 v70, v48, v49
	v_cvt_pk_bf16_f32 v71, v50, v51
	s_waitcnt vmcnt(0)
	v_mul_f32_e32 v76, v67, v44
	v_cndmask_b32_e64 v44, v56, v73, s[8:9]
	v_add_u32_e32 v56, v55, v64
	v_cndmask_b32_e64 v47, v47, v76, s[8:9]
	v_mad_u64_u32 v[56:57], s[24:25], v56, s86, v[54:55]
	v_cvt_pk_bf16_f32 v72, v44, v45
	v_cvt_pk_bf16_f32 v73, v46, v47
	v_lshl_add_u32 v56, v56, 1, v66
	ds_write_b128 v56, v[70:73]
	s_cbranch_vccz .LBB0_1350
	s_movk_i32 s16, 0x7f
	v_cmp_lt_i32_e32 vcc, s16, v64
	v_add_u32_e32 v56, s13, v64
	s_and_b64 vcc, s[18:19], vcc
	v_cndmask_b32_e32 v70, -1, v56, vcc
	s_mov_b64 s[60:61], 0

; #define LAS __attribute__((address_space(3)))
; __device__ __forceinline__ bf16x8 pack8(const float* v) { u32x4 w; w.x = pk2(v[0], v[1]); w.y = pk2(v[2], v[3]); w.z = pk2(v[4], v[5]); w.w = pk2(v[6], v[7]); return __builtin_bit_cast(bf16x8, w); }
; __device__ __forceinline__ void unpack8(u32x4 w, float* v) { v[0] = bflo(w.x); v[1] = bfhi(w.x); v[2] = bflo(w.y); v[3] = bfhi(w.y); v[4] = bflo(w.z); v[5] = bfhi(w.z); v[6] = bflo(w.w); v[7] = bfhi(w.w); }
; __device__ __forceinline__ void mixer_unit(const Params& p, int layer, int cu, LAS unsigned char* L, int wv) {
;     ...
;         for (int ps = 0; ps < 12; ++ps) if (ps < npass) {
;             const int kk = klo + 16 * ps + rsub;
;             float v[8]; unpack8(raw[ps], v);
;             float ss = 0.f;
; #pragma unroll
;             for (int i = 0; i < 8; ++i) ss += v[i] * v[i];
;             ss += __shfl_xor(ss, 1); ss += __shfl_xor(ss, 2); ss += __shfl_xor(ss, 4);
;             const float rs = __builtin_amdgcn_rsqf(ss * (1.0f / 64.0f) + EPS);
; #pragma unroll
;             for (int i = 0; i < 8; ++i) { if (isK) v[i] = v[i] * rs * kn[i]; }
;             *(LAS bf16x8*)(L + (isK ? LK_OFF : LV_OFF) + ((kvh * 192 + kk) * KROW + sub * 8) * 2) = pack8(v);
;             int orow = -1;
;             if (is_s) orow = kk - 64; else if (c >= 30 && kk >= 128) orow = (c - 30) * 64 + (kk - 128);
;             if (orow >= 0 && !(isK && sub < 2)) {
;                 float* dst = POUT + (isK ? (is_s ? O_KS : O_KP) : (is_s ? O_VS : O_VP)) + ((((size_t)layer * NB + b) * 128 + orow) * 2 + kvh) * 64 + sub * 8;
;                 *(f32x4*)dst = (f32x4){v[0], v[1], v[2], v[3]}; *(f32x4*)(dst + 4) = (f32x4){v[4], v[5], v[6], v[7]};
;             }
;         }
.LBB0_1352:
	v_cmp_gt_u32_e32 vcc, 2, v68
	s_and_b64 s[24:25], s[8:9], vcc
	s_xor_b64 s[60:61], s[24:25], -1
	v_mov_b32_e32 v56, s48
	v_mov_b32_e32 v57, s12
	s_lshl_b64 s[48:49], s[42:43], 8
	v_cmp_lt_i32_e32 vcc, -1, v70
	v_cndmask_b32_e64 v68, v56, v57, s[8:9]
	v_or_b32_e32 v56, s48, v69
	v_mov_b32_e32 v57, s49
	s_and_b64 s[30:31], vcc, s[60:61]
	s_and_saveexec_b64 s[24:25], s[30:31]
	s_cbranch_execz .LBB0_1354
	v_mov_b32_e32 v69, v161
	v_lshlrev_b32_e32 v160, 2, v68
	v_add_u32_e32 v69, 0, v69
	v_add_u32_e32 v69, 0x201c8, v69
	s_nop 0
	s_waitcnt lgkmcnt(0)
	v_readlane_b32 s31, v251, 51
	v_readlane_b32 s30, v251, 50
	s_nop 1
	v_lshl_add_u64 v[72:73], s[30:31], 0, v[160:161]
	v_lshlrev_b32_e32 v160, 1, v70
	v_lshl_add_u64 v[70:71], v[56:57], 0, v[160:161]
	v_lshlrev_b64 v[70:71], 8, v[70:71]
	v_lshl_add_u64 v[70:71], v[72:73], 0, v[70:71]
	v_lshl_add_u64 v[70:71], v[52:53], 2, v[70:71]
	global_store_dwordx4 v[70:71], v[48:51], off
	global_store_dwordx4 v[70:71], v[44:47], off offset:16
.LBB0_1354:
	s_or_b64 exec, exec, s[24:25]
	v_and_b32_e32 v49, 0xffff0000, v40
	v_lshlrev_b32_e32 v48, 16, v40
	v_mul_f32_e32 v50, v49, v49
	v_lshlrev_b32_e32 v46, 16, v41
	v_fmac_f32_e32 v50, v48, v48
	v_and_b32_e32 v47, 0xffff0000, v41
	v_fmac_f32_e32 v50, v46, v46
	v_and_b32_e32 v40, 0xffff0000, v42
	v_lshlrev_b32_e32 v41, 16, v42
	v_fmac_f32_e32 v50, v47, v47
	v_pk_mul_f32 v[44:45], v[40:41], v[40:41]
	v_pk_mov_b32 v[40:41], v[40:41], v[40:41] op_sel:[1,0]
	v_add_f32_e32 v42, v45, v50
	v_add_f32_e32 v50, v44, v42
	v_and_b32_e32 v42, 0xffff0000, v43
	v_lshlrev_b32_e32 v43, 16, v43
	v_pk_mul_f32 v[44:45], v[42:43], v[42:43]
	v_pk_mov_b32 v[42:43], v[42:43], v[42:43] op_sel:[1,0]
	v_add_f32_e32 v45, v45, v50
	v_add_f32_e32 v44, v44, v45
	s_and_b64 vcc, exec, s[6:7]
	s_nop 1
	v_add_f32_dpp v44, v44, v44 quad_perm:[1,0,3,2] row_mask:0xf bank_mask:0xf
	s_nop 1
	v_add_f32_dpp v44, v44, v44 quad_perm:[2,3,0,1] row_mask:0xf bank_mask:0xf
	s_nop 1
	v_add_f32_dpp v44, v44, v44 row_half_mirror row_mask:0xf bank_mask:0xf
	s_nop 0
	v_fmamk_f32 v44, v44, 0x3c800000, v189
	v_rsq_f32_e32 v44, v44
	s_nop 0
	v_mul_f32_e32 v45, v44, v48
	v_mul_f32_e32 v50, v44, v49
	v_mul_f32_e32 v51, v44, v46
	v_mul_f32_e32 v69, v58, v45
	v_mul_f32_e32 v45, v59, v50
	v_mul_f32_e32 v50, v60, v51
	v_mul_f32_e32 v51, v44, v47
	v_mul_f32_e32 v70, v44, v40
	v_mul_f32_e32 v71, v44, v41
	v_mul_f32_e32 v72, v44, v42
	v_mul_f32_e32 v44, v44, v43
	v_mul_f32_e32 v44, v67, v44
	v_cndmask_b32_e64 v43, v43, v44, s[8:9]
	v_cndmask_b32_e64 v44, v48, v69, s[8:9]
	v_add_u32_e32 v48, 16, v64
	v_mul_f32_e32 v51, v61, v51
	v_mul_f32_e32 v70, v62, v70
	v_mul_f32_e32 v71, v63, v71
	v_mul_f32_e32 v72, v65, v72
	v_cndmask_b32_e64 v45, v49, v45, s[8:9]
	v_add_u32_e32 v49, v55, v48
	v_cndmask_b32_e64 v42, v42, v72, s[8:9]
	v_cndmask_b32_e64 v41, v41, v71, s[8:9]
	v_cndmask_b32_e64 v40, v40, v70, s[8:9]
	v_cndmask_b32_e64 v47, v47, v51, s[8:9]
	v_cndmask_b32_e64 v46, v46, v50, s[8:9]
	v_mad_u64_u32 v[50:51], s[24:25], v49, s86, v[54:55]
	v_cvt_pk_bf16_f32 v70, v44, v45
	v_cvt_pk_bf16_f32 v71, v46, v47
	v_cvt_pk_bf16_f32 v72, v40, v41
	v_cvt_pk_bf16_f32 v73, v42, v43
	v_lshl_add_u32 v49, v50, 1, v66
	s_mov_b64 s[24:25], -1
	ds_write_b128 v49, v[70:73]
	s_cbranch_vccnz .LBB0_1374
	s_movk_i32 s16, 0x6f
	v_cmp_lt_i32_e32 vcc, s16, v64
	v_add_u32_e32 v49, s13, v48
	s_and_b64 vcc, s[18:19], vcc
	v_cndmask_b32_e32 v49, -1, v49, vcc
	s_cbranch_execz .LBB0_1375

; #define LAS __attribute__((address_space(3)))
; __device__ __forceinline__ bf16x8 pack8(const float* v) { u32x4 w; w.x = pk2(v[0], v[1]); w.y = pk2(v[2], v[3]); w.z = pk2(v[4], v[5]); w.w = pk2(v[6], v[7]); return __builtin_bit_cast(bf16x8, w); }
; __device__ __forceinline__ void unpack8(u32x4 w, float* v) { v[0] = bflo(w.x); v[1] = bfhi(w.x); v[2] = bflo(w.y); v[3] = bfhi(w.y); v[4] = bflo(w.z); v[5] = bfhi(w.z); v[6] = bflo(w.w); v[7] = bfhi(w.w); }
; __device__ __forceinline__ void mixer_unit(const Params& p, int layer, int cu, LAS unsigned char* L, int wv) {
;     ...
;         for (int ps = 0; ps < 12; ++ps) if (ps < npass) {
;             const int kk = klo + 16 * ps + rsub;
;             float v[8]; unpack8(raw[ps], v);
;             float ss = 0.f;
; #pragma unroll
;             for (int i = 0; i < 8; ++i) ss += v[i] * v[i];
;             ss += __shfl_xor(ss, 1); ss += __shfl_xor(ss, 2); ss += __shfl_xor(ss, 4);
;             const float rs = __builtin_amdgcn_rsqf(ss * (1.0f / 64.0f) + EPS);
; #pragma unroll
;             for (int i = 0; i < 8; ++i) { if (isK) v[i] = v[i] * rs * kn[i]; }
;             *(LAS bf16x8*)(L + (isK ? LK_OFF : LV_OFF) + ((kvh * 192 + kk) * KROW + sub * 8) * 2) = pack8(v);
;             int orow = -1;
;             if (is_s) orow = kk - 64; else if (c >= 30 && kk >= 128) orow = (c - 30) * 64 + (kk - 128);
;             if (orow >= 0 && !(isK && sub < 2)) {
;                 float* dst = POUT + (isK ? (is_s ? O_KS : O_KP) : (is_s ? O_VS : O_VP)) + ((((size_t)layer * NB + b) * 128 + orow) * 2 + kvh) * 64 + sub * 8;
;                 *(f32x4*)dst = (f32x4){v[0], v[1], v[2], v[3]}; *(f32x4*)(dst + 4) = (f32x4){v[4], v[5], v[6], v[7]};
;             }
;         }
.LBB0_1357:
	v_mov_b32_e32 v50, v161
	v_lshlrev_b32_e32 v160, 2, v68
	v_add_u32_e32 v50, 0, v50
	v_add_u32_e32 v50, 0x201c8, v50
	s_nop 0
	s_waitcnt lgkmcnt(0)
	v_readlane_b32 s31, v251, 51
	v_readlane_b32 s30, v251, 50
	s_nop 1
	v_lshl_add_u64 v[50:51], s[30:31], 0, v[160:161]
	v_lshlrev_b32_e32 v160, 1, v49
	v_lshl_add_u64 v[70:71], v[56:57], 0, v[160:161]
	v_lshlrev_b64 v[70:71], 8, v[70:71]
	v_lshl_add_u64 v[50:51], v[50:51], 0, v[70:71]
	v_lshl_add_u64 v[50:51], v[52:53], 2, v[50:51]
	global_store_dwordx4 v[50:51], v[44:47], off
	global_store_dwordx4 v[50:51], v[40:43], off offset:16
.LBB0_1358:
	s_or_b64 exec, exec, s[24:25]
	v_and_b32_e32 v45, 0xffff0000, v36
	v_lshlrev_b32_e32 v44, 16, v36
	v_mul_f32_e32 v46, v45, v45
	v_lshlrev_b32_e32 v42, 16, v37
	v_fmac_f32_e32 v46, v44, v44
	v_and_b32_e32 v43, 0xffff0000, v37
	v_fmac_f32_e32 v46, v42, v42
	v_and_b32_e32 v36, 0xffff0000, v38
	v_lshlrev_b32_e32 v37, 16, v38
	v_fmac_f32_e32 v46, v43, v43
	v_pk_mul_f32 v[40:41], v[36:37], v[36:37]
	v_pk_mov_b32 v[36:37], v[36:37], v[36:37] op_sel:[1,0]
	v_add_f32_e32 v38, v41, v46
	v_add_f32_e32 v46, v40, v38
	v_and_b32_e32 v38, 0xffff0000, v39
	v_lshlrev_b32_e32 v39, 16, v39
	v_pk_mul_f32 v[40:41], v[38:39], v[38:39]
	v_pk_mov_b32 v[38:39], v[38:39], v[38:39] op_sel:[1,0]
	v_add_f32_e32 v41, v41, v46
	v_add_f32_e32 v40, v40, v41
	s_and_b64 vcc, exec, s[6:7]
	s_nop 1
	v_add_f32_dpp v40, v40, v40 quad_perm:[1,0,3,2] row_mask:0xf bank_mask:0xf
	s_nop 1
	v_add_f32_dpp v40, v40, v40 quad_perm:[2,3,0,1] row_mask:0xf bank_mask:0xf
	s_nop 1
	v_add_f32_dpp v40, v40, v40 row_half_mirror row_mask:0xf bank_mask:0xf
	s_nop 0
	v_fmamk_f32 v40, v40, 0x3c800000, v189
	v_rsq_f32_e32 v40, v40
	s_nop 0
	v_mul_f32_e32 v41, v40, v44
	v_mul_f32_e32 v46, v40, v45
	v_mul_f32_e32 v47, v40, v42
	v_mul_f32_e32 v49, v58, v41
	v_mul_f32_e32 v41, v59, v46
	v_mul_f32_e32 v46, v60, v47
	v_mul_f32_e32 v47, v40, v43
	v_mul_f32_e32 v50, v40, v36
	v_mul_f32_e32 v51, v40, v37
	v_mul_f32_e32 v69, v40, v38
	v_mul_f32_e32 v40, v40, v39
	v_mul_f32_e32 v40, v67, v40
	v_cndmask_b32_e64 v39, v39, v40, s[8:9]
	v_cndmask_b32_e64 v40, v44, v49, s[8:9]
	v_add_u32_e32 v44, 32, v64
	v_mul_f32_e32 v47, v61, v47
	v_mul_f32_e32 v50, v62, v50
	v_mul_f32_e32 v51, v63, v51
	v_mul_f32_e32 v69, v65, v69
	v_cndmask_b32_e64 v41, v45, v41, s[8:9]
	v_add_u32_e32 v45, v55, v44
	v_cndmask_b32_e64 v38, v38, v69, s[8:9]
	v_cndmask_b32_e64 v37, v37, v51, s[8:9]
	v_cndmask_b32_e64 v36, v36, v50, s[8:9]
	v_cndmask_b32_e64 v43, v43, v47, s[8:9]
	v_cndmask_b32_e64 v42, v42, v46, s[8:9]
	v_mad_u64_u32 v[46:47], s[24:25], v45, s86, v[54:55]
	v_cvt_pk_bf16_f32 v70, v40, v41
	v_cvt_pk_bf16_f32 v71, v42, v43
	v_cvt_pk_bf16_f32 v72, v36, v37
	v_cvt_pk_bf16_f32 v73, v38, v39
	v_lshl_add_u32 v45, v46, 1, v66
	s_mov_b64 s[24:25], -1
	ds_write_b128 v45, v[70:73]
	s_cbranch_vccnz .LBB0_1376
	s_movk_i32 s16, 0x5f
	v_cmp_lt_i32_e32 vcc, s16, v64
	v_add_u32_e32 v45, s13, v44
	s_and_b64 vcc, s[18:19], vcc
	v_cndmask_b32_e32 v45, -1, v45, vcc
	s_cbranch_execz .LBB0_1377

; #define LAS __attribute__((address_space(3)))
; __device__ __forceinline__ bf16x8 pack8(const float* v) { u32x4 w; w.x = pk2(v[0], v[1]); w.y = pk2(v[2], v[3]); w.z = pk2(v[4], v[5]); w.w = pk2(v[6], v[7]); return __builtin_bit_cast(bf16x8, w); }
; __device__ __forceinline__ void unpack8(u32x4 w, float* v) { v[0] = bflo(w.x); v[1] = bfhi(w.x); v[2] = bflo(w.y); v[3] = bfhi(w.y); v[4] = bflo(w.z); v[5] = bfhi(w.z); v[6] = bflo(w.w); v[7] = bfhi(w.w); }
; __device__ __forceinline__ void mixer_unit(const Params& p, int layer, int cu, LAS unsigned char* L, int wv) {
;     ...
;         for (int ps = 0; ps < 12; ++ps) if (ps < npass) {
;             const int kk = klo + 16 * ps + rsub;
;             float v[8]; unpack8(raw[ps], v);
;             float ss = 0.f;
; #pragma unroll
;             for (int i = 0; i < 8; ++i) ss += v[i] * v[i];
;             ss += __shfl_xor(ss, 1); ss += __shfl_xor(ss, 2); ss += __shfl_xor(ss, 4);
;             const float rs = __builtin_amdgcn_rsqf(ss * (1.0f / 64.0f) + EPS);
; #pragma unroll
;             for (int i = 0; i < 8; ++i) { if (isK) v[i] = v[i] * rs * kn[i]; }
;             *(LAS bf16x8*)(L + (isK ? LK_OFF : LV_OFF) + ((kvh * 192 + kk) * KROW + sub * 8) * 2) = pack8(v);
;             int orow = -1;
;             if (is_s) orow = kk - 64; else if (c >= 30 && kk >= 128) orow = (c - 30) * 64 + (kk - 128);
;             if (orow >= 0 && !(isK && sub < 2)) {
;                 float* dst = POUT + (isK ? (is_s ? O_KS : O_KP) : (is_s ? O_VS : O_VP)) + ((((size_t)layer * NB + b) * 128 + orow) * 2 + kvh) * 64 + sub * 8;
;                 *(f32x4*)dst = (f32x4){v[0], v[1], v[2], v[3]}; *(f32x4*)(dst + 4) = (f32x4){v[4], v[5], v[6], v[7]};
;             }
;         }
.LBB0_1361:
	v_mov_b32_e32 v46, v161
	v_lshlrev_b32_e32 v160, 2, v68
	v_add_u32_e32 v46, 0, v46
	v_add_u32_e32 v46, 0x201c8, v46
	s_nop 0
	s_waitcnt lgkmcnt(0)
	v_readlane_b32 s31, v251, 51
	v_readlane_b32 s30, v251, 50
	s_nop 1
	v_lshl_add_u64 v[46:47], s[30:31], 0, v[160:161]
	v_lshlrev_b32_e32 v160, 1, v45
	v_lshl_add_u64 v[50:51], v[56:57], 0, v[160:161]
	v_lshlrev_b64 v[50:51], 8, v[50:51]
	v_lshl_add_u64 v[46:47], v[46:47], 0, v[50:51]
	v_lshl_add_u64 v[46:47], v[52:53], 2, v[46:47]
	global_store_dwordx4 v[46:47], v[40:43], off
	global_store_dwordx4 v[46:47], v[36:39], off offset:16
.LBB0_1362:
	s_or_b64 exec, exec, s[24:25]
	v_and_b32_e32 v41, 0xffff0000, v32
	v_lshlrev_b32_e32 v40, 16, v32
	v_mul_f32_e32 v42, v41, v41
	v_lshlrev_b32_e32 v38, 16, v33
	v_fmac_f32_e32 v42, v40, v40
	v_and_b32_e32 v39, 0xffff0000, v33
	v_fmac_f32_e32 v42, v38, v38
	v_and_b32_e32 v32, 0xffff0000, v34
	v_lshlrev_b32_e32 v33, 16, v34
	v_fmac_f32_e32 v42, v39, v39
	v_pk_mul_f32 v[36:37], v[32:33], v[32:33]
	v_pk_mov_b32 v[32:33], v[32:33], v[32:33] op_sel:[1,0]
	v_add_f32_e32 v34, v37, v42
	v_add_f32_e32 v42, v36, v34
	v_and_b32_e32 v34, 0xffff0000, v35
	v_lshlrev_b32_e32 v35, 16, v35
	v_pk_mul_f32 v[36:37], v[34:35], v[34:35]
	v_pk_mov_b32 v[34:35], v[34:35], v[34:35] op_sel:[1,0]
	v_add_f32_e32 v37, v37, v42
	v_add_f32_e32 v36, v36, v37
	s_and_b64 vcc, exec, s[6:7]
	s_nop 1
	v_add_f32_dpp v36, v36, v36 quad_perm:[1,0,3,2] row_mask:0xf bank_mask:0xf
	s_nop 1
	v_add_f32_dpp v36, v36, v36 quad_perm:[2,3,0,1] row_mask:0xf bank_mask:0xf
	s_nop 1
	v_add_f32_dpp v36, v36, v36 row_half_mirror row_mask:0xf bank_mask:0xf
	s_nop 0
	v_fmamk_f32 v36, v36, 0x3c800000, v189
	v_rsq_f32_e32 v36, v36
	s_nop 0
	v_mul_f32_e32 v37, v36, v40
	v_mul_f32_e32 v42, v36, v41
	v_mul_f32_e32 v43, v36, v38
	v_mul_f32_e32 v45, v58, v37
	v_mul_f32_e32 v37, v59, v42
	v_mul_f32_e32 v42, v60, v43
	v_mul_f32_e32 v43, v36, v39
	v_mul_f32_e32 v46, v36, v32
	v_mul_f32_e32 v47, v36, v33
	v_mul_f32_e32 v49, v36, v34
	v_mul_f32_e32 v36, v36, v35
	v_mul_f32_e32 v36, v67, v36
	v_cndmask_b32_e64 v35, v35, v36, s[8:9]
	v_cndmask_b32_e64 v36, v40, v45, s[8:9]
	v_add_u32_e32 v40, 48, v64
	v_mul_f32_e32 v43, v61, v43
	v_mul_f32_e32 v46, v62, v46
	v_mul_f32_e32 v47, v63, v47
	v_mul_f32_e32 v49, v65, v49
	v_cndmask_b32_e64 v37, v41, v37, s[8:9]
	v_add_u32_e32 v41, v55, v40
	v_cndmask_b32_e64 v34, v34, v49, s[8:9]
	v_cndmask_b32_e64 v33, v33, v47, s[8:9]
	v_cndmask_b32_e64 v32, v32, v46, s[8:9]
	v_cndmask_b32_e64 v39, v39, v43, s[8:9]
	v_cndmask_b32_e64 v38, v38, v42, s[8:9]
	v_mad_u64_u32 v[42:43], s[24:25], v41, s86, v[54:55]
	v_cvt_pk_bf16_f32 v70, v36, v37
	v_cvt_pk_bf16_f32 v71, v38, v39
	v_cvt_pk_bf16_f32 v72, v32, v33
	v_cvt_pk_bf16_f32 v73, v34, v35
	v_lshl_add_u32 v41, v42, 1, v66
	s_mov_b64 s[24:25], -1
	ds_write_b128 v41, v[70:73]
	s_cbranch_vccnz .LBB0_1378
	s_movk_i32 s16, 0x4f
	v_cmp_lt_i32_e32 vcc, s16, v64
	v_add_u32_e32 v41, s13, v40
	s_and_b64 vcc, s[18:19], vcc
	v_cndmask_b32_e32 v41, -1, v41, vcc
	s_cbranch_execz .LBB0_1379

; __device__ __forceinline__ void mixer_unit(const Params& p, int layer, int cu, LAS unsigned char* L, int wv) {
;     ...
;             int orow = -1;
;             if (is_s) orow = kk - 64; else if (c >= 30 && kk >= 128) orow = (c - 30) * 64 + (kk - 128);
;             if (orow >= 0 && !(isK && sub < 2)) {
;                 float* dst = POUT + (isK ? (is_s ? O_KS : O_KP) : (is_s ? O_VS : O_VP)) + ((((size_t)layer * NB + b) * 128 + orow) * 2 + kvh) * 64 + sub * 8;
;                 *(f32x4*)dst = (f32x4){v[0], v[1], v[2], v[3]}; *(f32x4*)(dst + 4) = (f32x4){v[4], v[5], v[6], v[7]};
;             }
.LBB0_1365:
	v_mov_b32_e32 v42, v161
	v_lshlrev_b32_e32 v160, 2, v68
	v_add_u32_e32 v42, 0, v42
	v_add_u32_e32 v42, 0x201c8, v42
	s_nop 0
	s_waitcnt lgkmcnt(0)
	v_readlane_b32 s31, v251, 51
	v_readlane_b32 s30, v251, 50
	s_nop 1
	v_lshl_add_u64 v[42:43], s[30:31], 0, v[160:161]
	v_lshlrev_b32_e32 v160, 1, v41
	v_lshl_add_u64 v[46:47], v[56:57], 0, v[160:161]
	v_lshlrev_b64 v[46:47], 8, v[46:47]
	v_lshl_add_u64 v[42:43], v[42:43], 0, v[46:47]
	v_lshl_add_u64 v[42:43], v[52:53], 2, v[42:43]
	global_store_dwordx4 v[42:43], v[36:39], off
	global_store_dwordx4 v[42:43], v[32:35], off offset:16
	s_or_b64 exec, exec, s[24:25]
	s_andn2_b64 vcc, exec, s[56:57]
	s_cbranch_vccz .LBB0_1381

; #define LAS __attribute__((address_space(3)))
; __device__ __forceinline__ bf16x8 pack8(const float* v) { u32x4 w; w.x = pk2(v[0], v[1]); w.y = pk2(v[2], v[3]); w.z = pk2(v[4], v[5]); w.w = pk2(v[6], v[7]); return __builtin_bit_cast(bf16x8, w); }
; __device__ __forceinline__ void unpack8(u32x4 w, float* v) { v[0] = bflo(w.x); v[1] = bfhi(w.x); v[2] = bflo(w.y); v[3] = bfhi(w.y); v[4] = bflo(w.z); v[5] = bfhi(w.z); v[6] = bflo(w.w); v[7] = bfhi(w.w); }
; __device__ __forceinline__ void mixer_unit(const Params& p, int layer, int cu, LAS unsigned char* L, int wv) {
;     ...
;         for (int ps = 0; ps < 12; ++ps) if (ps < npass) {
;             const int kk = klo + 16 * ps + rsub;
;             float v[8]; unpack8(raw[ps], v);
;             float ss = 0.f;
; #pragma unroll
;             for (int i = 0; i < 8; ++i) ss += v[i] * v[i];
;             ss += __shfl_xor(ss, 1); ss += __shfl_xor(ss, 2); ss += __shfl_xor(ss, 4);
;             const float rs = __builtin_amdgcn_rsqf(ss * (1.0f / 64.0f) + EPS);
; #pragma unroll
;             for (int i = 0; i < 8; ++i) { if (isK) v[i] = v[i] * rs * kn[i]; }
;             *(LAS bf16x8*)(L + (isK ? LK_OFF : LV_OFF) + ((kvh * 192 + kk) * KROW + sub * 8) * 2) = pack8(v);
;             int orow = -1;
;             if (is_s) orow = kk - 64; else if (c >= 30 && kk >= 128) orow = (c - 30) * 64 + (kk - 128);
;             if (orow >= 0 && !(isK && sub < 2)) {
;                 float* dst = POUT + (isK ? (is_s ? O_KS : O_KP) : (is_s ? O_VS : O_VP)) + ((((size_t)layer * NB + b) * 128 + orow) * 2 + kvh) * 64 + sub * 8;
;                 *(f32x4*)dst = (f32x4){v[0], v[1], v[2], v[3]}; *(f32x4*)(dst + 4) = (f32x4){v[4], v[5], v[6], v[7]};
;             }
;         }
.LBB0_1367:
	v_and_b32_e32 v33, 0xffff0000, v24
	v_lshlrev_b32_e32 v32, 16, v24
	v_mul_f32_e32 v34, v33, v33
	v_lshlrev_b32_e32 v30, 16, v25
	v_fmac_f32_e32 v34, v32, v32
	v_and_b32_e32 v31, 0xffff0000, v25
	v_fmac_f32_e32 v34, v30, v30
	v_and_b32_e32 v24, 0xffff0000, v26
	v_lshlrev_b32_e32 v25, 16, v26
	v_fmac_f32_e32 v34, v31, v31
	v_pk_mul_f32 v[28:29], v[24:25], v[24:25]
	v_pk_mov_b32 v[24:25], v[24:25], v[24:25] op_sel:[1,0]
	v_add_f32_e32 v26, v29, v34
	v_add_f32_e32 v34, v28, v26
	v_and_b32_e32 v26, 0xffff0000, v27
	v_lshlrev_b32_e32 v27, 16, v27
	v_pk_mul_f32 v[28:29], v[26:27], v[26:27]
	v_pk_mov_b32 v[26:27], v[26:27], v[26:27] op_sel:[1,0]
	v_add_f32_e32 v29, v29, v34
	v_add_f32_e32 v28, v28, v29
	v_cmp_lt_i32_e32 vcc, 47, v64
	s_and_b64 vcc, s[18:19], vcc
	s_nop 1
	v_add_f32_dpp v28, v28, v28 quad_perm:[1,0,3,2] row_mask:0xf bank_mask:0xf
	s_nop 1
	v_add_f32_dpp v28, v28, v28 quad_perm:[2,3,0,1] row_mask:0xf bank_mask:0xf
	s_nop 1
	v_add_f32_dpp v28, v28, v28 row_half_mirror row_mask:0xf bank_mask:0xf
	s_nop 0
	v_fmamk_f32 v28, v28, 0x3c800000, v189
	v_rsq_f32_e32 v28, v28
	s_nop 0
	v_mul_f32_e32 v29, v28, v32
	v_mul_f32_e32 v34, v28, v33
	v_mul_f32_e32 v35, v28, v30
	v_mul_f32_e32 v38, v28, v25
	v_mul_f32_e32 v36, v58, v29
	v_mul_f32_e32 v29, v59, v34
	v_mul_f32_e32 v34, v60, v35
	v_mul_f32_e32 v35, v28, v31
	v_mul_f32_e32 v37, v28, v24
	v_mul_f32_e32 v38, v63, v38
	v_mul_f32_e32 v39, v28, v26
	v_mul_f32_e32 v28, v28, v27
	v_mul_f32_e32 v28, v67, v28
	v_cndmask_b32_e64 v25, v25, v38, s[8:9]
	v_add_u32_e32 v38, 0x50, v64
	v_mul_f32_e32 v35, v61, v35
	v_mul_f32_e32 v37, v62, v37
	v_mul_f32_e32 v39, v65, v39
	v_cndmask_b32_e64 v27, v27, v28, s[8:9]
	v_cndmask_b32_e64 v28, v32, v36, s[8:9]
	v_add_u32_e32 v36, v55, v38
	v_cndmask_b32_e64 v26, v26, v39, s[8:9]
	v_cndmask_b32_e64 v24, v24, v37, s[8:9]
	v_cndmask_b32_e64 v31, v31, v35, s[8:9]
	v_cndmask_b32_e64 v30, v30, v34, s[8:9]
	v_cndmask_b32_e64 v29, v33, v29, s[8:9]
	v_mad_u64_u32 v[36:37], s[24:25], v36, s86, v[54:55]
	v_cvt_pk_bf16_f32 v32, v28, v29
	v_cvt_pk_bf16_f32 v33, v30, v31
	v_cvt_pk_bf16_f32 v34, v24, v25
	v_cvt_pk_bf16_f32 v35, v26, v27
	v_lshl_add_u32 v36, v36, 1, v66
	ds_write_b128 v36, v[32:35]
	v_add_u32_e32 v32, s13, v38
	v_cndmask_b32_e32 v32, -1, v32, vcc
	v_cndmask_b32_e64 v32, v32, v48, s[4:5]
	v_cmp_lt_i32_e32 vcc, -1, v32
	s_and_b64 s[30:31], vcc, s[60:61]
	s_and_saveexec_b64 s[24:25], s[30:31]
	s_cbranch_execz .LBB0_1369
	v_mov_b32_e32 v33, v161
	v_lshlrev_b32_e32 v160, 2, v68
	v_add_u32_e32 v33, 0, v33
	v_add_u32_e32 v33, 0x201c8, v33
	s_nop 0
	s_waitcnt lgkmcnt(0)
	v_readlane_b32 s31, v251, 51
	v_readlane_b32 s30, v251, 50
	s_nop 1
	v_lshl_add_u64 v[34:35], s[30:31], 0, v[160:161]
	v_lshlrev_b32_e32 v160, 1, v32
	v_lshl_add_u64 v[32:33], v[56:57], 0, v[160:161]
	v_lshlrev_b64 v[32:33], 8, v[32:33]
	v_lshl_add_u64 v[32:33], v[34:35], 0, v[32:33]
	v_lshl_add_u64 v[32:33], v[52:53], 2, v[32:33]
	global_store_dwordx4 v[32:33], v[28:31], off
	global_store_dwordx4 v[32:33], v[24:27], off offset:16

; #define LAS __attribute__((address_space(3)))
; __device__ __forceinline__ bf16x8 pack8(const float* v) { u32x4 w; w.x = pk2(v[0], v[1]); w.y = pk2(v[2], v[3]); w.z = pk2(v[4], v[5]); w.w = pk2(v[6], v[7]); return __builtin_bit_cast(bf16x8, w); }
; __device__ __forceinline__ void unpack8(u32x4 w, float* v) { v[0] = bflo(w.x); v[1] = bfhi(w.x); v[2] = bflo(w.y); v[3] = bfhi(w.y); v[4] = bflo(w.z); v[5] = bfhi(w.z); v[6] = bflo(w.w); v[7] = bfhi(w.w); }
; __device__ __forceinline__ void mixer_unit(const Params& p, int layer, int cu, LAS unsigned char* L, int wv) {
;     ...
;         for (int ps = 0; ps < 12; ++ps) if (ps < npass) {
;             const int kk = klo + 16 * ps + rsub;
;             float v[8]; unpack8(raw[ps], v);
;             float ss = 0.f;
; #pragma unroll
;             for (int i = 0; i < 8; ++i) ss += v[i] * v[i];
;             ss += __shfl_xor(ss, 1); ss += __shfl_xor(ss, 2); ss += __shfl_xor(ss, 4);
;             const float rs = __builtin_amdgcn_rsqf(ss * (1.0f / 64.0f) + EPS);
; #pragma unroll
;             for (int i = 0; i < 8; ++i) { if (isK) v[i] = v[i] * rs * kn[i]; }
;             *(LAS bf16x8*)(L + (isK ? LK_OFF : LV_OFF) + ((kvh * 192 + kk) * KROW + sub * 8) * 2) = pack8(v);
;             int orow = -1;
;             if (is_s) orow = kk - 64; else if (c >= 30 && kk >= 128) orow = (c - 30) * 64 + (kk - 128);
;             if (orow >= 0 && !(isK && sub < 2)) {
;                 float* dst = POUT + (isK ? (is_s ? O_KS : O_KP) : (is_s ? O_VS : O_VP)) + ((((size_t)layer * NB + b) * 128 + orow) * 2 + kvh) * 64 + sub * 8;
;                 *(f32x4*)dst = (f32x4){v[0], v[1], v[2], v[3]}; *(f32x4*)(dst + 4) = (f32x4){v[4], v[5], v[6], v[7]};
;             }
;         }
.LBB0_1371:
	v_and_b32_e32 v25, 0xffff0000, v16
	v_lshlrev_b32_e32 v24, 16, v16
	v_mul_f32_e32 v26, v25, v25
	v_lshlrev_b32_e32 v22, 16, v17
	v_fmac_f32_e32 v26, v24, v24
	v_and_b32_e32 v23, 0xffff0000, v17
	v_fmac_f32_e32 v26, v22, v22
	v_and_b32_e32 v16, 0xffff0000, v18
	v_lshlrev_b32_e32 v17, 16, v18
	v_fmac_f32_e32 v26, v23, v23
	v_pk_mul_f32 v[20:21], v[16:17], v[16:17]
	v_pk_mov_b32 v[16:17], v[16:17], v[16:17] op_sel:[1,0]
	v_add_f32_e32 v18, v21, v26
	v_add_f32_e32 v26, v20, v18
	v_and_b32_e32 v18, 0xffff0000, v19
	v_lshlrev_b32_e32 v19, 16, v19
	v_pk_mul_f32 v[20:21], v[18:19], v[18:19]
	v_pk_mov_b32 v[18:19], v[18:19], v[18:19] op_sel:[1,0]
	v_add_f32_e32 v21, v21, v26
	v_add_f32_e32 v20, v20, v21
	v_cmp_lt_i32_e32 vcc, 15, v64
	s_and_b64 vcc, s[18:19], vcc
	s_nop 1
	v_add_f32_dpp v20, v20, v20 quad_perm:[1,0,3,2] row_mask:0xf bank_mask:0xf
	s_nop 1
	v_add_f32_dpp v20, v20, v20 quad_perm:[2,3,0,1] row_mask:0xf bank_mask:0xf
	s_nop 1
	v_add_f32_dpp v20, v20, v20 row_half_mirror row_mask:0xf bank_mask:0xf
	s_nop 0
	v_fmamk_f32 v20, v20, 0x3c800000, v189
	v_rsq_f32_e32 v20, v20
	s_nop 0
	v_mul_f32_e32 v21, v20, v24
	v_mul_f32_e32 v26, v20, v25
	v_mul_f32_e32 v27, v20, v22
	v_mul_f32_e32 v30, v20, v17
	v_mul_f32_e32 v28, v58, v21
	v_mul_f32_e32 v21, v59, v26
	v_mul_f32_e32 v26, v60, v27
	v_mul_f32_e32 v27, v20, v23
	v_mul_f32_e32 v29, v20, v16
	v_mul_f32_e32 v30, v63, v30
	v_mul_f32_e32 v31, v20, v18
	v_mul_f32_e32 v20, v20, v19
	v_mul_f32_e32 v20, v67, v20
	v_cndmask_b32_e64 v17, v17, v30, s[8:9]
	v_add_u32_e32 v30, 0x70, v64
	v_mul_f32_e32 v27, v61, v27
	v_mul_f32_e32 v29, v62, v29
	v_mul_f32_e32 v31, v65, v31
	v_cndmask_b32_e64 v19, v19, v20, s[8:9]
	v_cndmask_b32_e64 v20, v24, v28, s[8:9]
	v_add_u32_e32 v28, v55, v30
	v_cndmask_b32_e64 v18, v18, v31, s[8:9]
	v_cndmask_b32_e64 v16, v16, v29, s[8:9]
	v_cndmask_b32_e64 v23, v23, v27, s[8:9]
	v_cndmask_b32_e64 v22, v22, v26, s[8:9]
	v_cndmask_b32_e64 v21, v25, v21, s[8:9]
	v_mad_u64_u32 v[28:29], s[24:25], v28, s86, v[54:55]
	v_cvt_pk_bf16_f32 v24, v20, v21
	v_cvt_pk_bf16_f32 v25, v22, v23
	v_cvt_pk_bf16_f32 v26, v16, v17
	v_cvt_pk_bf16_f32 v27, v18, v19
	v_lshl_add_u32 v28, v28, 1, v66
	ds_write_b128 v28, v[24:27]
	v_add_u32_e32 v24, s13, v30
	v_cndmask_b32_e32 v24, -1, v24, vcc
	v_cndmask_b32_e64 v24, v24, v40, s[4:5]
	v_cmp_lt_i32_e32 vcc, -1, v24
	s_and_b64 s[30:31], vcc, s[60:61]
	s_and_saveexec_b64 s[24:25], s[30:31]
	s_cbranch_execz .LBB0_1373
	v_mov_b32_e32 v25, v161
	v_lshlrev_b32_e32 v160, 2, v68
	v_add_u32_e32 v25, 0, v25
	v_add_u32_e32 v25, 0x201c8, v25
	s_nop 0
	s_waitcnt lgkmcnt(0)
	v_readlane_b32 s31, v251, 51
	v_readlane_b32 s30, v251, 50
	s_nop 1
	v_lshl_add_u64 v[26:27], s[30:31], 0, v[160:161]
	v_lshlrev_b32_e32 v160, 1, v24
	v_lshl_add_u64 v[24:25], v[56:57], 0, v[160:161]
	v_lshlrev_b64 v[24:25], 8, v[24:25]
	v_lshl_add_u64 v[24:25], v[26:27], 0, v[24:25]
	v_lshl_add_u64 v[24:25], v[52:53], 2, v[24:25]
	global_store_dwordx4 v[24:25], v[20:23], off
	global_store_dwordx4 v[24:25], v[16:19], off offset:16

; #define LAS __attribute__((address_space(3)))
; __device__ __forceinline__ bf16x8 pack8(const float* v) { u32x4 w; w.x = pk2(v[0], v[1]); w.y = pk2(v[2], v[3]); w.z = pk2(v[4], v[5]); w.w = pk2(v[6], v[7]); return __builtin_bit_cast(bf16x8, w); }
; __device__ __forceinline__ void unpack8(u32x4 w, float* v) { v[0] = bflo(w.x); v[1] = bfhi(w.x); v[2] = bflo(w.y); v[3] = bfhi(w.y); v[4] = bflo(w.z); v[5] = bfhi(w.z); v[6] = bflo(w.w); v[7] = bfhi(w.w); }
; __device__ __forceinline__ void mixer_unit(const Params& p, int layer, int cu, LAS unsigned char* L, int wv) {
;     ...
;         for (int ps = 0; ps < 12; ++ps) if (ps < npass) {
;             const int kk = klo + 16 * ps + rsub;
;             float v[8]; unpack8(raw[ps], v);
;             float ss = 0.f;
; #pragma unroll
;             for (int i = 0; i < 8; ++i) ss += v[i] * v[i];
;             ss += __shfl_xor(ss, 1); ss += __shfl_xor(ss, 2); ss += __shfl_xor(ss, 4);
;             const float rs = __builtin_amdgcn_rsqf(ss * (1.0f / 64.0f) + EPS);
; #pragma unroll
;             for (int i = 0; i < 8; ++i) { if (isK) v[i] = v[i] * rs * kn[i]; }
;             *(LAS bf16x8*)(L + (isK ? LK_OFF : LV_OFF) + ((kvh * 192 + kk) * KROW + sub * 8) * 2) = pack8(v);
;             int orow = -1;
;             if (is_s) orow = kk - 64; else if (c >= 30 && kk >= 128) orow = (c - 30) * 64 + (kk - 128);
;             if (orow >= 0 && !(isK && sub < 2)) {
;                 float* dst = POUT + (isK ? (is_s ? O_KS : O_KP) : (is_s ? O_VS : O_VP)) + ((((size_t)layer * NB + b) * 128 + orow) * 2 + kvh) * 64 + sub * 8;
;                 *(f32x4*)dst = (f32x4){v[0], v[1], v[2], v[3]}; *(f32x4*)(dst + 4) = (f32x4){v[4], v[5], v[6], v[7]};
;             }
;         }
.LBB0_1381:
	v_and_b32_e32 v37, 0xffff0000, v28
	v_lshlrev_b32_e32 v36, 16, v28
	v_mul_f32_e32 v38, v37, v37
	v_lshlrev_b32_e32 v34, 16, v29
	v_fmac_f32_e32 v38, v36, v36
	v_and_b32_e32 v35, 0xffff0000, v29
	v_fmac_f32_e32 v38, v34, v34
	v_and_b32_e32 v28, 0xffff0000, v30
	v_lshlrev_b32_e32 v29, 16, v30
	v_fmac_f32_e32 v38, v35, v35
	v_pk_mul_f32 v[32:33], v[28:29], v[28:29]
	v_pk_mov_b32 v[28:29], v[28:29], v[28:29] op_sel:[1,0]
	v_add_f32_e32 v30, v33, v38
	v_add_f32_e32 v38, v32, v30
	v_and_b32_e32 v30, 0xffff0000, v31
	v_lshlrev_b32_e32 v31, 16, v31
	v_pk_mul_f32 v[32:33], v[30:31], v[30:31]
	v_pk_mov_b32 v[30:31], v[30:31], v[30:31] op_sel:[1,0]
	v_add_f32_e32 v33, v33, v38
	v_add_f32_e32 v32, v32, v33
	v_cmp_lt_i32_e32 vcc, 63, v64
	s_and_b64 vcc, s[18:19], vcc
	s_nop 1
	v_add_f32_dpp v32, v32, v32 quad_perm:[1,0,3,2] row_mask:0xf bank_mask:0xf
	s_nop 1
	v_add_f32_dpp v32, v32, v32 quad_perm:[2,3,0,1] row_mask:0xf bank_mask:0xf
	s_nop 1
	v_add_f32_dpp v32, v32, v32 row_half_mirror row_mask:0xf bank_mask:0xf
	s_nop 0
	v_fmamk_f32 v32, v32, 0x3c800000, v189
	v_rsq_f32_e32 v32, v32
	s_nop 0
	v_mul_f32_e32 v33, v32, v36
	v_mul_f32_e32 v38, v32, v37
	v_mul_f32_e32 v39, v32, v34
	v_mul_f32_e32 v41, v58, v33
	v_mul_f32_e32 v33, v59, v38
	v_mul_f32_e32 v38, v60, v39
	v_mul_f32_e32 v39, v32, v35
	v_mul_f32_e32 v42, v32, v28
	v_mul_f32_e32 v43, v32, v29
	v_mul_f32_e32 v45, v32, v30
	v_mul_f32_e32 v32, v32, v31
	v_mul_f32_e32 v32, v67, v32
	v_mul_f32_e32 v42, v62, v42
	v_cndmask_b32_e64 v31, v31, v32, s[8:9]
	v_cndmask_b32_e64 v32, v36, v41, s[8:9]
	v_add_u32_e32 v41, 64, v64
	v_mul_f32_e32 v39, v61, v39
	v_mul_f32_e32 v43, v63, v43
	v_mul_f32_e32 v45, v65, v45
	v_cndmask_b32_e64 v28, v28, v42, s[8:9]
	v_add_u32_e32 v42, v55, v41
	v_cndmask_b32_e64 v30, v30, v45, s[8:9]
	v_cndmask_b32_e64 v29, v29, v43, s[8:9]
	v_cndmask_b32_e64 v35, v35, v39, s[8:9]
	v_cndmask_b32_e64 v34, v34, v38, s[8:9]
	v_cndmask_b32_e64 v33, v37, v33, s[8:9]
	v_mad_u64_u32 v[42:43], s[24:25], v42, s86, v[54:55]
	v_cvt_pk_bf16_f32 v36, v32, v33
	v_cvt_pk_bf16_f32 v37, v34, v35
	v_cvt_pk_bf16_f32 v38, v28, v29
	v_cvt_pk_bf16_f32 v39, v30, v31
	v_lshl_add_u32 v42, v42, 1, v66
	ds_write_b128 v42, v[36:39]
	v_add_u32_e32 v36, s13, v41
	v_cndmask_b32_e32 v36, -1, v36, vcc
	v_cndmask_b32_e64 v36, v36, v64, s[4:5]
	v_cmp_lt_i32_e32 vcc, -1, v36
	s_and_b64 s[30:31], vcc, s[60:61]
	s_and_saveexec_b64 s[24:25], s[30:31]
	s_cbranch_execz .LBB0_1383
	v_mov_b32_e32 v37, v161
	v_lshlrev_b32_e32 v160, 2, v68
	v_add_u32_e32 v37, 0, v37
	v_add_u32_e32 v37, 0x201c8, v37
	s_nop 0
	s_waitcnt lgkmcnt(0)
	v_readlane_b32 s31, v251, 51
	v_readlane_b32 s30, v251, 50
	s_nop 1
	v_lshl_add_u64 v[38:39], s[30:31], 0, v[160:161]
	v_lshlrev_b32_e32 v160, 1, v36
	v_lshl_add_u64 v[36:37], v[56:57], 0, v[160:161]
	v_lshlrev_b64 v[36:37], 8, v[36:37]
	v_lshl_add_u64 v[36:37], v[38:39], 0, v[36:37]
	v_lshl_add_u64 v[36:37], v[52:53], 2, v[36:37]
	global_store_dwordx4 v[36:37], v[32:35], off
	global_store_dwordx4 v[36:37], v[28:31], off offset:16

; #define LAS __attribute__((address_space(3)))
; __device__ __forceinline__ bf16x8 pack8(const float* v) { u32x4 w; w.x = pk2(v[0], v[1]); w.y = pk2(v[2], v[3]); w.z = pk2(v[4], v[5]); w.w = pk2(v[6], v[7]); return __builtin_bit_cast(bf16x8, w); }
; __device__ __forceinline__ void unpack8(u32x4 w, float* v) { v[0] = bflo(w.x); v[1] = bfhi(w.x); v[2] = bflo(w.y); v[3] = bfhi(w.y); v[4] = bflo(w.z); v[5] = bfhi(w.z); v[6] = bflo(w.w); v[7] = bfhi(w.w); }
; __device__ __forceinline__ void mixer_unit(const Params& p, int layer, int cu, LAS unsigned char* L, int wv) {
;     ...
;         for (int ps = 0; ps < 12; ++ps) if (ps < npass) {
;             const int kk = klo + 16 * ps + rsub;
;             float v[8]; unpack8(raw[ps], v);
;             float ss = 0.f;
; #pragma unroll
;             for (int i = 0; i < 8; ++i) ss += v[i] * v[i];
;             ss += __shfl_xor(ss, 1); ss += __shfl_xor(ss, 2); ss += __shfl_xor(ss, 4);
;             const float rs = __builtin_amdgcn_rsqf(ss * (1.0f / 64.0f) + EPS);
; #pragma unroll
;             for (int i = 0; i < 8; ++i) { if (isK) v[i] = v[i] * rs * kn[i]; }
;             *(LAS bf16x8*)(L + (isK ? LK_OFF : LV_OFF) + ((kvh * 192 + kk) * KROW + sub * 8) * 2) = pack8(v);
;             int orow = -1;
;             if (is_s) orow = kk - 64; else if (c >= 30 && kk >= 128) orow = (c - 30) * 64 + (kk - 128);
;             if (orow >= 0 && !(isK && sub < 2)) {
;                 float* dst = POUT + (isK ? (is_s ? O_KS : O_KP) : (is_s ? O_VS : O_VP)) + ((((size_t)layer * NB + b) * 128 + orow) * 2 + kvh) * 64 + sub * 8;
;                 *(f32x4*)dst = (f32x4){v[0], v[1], v[2], v[3]}; *(f32x4*)(dst + 4) = (f32x4){v[4], v[5], v[6], v[7]};
;             }
;         }
.LBB0_1385:
	v_and_b32_e32 v29, 0xffff0000, v20
	v_lshlrev_b32_e32 v28, 16, v20
	v_mul_f32_e32 v30, v29, v29
	v_lshlrev_b32_e32 v26, 16, v21
	v_fmac_f32_e32 v30, v28, v28
	v_and_b32_e32 v27, 0xffff0000, v21
	v_fmac_f32_e32 v30, v26, v26
	v_and_b32_e32 v20, 0xffff0000, v22
	v_lshlrev_b32_e32 v21, 16, v22
	v_fmac_f32_e32 v30, v27, v27
	v_pk_mul_f32 v[24:25], v[20:21], v[20:21]
	v_pk_mov_b32 v[20:21], v[20:21], v[20:21] op_sel:[1,0]
	v_add_f32_e32 v22, v25, v30
	v_add_f32_e32 v30, v24, v22
	v_and_b32_e32 v22, 0xffff0000, v23
	v_lshlrev_b32_e32 v23, 16, v23
	v_pk_mul_f32 v[24:25], v[22:23], v[22:23]
	v_pk_mov_b32 v[22:23], v[22:23], v[22:23] op_sel:[1,0]
	v_add_f32_e32 v25, v25, v30
	v_add_f32_e32 v24, v24, v25
	v_cmp_lt_i32_e32 vcc, 31, v64
	s_and_b64 vcc, s[18:19], vcc
	s_nop 1
	v_add_f32_dpp v24, v24, v24 quad_perm:[1,0,3,2] row_mask:0xf bank_mask:0xf
	s_nop 1
	v_add_f32_dpp v24, v24, v24 quad_perm:[2,3,0,1] row_mask:0xf bank_mask:0xf
	s_nop 1
	v_add_f32_dpp v24, v24, v24 row_half_mirror row_mask:0xf bank_mask:0xf
	s_nop 0
	v_fmamk_f32 v24, v24, 0x3c800000, v189
	v_rsq_f32_e32 v24, v24
	s_nop 0
	v_mul_f32_e32 v25, v24, v28
	v_mul_f32_e32 v30, v24, v29
	v_mul_f32_e32 v31, v24, v26
	v_mul_f32_e32 v34, v24, v21
	v_mul_f32_e32 v32, v58, v25
	v_mul_f32_e32 v25, v59, v30
	v_mul_f32_e32 v30, v60, v31
	v_mul_f32_e32 v31, v24, v27
	v_mul_f32_e32 v33, v24, v20
	v_mul_f32_e32 v34, v63, v34
	v_mul_f32_e32 v35, v24, v22
	v_mul_f32_e32 v24, v24, v23
	v_mul_f32_e32 v24, v67, v24
	v_cndmask_b32_e64 v21, v21, v34, s[8:9]
	v_add_u32_e32 v34, 0x60, v64
	v_mul_f32_e32 v31, v61, v31
	v_mul_f32_e32 v33, v62, v33
	v_mul_f32_e32 v35, v65, v35
	v_cndmask_b32_e64 v23, v23, v24, s[8:9]
	v_cndmask_b32_e64 v24, v28, v32, s[8:9]
	v_add_u32_e32 v32, v55, v34
	v_cndmask_b32_e64 v22, v22, v35, s[8:9]
	v_cndmask_b32_e64 v20, v20, v33, s[8:9]
	v_cndmask_b32_e64 v27, v27, v31, s[8:9]
	v_cndmask_b32_e64 v26, v26, v30, s[8:9]
	v_cndmask_b32_e64 v25, v29, v25, s[8:9]
	v_mad_u64_u32 v[32:33], s[24:25], v32, s86, v[54:55]
	v_cvt_pk_bf16_f32 v28, v24, v25
	v_cvt_pk_bf16_f32 v29, v26, v27
	v_cvt_pk_bf16_f32 v30, v20, v21
	v_cvt_pk_bf16_f32 v31, v22, v23
	v_lshl_add_u32 v32, v32, 1, v66
	ds_write_b128 v32, v[28:31]
	v_add_u32_e32 v28, s13, v34
	v_cndmask_b32_e32 v28, -1, v28, vcc
	v_cndmask_b32_e64 v28, v28, v44, s[4:5]
	v_cmp_lt_i32_e32 vcc, -1, v28
	s_and_b64 s[30:31], vcc, s[60:61]
	s_and_saveexec_b64 s[24:25], s[30:31]
	s_cbranch_execz .LBB0_1387
	v_mov_b32_e32 v29, v161
	v_lshlrev_b32_e32 v160, 2, v68
	v_add_u32_e32 v29, 0, v29
	v_add_u32_e32 v29, 0x201c8, v29
	s_nop 0
	s_waitcnt lgkmcnt(0)
	v_readlane_b32 s31, v251, 51
	v_readlane_b32 s30, v251, 50
	s_nop 1
	v_lshl_add_u64 v[30:31], s[30:31], 0, v[160:161]
	v_lshlrev_b32_e32 v160, 1, v28
	v_lshl_add_u64 v[28:29], v[56:57], 0, v[160:161]
	v_lshlrev_b64 v[28:29], 8, v[28:29]
	v_lshl_add_u64 v[28:29], v[30:31], 0, v[28:29]
	v_lshl_add_u64 v[28:29], v[52:53], 2, v[28:29]
	global_store_dwordx4 v[28:29], v[24:27], off
	global_store_dwordx4 v[28:29], v[20:23], off offset:16

; #define LAS __attribute__((address_space(3)))
; __device__ __forceinline__ bf16x8 pack8(const float* v) { u32x4 w; w.x = pk2(v[0], v[1]); w.y = pk2(v[2], v[3]); w.z = pk2(v[4], v[5]); w.w = pk2(v[6], v[7]); return __builtin_bit_cast(bf16x8, w); }
; __device__ __forceinline__ void unpack8(u32x4 w, float* v) { v[0] = bflo(w.x); v[1] = bfhi(w.x); v[2] = bflo(w.y); v[3] = bfhi(w.y); v[4] = bflo(w.z); v[5] = bfhi(w.z); v[6] = bflo(w.w); v[7] = bfhi(w.w); }
; __device__ __forceinline__ void mixer_unit(const Params& p, int layer, int cu, LAS unsigned char* L, int wv) {
;     ...
;         for (int ps = 0; ps < 12; ++ps) if (ps < npass) {
;             const int kk = klo + 16 * ps + rsub;
;             float v[8]; unpack8(raw[ps], v);
;             float ss = 0.f;
; #pragma unroll
;             for (int i = 0; i < 8; ++i) ss += v[i] * v[i];
;             ss += __shfl_xor(ss, 1); ss += __shfl_xor(ss, 2); ss += __shfl_xor(ss, 4);
;             const float rs = __builtin_amdgcn_rsqf(ss * (1.0f / 64.0f) + EPS);
; #pragma unroll
;             for (int i = 0; i < 8; ++i) { if (isK) v[i] = v[i] * rs * kn[i]; }
;             *(LAS bf16x8*)(L + (isK ? LK_OFF : LV_OFF) + ((kvh * 192 + kk) * KROW + sub * 8) * 2) = pack8(v);
;             int orow = -1;
;             if (is_s) orow = kk - 64; else if (c >= 30 && kk >= 128) orow = (c - 30) * 64 + (kk - 128);
;             if (orow >= 0 && !(isK && sub < 2)) {
;                 float* dst = POUT + (isK ? (is_s ? O_KS : O_KP) : (is_s ? O_VS : O_VP)) + ((((size_t)layer * NB + b) * 128 + orow) * 2 + kvh) * 64 + sub * 8;
;                 *(f32x4*)dst = (f32x4){v[0], v[1], v[2], v[3]}; *(f32x4*)(dst + 4) = (f32x4){v[4], v[5], v[6], v[7]};
;             }
;         }
.LBB0_1389:
	v_and_b32_e32 v21, 0xffff0000, v12
	v_lshlrev_b32_e32 v20, 16, v12
	v_mul_f32_e32 v22, v21, v21
	v_lshlrev_b32_e32 v18, 16, v13
	v_fmac_f32_e32 v22, v20, v20
	v_and_b32_e32 v19, 0xffff0000, v13
	v_fmac_f32_e32 v22, v18, v18
	v_and_b32_e32 v12, 0xffff0000, v14
	v_lshlrev_b32_e32 v13, 16, v14
	v_fmac_f32_e32 v22, v19, v19
	v_pk_mul_f32 v[16:17], v[12:13], v[12:13]
	v_pk_mov_b32 v[12:13], v[12:13], v[12:13] op_sel:[1,0]
	v_add_f32_e32 v14, v17, v22
	v_add_f32_e32 v22, v16, v14
	v_and_b32_e32 v14, 0xffff0000, v15
	v_lshlrev_b32_e32 v15, 16, v15
	v_pk_mul_f32 v[16:17], v[14:15], v[14:15]
	v_pk_mov_b32 v[14:15], v[14:15], v[14:15] op_sel:[1,0]
	v_add_f32_e32 v17, v17, v22
	v_add_f32_e32 v16, v16, v17
	s_and_b64 vcc, exec, s[6:7]
	s_nop 1
	v_add_f32_dpp v16, v16, v16 quad_perm:[1,0,3,2] row_mask:0xf bank_mask:0xf
	s_nop 1
	v_add_f32_dpp v16, v16, v16 quad_perm:[2,3,0,1] row_mask:0xf bank_mask:0xf
	s_nop 1
	v_add_f32_dpp v16, v16, v16 row_half_mirror row_mask:0xf bank_mask:0xf
	s_nop 0
	v_fmamk_f32 v16, v16, 0x3c800000, v189
	v_rsq_f32_e32 v16, v16
	s_nop 0
	v_mul_f32_e32 v17, v16, v20
	v_mul_f32_e32 v22, v16, v21
	v_mul_f32_e32 v23, v16, v18
	v_mul_f32_e32 v24, v58, v17
	v_mul_f32_e32 v17, v59, v22
	v_mul_f32_e32 v22, v60, v23
	v_mul_f32_e32 v23, v16, v19
	v_mul_f32_e32 v25, v16, v12
	v_mul_f32_e32 v26, v16, v13
	v_mul_f32_e32 v27, v16, v14
	v_mul_f32_e32 v16, v16, v15
	v_mul_f32_e32 v16, v67, v16
	v_cndmask_b32_e64 v17, v21, v17, s[8:9]
	v_add_u32_e32 v21, 0x80, v64
	v_mul_f32_e32 v23, v61, v23
	v_mul_f32_e32 v25, v62, v25
	v_mul_f32_e32 v26, v63, v26
	v_mul_f32_e32 v27, v65, v27
	v_cndmask_b32_e64 v15, v15, v16, s[8:9]
	v_cndmask_b32_e64 v16, v20, v24, s[8:9]
	v_add_u32_e32 v20, v55, v21
	v_cndmask_b32_e64 v14, v14, v27, s[8:9]
	v_cndmask_b32_e64 v13, v13, v26, s[8:9]
	v_cndmask_b32_e64 v12, v12, v25, s[8:9]
	v_cndmask_b32_e64 v19, v19, v23, s[8:9]
	v_cndmask_b32_e64 v18, v18, v22, s[8:9]
	v_mad_u64_u32 v[26:27], s[10:11], v20, s86, v[54:55]
	v_cvt_pk_bf16_f32 v22, v16, v17
	v_cvt_pk_bf16_f32 v23, v18, v19
	v_cvt_pk_bf16_f32 v24, v12, v13
	v_cvt_pk_bf16_f32 v25, v14, v15
	v_lshl_add_u32 v20, v26, 1, v66
	s_mov_b64 s[10:11], -1
	ds_write_b128 v20, v[22:25]
	s_cbranch_vccnz .LBB0_1391
	v_cmp_lt_i32_e32 vcc, -1, v64
	v_add_u32_e32 v20, s13, v21
	s_and_b64 vcc, s[18:19], vcc
	v_cndmask_b32_e32 v20, -1, v20, vcc
	s_mov_b64 s[10:11], 0

; #define LAS __attribute__((address_space(3)))
; __device__ __forceinline__ bf16x8 pack8(const float* v) { u32x4 w; w.x = pk2(v[0], v[1]); w.y = pk2(v[2], v[3]); w.z = pk2(v[4], v[5]); w.w = pk2(v[6], v[7]); return __builtin_bit_cast(bf16x8, w); }
; __device__ __forceinline__ void unpack8(u32x4 w, float* v) { v[0] = bflo(w.x); v[1] = bfhi(w.x); v[2] = bflo(w.y); v[3] = bfhi(w.y); v[4] = bflo(w.z); v[5] = bfhi(w.z); v[6] = bflo(w.w); v[7] = bfhi(w.w); }
; __device__ __forceinline__ void mixer_unit(const Params& p, int layer, int cu, LAS unsigned char* L, int wv) {
;     ...
;         for (int ps = 0; ps < 12; ++ps) if (ps < npass) {
;             const int kk = klo + 16 * ps + rsub;
;             float v[8]; unpack8(raw[ps], v);
;             float ss = 0.f;
; #pragma unroll
;             for (int i = 0; i < 8; ++i) ss += v[i] * v[i];
;             ss += __shfl_xor(ss, 1); ss += __shfl_xor(ss, 2); ss += __shfl_xor(ss, 4);
;             const float rs = __builtin_amdgcn_rsqf(ss * (1.0f / 64.0f) + EPS);
; #pragma unroll
;             for (int i = 0; i < 8; ++i) { if (isK) v[i] = v[i] * rs * kn[i]; }
;             *(LAS bf16x8*)(L + (isK ? LK_OFF : LV_OFF) + ((kvh * 192 + kk) * KROW + sub * 8) * 2) = pack8(v);
;             int orow = -1;
;             if (is_s) orow = kk - 64; else if (c >= 30 && kk >= 128) orow = (c - 30) * 64 + (kk - 128);
;             if (orow >= 0 && !(isK && sub < 2)) {
;                 float* dst = POUT + (isK ? (is_s ? O_KS : O_KP) : (is_s ? O_VS : O_VP)) + ((((size_t)layer * NB + b) * 128 + orow) * 2 + kvh) * 64 + sub * 8;
;                 *(f32x4*)dst = (f32x4){v[0], v[1], v[2], v[3]}; *(f32x4*)(dst + 4) = (f32x4){v[4], v[5], v[6], v[7]};
;             }
;         }
.LBB0_1393:
	v_cmp_lt_i32_e32 vcc, -1, v20
	s_and_b64 s[24:25], vcc, s[60:61]
	v_lshlrev_b32_e32 v160, 2, v68
	s_and_saveexec_b64 s[10:11], s[24:25]
	s_cbranch_execz .LBB0_1395
	v_mov_b32_e32 v21, v161
	v_lshlrev_b32_e32 v20, 1, v20
	v_add_u32_e32 v21, 0, v21
	v_add_u32_e32 v21, 0x201c8, v21
	s_nop 0
	v_mov_b32_e32 v21, v161
	v_lshl_add_u64 v[20:21], v[56:57], 0, v[20:21]
	v_lshlrev_b64 v[20:21], 8, v[20:21]
	s_waitcnt lgkmcnt(0)
	v_readlane_b32 s25, v251, 51
	v_readlane_b32 s24, v251, 50
	s_nop 1
	v_lshl_add_u64 v[22:23], s[24:25], 0, v[160:161]
	v_lshl_add_u64 v[20:21], v[22:23], 0, v[20:21]
	v_lshl_add_u64 v[20:21], v[52:53], 2, v[20:21]
	global_store_dwordx4 v[20:21], v[16:19], off
	global_store_dwordx4 v[20:21], v[12:15], off offset:16
.LBB0_1395:
	s_or_b64 exec, exec, s[10:11]
	v_and_b32_e32 v17, 0xffff0000, v8
	v_lshlrev_b32_e32 v16, 16, v8
	v_mul_f32_e32 v18, v17, v17
	v_lshlrev_b32_e32 v14, 16, v9
	v_fmac_f32_e32 v18, v16, v16
	v_and_b32_e32 v15, 0xffff0000, v9
	v_fmac_f32_e32 v18, v14, v14
	v_and_b32_e32 v8, 0xffff0000, v10
	v_lshlrev_b32_e32 v9, 16, v10
	v_fmac_f32_e32 v18, v15, v15
	v_pk_mul_f32 v[12:13], v[8:9], v[8:9]
	v_pk_mov_b32 v[8:9], v[8:9], v[8:9] op_sel:[1,0]
	v_add_f32_e32 v10, v13, v18
	v_add_f32_e32 v18, v12, v10
	v_and_b32_e32 v10, 0xffff0000, v11
	v_lshlrev_b32_e32 v11, 16, v11
	v_pk_mul_f32 v[12:13], v[10:11], v[10:11]
	v_pk_mov_b32 v[10:11], v[10:11], v[10:11] op_sel:[1,0]
	v_add_f32_e32 v13, v13, v18
	v_add_f32_e32 v12, v12, v13
	s_and_b64 vcc, exec, s[6:7]
	s_nop 1
	v_add_f32_dpp v12, v12, v12 quad_perm:[1,0,3,2] row_mask:0xf bank_mask:0xf
	s_nop 1
	v_add_f32_dpp v12, v12, v12 quad_perm:[2,3,0,1] row_mask:0xf bank_mask:0xf
	s_nop 1
	v_add_f32_dpp v12, v12, v12 row_half_mirror row_mask:0xf bank_mask:0xf
	s_nop 0
	v_fmamk_f32 v12, v12, 0x3c800000, v189
	v_rsq_f32_e32 v12, v12
	s_nop 0
	v_mul_f32_e32 v13, v12, v16
	v_mul_f32_e32 v18, v12, v17
	v_mul_f32_e32 v19, v12, v14
	v_mul_f32_e32 v20, v58, v13
	v_mul_f32_e32 v13, v59, v18
	v_mul_f32_e32 v18, v60, v19
	v_mul_f32_e32 v19, v12, v15
	v_mul_f32_e32 v21, v12, v8
	v_mul_f32_e32 v22, v12, v9
	v_mul_f32_e32 v23, v12, v10
	v_mul_f32_e32 v12, v12, v11
	v_mul_f32_e32 v12, v67, v12
	v_cndmask_b32_e64 v13, v17, v13, s[8:9]
	v_add_u32_e32 v17, 0x90, v64
	v_mul_f32_e32 v19, v61, v19
	v_mul_f32_e32 v21, v62, v21
	v_mul_f32_e32 v22, v63, v22
	v_mul_f32_e32 v23, v65, v23
	v_cndmask_b32_e64 v11, v11, v12, s[8:9]
	v_cndmask_b32_e64 v12, v16, v20, s[8:9]
	v_add_u32_e32 v16, v55, v17
	v_cndmask_b32_e64 v10, v10, v23, s[8:9]
	v_cndmask_b32_e64 v9, v9, v22, s[8:9]
	v_cndmask_b32_e64 v8, v8, v21, s[8:9]
	v_cndmask_b32_e64 v15, v15, v19, s[8:9]
	v_cndmask_b32_e64 v14, v14, v18, s[8:9]
	v_mad_u64_u32 v[22:23], s[10:11], v16, s86, v[54:55]
	v_cvt_pk_bf16_f32 v18, v12, v13
	v_cvt_pk_bf16_f32 v19, v14, v15
	v_cvt_pk_bf16_f32 v20, v8, v9
	v_cvt_pk_bf16_f32 v21, v10, v11
	v_lshl_add_u32 v16, v22, 1, v66
	s_mov_b64 s[10:11], -1
	ds_write_b128 v16, v[18:21]
	s_cbranch_vccnz .LBB0_1474
	s_movk_i32 s10, 0xffef
	v_cmp_lt_i32_e32 vcc, s10, v64
	v_add_u32_e32 v16, s13, v17
	s_and_b64 vcc, s[18:19], vcc
	v_cndmask_b32_e32 v16, -1, v16, vcc
	s_cbranch_execz .LBB0_1475

; #define LAS __attribute__((address_space(3)))
; __device__ __forceinline__ bf16x8 pack8(const float* v) { u32x4 w; w.x = pk2(v[0], v[1]); w.y = pk2(v[2], v[3]); w.z = pk2(v[4], v[5]); w.w = pk2(v[6], v[7]); return __builtin_bit_cast(bf16x8, w); }
; __device__ __forceinline__ void unpack8(u32x4 w, float* v) { v[0] = bflo(w.x); v[1] = bfhi(w.x); v[2] = bflo(w.y); v[3] = bfhi(w.y); v[4] = bflo(w.z); v[5] = bfhi(w.z); v[6] = bflo(w.w); v[7] = bfhi(w.w); }
; __device__ __forceinline__ void mixer_unit(const Params& p, int layer, int cu, LAS unsigned char* L, int wv) {
;     ...
;         for (int ps = 0; ps < 12; ++ps) if (ps < npass) {
;             const int kk = klo + 16 * ps + rsub;
;             float v[8]; unpack8(raw[ps], v);
;             float ss = 0.f;
; #pragma unroll
;             for (int i = 0; i < 8; ++i) ss += v[i] * v[i];
;             ss += __shfl_xor(ss, 1); ss += __shfl_xor(ss, 2); ss += __shfl_xor(ss, 4);
;             const float rs = __builtin_amdgcn_rsqf(ss * (1.0f / 64.0f) + EPS);
; #pragma unroll
;             for (int i = 0; i < 8; ++i) { if (isK) v[i] = v[i] * rs * kn[i]; }
;             *(LAS bf16x8*)(L + (isK ? LK_OFF : LV_OFF) + ((kvh * 192 + kk) * KROW + sub * 8) * 2) = pack8(v);
;             int orow = -1;
;             if (is_s) orow = kk - 64; else if (c >= 30 && kk >= 128) orow = (c - 30) * 64 + (kk - 128);
;             if (orow >= 0 && !(isK && sub < 2)) {
;                 float* dst = POUT + (isK ? (is_s ? O_KS : O_KP) : (is_s ? O_VS : O_VP)) + ((((size_t)layer * NB + b) * 128 + orow) * 2 + kvh) * 64 + sub * 8;
;                 *(f32x4*)dst = (f32x4){v[0], v[1], v[2], v[3]}; *(f32x4*)(dst + 4) = (f32x4){v[4], v[5], v[6], v[7]};
;             }
;         }
.LBB0_1398:
	v_mov_b32_e32 v17, v161
	v_lshlrev_b32_e32 v16, 1, v16
	v_add_u32_e32 v17, 0, v17
	v_add_u32_e32 v17, 0x201c8, v17
	s_nop 0
	v_mov_b32_e32 v17, v161
	v_lshl_add_u64 v[16:17], v[56:57], 0, v[16:17]
	v_lshlrev_b64 v[16:17], 8, v[16:17]
	s_waitcnt lgkmcnt(0)
	v_readlane_b32 s25, v251, 51
	v_readlane_b32 s24, v251, 50
	s_nop 1
	v_lshl_add_u64 v[18:19], s[24:25], 0, v[160:161]
	v_lshl_add_u64 v[16:17], v[18:19], 0, v[16:17]
	v_lshl_add_u64 v[16:17], v[52:53], 2, v[16:17]
	global_store_dwordx4 v[16:17], v[12:15], off
	global_store_dwordx4 v[16:17], v[8:11], off offset:16
.LBB0_1399:
	s_or_b64 exec, exec, s[10:11]
	v_and_b32_e32 v13, 0xffff0000, v4
	v_lshlrev_b32_e32 v12, 16, v4
	v_mul_f32_e32 v14, v13, v13
	v_lshlrev_b32_e32 v10, 16, v5
	v_fmac_f32_e32 v14, v12, v12
	v_and_b32_e32 v11, 0xffff0000, v5
	v_fmac_f32_e32 v14, v10, v10
	v_and_b32_e32 v4, 0xffff0000, v6
	v_lshlrev_b32_e32 v5, 16, v6
	v_fmac_f32_e32 v14, v11, v11
	v_pk_mul_f32 v[8:9], v[4:5], v[4:5]
	v_pk_mov_b32 v[4:5], v[4:5], v[4:5] op_sel:[1,0]
	v_add_f32_e32 v6, v9, v14
	v_add_f32_e32 v14, v8, v6
	v_and_b32_e32 v6, 0xffff0000, v7
	v_lshlrev_b32_e32 v7, 16, v7
	v_pk_mul_f32 v[8:9], v[6:7], v[6:7]
	v_pk_mov_b32 v[6:7], v[6:7], v[6:7] op_sel:[1,0]
	v_add_f32_e32 v9, v9, v14
	v_add_f32_e32 v8, v8, v9
	s_and_b64 vcc, exec, s[6:7]
	s_nop 1
	v_add_f32_dpp v8, v8, v8 quad_perm:[1,0,3,2] row_mask:0xf bank_mask:0xf
	s_nop 1
	v_add_f32_dpp v8, v8, v8 quad_perm:[2,3,0,1] row_mask:0xf bank_mask:0xf
	s_nop 1
	v_add_f32_dpp v8, v8, v8 row_half_mirror row_mask:0xf bank_mask:0xf
	s_nop 0
	v_fmamk_f32 v8, v8, 0x3c800000, v189
	v_rsq_f32_e32 v8, v8
	s_nop 0
	v_mul_f32_e32 v9, v8, v12
	v_mul_f32_e32 v14, v8, v13
	v_mul_f32_e32 v15, v8, v10
	v_mul_f32_e32 v16, v58, v9
	v_mul_f32_e32 v9, v59, v14
	v_mul_f32_e32 v14, v60, v15
	v_mul_f32_e32 v15, v8, v11
	v_mul_f32_e32 v17, v8, v4
	v_mul_f32_e32 v18, v8, v5
	v_mul_f32_e32 v19, v8, v6
	v_mul_f32_e32 v8, v8, v7
	v_mul_f32_e32 v8, v67, v8
	v_cndmask_b32_e64 v9, v13, v9, s[8:9]
	v_add_u32_e32 v13, 0xa0, v64
	v_mul_f32_e32 v15, v61, v15
	v_mul_f32_e32 v17, v62, v17
	v_mul_f32_e32 v18, v63, v18
	v_mul_f32_e32 v19, v65, v19
	v_cndmask_b32_e64 v7, v7, v8, s[8:9]
	v_cndmask_b32_e64 v8, v12, v16, s[8:9]
	v_add_u32_e32 v12, v55, v13
	v_cndmask_b32_e64 v6, v6, v19, s[8:9]
	v_cndmask_b32_e64 v5, v5, v18, s[8:9]
	v_cndmask_b32_e64 v4, v4, v17, s[8:9]
	v_cndmask_b32_e64 v11, v11, v15, s[8:9]
	v_cndmask_b32_e64 v10, v10, v14, s[8:9]
	v_mad_u64_u32 v[18:19], s[10:11], v12, s86, v[54:55]
	v_cvt_pk_bf16_f32 v14, v8, v9
	v_cvt_pk_bf16_f32 v15, v10, v11
	v_cvt_pk_bf16_f32 v16, v4, v5
	v_cvt_pk_bf16_f32 v17, v6, v7
	v_lshl_add_u32 v12, v18, 1, v66
	s_mov_b64 s[10:11], -1
	ds_write_b128 v12, v[14:17]
	s_cbranch_vccnz .LBB0_1476
	s_movk_i32 s10, 0xffdf
	v_cmp_lt_i32_e32 vcc, s10, v64
	v_add_u32_e32 v12, s13, v13
	s_and_b64 vcc, s[18:19], vcc
	v_cndmask_b32_e32 v12, -1, v12, vcc
	s_cbranch_execz .LBB0_1477

; #define LAS __attribute__((address_space(3)))
; __device__ __forceinline__ bf16x8 pack8(const float* v) { u32x4 w; w.x = pk2(v[0], v[1]); w.y = pk2(v[2], v[3]); w.z = pk2(v[4], v[5]); w.w = pk2(v[6], v[7]); return __builtin_bit_cast(bf16x8, w); }
; __device__ __forceinline__ void unpack8(u32x4 w, float* v) { v[0] = bflo(w.x); v[1] = bfhi(w.x); v[2] = bflo(w.y); v[3] = bfhi(w.y); v[4] = bflo(w.z); v[5] = bfhi(w.z); v[6] = bflo(w.w); v[7] = bfhi(w.w); }
; __device__ __forceinline__ void mixer_unit(const Params& p, int layer, int cu, LAS unsigned char* L, int wv) {
;     ...
;         for (int ps = 0; ps < 12; ++ps) if (ps < npass) {
;             const int kk = klo + 16 * ps + rsub;
;             float v[8]; unpack8(raw[ps], v);
;             float ss = 0.f;
; #pragma unroll
;             for (int i = 0; i < 8; ++i) ss += v[i] * v[i];
;             ss += __shfl_xor(ss, 1); ss += __shfl_xor(ss, 2); ss += __shfl_xor(ss, 4);
;             const float rs = __builtin_amdgcn_rsqf(ss * (1.0f / 64.0f) + EPS);
; #pragma unroll
;             for (int i = 0; i < 8; ++i) { if (isK) v[i] = v[i] * rs * kn[i]; }
;             *(LAS bf16x8*)(L + (isK ? LK_OFF : LV_OFF) + ((kvh * 192 + kk) * KROW + sub * 8) * 2) = pack8(v);
;             int orow = -1;
;             if (is_s) orow = kk - 64; else if (c >= 30 && kk >= 128) orow = (c - 30) * 64 + (kk - 128);
;             if (orow >= 0 && !(isK && sub < 2)) {
;                 float* dst = POUT + (isK ? (is_s ? O_KS : O_KP) : (is_s ? O_VS : O_VP)) + ((((size_t)layer * NB + b) * 128 + orow) * 2 + kvh) * 64 + sub * 8;
;                 *(f32x4*)dst = (f32x4){v[0], v[1], v[2], v[3]}; *(f32x4*)(dst + 4) = (f32x4){v[4], v[5], v[6], v[7]};
;             }
;         }
.LBB0_1402:
	v_mov_b32_e32 v13, v161
	v_lshlrev_b32_e32 v12, 1, v12
	v_add_u32_e32 v13, 0, v13
	v_add_u32_e32 v13, 0x201c8, v13
	s_nop 0
	v_mov_b32_e32 v13, v161
	v_lshl_add_u64 v[12:13], v[56:57], 0, v[12:13]
	v_lshlrev_b64 v[12:13], 8, v[12:13]
	s_waitcnt lgkmcnt(0)
	v_readlane_b32 s25, v251, 51
	v_readlane_b32 s24, v251, 50
	s_nop 1
	v_lshl_add_u64 v[14:15], s[24:25], 0, v[160:161]
	v_lshl_add_u64 v[12:13], v[14:15], 0, v[12:13]
	v_lshl_add_u64 v[12:13], v[52:53], 2, v[12:13]
	global_store_dwordx4 v[12:13], v[8:11], off
	global_store_dwordx4 v[12:13], v[4:7], off offset:16
.LBB0_1403:
	s_or_b64 exec, exec, s[10:11]
	v_and_b32_e32 v9, 0xffff0000, v0
	v_lshlrev_b32_e32 v8, 16, v0
	v_mul_f32_e32 v10, v9, v9
	v_lshlrev_b32_e32 v6, 16, v1
	v_fmac_f32_e32 v10, v8, v8
	v_and_b32_e32 v7, 0xffff0000, v1
	v_fmac_f32_e32 v10, v6, v6
	v_and_b32_e32 v0, 0xffff0000, v2
	v_lshlrev_b32_e32 v1, 16, v2
	v_fmac_f32_e32 v10, v7, v7
	v_pk_mul_f32 v[4:5], v[0:1], v[0:1]
	v_pk_mov_b32 v[0:1], v[0:1], v[0:1] op_sel:[1,0]
	v_add_f32_e32 v2, v5, v10
	v_add_f32_e32 v10, v4, v2
	v_and_b32_e32 v2, 0xffff0000, v3
	v_lshlrev_b32_e32 v3, 16, v3
	v_pk_mul_f32 v[4:5], v[2:3], v[2:3]
	v_pk_mov_b32 v[2:3], v[2:3], v[2:3] op_sel:[1,0]
	v_add_f32_e32 v5, v5, v10
	v_add_f32_e32 v4, v4, v5
	s_and_b64 vcc, exec, s[6:7]
	s_mov_b64 s[6:7], -1
	s_nop 1
	v_add_f32_dpp v4, v4, v4 quad_perm:[1,0,3,2] row_mask:0xf bank_mask:0xf
	s_nop 1
	v_add_f32_dpp v4, v4, v4 quad_perm:[2,3,0,1] row_mask:0xf bank_mask:0xf
	s_nop 1
	v_add_f32_dpp v4, v4, v4 row_half_mirror row_mask:0xf bank_mask:0xf
	s_nop 0
	v_fmamk_f32 v4, v4, 0x3c800000, v189
	v_rsq_f32_e32 v4, v4
	s_nop 0
	v_mul_f32_e32 v5, v4, v8
	v_mul_f32_e32 v10, v4, v9
	v_mul_f32_e32 v11, v4, v6
	v_mul_f32_e32 v12, v58, v5
	v_mul_f32_e32 v5, v59, v10
	v_mul_f32_e32 v10, v60, v11
	v_mul_f32_e32 v11, v4, v7
	v_mul_f32_e32 v13, v4, v0
	v_mul_f32_e32 v14, v4, v1
	v_mul_f32_e32 v15, v4, v2
	v_mul_f32_e32 v4, v4, v3
	v_mul_f32_e32 v4, v67, v4
	v_cndmask_b32_e64 v5, v9, v5, s[8:9]
	v_add_u32_e32 v9, 0xb0, v64
	v_mul_f32_e32 v11, v61, v11
	v_mul_f32_e32 v13, v62, v13
	v_mul_f32_e32 v14, v63, v14
	v_mul_f32_e32 v15, v65, v15
	v_cndmask_b32_e64 v3, v3, v4, s[8:9]
	v_cndmask_b32_e64 v4, v8, v12, s[8:9]
	v_add_u32_e32 v8, v55, v9
	v_cndmask_b32_e64 v2, v2, v15, s[8:9]
	v_cndmask_b32_e64 v1, v1, v14, s[8:9]
	v_cndmask_b32_e64 v0, v0, v13, s[8:9]
	v_cndmask_b32_e64 v7, v7, v11, s[8:9]
	v_cndmask_b32_e64 v6, v6, v10, s[8:9]
	v_mad_u64_u32 v[14:15], s[8:9], v8, s86, v[54:55]
	v_cvt_pk_bf16_f32 v10, v4, v5
	v_cvt_pk_bf16_f32 v11, v6, v7
	v_cvt_pk_bf16_f32 v12, v0, v1
	v_cvt_pk_bf16_f32 v13, v2, v3
	v_lshl_add_u32 v8, v14, 1, v66
	ds_write_b128 v8, v[10:13]
	s_cbranch_vccnz .LBB0_1478
	s_movk_i32 s6, 0xffcf
	v_cmp_lt_i32_e32 vcc, s6, v64
	v_add_u32_e32 v8, s13, v9
	s_and_b64 vcc, s[18:19], vcc
	v_cndmask_b32_e32 v8, -1, v8, vcc
	s_cbranch_execz .LBB0_1479

; __device__ __forceinline__ void mixer_unit(const Params& p, int layer, int cu, LAS unsigned char* L, int wv) {
;     ...
;             int orow = -1;
;             if (is_s) orow = kk - 64; else if (c >= 30 && kk >= 128) orow = (c - 30) * 64 + (kk - 128);
;             if (orow >= 0 && !(isK && sub < 2)) {
;                 float* dst = POUT + (isK ? (is_s ? O_KS : O_KP) : (is_s ? O_VS : O_VP)) + ((((size_t)layer * NB + b) * 128 + orow) * 2 + kvh) * 64 + sub * 8;
;                 *(f32x4*)dst = (f32x4){v[0], v[1], v[2], v[3]}; *(f32x4*)(dst + 4) = (f32x4){v[4], v[5], v[6], v[7]};
;             }
.LBB0_1406:
	v_mov_b32_e32 v9, v161
	s_nop 0
	v_add_u32_e32 v9, 0, v9
	v_add_u32_e32 v9, 0x201c8, v9
	s_nop 0
	s_waitcnt lgkmcnt(0)
	v_readlane_b32 s9, v251, 51
	v_readlane_b32 s8, v251, 50
	s_nop 1
	v_lshl_add_u64 v[10:11], s[8:9], 0, v[160:161]
	v_lshlrev_b32_e32 v160, 1, v8
	v_lshl_add_u64 v[8:9], v[56:57], 0, v[160:161]
	v_lshlrev_b64 v[8:9], 8, v[8:9]
	v_lshl_add_u64 v[8:9], v[10:11], 0, v[8:9]
	v_lshl_add_u64 v[8:9], v[52:53], 2, v[8:9]
	global_store_dwordx4 v[8:9], v[4:7], off
	global_store_dwordx4 v[8:9], v[0:3], off offset:16

; #define PIN(i) ((const float*)ldq_(L, (i)))
; __device__ __forceinline__ void unpack8(u32x4 w, float* v) { v[0] = bflo(w.x); v[1] = bfhi(w.x); v[2] = bflo(w.y); v[3] = bfhi(w.y); v[4] = bflo(w.z); v[5] = bfhi(w.z); v[6] = bflo(w.w); v[7] = bfhi(w.w); }
; __device__ __forceinline__ void mixer_unit(const Params& p, int layer, int cu, LAS unsigned char* L, int wv) {
;     ...
;     bf16x8 qf[4][2];
;     {
;         float gq0[8], gq1[8];
; #pragma unroll
;         for (int i = 0; i < 8; ++i) { gq0[i] = PIN(I_QN)[layer * 64 + 8 * quad + i]; gq1[i] = PIN(I_QN)[layer * 64 + 32 + 8 * quad + i]; }
;         constexpr float QS = 0.125f * LOG2E;
; #pragma unroll
;         for (int qb = 0; qb < 4; ++qb) {
;             float v0[8], v1[8]; unpack8(qraw[qb][0], v0); unpack8(qraw[qb][1], v1);
;             float ss = 0.f;
; #pragma unroll
;             for (int i = 0; i < 8; ++i) ss += v0[i] * v0[i] + v1[i] * v1[i];
;             ss += __shfl_xor(ss, 16); ss += __shfl_xor(ss, 32);
;             const float rs = __builtin_amdgcn_rsqf(ss * (1.0f / 64.0f) + EPS);
;             float pv[8];
; #pragma unroll
;             for (int i = 0; i < 8; ++i) { v0[i] = v0[i] * rs * gq0[i]; v1[i] = v1[i] * rs * gq1[i] * QS; pv[i] = __shfl_xor(v0[i], 16); }
.LBB0_1416:
	s_or_b64 exec, exec, s[10:11]
	v_mov_b32_e32 v96, v161
	v_bfe_u32 v122, v178, 4, 2
	v_add_u32_e32 v96, s23, v96
	s_nop 0
	v_lshlrev_b32_e32 v180, 3, v122
	v_or_b32_e32 v160, s63, v180
	v_lshlrev_b64 v[100:101], 2, v[160:161]
	v_mov_b32_e32 v102, v161
	s_waitcnt lgkmcnt(0)
	v_readlane_b32 s9, v251, 25
	v_readlane_b32 s8, v251, 24
	v_mov_b32_e32 v104, v161
	v_mov_b32_e32 v106, v161
	v_lshl_add_u64 v[96:97], s[8:9], 0, v[100:101]
	global_load_dword v96, v[96:97], off
	v_mov_b32_e32 v97, v161
	s_waitcnt vmcnt(8)
	v_and_b32_e32 v108, 0xffff0000, v90
	v_add_u32_e32 v97, s23, v97
	s_nop 0
	v_mov_b32_e32 v97, v161
	v_lshlrev_b32_e32 v109, 16, v90
	v_and_b32_e32 v110, 0xffff0000, v91
	v_lshlrev_b32_e32 v111, 16, v91
	s_waitcnt lgkmcnt(0)
	v_readlane_b32 s9, v251, 25
	v_readlane_b32 s8, v251, 24
	s_waitcnt vmcnt(7)
	v_and_b32_e32 v90, 0xffff0000, v95
	v_lshlrev_b32_e32 v91, 16, v95
	v_lshl_add_u64 v[98:99], s[8:9], 0, v[100:101]
	global_load_dword v132, v[98:99], off offset:128
	v_lshlrev_b32_e32 v116, 16, v88
	v_add_u32_e32 v97, s23, v97
	s_nop 0
	v_and_b32_e32 v117, 0xffff0000, v88
	v_lshlrev_b32_e32 v118, 16, v89
	v_and_b32_e32 v119, 0xffff0000, v89
	v_cmp_gt_u32_e32 vcc, 16, v181
	s_waitcnt lgkmcnt(0)
	v_readlane_b32 s9, v251, 25
	v_readlane_b32 s8, v251, 24
	s_nop 1
	v_lshl_add_u64 v[98:99], s[8:9], 0, v[100:101]
	global_load_dword v97, v[98:99], off offset:4
	s_nop 0
	v_add_u32_e32 v98, s23, v102
	ds_read_b64 v[98:99], v98
	v_mov_b32_e32 v102, v161
	s_waitcnt lgkmcnt(0)
	v_readfirstlane_b32 s9, v99
	v_readfirstlane_b32 s8, v98
	s_nop 1
	v_lshl_add_u64 v[98:99], s[8:9], 0, v[100:101]
	global_load_dword v133, v[98:99], off offset:132
	s_nop 0
	v_add_u32_e32 v98, s23, v102
	ds_read_b64 v[98:99], v98
	v_mov_b32_e32 v102, v161
	s_waitcnt lgkmcnt(0)
	v_readfirstlane_b32 s9, v99
	v_readfirstlane_b32 s8, v98
	s_nop 1
	v_lshl_add_u64 v[98:99], s[8:9], 0, v[100:101]
	global_load_dword v98, v[98:99], off offset:8
	s_nop 0
	v_add_u32_e32 v99, s23, v102
	ds_read_b64 v[102:103], v99
	v_mov_b32_e32 v99, v161
	s_waitcnt lgkmcnt(0)
	v_readfirstlane_b32 s9, v103
	v_readfirstlane_b32 s8, v102
	s_nop 1
	v_lshl_add_u64 v[102:103], s[8:9], 0, v[100:101]
	global_load_dword v134, v[102:103], off offset:136
	s_nop 0
	v_add_u32_e32 v99, s23, v99
	s_nop 0
	s_waitcnt lgkmcnt(0)
	v_readlane_b32 s9, v251, 25
	v_readlane_b32 s8, v251, 24
	s_nop 1
	v_lshl_add_u64 v[102:103], s[8:9], 0, v[100:101]
	global_load_dword v99, v[102:103], off offset:12
	s_nop 0
	v_add_u32_e32 v102, s23, v104
	ds_read_b64 v[102:103], v102
	v_mov_b32_e32 v104, v161
	s_waitcnt lgkmcnt(0)
	v_readfirstlane_b32 s9, v103
	v_readfirstlane_b32 s8, v102
	s_nop 1
	v_lshl_add_u64 v[102:103], s[8:9], 0, v[100:101]
	global_load_dword v135, v[102:103], off offset:140
	s_nop 0
	v_add_u32_e32 v102, s23, v104
	ds_read_b64 v[102:103], v102
	v_mov_b32_e32 v104, v161
	s_waitcnt lgkmcnt(0)
	v_readfirstlane_b32 s9, v103
	v_readfirstlane_b32 s8, v102
	s_nop 1
	v_lshl_add_u64 v[102:103], s[8:9], 0, v[100:101]
	global_load_dword v102, v[102:103], off offset:16
	s_nop 0
	v_add_u32_e32 v103, s23, v104
	ds_read_b64 v[104:105], v103
	v_mov_b32_e32 v103, v161
	s_waitcnt lgkmcnt(0)
	v_readfirstlane_b32 s9, v105
	v_readfirstlane_b32 s8, v104
	s_nop 1
	v_lshl_add_u64 v[104:105], s[8:9], 0, v[100:101]
	global_load_dword v137, v[104:105], off offset:144
	s_nop 0
	v_add_u32_e32 v103, s23, v103
	s_nop 0
	s_waitcnt lgkmcnt(0)
	v_readlane_b32 s9, v251, 25
	v_readlane_b32 s8, v251, 24
	s_nop 1
	v_lshl_add_u64 v[104:105], s[8:9], 0, v[100:101]
	global_load_dword v103, v[104:105], off offset:20
	s_nop 0
	v_add_u32_e32 v104, s23, v106
	ds_read_b64 v[104:105], v104
	v_mov_b32_e32 v106, v161
	s_waitcnt lgkmcnt(0)
	v_readfirstlane_b32 s9, v105
	v_readfirstlane_b32 s8, v104
	s_nop 1
	v_lshl_add_u64 v[104:105], s[8:9], 0, v[100:101]
	global_load_dword v136, v[104:105], off offset:148
	s_nop 0
	v_add_u32_e32 v104, s23, v106
	ds_read_b64 v[104:105], v104
	v_mov_b32_e32 v106, v161
	s_waitcnt lgkmcnt(0)
	v_readfirstlane_b32 s9, v105
	v_readfirstlane_b32 s8, v104
	s_nop 1
	v_lshl_add_u64 v[104:105], s[8:9], 0, v[100:101]
	global_load_dword v112, v[104:105], off offset:24
	s_nop 0
	v_add_u32_e32 v104, s23, v106
	ds_read_b64 v[104:105], v104
	v_mov_b32_e32 v106, v161
	s_waitcnt lgkmcnt(0)
	v_readfirstlane_b32 s9, v105
	v_readfirstlane_b32 s8, v104
	s_nop 1
	v_lshl_add_u64 v[104:105], s[8:9], 0, v[100:101]
	global_load_dword v139, v[104:105], off offset:152
	s_nop 0
	v_add_u32_e32 v104, s23, v106
	ds_read_b64 v[104:105], v104
	v_mov_b32_e32 v106, v161
	s_waitcnt lgkmcnt(0)
	v_readfirstlane_b32 s9, v105
	v_readfirstlane_b32 s8, v104
	s_nop 1
	v_lshl_add_u64 v[104:105], s[8:9], 0, v[100:101]
	global_load_dword v113, v[104:105], off offset:28
	s_nop 0
	v_add_u32_e32 v104, s23, v106
	ds_read_b64 v[104:105], v104
	s_waitcnt lgkmcnt(0)
	v_readfirstlane_b32 s9, v105
	v_readfirstlane_b32 s8, v104
	s_nop 1
	v_lshl_add_u64 v[100:101], s[8:9], 0, v[100:101]
	global_load_dword v138, v[100:101], off offset:156
	v_and_b32_e32 v100, 0xffff0000, v94
	v_lshlrev_b32_e32 v101, 16, v94
	v_pk_mul_f32 v[104:105], v[100:101], v[100:101]
	v_pk_mul_f32 v[94:95], v[90:91], v[90:91]
	v_pk_fma_f32 v[106:107], v[108:109], v[108:109], v[104:105]
	v_lshlrev_b32_e32 v104, 16, v92
	v_and_b32_e32 v105, 0xffff0000, v92
	v_pk_fma_f32 v[114:115], v[110:111], v[110:111], v[94:95]
	v_lshlrev_b32_e32 v94, 16, v93
	v_and_b32_e32 v95, 0xffff0000, v93
	v_pk_mul_f32 v[92:93], v[104:105], v[104:105]
	v_pk_mul_f32 v[88:89], v[94:95], v[94:95]
	v_pk_fma_f32 v[92:93], v[116:117], v[116:117], v[92:93]
	v_pk_fma_f32 v[88:89], v[118:119], v[118:119], v[88:89]
	v_add_f32_e32 v92, v92, v93
	v_add_f32_e32 v88, v88, v92
	v_add_f32_e32 v88, v89, v88
	v_add_f32_e32 v88, v107, v88
	v_add_f32_e32 v88, v106, v88
	v_add_f32_e32 v88, v115, v88
	v_add_f32_e32 v88, v114, v88
	ds_bpermute_b32 v89, v184, v88
	s_waitcnt lgkmcnt(0)
	v_add_f32_e32 v88, v88, v89
	ds_bpermute_b32 v89, v185, v88
	s_waitcnt lgkmcnt(0)
	v_add_f32_e32 v88, v88, v89
	v_fmamk_f32 v88, v88, 0x3c800000, v189
	v_rsq_f32_e32 v92, v88
	s_nop 0
	v_pk_mul_f32 v[88:89], v[92:93], v[116:117] op_sel_hi:[0,1]
	v_pk_mul_f32 v[106:107], v[92:93], v[118:119] op_sel_hi:[0,1]
	v_pk_mul_f32 v[108:109], v[92:93], v[108:109] op_sel_hi:[0,1]
	v_pk_mul_f32 v[110:111], v[92:93], v[110:111] op_sel_hi:[0,1]
	s_waitcnt vmcnt(13)
	v_pk_mul_f32 v[88:89], v[96:97], v[88:89]
	s_waitcnt vmcnt(9)
	v_pk_mul_f32 v[106:107], v[98:99], v[106:107]
	s_waitcnt vmcnt(5)
	v_pk_mul_f32 v[108:109], v[102:103], v[108:109] op_sel:[0,1] op_sel_hi:[1,0]
	ds_bpermute_b32 v120, v184, v88
	ds_bpermute_b32 v121, v184, v89
	ds_bpermute_b32 v118, v184, v106
	ds_bpermute_b32 v119, v184, v107
	ds_bpermute_b32 v116, v184, v108
	ds_bpermute_b32 v117, v184, v109
	s_waitcnt vmcnt(1)
	v_pk_mul_f32 v[110:111], v[112:113], v[110:111] op_sel:[0,1] op_sel_hi:[1,0]
	ds_bpermute_b32 v114, v184, v110
	ds_bpermute_b32 v115, v184, v111
	s_and_saveexec_b64 s[8:9], s[6:7]
	s_cbranch_execz .LBB0_1418
; __device__ __forceinline__ void mixer_unit(const Params& p, int layer, int cu, LAS unsigned char* L, int wv) {
;     ...
;             if (quad < 2) {
;                 const f32x4 c0 = rq[qb][0], c1 = rq[qb][1], s0 = rq[qb][2], s1 = rq[qb][3];
; #pragma unroll
;                 for (int i = 0; i < 8; ++i) { const float cs = i < 4 ? c0[i & 3] : c1[i & 3], sn = i < 4 ? s0[i & 3] : s1[i & 3]; v0[i] = (quad == 0) ? v0[i] * cs - pv[i] * sn : v0[i] * cs + pv[i] * sn; }
;             }
	s_waitcnt lgkmcnt(6)
	v_pk_mul_f32 v[84:85], v[84:85], v[120:121]
	s_waitcnt lgkmcnt(4)
	v_pk_mul_f32 v[86:87], v[86:87], v[118:119]
	s_waitcnt lgkmcnt(2)
	v_pk_mul_f32 v[80:81], v[80:81], v[116:117]
	s_waitcnt lgkmcnt(0)
	v_pk_mul_f32 v[82:83], v[82:83], v[114:115]
	v_cndmask_b32_e64 v85, v85, -v85, vcc
	v_cndmask_b32_e64 v84, v84, -v84, vcc
	v_cndmask_b32_e64 v87, v87, -v87, vcc
	v_cndmask_b32_e64 v86, v86, -v86, vcc
	v_cndmask_b32_e64 v81, v81, -v81, vcc
	v_cndmask_b32_e64 v80, v80, -v80, vcc
	v_cndmask_b32_e64 v83, v83, -v83, vcc
	v_cndmask_b32_e64 v82, v82, -v82, vcc
	v_pk_fma_f32 v[88:89], v[72:73], v[88:89], v[84:85]
	v_pk_fma_f32 v[106:107], v[74:75], v[106:107], v[86:87]
	v_pk_fma_f32 v[108:109], v[76:77], v[108:109], v[80:81]
	v_pk_fma_f32 v[110:111], v[78:79], v[110:111], v[82:83]

; #define LAS __attribute__((address_space(3)))
; #define PIN(i) ((const float*)ldq_(L, (i)))
; __device__ __forceinline__ bf16x8 pack8(const float* v) { u32x4 w; w.x = pk2(v[0], v[1]); w.y = pk2(v[2], v[3]); w.z = pk2(v[4], v[5]); w.w = pk2(v[6], v[7]); return __builtin_bit_cast(bf16x8, w); }
; __device__ __forceinline__ void mixer_unit(const Params& p, int layer, int cu, LAS unsigned char* L, int wv) {
;     ...
; #pragma unroll
;             for (int i = 0; i < 8; ++i) v0[i] *= QS;
;             qf[qb][0] = pack8(v0); qf[qb][1] = pack8(v1);
;         }
;     }
;     __syncthreads();
;     {
;         const float sinkv = PIN(I_SINK)[layer * 8 + h] * LOG2E;
;         const LAS unsigned char* Kb = L + LK_OFF + ((kvhq * 192 + q16) * KROW + 8 * quad) * 2;
;         const LAS unsigned char* Vb = L + LV_OFF + ((kvhq * 192 + 4 * quad + (q16 >> 2)) * KROW + 4 * (q16 & 3)) * 2;
; #pragma unroll
;         for (int pr = 0; pr < 2; ++pr) {
;             f32x4 s[2][12];
; #pragma unroll
;             for (int kt = 0; kt < 12; ++kt) {
;                 if (16 * kt >= kstart) {
;                     const bf16x8 k0 = *(const LAS bf16x8*)(Kb + kt * 16 * KROW * 2), k1 = *(const LAS bf16x8*)(Kb + kt * 16 * KROW * 2 + 64);
; #pragma unroll
;                     for (int e = 0; e < 2; ++e) { s[e][kt] = __builtin_amdgcn_mfma_f32_16x16x32_bf16(k0, qf[2 * pr + e][0], (f32x4){0.f, 0.f, 0.f, 0.f}, 0, 0, 0);
;                         s[e][kt] = __builtin_amdgcn_mfma_f32_16x16x32_bf16(k1, qf[2 * pr + e][1], s[e][kt], 0, 0, 0); }
;                 } else { s[0][kt] = (f32x4){-1e30f, -1e30f, -1e30f, -1e30f}; s[1][kt] = s[0][kt]; }
.LBB0_1424:
	s_or_b64 exec, exec, s[8:9]
	v_mov_b32_e32 v69, v68
	s_waitcnt lgkmcnt(0)
	v_pk_mul_f32 v[0:1], v[68:69], v[74:75]
	v_pk_mul_f32 v[4:5], v[68:69], v[72:73]
	v_pk_mul_f32 v[0:1], v[132:133], v[0:1]
	v_pk_mul_f32 v[4:5], v[136:137], v[4:5]
	v_pk_mul_f32 v[6:7], v[68:69], v[66:67]
	v_pk_mul_f32 v[0:1], v[0:1], s[78:79] op_sel_hi:[1,0]
	v_pk_mul_f32 v[4:5], v[4:5], s[78:79] op_sel_hi:[1,0]
	s_waitcnt vmcnt(0)
	v_pk_mul_f32 v[6:7], v[138:139], v[6:7]
	v_cvt_pk_bf16_f32 v32, v0, v1
	v_pk_mul_f32 v[6:7], v[6:7], s[78:79] op_sel_hi:[1,0]
	v_pk_mov_b32 v[0:1], v[4:5], v[4:5] op_sel:[1,0]
	v_mov_b32_e32 v93, v92
	v_cvt_pk_bf16_f32 v34, v0, v1
	v_pk_mov_b32 v[0:1], v[6:7], v[6:7] op_sel:[1,0]
	v_pk_mul_f32 v[4:5], v[92:93], v[100:101]
	v_cvt_pk_bf16_f32 v35, v0, v1
	v_pk_mul_f32 v[0:1], v[92:93], v[104:105]
	v_pk_mul_f32 v[4:5], v[136:137], v[4:5]
	v_pk_mul_f32 v[0:1], v[132:133], v[0:1]
	v_pk_mul_f32 v[6:7], v[92:93], v[90:91]
	v_pk_mul_f32 v[0:1], v[0:1], s[78:79] op_sel_hi:[1,0]
	v_pk_mul_f32 v[4:5], v[4:5], s[78:79] op_sel_hi:[1,0]
	v_pk_mul_f32 v[6:7], v[138:139], v[6:7]
	v_cvt_pk_bf16_f32 v40, v0, v1
	v_pk_mul_f32 v[6:7], v[6:7], s[78:79] op_sel_hi:[1,0]
	v_pk_mov_b32 v[0:1], v[4:5], v[4:5] op_sel:[1,0]
	s_nop 0
	v_cvt_pk_bf16_f32 v42, v0, v1
	v_pk_mov_b32 v[0:1], v[6:7], v[6:7] op_sel:[1,0]
	s_barrier
	v_cvt_pk_bf16_f32 v43, v0, v1
	v_mov_b32_e32 v0, v161
	s_ashr_i32 s52, s66, 6
	v_add_u32_e32 v0, 0, v0
	v_add_u32_e32 v0, 0x20170, v0
	s_nop 0
	s_add_i32 s6, s52, s64
	s_ashr_i32 s7, s6, 31
	s_ashr_i32 s16, s66, 8
	s_lshl_b64 s[6:7], s[6:7], 2
	s_waitcnt lgkmcnt(0)
	v_readlane_b32 s9, v251, 28
	v_readlane_b32 s8, v251, 29
	s_add_u32 s6, s9, s6
	s_addc_u32 s7, s8, s7
	global_load_dword v0, v161, s[6:7]
	v_pk_mul_f32 v[2:3], v[68:69], v[70:71]
	s_mulk_i32 s16, 0xc0
	v_pk_mul_f32 v[2:3], v[134:135], v[2:3]
	v_or_b32_e32 v1, s16, v179
	v_pk_mul_f32 v[2:3], v[2:3], s[78:79] op_sel_hi:[1,0]
	v_pk_mul_f32 v[8:9], v[64:65], s[78:79] op_sel_hi:[1,0]
	v_cvt_pk_bf16_f32 v33, v2, v3
	v_pk_mul_f32 v[2:3], v[92:93], v[94:95]
	v_pk_mul_f32 v[10:11], v[76:77], s[78:79] op_sel_hi:[1,0]
	v_pk_mul_f32 v[12:13], v[78:79], s[78:79] op_sel_hi:[1,0]
	v_pk_mul_f32 v[14:15], v[80:81], s[78:79] op_sel_hi:[1,0]
	v_pk_mul_f32 v[2:3], v[134:135], v[2:3]
	v_mul_lo_u32 v1, v1, s86
	v_cvt_pk_bf16_f32 v36, v8, v9
	v_cvt_pk_bf16_f32 v37, v10, v11
	v_cvt_pk_bf16_f32 v38, v12, v13
	v_cvt_pk_bf16_f32 v39, v14, v15
	v_pk_mul_f32 v[2:3], v[2:3], s[78:79] op_sel_hi:[1,0]
	v_pk_mul_f32 v[8:9], v[88:89], s[78:79] op_sel_hi:[1,0]
	v_pk_mul_f32 v[10:11], v[106:107], s[78:79] op_sel_hi:[1,0]
	v_pk_mul_f32 v[12:13], v[108:109], s[78:79] op_sel_hi:[1,0]
	v_pk_mul_f32 v[14:15], v[110:111], s[78:79] op_sel_hi:[1,0]
	v_add_lshl_u32 v1, v1, v180, 1
	s_cmp_eq_u32 s15, 0
	v_cvt_pk_bf16_f32 v44, v8, v9
	v_cvt_pk_bf16_f32 v45, v10, v11
	v_cvt_pk_bf16_f32 v46, v12, v13
	v_cvt_pk_bf16_f32 v47, v14, v15
	v_cvt_pk_bf16_f32 v41, v2, v3
	v_mov_b32_e32 v48, 0xf149f2ca
	s_cselect_b64 s[8:9], -1, 0
	s_cmp_lg_u32 s15, 0
	v_add_u32_e32 v127, 0, v1
	v_mov_b32_e32 v52, 0xf149f2ca
	v_mov_b32_e32 v53, 0xf149f2ca
	v_mov_b32_e32 v54, 0xf149f2ca
	v_mov_b32_e32 v55, 0xf149f2ca
	v_mov_b32_e32 v80, 0xf149f2ca
	v_mov_b32_e32 v81, 0xf149f2ca
	v_mov_b32_e32 v82, 0xf149f2ca
	v_mov_b32_e32 v83, 0xf149f2ca
	s_cbranch_scc1 .LBB0_1426
	ds_read_b128 v[2:5], v127
	ds_read_b128 v[6:9], v127 offset:64
	s_waitcnt lgkmcnt(1)
	v_mfma_f32_16x16x32_bf16 v[10:13], v[2:5], v[44:47], 0
	v_mfma_f32_16x16x32_bf16 v[2:5], v[2:5], v[36:39], 0
	s_waitcnt lgkmcnt(0)
	v_mfma_f32_16x16x32_bf16 v[80:83], v[6:9], v[40:43], v[10:13]
	v_mfma_f32_16x16x32_bf16 v[52:55], v[6:9], v[32:35], v[2:5]

; __device__ __forceinline__ void mixer_unit(const Params& p, int layer, int cu, LAS unsigned char* L, int wv) {
;     ...
;             float inv[2];
; #pragma unroll
;             for (int e = 0; e < 2; ++e) {
;                 float mx = sinkv;
; #pragma unroll
;                 for (int kt = 0; kt < 12; ++kt) mx = fmaxf(fmaxf(mx, fmaxf(s[e][kt][0], s[e][kt][1])), fmaxf(s[e][kt][2], s[e][kt][3]));
;                 mx = fmaxf(mx, __shfl_xor(mx, 16)); mx = fmaxf(mx, __shfl_xor(mx, 32));
;                 float l = 0.f;
; #pragma unroll
;                 for (int kt = 0; kt < 12; ++kt)
; #pragma unroll
;                     for (int j = 0; j < 4; ++j) { s[e][kt][j] = __builtin_amdgcn_exp2f(s[e][kt][j] - mx); l += s[e][kt][j]; }
;                 l += __shfl_xor(l, 16); l += __shfl_xor(l, 32);
;                 l += __builtin_amdgcn_exp2f(sinkv - mx);
;                 inv[e] = 1.0f / l;
;             }
;             f32x4 o[2][4];
; #pragma unroll
;             for (int e = 0; e < 2; ++e)
; #pragma unroll
;                 for (int dt = 0; dt < 4; ++dt) o[e][dt] = (f32x4){0.f, 0.f, 0.f, 0.f};
; #pragma unroll
;             for (int si = 0; si < 6; ++si) {
;                 if (32 * si >= kstart) {
;                     bf16x8 pf[2];
; #pragma unroll
;                     for (int e = 0; e < 2; ++e) { u32x4 pw; pw.x = pk2(s[e][2 * si][0], s[e][2 * si][1]); pw.y = pk2(s[e][2 * si][2], s[e][2 * si][3]); pw.z = pk2(s[e][2 * si + 1][0], s[e][2 * si + 1][1]); pw.w = pk2(s[e][2 * si + 1][2], s[e][2 * si + 1][3]); pf[e] = __builtin_bit_cast(bf16x8, pw); }
; #pragma unroll
;                     for (int dt = 0; dt < 4; ++dt) {
;                         const u32x2 a = tr_read(Vb + ((32 * si) * KROW + 16 * dt) * 2), bq = tr_read(Vb + ((32 * si + 16) * KROW + 16 * dt) * 2);
;                         const u32x4 vw = {a.x, a.y, bq.x, bq.y}; const bf16x8 vf = __builtin_bit_cast(bf16x8, vw);
; #pragma unroll
;                         for (int e = 0; e < 2; ++e) o[e][dt] = __builtin_amdgcn_mfma_f32_16x16x32_bf16(vf, pf[e], o[e][dt], 0, 0, 0);
;                     }
;                 }
;             }
; #pragma unroll
;             for (int e = 0; e < 2; ++e) { const int row = tok0 + 16 * (2 * pr + e) + q16;
; #pragma unroll
.LBB0_1486:
	v_sub_f32_e32 v32, v160, v32
	v_exp_f32_e32 v32, v32
	s_waitcnt lgkmcnt(1)
	v_add_f32_e32 v40, v66, v67
	v_sub_f32_e32 v36, v160, v36
	v_exp_f32_e32 v36, v36
	v_add_f32_e32 v32, v32, v40
	v_div_scale_f32 v40, s[6:7], v32, v32, 1.0
	v_rcp_f32_e32 v42, v40
	v_cvt_pk_bf16_f32 v37, v35, v37
	v_cvt_pk_bf16_f32 v38, v38, v39
	v_cvt_pk_bf16_f32 v39, v82, v83
	v_fma_f32 v66, -v40, v42, 1.0
	v_fmac_f32_e32 v42, v66, v42
	v_div_scale_f32 v66, vcc, 1.0, v32, 1.0
	v_mul_f32_e32 v67, v66, v42
	v_fma_f32 v68, -v40, v67, v66
	v_fmac_f32_e32 v67, v68, v42
	v_fma_f32 v40, -v40, v67, v66
	v_div_fmas_f32 v40, v40, v42, v67
	v_div_fixup_f32 v42, v40, v32, 1.0
	s_waitcnt lgkmcnt(0)
	v_add_f32_e32 v32, v64, v65
	v_add_f32_e32 v32, v36, v32
	v_div_scale_f32 v36, s[6:7], v32, v32, 1.0
	v_rcp_f32_e32 v40, v36
	v_cvt_pk_bf16_f32 v35, v62, v63
	v_ashrrev_i32_e32 v127, 31, v126
	v_ashrrev_i32_e32 v125, 31, v124
	v_fma_f32 v64, -v36, v40, 1.0
	v_fmac_f32_e32 v40, v64, v40
	v_div_scale_f32 v64, vcc, 1.0, v32, 1.0
	v_mul_f32_e32 v65, v64, v40
	v_fma_f32 v66, -v36, v65, v64
	v_fmac_f32_e32 v65, v66, v40
	v_fma_f32 v36, -v36, v65, v64
	v_div_fmas_f32 v36, v36, v40, v65
	v_div_fixup_f32 v40, v36, v32, 1.0
	v_cvt_pk_bf16_f32 v36, v33, v34
	v_cvt_pk_bf16_f32 v32, v56, v57
	v_cvt_pk_bf16_f32 v33, v58, v59
	v_cvt_pk_bf16_f32 v34, v60, v61
	ds_read_b64_tr_b16 v[56:57], v116 offset:18432
	ds_read_b64_tr_b16 v[60:61], v116 offset:18464
	ds_read_b64_tr_b16 v[58:59], v116 offset:20736
	s_waitcnt lgkmcnt(0)
	v_mfma_f32_16x16x32_bf16 v[24:27], v[56:59], v[36:39], v[24:27]
	ds_read_b64_tr_b16 v[62:63], v116 offset:20768
	s_ashr_i32 s8, s66, 7
	s_bfe_u32 s9, s66, 0x10006
	v_mfma_f32_16x16x32_bf16 v[20:23], v[56:59], v[32:35], v[20:23]
	ds_read_b64_tr_b16 v[56:57], v116 offset:18496
	ds_read_b64_tr_b16 v[58:59], v116 offset:20800
	s_cmpk_gt_u32 s66, 0x7f
	s_waitcnt lgkmcnt(0)
	v_mfma_f32_16x16x32_bf16 v[12:15], v[56:59], v[36:39], v[12:15]
	v_mfma_f32_16x16x32_bf16 v[8:11], v[56:59], v[32:35], v[8:11]
	ds_read_b64_tr_b16 v[56:57], v116 offset:18528
	ds_read_b64_tr_b16 v[58:59], v116 offset:20832
	v_mfma_f32_16x16x32_bf16 v[16:19], v[60:63], v[32:35], v[16:19]
	s_waitcnt lgkmcnt(0)
	v_mfma_f32_16x16x32_bf16 v[0:3], v[56:59], v[32:35], v[0:3]
	v_cvt_pk_bf16_f32 v33, v44, v45
	v_cvt_pk_bf16_f32 v34, v46, v47
	ds_read_b64_tr_b16 v[44:45], v116 offset:23040
	ds_read_b64_tr_b16 v[46:47], v116 offset:25344
	v_mfma_f32_16x16x32_bf16 v[28:31], v[60:63], v[36:39], v[28:31]
	v_cvt_pk_bf16_f32 v32, v41, v43
	v_cvt_pk_bf16_f32 v35, v80, v81
	v_mfma_f32_16x16x32_bf16 v[4:7], v[56:59], v[36:39], v[4:7]
	v_cvt_pk_bf16_f32 v36, v48, v49
	v_cvt_pk_bf16_f32 v37, v50, v51
	v_cvt_pk_bf16_f32 v38, v52, v53
	v_cvt_pk_bf16_f32 v39, v54, v55
	s_waitcnt lgkmcnt(0)
	v_mfma_f32_16x16x32_bf16 v[24:27], v[44:47], v[32:35], v[24:27]
	v_mfma_f32_16x16x32_bf16 v[20:23], v[44:47], v[36:39], v[20:23]
	ds_read_b64_tr_b16 v[44:45], v116 offset:23072
	ds_read_b64_tr_b16 v[46:47], v116 offset:25376
	s_nop 4
	v_pk_mul_f32 v[24:25], v[42:43], v[24:25] op_sel_hi:[0,1]
	v_pk_mul_f32 v[26:27], v[42:43], v[26:27] op_sel_hi:[0,1]
	s_waitcnt lgkmcnt(0)
	v_mfma_f32_16x16x32_bf16 v[28:31], v[44:47], v[32:35], v[28:31]
	v_cvt_pk_bf16_f32 v24, v24, v25
	v_cvt_pk_bf16_f32 v25, v26, v27
	v_mfma_f32_16x16x32_bf16 v[16:19], v[44:47], v[36:39], v[16:19]
	ds_read_b64_tr_b16 v[44:45], v116 offset:23104
	ds_read_b64_tr_b16 v[46:47], v116 offset:25408
	s_nop 2
	v_pk_mul_f32 v[26:27], v[42:43], v[30:31] op_sel_hi:[0,1]
	s_waitcnt lgkmcnt(0)
	v_mfma_f32_16x16x32_bf16 v[12:15], v[44:47], v[32:35], v[12:15]
	v_mfma_f32_16x16x32_bf16 v[8:11], v[44:47], v[36:39], v[8:11]
	ds_read_b64_tr_b16 v[44:45], v116 offset:23136
	ds_read_b64_tr_b16 v[46:47], v116 offset:25440
	s_nop 4
	v_pk_mul_f32 v[12:13], v[42:43], v[12:13] op_sel_hi:[0,1]
	v_pk_mul_f32 v[14:15], v[42:43], v[14:15] op_sel_hi:[0,1]
	s_waitcnt lgkmcnt(0)
	v_mfma_f32_16x16x32_bf16 v[4:7], v[44:47], v[32:35], v[4:7]
	v_lshlrev_b64 v[32:33], 11, v[126:127]
	v_lshl_add_u64 v[32:33], v[114:115], 0, v[32:33]
	v_cvt_pk_bf16_f32 v12, v12, v13
	s_nop 4
	v_pk_mul_f32 v[4:5], v[42:43], v[4:5] op_sel_hi:[0,1]
	v_pk_mul_f32 v[6:7], v[42:43], v[6:7] op_sel_hi:[0,1]
	v_cvt_pk_bf16_f32 v13, v14, v15
	v_cvt_pk_bf16_f32 v4, v4, v5
	v_cvt_pk_bf16_f32 v5, v6, v7
	v_mfma_f32_16x16x32_bf16 v[0:3], v[44:47], v[36:39], v[0:3]
	global_store_dwordx2 v[32:33], v[12:13], off offset:64
	global_store_dwordx2 v[32:33], v[4:5], off offset:96
	v_lshlrev_b64 v[4:5], 11, v[124:125]
	v_pk_mul_f32 v[6:7], v[40:41], v[20:21] op_sel_hi:[0,1]
	v_pk_mul_f32 v[12:13], v[40:41], v[22:23] op_sel_hi:[0,1]
	v_lshl_add_u64 v[4:5], v[114:115], 0, v[4:5]
	v_cvt_pk_bf16_f32 v6, v6, v7
	v_cvt_pk_bf16_f32 v7, v12, v13
	global_store_dwordx2 v[4:5], v[6:7], off
	v_pk_mul_f32 v[6:7], v[40:41], v[16:17] op_sel_hi:[0,1]
	v_pk_mul_f32 v[12:13], v[40:41], v[18:19] op_sel_hi:[0,1]
	v_cvt_pk_bf16_f32 v6, v6, v7
	v_cvt_pk_bf16_f32 v7, v12, v13
	global_store_dwordx2 v[32:33], v[24:25], off
	v_pk_mul_f32 v[24:25], v[42:43], v[28:29] op_sel_hi:[0,1]
	global_store_dwordx2 v[4:5], v[6:7], off offset:32
	v_pk_mul_f32 v[6:7], v[40:41], v[8:9] op_sel_hi:[0,1]
	v_pk_mul_f32 v[8:9], v[40:41], v[10:11] op_sel_hi:[0,1]
	v_pk_mul_f32 v[0:1], v[40:41], v[0:1] op_sel_hi:[0,1]
	v_pk_mul_f32 v[2:3], v[40:41], v[2:3] op_sel_hi:[0,1]
	v_cvt_pk_bf16_f32 v24, v24, v25
	v_cvt_pk_bf16_f32 v25, v26, v27
	v_cvt_pk_bf16_f32 v6, v6, v7
	v_cvt_pk_bf16_f32 v7, v8, v9
	v_cvt_pk_bf16_f32 v0, v0, v1
	v_cvt_pk_bf16_f32 v1, v2, v3
	global_store_dwordx2 v[32:33], v[24:25], off offset:32
	global_store_dwordx2 v[4:5], v[6:7], off offset:64
	global_store_dwordx2 v[4:5], v[0:1], off offset:96
	s_barrier
	s_cbranch_scc0 .LBB0_1492
	s_cmp_lt_i32 s8, 2
	s_mov_b64 s[18:19], 0
	s_cbranch_scc1 .LBB0_1496
	s_mov_b64 s[48:49], -1
	s_mov_b64 s[44:45], 0
	s_cmp_eq_u32 s8, 2
	s_mov_b64 s[10:11], 0
	s_cbranch_scc0 .LBB0_1497
	v_mov_b32_e32 v0, v161
	v_lshrrev_b32_e32 v2, 1, v178
	v_add_u32_e32 v0, 0, v0
	v_add_u32_e32 v0, 0x20130, v0
	s_nop 0
	s_mul_i32 s10, s43, 0x7800
	s_mul_hi_u32 s11, s42, 0x7800
	v_and_b32_e32 v2, 24, v2
	s_add_i32 s11, s11, s10
	s_waitcnt lgkmcnt(0)
	v_readlane_b32 s7, v251, 12
	s_mul_i32 s10, s42, 0x7800
	v_lshl_or_b32 v113, s9, 5, v2
	v_readlane_b32 s6, v251, 13
	s_add_u32 s10, s7, s10
	s_addc_u32 s11, s6, s11
	v_add_u32_e32 v5, -7, v113
	s_not_b32 s14, s77
	v_cmp_eq_u32_e64 s[6:7], 0, v113
	s_mov_b64 s[24:25], 0
	s_and_saveexec_b64 s[30:31], s[6:7]
	s_cbranch_execz .LBB0_1546
	s_and_b64 vcc, exec, s[40:41]
	s_cbranch_vccz .LBB0_1544
	v_cmp_lt_u32_e32 vcc, s14, v5
	s_and_b64 s[48:49], vcc, exec
	s_branch .LBB0_1545

; #define LAS __attribute__((address_space(3)))
; #define PIN(i) ((const float*)ldq_(L, (i)))
; __device__ __forceinline__ unsigned pk2(float lo, float hi) { f32x2 v = {lo, hi}; bf16x2_t b = __builtin_convertvector(v, bf16x2_t); return __builtin_bit_cast(unsigned, b); }
; template <int W> __device__ __forceinline__ void pool_stage(const Params& p, const bf16_t* z, int layer, bool is_s, int b, int c, int tok0, int g, int half, int lane, LAS unsigned char* L) {
;     const int oct = lane & 15, tq = lane >> 4, c0 = 128 * g + 8 * oct, t0 = 32 * half + 8 * tq;
;     const float* sp = PIN(I_SP) + ((size_t)layer * NB + b) * 15 * 512 + c0;
;     u32x4 raw[W + 7];
; #pragma unroll
;     for (int j = 0; j < W + 7; ++j) {
;         const int t = t0 - (W - 1) + j;
;         u32x4 r = {0u, 0u, 0u, 0u};
;         if (t >= 0 || (!is_s && c * 64 + t >= 0)) r = *(const u32x4*)(z + (size_t)(tok0 + t) * NIN + 768 + c0);
;         else if (is_s) { const f32x4 a = *(const f32x4*)(sp + (15 + t) * 512), bb = *(const f32x4*)(sp + (15 + t) * 512 + 4); r.x = pk2(a[0], a[1]); r.y = pk2(a[2], a[3]); r.z = pk2(bb[0], bb[1]); r.w = pk2(bb[2], bb[3]); }
;         raw[j] = r;
.LBB0_1499:
	s_and_b64 vcc, exec, s[18:19]
	s_cbranch_vccz .LBB0_1774
	v_mov_b32_e32 v0, v161
	v_lshrrev_b32_e32 v2, 1, v178
	v_add_u32_e32 v0, 0, v0
	v_add_u32_e32 v0, 0x20130, v0
	s_nop 0
	s_mul_i32 s14, s43, 0x7800
	s_mul_hi_u32 s15, s42, 0x7800
	v_and_b32_e32 v2, 24, v2
	s_add_i32 s15, s15, s14
	s_waitcnt lgkmcnt(0)
	v_readlane_b32 s7, v251, 12
	s_mul_i32 s14, s42, 0x7800
	v_lshl_or_b32 v113, s9, 5, v2
	v_readlane_b32 s6, v251, 13
	s_add_u32 s18, s7, s14
	s_addc_u32 s19, s6, s15
	v_add_u32_e32 v5, -3, v113
	s_not_b32 s14, s77
	v_cmp_eq_u32_e64 s[6:7], 0, v113
	s_mov_b64 s[44:45], -1
	s_mov_b64 s[24:25], 0
	s_and_saveexec_b64 s[30:31], s[6:7]
	s_cbranch_execz .LBB0_1505
	s_and_b64 vcc, exec, s[40:41]
	s_cbranch_vccz .LBB0_1503
	v_cmp_lt_u32_e32 vcc, s14, v5
	s_and_b64 s[44:45], vcc, exec
	s_branch .LBB0_1504

; #define LAS __attribute__((address_space(3)))
; __device__ __forceinline__ unsigned pk2(float lo, float hi) { f32x2 v = {lo, hi}; bf16x2_t b = __builtin_convertvector(v, bf16x2_t); return __builtin_bit_cast(unsigned, b); }
; __device__ __forceinline__ bf16x8 pack8(const float* v) { u32x4 w; w.x = pk2(v[0], v[1]); w.y = pk2(v[2], v[3]); w.z = pk2(v[4], v[5]); w.w = pk2(v[6], v[7]); return __builtin_bit_cast(bf16x8, w); }
; __device__ __forceinline__ void unpack8(u32x4 w, float* v) { v[0] = bflo(w.x); v[1] = bfhi(w.x); v[2] = bflo(w.y); v[3] = bfhi(w.y); v[4] = bflo(w.z); v[5] = bfhi(w.z); v[6] = bflo(w.w); v[7] = bfhi(w.w); }
; template <int W> __device__ __forceinline__ void pool_stage(const Params& p, const bf16_t* z, int layer, bool is_s, int b, int c, int tok0, int g, int half, int lane, LAS unsigned char* L) {
;     ...
;     u32x4 raw[W + 7];
; #pragma unroll
;     for (int j = 0; j < W + 7; ++j) {
;         const int t = t0 - (W - 1) + j;
;         u32x4 r = {0u, 0u, 0u, 0u};
;         if (t >= 0 || (!is_s && c * 64 + t >= 0)) r = *(const u32x4*)(z + (size_t)(tok0 + t) * NIN + 768 + c0);
;         else if (is_s) { const f32x4 a = *(const f32x4*)(sp + (15 + t) * 512), bb = *(const f32x4*)(sp + (15 + t) * 512 + 4); r.x = pk2(a[0], a[1]); r.y = pk2(a[2], a[3]); r.z = pk2(bb[0], bb[1]); r.w = pk2(bb[2], bb[3]); }
;         raw[j] = r;
;     }
;     float sum[8];
; #pragma unroll
;     for (int i = 0; i < 8; ++i) sum[i] = 0.f;
; #pragma unroll
;     for (int j = 0; j < W - 1; ++j) { float u[8]; unpack8(raw[j], u);
; #pragma unroll
;         for (int i = 0; i < 8; ++i) sum[i] += u[i]; }
; #pragma unroll
;     for (int ti = 0; ti < 8; ++ti) {
;         const int t = t0 + ti; float u[8], ul[8], d[8]; unpack8(raw[W - 1 + ti], u); unpack8(raw[ti], ul);
;         const int cnt = is_s ? W : min(c * 64 + t + 1, W); const float rc = 1.0f / (float)cnt;
; #pragma unroll
;         for (int i = 0; i < 8; ++i) { sum[i] += u[i]; d[i] = sum[i] * rc - u[i]; sum[i] -= ul[i]; }
;         *(LAS bf16x8*)(L + (t * DROW + c0) * 2) = pack8(d);
;         if (t >= 49 && (is_s || c == 31)) { float* o = POUT + (is_s ? O_US : O_UP) + (((size_t)layer * NB + b) * 15 + (t - 49)) * 512 + c0;
;             *(f32x4*)o = (f32x4){u[0], u[1], u[2], u[3]}; *(f32x4*)(o + 4) = (f32x4){u[4], u[5], u[6], u[7]}; }
.LBB0_1527:
	s_or_b64 exec, exec, s[6:7]
	v_add_u32_e32 v10, s67, v113
	v_mov_b64_e32 v[6:7], s[34:35]
	v_mad_i64_i32 v[8:9], s[6:7], v10, s84, v[6:7]
	v_mov_b32_e32 v5, v161
	v_lshl_add_u64 v[8:9], v[8:9], 0, v[4:5]
	v_or_b32_e32 v76, 1, v113
	v_or_b32_e32 v75, 2, v113
	v_or_b32_e32 v74, 3, v113
	global_load_dwordx4 v[20:23], v[8:9], off offset:1792
	v_or_b32_e32 v73, 5, v113
	v_or_b32_e32 v72, 6, v113
	v_or_b32_e32 v71, 7, v113
	s_waitcnt vmcnt(1)
	v_lshlrev_b32_e32 v54, 16, v0
	v_and_b32_e32 v55, 0xffff0000, v0
	v_lshlrev_b32_e32 v58, 16, v2
	v_and_b32_e32 v59, 0xffff0000, v2
	v_add_u32_e32 v0, s67, v76
	v_add_u32_e32 v2, s67, v75
	v_add_u32_e32 v8, s67, v74
	v_add_u32_e32 v10, 4, v10
	v_lshlrev_b32_e32 v56, 16, v1
	v_and_b32_e32 v57, 0xffff0000, v1
	v_lshlrev_b32_e32 v60, 16, v3
	v_and_b32_e32 v61, 0xffff0000, v3
	v_add_u32_e32 v12, s67, v73
	v_add_u32_e32 v14, s67, v72
	v_add_u32_e32 v16, s67, v71
	v_mad_i64_i32 v[0:1], s[6:7], v0, s84, v[6:7]
	v_mad_i64_i32 v[2:3], s[6:7], v2, s84, v[6:7]
	v_mad_i64_i32 v[8:9], s[6:7], v8, s84, v[6:7]
	v_mad_i64_i32 v[10:11], s[6:7], v10, s84, v[6:7]
	v_mad_i64_i32 v[12:13], s[6:7], v12, s84, v[6:7]
	v_mad_i64_i32 v[14:15], s[6:7], v14, s84, v[6:7]
	v_mad_i64_i32 v[6:7], s[6:7], v16, s84, v[6:7]
	v_lshl_add_u64 v[0:1], v[0:1], 0, v[4:5]
	v_lshl_add_u64 v[2:3], v[2:3], 0, v[4:5]
	v_lshl_add_u64 v[8:9], v[8:9], 0, v[4:5]
	v_lshl_add_u64 v[10:11], v[10:11], 0, v[4:5]
	v_lshl_add_u64 v[16:17], v[12:13], 0, v[4:5]
	v_lshl_add_u64 v[18:19], v[14:15], 0, v[4:5]
	v_lshl_add_u64 v[44:45], v[6:7], 0, v[4:5]
	global_load_dwordx4 v[36:39], v[0:1], off offset:1792
	global_load_dwordx4 v[40:43], v[2:3], off offset:1792
	global_load_dwordx4 v[24:27], v[8:9], off offset:1792
	global_load_dwordx4 v[12:15], v[10:11], off offset:1792
	s_nop 0
	global_load_dwordx4 v[8:11], v[16:17], off offset:1792
	global_load_dwordx4 v[4:7], v[18:19], off offset:1792
	global_load_dwordx4 v[0:3], v[44:45], off offset:1792
	v_or_b32_e32 v16, s77, v113
	v_min_u32_e32 v16, 3, v16
	v_add_u32_e32 v16, 1, v16
	v_cvt_f32_ubyte0_e32 v44, v16
	v_div_scale_f32 v45, s[18:19], v44, v44, 1.0
	v_rcp_f32_e32 v46, v45
	v_div_scale_f32 v47, vcc, 1.0, v44, 1.0
	s_mul_i32 s14, s43, 15
	v_fma_f32 v16, -v45, v46, 1.0
	v_fmac_f32_e32 v46, v16, v46
	v_mul_f32_e32 v48, v47, v46
	v_fma_f32 v49, -v45, v48, v47
	v_fmac_f32_e32 v48, v49, v46
	v_fma_f32 v45, -v45, v48, v47
	v_div_fmas_f32 v45, v45, v46, v48
	v_div_fixup_f32 v44, v45, v44, 1.0
	s_mul_hi_u32 s15, s42, 15
	v_cndmask_b32_e64 v78, v44, v202, s[4:5]
	v_pk_add_f32 v[44:45], v[54:55], 0 op_sel_hi:[1,0]
	v_lshlrev_b32_e32 v52, 16, v28
	v_and_b32_e32 v53, 0xffff0000, v28
	s_add_i32 s7, s15, s14
	v_pk_add_f32 v[46:47], v[44:45], v[52:53]
	v_lshlrev_b32_e32 v44, 16, v32
	v_and_b32_e32 v45, 0xffff0000, v32
	s_cmp_eq_u32 s76, 31
	v_pk_add_f32 v[46:47], v[46:47], v[44:45]
	s_cselect_b64 s[14:15], -1, 0
	v_lshlrev_b32_e32 v62, 16, v29
	v_and_b32_e32 v63, 0xffff0000, v29
	s_or_b64 s[18:19], s[4:5], s[14:15]
	v_lshlrev_b32_e32 v64, 16, v30
	v_and_b32_e32 v65, 0xffff0000, v30
	v_pk_add_f32 v[50:51], v[60:61], 0 op_sel_hi:[1,0]
	v_lshlrev_b32_e32 v66, 16, v31
	v_and_b32_e32 v67, 0xffff0000, v31
	s_and_b64 s[14:15], s[4:5], exec
	s_waitcnt vmcnt(7)
	v_lshlrev_b32_e32 v16, 16, v20
	v_and_b32_e32 v17, 0xffff0000, v20
	v_pk_add_f32 v[68:69], v[46:47], v[16:17]
	v_pk_add_f32 v[46:47], v[56:57], 0 op_sel_hi:[1,0]
	v_lshlrev_b32_e32 v48, 16, v34
	v_pk_add_f32 v[28:29], v[46:47], v[62:63]
	v_lshlrev_b32_e32 v46, 16, v33
	v_and_b32_e32 v47, 0xffff0000, v33
	v_pk_add_f32 v[32:33], v[58:59], 0 op_sel_hi:[1,0]
	v_and_b32_e32 v49, 0xffff0000, v34
	v_pk_add_f32 v[32:33], v[32:33], v[64:65]
	v_pk_add_f32 v[30:31], v[50:51], v[66:67]
	v_lshlrev_b32_e32 v50, 16, v35
	v_and_b32_e32 v51, 0xffff0000, v35
	s_mov_b32 s14, 0x4678000
	v_lshlrev_b32_e32 v18, 16, v21
	v_and_b32_e32 v19, 0xffff0000, v21
	v_lshlrev_b32_e32 v20, 16, v22
	v_and_b32_e32 v21, 0xffff0000, v22
	v_lshlrev_b32_e32 v22, 16, v23
	v_and_b32_e32 v23, 0xffff0000, v23
	v_pk_add_f32 v[28:29], v[28:29], v[46:47]
	v_pk_add_f32 v[32:33], v[32:33], v[48:49]
	v_pk_add_f32 v[30:31], v[30:31], v[50:51]
	v_or_b32_e32 v92, 0x80, v70
	s_cselect_b32 s16, s14, 0x4400000
	v_pk_add_f32 v[28:29], v[28:29], v[18:19]
	v_pk_add_f32 v[32:33], v[32:33], v[20:21]
	v_pk_add_f32 v[30:31], v[30:31], v[22:23]
	s_movk_i32 s14, 0x208
	v_pk_fma_f32 v[80:81], v[78:79], v[68:69], v[16:17] op_sel_hi:[0,1,1] neg_lo:[0,0,1] neg_hi:[0,0,1]
	v_pk_fma_f32 v[82:83], v[78:79], v[28:29], v[18:19] op_sel_hi:[0,1,1] neg_lo:[0,0,1] neg_hi:[0,0,1]
	v_pk_fma_f32 v[84:85], v[78:79], v[32:33], v[20:21] op_sel_hi:[0,1,1] neg_lo:[0,0,1] neg_hi:[0,0,1]
	v_pk_fma_f32 v[34:35], v[78:79], v[30:31], v[22:23] op_sel_hi:[0,1,1] neg_lo:[0,0,1] neg_hi:[0,0,1]
	v_mad_u32_u24 v77, v113, s14, v92
	v_cmp_lt_u32_e32 vcc, 48, v113
	s_mul_i32 s6, s42, 15
	v_cvt_pk_bf16_f32 v78, v80, v81
	v_cvt_pk_bf16_f32 v79, v82, v83
	v_cvt_pk_bf16_f32 v80, v84, v85
	v_cvt_pk_bf16_f32 v81, v34, v35
	v_lshl_add_u32 v34, v77, 1, 0
	s_and_b64 s[14:15], s[18:19], vcc
	ds_write_b128 v34, v[78:81]
	s_and_saveexec_b64 s[24:25], s[14:15]
	s_cbranch_execz .LBB0_1529
	v_mov_b32_e32 v34, v161
	s_lshl_b32 s14, s16, 2
	v_add_u32_e32 v34, 0, v34
	v_add_u32_e32 v34, 0x201c8, v34
	s_nop 0
	v_subrev_u32_e32 v78, 49, v113
	v_mov_b32_e32 v79, v161
	s_waitcnt lgkmcnt(0)
	v_readlane_b32 s21, v251, 50
	v_readlane_b32 s15, v251, 51
	s_add_u32 s14, s21, s14
	v_lshl_add_u64 v[34:35], s[6:7], 0, v[78:79]
	s_addc_u32 s15, s15, 0
	v_lshlrev_b64 v[34:35], 11, v[34:35]
	v_lshl_add_u64 v[34:35], s[14:15], 0, v[34:35]
	v_lshl_add_u64 v[34:35], v[34:35], 0, v[160:161]
	global_store_dwordx4 v[34:35], v[16:19], off offset:512
	global_store_dwordx4 v[34:35], v[20:23], off offset:528
; #define LAS __attribute__((address_space(3)))
; __device__ __forceinline__ bf16x8 pack8(const float* v) { u32x4 w; w.x = pk2(v[0], v[1]); w.y = pk2(v[2], v[3]); w.z = pk2(v[4], v[5]); w.w = pk2(v[6], v[7]); return __builtin_bit_cast(bf16x8, w); }
; __device__ __forceinline__ void unpack8(u32x4 w, float* v) { v[0] = bflo(w.x); v[1] = bfhi(w.x); v[2] = bflo(w.y); v[3] = bfhi(w.y); v[4] = bflo(w.z); v[5] = bfhi(w.z); v[6] = bflo(w.w); v[7] = bfhi(w.w); }
; template <int W> __device__ __forceinline__ void pool_stage(const Params& p, const bf16_t* z, int layer, bool is_s, int b, int c, int tok0, int g, int half, int lane, LAS unsigned char* L) {
;     ...
;     for (int ti = 0; ti < 8; ++ti) {
;         const int t = t0 + ti; float u[8], ul[8], d[8]; unpack8(raw[W - 1 + ti], u); unpack8(raw[ti], ul);
;         const int cnt = is_s ? W : min(c * 64 + t + 1, W); const float rc = 1.0f / (float)cnt;
; #pragma unroll
;         for (int i = 0; i < 8; ++i) { sum[i] += u[i]; d[i] = sum[i] * rc - u[i]; sum[i] -= ul[i]; }
;         *(LAS bf16x8*)(L + (t * DROW + c0) * 2) = pack8(d);
;         if (t >= 49 && (is_s || c == 31)) { float* o = POUT + (is_s ? O_US : O_UP) + (((size_t)layer * NB + b) * 15 + (t - 49)) * 512 + c0;
;             *(f32x4*)o = (f32x4){u[0], u[1], u[2], u[3]}; *(f32x4*)(o + 4) = (f32x4){u[4], u[5], u[6], u[7]}; }
.LBB0_1529:
	s_or_b64 exec, exec, s[24:25]
	v_pk_add_f32 v[58:59], v[32:33], v[58:59] neg_lo:[0,1] neg_hi:[0,1]
	v_or_b32_e32 v33, s77, v76
	v_min_u32_e32 v33, 3, v33
	v_add_u32_e32 v33, 1, v33
	v_pk_add_f32 v[56:57], v[28:29], v[56:57] neg_lo:[0,1] neg_hi:[0,1]
	s_waitcnt vmcnt(6)
	v_lshlrev_b32_e32 v28, 16, v36
	v_and_b32_e32 v29, 0xffff0000, v36
	v_cvt_f32_ubyte0_e32 v36, v33
	v_pk_add_f32 v[60:61], v[30:31], v[60:61] neg_lo:[0,1] neg_hi:[0,1]
	v_lshlrev_b32_e32 v30, 16, v37
	v_and_b32_e32 v31, 0xffff0000, v37
	v_div_scale_f32 v37, s[14:15], v36, v36, 1.0
	v_pk_add_f32 v[54:55], v[68:69], v[54:55] neg_lo:[0,1] neg_hi:[0,1]
	v_rcp_f32_e32 v68, v37
	v_lshlrev_b32_e32 v32, 16, v38
	v_and_b32_e32 v33, 0xffff0000, v38
	v_lshlrev_b32_e32 v34, 16, v39
	v_fma_f32 v38, -v37, v68, 1.0
	v_fmac_f32_e32 v68, v38, v68
	v_div_scale_f32 v38, vcc, 1.0, v36, 1.0
	v_and_b32_e32 v35, 0xffff0000, v39
	v_mul_f32_e32 v39, v38, v68
	v_fma_f32 v69, -v37, v39, v38
	v_fmac_f32_e32 v39, v69, v68
	v_fma_f32 v37, -v37, v39, v38
	v_div_fmas_f32 v37, v37, v68, v39
	v_div_fixup_f32 v36, v37, v36, 1.0
	v_cndmask_b32_e64 v68, v36, v202, s[4:5]
	v_pk_add_f32 v[36:37], v[54:55], v[28:29]
	v_pk_add_f32 v[38:39], v[56:57], v[30:31]
	v_pk_add_f32 v[56:57], v[60:61], v[34:35]
	v_pk_fma_f32 v[78:79], v[68:69], v[36:37], v[28:29] op_sel_hi:[0,1,1] neg_lo:[0,0,1] neg_hi:[0,0,1]
	v_pk_fma_f32 v[80:81], v[68:69], v[38:39], v[30:31] op_sel_hi:[0,1,1] neg_lo:[0,0,1] neg_hi:[0,0,1]
	v_pk_add_f32 v[54:55], v[58:59], v[32:33]
	v_pk_fma_f32 v[60:61], v[68:69], v[56:57], v[34:35] op_sel_hi:[0,1,1] neg_lo:[0,0,1] neg_hi:[0,0,1]
	v_pk_fma_f32 v[58:59], v[68:69], v[54:55], v[32:33] op_sel_hi:[0,1,1] neg_lo:[0,0,1] neg_hi:[0,0,1]
	v_cvt_pk_bf16_f32 v78, v78, v79
	v_cvt_pk_bf16_f32 v79, v80, v81
	v_cvt_pk_bf16_f32 v81, v60, v61
	v_add_u32_e32 v60, 0x208, v77
	v_cmp_lt_u32_e32 vcc, 47, v113
	v_cvt_pk_bf16_f32 v80, v58, v59
	v_lshl_add_u32 v58, v60, 1, 0
	s_and_b64 s[44:45], s[18:19], vcc
	ds_write_b128 v58, v[78:81]
	s_and_saveexec_b64 s[24:25], s[44:45]
	s_cbranch_execz .LBB0_1531
	v_mov_b32_e32 v58, v161
	s_lshl_b32 s14, s16, 2
	v_add_u32_e32 v58, 0, v58
	v_add_u32_e32 v58, 0x201c8, v58
	s_nop 0
	v_subrev_u32_e32 v68, 48, v113
	v_mov_b32_e32 v69, v161
	s_waitcnt lgkmcnt(0)
	v_readlane_b32 s21, v251, 50
	v_readlane_b32 s15, v251, 51
	s_add_u32 s14, s21, s14
	v_lshl_add_u64 v[58:59], s[6:7], 0, v[68:69]
	s_addc_u32 s15, s15, 0
	v_lshlrev_b64 v[58:59], 11, v[58:59]
	v_lshl_add_u64 v[58:59], s[14:15], 0, v[58:59]
	v_lshl_add_u64 v[58:59], v[58:59], 0, v[160:161]
	global_store_dwordx4 v[58:59], v[28:31], off offset:512
	global_store_dwordx4 v[58:59], v[32:35], off offset:528
.LBB0_1531:
	s_or_b64 exec, exec, s[24:25]
	v_pk_add_f32 v[58:59], v[38:39], v[62:63] neg_lo:[0,1] neg_hi:[0,1]
	s_waitcnt vmcnt(5)
	v_lshlrev_b32_e32 v38, 16, v41
	v_and_b32_e32 v39, 0xffff0000, v41
	v_or_b32_e32 v41, s77, v75
	v_min_u32_e32 v41, 3, v41
	v_add_u32_e32 v41, 1, v41
	v_pk_add_f32 v[62:63], v[54:55], v[64:65] neg_lo:[0,1] neg_hi:[0,1]
	v_cvt_f32_ubyte0_e32 v54, v41
	v_div_scale_f32 v55, s[14:15], v54, v54, 1.0
	v_pk_add_f32 v[64:65], v[56:57], v[66:67] neg_lo:[0,1] neg_hi:[0,1]
	v_rcp_f32_e32 v56, v55
	v_pk_add_f32 v[52:53], v[36:37], v[52:53] neg_lo:[0,1] neg_hi:[0,1]
	v_lshlrev_b32_e32 v36, 16, v40
	v_and_b32_e32 v37, 0xffff0000, v40
	v_fma_f32 v57, -v55, v56, 1.0
	v_fmac_f32_e32 v56, v57, v56
	v_div_scale_f32 v57, vcc, 1.0, v54, 1.0
	v_mul_f32_e32 v61, v57, v56
	v_fma_f32 v66, -v55, v61, v57
	v_fmac_f32_e32 v61, v66, v56
	v_fma_f32 v55, -v55, v61, v57
	v_div_fmas_f32 v55, v55, v56, v61
	v_lshlrev_b32_e32 v40, 16, v42
	v_and_b32_e32 v41, 0xffff0000, v42
	v_lshlrev_b32_e32 v42, 16, v43
	v_and_b32_e32 v43, 0xffff0000, v43
	v_div_fixup_f32 v54, v55, v54, 1.0
	v_cndmask_b32_e64 v66, v54, v202, s[4:5]
	v_pk_add_f32 v[52:53], v[52:53], v[36:37]
	v_pk_add_f32 v[54:55], v[58:59], v[38:39]
	v_pk_add_f32 v[56:57], v[62:63], v[40:41]
	v_pk_add_f32 v[58:59], v[64:65], v[42:43]
	v_pk_fma_f32 v[68:69], v[66:67], v[52:53], v[36:37] op_sel_hi:[0,1,1] neg_lo:[0,0,1] neg_hi:[0,0,1]
	v_pk_fma_f32 v[76:77], v[66:67], v[54:55], v[38:39] op_sel_hi:[0,1,1] neg_lo:[0,0,1] neg_hi:[0,0,1]
	v_pk_fma_f32 v[78:79], v[66:67], v[56:57], v[40:41] op_sel_hi:[0,1,1] neg_lo:[0,0,1] neg_hi:[0,0,1]
	v_pk_fma_f32 v[66:67], v[66:67], v[58:59], v[42:43] op_sel_hi:[0,1,1] neg_lo:[0,0,1] neg_hi:[0,0,1]
	v_add_u32_e32 v60, 0x208, v60
	v_cvt_pk_bf16_f32 v62, v68, v69
	v_cvt_pk_bf16_f32 v63, v76, v77
	v_cvt_pk_bf16_f32 v64, v78, v79
	v_cvt_pk_bf16_f32 v65, v66, v67
	v_lshl_add_u32 v61, v60, 1, 0
	ds_write_b128 v61, v[62:65]
	s_and_saveexec_b64 s[24:25], s[44:45]
	s_cbranch_execz .LBB0_1533
	v_mov_b32_e32 v61, v161
	s_lshl_b32 s14, s16, 2
	v_add_u32_e32 v61, 0, v61
	v_add_u32_e32 v61, 0x201c8, v61
	s_nop 0
	v_subrev_u32_e32 v64, 47, v113
	v_mov_b32_e32 v65, v161
	s_waitcnt lgkmcnt(0)
	v_readlane_b32 s21, v251, 50
	v_readlane_b32 s15, v251, 51
	s_add_u32 s14, s21, s14
	v_lshl_add_u64 v[62:63], s[6:7], 0, v[64:65]
	s_addc_u32 s15, s15, 0
	v_lshlrev_b64 v[62:63], 11, v[62:63]
	v_lshl_add_u64 v[62:63], s[14:15], 0, v[62:63]
	v_lshl_add_u64 v[62:63], v[62:63], 0, v[160:161]
	global_store_dwordx4 v[62:63], v[36:39], off offset:512
	global_store_dwordx4 v[62:63], v[40:43], off offset:528
; #define LAS __attribute__((address_space(3)))
; __device__ __forceinline__ bf16x8 pack8(const float* v) { u32x4 w; w.x = pk2(v[0], v[1]); w.y = pk2(v[2], v[3]); w.z = pk2(v[4], v[5]); w.w = pk2(v[6], v[7]); return __builtin_bit_cast(bf16x8, w); }
; __device__ __forceinline__ void unpack8(u32x4 w, float* v) { v[0] = bflo(w.x); v[1] = bfhi(w.x); v[2] = bflo(w.y); v[3] = bfhi(w.y); v[4] = bflo(w.z); v[5] = bfhi(w.z); v[6] = bflo(w.w); v[7] = bfhi(w.w); }
; template <int W> __device__ __forceinline__ void pool_stage(const Params& p, const bf16_t* z, int layer, bool is_s, int b, int c, int tok0, int g, int half, int lane, LAS unsigned char* L) {
;     ...
;     for (int ti = 0; ti < 8; ++ti) {
;         const int t = t0 + ti; float u[8], ul[8], d[8]; unpack8(raw[W - 1 + ti], u); unpack8(raw[ti], ul);
;         const int cnt = is_s ? W : min(c * 64 + t + 1, W); const float rc = 1.0f / (float)cnt;
; #pragma unroll
;         for (int i = 0; i < 8; ++i) { sum[i] += u[i]; d[i] = sum[i] * rc - u[i]; sum[i] -= ul[i]; }
;         *(LAS bf16x8*)(L + (t * DROW + c0) * 2) = pack8(d);
;         if (t >= 49 && (is_s || c == 31)) { float* o = POUT + (is_s ? O_US : O_UP) + (((size_t)layer * NB + b) * 15 + (t - 49)) * 512 + c0;
;             *(f32x4*)o = (f32x4){u[0], u[1], u[2], u[3]}; *(f32x4*)(o + 4) = (f32x4){u[4], u[5], u[6], u[7]}; }
.LBB0_1533:
	s_or_b64 exec, exec, s[24:25]
	v_pk_add_f32 v[52:53], v[52:53], v[44:45] neg_lo:[0,1] neg_hi:[0,1]
	v_pk_add_f32 v[54:55], v[54:55], v[46:47] neg_lo:[0,1] neg_hi:[0,1]
	v_pk_add_f32 v[56:57], v[56:57], v[48:49] neg_lo:[0,1] neg_hi:[0,1]
	s_waitcnt vmcnt(4)
	v_lshlrev_b32_e32 v44, 16, v24
	v_and_b32_e32 v45, 0xffff0000, v24
	v_lshlrev_b32_e32 v46, 16, v25
	v_and_b32_e32 v47, 0xffff0000, v25
	v_lshlrev_b32_e32 v24, 16, v26
	v_and_b32_e32 v25, 0xffff0000, v26
	v_pk_add_f32 v[58:59], v[58:59], v[50:51] neg_lo:[0,1] neg_hi:[0,1]
	v_pk_add_f32 v[48:49], v[52:53], v[44:45]
	s_mov_b32 s14, 0x3e800000
	v_pk_add_f32 v[50:51], v[54:55], v[46:47]
	v_pk_add_f32 v[52:53], v[56:57], v[24:25]
	v_lshlrev_b32_e32 v26, 16, v27
	v_and_b32_e32 v27, 0xffff0000, v27
	v_pk_fma_f32 v[62:63], v[48:49], s[14:15], v[44:45] op_sel_hi:[1,0,1] neg_lo:[0,0,1] neg_hi:[0,0,1]
	v_pk_fma_f32 v[64:65], v[50:51], s[14:15], v[46:47] op_sel_hi:[1,0,1] neg_lo:[0,0,1] neg_hi:[0,0,1]
	v_pk_fma_f32 v[56:57], v[52:53], s[14:15], v[24:25] op_sel_hi:[1,0,1] neg_lo:[0,0,1] neg_hi:[0,0,1]
	v_pk_add_f32 v[54:55], v[58:59], v[26:27]
	v_cvt_pk_bf16_f32 v62, v62, v63
	v_pk_fma_f32 v[58:59], v[54:55], s[14:15], v[26:27] op_sel_hi:[1,0,1] neg_lo:[0,0,1] neg_hi:[0,0,1]
	v_cvt_pk_bf16_f32 v63, v64, v65
	v_cvt_pk_bf16_f32 v64, v56, v57
	v_add_u32_e32 v56, 0x208, v60
	v_cmp_lt_u32_e32 vcc, 48, v74
	v_cvt_pk_bf16_f32 v65, v58, v59
	v_lshl_add_u32 v57, v56, 1, 0
	s_and_b64 s[14:15], s[18:19], vcc
	ds_write_b128 v57, v[62:65]
	s_and_saveexec_b64 s[24:25], s[14:15]
	s_cbranch_execz .LBB0_1535
	v_mov_b32_e32 v57, v161
	s_lshl_b32 s14, s16, 2
	v_add_u32_e32 v57, 0, v57
	v_add_u32_e32 v57, 0x201c8, v57
	s_nop 0
	v_subrev_u32_e32 v60, 46, v113
	v_mov_b32_e32 v61, v161
	s_waitcnt lgkmcnt(0)
	v_readlane_b32 s21, v251, 50
	v_readlane_b32 s15, v251, 51
	s_add_u32 s14, s21, s14
	v_lshl_add_u64 v[58:59], s[6:7], 0, v[60:61]
	s_addc_u32 s15, s15, 0
	v_lshlrev_b64 v[58:59], 11, v[58:59]
	v_lshl_add_u64 v[58:59], s[14:15], 0, v[58:59]
	v_lshl_add_u64 v[58:59], v[58:59], 0, v[160:161]
	global_store_dwordx4 v[58:59], v[44:47], off offset:512
	global_store_dwordx4 v[58:59], v[24:27], off offset:528
.LBB0_1535:
	s_or_b64 exec, exec, s[24:25]
	v_pk_add_f32 v[48:49], v[48:49], v[16:17] neg_lo:[0,1] neg_hi:[0,1]
	v_pk_add_f32 v[50:51], v[50:51], v[18:19] neg_lo:[0,1] neg_hi:[0,1]
	v_pk_add_f32 v[52:53], v[52:53], v[20:21] neg_lo:[0,1] neg_hi:[0,1]
	v_pk_add_f32 v[54:55], v[54:55], v[22:23] neg_lo:[0,1] neg_hi:[0,1]
	s_waitcnt vmcnt(3)
	v_lshlrev_b32_e32 v16, 16, v12
	v_and_b32_e32 v17, 0xffff0000, v12
	v_lshlrev_b32_e32 v18, 16, v13
	v_and_b32_e32 v19, 0xffff0000, v13
	v_lshlrev_b32_e32 v12, 16, v14
	v_and_b32_e32 v13, 0xffff0000, v14
	v_lshlrev_b32_e32 v14, 16, v15
	v_and_b32_e32 v15, 0xffff0000, v15
	v_mul_u32_u24_e32 v57, 0x208, v113
	v_pk_add_f32 v[20:21], v[48:49], v[16:17]
	s_mov_b32 s14, 0x3e800000
	v_pk_add_f32 v[22:23], v[50:51], v[18:19]
	v_pk_add_f32 v[48:49], v[52:53], v[12:13]
	v_pk_add_f32 v[50:51], v[54:55], v[14:15]
	v_pk_fma_f32 v[58:59], v[20:21], s[14:15], v[16:17] op_sel_hi:[1,0,1] neg_lo:[0,0,1] neg_hi:[0,0,1]
	v_pk_fma_f32 v[60:61], v[22:23], s[14:15], v[18:19] op_sel_hi:[1,0,1] neg_lo:[0,0,1] neg_hi:[0,0,1]
	v_pk_fma_f32 v[62:63], v[48:49], s[14:15], v[12:13] op_sel_hi:[1,0,1] neg_lo:[0,0,1] neg_hi:[0,0,1]
	v_pk_fma_f32 v[64:65], v[50:51], s[14:15], v[14:15] op_sel_hi:[1,0,1] neg_lo:[0,0,1] neg_hi:[0,0,1]
	v_add_u32_e32 v57, v70, v57
	v_cvt_pk_bf16_f32 v52, v58, v59
	v_cvt_pk_bf16_f32 v53, v60, v61
	v_cvt_pk_bf16_f32 v54, v62, v63
	v_cvt_pk_bf16_f32 v55, v64, v65
	v_lshl_add_u32 v57, v57, 1, 0
	ds_write_b128 v57, v[52:55] offset:4416
	s_and_saveexec_b64 s[24:25], s[44:45]
	s_cbranch_execz .LBB0_1537
	v_mov_b32_e32 v52, v161
	s_lshl_b32 s14, s16, 2
	v_add_u32_e32 v52, 0, v52
	v_add_u32_e32 v52, 0x201c8, v52
	s_nop 0
	v_subrev_u32_e32 v54, 45, v113
	v_mov_b32_e32 v55, v161
	s_waitcnt lgkmcnt(0)
	v_readlane_b32 s21, v251, 50
	v_readlane_b32 s15, v251, 51
	s_add_u32 s14, s21, s14
	v_lshl_add_u64 v[52:53], s[6:7], 0, v[54:55]
	s_addc_u32 s15, s15, 0
	v_lshlrev_b64 v[52:53], 11, v[52:53]
	v_lshl_add_u64 v[52:53], s[14:15], 0, v[52:53]
	v_lshl_add_u64 v[52:53], v[52:53], 0, v[160:161]
	global_store_dwordx4 v[52:53], v[16:19], off offset:512
	global_store_dwordx4 v[52:53], v[12:15], off offset:528
; #define LAS __attribute__((address_space(3)))
; __device__ __forceinline__ bf16x8 pack8(const float* v) { u32x4 w; w.x = pk2(v[0], v[1]); w.y = pk2(v[2], v[3]); w.z = pk2(v[4], v[5]); w.w = pk2(v[6], v[7]); return __builtin_bit_cast(bf16x8, w); }
; __device__ __forceinline__ void unpack8(u32x4 w, float* v) { v[0] = bflo(w.x); v[1] = bfhi(w.x); v[2] = bflo(w.y); v[3] = bfhi(w.y); v[4] = bflo(w.z); v[5] = bfhi(w.z); v[6] = bflo(w.w); v[7] = bfhi(w.w); }
; template <int W> __device__ __forceinline__ void pool_stage(const Params& p, const bf16_t* z, int layer, bool is_s, int b, int c, int tok0, int g, int half, int lane, LAS unsigned char* L) {
;     ...
;     for (int ti = 0; ti < 8; ++ti) {
;         const int t = t0 + ti; float u[8], ul[8], d[8]; unpack8(raw[W - 1 + ti], u); unpack8(raw[ti], ul);
;         const int cnt = is_s ? W : min(c * 64 + t + 1, W); const float rc = 1.0f / (float)cnt;
; #pragma unroll
;         for (int i = 0; i < 8; ++i) { sum[i] += u[i]; d[i] = sum[i] * rc - u[i]; sum[i] -= ul[i]; }
;         *(LAS bf16x8*)(L + (t * DROW + c0) * 2) = pack8(d);
;         if (t >= 49 && (is_s || c == 31)) { float* o = POUT + (is_s ? O_US : O_UP) + (((size_t)layer * NB + b) * 15 + (t - 49)) * 512 + c0;
;             *(f32x4*)o = (f32x4){u[0], u[1], u[2], u[3]}; *(f32x4*)(o + 4) = (f32x4){u[4], u[5], u[6], u[7]}; }
.LBB0_1537:
	s_or_b64 exec, exec, s[24:25]
	s_nop 0
	v_pk_add_f32 v[14:15], v[20:21], v[28:29] neg_lo:[0,1] neg_hi:[0,1]
	s_waitcnt vmcnt(2)
	v_lshlrev_b32_e32 v12, 16, v8
	v_and_b32_e32 v13, 0xffff0000, v8
	v_pk_add_f32 v[18:19], v[22:23], v[30:31] neg_lo:[0,1] neg_hi:[0,1]
	v_pk_add_f32 v[20:21], v[48:49], v[32:33] neg_lo:[0,1] neg_hi:[0,1]
	v_pk_add_f32 v[22:23], v[50:51], v[34:35] neg_lo:[0,1] neg_hi:[0,1]
	v_pk_add_f32 v[16:17], v[14:15], v[12:13]
	s_mov_b32 s14, 0x3e800000
	v_lshlrev_b32_e32 v14, 16, v9
	v_and_b32_e32 v15, 0xffff0000, v9
	v_lshlrev_b32_e32 v8, 16, v10
	v_and_b32_e32 v9, 0xffff0000, v10
	v_lshlrev_b32_e32 v10, 16, v11
	v_and_b32_e32 v11, 0xffff0000, v11
	v_pk_fma_f32 v[28:29], v[16:17], s[14:15], v[12:13] op_sel_hi:[1,0,1] neg_lo:[0,0,1] neg_hi:[0,0,1]
	v_pk_add_f32 v[18:19], v[18:19], v[14:15]
	v_pk_add_f32 v[20:21], v[20:21], v[8:9]
	v_pk_add_f32 v[22:23], v[22:23], v[10:11]
	v_pk_fma_f32 v[32:33], v[18:19], s[14:15], v[14:15] op_sel_hi:[1,0,1] neg_lo:[0,0,1] neg_hi:[0,0,1]
	v_pk_fma_f32 v[34:35], v[20:21], s[14:15], v[8:9] op_sel_hi:[1,0,1] neg_lo:[0,0,1] neg_hi:[0,0,1]
	v_pk_fma_f32 v[48:49], v[22:23], s[14:15], v[10:11] op_sel_hi:[1,0,1] neg_lo:[0,0,1] neg_hi:[0,0,1]
	v_cvt_pk_bf16_f32 v30, v28, v29
	v_add_u32_e32 v28, 0x410, v56
	v_cmp_lt_u32_e32 vcc, 48, v73
	v_cvt_pk_bf16_f32 v31, v32, v33
	v_cvt_pk_bf16_f32 v32, v34, v35
	v_cvt_pk_bf16_f32 v33, v48, v49
	v_lshl_add_u32 v29, v28, 1, 0
	s_and_b64 s[14:15], s[18:19], vcc
	ds_write_b128 v29, v[30:33]
	s_and_saveexec_b64 s[24:25], s[14:15]
	s_cbranch_execz .LBB0_1539
	v_mov_b32_e32 v29, v161
	s_lshl_b32 s14, s16, 2
	v_add_u32_e32 v29, 0, v29
	v_add_u32_e32 v29, 0x201c8, v29
	s_nop 0
	v_subrev_u32_e32 v32, 44, v113
	v_mov_b32_e32 v33, v161
	s_waitcnt lgkmcnt(0)
	v_readlane_b32 s21, v251, 50
	v_readlane_b32 s15, v251, 51
	s_add_u32 s14, s21, s14
	v_lshl_add_u64 v[30:31], s[6:7], 0, v[32:33]
	s_addc_u32 s15, s15, 0
	v_lshlrev_b64 v[30:31], 11, v[30:31]
	v_lshl_add_u64 v[30:31], s[14:15], 0, v[30:31]
	v_lshl_add_u64 v[30:31], v[30:31], 0, v[160:161]
	global_store_dwordx4 v[30:31], v[12:15], off offset:512
	global_store_dwordx4 v[30:31], v[8:11], off offset:528
.LBB0_1539:
	s_or_b64 exec, exec, s[24:25]
	s_nop 0
	v_pk_add_f32 v[10:11], v[16:17], v[36:37] neg_lo:[0,1] neg_hi:[0,1]
	s_waitcnt vmcnt(1)
	v_lshlrev_b32_e32 v8, 16, v4
	v_and_b32_e32 v9, 0xffff0000, v4
	v_pk_add_f32 v[14:15], v[18:19], v[38:39] neg_lo:[0,1] neg_hi:[0,1]
	v_pk_add_f32 v[16:17], v[20:21], v[40:41] neg_lo:[0,1] neg_hi:[0,1]
	v_pk_add_f32 v[18:19], v[22:23], v[42:43] neg_lo:[0,1] neg_hi:[0,1]
	v_pk_add_f32 v[12:13], v[10:11], v[8:9]
	s_mov_b32 s14, 0x3e800000
	v_lshlrev_b32_e32 v10, 16, v5
	v_and_b32_e32 v11, 0xffff0000, v5
	v_lshlrev_b32_e32 v4, 16, v6
	v_and_b32_e32 v5, 0xffff0000, v6
	v_lshlrev_b32_e32 v6, 16, v7
	v_and_b32_e32 v7, 0xffff0000, v7
	v_pk_fma_f32 v[20:21], v[12:13], s[14:15], v[8:9] op_sel_hi:[1,0,1] neg_lo:[0,0,1] neg_hi:[0,0,1]
	v_pk_add_f32 v[14:15], v[14:15], v[10:11]
	v_pk_add_f32 v[16:17], v[16:17], v[4:5]
	v_pk_add_f32 v[18:19], v[18:19], v[6:7]
	v_pk_fma_f32 v[22:23], v[14:15], s[14:15], v[10:11] op_sel_hi:[1,0,1] neg_lo:[0,0,1] neg_hi:[0,0,1]
	v_pk_fma_f32 v[32:33], v[16:17], s[14:15], v[4:5] op_sel_hi:[1,0,1] neg_lo:[0,0,1] neg_hi:[0,0,1]
	v_pk_fma_f32 v[34:35], v[18:19], s[14:15], v[6:7] op_sel_hi:[1,0,1] neg_lo:[0,0,1] neg_hi:[0,0,1]
	v_cvt_pk_bf16_f32 v30, v20, v21
	v_add_u32_e32 v20, 0x208, v28
	v_cmp_lt_u32_e32 vcc, 48, v72
	v_cvt_pk_bf16_f32 v31, v22, v23
	v_cvt_pk_bf16_f32 v32, v32, v33
	v_cvt_pk_bf16_f32 v33, v34, v35
	v_lshl_add_u32 v20, v20, 1, 0
	s_and_b64 s[14:15], s[18:19], vcc
	ds_write_b128 v20, v[30:33]
	s_and_saveexec_b64 s[24:25], s[14:15]
	s_cbranch_execz .LBB0_1541
	v_mov_b32_e32 v21, v161
	s_lshl_b32 s14, s16, 2
	v_add_u32_e32 v21, 0, v21
	v_add_u32_e32 v21, 0x201c8, v21
	s_nop 0
	v_subrev_u32_e32 v28, 43, v113
	v_mov_b32_e32 v29, v161
	s_waitcnt lgkmcnt(0)
	v_readlane_b32 s21, v251, 50
	v_readlane_b32 s15, v251, 51
	s_add_u32 s14, s21, s14
	v_lshl_add_u64 v[22:23], s[6:7], 0, v[28:29]
	s_addc_u32 s15, s15, 0
	v_lshlrev_b64 v[22:23], 11, v[22:23]
	v_lshl_add_u64 v[22:23], s[14:15], 0, v[22:23]
	v_lshl_add_u64 v[22:23], v[22:23], 0, v[160:161]
	global_store_dwordx4 v[22:23], v[8:11], off offset:512
	global_store_dwordx4 v[22:23], v[4:7], off offset:528
.LBB0_1541:
	s_or_b64 exec, exec, s[24:25]
	s_nop 0
	v_pk_add_f32 v[6:7], v[14:15], v[46:47] neg_lo:[0,1] neg_hi:[0,1]
	s_waitcnt vmcnt(0)
	v_lshlrev_b32_e32 v10, 16, v1
	v_and_b32_e32 v11, 0xffff0000, v1
	v_lshlrev_b32_e32 v8, 16, v0
	v_and_b32_e32 v9, 0xffff0000, v0
	s_mov_b32 s14, 0x3e800000
	v_pk_add_f32 v[0:1], v[6:7], v[10:11]
	v_pk_add_f32 v[4:5], v[12:13], v[44:45] neg_lo:[0,1] neg_hi:[0,1]
	v_pk_add_f32 v[12:13], v[16:17], v[24:25] neg_lo:[0,1] neg_hi:[0,1]
	v_pk_add_f32 v[14:15], v[18:19], v[26:27] neg_lo:[0,1] neg_hi:[0,1]
	v_pk_fma_f32 v[6:7], v[0:1], s[14:15], v[10:11] op_sel_hi:[1,0,1] neg_lo:[0,0,1] neg_hi:[0,0,1]
	v_lshlrev_b32_e32 v0, 16, v2
	v_and_b32_e32 v1, 0xffff0000, v2
	v_lshlrev_b32_e32 v2, 16, v3
	v_and_b32_e32 v3, 0xffff0000, v3
	v_pk_add_f32 v[4:5], v[4:5], v[8:9]
	v_pk_add_f32 v[12:13], v[12:13], v[0:1]
	v_pk_add_f32 v[14:15], v[14:15], v[2:3]
	v_pk_fma_f32 v[4:5], v[4:5], s[14:15], v[8:9] op_sel_hi:[1,0,1] neg_lo:[0,0,1] neg_hi:[0,0,1]
	v_pk_fma_f32 v[12:13], v[12:13], s[14:15], v[0:1] op_sel_hi:[1,0,1] neg_lo:[0,0,1] neg_hi:[0,0,1]
	v_pk_fma_f32 v[14:15], v[14:15], s[14:15], v[2:3] op_sel_hi:[1,0,1] neg_lo:[0,0,1] neg_hi:[0,0,1]
	v_cmp_lt_u32_e32 vcc, 48, v71
	v_cvt_pk_bf16_f32 v4, v4, v5
	v_cvt_pk_bf16_f32 v5, v6, v7
	v_cvt_pk_bf16_f32 v6, v12, v13
	v_cvt_pk_bf16_f32 v7, v14, v15
	s_and_b64 s[14:15], s[18:19], vcc
	ds_write_b128 v20, v[4:7] offset:1040
	s_and_saveexec_b64 s[24:25], s[14:15]
	s_xor_b64 s[24:25], exec, s[24:25]
	s_cbranch_execz .LBB0_1543
	v_mov_b32_e32 v4, v161
	s_or_b64 s[10:11], s[10:11], exec
	v_add_u32_e32 v4, 0, v4
	v_add_u32_e32 v4, 0x201c8, v4
	s_nop 0
	s_waitcnt lgkmcnt(0)
	v_readlane_b32 s19, v251, 51
	v_readlane_b32 s18, v251, 50

; __device__ __forceinline__ unsigned pk2(float lo, float hi) { f32x2 v = {lo, hi}; bf16x2_t b = __builtin_convertvector(v, bf16x2_t); return __builtin_bit_cast(unsigned, b); }
; __device__ __forceinline__ void unpack8(u32x4 w, float* v) { v[0] = bflo(w.x); v[1] = bfhi(w.x); v[2] = bflo(w.y); v[3] = bfhi(w.y); v[4] = bflo(w.z); v[5] = bfhi(w.z); v[6] = bflo(w.w); v[7] = bfhi(w.w); }
; template <int W> __device__ __forceinline__ void pool_stage(const Params& p, const bf16_t* z, int layer, bool is_s, int b, int c, int tok0, int g, int half, int lane, LAS unsigned char* L) {
;     ...
;     for (int j = 0; j < W + 7; ++j) {
;         const int t = t0 - (W - 1) + j;
;         u32x4 r = {0u, 0u, 0u, 0u};
;         if (t >= 0 || (!is_s && c * 64 + t >= 0)) r = *(const u32x4*)(z + (size_t)(tok0 + t) * NIN + 768 + c0);
;         else if (is_s) { const f32x4 a = *(const f32x4*)(sp + (15 + t) * 512), bb = *(const f32x4*)(sp + (15 + t) * 512 + 4); r.x = pk2(a[0], a[1]); r.y = pk2(a[2], a[3]); r.z = pk2(bb[0], bb[1]); r.w = pk2(bb[2], bb[3]); }
;         raw[j] = r;
;     }
;     float sum[8];
; #pragma unroll
;     for (int i = 0; i < 8; ++i) sum[i] = 0.f;
; #pragma unroll
;     for (int j = 0; j < W - 1; ++j) { float u[8]; unpack8(raw[j], u);
; #pragma unroll
;         for (int i = 0; i < 8; ++i) sum[i] += u[i]; }
; #pragma unroll
;     for (int ti = 0; ti < 8; ++ti) {
;         const int t = t0 + ti; float u[8], ul[8], d[8]; unpack8(raw[W - 1 + ti], u); unpack8(raw[ti], ul);
;         const int cnt = is_s ? W : min(c * 64 + t + 1, W); const float rc = 1.0f / (float)cnt;
; #pragma unroll
;         for (int i = 0; i < 8; ++i) { sum[i] += u[i]; d[i] = sum[i] * rc - u[i]; sum[i] -= ul[i]; }
.LBB0_1604:
	s_or_b64 exec, exec, s[6:7]
	v_add_u32_e32 v5, s67, v113
	v_mov_b64_e32 v[6:7], s[34:35]
	v_or_b32_e32 v107, 1, v113
	v_or_b32_e32 v92, 0x100, v12
	v_mad_i64_i32 v[12:13], s[6:7], v5, s84, v[6:7]
	v_mov_b32_e32 v5, v161
	v_add_u32_e32 v14, s67, v107
	v_lshl_add_u64 v[12:13], v[12:13], 0, v[4:5]
	v_mad_i64_i32 v[14:15], s[6:7], v14, s84, v[6:7]
	v_lshl_add_u64 v[14:15], v[14:15], 0, v[4:5]
	global_load_dwordx4 v[108:111], v[12:13], off offset:2048
	global_load_dwordx4 v[44:47], v[14:15], off offset:2048
	v_or_b32_e32 v106, 2, v113
	v_or_b32_e32 v105, 3, v113
	v_add_u32_e32 v12, s67, v106
	v_add_u32_e32 v14, s67, v105
	v_mad_i64_i32 v[12:13], s[6:7], v12, s84, v[6:7]
	v_mad_i64_i32 v[14:15], s[6:7], v14, s84, v[6:7]
	v_lshl_add_u64 v[12:13], v[12:13], 0, v[4:5]
	v_lshl_add_u64 v[14:15], v[14:15], 0, v[4:5]
	v_or_b32_e32 v104, 4, v113
	v_or_b32_e32 v103, 5, v113
	global_load_dwordx4 v[36:39], v[12:13], off offset:2048
	global_load_dwordx4 v[28:31], v[14:15], off offset:2048
	v_add_u32_e32 v12, s67, v104
	v_add_u32_e32 v14, s67, v103
	v_mad_i64_i32 v[12:13], s[6:7], v12, s84, v[6:7]
	v_mad_i64_i32 v[14:15], s[6:7], v14, s84, v[6:7]
	v_lshl_add_u64 v[12:13], v[12:13], 0, v[4:5]
	v_lshl_add_u64 v[14:15], v[14:15], 0, v[4:5]
	v_or_b32_e32 v102, 6, v113
	v_or_b32_e32 v93, 7, v113
	global_load_dwordx4 v[24:27], v[12:13], off offset:2048
	global_load_dwordx4 v[20:23], v[14:15], off offset:2048
	v_add_u32_e32 v12, s67, v102
	v_add_u32_e32 v14, s67, v93
	v_mad_i64_i32 v[12:13], s[6:7], v12, s84, v[6:7]
	v_mad_i64_i32 v[6:7], s[6:7], v14, s84, v[6:7]
	v_lshl_add_u64 v[12:13], v[12:13], 0, v[4:5]
	v_lshl_add_u64 v[4:5], v[6:7], 0, v[4:5]
	global_load_dwordx4 v[12:15], v[12:13], off offset:2048
	s_nop 0
	global_load_dwordx4 v[4:7], v[4:5], off offset:2048
	s_waitcnt vmcnt(8)
	v_lshlrev_b32_e32 v70, 16, v32
	v_and_b32_e32 v71, 0xffff0000, v32
	v_or_b32_e32 v32, s77, v113
	v_min_u32_e32 v32, 7, v32
	v_add_u32_e32 v32, 1, v32
	v_cvt_f32_ubyte0_e32 v32, v32
	v_lshlrev_b32_e32 v72, 16, v33
	v_and_b32_e32 v73, 0xffff0000, v33
	v_div_scale_f32 v33, s[14:15], v32, v32, 1.0
	v_lshlrev_b32_e32 v74, 16, v34
	v_and_b32_e32 v75, 0xffff0000, v34
	v_rcp_f32_e32 v34, v33
	v_lshlrev_b32_e32 v76, 16, v35
	v_and_b32_e32 v77, 0xffff0000, v35
	v_lshlrev_b32_e32 v58, 16, v48
	v_fma_f32 v35, -v33, v34, 1.0
	v_fmac_f32_e32 v34, v35, v34
	v_div_scale_f32 v35, vcc, 1.0, v32, 1.0
	v_and_b32_e32 v59, 0xffff0000, v48
	v_lshlrev_b32_e32 v60, 16, v49
	v_and_b32_e32 v61, 0xffff0000, v49
	v_lshlrev_b32_e32 v48, 16, v54
	v_and_b32_e32 v49, 0xffff0000, v54
	v_mul_f32_e32 v54, v35, v34
	v_lshlrev_b32_e32 v66, 16, v42
	v_and_b32_e32 v67, 0xffff0000, v42
	v_lshlrev_b32_e32 v68, 16, v43
	v_and_b32_e32 v69, 0xffff0000, v43
	v_lshlrev_b32_e32 v42, 16, v55
	v_and_b32_e32 v43, 0xffff0000, v55
	v_fma_f32 v55, -v33, v54, v35
	v_fmac_f32_e32 v54, v55, v34
	v_fma_f32 v33, -v33, v54, v35
	v_div_fmas_f32 v33, v33, v34, v54
	v_div_fixup_f32 v32, v33, v32, 1.0
	v_lshlrev_b32_e32 v88, 16, v0
	v_and_b32_e32 v89, 0xffff0000, v0
	v_cndmask_b32_e64 v114, v32, v200, s[4:5]
	v_lshlrev_b32_e32 v80, 16, v8
	v_and_b32_e32 v81, 0xffff0000, v8
	v_pk_add_f32 v[32:33], v[88:89], 0 op_sel_hi:[1,0]
	v_lshlrev_b32_e32 v90, 16, v1
	v_and_b32_e32 v91, 0xffff0000, v1
	v_pk_add_f32 v[32:33], v[32:33], v[80:81]
	v_lshlrev_b32_e32 v54, 16, v16
	v_and_b32_e32 v55, 0xffff0000, v16
	v_lshlrev_b32_e32 v82, 16, v9
	v_and_b32_e32 v83, 0xffff0000, v9
	v_pk_add_f32 v[0:1], v[90:91], 0 op_sel_hi:[1,0]
	v_pk_add_f32 v[32:33], v[32:33], v[54:55]
	v_pk_add_f32 v[0:1], v[0:1], v[82:83]
	v_lshlrev_b32_e32 v16, 16, v17
	v_and_b32_e32 v17, 0xffff0000, v17
	v_lshlrev_b32_e32 v62, 16, v40
	v_and_b32_e32 v63, 0xffff0000, v40
	v_pk_add_f32 v[32:33], v[32:33], v[70:71]
	v_pk_add_f32 v[0:1], v[0:1], v[16:17]
	v_lshlrev_b32_e32 v64, 16, v41
	v_and_b32_e32 v65, 0xffff0000, v41
	v_pk_add_f32 v[32:33], v[32:33], v[62:63]
	v_pk_add_f32 v[0:1], v[0:1], v[72:73]
	v_lshlrev_b32_e32 v56, 16, v52
	v_and_b32_e32 v57, 0xffff0000, v52
	v_pk_add_f32 v[32:33], v[32:33], v[58:59]
	v_pk_add_f32 v[0:1], v[0:1], v[64:65]
	v_lshlrev_b32_e32 v40, 16, v53
	v_and_b32_e32 v41, 0xffff0000, v53
	v_pk_add_f32 v[34:35], v[32:33], v[56:57]
	s_waitcnt vmcnt(7)
	v_lshlrev_b32_e32 v32, 16, v108
	v_and_b32_e32 v33, 0xffff0000, v108
	v_pk_add_f32 v[0:1], v[0:1], v[60:61]
	v_pk_add_f32 v[94:95], v[34:35], v[32:33]
	v_pk_add_f32 v[0:1], v[0:1], v[40:41]
	v_lshlrev_b32_e32 v34, 16, v109
	v_and_b32_e32 v35, 0xffff0000, v109
	v_lshlrev_b32_e32 v96, 16, v2
	v_and_b32_e32 v97, 0xffff0000, v2
	v_pk_add_f32 v[8:9], v[0:1], v[34:35]
	v_lshlrev_b32_e32 v84, 16, v10
	v_and_b32_e32 v85, 0xffff0000, v10
	v_pk_add_f32 v[0:1], v[96:97], 0 op_sel_hi:[1,0]
	v_lshlrev_b32_e32 v78, 16, v18
	v_pk_add_f32 v[0:1], v[0:1], v[84:85]
	v_and_b32_e32 v79, 0xffff0000, v18
	v_pk_add_f32 v[0:1], v[0:1], v[78:79]
	v_lshlrev_b32_e32 v52, 16, v50
	v_pk_add_f32 v[0:1], v[0:1], v[74:75]
	v_and_b32_e32 v53, 0xffff0000, v50
	v_pk_add_f32 v[0:1], v[0:1], v[66:67]
	v_lshlrev_b32_e32 v100, 16, v3
	v_pk_add_f32 v[0:1], v[0:1], v[52:53]
	v_and_b32_e32 v101, 0xffff0000, v3
	v_pk_add_f32 v[86:87], v[0:1], v[48:49]
	v_lshlrev_b32_e32 v0, 16, v110
	v_and_b32_e32 v1, 0xffff0000, v110
	s_mul_i32 s6, s43, 15
	s_mul_hi_u32 s7, s42, 15
	v_pk_add_f32 v[98:99], v[86:87], v[0:1]
	v_lshlrev_b32_e32 v86, 16, v11
	v_and_b32_e32 v87, 0xffff0000, v11
	v_pk_add_f32 v[2:3], v[100:101], 0 op_sel_hi:[1,0]
	s_add_i32 s7, s7, s6
	v_pk_add_f32 v[2:3], v[2:3], v[86:87]
	v_lshlrev_b32_e32 v18, 16, v19
	v_and_b32_e32 v19, 0xffff0000, v19
	s_cmp_eq_u32 s76, 31
	v_pk_add_f32 v[2:3], v[2:3], v[18:19]
	s_cselect_b64 s[10:11], -1, 0
	v_pk_add_f32 v[2:3], v[2:3], v[76:77]
	v_lshlrev_b32_e32 v50, 16, v51
	v_and_b32_e32 v51, 0xffff0000, v51
	s_or_b64 s[10:11], s[4:5], s[10:11]
	v_pk_add_f32 v[2:3], v[2:3], v[68:69]
	s_and_b64 s[14:15], s[4:5], exec
	v_pk_add_f32 v[2:3], v[2:3], v[50:51]
	s_mov_b32 s14, 0x4678000
	v_pk_add_f32 v[10:11], v[2:3], v[42:43]
	v_lshlrev_b32_e32 v2, 16, v111
	v_and_b32_e32 v3, 0xffff0000, v111
	s_cselect_b32 s16, s14, 0x4400000
	v_pk_fma_f32 v[108:109], v[114:115], v[8:9], v[34:35] op_sel_hi:[0,1,1] neg_lo:[0,0,1] neg_hi:[0,0,1]
	v_pk_add_f32 v[10:11], v[10:11], v[2:3]
	s_movk_i32 s14, 0x208
	v_pk_fma_f32 v[116:117], v[114:115], v[94:95], v[32:33] op_sel_hi:[0,1,1] neg_lo:[0,0,1] neg_hi:[0,0,1]
	v_pk_fma_f32 v[118:119], v[114:115], v[98:99], v[0:1] op_sel_hi:[0,1,1] neg_lo:[0,0,1] neg_hi:[0,0,1]
	v_pk_fma_f32 v[110:111], v[114:115], v[10:11], v[2:3] op_sel_hi:[0,1,1] neg_lo:[0,0,1] neg_hi:[0,0,1]
	v_cvt_pk_bf16_f32 v115, v108, v109
	v_mad_u32_u24 v108, v113, s14, v92
	v_cmp_lt_u32_e32 vcc, 48, v113
	s_mul_i32 s6, s42, 15
	v_cvt_pk_bf16_f32 v114, v116, v117
	v_cvt_pk_bf16_f32 v116, v118, v119
	v_cvt_pk_bf16_f32 v117, v110, v111
	v_lshl_add_u32 v109, v108, 1, 0
	s_and_b64 s[14:15], s[10:11], vcc
	ds_write_b128 v109, v[114:117]
	s_and_saveexec_b64 s[24:25], s[14:15]
	s_cbranch_execz .LBB0_1606
; #define LAS __attribute__((address_space(3)))
; __device__ __forceinline__ bf16x8 pack8(const float* v) { u32x4 w; w.x = pk2(v[0], v[1]); w.y = pk2(v[2], v[3]); w.z = pk2(v[4], v[5]); w.w = pk2(v[6], v[7]); return __builtin_bit_cast(bf16x8, w); }
; __device__ __forceinline__ void unpack8(u32x4 w, float* v) { v[0] = bflo(w.x); v[1] = bfhi(w.x); v[2] = bflo(w.y); v[3] = bfhi(w.y); v[4] = bflo(w.z); v[5] = bfhi(w.z); v[6] = bflo(w.w); v[7] = bfhi(w.w); }
; template <int W> __device__ __forceinline__ void pool_stage(const Params& p, const bf16_t* z, int layer, bool is_s, int b, int c, int tok0, int g, int half, int lane, LAS unsigned char* L) {
;     ...
;     for (int ti = 0; ti < 8; ++ti) {
;         const int t = t0 + ti; float u[8], ul[8], d[8]; unpack8(raw[W - 1 + ti], u); unpack8(raw[ti], ul);
;         const int cnt = is_s ? W : min(c * 64 + t + 1, W); const float rc = 1.0f / (float)cnt;
; #pragma unroll
;         for (int i = 0; i < 8; ++i) { sum[i] += u[i]; d[i] = sum[i] * rc - u[i]; sum[i] -= ul[i]; }
;         *(LAS bf16x8*)(L + (t * DROW + c0) * 2) = pack8(d);
;         if (t >= 49 && (is_s || c == 31)) { float* o = POUT + (is_s ? O_US : O_UP) + (((size_t)layer * NB + b) * 15 + (t - 49)) * 512 + c0;
;             *(f32x4*)o = (f32x4){u[0], u[1], u[2], u[3]}; *(f32x4*)(o + 4) = (f32x4){u[4], u[5], u[6], u[7]}; }
	v_mov_b32_e32 v109, v161
	s_lshl_b32 s14, s16, 2
	v_add_u32_e32 v109, 0, v109
	v_add_u32_e32 v109, 0x201c8, v109
	s_nop 0
	v_subrev_u32_e32 v114, 49, v113
	v_mov_b32_e32 v115, v161
	s_waitcnt lgkmcnt(0)
	v_readlane_b32 s21, v251, 50
	v_readlane_b32 s15, v251, 51
	s_add_u32 s14, s21, s14
	v_lshl_add_u64 v[110:111], s[6:7], 0, v[114:115]
	s_addc_u32 s15, s15, 0
	v_lshlrev_b64 v[110:111], 11, v[110:111]
	v_lshl_add_u64 v[110:111], s[14:15], 0, v[110:111]
	v_lshl_add_u64 v[110:111], v[110:111], 0, v[160:161]
	global_store_dwordx4 v[110:111], v[32:35], off offset:1024
	global_store_dwordx4 v[110:111], v[0:3], off offset:1040
.LBB0_1606:
	s_or_b64 exec, exec, s[24:25]
	s_nop 0
	v_or_b32_e32 v0, s77, v107
	v_min_u32_e32 v0, 7, v0
	v_add_u32_e32 v0, 1, v0
	v_cvt_f32_ubyte0_e32 v0, v0
	v_div_scale_f32 v1, s[14:15], v0, v0, 1.0
	v_rcp_f32_e32 v32, v1
	v_pk_add_f32 v[8:9], v[8:9], v[90:91] neg_lo:[0,1] neg_hi:[0,1]
	v_pk_add_f32 v[90:91], v[10:11], v[100:101] neg_lo:[0,1] neg_hi:[0,1]
	v_pk_add_f32 v[2:3], v[94:95], v[88:89] neg_lo:[0,1] neg_hi:[0,1]
	v_fma_f32 v10, -v1, v32, 1.0
	v_fmac_f32_e32 v32, v10, v32
	v_div_scale_f32 v10, vcc, 1.0, v0, 1.0
	v_mul_f32_e32 v11, v10, v32
	v_fma_f32 v33, -v1, v11, v10
	v_fmac_f32_e32 v11, v33, v32
	v_fma_f32 v1, -v1, v11, v10
	v_div_fmas_f32 v1, v1, v32, v11
	v_div_fixup_f32 v0, v1, v0, 1.0
	v_cndmask_b32_e64 v94, v0, v200, s[4:5]
	s_waitcnt vmcnt(6)
	v_lshlrev_b32_e32 v0, 16, v44
	v_and_b32_e32 v1, 0xffff0000, v44
	v_pk_add_f32 v[34:35], v[2:3], v[0:1]
	v_lshlrev_b32_e32 v2, 16, v45
	v_and_b32_e32 v3, 0xffff0000, v45
	v_pk_add_f32 v[88:89], v[98:99], v[96:97] neg_lo:[0,1] neg_hi:[0,1]
	v_pk_add_f32 v[32:33], v[8:9], v[2:3]
	v_lshlrev_b32_e32 v8, 16, v46
	v_and_b32_e32 v9, 0xffff0000, v46
	v_pk_add_f32 v[44:45], v[88:89], v[8:9]
	v_lshlrev_b32_e32 v10, 16, v47
	v_and_b32_e32 v11, 0xffff0000, v47
	v_pk_fma_f32 v[96:97], v[94:95], v[34:35], v[0:1] op_sel_hi:[0,1,1] neg_lo:[0,0,1] neg_hi:[0,0,1]
	v_pk_fma_f32 v[88:89], v[94:95], v[44:45], v[8:9] op_sel_hi:[0,1,1] neg_lo:[0,0,1] neg_hi:[0,0,1]
	v_pk_add_f32 v[46:47], v[90:91], v[10:11]
	v_pk_fma_f32 v[98:99], v[94:95], v[32:33], v[2:3] op_sel_hi:[0,1,1] neg_lo:[0,0,1] neg_hi:[0,0,1]
	v_pk_fma_f32 v[90:91], v[94:95], v[46:47], v[10:11] op_sel_hi:[0,1,1] neg_lo:[0,0,1] neg_hi:[0,0,1]
	v_cvt_pk_bf16_f32 v94, v96, v97
	v_cvt_pk_bf16_f32 v96, v88, v89
	v_add_u32_e32 v88, 0x208, v108
	v_cmp_lt_u32_e32 vcc, 47, v113
	v_cvt_pk_bf16_f32 v95, v98, v99
	v_cvt_pk_bf16_f32 v97, v90, v91
	v_lshl_add_u32 v89, v88, 1, 0
	s_and_b64 s[48:49], s[10:11], vcc
	ds_write_b128 v89, v[94:97]
	s_and_saveexec_b64 s[24:25], s[48:49]
	s_cbranch_execz .LBB0_1608
	v_mov_b32_e32 v89, v161
	s_lshl_b32 s14, s16, 2
	v_add_u32_e32 v89, 0, v89
	v_add_u32_e32 v89, 0x201c8, v89
	s_nop 0
	v_subrev_u32_e32 v94, 48, v113
	v_mov_b32_e32 v95, v161
	s_waitcnt lgkmcnt(0)
	v_readlane_b32 s21, v251, 50
	v_readlane_b32 s15, v251, 51
	s_add_u32 s14, s21, s14
	v_lshl_add_u64 v[90:91], s[6:7], 0, v[94:95]
	s_addc_u32 s15, s15, 0
	v_lshlrev_b64 v[90:91], 11, v[90:91]
	v_lshl_add_u64 v[90:91], s[14:15], 0, v[90:91]
	v_lshl_add_u64 v[90:91], v[90:91], 0, v[160:161]
	global_store_dwordx4 v[90:91], v[0:3], off offset:1024
	global_store_dwordx4 v[90:91], v[8:11], off offset:1040
.LBB0_1608:
	s_or_b64 exec, exec, s[24:25]
	v_or_b32_e32 v0, s77, v106
	v_min_u32_e32 v0, 7, v0
	v_add_u32_e32 v0, 1, v0
	v_cvt_f32_ubyte0_e32 v0, v0
	v_div_scale_f32 v1, s[14:15], v0, v0, 1.0
	v_pk_add_f32 v[2:3], v[34:35], v[80:81] neg_lo:[0,1] neg_hi:[0,1]
	v_rcp_f32_e32 v34, v1
	v_pk_add_f32 v[8:9], v[32:33], v[82:83] neg_lo:[0,1] neg_hi:[0,1]
	v_pk_add_f32 v[10:11], v[44:45], v[84:85] neg_lo:[0,1] neg_hi:[0,1]
	v_pk_add_f32 v[44:45], v[46:47], v[86:87] neg_lo:[0,1] neg_hi:[0,1]
	v_fma_f32 v32, -v1, v34, 1.0
	v_fmac_f32_e32 v34, v32, v34
	v_div_scale_f32 v32, vcc, 1.0, v0, 1.0
	v_mul_f32_e32 v33, v32, v34
	v_fma_f32 v35, -v1, v33, v32
	v_fmac_f32_e32 v33, v35, v34
	v_fma_f32 v1, -v1, v33, v32
	v_div_fmas_f32 v1, v1, v34, v33
	v_div_fixup_f32 v0, v1, v0, 1.0
	v_cndmask_b32_e64 v46, v0, v200, s[4:5]
	s_waitcnt vmcnt(5)
	v_lshlrev_b32_e32 v0, 16, v36
	v_and_b32_e32 v1, 0xffff0000, v36
	v_pk_add_f32 v[34:35], v[2:3], v[0:1]
	v_lshlrev_b32_e32 v2, 16, v37
	v_and_b32_e32 v3, 0xffff0000, v37
	v_pk_add_f32 v[32:33], v[8:9], v[2:3]
	v_lshlrev_b32_e32 v8, 16, v38
	v_and_b32_e32 v9, 0xffff0000, v38
	v_pk_add_f32 v[36:37], v[10:11], v[8:9]
	v_lshlrev_b32_e32 v10, 16, v39
	v_and_b32_e32 v11, 0xffff0000, v39
	v_pk_add_f32 v[38:39], v[44:45], v[10:11]
	v_pk_fma_f32 v[80:81], v[46:47], v[34:35], v[0:1] op_sel_hi:[0,1,1] neg_lo:[0,0,1] neg_hi:[0,0,1]
	v_pk_fma_f32 v[82:83], v[46:47], v[32:33], v[2:3] op_sel_hi:[0,1,1] neg_lo:[0,0,1] neg_hi:[0,0,1]
	v_pk_fma_f32 v[44:45], v[46:47], v[38:39], v[10:11] op_sel_hi:[0,1,1] neg_lo:[0,0,1] neg_hi:[0,0,1]
	v_pk_fma_f32 v[84:85], v[46:47], v[36:37], v[8:9] op_sel_hi:[0,1,1] neg_lo:[0,0,1] neg_hi:[0,0,1]
	v_cvt_pk_bf16_f32 v80, v80, v81
	v_cvt_pk_bf16_f32 v81, v82, v83
	v_cvt_pk_bf16_f32 v83, v44, v45
	v_add_u32_e32 v44, 0x208, v88
	v_cvt_pk_bf16_f32 v82, v84, v85
	v_lshl_add_u32 v45, v44, 1, 0
	ds_write_b128 v45, v[80:83]
	s_and_saveexec_b64 s[24:25], s[48:49]
	s_cbranch_execz .LBB0_1610
	v_mov_b32_e32 v45, v161
	s_lshl_b32 s14, s16, 2
	v_add_u32_e32 v45, 0, v45
	v_add_u32_e32 v45, 0x201c8, v45
	s_nop 0
	v_subrev_u32_e32 v80, 47, v113
	v_mov_b32_e32 v81, v161
	s_waitcnt lgkmcnt(0)
	v_readlane_b32 s21, v251, 50
	v_readlane_b32 s15, v251, 51
	s_add_u32 s14, s21, s14
	v_lshl_add_u64 v[46:47], s[6:7], 0, v[80:81]
	s_addc_u32 s15, s15, 0
	v_lshlrev_b64 v[46:47], 11, v[46:47]
	v_lshl_add_u64 v[46:47], s[14:15], 0, v[46:47]
	v_lshl_add_u64 v[46:47], v[46:47], 0, v[160:161]
	global_store_dwordx4 v[46:47], v[0:3], off offset:1024
	global_store_dwordx4 v[46:47], v[8:11], off offset:1040
; #define LAS __attribute__((address_space(3)))
; __device__ __forceinline__ bf16x8 pack8(const float* v) { u32x4 w; w.x = pk2(v[0], v[1]); w.y = pk2(v[2], v[3]); w.z = pk2(v[4], v[5]); w.w = pk2(v[6], v[7]); return __builtin_bit_cast(bf16x8, w); }
; __device__ __forceinline__ void unpack8(u32x4 w, float* v) { v[0] = bflo(w.x); v[1] = bfhi(w.x); v[2] = bflo(w.y); v[3] = bfhi(w.y); v[4] = bflo(w.z); v[5] = bfhi(w.z); v[6] = bflo(w.w); v[7] = bfhi(w.w); }
; template <int W> __device__ __forceinline__ void pool_stage(const Params& p, const bf16_t* z, int layer, bool is_s, int b, int c, int tok0, int g, int half, int lane, LAS unsigned char* L) {
;     ...
;     for (int ti = 0; ti < 8; ++ti) {
;         const int t = t0 + ti; float u[8], ul[8], d[8]; unpack8(raw[W - 1 + ti], u); unpack8(raw[ti], ul);
;         const int cnt = is_s ? W : min(c * 64 + t + 1, W); const float rc = 1.0f / (float)cnt;
; #pragma unroll
;         for (int i = 0; i < 8; ++i) { sum[i] += u[i]; d[i] = sum[i] * rc - u[i]; sum[i] -= ul[i]; }
;         *(LAS bf16x8*)(L + (t * DROW + c0) * 2) = pack8(d);
;         if (t >= 49 && (is_s || c == 31)) { float* o = POUT + (is_s ? O_US : O_UP) + (((size_t)layer * NB + b) * 15 + (t - 49)) * 512 + c0;
;             *(f32x4*)o = (f32x4){u[0], u[1], u[2], u[3]}; *(f32x4*)(o + 4) = (f32x4){u[4], u[5], u[6], u[7]}; }
.LBB0_1610:
	s_or_b64 exec, exec, s[24:25]
	v_or_b32_e32 v0, s77, v105
	v_min_u32_e32 v0, 7, v0
	v_add_u32_e32 v0, 1, v0
	v_cvt_f32_ubyte0_e32 v0, v0
	v_div_scale_f32 v1, s[14:15], v0, v0, 1.0
	v_pk_add_f32 v[2:3], v[34:35], v[54:55] neg_lo:[0,1] neg_hi:[0,1]
	v_rcp_f32_e32 v34, v1
	v_pk_add_f32 v[8:9], v[32:33], v[16:17] neg_lo:[0,1] neg_hi:[0,1]
	v_pk_add_f32 v[32:33], v[38:39], v[18:19] neg_lo:[0,1] neg_hi:[0,1]
	v_pk_add_f32 v[10:11], v[36:37], v[78:79] neg_lo:[0,1] neg_hi:[0,1]
	v_fma_f32 v16, -v1, v34, 1.0
	v_fmac_f32_e32 v34, v16, v34
	v_div_scale_f32 v16, vcc, 1.0, v0, 1.0
	v_mul_f32_e32 v17, v16, v34
	v_fma_f32 v18, -v1, v17, v16
	v_fmac_f32_e32 v17, v18, v34
	v_fma_f32 v1, -v1, v17, v16
	v_div_fmas_f32 v1, v1, v34, v17
	v_div_fixup_f32 v0, v1, v0, 1.0
	v_cndmask_b32_e64 v34, v0, v200, s[4:5]
	s_waitcnt vmcnt(4)
	v_lshlrev_b32_e32 v0, 16, v28
	v_and_b32_e32 v1, 0xffff0000, v28
	v_pk_add_f32 v[16:17], v[2:3], v[0:1]
	v_lshlrev_b32_e32 v2, 16, v29
	v_and_b32_e32 v3, 0xffff0000, v29
	v_pk_add_f32 v[18:19], v[8:9], v[2:3]
	v_lshlrev_b32_e32 v8, 16, v30
	v_and_b32_e32 v9, 0xffff0000, v30
	v_pk_add_f32 v[28:29], v[10:11], v[8:9]
	v_lshlrev_b32_e32 v10, 16, v31
	v_and_b32_e32 v11, 0xffff0000, v31
	v_pk_add_f32 v[30:31], v[32:33], v[10:11]
	v_pk_fma_f32 v[36:37], v[34:35], v[16:17], v[0:1] op_sel_hi:[0,1,1] neg_lo:[0,0,1] neg_hi:[0,0,1]
	v_pk_fma_f32 v[32:33], v[34:35], v[30:31], v[10:11] op_sel_hi:[0,1,1] neg_lo:[0,0,1] neg_hi:[0,0,1]
	v_pk_fma_f32 v[38:39], v[34:35], v[18:19], v[2:3] op_sel_hi:[0,1,1] neg_lo:[0,0,1] neg_hi:[0,0,1]
	v_pk_fma_f32 v[46:47], v[34:35], v[28:29], v[8:9] op_sel_hi:[0,1,1] neg_lo:[0,0,1] neg_hi:[0,0,1]
	v_cvt_pk_bf16_f32 v34, v36, v37
	v_cvt_pk_bf16_f32 v37, v32, v33
	v_add_u32_e32 v32, 0x208, v44
	v_cmp_lt_u32_e32 vcc, 48, v105
	v_cvt_pk_bf16_f32 v35, v38, v39
	v_cvt_pk_bf16_f32 v36, v46, v47
	v_lshl_add_u32 v33, v32, 1, 0
	s_and_b64 s[14:15], s[10:11], vcc
	ds_write_b128 v33, v[34:37]
	s_and_saveexec_b64 s[24:25], s[14:15]
	s_cbranch_execz .LBB0_1612
	v_mov_b32_e32 v33, v161
	s_lshl_b32 s14, s16, 2
	v_add_u32_e32 v33, 0, v33
	v_add_u32_e32 v33, 0x201c8, v33
	s_nop 0
	v_subrev_u32_e32 v36, 46, v113
	v_mov_b32_e32 v37, v161
	s_waitcnt lgkmcnt(0)
	v_readlane_b32 s21, v251, 50
	v_readlane_b32 s15, v251, 51
	s_add_u32 s14, s21, s14
	v_lshl_add_u64 v[34:35], s[6:7], 0, v[36:37]
	s_addc_u32 s15, s15, 0
	v_lshlrev_b64 v[34:35], 11, v[34:35]
	v_lshl_add_u64 v[34:35], s[14:15], 0, v[34:35]
	v_lshl_add_u64 v[34:35], v[34:35], 0, v[160:161]
	global_store_dwordx4 v[34:35], v[0:3], off offset:1024
	global_store_dwordx4 v[34:35], v[8:11], off offset:1040
.LBB0_1612:
	s_or_b64 exec, exec, s[24:25]
	v_or_b32_e32 v1, s77, v104
	v_min_u32_e32 v1, 7, v1
	v_add_u32_e32 v1, 1, v1
	s_waitcnt vmcnt(3)
	v_lshlrev_b32_e32 v8, 16, v24
	v_and_b32_e32 v9, 0xffff0000, v24
	v_cvt_f32_ubyte0_e32 v24, v1
	v_lshlrev_b32_e32 v10, 16, v25
	v_and_b32_e32 v11, 0xffff0000, v25
	v_div_scale_f32 v25, s[14:15], v24, v24, 1.0
	v_rcp_f32_e32 v33, v25
	v_lshlrev_b32_e32 v0, 16, v26
	v_and_b32_e32 v1, 0xffff0000, v26
	v_lshlrev_b32_e32 v2, 16, v27
	v_fma_f32 v26, -v25, v33, 1.0
	v_fmac_f32_e32 v33, v26, v33
	v_div_scale_f32 v26, vcc, 1.0, v24, 1.0
	v_and_b32_e32 v3, 0xffff0000, v27
	v_mul_f32_e32 v27, v26, v33
	v_fma_f32 v34, -v25, v27, v26
	v_fmac_f32_e32 v27, v34, v33
	v_fma_f32 v25, -v25, v27, v26
	v_div_fmas_f32 v25, v25, v33, v27
	v_pk_add_f32 v[16:17], v[16:17], v[70:71] neg_lo:[0,1] neg_hi:[0,1]
	v_pk_add_f32 v[18:19], v[18:19], v[72:73] neg_lo:[0,1] neg_hi:[0,1]
	v_pk_add_f32 v[28:29], v[28:29], v[74:75] neg_lo:[0,1] neg_hi:[0,1]
	v_div_fixup_f32 v24, v25, v24, 1.0
	v_pk_add_f32 v[30:31], v[30:31], v[76:77] neg_lo:[0,1] neg_hi:[0,1]
	v_cndmask_b32_e64 v34, v24, v200, s[4:5]
	v_pk_add_f32 v[24:25], v[16:17], v[8:9]
	v_pk_add_f32 v[16:17], v[18:19], v[10:11]
	v_pk_add_f32 v[18:19], v[28:29], v[0:1]
	v_pk_fma_f32 v[36:37], v[34:35], v[24:25], v[8:9] op_sel_hi:[0,1,1] neg_lo:[0,0,1] neg_hi:[0,0,1]
	v_pk_fma_f32 v[28:29], v[34:35], v[18:19], v[0:1] op_sel_hi:[0,1,1] neg_lo:[0,0,1] neg_hi:[0,0,1]
	v_pk_add_f32 v[26:27], v[30:31], v[2:3]
	v_pk_fma_f32 v[38:39], v[34:35], v[16:17], v[10:11] op_sel_hi:[0,1,1] neg_lo:[0,0,1] neg_hi:[0,0,1]
	v_pk_fma_f32 v[30:31], v[34:35], v[26:27], v[2:3] op_sel_hi:[0,1,1] neg_lo:[0,0,1] neg_hi:[0,0,1]
	v_cvt_pk_bf16_f32 v34, v36, v37
	v_cvt_pk_bf16_f32 v36, v28, v29
	v_add_u32_e32 v28, 0x208, v32
	v_cvt_pk_bf16_f32 v35, v38, v39
	v_cvt_pk_bf16_f32 v37, v30, v31
	v_lshl_add_u32 v29, v28, 1, 0
	ds_write_b128 v29, v[34:37]
	s_and_saveexec_b64 s[24:25], s[48:49]
	s_cbranch_execz .LBB0_1614
	v_mov_b32_e32 v29, v161
	s_lshl_b32 s14, s16, 2
	v_add_u32_e32 v29, 0, v29
	v_add_u32_e32 v29, 0x201c8, v29
	s_nop 0
	v_subrev_u32_e32 v32, 45, v113
	v_mov_b32_e32 v33, v161
	s_waitcnt lgkmcnt(0)
	v_readlane_b32 s21, v251, 50
	v_readlane_b32 s15, v251, 51
	s_add_u32 s14, s21, s14
	v_lshl_add_u64 v[30:31], s[6:7], 0, v[32:33]
	s_addc_u32 s15, s15, 0
	v_lshlrev_b64 v[30:31], 11, v[30:31]
	v_lshl_add_u64 v[30:31], s[14:15], 0, v[30:31]
	v_lshl_add_u64 v[30:31], v[30:31], 0, v[160:161]
	global_store_dwordx4 v[30:31], v[8:11], off offset:1024
	global_store_dwordx4 v[30:31], v[0:3], off offset:1040
; #define LAS __attribute__((address_space(3)))
; __device__ __forceinline__ bf16x8 pack8(const float* v) { u32x4 w; w.x = pk2(v[0], v[1]); w.y = pk2(v[2], v[3]); w.z = pk2(v[4], v[5]); w.w = pk2(v[6], v[7]); return __builtin_bit_cast(bf16x8, w); }
; __device__ __forceinline__ void unpack8(u32x4 w, float* v) { v[0] = bflo(w.x); v[1] = bfhi(w.x); v[2] = bflo(w.y); v[3] = bfhi(w.y); v[4] = bflo(w.z); v[5] = bfhi(w.z); v[6] = bflo(w.w); v[7] = bfhi(w.w); }
; template <int W> __device__ __forceinline__ void pool_stage(const Params& p, const bf16_t* z, int layer, bool is_s, int b, int c, int tok0, int g, int half, int lane, LAS unsigned char* L) {
;     ...
;     for (int ti = 0; ti < 8; ++ti) {
;         const int t = t0 + ti; float u[8], ul[8], d[8]; unpack8(raw[W - 1 + ti], u); unpack8(raw[ti], ul);
;         const int cnt = is_s ? W : min(c * 64 + t + 1, W); const float rc = 1.0f / (float)cnt;
; #pragma unroll
;         for (int i = 0; i < 8; ++i) { sum[i] += u[i]; d[i] = sum[i] * rc - u[i]; sum[i] -= ul[i]; }
;         *(LAS bf16x8*)(L + (t * DROW + c0) * 2) = pack8(d);
;         if (t >= 49 && (is_s || c == 31)) { float* o = POUT + (is_s ? O_US : O_UP) + (((size_t)layer * NB + b) * 15 + (t - 49)) * 512 + c0;
;             *(f32x4*)o = (f32x4){u[0], u[1], u[2], u[3]}; *(f32x4*)(o + 4) = (f32x4){u[4], u[5], u[6], u[7]}; }
.LBB0_1614:
	s_or_b64 exec, exec, s[24:25]
	s_nop 0
	v_or_b32_e32 v0, s77, v103
	v_min_u32_e32 v0, 7, v0
	v_add_u32_e32 v0, 1, v0
	v_cvt_f32_ubyte0_e32 v0, v0
	v_div_scale_f32 v1, s[14:15], v0, v0, 1.0
	v_rcp_f32_e32 v29, v1
	v_pk_add_f32 v[8:9], v[16:17], v[64:65] neg_lo:[0,1] neg_hi:[0,1]
	v_pk_add_f32 v[10:11], v[18:19], v[66:67] neg_lo:[0,1] neg_hi:[0,1]
	v_pk_add_f32 v[2:3], v[24:25], v[62:63] neg_lo:[0,1] neg_hi:[0,1]
	v_fma_f32 v16, -v1, v29, 1.0
	v_fmac_f32_e32 v29, v16, v29
	v_div_scale_f32 v16, vcc, 1.0, v0, 1.0
	v_mul_f32_e32 v17, v16, v29
	v_fma_f32 v18, -v1, v17, v16
	v_fmac_f32_e32 v17, v18, v29
	v_fma_f32 v1, -v1, v17, v16
	v_div_fmas_f32 v1, v1, v29, v17
	v_div_fixup_f32 v0, v1, v0, 1.0
	v_pk_add_f32 v[24:25], v[26:27], v[68:69] neg_lo:[0,1] neg_hi:[0,1]
	v_cndmask_b32_e64 v26, v0, v200, s[4:5]
	s_waitcnt vmcnt(2)
	v_lshlrev_b32_e32 v0, 16, v20
	v_and_b32_e32 v1, 0xffff0000, v20
	v_pk_add_f32 v[18:19], v[2:3], v[0:1]
	v_lshlrev_b32_e32 v2, 16, v21
	v_and_b32_e32 v3, 0xffff0000, v21
	v_pk_add_f32 v[16:17], v[8:9], v[2:3]
	v_lshlrev_b32_e32 v8, 16, v22
	v_and_b32_e32 v9, 0xffff0000, v22
	v_pk_add_f32 v[20:21], v[10:11], v[8:9]
	v_lshlrev_b32_e32 v10, 16, v23
	v_and_b32_e32 v11, 0xffff0000, v23
	v_pk_add_f32 v[22:23], v[24:25], v[10:11]
	v_pk_fma_f32 v[30:31], v[26:27], v[18:19], v[0:1] op_sel_hi:[0,1,1] neg_lo:[0,0,1] neg_hi:[0,0,1]
	v_pk_fma_f32 v[32:33], v[26:27], v[16:17], v[2:3] op_sel_hi:[0,1,1] neg_lo:[0,0,1] neg_hi:[0,0,1]
	v_pk_fma_f32 v[24:25], v[26:27], v[22:23], v[10:11] op_sel_hi:[0,1,1] neg_lo:[0,0,1] neg_hi:[0,0,1]
	v_pk_fma_f32 v[34:35], v[26:27], v[20:21], v[8:9] op_sel_hi:[0,1,1] neg_lo:[0,0,1] neg_hi:[0,0,1]
	v_cvt_pk_bf16_f32 v30, v30, v31
	v_cvt_pk_bf16_f32 v31, v32, v33
	v_cvt_pk_bf16_f32 v33, v24, v25
	v_add_u32_e32 v24, 0x208, v28
	v_cmp_lt_u32_e32 vcc, 48, v103
	v_cvt_pk_bf16_f32 v32, v34, v35
	v_lshl_add_u32 v25, v24, 1, 0
	s_and_b64 s[14:15], s[10:11], vcc
	ds_write_b128 v25, v[30:33]
	s_and_saveexec_b64 s[24:25], s[14:15]
	s_cbranch_execz .LBB0_1616
	v_mov_b32_e32 v25, v161
	s_lshl_b32 s14, s16, 2
	v_add_u32_e32 v25, 0, v25
	v_add_u32_e32 v25, 0x201c8, v25
	s_nop 0
	v_subrev_u32_e32 v28, 44, v113
	v_mov_b32_e32 v29, v161
	s_waitcnt lgkmcnt(0)
	v_readlane_b32 s21, v251, 50
	v_readlane_b32 s15, v251, 51
	s_add_u32 s14, s21, s14
	v_lshl_add_u64 v[26:27], s[6:7], 0, v[28:29]
	s_addc_u32 s15, s15, 0
	v_lshlrev_b64 v[26:27], 11, v[26:27]
	v_lshl_add_u64 v[26:27], s[14:15], 0, v[26:27]
	v_lshl_add_u64 v[26:27], v[26:27], 0, v[160:161]
	global_store_dwordx4 v[26:27], v[0:3], off offset:1024
	global_store_dwordx4 v[26:27], v[8:11], off offset:1040
.LBB0_1616:
	s_or_b64 exec, exec, s[24:25]
	v_or_b32_e32 v0, s77, v102
	v_min_u32_e32 v0, 7, v0
	v_add_u32_e32 v0, 1, v0
	v_cvt_f32_ubyte0_e32 v0, v0
	v_div_scale_f32 v1, s[14:15], v0, v0, 1.0
	v_pk_add_f32 v[2:3], v[18:19], v[58:59] neg_lo:[0,1] neg_hi:[0,1]
	v_rcp_f32_e32 v18, v1
	v_pk_add_f32 v[8:9], v[16:17], v[60:61] neg_lo:[0,1] neg_hi:[0,1]
	v_pk_add_f32 v[10:11], v[20:21], v[52:53] neg_lo:[0,1] neg_hi:[0,1]
	v_pk_add_f32 v[20:21], v[22:23], v[50:51] neg_lo:[0,1] neg_hi:[0,1]
	v_fma_f32 v16, -v1, v18, 1.0
	v_fmac_f32_e32 v18, v16, v18
	v_div_scale_f32 v16, vcc, 1.0, v0, 1.0
	v_mul_f32_e32 v17, v16, v18
	v_fma_f32 v19, -v1, v17, v16
	v_fmac_f32_e32 v17, v19, v18
	v_fma_f32 v1, -v1, v17, v16
	v_div_fmas_f32 v1, v1, v18, v17
	v_div_fixup_f32 v0, v1, v0, 1.0
	v_cndmask_b32_e64 v22, v0, v200, s[4:5]
	s_waitcnt vmcnt(1)
	v_lshlrev_b32_e32 v0, 16, v12
	v_and_b32_e32 v1, 0xffff0000, v12
	v_pk_add_f32 v[16:17], v[2:3], v[0:1]
	v_lshlrev_b32_e32 v2, 16, v13
	v_and_b32_e32 v3, 0xffff0000, v13
	v_pk_add_f32 v[12:13], v[8:9], v[2:3]
	v_lshlrev_b32_e32 v8, 16, v14
	v_and_b32_e32 v9, 0xffff0000, v14
	v_pk_add_f32 v[18:19], v[10:11], v[8:9]
	v_lshlrev_b32_e32 v10, 16, v15
	v_and_b32_e32 v11, 0xffff0000, v15
	v_pk_add_f32 v[14:15], v[20:21], v[10:11]
	v_pk_fma_f32 v[26:27], v[22:23], v[16:17], v[0:1] op_sel_hi:[0,1,1] neg_lo:[0,0,1] neg_hi:[0,0,1]
	v_pk_fma_f32 v[28:29], v[22:23], v[12:13], v[2:3] op_sel_hi:[0,1,1] neg_lo:[0,0,1] neg_hi:[0,0,1]
	v_pk_fma_f32 v[20:21], v[22:23], v[14:15], v[10:11] op_sel_hi:[0,1,1] neg_lo:[0,0,1] neg_hi:[0,0,1]
	v_pk_fma_f32 v[30:31], v[22:23], v[18:19], v[8:9] op_sel_hi:[0,1,1] neg_lo:[0,0,1] neg_hi:[0,0,1]
	v_cvt_pk_bf16_f32 v26, v26, v27
	v_cvt_pk_bf16_f32 v27, v28, v29
	v_cvt_pk_bf16_f32 v29, v20, v21
	v_add_u32_e32 v20, 0x208, v24
	v_cmp_lt_u32_e32 vcc, 48, v102
	v_cvt_pk_bf16_f32 v28, v30, v31
	v_lshl_add_u32 v20, v20, 1, 0
	s_and_b64 s[14:15], s[10:11], vcc
	ds_write_b128 v20, v[26:29]
	s_and_saveexec_b64 s[24:25], s[14:15]
	s_cbranch_execz .LBB0_1618
	v_mov_b32_e32 v21, v161
	s_lshl_b32 s14, s16, 2
	v_add_u32_e32 v21, 0, v21
	v_add_u32_e32 v21, 0x201c8, v21
	s_nop 0
	v_subrev_u32_e32 v24, 43, v113
	v_mov_b32_e32 v25, v161
	s_waitcnt lgkmcnt(0)
	v_readlane_b32 s21, v251, 50
	v_readlane_b32 s15, v251, 51
	s_add_u32 s14, s21, s14
	v_lshl_add_u64 v[22:23], s[6:7], 0, v[24:25]
	s_addc_u32 s15, s15, 0
	v_lshlrev_b64 v[22:23], 11, v[22:23]
	v_lshl_add_u64 v[22:23], s[14:15], 0, v[22:23]
	v_lshl_add_u64 v[22:23], v[22:23], 0, v[160:161]
	global_store_dwordx4 v[22:23], v[0:3], off offset:1024
	global_store_dwordx4 v[22:23], v[8:11], off offset:1040
.LBB0_1618:
	s_or_b64 exec, exec, s[24:25]
	v_pk_add_f32 v[0:1], v[16:17], v[56:57] neg_lo:[0,1] neg_hi:[0,1]
	s_waitcnt vmcnt(0)
	v_lshlrev_b32_e32 v8, 16, v4
	v_and_b32_e32 v9, 0xffff0000, v4
	v_pk_add_f32 v[2:3], v[12:13], v[40:41] neg_lo:[0,1] neg_hi:[0,1]
	v_pk_add_f32 v[0:1], v[0:1], v[8:9]
	s_mov_b32 s14, 0x3e000000
	v_lshlrev_b32_e32 v10, 16, v5
	v_and_b32_e32 v11, 0xffff0000, v5
	v_pk_fma_f32 v[16:17], v[0:1], s[14:15], v[8:9] op_sel_hi:[1,0,1] neg_lo:[0,0,1] neg_hi:[0,0,1]
	v_pk_add_f32 v[0:1], v[2:3], v[10:11]
	v_pk_add_f32 v[12:13], v[18:19], v[48:49] neg_lo:[0,1] neg_hi:[0,1]
	v_pk_fma_f32 v[18:19], v[0:1], s[14:15], v[10:11] op_sel_hi:[1,0,1] neg_lo:[0,0,1] neg_hi:[0,0,1]
	v_lshlrev_b32_e32 v0, 16, v6
	v_and_b32_e32 v1, 0xffff0000, v6
	v_pk_add_f32 v[2:3], v[12:13], v[0:1]
	v_pk_add_f32 v[14:15], v[14:15], v[42:43] neg_lo:[0,1] neg_hi:[0,1]
	v_pk_fma_f32 v[12:13], v[2:3], s[14:15], v[0:1] op_sel_hi:[1,0,1] neg_lo:[0,0,1] neg_hi:[0,0,1]
	v_lshlrev_b32_e32 v2, 16, v7
	v_and_b32_e32 v3, 0xffff0000, v7
	v_pk_add_f32 v[4:5], v[14:15], v[2:3]
	v_cmp_lt_u32_e32 vcc, 48, v93
	v_pk_fma_f32 v[14:15], v[4:5], s[14:15], v[2:3] op_sel_hi:[1,0,1] neg_lo:[0,0,1] neg_hi:[0,0,1]
	v_cvt_pk_bf16_f32 v4, v16, v17
	v_cvt_pk_bf16_f32 v5, v18, v19
	v_cvt_pk_bf16_f32 v6, v12, v13
	v_cvt_pk_bf16_f32 v7, v14, v15
	s_and_b64 s[14:15], s[10:11], vcc
	s_mov_b64 s[48:49], 0
	s_mov_b64 s[10:11], 0
	ds_write_b128 v20, v[4:7] offset:1040
	s_and_saveexec_b64 s[28:29], s[14:15]
	s_xor_b64 s[30:31], exec, s[28:29]
	s_cbranch_execz .LBB0_1620
	v_mov_b32_e32 v4, v161
	s_mov_b64 s[10:11], exec
	v_add_u32_e32 v4, 0, v4
	v_add_u32_e32 v4, 0x201c8, v4
	s_nop 0
	s_waitcnt lgkmcnt(0)
	v_readlane_b32 s25, v251, 51
	v_readlane_b32 s24, v251, 50

; #define LAS __attribute__((address_space(3)))
; #define PIN(i) ((const float*)ldq_(L, (i)))
; __device__ __forceinline__ unsigned pk2(float lo, float hi) { f32x2 v = {lo, hi}; bf16x2_t b = __builtin_convertvector(v, bf16x2_t); return __builtin_bit_cast(unsigned, b); }
; template <int W> __device__ __forceinline__ void pool_stage(const Params& p, const bf16_t* z, int layer, bool is_s, int b, int c, int tok0, int g, int half, int lane, LAS unsigned char* L) {
;     const int oct = lane & 15, tq = lane >> 4, c0 = 128 * g + 8 * oct, t0 = 32 * half + 8 * tq;
;     const float* sp = PIN(I_SP) + ((size_t)layer * NB + b) * 15 * 512 + c0;
;     u32x4 raw[W + 7];
; #pragma unroll
;     for (int j = 0; j < W + 7; ++j) {
;         const int t = t0 - (W - 1) + j;
;         u32x4 r = {0u, 0u, 0u, 0u};
;         if (t >= 0 || (!is_s && c * 64 + t >= 0)) r = *(const u32x4*)(z + (size_t)(tok0 + t) * NIN + 768 + c0);
;         else if (is_s) { const f32x4 a = *(const f32x4*)(sp + (15 + t) * 512), bb = *(const f32x4*)(sp + (15 + t) * 512 + 4); r.x = pk2(a[0], a[1]); r.y = pk2(a[2], a[3]); r.z = pk2(bb[0], bb[1]); r.w = pk2(bb[2], bb[3]); }
;         raw[j] = r;
.LBB0_1622:
	v_lshlrev_b32_e32 v0, 3, v181
	v_and_b32_e32 v2, 0x78, v0
	v_mov_b32_e32 v0, v161
	s_and_b32 s6, s66, 0xffffff80
	v_add_u32_e32 v0, 0, v0
	v_add_u32_e32 v0, 0x20130, v0
	s_nop 0
	s_mul_i32 s14, s43, 0x7800
	s_mul_hi_u32 s15, s42, 0x7800
	v_or_b32_e32 v92, s6, v2
	v_lshrrev_b32_e32 v2, 1, v178
	s_waitcnt lgkmcnt(0)
	v_readlane_b32 s6, v251, 12
	s_add_i32 s15, s15, s14
	s_mul_i32 s14, s42, 0x7800
	v_and_b32_e32 v22, 24, v2
	v_readlane_b32 s7, v251, 13
	s_add_u32 s6, s6, s14
	v_lshl_or_b32 v113, s9, 5, v22
	s_addc_u32 s7, s7, s15
	v_ashrrev_i32_e32 v93, 31, v92
	v_lshl_add_u64 v[20:21], v[92:93], 2, s[6:7]
	v_add_u32_e32 v4, -15, v113
	s_not_b32 s14, s77
	v_cmp_gt_u32_e32 vcc, 15, v113
	s_mov_b64 s[18:19], -1
	s_and_saveexec_b64 s[6:7], vcc
	s_cbranch_execz .LBB0_1629
	s_and_b64 vcc, exec, s[40:41]
	s_cbranch_vccz .LBB0_1625
	v_cmp_lt_u32_e32 vcc, s14, v4
	s_mov_b64 s[24:25], 0
	s_and_b64 s[18:19], vcc, exec
	s_branch .LBB0_1626

; __device__ __forceinline__ unsigned pk2(float lo, float hi) { f32x2 v = {lo, hi}; bf16x2_t b = __builtin_convertvector(v, bf16x2_t); return __builtin_bit_cast(unsigned, b); }
; __device__ __forceinline__ void unpack8(u32x4 w, float* v) { v[0] = bflo(w.x); v[1] = bfhi(w.x); v[2] = bflo(w.y); v[3] = bfhi(w.y); v[4] = bflo(w.z); v[5] = bfhi(w.z); v[6] = bflo(w.w); v[7] = bfhi(w.w); }
; template <int W> __device__ __forceinline__ void pool_stage(const Params& p, const bf16_t* z, int layer, bool is_s, int b, int c, int tok0, int g, int half, int lane, LAS unsigned char* L) {
;     ...
;     for (int j = 0; j < W + 7; ++j) {
;         const int t = t0 - (W - 1) + j;
;         u32x4 r = {0u, 0u, 0u, 0u};
;         if (t >= 0 || (!is_s && c * 64 + t >= 0)) r = *(const u32x4*)(z + (size_t)(tok0 + t) * NIN + 768 + c0);
;         else if (is_s) { const f32x4 a = *(const f32x4*)(sp + (15 + t) * 512), bb = *(const f32x4*)(sp + (15 + t) * 512 + 4); r.x = pk2(a[0], a[1]); r.y = pk2(a[2], a[3]); r.z = pk2(bb[0], bb[1]); r.w = pk2(bb[2], bb[3]); }
;         raw[j] = r;
;     }
;     float sum[8];
; #pragma unroll
;     for (int i = 0; i < 8; ++i) sum[i] = 0.f;
; #pragma unroll
;     for (int j = 0; j < W - 1; ++j) { float u[8]; unpack8(raw[j], u);
; #pragma unroll
;         for (int i = 0; i < 8; ++i) sum[i] += u[i]; }
.LBB0_1757:
	s_or_b64 exec, exec, s[6:7]
	v_add_u32_e32 v22, s67, v113
	v_mov_b64_e32 v[20:21], s[34:35]
	v_or_b32_e32 v128, 1, v113
	v_mad_i64_i32 v[22:23], s[6:7], v22, s84, v[20:21]
	v_lshlrev_b64 v[32:33], 1, v[92:93]
	v_add_u32_e32 v34, s67, v128
	v_lshl_add_u64 v[22:23], v[22:23], 0, v[32:33]
	v_mad_i64_i32 v[34:35], s[6:7], v34, s84, v[20:21]
	v_lshl_add_u64 v[34:35], v[34:35], 0, v[32:33]
	global_load_dwordx4 v[88:91], v[22:23], off offset:1536
	global_load_dwordx4 v[76:79], v[34:35], off offset:1536
	v_or_b32_e32 v127, 2, v113
	v_or_b32_e32 v126, 3, v113
	v_add_u32_e32 v22, s67, v127
	v_add_u32_e32 v34, s67, v126
	v_mad_i64_i32 v[22:23], s[6:7], v22, s84, v[20:21]
	v_mad_i64_i32 v[34:35], s[6:7], v34, s84, v[20:21]
	v_lshl_add_u64 v[22:23], v[22:23], 0, v[32:33]
	v_lshl_add_u64 v[34:35], v[34:35], 0, v[32:33]
	v_or_b32_e32 v125, 4, v113
	v_or_b32_e32 v124, 5, v113
	global_load_dwordx4 v[60:63], v[22:23], off offset:1536
	global_load_dwordx4 v[56:59], v[34:35], off offset:1536
	v_add_u32_e32 v22, s67, v125
	v_add_u32_e32 v34, s67, v124
	v_mad_i64_i32 v[22:23], s[6:7], v22, s84, v[20:21]
	v_mad_i64_i32 v[34:35], s[6:7], v34, s84, v[20:21]
	v_lshl_add_u64 v[22:23], v[22:23], 0, v[32:33]
	v_lshl_add_u64 v[34:35], v[34:35], 0, v[32:33]
	v_or_b32_e32 v123, 6, v113
	v_or_b32_e32 v122, 7, v113
	global_load_dwordx4 v[52:55], v[22:23], off offset:1536
	global_load_dwordx4 v[44:47], v[34:35], off offset:1536
	v_add_u32_e32 v22, s67, v123
	v_add_u32_e32 v34, s67, v122
	v_mad_i64_i32 v[22:23], s[6:7], v22, s84, v[20:21]
	v_mad_i64_i32 v[20:21], s[6:7], v34, s84, v[20:21]
	v_lshl_add_u64 v[22:23], v[22:23], 0, v[32:33]
	v_lshl_add_u64 v[20:21], v[20:21], 0, v[32:33]
	global_load_dwordx4 v[32:35], v[22:23], off offset:1536
	s_nop 0
	global_load_dwordx4 v[20:23], v[20:21], off offset:1536
	s_waitcnt vmcnt(8)
	v_lshlrev_b32_e32 v96, 16, v24
	v_and_b32_e32 v97, 0xffff0000, v24
	v_lshlrev_b32_e32 v98, 16, v25
	v_and_b32_e32 v99, 0xffff0000, v25
	v_lshlrev_b32_e32 v24, 16, v42
	v_and_b32_e32 v25, 0xffff0000, v42
	v_or_b32_e32 v42, s77, v113
	v_min_u32_e32 v42, 15, v42
	v_add_u32_e32 v42, 1, v42
	v_cvt_f32_ubyte0_e32 v42, v42
	v_lshlrev_b32_e32 v104, 16, v18
	v_and_b32_e32 v105, 0xffff0000, v18
	v_lshlrev_b32_e32 v106, 16, v19
	v_and_b32_e32 v107, 0xffff0000, v19
	v_lshlrev_b32_e32 v18, 16, v43
	v_and_b32_e32 v19, 0xffff0000, v43
	v_div_scale_f32 v43, s[18:19], v42, v42, 1.0
	v_lshlrev_b32_e32 v108, 16, v12
	v_and_b32_e32 v109, 0xffff0000, v12
	v_lshlrev_b32_e32 v110, 16, v13
	v_and_b32_e32 v111, 0xffff0000, v13
	v_lshlrev_b32_e32 v12, 16, v64
	v_and_b32_e32 v13, 0xffff0000, v64
	v_rcp_f32_e32 v64, v43
	v_lshlrev_b32_e32 v114, 16, v14
	v_and_b32_e32 v115, 0xffff0000, v14
	v_lshlrev_b32_e32 v116, 16, v15
	v_and_b32_e32 v117, 0xffff0000, v15
	v_lshlrev_b32_e32 v14, 16, v65
	v_and_b32_e32 v15, 0xffff0000, v65
	v_fma_f32 v65, -v43, v64, 1.0
	v_fmac_f32_e32 v64, v65, v64
	v_div_scale_f32 v65, vcc, 1.0, v42, 1.0
	v_lshlrev_b32_e32 v130, 16, v66
	v_and_b32_e32 v131, 0xffff0000, v66
	v_lshlrev_b32_e32 v118, 16, v67
	v_and_b32_e32 v119, 0xffff0000, v67
	v_lshlrev_b32_e32 v66, 16, v72
	v_and_b32_e32 v67, 0xffff0000, v72
	v_mul_f32_e32 v72, v65, v64
	v_lshlrev_b32_e32 v132, 16, v73
	v_and_b32_e32 v133, 0xffff0000, v73
	v_fma_f32 v73, -v43, v72, v65
	v_fmac_f32_e32 v72, v73, v64
	v_fma_f32 v43, -v43, v72, v65
	v_div_fmas_f32 v43, v43, v64, v72
	v_lshlrev_b32_e32 v72, 16, v0
	v_and_b32_e32 v73, 0xffff0000, v0
	v_div_fixup_f32 v42, v43, v42, 1.0
	v_lshlrev_b32_e32 v64, 16, v4
	v_and_b32_e32 v65, 0xffff0000, v4
	v_pk_add_f32 v[146:147], v[72:73], 0 op_sel_hi:[1,0]
	v_cndmask_b32_e64 v140, v42, v201, s[4:5]
	v_lshlrev_b32_e32 v42, 16, v8
	v_and_b32_e32 v43, 0xffff0000, v8
	v_pk_add_f32 v[146:147], v[146:147], v[64:65]
	v_lshlrev_b32_e32 v100, 16, v16
	v_pk_add_f32 v[146:147], v[146:147], v[42:43]
	v_and_b32_e32 v101, 0xffff0000, v16
	v_pk_add_f32 v[146:147], v[146:147], v[108:109]
	v_lshlrev_b32_e32 v94, 16, v40
	v_pk_add_f32 v[146:147], v[146:147], v[100:101]
	v_and_b32_e32 v95, 0xffff0000, v40
	v_pk_add_f32 v[146:147], v[146:147], v[96:97]
	v_lshlrev_b32_e32 v134, 16, v74
	v_and_b32_e32 v135, 0xffff0000, v74
	v_lshlrev_b32_e32 v120, 16, v75
	v_and_b32_e32 v121, 0xffff0000, v75
	v_lshlrev_b32_e32 v74, 16, v84
	v_and_b32_e32 v75, 0xffff0000, v84
	v_lshlrev_b32_e32 v136, 16, v85
	v_and_b32_e32 v137, 0xffff0000, v85
	v_lshlrev_b32_e32 v84, 16, v28
	v_and_b32_e32 v85, 0xffff0000, v28
	v_pk_add_f32 v[146:147], v[146:147], v[94:95]
	v_lshlrev_b32_e32 v142, 16, v36
	v_and_b32_e32 v143, 0xffff0000, v36
	v_pk_add_f32 v[84:85], v[146:147], v[84:85]
	v_lshlrev_b32_e32 v144, 16, v48
	v_and_b32_e32 v145, 0xffff0000, v48
	v_pk_add_f32 v[84:85], v[84:85], v[142:143]
	v_lshlrev_b32_e32 v4, 16, v37
	v_pk_add_f32 v[84:85], v[84:85], v[144:145]
	v_lshlrev_b32_e32 v8, 16, v9
	v_pk_add_f32 v[12:13], v[84:85], v[12:13]
	v_and_b32_e32 v9, 0xffff0000, v9
	v_pk_add_f32 v[12:13], v[12:13], v[66:67]
	v_lshlrev_b32_e32 v66, 16, v68
	v_pk_add_f32 v[12:13], v[12:13], v[74:75]
	v_and_b32_e32 v67, 0xffff0000, v68
	v_pk_add_f32 v[12:13], v[12:13], v[66:67]
	v_lshlrev_b32_e32 v66, 16, v80
	v_and_b32_e32 v67, 0xffff0000, v80
	v_pk_add_f32 v[66:67], v[12:13], v[66:67]
	s_waitcnt vmcnt(7)
; #define LAS __attribute__((address_space(3)))
; __device__ __forceinline__ bf16x8 pack8(const float* v) { u32x4 w; w.x = pk2(v[0], v[1]); w.y = pk2(v[2], v[3]); w.z = pk2(v[4], v[5]); w.w = pk2(v[6], v[7]); return __builtin_bit_cast(bf16x8, w); }
; __device__ __forceinline__ void unpack8(u32x4 w, float* v) { v[0] = bflo(w.x); v[1] = bfhi(w.x); v[2] = bflo(w.y); v[3] = bfhi(w.y); v[4] = bflo(w.z); v[5] = bfhi(w.z); v[6] = bflo(w.w); v[7] = bfhi(w.w); }
; template <int W> __device__ __forceinline__ void pool_stage(const Params& p, const bf16_t* z, int layer, bool is_s, int b, int c, int tok0, int g, int half, int lane, LAS unsigned char* L) {
;     ...
;     for (int j = 0; j < W - 1; ++j) { float u[8]; unpack8(raw[j], u);
; #pragma unroll
;         for (int i = 0; i < 8; ++i) sum[i] += u[i]; }
; #pragma unroll
;     for (int ti = 0; ti < 8; ++ti) {
;         const int t = t0 + ti; float u[8], ul[8], d[8]; unpack8(raw[W - 1 + ti], u); unpack8(raw[ti], ul);
;         const int cnt = is_s ? W : min(c * 64 + t + 1, W); const float rc = 1.0f / (float)cnt;
; #pragma unroll
;         for (int i = 0; i < 8; ++i) { sum[i] += u[i]; d[i] = sum[i] * rc - u[i]; sum[i] -= ul[i]; }
;         *(LAS bf16x8*)(L + (t * DROW + c0) * 2) = pack8(d);
;         if (t >= 49 && (is_s || c == 31)) { float* o = POUT + (is_s ? O_US : O_UP) + (((size_t)layer * NB + b) * 15 + (t - 49)) * 512 + c0;
;             *(f32x4*)o = (f32x4){u[0], u[1], u[2], u[3]}; *(f32x4*)(o + 4) = (f32x4){u[4], u[5], u[6], u[7]}; }
	v_lshlrev_b32_e32 v12, 16, v88
	v_and_b32_e32 v13, 0xffff0000, v88
	v_lshlrev_b32_e32 v74, 16, v1
	v_and_b32_e32 v75, 0xffff0000, v1
	v_pk_add_f32 v[84:85], v[66:67], v[12:13]
	v_lshlrev_b32_e32 v66, 16, v5
	v_and_b32_e32 v67, 0xffff0000, v5
	v_and_b32_e32 v5, 0xffff0000, v37
	v_pk_add_f32 v[36:37], v[74:75], 0 op_sel_hi:[1,0]
	v_lshlrev_b32_e32 v102, 16, v17
	v_pk_add_f32 v[36:37], v[36:37], v[66:67]
	v_and_b32_e32 v103, 0xffff0000, v17
	v_pk_add_f32 v[36:37], v[36:37], v[8:9]
	v_lshlrev_b32_e32 v16, 16, v41
	v_pk_add_f32 v[36:37], v[36:37], v[110:111]
	v_and_b32_e32 v17, 0xffff0000, v41
	v_pk_add_f32 v[36:37], v[36:37], v[102:103]
	v_lshlrev_b32_e32 v0, 16, v29
	v_pk_add_f32 v[36:37], v[36:37], v[98:99]
	v_and_b32_e32 v1, 0xffff0000, v29
	v_pk_add_f32 v[36:37], v[36:37], v[16:17]
	v_lshlrev_b32_e32 v28, 16, v49
	v_pk_add_f32 v[0:1], v[36:37], v[0:1]
	v_and_b32_e32 v29, 0xffff0000, v49
	v_pk_add_f32 v[0:1], v[0:1], v[4:5]
	v_lshlrev_b32_e32 v4, 16, v69
	v_pk_add_f32 v[0:1], v[0:1], v[28:29]
	v_and_b32_e32 v5, 0xffff0000, v69
	v_lshlrev_b32_e32 v68, 16, v2
	v_and_b32_e32 v69, 0xffff0000, v2
	v_pk_add_f32 v[0:1], v[0:1], v[14:15]
	v_lshlrev_b32_e32 v14, 16, v89
	v_and_b32_e32 v15, 0xffff0000, v89
	v_lshlrev_b32_e32 v36, 16, v6
	v_and_b32_e32 v37, 0xffff0000, v6
	v_pk_add_f32 v[88:89], v[68:69], 0 op_sel_hi:[1,0]
	v_lshlrev_b32_e32 v28, 16, v10
	v_and_b32_e32 v29, 0xffff0000, v10
	v_pk_add_f32 v[88:89], v[88:89], v[36:37]
	v_pk_add_f32 v[0:1], v[0:1], v[132:133]
	v_pk_add_f32 v[88:89], v[88:89], v[28:29]
	v_pk_add_f32 v[0:1], v[0:1], v[136:137]
	v_pk_add_f32 v[88:89], v[88:89], v[114:115]
	v_lshlrev_b32_e32 v40, 16, v26
	v_and_b32_e32 v41, 0xffff0000, v26
	v_pk_add_f32 v[0:1], v[0:1], v[4:5]
	v_lshlrev_b32_e32 v4, 16, v81
	v_and_b32_e32 v5, 0xffff0000, v81
	v_pk_add_f32 v[88:89], v[88:89], v[104:105]
	v_pk_add_f32 v[0:1], v[0:1], v[4:5]
	v_pk_add_f32 v[88:89], v[88:89], v[40:41]
	v_pk_add_f32 v[4:5], v[0:1], v[14:15]
	v_lshlrev_b32_e32 v0, 16, v30
	v_and_b32_e32 v1, 0xffff0000, v30
	v_pk_add_f32 v[88:89], v[88:89], v[24:25]
	v_lshlrev_b32_e32 v48, 16, v38
	v_and_b32_e32 v49, 0xffff0000, v38
	v_pk_add_f32 v[0:1], v[88:89], v[0:1]
	v_lshlrev_b32_e32 v80, 16, v50
	v_and_b32_e32 v81, 0xffff0000, v50
	v_pk_add_f32 v[0:1], v[0:1], v[48:49]
	v_lshlrev_b32_e32 v138, 16, v86
	v_pk_add_f32 v[0:1], v[0:1], v[80:81]
	v_and_b32_e32 v139, 0xffff0000, v86
	v_pk_add_f32 v[0:1], v[0:1], v[130:131]
	v_lshlrev_b32_e32 v48, 16, v70
	v_pk_add_f32 v[0:1], v[0:1], v[134:135]
	v_and_b32_e32 v49, 0xffff0000, v70
	v_pk_add_f32 v[0:1], v[0:1], v[138:139]
	v_lshlrev_b32_e32 v88, 16, v3
	v_pk_add_f32 v[0:1], v[0:1], v[48:49]
	v_lshlrev_b32_e32 v48, 16, v82
	v_and_b32_e32 v49, 0xffff0000, v82
	v_pk_add_f32 v[48:49], v[0:1], v[48:49]
	v_lshlrev_b32_e32 v0, 16, v90
	v_and_b32_e32 v1, 0xffff0000, v90
	v_and_b32_e32 v89, 0xffff0000, v3
	v_pk_add_f32 v[80:81], v[48:49], v[0:1]
	v_lshlrev_b32_e32 v48, 16, v7
	v_and_b32_e32 v49, 0xffff0000, v7
	v_lshlrev_b32_e32 v6, 16, v39
	v_and_b32_e32 v7, 0xffff0000, v39
	v_pk_add_f32 v[38:39], v[88:89], 0 op_sel_hi:[1,0]
	v_lshlrev_b32_e32 v10, 16, v11
	v_and_b32_e32 v11, 0xffff0000, v11
	v_pk_add_f32 v[38:39], v[38:39], v[48:49]
	v_lshlrev_b32_e32 v26, 16, v27
	v_pk_add_f32 v[38:39], v[38:39], v[10:11]
	v_and_b32_e32 v27, 0xffff0000, v27
	v_pk_add_f32 v[38:39], v[38:39], v[116:117]
	v_lshlrev_b32_e32 v2, 16, v31
	v_pk_add_f32 v[38:39], v[38:39], v[106:107]
	v_and_b32_e32 v3, 0xffff0000, v31
	v_pk_add_f32 v[38:39], v[38:39], v[26:27]
	s_mul_i32 s6, s43, 15
	v_pk_add_f32 v[38:39], v[38:39], v[18:19]
	s_mul_hi_u32 s7, s42, 15
	v_pk_add_f32 v[2:3], v[38:39], v[2:3]
	v_lshlrev_b32_e32 v30, 16, v51
	v_and_b32_e32 v31, 0xffff0000, v51
	v_pk_add_f32 v[2:3], v[2:3], v[6:7]
	s_add_i32 s7, s7, s6
	v_pk_add_f32 v[2:3], v[2:3], v[30:31]
	s_cmp_eq_u32 s76, 31
	v_pk_add_f32 v[2:3], v[2:3], v[118:119]
	v_lshlrev_b32_e32 v86, 16, v87
	v_and_b32_e32 v87, 0xffff0000, v87
	s_cselect_b64 s[14:15], -1, 0
	v_pk_add_f32 v[2:3], v[2:3], v[120:121]
	s_or_b64 s[18:19], s[4:5], s[14:15]
	v_pk_add_f32 v[2:3], v[2:3], v[86:87]
	v_lshlrev_b32_e32 v6, 16, v71
	v_and_b32_e32 v7, 0xffff0000, v71
	s_and_b64 s[14:15], s[4:5], exec
	v_pk_add_f32 v[2:3], v[2:3], v[6:7]
	v_lshlrev_b32_e32 v6, 16, v83
	v_and_b32_e32 v7, 0xffff0000, v83
	s_mov_b32 s14, 0x4678000
	v_pk_add_f32 v[6:7], v[2:3], v[6:7]
	v_lshlrev_b32_e32 v2, 16, v91
	v_and_b32_e32 v3, 0xffff0000, v91
	s_cselect_b32 s16, s14, 0x4400000
	v_pk_add_f32 v[6:7], v[6:7], v[2:3]
	s_movk_i32 s14, 0x208
	v_pk_fma_f32 v[142:143], v[140:141], v[84:85], v[12:13] op_sel_hi:[0,1,1] neg_lo:[0,0,1] neg_hi:[0,0,1]
	v_pk_fma_f32 v[132:133], v[140:141], v[4:5], v[14:15] op_sel_hi:[0,1,1] neg_lo:[0,0,1] neg_hi:[0,0,1]
	v_pk_fma_f32 v[130:131], v[140:141], v[80:81], v[0:1] op_sel_hi:[0,1,1] neg_lo:[0,0,1] neg_hi:[0,0,1]
	v_pk_fma_f32 v[30:31], v[140:141], v[6:7], v[2:3] op_sel_hi:[0,1,1] neg_lo:[0,0,1] neg_hi:[0,0,1]
	v_mad_u32_u24 v50, v113, s14, v92
	v_cmp_lt_u32_e32 vcc, 48, v113
	s_mul_i32 s6, s42, 15
	v_cvt_pk_bf16_f32 v118, v142, v143
	v_cvt_pk_bf16_f32 v119, v132, v133
	v_cvt_pk_bf16_f32 v120, v130, v131
	v_cvt_pk_bf16_f32 v121, v30, v31
	v_lshl_add_u32 v30, v50, 1, 0
	s_and_b64 s[14:15], s[18:19], vcc
	ds_write_b128 v30, v[118:121]
	s_and_saveexec_b64 s[24:25], s[14:15]
	s_cbranch_execz .LBB0_1759
	v_mov_b32_e32 v30, v161
	s_lshl_b32 s21, s16, 2
	v_add_u32_e32 v30, 0, v30
	v_add_u32_e32 v30, 0x201c8, v30
	s_nop 0
	v_subrev_u32_e32 v160, 49, v113
	s_waitcnt lgkmcnt(0)
	v_readlane_b32 s14, v251, 50
	v_readlane_b32 s15, v251, 51
	s_add_u32 s14, s14, s21
	v_lshl_add_u64 v[30:31], s[6:7], 0, v[160:161]
	s_addc_u32 s15, s15, 0
	v_lshlrev_b64 v[30:31], 11, v[30:31]
	v_lshl_add_u64 v[30:31], s[14:15], 0, v[30:31]
	v_lshl_add_u64 v[30:31], v[92:93], 2, v[30:31]
	global_store_dwordx4 v[30:31], v[12:15], off
	global_store_dwordx4 v[30:31], v[0:3], off offset:16
; #define LAS __attribute__((address_space(3)))
; __device__ __forceinline__ bf16x8 pack8(const float* v) { u32x4 w; w.x = pk2(v[0], v[1]); w.y = pk2(v[2], v[3]); w.z = pk2(v[4], v[5]); w.w = pk2(v[6], v[7]); return __builtin_bit_cast(bf16x8, w); }
; __device__ __forceinline__ void unpack8(u32x4 w, float* v) { v[0] = bflo(w.x); v[1] = bfhi(w.x); v[2] = bflo(w.y); v[3] = bfhi(w.y); v[4] = bflo(w.z); v[5] = bfhi(w.z); v[6] = bflo(w.w); v[7] = bfhi(w.w); }
; template <int W> __device__ __forceinline__ void pool_stage(const Params& p, const bf16_t* z, int layer, bool is_s, int b, int c, int tok0, int g, int half, int lane, LAS unsigned char* L) {
;     ...
;     for (int ti = 0; ti < 8; ++ti) {
;         const int t = t0 + ti; float u[8], ul[8], d[8]; unpack8(raw[W - 1 + ti], u); unpack8(raw[ti], ul);
;         const int cnt = is_s ? W : min(c * 64 + t + 1, W); const float rc = 1.0f / (float)cnt;
; #pragma unroll
;         for (int i = 0; i < 8; ++i) { sum[i] += u[i]; d[i] = sum[i] * rc - u[i]; sum[i] -= ul[i]; }
;         *(LAS bf16x8*)(L + (t * DROW + c0) * 2) = pack8(d);
;         if (t >= 49 && (is_s || c == 31)) { float* o = POUT + (is_s ? O_US : O_UP) + (((size_t)layer * NB + b) * 15 + (t - 49)) * 512 + c0;
;             *(f32x4*)o = (f32x4){u[0], u[1], u[2], u[3]}; *(f32x4*)(o + 4) = (f32x4){u[4], u[5], u[6], u[7]}; }
.LBB0_1759:
	s_or_b64 exec, exec, s[24:25]
	s_nop 0
	v_or_b32_e32 v0, s77, v128
	v_min_u32_e32 v0, 15, v0
	v_add_u32_e32 v0, 1, v0
	v_cvt_f32_ubyte0_e32 v0, v0
	v_div_scale_f32 v1, s[14:15], v0, v0, 1.0
	v_rcp_f32_e32 v12, v1
	v_pk_add_f32 v[38:39], v[6:7], v[88:89] neg_lo:[0,1] neg_hi:[0,1]
	v_pk_add_f32 v[2:3], v[84:85], v[72:73] neg_lo:[0,1] neg_hi:[0,1]
	v_pk_add_f32 v[30:31], v[80:81], v[68:69] neg_lo:[0,1] neg_hi:[0,1]
	v_fma_f32 v6, -v1, v12, 1.0
	v_fmac_f32_e32 v12, v6, v12
	v_div_scale_f32 v6, vcc, 1.0, v0, 1.0
	v_mul_f32_e32 v7, v6, v12
	v_fma_f32 v13, -v1, v7, v6
	v_fmac_f32_e32 v7, v13, v12
	v_fma_f32 v1, -v1, v7, v6
	v_div_fmas_f32 v1, v1, v12, v7
	v_div_fixup_f32 v0, v1, v0, 1.0
	v_cndmask_b32_e64 v68, v0, v201, s[4:5]
	s_waitcnt vmcnt(6)
	v_lshlrev_b32_e32 v0, 16, v76
	v_and_b32_e32 v1, 0xffff0000, v76
	v_pk_add_f32 v[4:5], v[4:5], v[74:75] neg_lo:[0,1] neg_hi:[0,1]
	v_pk_add_f32 v[14:15], v[2:3], v[0:1]
	v_lshlrev_b32_e32 v2, 16, v77
	v_and_b32_e32 v3, 0xffff0000, v77
	v_pk_add_f32 v[12:13], v[4:5], v[2:3]
	v_lshlrev_b32_e32 v4, 16, v78
	v_and_b32_e32 v5, 0xffff0000, v78
	v_lshlrev_b32_e32 v6, 16, v79
	v_and_b32_e32 v7, 0xffff0000, v79
	v_pk_add_f32 v[30:31], v[30:31], v[4:5]
	v_pk_add_f32 v[38:39], v[38:39], v[6:7]
	v_pk_fma_f32 v[70:71], v[68:69], v[14:15], v[0:1] op_sel_hi:[0,1,1] neg_lo:[0,0,1] neg_hi:[0,0,1]
	v_pk_fma_f32 v[72:73], v[68:69], v[12:13], v[2:3] op_sel_hi:[0,1,1] neg_lo:[0,0,1] neg_hi:[0,0,1]
	v_pk_fma_f32 v[74:75], v[68:69], v[30:31], v[4:5] op_sel_hi:[0,1,1] neg_lo:[0,0,1] neg_hi:[0,0,1]
	v_pk_fma_f32 v[76:77], v[68:69], v[38:39], v[6:7] op_sel_hi:[0,1,1] neg_lo:[0,0,1] neg_hi:[0,0,1]
	v_add_u32_e32 v50, 0x208, v50
	v_cmp_lt_u32_e32 vcc, 47, v113
	v_cvt_pk_bf16_f32 v68, v70, v71
	v_cvt_pk_bf16_f32 v69, v72, v73
	v_cvt_pk_bf16_f32 v70, v74, v75
	v_cvt_pk_bf16_f32 v71, v76, v77
	v_lshl_add_u32 v51, v50, 1, 0
	s_and_b64 s[44:45], s[18:19], vcc
	ds_write_b128 v51, v[68:71]
	s_and_saveexec_b64 s[24:25], s[44:45]
	s_cbranch_execz .LBB0_1761
	v_mov_b32_e32 v51, v161
	s_lshl_b32 s21, s16, 2
	v_add_u32_e32 v51, 0, v51
	v_add_u32_e32 v51, 0x201c8, v51
	s_nop 0
	v_subrev_u32_e32 v160, 48, v113
	s_waitcnt lgkmcnt(0)
	v_readlane_b32 s14, v251, 50
	v_readlane_b32 s15, v251, 51
	s_add_u32 s14, s14, s21
	v_lshl_add_u64 v[68:69], s[6:7], 0, v[160:161]
	s_addc_u32 s15, s15, 0
	v_lshlrev_b64 v[68:69], 11, v[68:69]
	v_lshl_add_u64 v[68:69], s[14:15], 0, v[68:69]
	v_lshl_add_u64 v[68:69], v[92:93], 2, v[68:69]
	global_store_dwordx4 v[68:69], v[0:3], off
	global_store_dwordx4 v[68:69], v[4:7], off offset:16
.LBB0_1761:
	s_or_b64 exec, exec, s[24:25]
	v_or_b32_e32 v0, s77, v127
	v_min_u32_e32 v0, 15, v0
	v_add_u32_e32 v0, 1, v0
	v_cvt_f32_ubyte0_e32 v0, v0
	v_div_scale_f32 v1, s[14:15], v0, v0, 1.0
	v_pk_add_f32 v[2:3], v[14:15], v[64:65] neg_lo:[0,1] neg_hi:[0,1]
	v_rcp_f32_e32 v14, v1
	v_pk_add_f32 v[4:5], v[12:13], v[66:67] neg_lo:[0,1] neg_hi:[0,1]
	v_pk_add_f32 v[6:7], v[30:31], v[36:37] neg_lo:[0,1] neg_hi:[0,1]
	v_pk_add_f32 v[36:37], v[38:39], v[48:49] neg_lo:[0,1] neg_hi:[0,1]
	v_fma_f32 v12, -v1, v14, 1.0
	v_fmac_f32_e32 v14, v12, v14
	v_div_scale_f32 v12, vcc, 1.0, v0, 1.0
	v_mul_f32_e32 v13, v12, v14
	v_fma_f32 v15, -v1, v13, v12
	v_fmac_f32_e32 v13, v15, v14
	v_fma_f32 v1, -v1, v13, v12
	v_div_fmas_f32 v1, v1, v14, v13
	v_div_fixup_f32 v0, v1, v0, 1.0
	v_cndmask_b32_e64 v38, v0, v201, s[4:5]
	s_waitcnt vmcnt(5)
	v_lshlrev_b32_e32 v0, 16, v60
	v_and_b32_e32 v1, 0xffff0000, v60
	v_pk_add_f32 v[14:15], v[2:3], v[0:1]
	v_lshlrev_b32_e32 v2, 16, v61
	v_and_b32_e32 v3, 0xffff0000, v61
	v_pk_add_f32 v[12:13], v[4:5], v[2:3]
	v_lshlrev_b32_e32 v4, 16, v62
	v_and_b32_e32 v5, 0xffff0000, v62
	v_pk_add_f32 v[30:31], v[6:7], v[4:5]
	v_lshlrev_b32_e32 v6, 16, v63
	v_and_b32_e32 v7, 0xffff0000, v63
	v_pk_add_f32 v[36:37], v[36:37], v[6:7]
	v_pk_fma_f32 v[48:49], v[38:39], v[14:15], v[0:1] op_sel_hi:[0,1,1] neg_lo:[0,0,1] neg_hi:[0,0,1]
	v_pk_fma_f32 v[64:65], v[38:39], v[12:13], v[2:3] op_sel_hi:[0,1,1] neg_lo:[0,0,1] neg_hi:[0,0,1]
	v_pk_fma_f32 v[66:67], v[38:39], v[30:31], v[4:5] op_sel_hi:[0,1,1] neg_lo:[0,0,1] neg_hi:[0,0,1]
	v_pk_fma_f32 v[38:39], v[38:39], v[36:37], v[6:7] op_sel_hi:[0,1,1] neg_lo:[0,0,1] neg_hi:[0,0,1]
	v_cvt_pk_bf16_f32 v63, v38, v39
	v_add_u32_e32 v38, 0x208, v50
	v_cvt_pk_bf16_f32 v60, v48, v49
	v_cvt_pk_bf16_f32 v61, v64, v65
	v_cvt_pk_bf16_f32 v62, v66, v67
	v_lshl_add_u32 v39, v38, 1, 0
	ds_write_b128 v39, v[60:63]
	s_and_saveexec_b64 s[24:25], s[44:45]
	s_cbranch_execz .LBB0_1763
	v_mov_b32_e32 v39, v161
	s_lshl_b32 s21, s16, 2
	v_add_u32_e32 v39, 0, v39
	v_add_u32_e32 v39, 0x201c8, v39
	s_nop 0
	v_subrev_u32_e32 v160, 47, v113
	s_waitcnt lgkmcnt(0)
	v_readlane_b32 s14, v251, 50
	v_readlane_b32 s15, v251, 51
	s_add_u32 s14, s14, s21
	v_lshl_add_u64 v[48:49], s[6:7], 0, v[160:161]
	s_addc_u32 s15, s15, 0
	v_lshlrev_b64 v[48:49], 11, v[48:49]
	v_lshl_add_u64 v[48:49], s[14:15], 0, v[48:49]
	v_lshl_add_u64 v[48:49], v[92:93], 2, v[48:49]
	global_store_dwordx4 v[48:49], v[0:3], off
	global_store_dwordx4 v[48:49], v[4:7], off offset:16
; #define LAS __attribute__((address_space(3)))
; __device__ __forceinline__ bf16x8 pack8(const float* v) { u32x4 w; w.x = pk2(v[0], v[1]); w.y = pk2(v[2], v[3]); w.z = pk2(v[4], v[5]); w.w = pk2(v[6], v[7]); return __builtin_bit_cast(bf16x8, w); }
; __device__ __forceinline__ void unpack8(u32x4 w, float* v) { v[0] = bflo(w.x); v[1] = bfhi(w.x); v[2] = bflo(w.y); v[3] = bfhi(w.y); v[4] = bflo(w.z); v[5] = bfhi(w.z); v[6] = bflo(w.w); v[7] = bfhi(w.w); }
; template <int W> __device__ __forceinline__ void pool_stage(const Params& p, const bf16_t* z, int layer, bool is_s, int b, int c, int tok0, int g, int half, int lane, LAS unsigned char* L) {
;     ...
;     for (int ti = 0; ti < 8; ++ti) {
;         const int t = t0 + ti; float u[8], ul[8], d[8]; unpack8(raw[W - 1 + ti], u); unpack8(raw[ti], ul);
;         const int cnt = is_s ? W : min(c * 64 + t + 1, W); const float rc = 1.0f / (float)cnt;
; #pragma unroll
;         for (int i = 0; i < 8; ++i) { sum[i] += u[i]; d[i] = sum[i] * rc - u[i]; sum[i] -= ul[i]; }
;         *(LAS bf16x8*)(L + (t * DROW + c0) * 2) = pack8(d);
;         if (t >= 49 && (is_s || c == 31)) { float* o = POUT + (is_s ? O_US : O_UP) + (((size_t)layer * NB + b) * 15 + (t - 49)) * 512 + c0;
;             *(f32x4*)o = (f32x4){u[0], u[1], u[2], u[3]}; *(f32x4*)(o + 4) = (f32x4){u[4], u[5], u[6], u[7]}; }
.LBB0_1763:
	s_or_b64 exec, exec, s[24:25]
	v_or_b32_e32 v0, s77, v126
	v_min_u32_e32 v0, 15, v0
	v_add_u32_e32 v0, 1, v0
	v_cvt_f32_ubyte0_e32 v0, v0
	v_div_scale_f32 v1, s[14:15], v0, v0, 1.0
	v_rcp_f32_e32 v39, v1
	v_pk_add_f32 v[4:5], v[12:13], v[8:9] neg_lo:[0,1] neg_hi:[0,1]
	v_pk_add_f32 v[2:3], v[14:15], v[42:43] neg_lo:[0,1] neg_hi:[0,1]
	v_pk_add_f32 v[14:15], v[36:37], v[10:11] neg_lo:[0,1] neg_hi:[0,1]
	v_fma_f32 v8, -v1, v39, 1.0
	v_fmac_f32_e32 v39, v8, v39
	v_div_scale_f32 v8, vcc, 1.0, v0, 1.0
	v_mul_f32_e32 v9, v8, v39
	v_fma_f32 v10, -v1, v9, v8
	v_fmac_f32_e32 v9, v10, v39
	v_fma_f32 v1, -v1, v9, v8
	v_div_fmas_f32 v1, v1, v39, v9
	v_div_fixup_f32 v0, v1, v0, 1.0
	v_pk_add_f32 v[6:7], v[30:31], v[28:29] neg_lo:[0,1] neg_hi:[0,1]
	v_cndmask_b32_e64 v28, v0, v201, s[4:5]
	s_waitcnt vmcnt(4)
	v_lshlrev_b32_e32 v0, 16, v56
	v_and_b32_e32 v1, 0xffff0000, v56
	v_pk_add_f32 v[8:9], v[2:3], v[0:1]
	v_lshlrev_b32_e32 v2, 16, v57
	v_and_b32_e32 v3, 0xffff0000, v57
	v_pk_add_f32 v[10:11], v[4:5], v[2:3]
	v_lshlrev_b32_e32 v4, 16, v58
	v_and_b32_e32 v5, 0xffff0000, v58
	v_pk_add_f32 v[12:13], v[6:7], v[4:5]
	v_lshlrev_b32_e32 v6, 16, v59
	v_and_b32_e32 v7, 0xffff0000, v59
	v_pk_add_f32 v[14:15], v[14:15], v[6:7]
	v_pk_fma_f32 v[30:31], v[28:29], v[8:9], v[0:1] op_sel_hi:[0,1,1] neg_lo:[0,0,1] neg_hi:[0,0,1]
	v_pk_fma_f32 v[36:37], v[28:29], v[10:11], v[2:3] op_sel_hi:[0,1,1] neg_lo:[0,0,1] neg_hi:[0,0,1]
	v_pk_fma_f32 v[42:43], v[28:29], v[12:13], v[4:5] op_sel_hi:[0,1,1] neg_lo:[0,0,1] neg_hi:[0,0,1]
	v_pk_fma_f32 v[28:29], v[28:29], v[14:15], v[6:7] op_sel_hi:[0,1,1] neg_lo:[0,0,1] neg_hi:[0,0,1]
	v_cvt_pk_bf16_f32 v51, v28, v29
	v_add_u32_e32 v28, 0x208, v38
	v_cmp_lt_u32_e32 vcc, 48, v126
	v_cvt_pk_bf16_f32 v48, v30, v31
	v_cvt_pk_bf16_f32 v49, v36, v37
	v_cvt_pk_bf16_f32 v50, v42, v43
	v_lshl_add_u32 v29, v28, 1, 0
	s_and_b64 s[14:15], s[18:19], vcc
	ds_write_b128 v29, v[48:51]
	s_and_saveexec_b64 s[24:25], s[14:15]
	s_cbranch_execz .LBB0_1765
	v_mov_b32_e32 v29, v161
	s_lshl_b32 s21, s16, 2
	v_add_u32_e32 v29, 0, v29
	v_add_u32_e32 v29, 0x201c8, v29
	s_nop 0
	v_subrev_u32_e32 v160, 46, v113
	s_waitcnt lgkmcnt(0)
	v_readlane_b32 s14, v251, 50
	v_readlane_b32 s15, v251, 51
	s_add_u32 s14, s14, s21
	v_lshl_add_u64 v[30:31], s[6:7], 0, v[160:161]
	s_addc_u32 s15, s15, 0
	v_lshlrev_b64 v[30:31], 11, v[30:31]
	v_lshl_add_u64 v[30:31], s[14:15], 0, v[30:31]
	v_lshl_add_u64 v[30:31], v[92:93], 2, v[30:31]
	global_store_dwordx4 v[30:31], v[0:3], off
	global_store_dwordx4 v[30:31], v[4:7], off offset:16
.LBB0_1765:
	s_or_b64 exec, exec, s[24:25]
	v_or_b32_e32 v1, s77, v125
	v_min_u32_e32 v1, 15, v1
	v_add_u32_e32 v1, 1, v1
	v_pk_add_f32 v[30:31], v[12:13], v[114:115] neg_lo:[0,1] neg_hi:[0,1]
	v_cvt_f32_ubyte0_e32 v12, v1
	v_div_scale_f32 v13, s[14:15], v12, v12, 1.0
	v_rcp_f32_e32 v29, v13
	v_pk_add_f32 v[8:9], v[8:9], v[108:109] neg_lo:[0,1] neg_hi:[0,1]
	v_pk_add_f32 v[10:11], v[10:11], v[110:111] neg_lo:[0,1] neg_hi:[0,1]
	v_pk_add_f32 v[14:15], v[14:15], v[116:117] neg_lo:[0,1] neg_hi:[0,1]
	v_fma_f32 v36, -v13, v29, 1.0
	v_fmac_f32_e32 v29, v36, v29
	v_div_scale_f32 v36, vcc, 1.0, v12, 1.0
	v_mul_f32_e32 v37, v36, v29
	v_fma_f32 v38, -v13, v37, v36
	v_fmac_f32_e32 v37, v38, v29
	v_fma_f32 v13, -v13, v37, v36
	v_div_fmas_f32 v13, v13, v29, v37
	s_waitcnt vmcnt(3)
	v_lshlrev_b32_e32 v4, 16, v52
	v_and_b32_e32 v5, 0xffff0000, v52
	v_lshlrev_b32_e32 v6, 16, v53
	v_and_b32_e32 v7, 0xffff0000, v53
	v_lshlrev_b32_e32 v0, 16, v54
	v_and_b32_e32 v1, 0xffff0000, v54
	v_lshlrev_b32_e32 v2, 16, v55
	v_and_b32_e32 v3, 0xffff0000, v55
	v_div_fixup_f32 v12, v13, v12, 1.0
	v_cndmask_b32_e64 v36, v12, v201, s[4:5]
	v_pk_add_f32 v[12:13], v[8:9], v[4:5]
	v_pk_add_f32 v[8:9], v[10:11], v[6:7]
	v_pk_add_f32 v[10:11], v[30:31], v[0:1]
	v_pk_add_f32 v[14:15], v[14:15], v[2:3]
	v_pk_fma_f32 v[38:39], v[36:37], v[12:13], v[4:5] op_sel_hi:[0,1,1] neg_lo:[0,0,1] neg_hi:[0,0,1]
	v_pk_fma_f32 v[42:43], v[36:37], v[8:9], v[6:7] op_sel_hi:[0,1,1] neg_lo:[0,0,1] neg_hi:[0,0,1]
	v_pk_fma_f32 v[30:31], v[36:37], v[10:11], v[0:1] op_sel_hi:[0,1,1] neg_lo:[0,0,1] neg_hi:[0,0,1]
	v_pk_fma_f32 v[48:49], v[36:37], v[14:15], v[2:3] op_sel_hi:[0,1,1] neg_lo:[0,0,1] neg_hi:[0,0,1]
	v_add_u32_e32 v28, 0x208, v28
	v_cvt_pk_bf16_f32 v36, v38, v39
	v_cvt_pk_bf16_f32 v37, v42, v43
	v_cvt_pk_bf16_f32 v38, v30, v31
	v_cvt_pk_bf16_f32 v39, v48, v49
	v_lshl_add_u32 v29, v28, 1, 0
	ds_write_b128 v29, v[36:39]
	s_and_saveexec_b64 s[24:25], s[44:45]
	s_cbranch_execz .LBB0_1767
	v_mov_b32_e32 v29, v161
	s_lshl_b32 s21, s16, 2
	v_add_u32_e32 v29, 0, v29
	v_add_u32_e32 v29, 0x201c8, v29
	s_nop 0
	v_subrev_u32_e32 v160, 45, v113
	s_waitcnt lgkmcnt(0)
	v_readlane_b32 s14, v251, 50
	v_readlane_b32 s15, v251, 51
	s_add_u32 s14, s14, s21
	v_lshl_add_u64 v[30:31], s[6:7], 0, v[160:161]
	s_addc_u32 s15, s15, 0
	v_lshlrev_b64 v[30:31], 11, v[30:31]
	v_lshl_add_u64 v[30:31], s[14:15], 0, v[30:31]
	v_lshl_add_u64 v[30:31], v[92:93], 2, v[30:31]
	global_store_dwordx4 v[30:31], v[4:7], off
	global_store_dwordx4 v[30:31], v[0:3], off offset:16
; #define LAS __attribute__((address_space(3)))
; __device__ __forceinline__ bf16x8 pack8(const float* v) { u32x4 w; w.x = pk2(v[0], v[1]); w.y = pk2(v[2], v[3]); w.z = pk2(v[4], v[5]); w.w = pk2(v[6], v[7]); return __builtin_bit_cast(bf16x8, w); }
; __device__ __forceinline__ void unpack8(u32x4 w, float* v) { v[0] = bflo(w.x); v[1] = bfhi(w.x); v[2] = bflo(w.y); v[3] = bfhi(w.y); v[4] = bflo(w.z); v[5] = bfhi(w.z); v[6] = bflo(w.w); v[7] = bfhi(w.w); }
; template <int W> __device__ __forceinline__ void pool_stage(const Params& p, const bf16_t* z, int layer, bool is_s, int b, int c, int tok0, int g, int half, int lane, LAS unsigned char* L) {
;     ...
;     for (int ti = 0; ti < 8; ++ti) {
;         const int t = t0 + ti; float u[8], ul[8], d[8]; unpack8(raw[W - 1 + ti], u); unpack8(raw[ti], ul);
;         const int cnt = is_s ? W : min(c * 64 + t + 1, W); const float rc = 1.0f / (float)cnt;
; #pragma unroll
;         for (int i = 0; i < 8; ++i) { sum[i] += u[i]; d[i] = sum[i] * rc - u[i]; sum[i] -= ul[i]; }
;         *(LAS bf16x8*)(L + (t * DROW + c0) * 2) = pack8(d);
;         if (t >= 49 && (is_s || c == 31)) { float* o = POUT + (is_s ? O_US : O_UP) + (((size_t)layer * NB + b) * 15 + (t - 49)) * 512 + c0;
;             *(f32x4*)o = (f32x4){u[0], u[1], u[2], u[3]}; *(f32x4*)(o + 4) = (f32x4){u[4], u[5], u[6], u[7]}; }
.LBB0_1767:
	s_or_b64 exec, exec, s[24:25]
	s_nop 0
	v_or_b32_e32 v0, s77, v124
	v_min_u32_e32 v0, 15, v0
	v_add_u32_e32 v0, 1, v0
	v_cvt_f32_ubyte0_e32 v0, v0
	v_div_scale_f32 v1, s[14:15], v0, v0, 1.0
	v_pk_add_f32 v[2:3], v[12:13], v[100:101] neg_lo:[0,1] neg_hi:[0,1]
	v_rcp_f32_e32 v12, v1
	v_pk_add_f32 v[4:5], v[8:9], v[102:103] neg_lo:[0,1] neg_hi:[0,1]
	v_pk_add_f32 v[6:7], v[10:11], v[104:105] neg_lo:[0,1] neg_hi:[0,1]
	v_pk_add_f32 v[14:15], v[14:15], v[106:107] neg_lo:[0,1] neg_hi:[0,1]
	v_fma_f32 v8, -v1, v12, 1.0
	v_fmac_f32_e32 v12, v8, v12
	v_div_scale_f32 v8, vcc, 1.0, v0, 1.0
	v_mul_f32_e32 v9, v8, v12
	v_fma_f32 v10, -v1, v9, v8
	v_fmac_f32_e32 v9, v10, v12
	v_fma_f32 v1, -v1, v9, v8
	v_div_fmas_f32 v1, v1, v12, v9
	v_div_fixup_f32 v0, v1, v0, 1.0
	v_cndmask_b32_e64 v30, v0, v201, s[4:5]
	s_waitcnt vmcnt(2)
	v_lshlrev_b32_e32 v0, 16, v44
	v_and_b32_e32 v1, 0xffff0000, v44
	v_pk_add_f32 v[10:11], v[2:3], v[0:1]
	v_lshlrev_b32_e32 v2, 16, v45
	v_and_b32_e32 v3, 0xffff0000, v45
	v_pk_add_f32 v[8:9], v[4:5], v[2:3]
	v_lshlrev_b32_e32 v4, 16, v46
	v_and_b32_e32 v5, 0xffff0000, v46
	v_pk_add_f32 v[12:13], v[6:7], v[4:5]
	v_lshlrev_b32_e32 v6, 16, v47
	v_and_b32_e32 v7, 0xffff0000, v47
	v_pk_add_f32 v[14:15], v[14:15], v[6:7]
	v_pk_fma_f32 v[36:37], v[30:31], v[10:11], v[0:1] op_sel_hi:[0,1,1] neg_lo:[0,0,1] neg_hi:[0,0,1]
	v_pk_fma_f32 v[38:39], v[30:31], v[8:9], v[2:3] op_sel_hi:[0,1,1] neg_lo:[0,0,1] neg_hi:[0,0,1]
	v_pk_fma_f32 v[42:43], v[30:31], v[12:13], v[4:5] op_sel_hi:[0,1,1] neg_lo:[0,0,1] neg_hi:[0,0,1]
	v_pk_fma_f32 v[30:31], v[30:31], v[14:15], v[6:7] op_sel_hi:[0,1,1] neg_lo:[0,0,1] neg_hi:[0,0,1]
	v_add_u32_e32 v28, 0x208, v28
	v_cmp_lt_u32_e32 vcc, 48, v124
	v_cvt_pk_bf16_f32 v36, v36, v37
	v_cvt_pk_bf16_f32 v37, v38, v39
	v_cvt_pk_bf16_f32 v38, v42, v43
	v_cvt_pk_bf16_f32 v39, v30, v31
	v_lshl_add_u32 v29, v28, 1, 0
	s_and_b64 s[14:15], s[18:19], vcc
	ds_write_b128 v29, v[36:39]
	s_and_saveexec_b64 s[24:25], s[14:15]
	s_cbranch_execz .LBB0_1769
	v_mov_b32_e32 v29, v161
	s_lshl_b32 s21, s16, 2
	v_add_u32_e32 v29, 0, v29
	v_add_u32_e32 v29, 0x201c8, v29
	s_nop 0
	v_subrev_u32_e32 v160, 44, v113
	s_waitcnt lgkmcnt(0)
	v_readlane_b32 s14, v251, 50
	v_readlane_b32 s15, v251, 51
	s_add_u32 s14, s14, s21
	v_lshl_add_u64 v[30:31], s[6:7], 0, v[160:161]
	s_addc_u32 s15, s15, 0
	v_lshlrev_b64 v[30:31], 11, v[30:31]
	v_lshl_add_u64 v[30:31], s[14:15], 0, v[30:31]
	v_lshl_add_u64 v[30:31], v[92:93], 2, v[30:31]
	global_store_dwordx4 v[30:31], v[0:3], off
	global_store_dwordx4 v[30:31], v[4:7], off offset:16
; #define LAS __attribute__((address_space(3)))
; __device__ __forceinline__ bf16x8 pack8(const float* v) { u32x4 w; w.x = pk2(v[0], v[1]); w.y = pk2(v[2], v[3]); w.z = pk2(v[4], v[5]); w.w = pk2(v[6], v[7]); return __builtin_bit_cast(bf16x8, w); }
; __device__ __forceinline__ void unpack8(u32x4 w, float* v) { v[0] = bflo(w.x); v[1] = bfhi(w.x); v[2] = bflo(w.y); v[3] = bfhi(w.y); v[4] = bflo(w.z); v[5] = bfhi(w.z); v[6] = bflo(w.w); v[7] = bfhi(w.w); }
; template <int W> __device__ __forceinline__ void pool_stage(const Params& p, const bf16_t* z, int layer, bool is_s, int b, int c, int tok0, int g, int half, int lane, LAS unsigned char* L) {
;     ...
;     for (int ti = 0; ti < 8; ++ti) {
;         const int t = t0 + ti; float u[8], ul[8], d[8]; unpack8(raw[W - 1 + ti], u); unpack8(raw[ti], ul);
;         const int cnt = is_s ? W : min(c * 64 + t + 1, W); const float rc = 1.0f / (float)cnt;
; #pragma unroll
;         for (int i = 0; i < 8; ++i) { sum[i] += u[i]; d[i] = sum[i] * rc - u[i]; sum[i] -= ul[i]; }
;         *(LAS bf16x8*)(L + (t * DROW + c0) * 2) = pack8(d);
;         if (t >= 49 && (is_s || c == 31)) { float* o = POUT + (is_s ? O_US : O_UP) + (((size_t)layer * NB + b) * 15 + (t - 49)) * 512 + c0;
;             *(f32x4*)o = (f32x4){u[0], u[1], u[2], u[3]}; *(f32x4*)(o + 4) = (f32x4){u[4], u[5], u[6], u[7]}; }
.LBB0_1769:
	s_or_b64 exec, exec, s[24:25]
	v_or_b32_e32 v0, s77, v123
	v_min_u32_e32 v0, 15, v0
	v_add_u32_e32 v0, 1, v0
	v_cvt_f32_ubyte0_e32 v0, v0
	v_div_scale_f32 v1, s[14:15], v0, v0, 1.0
	v_pk_add_f32 v[2:3], v[10:11], v[96:97] neg_lo:[0,1] neg_hi:[0,1]
	v_rcp_f32_e32 v10, v1
	v_pk_add_f32 v[4:5], v[8:9], v[98:99] neg_lo:[0,1] neg_hi:[0,1]
	v_pk_add_f32 v[14:15], v[14:15], v[26:27] neg_lo:[0,1] neg_hi:[0,1]
	v_pk_add_f32 v[6:7], v[12:13], v[40:41] neg_lo:[0,1] neg_hi:[0,1]
	v_fma_f32 v8, -v1, v10, 1.0
	v_fmac_f32_e32 v10, v8, v10
	v_div_scale_f32 v8, vcc, 1.0, v0, 1.0
	v_mul_f32_e32 v9, v8, v10
	v_fma_f32 v11, -v1, v9, v8
	v_fmac_f32_e32 v9, v11, v10
	v_fma_f32 v1, -v1, v9, v8
	v_div_fmas_f32 v1, v1, v10, v9
	v_div_fixup_f32 v0, v1, v0, 1.0
	v_cndmask_b32_e64 v26, v0, v201, s[4:5]
	s_waitcnt vmcnt(1)
	v_lshlrev_b32_e32 v0, 16, v32
	v_and_b32_e32 v1, 0xffff0000, v32
	v_pk_add_f32 v[8:9], v[2:3], v[0:1]
	v_lshlrev_b32_e32 v2, 16, v33
	v_and_b32_e32 v3, 0xffff0000, v33
	v_pk_add_f32 v[10:11], v[4:5], v[2:3]
	v_lshlrev_b32_e32 v4, 16, v34
	v_and_b32_e32 v5, 0xffff0000, v34
	v_pk_add_f32 v[12:13], v[6:7], v[4:5]
	v_lshlrev_b32_e32 v6, 16, v35
	v_and_b32_e32 v7, 0xffff0000, v35
	v_pk_add_f32 v[14:15], v[14:15], v[6:7]
	v_pk_fma_f32 v[30:31], v[26:27], v[8:9], v[0:1] op_sel_hi:[0,1,1] neg_lo:[0,0,1] neg_hi:[0,0,1]
	v_pk_fma_f32 v[32:33], v[26:27], v[10:11], v[2:3] op_sel_hi:[0,1,1] neg_lo:[0,0,1] neg_hi:[0,0,1]
	v_pk_fma_f32 v[36:37], v[26:27], v[12:13], v[4:5] op_sel_hi:[0,1,1] neg_lo:[0,0,1] neg_hi:[0,0,1]
	v_pk_fma_f32 v[26:27], v[26:27], v[14:15], v[6:7] op_sel_hi:[0,1,1] neg_lo:[0,0,1] neg_hi:[0,0,1]
	v_cvt_pk_bf16_f32 v30, v30, v31
	v_cvt_pk_bf16_f32 v31, v32, v33
	v_cvt_pk_bf16_f32 v33, v26, v27
	v_add_u32_e32 v26, 0x208, v28
	v_cmp_lt_u32_e32 vcc, 48, v123
	v_cvt_pk_bf16_f32 v32, v36, v37
	v_lshl_add_u32 v26, v26, 1, 0
	s_and_b64 s[14:15], s[18:19], vcc
	ds_write_b128 v26, v[30:33]
	s_and_saveexec_b64 s[24:25], s[14:15]
	s_cbranch_execz .LBB0_1771
	v_mov_b32_e32 v27, v161
	s_lshl_b32 s21, s16, 2
	v_add_u32_e32 v27, 0, v27
	v_add_u32_e32 v27, 0x201c8, v27
	s_nop 0
	v_subrev_u32_e32 v160, 43, v113
	s_waitcnt lgkmcnt(0)
	v_readlane_b32 s14, v251, 50
	v_readlane_b32 s15, v251, 51
	s_add_u32 s14, s14, s21
	v_lshl_add_u64 v[28:29], s[6:7], 0, v[160:161]
	s_addc_u32 s15, s15, 0
	v_lshlrev_b64 v[28:29], 11, v[28:29]
	v_lshl_add_u64 v[28:29], s[14:15], 0, v[28:29]
	v_lshl_add_u64 v[28:29], v[92:93], 2, v[28:29]
	global_store_dwordx4 v[28:29], v[0:3], off
	global_store_dwordx4 v[28:29], v[4:7], off offset:16
.LBB0_1771:
	s_or_b64 exec, exec, s[24:25]
	v_pk_add_f32 v[0:1], v[8:9], v[94:95] neg_lo:[0,1] neg_hi:[0,1]
	v_or_b32_e32 v8, s77, v122
	v_min_u32_e32 v8, 15, v8
	v_add_u32_e32 v8, 1, v8
	v_cvt_f32_ubyte0_e32 v8, v8
	v_div_scale_f32 v9, s[14:15], v8, v8, 1.0
	v_pk_add_f32 v[2:3], v[10:11], v[16:17] neg_lo:[0,1] neg_hi:[0,1]
	v_rcp_f32_e32 v10, v9
	v_pk_add_f32 v[4:5], v[12:13], v[24:25] neg_lo:[0,1] neg_hi:[0,1]
	v_pk_add_f32 v[6:7], v[14:15], v[18:19] neg_lo:[0,1] neg_hi:[0,1]
	v_fma_f32 v11, -v9, v10, 1.0
	v_fmac_f32_e32 v10, v11, v10
	v_div_scale_f32 v11, vcc, 1.0, v8, 1.0
	v_mul_f32_e32 v12, v11, v10
	v_fma_f32 v13, -v9, v12, v11
	v_fmac_f32_e32 v12, v13, v10
	v_fma_f32 v9, -v9, v12, v11
	v_div_fmas_f32 v9, v9, v10, v12
	v_div_fixup_f32 v8, v9, v8, 1.0
	v_cndmask_b32_e64 v12, v8, v201, s[4:5]
	s_waitcnt vmcnt(0)
	v_lshlrev_b32_e32 v8, 16, v20
	v_and_b32_e32 v9, 0xffff0000, v20
	v_pk_add_f32 v[0:1], v[0:1], v[8:9]
	v_lshlrev_b32_e32 v10, 16, v21
	v_and_b32_e32 v11, 0xffff0000, v21
	v_pk_fma_f32 v[14:15], v[12:13], v[0:1], v[8:9] op_sel_hi:[0,1,1] neg_lo:[0,0,1] neg_hi:[0,0,1]
	v_pk_add_f32 v[0:1], v[2:3], v[10:11]
	v_cmp_lt_u32_e32 vcc, 48, v122
	v_pk_fma_f32 v[16:17], v[12:13], v[0:1], v[10:11] op_sel_hi:[0,1,1] neg_lo:[0,0,1] neg_hi:[0,0,1]
	v_lshlrev_b32_e32 v0, 16, v22
	v_and_b32_e32 v1, 0xffff0000, v22
	v_pk_add_f32 v[2:3], v[4:5], v[0:1]
	s_and_b64 s[14:15], s[18:19], vcc
	v_pk_fma_f32 v[18:19], v[12:13], v[2:3], v[0:1] op_sel_hi:[0,1,1] neg_lo:[0,0,1] neg_hi:[0,0,1]
	v_lshlrev_b32_e32 v2, 16, v23
	v_and_b32_e32 v3, 0xffff0000, v23
	v_pk_add_f32 v[4:5], v[6:7], v[2:3]
	v_cvt_pk_bf16_f32 v6, v18, v19
	v_pk_fma_f32 v[12:13], v[12:13], v[4:5], v[2:3] op_sel_hi:[0,1,1] neg_lo:[0,0,1] neg_hi:[0,0,1]
	v_cvt_pk_bf16_f32 v4, v14, v15
	v_cvt_pk_bf16_f32 v5, v16, v17
	v_cvt_pk_bf16_f32 v7, v12, v13
	ds_write_b128 v26, v[4:7] offset:1040
	s_and_saveexec_b64 s[18:19], s[14:15]
	s_xor_b64 s[18:19], exec, s[18:19]
	s_cbranch_execz .LBB0_1773
	v_mov_b32_e32 v4, v161
	s_or_b64 s[10:11], s[10:11], exec
	v_add_u32_e32 v4, 0, v4
	v_add_u32_e32 v4, 0x201c8, v4
	s_nop 0
	s_waitcnt lgkmcnt(0)
	v_readlane_b32 s25, v251, 51
	v_readlane_b32 s24, v251, 50

; #define LAS __attribute__((address_space(3)))
; #define PIN(i) ((const float*)ldq_(L, (i)))
; __device__ __forceinline__ unsigned pk2(float lo, float hi) { f32x2 v = {lo, hi}; bf16x2_t b = __builtin_convertvector(v, bf16x2_t); return __builtin_bit_cast(unsigned, b); }
; template <int W> __device__ __forceinline__ void pool_stage(const Params& p, const bf16_t* z, int layer, bool is_s, int b, int c, int tok0, int g, int half, int lane, LAS unsigned char* L) {
;     const int oct = lane & 15, tq = lane >> 4, c0 = 128 * g + 8 * oct, t0 = 32 * half + 8 * tq;
;     const float* sp = PIN(I_SP) + ((size_t)layer * NB + b) * 15 * 512 + c0;
;     u32x4 raw[W + 7];
; #pragma unroll
;     for (int j = 0; j < W + 7; ++j) {
;         const int t = t0 - (W - 1) + j;
;         u32x4 r = {0u, 0u, 0u, 0u};
;         if (t >= 0 || (!is_s && c * 64 + t >= 0)) r = *(const u32x4*)(z + (size_t)(tok0 + t) * NIN + 768 + c0);
;         else if (is_s) { const f32x4 a = *(const f32x4*)(sp + (15 + t) * 512), bb = *(const f32x4*)(sp + (15 + t) * 512 + 4); r.x = pk2(a[0], a[1]); r.y = pk2(a[2], a[3]); r.z = pk2(bb[0], bb[1]); r.w = pk2(bb[2], bb[3]); }
;         raw[j] = r;
.LBB0_1775:
	v_mov_b32_e32 v0, v161
	v_lshrrev_b32_e32 v2, 1, v178
	v_add_u32_e32 v0, 0, v0
	v_add_u32_e32 v0, 0x20130, v0
	s_nop 0
	v_and_b32_e32 v2, 24, v2
	v_lshl_or_b32 v113, s52, 5, v2
	s_mov_b64 s[24:25], -1
	s_mov_b64 s[6:7], 0
	s_waitcnt lgkmcnt(0)
	v_readlane_b32 s14, v251, 13
	v_readlane_b32 s15, v251, 12
	v_subrev_co_u32_e32 v1, vcc, 1, v113
	s_and_saveexec_b64 s[18:19], vcc
	s_cbranch_execz .LBB0_1780
	s_and_b64 vcc, exec, s[40:41]
	s_cbranch_vccz .LBB0_1778
	s_cmp_lg_u32 s76, 0
	s_cselect_b64 s[24:25], -1, 0
	s_branch .LBB0_1779

; #define LAS __attribute__((address_space(3)))
; __device__ __forceinline__ unsigned pk2(float lo, float hi) { f32x2 v = {lo, hi}; bf16x2_t b = __builtin_convertvector(v, bf16x2_t); return __builtin_bit_cast(unsigned, b); }
; __device__ __forceinline__ bf16x8 pack8(const float* v) { u32x4 w; w.x = pk2(v[0], v[1]); w.y = pk2(v[2], v[3]); w.z = pk2(v[4], v[5]); w.w = pk2(v[6], v[7]); return __builtin_bit_cast(bf16x8, w); }
; __device__ __forceinline__ void unpack8(u32x4 w, float* v) { v[0] = bflo(w.x); v[1] = bfhi(w.x); v[2] = bflo(w.y); v[3] = bfhi(w.y); v[4] = bflo(w.z); v[5] = bfhi(w.z); v[6] = bflo(w.w); v[7] = bfhi(w.w); }
; template <int W> __device__ __forceinline__ void pool_stage(const Params& p, const bf16_t* z, int layer, bool is_s, int b, int c, int tok0, int g, int half, int lane, LAS unsigned char* L) {
;     ...
;     for (int j = 0; j < W + 7; ++j) {
;         const int t = t0 - (W - 1) + j;
;         u32x4 r = {0u, 0u, 0u, 0u};
;         if (t >= 0 || (!is_s && c * 64 + t >= 0)) r = *(const u32x4*)(z + (size_t)(tok0 + t) * NIN + 768 + c0);
;         else if (is_s) { const f32x4 a = *(const f32x4*)(sp + (15 + t) * 512), bb = *(const f32x4*)(sp + (15 + t) * 512 + 4); r.x = pk2(a[0], a[1]); r.y = pk2(a[2], a[3]); r.z = pk2(bb[0], bb[1]); r.w = pk2(bb[2], bb[3]); }
;         raw[j] = r;
;     }
;     float sum[8];
; #pragma unroll
;     for (int i = 0; i < 8; ++i) sum[i] = 0.f;
; #pragma unroll
;     for (int j = 0; j < W - 1; ++j) { float u[8]; unpack8(raw[j], u);
; #pragma unroll
;         for (int i = 0; i < 8; ++i) sum[i] += u[i]; }
; #pragma unroll
;     for (int ti = 0; ti < 8; ++ti) {
;         const int t = t0 + ti; float u[8], ul[8], d[8]; unpack8(raw[W - 1 + ti], u); unpack8(raw[ti], ul);
;         const int cnt = is_s ? W : min(c * 64 + t + 1, W); const float rc = 1.0f / (float)cnt;
; #pragma unroll
;         for (int i = 0; i < 8; ++i) { sum[i] += u[i]; d[i] = sum[i] * rc - u[i]; sum[i] -= ul[i]; }
;         *(LAS bf16x8*)(L + (t * DROW + c0) * 2) = pack8(d);
;         if (t >= 49 && (is_s || c == 31)) { float* o = POUT + (is_s ? O_US : O_UP) + (((size_t)layer * NB + b) * 15 + (t - 49)) * 512 + c0;
;             *(f32x4*)o = (f32x4){u[0], u[1], u[2], u[3]}; *(f32x4*)(o + 4) = (f32x4){u[4], u[5], u[6], u[7]}; }
.LBB0_1784:
	s_or_b64 exec, exec, s[18:19]
	v_add_u32_e32 v8, s67, v113
	v_mov_b64_e32 v[2:3], s[34:35]
	v_add_u32_e32 v6, 1, v8
	v_mad_i64_i32 v[4:5], s[6:7], v8, s84, v[2:3]
	v_mov_b32_e32 v1, v161
	v_mad_i64_i32 v[6:7], s[6:7], v6, s84, v[2:3]
	v_lshl_add_u64 v[4:5], v[4:5], 0, v[0:1]
	v_lshl_add_u64 v[6:7], v[6:7], 0, v[0:1]
	v_or_b32_e32 v57, 3, v113
	global_load_dwordx4 v[36:39], v[4:5], off offset:1536
	global_load_dwordx4 v[24:27], v[6:7], off offset:1536
	v_add_u32_e32 v4, 2, v8
	v_add_u32_e32 v6, s67, v57
	v_mad_i64_i32 v[4:5], s[6:7], v4, s84, v[2:3]
	v_mad_i64_i32 v[6:7], s[6:7], v6, s84, v[2:3]
	v_lshl_add_u64 v[4:5], v[4:5], 0, v[0:1]
	v_lshl_add_u64 v[6:7], v[6:7], 0, v[0:1]
	v_or_b32_e32 v56, 5, v113
	global_load_dwordx4 v[20:23], v[4:5], off offset:1536
	global_load_dwordx4 v[16:19], v[6:7], off offset:1536
	v_add_u32_e32 v4, 4, v8
	v_add_u32_e32 v6, s67, v56
	v_mad_i64_i32 v[4:5], s[6:7], v4, s84, v[2:3]
	v_mad_i64_i32 v[6:7], s[6:7], v6, s84, v[2:3]
	v_lshl_add_u64 v[4:5], v[4:5], 0, v[0:1]
	v_lshl_add_u64 v[6:7], v[6:7], 0, v[0:1]
	v_or_b32_e32 v55, 6, v113
	v_or_b32_e32 v54, 7, v113
	global_load_dwordx4 v[12:15], v[4:5], off offset:1536
	global_load_dwordx4 v[8:11], v[6:7], off offset:1536
	v_add_u32_e32 v4, s67, v55
	v_add_u32_e32 v6, s67, v54
	v_mad_i64_i32 v[4:5], s[6:7], v4, s84, v[2:3]
	v_mad_i64_i32 v[2:3], s[6:7], v6, s84, v[2:3]
	v_lshl_add_u64 v[4:5], v[4:5], 0, v[0:1]
	v_lshl_add_u64 v[0:1], v[2:3], 0, v[0:1]
	global_load_dwordx4 v[4:7], v[4:5], off offset:1536
	s_nop 0
	global_load_dwordx4 v[0:3], v[0:1], off offset:1536
	s_mul_i32 s7, s43, 15
	s_mul_hi_u32 s14, s42, 15
	s_add_i32 s7, s14, s7
	v_or_b32_e32 v32, s76, v113
	s_cmp_eq_u32 s76, 31
	v_cmp_eq_u32_e32 vcc, 0, v32
	s_cselect_b64 s[14:15], -1, 0
	s_waitcnt vmcnt(8)
	v_lshlrev_b32_e32 v40, 16, v28
	v_and_b32_e32 v41, 0xffff0000, v28
	v_lshlrev_b32_e32 v28, 16, v29
	v_and_b32_e32 v29, 0xffff0000, v29
	v_lshlrev_b32_e32 v42, 16, v30
	v_and_b32_e32 v43, 0xffff0000, v30
	v_lshlrev_b32_e32 v30, 16, v31
	v_and_b32_e32 v31, 0xffff0000, v31
	v_cndmask_b32_e64 v32, 0.5, 1.0, vcc
	s_or_b64 s[18:19], s[4:5], s[14:15]
	v_pk_add_f32 v[46:47], v[40:41], 0 op_sel_hi:[1,0]
	v_pk_add_f32 v[48:49], v[28:29], 0 op_sel_hi:[1,0]
	v_pk_add_f32 v[50:51], v[42:43], 0 op_sel_hi:[1,0]
	v_pk_add_f32 v[52:53], v[30:31], 0 op_sel_hi:[1,0]
	v_cndmask_b32_e64 v58, v32, 0.5, s[4:5]
	s_and_b64 s[4:5], s[4:5], exec
	s_mov_b32 s4, 0x4678000
	s_cselect_b32 s16, s4, 0x4400000
	s_movk_i32 s4, 0x208
	v_cmp_lt_u32_e32 vcc, 48, v113
	s_mul_i32 s6, s42, 15
	s_and_b64 s[14:15], vcc, s[18:19]
	s_waitcnt vmcnt(7)
	v_lshlrev_b32_e32 v32, 16, v36
	v_and_b32_e32 v33, 0xffff0000, v36
	v_lshlrev_b32_e32 v34, 16, v37
	v_and_b32_e32 v35, 0xffff0000, v37
	v_lshlrev_b32_e32 v36, 16, v38
	v_and_b32_e32 v37, 0xffff0000, v38
	v_lshlrev_b32_e32 v38, 16, v39
	v_and_b32_e32 v39, 0xffff0000, v39
	v_pk_add_f32 v[46:47], v[46:47], v[32:33]
	v_pk_add_f32 v[48:49], v[48:49], v[34:35]
	v_pk_add_f32 v[50:51], v[50:51], v[36:37]
	v_pk_add_f32 v[52:53], v[52:53], v[38:39]
	v_pk_fma_f32 v[60:61], v[58:59], v[46:47], v[32:33] op_sel_hi:[0,1,1] neg_lo:[0,0,1] neg_hi:[0,0,1]
	v_pk_fma_f32 v[62:63], v[58:59], v[48:49], v[34:35] op_sel_hi:[0,1,1] neg_lo:[0,0,1] neg_hi:[0,0,1]
	v_pk_fma_f32 v[64:65], v[58:59], v[50:51], v[36:37] op_sel_hi:[0,1,1] neg_lo:[0,0,1] neg_hi:[0,0,1]
	v_pk_fma_f32 v[58:59], v[58:59], v[52:53], v[38:39] op_sel_hi:[0,1,1] neg_lo:[0,0,1] neg_hi:[0,0,1]
	v_cvt_pk_bf16_f32 v60, v60, v61
	v_cvt_pk_bf16_f32 v61, v62, v63
	v_cvt_pk_bf16_f32 v63, v58, v59
	v_mad_u64_u32 v[58:59], s[4:5], v113, s4, v[160:161]
	v_cvt_pk_bf16_f32 v62, v64, v65
	v_lshl_add_u32 v58, v58, 1, 0
	ds_write_b128 v58, v[60:63]
	s_and_saveexec_b64 s[4:5], s[14:15]
	s_cbranch_execz .LBB0_1786
	v_mov_b32_e32 v45, v161
	s_lshl_b32 s14, s16, 2
	v_add_u32_e32 v45, 0, v45
	v_add_u32_e32 v45, 0x201c8, v45
	s_nop 0
	v_subrev_u32_e32 v62, 49, v113
	v_mov_b32_e32 v63, v161
	v_mov_b32_e32 v45, v161
	s_waitcnt lgkmcnt(0)
	v_readlane_b32 s21, v251, 50
	v_readlane_b32 s15, v251, 51
	s_add_u32 s14, s21, s14
	v_lshl_add_u64 v[60:61], s[6:7], 0, v[62:63]
	s_addc_u32 s15, s15, 0
	v_lshlrev_b64 v[60:61], 11, v[60:61]
	v_lshl_add_u64 v[60:61], s[14:15], 0, v[60:61]
	v_lshl_add_u64 v[60:61], v[60:61], 0, v[44:45]
	global_store_dwordx4 v[60:61], v[32:35], off
	global_store_dwordx4 v[60:61], v[36:39], off offset:16
.LBB0_1786:
	s_or_b64 exec, exec, s[4:5]
	v_pk_add_f32 v[40:41], v[46:47], v[40:41] neg_lo:[0,1] neg_hi:[0,1]
	v_pk_add_f32 v[48:49], v[48:49], v[28:29] neg_lo:[0,1] neg_hi:[0,1]
	s_waitcnt vmcnt(6)
	v_lshlrev_b32_e32 v28, 16, v24
	v_and_b32_e32 v29, 0xffff0000, v24
	v_pk_add_f32 v[42:43], v[50:51], v[42:43] neg_lo:[0,1] neg_hi:[0,1]
	v_pk_add_f32 v[50:51], v[52:53], v[30:31] neg_lo:[0,1] neg_hi:[0,1]
	v_pk_add_f32 v[46:47], v[40:41], v[28:29]
	v_lshlrev_b32_e32 v30, 16, v25
	v_and_b32_e32 v31, 0xffff0000, v25
	v_lshlrev_b32_e32 v40, 16, v26
	v_and_b32_e32 v41, 0xffff0000, v26
	v_pk_add_f32 v[24:25], v[48:49], v[30:31]
	v_pk_add_f32 v[48:49], v[42:43], v[40:41]
	v_lshlrev_b32_e32 v42, 16, v27
	v_and_b32_e32 v43, 0xffff0000, v27
	v_pk_add_f32 v[26:27], v[50:51], v[42:43]
	v_pk_fma_f32 v[52:53], v[46:47], 0.5, v[28:29] op_sel_hi:[1,0,1] neg_lo:[0,0,1] neg_hi:[0,0,1]
	v_pk_fma_f32 v[60:61], v[24:25], 0.5, v[30:31] op_sel_hi:[1,0,1] neg_lo:[0,0,1] neg_hi:[0,0,1]
	v_pk_fma_f32 v[62:63], v[48:49], 0.5, v[40:41] op_sel_hi:[1,0,1] neg_lo:[0,0,1] neg_hi:[0,0,1]
	v_pk_fma_f32 v[64:65], v[26:27], 0.5, v[42:43] op_sel_hi:[1,0,1] neg_lo:[0,0,1] neg_hi:[0,0,1]
	v_cmp_lt_u32_e32 vcc, 47, v113
	v_cvt_pk_bf16_f32 v50, v52, v53
	v_cvt_pk_bf16_f32 v51, v60, v61
	v_cvt_pk_bf16_f32 v52, v62, v63
	v_cvt_pk_bf16_f32 v53, v64, v65
	s_and_b64 s[4:5], vcc, s[18:19]
	ds_write_b128 v58, v[50:53] offset:1040
	s_and_saveexec_b64 s[24:25], s[4:5]
	s_cbranch_execz .LBB0_1788
	v_mov_b32_e32 v45, v161
	s_lshl_b32 s14, s16, 2
	v_add_u32_e32 v45, 0, v45
	v_add_u32_e32 v45, 0x201c8, v45
	s_nop 0
	v_subrev_u32_e32 v52, 48, v113
	v_mov_b32_e32 v53, v161
	v_mov_b32_e32 v45, v161
	s_waitcnt lgkmcnt(0)
	v_readlane_b32 s21, v251, 50
	v_readlane_b32 s15, v251, 51
	s_add_u32 s14, s21, s14
	v_lshl_add_u64 v[50:51], s[6:7], 0, v[52:53]
	s_addc_u32 s15, s15, 0
	v_lshlrev_b64 v[50:51], 11, v[50:51]
	v_lshl_add_u64 v[50:51], s[14:15], 0, v[50:51]
	v_lshl_add_u64 v[50:51], v[50:51], 0, v[44:45]
	global_store_dwordx4 v[50:51], v[28:31], off
	global_store_dwordx4 v[50:51], v[40:43], off offset:16
; #define LAS __attribute__((address_space(3)))
; __device__ __forceinline__ bf16x8 pack8(const float* v) { u32x4 w; w.x = pk2(v[0], v[1]); w.y = pk2(v[2], v[3]); w.z = pk2(v[4], v[5]); w.w = pk2(v[6], v[7]); return __builtin_bit_cast(bf16x8, w); }
; __device__ __forceinline__ void unpack8(u32x4 w, float* v) { v[0] = bflo(w.x); v[1] = bfhi(w.x); v[2] = bflo(w.y); v[3] = bfhi(w.y); v[4] = bflo(w.z); v[5] = bfhi(w.z); v[6] = bflo(w.w); v[7] = bfhi(w.w); }
; template <int W> __device__ __forceinline__ void pool_stage(const Params& p, const bf16_t* z, int layer, bool is_s, int b, int c, int tok0, int g, int half, int lane, LAS unsigned char* L) {
;     ...
;     for (int ti = 0; ti < 8; ++ti) {
;         const int t = t0 + ti; float u[8], ul[8], d[8]; unpack8(raw[W - 1 + ti], u); unpack8(raw[ti], ul);
;         const int cnt = is_s ? W : min(c * 64 + t + 1, W); const float rc = 1.0f / (float)cnt;
; #pragma unroll
;         for (int i = 0; i < 8; ++i) { sum[i] += u[i]; d[i] = sum[i] * rc - u[i]; sum[i] -= ul[i]; }
;         *(LAS bf16x8*)(L + (t * DROW + c0) * 2) = pack8(d);
;         if (t >= 49 && (is_s || c == 31)) { float* o = POUT + (is_s ? O_US : O_UP) + (((size_t)layer * NB + b) * 15 + (t - 49)) * 512 + c0;
;             *(f32x4*)o = (f32x4){u[0], u[1], u[2], u[3]}; *(f32x4*)(o + 4) = (f32x4){u[4], u[5], u[6], u[7]}; }
.LBB0_1788:
	s_or_b64 exec, exec, s[24:25]
	v_pk_add_f32 v[46:47], v[46:47], v[32:33] neg_lo:[0,1] neg_hi:[0,1]
	v_pk_add_f32 v[50:51], v[24:25], v[34:35] neg_lo:[0,1] neg_hi:[0,1]
	v_pk_add_f32 v[36:37], v[48:49], v[36:37] neg_lo:[0,1] neg_hi:[0,1]
	v_pk_add_f32 v[38:39], v[26:27], v[38:39] neg_lo:[0,1] neg_hi:[0,1]
	s_waitcnt vmcnt(5)
	v_lshlrev_b32_e32 v24, 16, v20
	v_and_b32_e32 v25, 0xffff0000, v20
	v_lshlrev_b32_e32 v26, 16, v21
	v_and_b32_e32 v27, 0xffff0000, v21
	v_lshlrev_b32_e32 v32, 16, v22
	v_and_b32_e32 v33, 0xffff0000, v22
	v_lshlrev_b32_e32 v34, 16, v23
	v_and_b32_e32 v35, 0xffff0000, v23
	v_pk_add_f32 v[20:21], v[46:47], v[24:25]
	v_pk_add_f32 v[22:23], v[50:51], v[26:27]
	v_pk_add_f32 v[36:37], v[36:37], v[32:33]
	v_pk_add_f32 v[38:39], v[38:39], v[34:35]
	v_pk_fma_f32 v[46:47], v[20:21], 0.5, v[24:25] op_sel_hi:[1,0,1] neg_lo:[0,0,1] neg_hi:[0,0,1]
	v_pk_fma_f32 v[48:49], v[22:23], 0.5, v[26:27] op_sel_hi:[1,0,1] neg_lo:[0,0,1] neg_hi:[0,0,1]
	v_pk_fma_f32 v[50:51], v[36:37], 0.5, v[32:33] op_sel_hi:[1,0,1] neg_lo:[0,0,1] neg_hi:[0,0,1]
	v_pk_fma_f32 v[52:53], v[38:39], 0.5, v[34:35] op_sel_hi:[1,0,1] neg_lo:[0,0,1] neg_hi:[0,0,1]
	v_cvt_pk_bf16_f32 v46, v46, v47
	v_cvt_pk_bf16_f32 v47, v48, v49
	v_cvt_pk_bf16_f32 v48, v50, v51
	v_cvt_pk_bf16_f32 v49, v52, v53
	ds_write_b128 v58, v[46:49] offset:2080
	s_and_saveexec_b64 s[24:25], s[4:5]
	s_cbranch_execz .LBB0_1790
	v_mov_b32_e32 v45, v161
	s_lshl_b32 s14, s16, 2
	v_add_u32_e32 v45, 0, v45
	v_add_u32_e32 v45, 0x201c8, v45
	s_nop 0
	v_subrev_u32_e32 v48, 47, v113
	v_mov_b32_e32 v49, v161
	v_mov_b32_e32 v45, v161
	s_waitcnt lgkmcnt(0)
	v_readlane_b32 s21, v251, 50
	v_readlane_b32 s15, v251, 51
	s_add_u32 s14, s21, s14
	v_lshl_add_u64 v[46:47], s[6:7], 0, v[48:49]
	s_addc_u32 s15, s15, 0
	v_lshlrev_b64 v[46:47], 11, v[46:47]
	v_lshl_add_u64 v[46:47], s[14:15], 0, v[46:47]
	v_lshl_add_u64 v[46:47], v[46:47], 0, v[44:45]
	global_store_dwordx4 v[46:47], v[24:27], off
	global_store_dwordx4 v[46:47], v[32:35], off offset:16
.LBB0_1790:
	s_or_b64 exec, exec, s[24:25]
	v_pk_add_f32 v[28:29], v[20:21], v[28:29] neg_lo:[0,1] neg_hi:[0,1]
	s_waitcnt vmcnt(4)
	v_lshlrev_b32_e32 v20, 16, v16
	v_and_b32_e32 v21, 0xffff0000, v16
	v_pk_add_f32 v[30:31], v[22:23], v[30:31] neg_lo:[0,1] neg_hi:[0,1]
	v_pk_add_f32 v[36:37], v[36:37], v[40:41] neg_lo:[0,1] neg_hi:[0,1]
	v_pk_add_f32 v[42:43], v[38:39], v[42:43] neg_lo:[0,1] neg_hi:[0,1]
	v_pk_add_f32 v[38:39], v[28:29], v[20:21]
	v_lshlrev_b32_e32 v22, 16, v17
	v_and_b32_e32 v23, 0xffff0000, v17
	v_lshlrev_b32_e32 v28, 16, v18
	v_and_b32_e32 v29, 0xffff0000, v18
	v_pk_add_f32 v[16:17], v[30:31], v[22:23]
	v_pk_add_f32 v[40:41], v[36:37], v[28:29]
	v_lshlrev_b32_e32 v30, 16, v19
	v_and_b32_e32 v31, 0xffff0000, v19
	v_pk_fma_f32 v[46:47], v[38:39], 0.5, v[20:21] op_sel_hi:[1,0,1] neg_lo:[0,0,1] neg_hi:[0,0,1]
	v_pk_fma_f32 v[48:49], v[16:17], 0.5, v[22:23] op_sel_hi:[1,0,1] neg_lo:[0,0,1] neg_hi:[0,0,1]
	v_pk_fma_f32 v[36:37], v[40:41], 0.5, v[28:29] op_sel_hi:[1,0,1] neg_lo:[0,0,1] neg_hi:[0,0,1]
	v_pk_add_f32 v[18:19], v[42:43], v[30:31]
	s_movk_i32 s14, 0x208
	v_pk_fma_f32 v[42:43], v[18:19], 0.5, v[30:31] op_sel_hi:[1,0,1] neg_lo:[0,0,1] neg_hi:[0,0,1]
	v_cvt_pk_bf16_f32 v46, v46, v47
	v_cvt_pk_bf16_f32 v47, v48, v49
	v_cvt_pk_bf16_f32 v48, v36, v37
	v_mad_u64_u32 v[36:37], s[14:15], v57, s14, v[160:161]
	v_cmp_lt_u32_e32 vcc, 48, v57
	v_cvt_pk_bf16_f32 v49, v42, v43
	v_lshl_add_u32 v37, v36, 1, 0
	s_and_b64 s[14:15], s[18:19], vcc
	ds_write_b128 v37, v[46:49]
	s_and_saveexec_b64 s[24:25], s[14:15]
	s_cbranch_execz .LBB0_1792
	v_mov_b32_e32 v37, v161
	s_lshl_b32 s14, s16, 2
	v_add_u32_e32 v37, 0, v37
	v_add_u32_e32 v37, 0x201c8, v37
	s_nop 0
	v_subrev_u32_e32 v46, 46, v113
	v_mov_b32_e32 v47, v161
	v_mov_b32_e32 v45, v161
	s_waitcnt lgkmcnt(0)
	v_readlane_b32 s21, v251, 50
	v_readlane_b32 s15, v251, 51
	s_add_u32 s14, s21, s14
	v_lshl_add_u64 v[42:43], s[6:7], 0, v[46:47]
	s_addc_u32 s15, s15, 0
	v_lshlrev_b64 v[42:43], 11, v[42:43]
	v_lshl_add_u64 v[42:43], s[14:15], 0, v[42:43]
	v_lshl_add_u64 v[42:43], v[42:43], 0, v[44:45]
	global_store_dwordx4 v[42:43], v[20:23], off
	global_store_dwordx4 v[42:43], v[28:31], off offset:16
.LBB0_1792:
	s_or_b64 exec, exec, s[24:25]
	v_pk_add_f32 v[38:39], v[38:39], v[24:25] neg_lo:[0,1] neg_hi:[0,1]
	v_pk_add_f32 v[42:43], v[16:17], v[26:27] neg_lo:[0,1] neg_hi:[0,1]
	v_pk_add_f32 v[32:33], v[40:41], v[32:33] neg_lo:[0,1] neg_hi:[0,1]
	v_pk_add_f32 v[34:35], v[18:19], v[34:35] neg_lo:[0,1] neg_hi:[0,1]
	s_waitcnt vmcnt(3)
	v_lshlrev_b32_e32 v16, 16, v12
	v_and_b32_e32 v17, 0xffff0000, v12
	v_lshlrev_b32_e32 v18, 16, v13
	v_and_b32_e32 v19, 0xffff0000, v13
	v_lshlrev_b32_e32 v24, 16, v14
	v_and_b32_e32 v25, 0xffff0000, v14
	v_lshlrev_b32_e32 v26, 16, v15
	v_and_b32_e32 v27, 0xffff0000, v15
	v_pk_add_f32 v[12:13], v[38:39], v[16:17]
	v_pk_add_f32 v[14:15], v[42:43], v[18:19]
	v_pk_add_f32 v[32:33], v[32:33], v[24:25]
	v_pk_add_f32 v[34:35], v[34:35], v[26:27]
	v_pk_fma_f32 v[38:39], v[12:13], 0.5, v[16:17] op_sel_hi:[1,0,1] neg_lo:[0,0,1] neg_hi:[0,0,1]
	v_pk_fma_f32 v[40:41], v[14:15], 0.5, v[18:19] op_sel_hi:[1,0,1] neg_lo:[0,0,1] neg_hi:[0,0,1]
	v_pk_fma_f32 v[42:43], v[32:33], 0.5, v[24:25] op_sel_hi:[1,0,1] neg_lo:[0,0,1] neg_hi:[0,0,1]
	v_pk_fma_f32 v[46:47], v[34:35], 0.5, v[26:27] op_sel_hi:[1,0,1] neg_lo:[0,0,1] neg_hi:[0,0,1]
	v_cvt_pk_bf16_f32 v38, v38, v39
	v_cvt_pk_bf16_f32 v39, v40, v41
	v_cvt_pk_bf16_f32 v40, v42, v43
	v_cvt_pk_bf16_f32 v41, v46, v47
	ds_write_b128 v58, v[38:41] offset:4160
	s_and_saveexec_b64 s[24:25], s[4:5]
	s_cbranch_execz .LBB0_1794
	v_mov_b32_e32 v37, v161
	s_lshl_b32 s4, s16, 2
	v_add_u32_e32 v37, 0, v37
	v_add_u32_e32 v37, 0x201c8, v37
	s_nop 0
	v_subrev_u32_e32 v40, 45, v113
	v_mov_b32_e32 v41, v161
	v_mov_b32_e32 v45, v161
	s_waitcnt lgkmcnt(0)
	v_readlane_b32 s14, v251, 50
	v_readlane_b32 s5, v251, 51
	s_add_u32 s4, s14, s4
	v_lshl_add_u64 v[38:39], s[6:7], 0, v[40:41]
	s_addc_u32 s5, s5, 0
	v_lshlrev_b64 v[38:39], 11, v[38:39]
	v_lshl_add_u64 v[38:39], s[4:5], 0, v[38:39]
	v_lshl_add_u64 v[38:39], v[38:39], 0, v[44:45]
	global_store_dwordx4 v[38:39], v[16:19], off
	global_store_dwordx4 v[38:39], v[24:27], off offset:16
; #define LAS __attribute__((address_space(3)))
; __device__ __forceinline__ bf16x8 pack8(const float* v) { u32x4 w; w.x = pk2(v[0], v[1]); w.y = pk2(v[2], v[3]); w.z = pk2(v[4], v[5]); w.w = pk2(v[6], v[7]); return __builtin_bit_cast(bf16x8, w); }
; __device__ __forceinline__ void unpack8(u32x4 w, float* v) { v[0] = bflo(w.x); v[1] = bfhi(w.x); v[2] = bflo(w.y); v[3] = bfhi(w.y); v[4] = bflo(w.z); v[5] = bfhi(w.z); v[6] = bflo(w.w); v[7] = bfhi(w.w); }
; template <int W> __device__ __forceinline__ void pool_stage(const Params& p, const bf16_t* z, int layer, bool is_s, int b, int c, int tok0, int g, int half, int lane, LAS unsigned char* L) {
;     ...
;     for (int ti = 0; ti < 8; ++ti) {
;         const int t = t0 + ti; float u[8], ul[8], d[8]; unpack8(raw[W - 1 + ti], u); unpack8(raw[ti], ul);
;         const int cnt = is_s ? W : min(c * 64 + t + 1, W); const float rc = 1.0f / (float)cnt;
; #pragma unroll
;         for (int i = 0; i < 8; ++i) { sum[i] += u[i]; d[i] = sum[i] * rc - u[i]; sum[i] -= ul[i]; }
;         *(LAS bf16x8*)(L + (t * DROW + c0) * 2) = pack8(d);
;         if (t >= 49 && (is_s || c == 31)) { float* o = POUT + (is_s ? O_US : O_UP) + (((size_t)layer * NB + b) * 15 + (t - 49)) * 512 + c0;
;             *(f32x4*)o = (f32x4){u[0], u[1], u[2], u[3]}; *(f32x4*)(o + 4) = (f32x4){u[4], u[5], u[6], u[7]}; }
.LBB0_1794:
	s_or_b64 exec, exec, s[24:25]
	v_pk_add_f32 v[20:21], v[12:13], v[20:21] neg_lo:[0,1] neg_hi:[0,1]
	s_waitcnt vmcnt(2)
	v_lshlrev_b32_e32 v12, 16, v8
	v_and_b32_e32 v13, 0xffff0000, v8
	v_pk_add_f32 v[22:23], v[14:15], v[22:23] neg_lo:[0,1] neg_hi:[0,1]
	v_pk_add_f32 v[28:29], v[32:33], v[28:29] neg_lo:[0,1] neg_hi:[0,1]
	v_pk_add_f32 v[30:31], v[34:35], v[30:31] neg_lo:[0,1] neg_hi:[0,1]
	v_pk_add_f32 v[20:21], v[20:21], v[12:13]
	v_lshlrev_b32_e32 v14, 16, v9
	v_and_b32_e32 v15, 0xffff0000, v9
	v_lshlrev_b32_e32 v8, 16, v10
	v_and_b32_e32 v9, 0xffff0000, v10
	v_lshlrev_b32_e32 v10, 16, v11
	v_and_b32_e32 v11, 0xffff0000, v11
	v_pk_fma_f32 v[32:33], v[20:21], 0.5, v[12:13] op_sel_hi:[1,0,1] neg_lo:[0,0,1] neg_hi:[0,0,1]
	v_pk_add_f32 v[22:23], v[22:23], v[14:15]
	v_pk_add_f32 v[28:29], v[28:29], v[8:9]
	v_pk_add_f32 v[30:31], v[30:31], v[10:11]
	v_pk_fma_f32 v[34:35], v[22:23], 0.5, v[14:15] op_sel_hi:[1,0,1] neg_lo:[0,0,1] neg_hi:[0,0,1]
	v_pk_fma_f32 v[40:41], v[28:29], 0.5, v[8:9] op_sel_hi:[1,0,1] neg_lo:[0,0,1] neg_hi:[0,0,1]
	v_pk_fma_f32 v[42:43], v[30:31], 0.5, v[10:11] op_sel_hi:[1,0,1] neg_lo:[0,0,1] neg_hi:[0,0,1]
	v_cvt_pk_bf16_f32 v38, v32, v33
	v_add_u32_e32 v32, 0x410, v36
	v_cmp_lt_u32_e32 vcc, 48, v56
	v_cvt_pk_bf16_f32 v39, v34, v35
	v_cvt_pk_bf16_f32 v40, v40, v41
	v_cvt_pk_bf16_f32 v41, v42, v43
	v_lshl_add_u32 v33, v32, 1, 0
	s_and_b64 s[14:15], s[18:19], vcc
	ds_write_b128 v33, v[38:41]
	s_and_saveexec_b64 s[4:5], s[14:15]
	s_cbranch_execz .LBB0_1796
	v_mov_b32_e32 v33, v161
	s_lshl_b32 s14, s16, 2
	v_add_u32_e32 v33, 0, v33
	v_add_u32_e32 v33, 0x201c8, v33
	s_nop 0
	v_subrev_u32_e32 v36, 44, v113
	v_mov_b32_e32 v37, v161
	v_mov_b32_e32 v45, v161
	s_waitcnt lgkmcnt(0)
	v_readlane_b32 s21, v251, 50
	v_readlane_b32 s15, v251, 51
	s_add_u32 s14, s21, s14
	v_lshl_add_u64 v[34:35], s[6:7], 0, v[36:37]
	s_addc_u32 s15, s15, 0
	v_lshlrev_b64 v[34:35], 11, v[34:35]
	v_lshl_add_u64 v[34:35], s[14:15], 0, v[34:35]
	v_lshl_add_u64 v[34:35], v[34:35], 0, v[44:45]
	global_store_dwordx4 v[34:35], v[12:15], off
	global_store_dwordx4 v[34:35], v[8:11], off offset:16
.LBB0_1796:
	s_or_b64 exec, exec, s[4:5]
	v_pk_add_f32 v[20:21], v[20:21], v[16:17] neg_lo:[0,1] neg_hi:[0,1]
	s_waitcnt vmcnt(1)
	v_lshlrev_b32_e32 v16, 16, v4
	v_and_b32_e32 v17, 0xffff0000, v4
	v_pk_add_f32 v[22:23], v[22:23], v[18:19] neg_lo:[0,1] neg_hi:[0,1]
	v_pk_add_f32 v[24:25], v[28:29], v[24:25] neg_lo:[0,1] neg_hi:[0,1]
	v_pk_add_f32 v[26:27], v[30:31], v[26:27] neg_lo:[0,1] neg_hi:[0,1]
	v_pk_add_f32 v[20:21], v[20:21], v[16:17]
	v_lshlrev_b32_e32 v18, 16, v5
	v_and_b32_e32 v19, 0xffff0000, v5
	v_lshlrev_b32_e32 v4, 16, v6
	v_and_b32_e32 v5, 0xffff0000, v6
	v_lshlrev_b32_e32 v6, 16, v7
	v_and_b32_e32 v7, 0xffff0000, v7
	v_pk_fma_f32 v[28:29], v[20:21], 0.5, v[16:17] op_sel_hi:[1,0,1] neg_lo:[0,0,1] neg_hi:[0,0,1]
	v_pk_add_f32 v[22:23], v[22:23], v[18:19]
	v_pk_add_f32 v[24:25], v[24:25], v[4:5]
	v_pk_add_f32 v[26:27], v[26:27], v[6:7]
	v_pk_fma_f32 v[30:31], v[22:23], 0.5, v[18:19] op_sel_hi:[1,0,1] neg_lo:[0,0,1] neg_hi:[0,0,1]
	v_pk_fma_f32 v[36:37], v[24:25], 0.5, v[4:5] op_sel_hi:[1,0,1] neg_lo:[0,0,1] neg_hi:[0,0,1]
	v_pk_fma_f32 v[38:39], v[26:27], 0.5, v[6:7] op_sel_hi:[1,0,1] neg_lo:[0,0,1] neg_hi:[0,0,1]
	v_cvt_pk_bf16_f32 v34, v28, v29
	v_add_u32_e32 v28, 0x208, v32
	v_cmp_lt_u32_e32 vcc, 48, v55
	v_cvt_pk_bf16_f32 v35, v30, v31
	v_cvt_pk_bf16_f32 v36, v36, v37
	v_cvt_pk_bf16_f32 v37, v38, v39
	v_lshl_add_u32 v28, v28, 1, 0
	s_and_b64 s[14:15], s[18:19], vcc
	ds_write_b128 v28, v[34:37]
	s_and_saveexec_b64 s[4:5], s[14:15]
	s_cbranch_execz .LBB0_1798
	v_mov_b32_e32 v29, v161
	s_lshl_b32 s14, s16, 2
	v_add_u32_e32 v29, 0, v29
	v_add_u32_e32 v29, 0x201c8, v29
	s_nop 0
	v_subrev_u32_e32 v32, 43, v113
	v_mov_b32_e32 v33, v161
	v_mov_b32_e32 v45, v161
	s_waitcnt lgkmcnt(0)
	v_readlane_b32 s21, v251, 50
	v_readlane_b32 s15, v251, 51
	s_add_u32 s14, s21, s14
	v_lshl_add_u64 v[30:31], s[6:7], 0, v[32:33]
	s_addc_u32 s15, s15, 0
	v_lshlrev_b64 v[30:31], 11, v[30:31]
	v_lshl_add_u64 v[30:31], s[14:15], 0, v[30:31]
	v_lshl_add_u64 v[30:31], v[30:31], 0, v[44:45]
	global_store_dwordx4 v[30:31], v[16:19], off
	global_store_dwordx4 v[30:31], v[4:7], off offset:16
.LBB0_1798:
	s_or_b64 exec, exec, s[4:5]
	s_nop 0
	v_pk_add_f32 v[6:7], v[22:23], v[14:15] neg_lo:[0,1] neg_hi:[0,1]
	v_pk_add_f32 v[14:15], v[26:27], v[10:11] neg_lo:[0,1] neg_hi:[0,1]
	s_waitcnt vmcnt(0)
	v_lshlrev_b32_e32 v10, 16, v1
	v_and_b32_e32 v11, 0xffff0000, v1
	v_pk_add_f32 v[4:5], v[20:21], v[12:13] neg_lo:[0,1] neg_hi:[0,1]
	v_pk_add_f32 v[12:13], v[24:25], v[8:9] neg_lo:[0,1] neg_hi:[0,1]
	v_lshlrev_b32_e32 v8, 16, v0
	v_and_b32_e32 v9, 0xffff0000, v0
	v_pk_add_f32 v[0:1], v[6:7], v[10:11]
	v_pk_add_f32 v[4:5], v[4:5], v[8:9]
	v_pk_fma_f32 v[6:7], v[0:1], 0.5, v[10:11] op_sel_hi:[1,0,1] neg_lo:[0,0,1] neg_hi:[0,0,1]
	v_lshlrev_b32_e32 v0, 16, v2
	v_and_b32_e32 v1, 0xffff0000, v2
	v_lshlrev_b32_e32 v2, 16, v3
	v_and_b32_e32 v3, 0xffff0000, v3
	v_pk_add_f32 v[12:13], v[12:13], v[0:1]
	v_pk_add_f32 v[14:15], v[14:15], v[2:3]
	v_pk_fma_f32 v[4:5], v[4:5], 0.5, v[8:9] op_sel_hi:[1,0,1] neg_lo:[0,0,1] neg_hi:[0,0,1]
	v_pk_fma_f32 v[12:13], v[12:13], 0.5, v[0:1] op_sel_hi:[1,0,1] neg_lo:[0,0,1] neg_hi:[0,0,1]
	v_pk_fma_f32 v[14:15], v[14:15], 0.5, v[2:3] op_sel_hi:[1,0,1] neg_lo:[0,0,1] neg_hi:[0,0,1]
	v_cmp_lt_u32_e32 vcc, 48, v54
	v_cvt_pk_bf16_f32 v4, v4, v5
	v_cvt_pk_bf16_f32 v5, v6, v7
	v_cvt_pk_bf16_f32 v6, v12, v13
	v_cvt_pk_bf16_f32 v7, v14, v15
	s_and_b64 s[14:15], s[18:19], vcc
	ds_write_b128 v28, v[4:7] offset:1040
	s_and_saveexec_b64 s[18:19], s[14:15]
	s_cbranch_execz .LBB0_1800
	v_mov_b32_e32 v4, v161
	s_or_b64 s[10:11], s[10:11], exec
	v_add_u32_e32 v4, 0, v4
	v_add_u32_e32 v4, 0x201c8, v4
	s_nop 0
	s_waitcnt lgkmcnt(0)
	v_readlane_b32 s5, v251, 51
	v_readlane_b32 s4, v251, 50

; __device__ __forceinline__ int tid_of(int wv) { return wv * 64 + (int)__builtin_amdgcn_mbcnt_hi(~0u, __builtin_amdgcn_mbcnt_lo(~0u, 0u)); }
; #define LAS __attribute__((address_space(3)))
; #define PIN(i) ((const float*)ldq_(L, (i)))
; #define PREP_CONV(bit, SRC, Kd, Nd, DST, GK, MODE) if (mask & (bit)) { for (int it = gw; it < ((Kd) / 64) * ((Nd) / 64); it += NGW) transpose_item((SRC), (Kd), (Nd), (bf16_t*)(wl + (DST)), (GK), (MODE), scr, it, lane); }
; __device__ __forceinline__ void transpose_item(const float* W, int K, int N, bf16_t* WT, const float* gk, int mode, LAS float* scr_, int item, int lane) {
;     LAS unsigned* scr = (LAS unsigned*)scr_;
;     const int nblk = N / 64, kb = item / nblk, nb = item % nblk, k0 = 64 * kb, n0 = 64 * nb;
;     const int sc = (mode == 1) ? (((n0 >> 7) & 1) * DFF + (n0 >> 8) * 128 + (n0 & 127)) : n0;
;     const float* src = W + (size_t)k0 * N + sc + lane;
;     float va[32], vb[32];
; #pragma unroll
;     for (int kp = 0; kp < 32; ++kp) { va[kp] = src[(size_t)(2 * kp) * N]; vb[kp] = src[(size_t)(2 * kp + 1) * N]; }
; __device__ __forceinline__ void prep(const Params& p, LAS unsigned char* L, int wv, int vb, int nvb, int l, int mask) {
;     int tid_ = tid_of(wv); asm volatile("" : "+v"(tid_));
;     const int tid = tid_, lane = tid & 63, wave = __builtin_amdgcn_readfirstlane(tid >> 6);
;     const int gw = vb * 8 + wave, NGW = nvb * 8; const int gt = vb * 512 + tid, NGT = nvb * 512;
;     LAS float* scr = (LAS float*)(L + wave * 16384);
;     unsigned char* ws = PWS; unsigned char* wl = ws + WS_W + (size_t)l * WL_STRIDE;
;     ...
;     PREP_CONV(PM_FFA_IN, PIN(I_WFFA_IN) + (size_t)l * DM * NFF2, DM, NFF2, WL_FFA_IN, PIN(I_NFFA) + l * DM, 1)
;     PREP_CONV(PM_FFA_OUT, PIN(I_WFFA_OUT) + (size_t)l * DFF * DM, DFF, DM, WL_FFA_OUT, nullptr, 0)
.LBB0_1801:
	s_mov_b32 s16, s2
	s_mov_b32 s4, s20
	s_mov_b32 s6, s60
	s_cmpk_eq_i32 s4, 0x100
	s_cselect_b64 s[4:5], -1, 0
	s_cmp_gt_i32 s16, 31
	s_cselect_b64 s[8:9], -1, 0
	s_and_b64 s[4:5], s[4:5], s[8:9]
	s_cmp_lt_i32 s6, 2
	s_cselect_b64 s[8:9], -1, 0
	s_and_b64 s[4:5], s[4:5], s[8:9]
	s_and_b64 vcc, exec, s[4:5]
	s_cbranch_vccz .LBB0_1895
	v_mov_b32_e32 v70, v183
	v_mov_b32_e32 v0, v161
	s_sub_i32 s29, s16, 32
	v_add_u32_e32 v0, 0, v0
	v_add_u32_e32 v0, 0x201c0, v0
	s_nop 0
	v_readfirstlane_b32 s4, v70
	s_ashr_i32 s4, s4, 6
	s_lshl_b32 s5, s29, 3
	s_add_i32 s34, s4, s5
	s_lshl_b32 s4, s4, 14
	s_add_i32 s12, s4, 0
	s_waitcnt lgkmcnt(0)
	v_readlane_b32 s15, v251, 48
	s_ashr_i32 s7, s6, 31
	s_mul_i32 s5, s6, 0x2900000
	v_and_b32_e32 v2, 63, v70
	v_readlane_b32 s14, v251, 49
	s_mul_hi_i32 s4, s6, 0x2900000
	s_add_u32 s8, s15, s5
	s_addc_u32 s9, s14, s4
	v_and_b32_e32 v0, 7, v70
	v_lshrrev_b32_e32 v71, 3, v2
	s_cmpk_gt_i32 s34, 0x2bf
	v_lshl_add_u32 v72, v2, 2, s12
	v_mul_u32_u24_e32 v3, 0x410, v0
	v_lshlrev_b32_e32 v0, 4, v0
	v_lshlrev_b32_e32 v22, 2, v71
	s_mov_b32 s26, 0x24000
	s_cbranch_scc1 .LBB0_1805
	v_mov_b32_e32 v1, v161
	v_lshl_add_u64 v[4:5], s[8:9], 0, v[0:1]
	s_mov_b64 s[4:5], 0xb00000
	v_lshl_add_u64 v[4:5], v[4:5], 0, s[4:5]
	s_mul_i32 s4, s34, 0x2c000
	v_mov_b32_e32 v6, s4
	s_movk_i32 s4, 0xb00
	v_add3_u32 v1, s12, v3, v22
	v_mad_u32_u24 v23, v71, s4, v6
	s_lshl_b32 s13, s34, 6
	v_lshlrev_b32_e32 v160, 2, v2
	s_mov_b32 s18, s34
.LBB0_1804:
	v_mov_b32_e32 v6, v161
	s_mul_i32 s10, s6, 0xb00000
	v_add_u32_e32 v6, 0, v6
	v_add_u32_e32 v6, 0x20148, v6
	s_nop 0
	v_add_u32_e32 v73, 0x400, v72
	v_add_u32_e32 v92, 0x800, v72
	v_add_u32_e32 v93, 0xc00, v72
	v_add_u32_e32 v94, 0x1000, v72
	s_waitcnt lgkmcnt(0)
	v_readlane_b32 s5, v251, 18
	v_readlane_b32 s4, v251, 19
	s_add_u32 s5, s5, s10
	s_mul_hi_i32 s10, s6, 0xb00000
	s_addc_u32 s19, s4, s10
	s_ashr_i32 s4, s18, 31
	s_lshr_b32 s4, s4, 28
	s_add_i32 s4, s18, s4
	s_ashr_i32 s4, s4, 4
	s_lshl_b32 s10, s4, 6
	s_lshl_b32 s11, s4, 10
	s_mul_i32 s21, s4, 0xffd40000
	s_sub_i32 s4, s13, s11
	s_ashr_i32 s11, s10, 31
	s_lshl_b64 s[24:25], s[10:11], 12
	v_lshl_add_u64 v[20:21], s[10:11], 1, v[4:5]
	s_add_u32 s10, s5, s24
	s_addc_u32 s11, s19, s25
	s_ashr_i32 s5, s4, 31
	v_add_u32_e32 v6, s21, v23
	s_lshl_b64 s[4:5], s[4:5], 2
	v_add_u32_e32 v8, 0x5800, v6
	v_add_u32_e32 v10, 0xb000, v6
	v_add_u32_e32 v12, 0x10800, v6
	v_add_u32_e32 v14, 0x16000, v6
	v_add_u32_e32 v16, 0x1b800, v6
	v_add_u32_e32 v18, 0x21000, v6
	v_add_u32_e32 v24, 0x26800, v6
	s_add_u32 s10, s10, s4
	v_ashrrev_i32_e32 v7, 31, v6
	v_ashrrev_i32_e32 v9, 31, v8
	v_ashrrev_i32_e32 v11, 31, v10
	v_ashrrev_i32_e32 v13, 31, v12
	v_ashrrev_i32_e32 v15, 31, v14
	v_ashrrev_i32_e32 v17, 31, v16
	v_ashrrev_i32_e32 v19, 31, v18
	v_ashrrev_i32_e32 v25, 31, v24
	s_addc_u32 s11, s11, s5
	v_lshl_add_u64 v[6:7], v[6:7], 1, v[20:21]
	v_lshl_add_u64 v[8:9], v[8:9], 1, v[20:21]
	v_lshl_add_u64 v[10:11], v[10:11], 1, v[20:21]
	v_lshl_add_u64 v[12:13], v[12:13], 1, v[20:21]
	v_lshl_add_u64 v[14:15], v[14:15], 1, v[20:21]
	v_lshl_add_u64 v[16:17], v[16:17], 1, v[20:21]
	v_lshl_add_u64 v[18:19], v[18:19], 1, v[20:21]
	v_lshl_add_u64 v[20:21], v[24:25], 1, v[20:21]
	v_lshl_add_u64 v[24:25], s[10:11], 0, v[160:161]
	v_add_co_u32_e32 v26, vcc, s79, v24
	global_load_dword v98, v160, s[10:11]
	s_nop 0
	v_addc_co_u32_e32 v27, vcc, 0, v25, vcc
	v_add_co_u32_e32 v28, vcc, s88, v24
	v_add_u32_e32 v95, 0x1400, v72
	s_nop 0
	v_addc_co_u32_e32 v29, vcc, 0, v25, vcc
	v_add_co_u32_e32 v30, vcc, s80, v24
	v_add_u32_e32 v96, 0x1800, v72
	s_nop 0
	v_addc_co_u32_e32 v31, vcc, 0, v25, vcc
	v_add_co_u32_e32 v32, vcc, s70, v24
	v_add_u32_e32 v97, 0x1c00, v72
	s_nop 0
	v_addc_co_u32_e32 v33, vcc, 0, v25, vcc
	v_add_co_u32_e32 v34, vcc, s71, v24
	s_add_i32 s4, s18, 0x700
	s_nop 0
	v_addc_co_u32_e32 v35, vcc, 0, v25, vcc
	v_add_co_u32_e32 v36, vcc, s91, v24
	s_add_i32 s13, s13, 0x1c000
	s_nop 0
	v_addc_co_u32_e32 v37, vcc, 0, v25, vcc
	v_add_co_u32_e32 v38, vcc, s92, v24
	v_add_u32_e32 v23, 0x13400000, v23
	s_nop 0
	v_addc_co_u32_e32 v39, vcc, 0, v25, vcc
	v_add_co_u32_e32 v40, vcc, s37, v24
	s_cmpk_lt_i32 s18, 0xfbc0
	s_nop 0
	v_addc_co_u32_e32 v41, vcc, 0, v25, vcc
	v_add_co_u32_e32 v42, vcc, s94, v24
	s_mov_b32 s18, s4
	s_nop 0
	v_addc_co_u32_e32 v43, vcc, 0, v25, vcc
	v_add_co_u32_e32 v44, vcc, s46, v24
	s_nop 1
	v_addc_co_u32_e32 v45, vcc, 0, v25, vcc
	v_add_co_u32_e32 v46, vcc, s47, v24
	s_nop 1
	v_addc_co_u32_e32 v47, vcc, 0, v25, vcc
	v_add_co_u32_e32 v48, vcc, s59, v24
	s_waitcnt vmcnt(13)
	s_nop 0
	v_addc_co_u32_e32 v49, vcc, 0, v25, vcc
	s_waitcnt vmcnt(12)
	v_add_co_u32_e32 v50, vcc, s81, v24
	s_waitcnt vmcnt(11)
	s_nop 0
	v_addc_co_u32_e32 v51, vcc, 0, v25, vcc
	v_add_co_u32_e32 v52, vcc, s83, v24
	s_nop 1
	v_addc_co_u32_e32 v53, vcc, 0, v25, vcc
	v_add_co_u32_e32 v54, vcc, s27, v24
	s_nop 1
	v_addc_co_u32_e32 v55, vcc, 0, v25, vcc
	v_add_co_u32_e32 v56, vcc, s50, v24
	s_nop 1
	v_addc_co_u32_e32 v57, vcc, 0, v25, vcc
	v_add_co_u32_e32 v58, vcc, s53, v24
	s_nop 1
	v_addc_co_u32_e32 v59, vcc, 0, v25, vcc
	v_add_co_u32_e32 v60, vcc, s26, v24
	s_nop 1
	v_addc_co_u32_e32 v61, vcc, 0, v25, vcc
	v_add_co_u32_e32 v62, vcc, s73, v24
	s_nop 1
	v_addc_co_u32_e32 v63, vcc, 0, v25, vcc
	v_add_co_u32_e32 v64, vcc, s1, v24
	s_nop 1
	v_addc_co_u32_e32 v65, vcc, 0, v25, vcc
	s_waitcnt vmcnt(10)
; #define LAS __attribute__((address_space(3)))
; __device__ __forceinline__ void transpose_item(const float* W, int K, int N, bf16_t* WT, const float* gk, int mode, LAS float* scr_, int item, int lane) {
;     LAS unsigned* scr = (LAS unsigned*)scr_;
;     const int nblk = N / 64, kb = item / nblk, nb = item % nblk, k0 = 64 * kb, n0 = 64 * nb;
;     const int sc = (mode == 1) ? (((n0 >> 7) & 1) * DFF + (n0 >> 8) * 128 + (n0 & 127)) : n0;
;     const float* src = W + (size_t)k0 * N + sc + lane;
;     float va[32], vb[32];
; #pragma unroll
;     for (int kp = 0; kp < 32; ++kp) { va[kp] = src[(size_t)(2 * kp) * N]; vb[kp] = src[(size_t)(2 * kp + 1) * N]; }
	v_add_co_u32_e32 v66, vcc, s72, v24
	s_nop 1
	v_addc_co_u32_e32 v67, vcc, 0, v25, vcc
	v_add_co_u32_e32 v68, vcc, s82, v24
	s_nop 1
	v_addc_co_u32_e32 v69, vcc, 0, v25, vcc
	v_add_co_u32_e32 v74, vcc, s33, v24
	s_nop 1
	v_addc_co_u32_e32 v75, vcc, 0, v25, vcc
	v_add_co_u32_e32 v76, vcc, s22, v24
	s_nop 1
	v_addc_co_u32_e32 v77, vcc, 0, v25, vcc
	v_add_co_u32_e32 v78, vcc, s38, v24
	s_nop 1
	v_addc_co_u32_e32 v79, vcc, 0, v25, vcc
	v_add_co_u32_e32 v80, vcc, s39, v24
	s_nop 1
	v_addc_co_u32_e32 v81, vcc, 0, v25, vcc
	v_add_co_u32_e32 v82, vcc, s56, v24
	s_nop 1
	v_addc_co_u32_e32 v83, vcc, 0, v25, vcc
	v_add_co_u32_e32 v84, vcc, s69, v24
	s_nop 1
	v_addc_co_u32_e32 v85, vcc, 0, v25, vcc
	v_add_co_u32_e32 v86, vcc, s87, v24
	s_nop 1
	v_addc_co_u32_e32 v87, vcc, 0, v25, vcc
	v_add_co_u32_e32 v88, vcc, s90, v24
	s_nop 1
	v_addc_co_u32_e32 v89, vcc, 0, v25, vcc
	v_add_co_u32_e32 v90, vcc, s51, v24
	s_nop 1
	v_addc_co_u32_e32 v91, vcc, 0, v25, vcc
	v_add_co_u32_e32 v24, vcc, s52, v24
	s_nop 1
	v_addc_co_u32_e32 v25, vcc, 0, v25, vcc
	global_load_dword v99, v[26:27], off offset:-4096
	s_nop 0
	global_load_dword v26, v[26:27], off
	s_nop 0
	global_load_dword v27, v[28:29], off offset:-4096
	s_nop 0
	global_load_dword v28, v[28:29], off
	s_nop 0
	global_load_dword v29, v[30:31], off offset:-4096
	s_nop 0
	global_load_dword v30, v[30:31], off
	s_nop 0
	global_load_dword v31, v[32:33], off offset:-4096
	s_nop 0
	global_load_dword v32, v[32:33], off
	s_nop 0
	global_load_dword v33, v[34:35], off offset:-4096
	s_nop 0
	global_load_dword v34, v[34:35], off
	s_nop 0
	global_load_dword v35, v[36:37], off offset:-4096
	s_nop 0
	global_load_dword v36, v[36:37], off
	s_nop 0
	global_load_dword v37, v[38:39], off offset:-4096
	s_nop 0
	global_load_dword v38, v[38:39], off
	s_nop 0
	global_load_dword v39, v[40:41], off offset:-4096
	s_nop 0
	global_load_dword v40, v[40:41], off
	s_nop 0
	global_load_dword v41, v[42:43], off offset:-4096
	s_nop 0
	global_load_dword v42, v[42:43], off
	s_nop 0
	global_load_dword v43, v[44:45], off offset:-4096
	s_nop 0
	global_load_dword v44, v[44:45], off
	s_nop 0
	global_load_dword v45, v[46:47], off offset:-4096
	s_nop 0
	global_load_dword v46, v[46:47], off
	s_nop 0
	global_load_dword v47, v[48:49], off offset:-4096
	s_nop 0
	global_load_dword v48, v[48:49], off
	s_nop 0
	global_load_dword v49, v[50:51], off offset:-4096
	s_nop 0
	global_load_dword v50, v[50:51], off
	s_nop 0
	global_load_dword v51, v[52:53], off offset:-4096
	s_nop 0
	global_load_dword v52, v[52:53], off
	s_nop 0
	global_load_dword v53, v[54:55], off offset:-4096
	s_nop 0
	global_load_dword v54, v[54:55], off
	s_nop 0
	global_load_dword v55, v[56:57], off offset:-4096
	s_nop 0
	global_load_dword v56, v[56:57], off
	s_nop 0
	global_load_dword v57, v[58:59], off offset:-4096
	s_nop 0
	global_load_dword v58, v[58:59], off
	s_nop 0
	global_load_dword v59, v[60:61], off offset:-4096
	s_nop 0
	global_load_dword v60, v[60:61], off
	s_nop 0
	global_load_dword v61, v[62:63], off offset:-4096
	s_nop 0
	global_load_dword v62, v[62:63], off
	s_nop 0
	global_load_dword v63, v[64:65], off offset:-4096
	s_nop 0
	global_load_dword v64, v[64:65], off
	s_nop 0
	global_load_dword v65, v[66:67], off offset:-4096
	s_nop 0
	global_load_dword v66, v[66:67], off
	s_nop 0
	global_load_dword v67, v[68:69], off offset:-4096
	s_nop 0
	global_load_dword v68, v[68:69], off
	s_nop 0
	global_load_dword v69, v[74:75], off offset:-4096
	s_nop 0
	global_load_dword v74, v[74:75], off
	s_nop 0
	global_load_dword v75, v[76:77], off offset:-4096
	s_nop 0
	global_load_dword v76, v[76:77], off
	s_nop 0
	global_load_dword v77, v[78:79], off offset:-4096
	s_nop 0
	global_load_dword v78, v[78:79], off
	s_nop 0
	global_load_dword v79, v[80:81], off offset:-4096
	s_nop 0
	global_load_dword v80, v[80:81], off
	s_nop 0
	global_load_dword v81, v[82:83], off offset:-4096
	s_nop 0
	global_load_dword v82, v[82:83], off
	s_nop 0
	global_load_dword v83, v[84:85], off offset:-4096
	s_nop 0
	global_load_dword v84, v[84:85], off
	s_nop 0
	global_load_dword v85, v[86:87], off offset:-4096
	s_nop 0
	global_load_dword v86, v[86:87], off
	s_nop 0
	global_load_dword v87, v[88:89], off offset:-4096
	s_nop 0
	global_load_dword v88, v[88:89], off
	s_nop 0
	global_load_dword v89, v[90:91], off offset:-4096
	s_nop 0
	global_load_dword v90, v[90:91], off
	s_nop 0
	global_load_dword v24, v[24:25], off
	s_waitcnt vmcnt(62)
	v_cvt_pk_bf16_f32 v25, v98, v99
	s_waitcnt vmcnt(60)
; #define LAS __attribute__((address_space(3)))
; __device__ __forceinline__ unsigned pk2(float lo, float hi) { f32x2 v = {lo, hi}; bf16x2_t b = __builtin_convertvector(v, bf16x2_t); return __builtin_bit_cast(unsigned, b); }
; __device__ __forceinline__ void transpose_item(const float* W, int K, int N, bf16_t* WT, const float* gk, int mode, LAS float* scr_, int item, int lane) {
;     ...
; #pragma unroll
;     for (int kp = 0; kp < 32; ++kp) {
;         float a = va[kp], b = vb[kp];
;         if (gk) { a *= gk[k0 + 2 * kp]; b *= gk[k0 + 2 * kp + 1]; }
;         scr[kp * 65 + lane] = pk2(a, b);
;     }
;     asm volatile("s_waitcnt lgkmcnt(0)" ::: "memory");
;     const int c = lane & 7;
; #pragma unroll
;     for (int j = 0; j < 8; ++j) { const int r = (lane >> 3) + 8 * j; const LAS unsigned* q = scr + (4 * c) * 65 + r;
;         u32x4 o; o.x = q[0]; o.y = q[65]; o.z = q[130]; o.w = q[195];
;         *(u32x4*)(WT + (size_t)(n0 + r) * K + k0 + 8 * c) = o; }
;     asm volatile("s_waitcnt lgkmcnt(0)" ::: "memory");
	v_cvt_pk_bf16_f32 v26, v26, v27
	s_waitcnt vmcnt(58)
	v_cvt_pk_bf16_f32 v27, v28, v29
	s_waitcnt vmcnt(56)
	v_cvt_pk_bf16_f32 v28, v30, v31
	s_waitcnt vmcnt(54)
	v_cvt_pk_bf16_f32 v29, v32, v33
	s_waitcnt vmcnt(52)
	v_cvt_pk_bf16_f32 v30, v34, v35
	s_waitcnt vmcnt(50)
	v_cvt_pk_bf16_f32 v31, v36, v37
	s_waitcnt vmcnt(48)
	v_cvt_pk_bf16_f32 v32, v38, v39
	s_waitcnt vmcnt(46)
	v_cvt_pk_bf16_f32 v33, v40, v41
	s_waitcnt vmcnt(44)
	v_cvt_pk_bf16_f32 v34, v42, v43
	s_waitcnt vmcnt(42)
	v_cvt_pk_bf16_f32 v35, v44, v45
	s_waitcnt vmcnt(40)
	v_cvt_pk_bf16_f32 v36, v46, v47
	s_waitcnt vmcnt(38)
	v_cvt_pk_bf16_f32 v37, v48, v49
	s_waitcnt vmcnt(36)
	v_cvt_pk_bf16_f32 v38, v50, v51
	s_waitcnt vmcnt(34)
	v_cvt_pk_bf16_f32 v39, v52, v53
	s_waitcnt vmcnt(32)
	v_cvt_pk_bf16_f32 v40, v54, v55
	s_waitcnt vmcnt(30)
	v_cvt_pk_bf16_f32 v41, v56, v57
	s_waitcnt vmcnt(28)
	v_cvt_pk_bf16_f32 v42, v58, v59
	s_waitcnt vmcnt(26)
	v_cvt_pk_bf16_f32 v43, v60, v61
	s_waitcnt vmcnt(24)
	v_cvt_pk_bf16_f32 v44, v62, v63
	s_waitcnt vmcnt(22)
	v_cvt_pk_bf16_f32 v45, v64, v65
	s_waitcnt vmcnt(20)
	v_cvt_pk_bf16_f32 v46, v66, v67
	s_waitcnt vmcnt(18)
	v_cvt_pk_bf16_f32 v47, v68, v69
	s_waitcnt vmcnt(16)
	v_cvt_pk_bf16_f32 v48, v74, v75
	s_waitcnt vmcnt(14)
	v_cvt_pk_bf16_f32 v49, v76, v77
	s_waitcnt vmcnt(12)
	v_cvt_pk_bf16_f32 v50, v78, v79
	s_waitcnt vmcnt(10)
	v_cvt_pk_bf16_f32 v51, v80, v81
	s_waitcnt vmcnt(8)
	v_cvt_pk_bf16_f32 v52, v82, v83
	s_waitcnt vmcnt(6)
	v_cvt_pk_bf16_f32 v53, v84, v85
	s_waitcnt vmcnt(4)
	v_cvt_pk_bf16_f32 v54, v86, v87
	s_waitcnt vmcnt(2)
	v_cvt_pk_bf16_f32 v55, v88, v89
	s_waitcnt vmcnt(0)
	v_cvt_pk_bf16_f32 v24, v90, v24
	ds_write2_b32 v72, v25, v26 offset1:65
	ds_write2_b32 v72, v27, v28 offset0:130 offset1:195
	ds_write2_b32 v73, v29, v30 offset0:4 offset1:69
	ds_write2_b32 v73, v31, v32 offset0:134 offset1:199
	ds_write2_b32 v92, v33, v34 offset0:8 offset1:73
	ds_write2_b32 v92, v35, v36 offset0:138 offset1:203
	ds_write2_b32 v93, v37, v38 offset0:12 offset1:77
	ds_write2_b32 v93, v39, v40 offset0:142 offset1:207
	ds_write2_b32 v94, v41, v42 offset0:16 offset1:81
	ds_write2_b32 v94, v43, v44 offset0:146 offset1:211
	ds_write2_b32 v95, v45, v46 offset0:20 offset1:85
	ds_write2_b32 v95, v47, v48 offset0:150 offset1:215
	ds_write2_b32 v96, v49, v50 offset0:24 offset1:89
	ds_write2_b32 v96, v51, v52 offset0:154 offset1:219
	ds_write2_b32 v97, v53, v54 offset0:28 offset1:93
	ds_write2_b32 v97, v55, v24 offset0:158 offset1:223
	s_waitcnt lgkmcnt(0)
	ds_read2_b32 v[24:25], v1 offset0:65 offset1:73
	ds_read2_b32 v[44:45], v1 offset0:130 offset1:138
	ds_read2_b32 v[26:27], v1 offset0:195 offset1:203
	ds_read2_b32 v[46:47], v1 offset1:8
	ds_read2_b32 v[48:49], v1 offset0:16 offset1:24
	ds_read2_b32 v[28:29], v1 offset0:81 offset1:89
	ds_read2_b32 v[50:51], v1 offset0:146 offset1:154
	ds_read2_b32 v[30:31], v1 offset0:211 offset1:219
	ds_read2_b32 v[32:33], v1 offset0:97 offset1:105
	ds_read2_b32 v[52:53], v1 offset0:162 offset1:170
	ds_read2_b32 v[34:35], v1 offset0:227 offset1:235
	ds_read2_b32 v[54:55], v1 offset0:32 offset1:40
	ds_read2_b32 v[56:57], v1 offset0:48 offset1:56
	ds_read2_b32 v[36:37], v1 offset0:113 offset1:121
	ds_read2_b32 v[58:59], v1 offset0:178 offset1:186
	ds_read2_b32 v[38:39], v1 offset0:243 offset1:251
	s_waitcnt lgkmcnt(12)
	v_mov_b32_e32 v40, v46
	v_mov_b32_e32 v41, v24
	v_mov_b32_e32 v42, v44
	v_mov_b32_e32 v43, v26
	v_mov_b32_e32 v24, v47
	v_mov_b32_e32 v26, v45
	s_waitcnt lgkmcnt(11)
	v_mov_b32_e32 v44, v48
	s_waitcnt lgkmcnt(10)
	v_mov_b32_e32 v45, v28
	s_waitcnt lgkmcnt(9)
	v_mov_b32_e32 v46, v50
	s_waitcnt lgkmcnt(8)
	v_mov_b32_e32 v47, v30
	v_mov_b32_e32 v28, v49
	v_mov_b32_e32 v30, v51
	s_waitcnt lgkmcnt(4)
	v_mov_b32_e32 v48, v54
	v_mov_b32_e32 v49, v32
	v_mov_b32_e32 v50, v52
	v_mov_b32_e32 v51, v34
	v_mov_b32_e32 v32, v55
	v_mov_b32_e32 v34, v53
	s_waitcnt lgkmcnt(3)
	v_mov_b32_e32 v52, v56
	s_waitcnt lgkmcnt(2)
	v_mov_b32_e32 v53, v36
	s_waitcnt lgkmcnt(1)
	v_mov_b32_e32 v54, v58
	s_waitcnt lgkmcnt(0)
	v_mov_b32_e32 v55, v38
	v_mov_b32_e32 v36, v57
	v_mov_b32_e32 v38, v59
	global_store_dwordx4 v[6:7], v[40:43], off
	global_store_dwordx4 v[8:9], v[24:27], off
	global_store_dwordx4 v[10:11], v[44:47], off
	global_store_dwordx4 v[12:13], v[28:31], off
	global_store_dwordx4 v[14:15], v[48:51], off
	global_store_dwordx4 v[16:17], v[32:35], off
	global_store_dwordx4 v[18:19], v[52:55], off
	global_store_dwordx4 v[20:21], v[36:39], off
	s_waitcnt lgkmcnt(0)
	s_cbranch_scc1 .LBB0_1804

; #define LAS __attribute__((address_space(3)))
; #define PIN(i) ((const float*)ldq_(L, (i)))
; #define PREP_CONV(bit, SRC, Kd, Nd, DST, GK, MODE) if (mask & (bit)) { for (int it = gw; it < ((Kd) / 64) * ((Nd) / 64); it += NGW) transpose_item((SRC), (Kd), (Nd), (bf16_t*)(wl + (DST)), (GK), (MODE), scr, it, lane); }
; __device__ __forceinline__ void transpose_item(const float* W, int K, int N, bf16_t* WT, const float* gk, int mode, LAS float* scr_, int item, int lane) {
;     LAS unsigned* scr = (LAS unsigned*)scr_;
;     const int nblk = N / 64, kb = item / nblk, nb = item % nblk, k0 = 64 * kb, n0 = 64 * nb;
;     const int sc = (mode == 1) ? (((n0 >> 7) & 1) * DFF + (n0 >> 8) * 128 + (n0 & 127)) : n0;
;     const float* src = W + (size_t)k0 * N + sc + lane;
;     float va[32], vb[32];
; #pragma unroll
;     for (int kp = 0; kp < 32; ++kp) { va[kp] = src[(size_t)(2 * kp) * N]; vb[kp] = src[(size_t)(2 * kp + 1) * N]; }
; __device__ __forceinline__ void prep(const Params& p, LAS unsigned char* L, int wv, int vb, int nvb, int l, int mask) {
;     ...
;     PREP_CONV(PM_FFA_IN, PIN(I_WFFA_IN) + (size_t)l * DM * NFF2, DM, NFF2, WL_FFA_IN, PIN(I_NFFA) + l * DM, 1)
;     PREP_CONV(PM_FFA_OUT, PIN(I_WFFA_OUT) + (size_t)l * DFF * DM, DFF, DM, WL_FFA_OUT, nullptr, 0)
;     PREP_CONV(PM_WIN, PIN(I_WIN) + (size_t)l * DM * NIN, DM, NIN, WL_IN, PIN(I_NMIX) + l * DM, 0)
.LBB0_1808:
	v_mov_b32_e32 v2, v161
	s_mul_i32 s12, s6, 0x500000
	v_add_u32_e32 v2, 0, v2
	v_add_u32_e32 v2, 0x20158, v2
	ds_read_b64 v[2:3], v2
	s_mov_b64 s[30:31], -1
	s_waitcnt lgkmcnt(0)
	v_readfirstlane_b32 s5, v2
	v_mov_b32_e32 v2, v161
	v_readfirstlane_b32 s4, v3
	v_add_u32_e32 v2, 0, v2
	v_add_u32_e32 v2, 0x20150, v2
	s_nop 0
	s_add_u32 s13, s5, s12
	s_mul_hi_i32 s5, s6, 0x500000
	s_addc_u32 s21, s4, s5
	s_mul_hi_i32 s12, s34, 0x66666667
	s_waitcnt lgkmcnt(0)
	v_readlane_b32 s4, v251, 20
	v_readlane_b32 s5, v251, 21
	s_add_u32 s40, s4, s10
	s_addc_u32 s41, s5, s11
	s_lshr_b32 s18, s12, 31
	s_ashr_i32 s12, s12, 3
	s_add_i32 s24, s12, s18
	s_lshl_b32 s18, s24, 6
	s_mul_i32 s12, s24, 0xfffffb00
	s_add_i32 s12, s35, s12
	s_ashr_i32 s19, s18, 31
	s_mul_i32 s24, s24, 0x50000
	s_mul_hi_i32 s25, s18, 0x1400
	s_add_u32 s26, s13, s24
	s_addc_u32 s21, s21, s25
	s_ashr_i32 s13, s12, 31
	s_lshl_b64 s[24:25], s[12:13], 2
	s_add_u32 s24, s26, s24
	s_addc_u32 s25, s21, s25
	s_waitcnt vmcnt(9)
	v_lshl_add_u64 v[66:67], s[24:25], 0, v[160:161]
	s_movk_i32 s13, 0x1000
	v_add_co_u32_e32 v2, vcc, s13, v66
	s_movk_i32 s13, 0x3000
	s_nop 0
	v_addc_co_u32_e32 v3, vcc, 0, v67, vcc
	global_load_dword v63, v[2:3], off offset:1024
	v_add_co_u32_e32 v2, vcc, s79, v66
	global_load_dword v62, v160, s[24:25]
	s_nop 0
	v_addc_co_u32_e32 v3, vcc, 0, v67, vcc
	global_load_dword v64, v[2:3], off offset:2048
	v_add_co_u32_e32 v2, vcc, s13, v66
	s_movk_i32 s13, 0x5000
	s_nop 0
	v_addc_co_u32_e32 v3, vcc, 0, v67, vcc
	global_load_dword v65, v[2:3], off offset:3072
	v_add_co_u32_e32 v2, vcc, s13, v66
	s_movk_i32 s13, 0x7000
	s_nop 0
	v_addc_co_u32_e32 v3, vcc, 0, v67, vcc
	global_load_dword v54, v[2:3], off
	v_add_co_u32_e32 v2, vcc, s80, v66
	s_cmp_lg_u64 s[4:5], 0
	s_nop 0
	v_addc_co_u32_e32 v3, vcc, 0, v67, vcc
	global_load_dword v55, v[2:3], off offset:1024
	v_add_co_u32_e32 v2, vcc, s13, v66
	s_mov_b32 s13, 0xb000
	s_nop 0
	v_addc_co_u32_e32 v3, vcc, 0, v67, vcc
	global_load_dword v60, v[2:3], off offset:2048
	v_add_co_u32_e32 v2, vcc, s70, v66
	s_cselect_b64 s[24:25], -1, 0
	s_nop 0
	v_addc_co_u32_e32 v3, vcc, 0, v67, vcc
	global_load_dword v61, v[2:3], off offset:3072
	v_add_co_u32_e32 v2, vcc, s71, v66
	s_cmp_eq_u64 s[4:5], 0
	s_nop 0
	v_addc_co_u32_e32 v3, vcc, 0, v67, vcc
	global_load_dword v56, v[2:3], off
	v_add_co_u32_e32 v2, vcc, s13, v66
	s_mov_b32 s13, 0xd000
	s_nop 0
	v_addc_co_u32_e32 v3, vcc, 0, v67, vcc
	global_load_dword v57, v[2:3], off offset:1024
	v_add_co_u32_e32 v2, vcc, s91, v66
	s_nop 1
	v_addc_co_u32_e32 v3, vcc, 0, v67, vcc
	global_load_dword v58, v[2:3], off offset:2048
	v_add_co_u32_e32 v2, vcc, s13, v66
	s_mov_b32 s13, 0xf000
	s_nop 0
	v_addc_co_u32_e32 v3, vcc, 0, v67, vcc
	global_load_dword v59, v[2:3], off offset:3072
	v_add_co_u32_e32 v2, vcc, s13, v66
	s_mov_b32 s13, 0x11000
	s_nop 0
	v_addc_co_u32_e32 v3, vcc, 0, v67, vcc
	global_load_dword v46, v[2:3], off
	v_add_co_u32_e32 v2, vcc, s37, v66
	s_nop 1
	v_addc_co_u32_e32 v3, vcc, 0, v67, vcc
	global_load_dword v47, v[2:3], off offset:1024
	v_add_co_u32_e32 v2, vcc, s13, v66
	s_mov_b32 s13, 0x15000
	s_nop 0
	v_addc_co_u32_e32 v3, vcc, 0, v67, vcc
	global_load_dword v52, v[2:3], off offset:2048
	v_add_co_u32_e32 v2, vcc, s94, v66
	s_nop 1
	v_addc_co_u32_e32 v3, vcc, 0, v67, vcc
	global_load_dword v53, v[2:3], off offset:3072
	v_add_co_u32_e32 v2, vcc, s46, v66
	s_nop 1
	v_addc_co_u32_e32 v3, vcc, 0, v67, vcc
	global_load_dword v48, v[2:3], off
	v_add_co_u32_e32 v2, vcc, s13, v66
	s_mov_b32 s13, 0x17000
	s_nop 0
	v_addc_co_u32_e32 v3, vcc, 0, v67, vcc
	global_load_dword v49, v[2:3], off offset:1024
	v_add_co_u32_e32 v2, vcc, s47, v66
	s_nop 1
	v_addc_co_u32_e32 v3, vcc, 0, v67, vcc
	global_load_dword v50, v[2:3], off offset:2048
	v_add_co_u32_e32 v2, vcc, s13, v66
	s_mov_b32 s13, 0x19000
	s_nop 0
	v_addc_co_u32_e32 v3, vcc, 0, v67, vcc
	global_load_dword v51, v[2:3], off offset:3072
	v_add_co_u32_e32 v2, vcc, s13, v66
	s_mov_b32 s13, 0x1b000
	s_nop 0
	v_addc_co_u32_e32 v3, vcc, 0, v67, vcc
	global_load_dword v38, v[2:3], off
	v_add_co_u32_e32 v2, vcc, s81, v66
	s_nop 1
	v_addc_co_u32_e32 v3, vcc, 0, v67, vcc
	global_load_dword v39, v[2:3], off offset:1024
	v_add_co_u32_e32 v2, vcc, s13, v66
	s_mov_b32 s13, 0x1f000
	s_nop 0
	v_addc_co_u32_e32 v3, vcc, 0, v67, vcc
	global_load_dword v44, v[2:3], off offset:2048
	v_add_co_u32_e32 v2, vcc, s83, v66
	s_nop 1
	v_addc_co_u32_e32 v3, vcc, 0, v67, vcc
	global_load_dword v45, v[2:3], off offset:3072
	v_add_co_u32_e32 v2, vcc, s27, v66
	s_nop 1
	v_addc_co_u32_e32 v3, vcc, 0, v67, vcc
	global_load_dword v40, v[2:3], off
	v_add_co_u32_e32 v2, vcc, s13, v66
	s_mov_b32 s13, 0x21000
	s_nop 0
	v_addc_co_u32_e32 v3, vcc, 0, v67, vcc
	global_load_dword v41, v[2:3], off offset:1024
	v_add_co_u32_e32 v2, vcc, s50, v66
	s_nop 1
	v_addc_co_u32_e32 v3, vcc, 0, v67, vcc
	global_load_dword v42, v[2:3], off offset:2048
	v_add_co_u32_e32 v2, vcc, s13, v66
	s_mov_b32 s13, 0x23000
	s_nop 0
	v_addc_co_u32_e32 v3, vcc, 0, v67, vcc
	global_load_dword v43, v[2:3], off offset:3072
	v_add_co_u32_e32 v2, vcc, s13, v66
	s_mov_b32 s13, 0x25000
	s_nop 0
	v_addc_co_u32_e32 v3, vcc, 0, v67, vcc
	global_load_dword v30, v[2:3], off
	v_add_co_u32_e32 v2, vcc, s28, v66
	s_nop 1
; #define LAS __attribute__((address_space(3)))
; #define PIN(i) ((const float*)ldq_(L, (i)))
; #define PREP_CONV(bit, SRC, Kd, Nd, DST, GK, MODE) if (mask & (bit)) { for (int it = gw; it < ((Kd) / 64) * ((Nd) / 64); it += NGW) transpose_item((SRC), (Kd), (Nd), (bf16_t*)(wl + (DST)), (GK), (MODE), scr, it, lane); }
; __device__ __forceinline__ void transpose_item(const float* W, int K, int N, bf16_t* WT, const float* gk, int mode, LAS float* scr_, int item, int lane) {
;     LAS unsigned* scr = (LAS unsigned*)scr_;
;     const int nblk = N / 64, kb = item / nblk, nb = item % nblk, k0 = 64 * kb, n0 = 64 * nb;
;     const int sc = (mode == 1) ? (((n0 >> 7) & 1) * DFF + (n0 >> 8) * 128 + (n0 & 127)) : n0;
;     const float* src = W + (size_t)k0 * N + sc + lane;
;     float va[32], vb[32];
; #pragma unroll
;     for (int kp = 0; kp < 32; ++kp) { va[kp] = src[(size_t)(2 * kp) * N]; vb[kp] = src[(size_t)(2 * kp + 1) * N]; }
; #pragma unroll
;     for (int kp = 0; kp < 32; ++kp) {
;         float a = va[kp], b = vb[kp];
;         if (gk) { a *= gk[k0 + 2 * kp]; b *= gk[k0 + 2 * kp + 1]; }
; __device__ __forceinline__ void prep(const Params& p, LAS unsigned char* L, int wv, int vb, int nvb, int l, int mask) {
;     ...
;     PREP_CONV(PM_WIN, PIN(I_WIN) + (size_t)l * DM * NIN, DM, NIN, WL_IN, PIN(I_NMIX) + l * DM, 0)
	v_addc_co_u32_e32 v3, vcc, 0, v67, vcc
	global_load_dword v31, v[2:3], off offset:1024
	v_add_co_u32_e32 v2, vcc, s13, v66
	s_mov_b32 s13, 0x29000
	s_nop 0
	v_addc_co_u32_e32 v3, vcc, 0, v67, vcc
	global_load_dword v36, v[2:3], off offset:2048
	v_add_co_u32_e32 v2, vcc, s73, v66
	s_nop 1
	v_addc_co_u32_e32 v3, vcc, 0, v67, vcc
	global_load_dword v37, v[2:3], off offset:3072
	v_add_co_u32_e32 v2, vcc, s1, v66
	s_nop 1
	v_addc_co_u32_e32 v3, vcc, 0, v67, vcc
	global_load_dword v32, v[2:3], off
	v_add_co_u32_e32 v2, vcc, s13, v66
	s_mov_b32 s13, 0x2b000
	s_nop 0
	v_addc_co_u32_e32 v3, vcc, 0, v67, vcc
	global_load_dword v33, v[2:3], off offset:1024
	v_add_co_u32_e32 v2, vcc, s72, v66
	s_nop 1
	v_addc_co_u32_e32 v3, vcc, 0, v67, vcc
	global_load_dword v34, v[2:3], off offset:2048
	v_add_co_u32_e32 v2, vcc, s13, v66
	s_mov_b32 s13, 0x2d000
	s_nop 0
	v_addc_co_u32_e32 v3, vcc, 0, v67, vcc
	global_load_dword v35, v[2:3], off offset:3072
	v_add_co_u32_e32 v2, vcc, s13, v66
	s_mov_b32 s13, 0x2f000
	s_nop 0
	v_addc_co_u32_e32 v3, vcc, 0, v67, vcc
	global_load_dword v22, v[2:3], off
	v_add_co_u32_e32 v2, vcc, s33, v66
	s_nop 1
	v_addc_co_u32_e32 v3, vcc, 0, v67, vcc
	global_load_dword v23, v[2:3], off offset:1024
	v_add_co_u32_e32 v2, vcc, s13, v66
	s_mov_b32 s13, 0x33000
	s_nop 0
	v_addc_co_u32_e32 v3, vcc, 0, v67, vcc
	global_load_dword v28, v[2:3], off offset:2048
	v_add_co_u32_e32 v2, vcc, s22, v66
	s_nop 1
	v_addc_co_u32_e32 v3, vcc, 0, v67, vcc
	global_load_dword v29, v[2:3], off offset:3072
	v_add_co_u32_e32 v2, vcc, s38, v66
	s_nop 1
	v_addc_co_u32_e32 v3, vcc, 0, v67, vcc
	global_load_dword v24, v[2:3], off
	v_add_co_u32_e32 v2, vcc, s13, v66
	s_mov_b32 s13, 0x35000
	s_nop 0
	v_addc_co_u32_e32 v3, vcc, 0, v67, vcc
	global_load_dword v25, v[2:3], off offset:1024
	v_add_co_u32_e32 v2, vcc, s39, v66
	s_nop 1
	v_addc_co_u32_e32 v3, vcc, 0, v67, vcc
	global_load_dword v26, v[2:3], off offset:2048
	v_add_co_u32_e32 v2, vcc, s13, v66
	s_mov_b32 s13, 0x37000
	s_nop 0
	v_addc_co_u32_e32 v3, vcc, 0, v67, vcc
	global_load_dword v27, v[2:3], off offset:3072
	v_add_co_u32_e32 v2, vcc, s13, v66
	s_mov_b32 s13, 0x39000
	s_nop 0
	v_addc_co_u32_e32 v3, vcc, 0, v67, vcc
	global_load_dword v14, v[2:3], off
	v_add_co_u32_e32 v2, vcc, s69, v66
	s_nop 1
	v_addc_co_u32_e32 v3, vcc, 0, v67, vcc
	global_load_dword v15, v[2:3], off offset:1024
	v_add_co_u32_e32 v2, vcc, s13, v66
	s_mov_b32 s13, 0x3d000
	s_nop 0
	v_addc_co_u32_e32 v3, vcc, 0, v67, vcc
	global_load_dword v20, v[2:3], off offset:2048
	v_add_co_u32_e32 v2, vcc, s87, v66
	s_nop 1
	v_addc_co_u32_e32 v3, vcc, 0, v67, vcc
	global_load_dword v21, v[2:3], off offset:3072
	v_add_co_u32_e32 v2, vcc, s90, v66
	s_nop 1
	v_addc_co_u32_e32 v3, vcc, 0, v67, vcc
	global_load_dword v16, v[2:3], off
	v_add_co_u32_e32 v2, vcc, s13, v66
	s_mov_b32 s13, 0x41000
	s_nop 0
	v_addc_co_u32_e32 v3, vcc, 0, v67, vcc
	global_load_dword v17, v[2:3], off offset:1024
	v_add_co_u32_e32 v2, vcc, s51, v66
	s_nop 1
	v_addc_co_u32_e32 v3, vcc, 0, v67, vcc
	global_load_dword v18, v[2:3], off offset:2048
	v_add_co_u32_e32 v2, vcc, s52, v66
	s_nop 1
	v_addc_co_u32_e32 v3, vcc, 0, v67, vcc
	global_load_dword v19, v[2:3], off offset:3072
	v_add_co_u32_e32 v2, vcc, s13, v66
	s_mov_b32 s13, 0x43000
	s_nop 0
	v_addc_co_u32_e32 v3, vcc, 0, v67, vcc
	global_load_dword v4, v[2:3], off
	v_add_co_u32_e32 v2, vcc, s93, v66
	s_nop 1
	v_addc_co_u32_e32 v3, vcc, 0, v67, vcc
	global_load_dword v5, v[2:3], off offset:1024
	v_add_co_u32_e32 v2, vcc, s13, v66
	s_mov_b32 s13, 0x44000
	s_nop 0
	v_addc_co_u32_e32 v3, vcc, 0, v67, vcc
	global_load_dword v10, v[2:3], off offset:2048
	v_add_co_u32_e32 v2, vcc, s13, v66
	s_mov_b32 s13, 0x46000
	s_nop 0
	v_addc_co_u32_e32 v3, vcc, 0, v67, vcc
	global_load_dword v11, v[2:3], off offset:3072
	v_add_co_u32_e32 v2, vcc, s13, v66
	s_mov_b32 s13, 0x47000
	s_nop 0
	v_addc_co_u32_e32 v3, vcc, 0, v67, vcc
	global_load_dword v6, v[2:3], off
	v_add_co_u32_e32 v2, vcc, s13, v66
	s_mov_b32 s13, 0x48000
	s_nop 0
	v_addc_co_u32_e32 v3, vcc, 0, v67, vcc
	global_load_dword v7, v[2:3], off offset:1024
	v_add_co_u32_e32 v2, vcc, s13, v66
	s_mov_b32 s13, 0x49000
	s_nop 0
	v_addc_co_u32_e32 v3, vcc, 0, v67, vcc
	global_load_dword v12, v[2:3], off offset:2048
	v_add_co_u32_e32 v2, vcc, s13, v66
	s_mov_b32 s13, 0x4b000
	s_nop 0
	v_addc_co_u32_e32 v3, vcc, 0, v67, vcc
	global_load_dword v13, v[2:3], off offset:3072
	v_add_co_u32_e32 v2, vcc, s13, v66
	s_mov_b32 s13, 0x4c000
	s_nop 0
	v_addc_co_u32_e32 v3, vcc, 0, v67, vcc
	v_add_co_u32_e32 v8, vcc, s13, v66
	global_load_dword v2, v[2:3], off
	s_nop 0
	v_addc_co_u32_e32 v9, vcc, 0, v67, vcc
	global_load_dword v3, v[8:9], off offset:1024
	v_add_co_u32_e32 v8, vcc, 0x4d000, v66
	s_nop 1
	v_addc_co_u32_e32 v9, vcc, 0, v67, vcc
	v_add_co_u32_e32 v66, vcc, 0x4e000, v66
	global_load_dword v8, v[8:9], off offset:2048
	s_nop 0
	v_addc_co_u32_e32 v67, vcc, 0, v67, vcc
	global_load_dword v9, v[66:67], off offset:3072
	s_cbranch_scc1 .LBB0_1810
	s_lshl_b64 s[4:5], s[18:19], 2
	s_add_u32 s4, s40, s4
	s_addc_u32 s5, s41, s5
	global_load_dwordx4 v[66:69], v161, s[4:5]
	s_mov_b64 s[30:31], 0
	s_waitcnt vmcnt(0)
	v_pk_mul_f32 v[66:67], v[62:63], v[66:67]
	v_pk_mul_f32 v[68:69], v[64:65], v[68:69]

; #define PIN(i) ((const float*)ldq_(L, (i)))
; __device__ __forceinline__ unsigned pk2(float lo, float hi) { f32x2 v = {lo, hi}; bf16x2_t b = __builtin_convertvector(v, bf16x2_t); return __builtin_bit_cast(unsigned, b); }
; __device__ __forceinline__ void prep(const Params& p, LAS unsigned char* L, int wv, int vb, int nvb, int l, int mask) {
;     ...
;     if (mask & PM_POOL) {
;         for (int t = gt; t < 4 * 128 * 16; t += NGT) {
;             const int ko = t & 15, n = (t >> 4) & 127, g = (t >> 11) & 3;
;             const float* src = PIN(I_WPOOL) + ((size_t)(l * 4 + g) * 128 + 8 * ko) * 128 + n; const float sc = PIN(I_PSCALE)[l * 512 + g * 128 + n];
;             u32x4 o; o.x = pk2(src[0] * sc, src[128] * sc); o.y = pk2(src[256] * sc, src[384] * sc); o.z = pk2(src[512] * sc, src[640] * sc); o.w = pk2(src[768] * sc, src[896] * sc);
;             *(u32x4*)((bf16_t*)(wl + WL_POOL) + ((size_t)g * 128 + n) * 128 + 8 * ko) = o;
;         }
.LBB0_1874:
	v_mov_b32_e32 v4, v161
	v_add_u32_e32 v2, 0x1c000, v2
	v_add_u32_e32 v4, 0, v4
	v_add_u32_e32 v4, 0x20178, v4
	ds_read_b64 v[4:5], v4
	v_bfe_u32 v14, v2, 11, 2
	v_and_b32_e32 v15, 0x78, v3
	v_bfe_u32 v11, v2, 4, 7
	v_lshlrev_b32_e32 v160, 9, v15
	s_waitcnt lgkmcnt(0)
	v_readfirstlane_b32 s18, v4
	v_or_b32_e32 v4, s12, v14
	v_readfirstlane_b32 s19, v5
	v_ashrrev_i32_e32 v5, 31, v4
	v_lshlrev_b64 v[4:5], 16, v[4:5]
	v_lshl_add_u64 v[4:5], s[18:19], 0, v[4:5]
	v_lshl_add_u64 v[4:5], v[4:5], 0, v[160:161]
	v_lshlrev_b32_e32 v160, 2, v11
	v_lshl_add_u64 v[8:9], v[4:5], 0, v[160:161]
	v_mov_b32_e32 v4, v161
	v_lshlrev_b32_e32 v6, 7, v14
	v_add_u32_e32 v4, 0, v4
	v_add_u32_e32 v4, 0x20180, v4
	s_nop 0
	v_or3_b32 v6, v6, s13, v11
	v_ashrrev_i32_e32 v7, 31, v6
	v_cmp_lt_i32_e32 vcc, s21, v2
	v_add_u32_e32 v3, 0xe0000, v3
	s_waitcnt lgkmcnt(0)
	v_readlane_b32 s16, v251, 33
	v_readlane_b32 s18, v251, 32
	s_or_b64 s[10:11], vcc, s[10:11]
	v_mov_b32_e32 v5, s16
	v_mov_b32_e32 v4, s18
	v_lshl_add_u64 v[4:5], v[6:7], 2, v[4:5]
	global_load_dword v10, v[4:5], off
	s_nop 0
	global_load_dword v4, v[8:9], off
	global_load_dword v5, v[8:9], off offset:512
	global_load_dword v6, v[8:9], off offset:1024
	global_load_dword v7, v[8:9], off offset:1536
	s_waitcnt vmcnt(2)
	v_pk_mul_f32 v[4:5], v[10:11], v[4:5] op_sel_hi:[0,1]
	s_waitcnt vmcnt(0)
	v_pk_mul_f32 v[6:7], v[10:11], v[6:7] op_sel_hi:[0,1]
	v_cvt_pk_bf16_f32 v4, v4, v5
	v_cvt_pk_bf16_f32 v5, v6, v7
	global_load_dword v6, v[8:9], off offset:2048
	global_load_dword v7, v[8:9], off offset:2560
	global_load_dword v12, v[8:9], off offset:3072
	global_load_dword v13, v[8:9], off offset:3584
	s_waitcnt vmcnt(2)
	v_pk_mul_f32 v[6:7], v[10:11], v[6:7] op_sel_hi:[0,1]
	s_waitcnt vmcnt(0)
	v_pk_mul_f32 v[8:9], v[10:11], v[12:13] op_sel_hi:[0,1]
	v_cvt_pk_bf16_f32 v6, v6, v7
	v_cvt_pk_bf16_f32 v7, v8, v9
	v_lshlrev_b32_e32 v8, 8, v11
	v_lshl_or_b32 v160, v14, 15, v8
	v_lshl_add_u64 v[8:9], s[8:9], 0, v[160:161]
	v_lshlrev_b32_e32 v160, 1, v15
	v_lshl_add_u64 v[8:9], v[8:9], 0, v[160:161]
	global_store_dwordx4 v[8:9], v[4:7], off
	s_andn2_b64 exec, exec, s[10:11]
	s_cbranch_execnz .LBB0_1874

; #define PIN(i) ((const float*)ldq_(L, (i)))
; __device__ __forceinline__ void prep(const Params& p, LAS unsigned char* L, int wv, int vb, int nvb, int l, int mask) {
;     ...
;     if (mask & PM_P) {
;         bf16_t* pb = (bf16_t*)(ws + WS_PB) + (size_t)l * MT * PED;
;         for (int t0 = gt; t0 < MT * 32; t0 += 4 * NGT) {
;             f32x4 a[4], b[4]; size_t dsto[4];
; #pragma unroll
;             for (int u = 0; u < 4; ++u) {
;                 const int t = min(t0 + u * NGT, MT * 32 - 1);
;                 const int o8 = t & 31, m = t >> 5;
;                 const float* src = ((m < MP) ? PIN(I_PP) + ((size_t)l * MP + m) * PED : PIN(I_PS) + ((size_t)l * MS + (m - MP)) * PED) + 8 * o8;
;                 a[u] = *(const f32x4*)src; b[u] = *(const f32x4*)(src + 4); dsto[u] = (size_t)m * PED + 8 * o8;
.LBB0_1878:
	v_add_u32_e32 v35, 0x70000, v35
	v_ashrrev_i32_e32 v24, 5, v35
	v_cmp_lt_i32_e32 vcc, s57, v24
	s_and_saveexec_b64 s[14:15], vcc
	s_xor_b64 s[18:19], exec, s[14:15]
	s_cbranch_execz .LBB0_1880
	v_mov_b32_e32 v0, v161
	v_add_u32_e32 v160, 0xffff0000, v24
	v_add_u32_e32 v0, 0, v0
	v_add_u32_e32 v0, 0x20118, v0
	s_nop 0
	v_mov_b32_e32 v25, v161
	s_waitcnt lgkmcnt(0)
	v_readlane_b32 s14, v251, 6
	v_readlane_b32 s15, v251, 7
	s_add_u32 s14, s14, s10
	s_addc_u32 s15, s15, s11
	v_lshlrev_b64 v[0:1], 10, v[160:161]
	v_lshl_add_u64 v[0:1], s[14:15], 0, v[0:1]

; #define PIN(i) ((const float*)ldq_(L, (i)))
; __device__ __forceinline__ void prep(const Params& p, LAS unsigned char* L, int wv, int vb, int nvb, int l, int mask) {
;     ...
;     if (mask & PM_P) {
;         bf16_t* pb = (bf16_t*)(ws + WS_PB) + (size_t)l * MT * PED;
;         for (int t0 = gt; t0 < MT * 32; t0 += 4 * NGT) {
;             f32x4 a[4], b[4]; size_t dsto[4];
; #pragma unroll
;             for (int u = 0; u < 4; ++u) {
;                 const int t = min(t0 + u * NGT, MT * 32 - 1);
;                 const int o8 = t & 31, m = t >> 5;
;                 const float* src = ((m < MP) ? PIN(I_PP) + ((size_t)l * MP + m) * PED : PIN(I_PS) + ((size_t)l * MS + (m - MP)) * PED) + 8 * o8;
;                 a[u] = *(const f32x4*)src; b[u] = *(const f32x4*)(src + 4); dsto[u] = (size_t)m * PED + 8 * o8;
.LBB0_1882:
	s_or_b64 exec, exec, s[18:19]
	v_and_b32_e32 v36, 0xf8, v34
	v_lshlrev_b32_e32 v160, 2, v36
	v_lshl_add_u64 v[4:5], v[0:1], 0, v[160:161]
	global_load_dwordx4 v[0:3], v[4:5], off offset:16
	s_nop 0
	global_load_dwordx4 v[4:7], v[4:5], off
	v_min_i32_e32 v10, 0x1f3fff, v35
	v_add_u32_e32 v8, 0x1c000, v10
	v_ashrrev_i32_e32 v26, 5, v8
	v_cmp_lt_i32_e32 vcc, s57, v26
	s_and_saveexec_b64 s[14:15], vcc
	s_xor_b64 s[18:19], exec, s[14:15]
	s_cbranch_execz .LBB0_1884
	v_mov_b32_e32 v8, v161
	v_add_u32_e32 v160, 0xffff0000, v26
	v_add_u32_e32 v8, 0, v8
	v_add_u32_e32 v8, 0x20118, v8
	s_nop 0
	v_mov_b32_e32 v27, v161
	s_waitcnt lgkmcnt(0)
	v_readlane_b32 s14, v251, 6
	v_readlane_b32 s15, v251, 7
	s_add_u32 s14, s14, s10
	s_addc_u32 s15, s15, s11
	v_lshlrev_b64 v[8:9], 10, v[160:161]
	v_lshl_add_u64 v[8:9], s[14:15], 0, v[8:9]

; #define PIN(i) ((const float*)ldq_(L, (i)))
; __device__ __forceinline__ void prep(const Params& p, LAS unsigned char* L, int wv, int vb, int nvb, int l, int mask) {
;     ...
;     if (mask & PM_P) {
;         bf16_t* pb = (bf16_t*)(ws + WS_PB) + (size_t)l * MT * PED;
;         for (int t0 = gt; t0 < MT * 32; t0 += 4 * NGT) {
;             f32x4 a[4], b[4]; size_t dsto[4];
; #pragma unroll
;             for (int u = 0; u < 4; ++u) {
;                 const int t = min(t0 + u * NGT, MT * 32 - 1);
;                 const int o8 = t & 31, m = t >> 5;
;                 const float* src = ((m < MP) ? PIN(I_PP) + ((size_t)l * MP + m) * PED : PIN(I_PS) + ((size_t)l * MS + (m - MP)) * PED) + 8 * o8;
;                 a[u] = *(const f32x4*)src; b[u] = *(const f32x4*)(src + 4); dsto[u] = (size_t)m * PED + 8 * o8;
.LBB0_1886:
	s_or_b64 exec, exec, s[18:19]
	v_lshlrev_b32_e32 v10, 3, v10
	v_and_b32_e32 v37, 0xf8, v10
	v_lshlrev_b32_e32 v160, 2, v37
	v_lshl_add_u64 v[12:13], v[8:9], 0, v[160:161]
	global_load_dwordx4 v[8:11], v[12:13], off offset:16
	s_nop 0
	global_load_dwordx4 v[12:15], v[12:13], off
	v_min_i32_e32 v18, 0x1d7fff, v35
	v_add_u32_e32 v16, 0x38000, v18
	v_ashrrev_i32_e32 v28, 5, v16
	v_cmp_lt_i32_e32 vcc, s57, v28
	s_and_saveexec_b64 s[14:15], vcc
	s_xor_b64 s[18:19], exec, s[14:15]
	s_cbranch_execz .LBB0_1888
	v_mov_b32_e32 v16, v161
	v_add_u32_e32 v160, 0xffff0000, v28
	v_add_u32_e32 v16, 0, v16
	v_add_u32_e32 v16, 0x20118, v16
	s_nop 0
	v_mov_b32_e32 v29, v161
	s_waitcnt lgkmcnt(0)
	v_readlane_b32 s14, v251, 6
	v_readlane_b32 s15, v251, 7
	s_add_u32 s14, s14, s10
	s_addc_u32 s15, s15, s11
	v_lshlrev_b64 v[16:17], 10, v[160:161]
	v_lshl_add_u64 v[16:17], s[14:15], 0, v[16:17]

; #define PIN(i) ((const float*)ldq_(L, (i)))
; __device__ __forceinline__ void prep(const Params& p, LAS unsigned char* L, int wv, int vb, int nvb, int l, int mask) {
;     ...
;     if (mask & PM_P) {
;         bf16_t* pb = (bf16_t*)(ws + WS_PB) + (size_t)l * MT * PED;
;         for (int t0 = gt; t0 < MT * 32; t0 += 4 * NGT) {
;             f32x4 a[4], b[4]; size_t dsto[4];
; #pragma unroll
;             for (int u = 0; u < 4; ++u) {
;                 const int t = min(t0 + u * NGT, MT * 32 - 1);
;                 const int o8 = t & 31, m = t >> 5;
;                 const float* src = ((m < MP) ? PIN(I_PP) + ((size_t)l * MP + m) * PED : PIN(I_PS) + ((size_t)l * MS + (m - MP)) * PED) + 8 * o8;
;                 a[u] = *(const f32x4*)src; b[u] = *(const f32x4*)(src + 4); dsto[u] = (size_t)m * PED + 8 * o8;
.LBB0_1890:
	s_or_b64 exec, exec, s[18:19]
	v_lshlrev_b32_e32 v18, 3, v18
	v_and_b32_e32 v38, 0xf8, v18
	v_lshlrev_b32_e32 v160, 2, v38
	v_lshl_add_u64 v[20:21], v[16:17], 0, v[160:161]
	global_load_dwordx4 v[16:19], v[20:21], off offset:16
	s_nop 0
	global_load_dwordx4 v[20:23], v[20:21], off
	v_min_i32_e32 v39, 0x1bbfff, v35
	v_add_u32_e32 v30, 0x54000, v39
	v_ashrrev_i32_e32 v30, 5, v30
	v_cmp_lt_i32_e32 vcc, s57, v30
	s_and_saveexec_b64 s[14:15], vcc
	s_xor_b64 s[18:19], exec, s[14:15]
	s_cbranch_execz .LBB0_1892
	v_mov_b32_e32 v31, v161
	v_add_u32_e32 v160, 0xffff0000, v30
	v_add_u32_e32 v31, 0, v31
	v_add_u32_e32 v31, 0x20118, v31
	s_nop 0
	v_mov_b32_e32 v31, v161
	s_waitcnt lgkmcnt(0)
	v_readlane_b32 s14, v251, 6
	v_readlane_b32 s15, v251, 7
	s_add_u32 s14, s14, s10
	s_addc_u32 s15, s15, s11
	v_lshlrev_b64 v[32:33], 10, v[160:161]
	v_lshl_add_u64 v[32:33], s[14:15], 0, v[32:33]

; __device__ __forceinline__ unsigned xb_ld(unsigned* p)              { return __hip_atomic_load(p, __ATOMIC_RELAXED, __HIP_MEMORY_SCOPE_AGENT); }
; __device__ __forceinline__ void xcd_barrier_complete(unsigned* bar, unsigned x, unsigned& nloc, unsigned& nx) {
;     const unsigned G = gridDim.x * gridDim.y * gridDim.z;
;     unsigned sum, cnt, mine, sp = 0u;
;     for (;;) {
;         sum = 0u; cnt = 0u; mine = 0u;
; #pragma unroll
;         for (unsigned j = 0; j < 16; ++j) { const unsigned c = xb_ld(&bar[XB_XCNT(j)]); sum += c; cnt += (c > 0u) ? 1u : 0u; mine = (j == x) ? c : mine; }
; __device__ __forceinline__ void xcd_barrier(const XcdBarrier& b, bool t0) {
;     asm volatile("s_waitcnt vmcnt(0)" ::: "memory");
;     __syncthreads();
;     if (t0) {
;         unsigned* bar = b.bar;
;         __builtin_amdgcn_s_waitcnt(0);
;         unsigned nloc = b.st[0], nx = b.st[1];
;         if (nloc == 0u) { xcd_barrier_complete(bar, b.x, nloc, nx); b.st[0] = nloc; b.st[1] = nx; }
.LBB0_1895:
	v_mov_b32_e32 v0, v161
	v_mov_b32_e32 v2, v183
	v_add_u32_e32 v0, 0, v0
	v_add_u32_e32 v0, 0x201c0, v0
	s_nop 0
	s_getreg_b32 s8, hwreg(HW_REG_XCC_ID, 0, 4)
	s_waitcnt vmcnt(0)
	s_waitcnt lgkmcnt(0)
	v_readlane_b32 s7, v251, 49
	v_readlane_b32 s6, v251, 48
	v_cmp_eq_u32_e32 vcc, 0, v2
	s_barrier
	s_and_saveexec_b64 s[4:5], vcc
	s_cbranch_execz .LBB0_1947
	v_readlane_b32 s9, v250, 17
	s_waitcnt vmcnt(0) expcnt(0) lgkmcnt(0)
	s_and_b32 s14, s8, 15
	v_mov_b32_e32 v0, s9
	ds_read_b32 v2, v0
	v_readlane_b32 s9, v250, 18
	s_waitcnt lgkmcnt(0)
	v_cmp_ne_u32_e32 vcc, 0, v2
	v_mov_b32_e32 v0, s9
	ds_read_b32 v0, v0
	s_cbranch_vccnz .LBB0_1911
	s_add_u32 s8, s6, 0x28680200
	s_addc_u32 s9, s7, 0
	s_add_u32 s10, s6, 0x28680400
	s_addc_u32 s11, s7, 0
	s_add_u32 s12, s6, 0x28680500
	s_addc_u32 s13, s7, 0
	s_add_u32 s18, s6, 0x28680600
	s_addc_u32 s19, s7, 0
	s_add_u32 s34, s6, 0x28680700
	s_addc_u32 s35, s7, 0
	s_add_u32 s40, s6, 0x28680800
	s_addc_u32 s41, s7, 0
	s_add_u32 s42, s6, 0x28680900
	s_addc_u32 s43, s7, 0
	s_add_u32 s44, s6, 0x28680a00
	s_addc_u32 s45, s7, 0
	s_add_u32 s48, s6, 0x28680b00
	s_addc_u32 s49, s7, 0
	s_add_u32 s50, s6, 0x28680c00
	s_addc_u32 s51, s7, 0
	s_add_u32 s52, s6, 0x28680d00
	s_addc_u32 s53, s7, 0
	s_add_u32 s56, s6, 0x28680e00
	s_addc_u32 s57, s7, 0
	s_add_u32 s60, s6, 0x28680f00
	s_addc_u32 s61, s7, 0
	s_add_u32 s62, s6, 0x28681000
	s_addc_u32 s63, s7, 0
	s_add_u32 s64, s6, 0x28681100
	s_addc_u32 s65, s7, 0
	s_add_u32 s66, s6, 0x28681200
	s_addc_u32 s67, s7, 0
	s_add_u32 s24, s6, 0x28681300
	s_addc_u32 s25, s7, 0
	s_mov_b32 s15, 1
	s_branch .LBB0_1899

; __device__ __forceinline__ int tid_of(int wv) { return wv * 64 + (int)__builtin_amdgcn_mbcnt_hi(~0u, __builtin_amdgcn_mbcnt_lo(~0u, 0u)); }
; #define LAS __attribute__((address_space(3)))
; #define PIN(i) ((const float*)ldq_(L, (i)))
; #define PREP_CONV(bit, SRC, Kd, Nd, DST, GK, MODE) if (mask & (bit)) { for (int it = gw; it < ((Kd) / 64) * ((Nd) / 64); it += NGW) transpose_item((SRC), (Kd), (Nd), (bf16_t*)(wl + (DST)), (GK), (MODE), scr, it, lane); }
; __device__ __forceinline__ void prep(const Params& p, LAS unsigned char* L, int wv, int vb, int nvb, int l, int mask) {
;     int tid_ = tid_of(wv); asm volatile("" : "+v"(tid_));
;     const int tid = tid_, lane = tid & 63, wave = __builtin_amdgcn_readfirstlane(tid >> 6);
;     const int gw = vb * 8 + wave, NGW = nvb * 8; const int gt = vb * 512 + tid, NGT = nvb * 512;
;     LAS float* scr = (LAS float*)(L + wave * 16384);
;     unsigned char* ws = PWS; unsigned char* wl = ws + WS_W + (size_t)l * WL_STRIDE;
;     ...
;     PREP_CONV(PM_FFA_IN, PIN(I_WFFA_IN) + (size_t)l * DM * NFF2, DM, NFF2, WL_FFA_IN, PIN(I_NFFA) + l * DM, 1)
;     PREP_CONV(PM_FFA_OUT, PIN(I_WFFA_OUT) + (size_t)l * DFF * DM, DFF, DM, WL_FFA_OUT, nullptr, 0)
;     PREP_CONV(PM_WIN, PIN(I_WIN) + (size_t)l * DM * NIN, DM, NIN, WL_IN, PIN(I_NMIX) + l * DM, 0)
;     PREP_CONV(PM_WOUT, PIN(I_WOUT) + (size_t)l * DM * DM, DM, DM, WL_OUT, nullptr, 0)
;     PREP_CONV(PM_FFB_IN, PIN(I_WFFB_IN) + (size_t)l * DM * NFF2, DM, NFF2, WL_FFB_IN, PIN(I_NFFB) + l * DM, 1)
.LBB0_1979:
	s_mov_b32 s6, s20
	s_mov_b32 s4, s60
	s_mov_b32 s5, s2
	s_cmpk_eq_i32 s6, 0x100
	s_cselect_b64 s[6:7], -1, 0
	s_cmp_gt_i32 s5, 31
	s_cselect_b64 s[8:9], -1, 0
	s_and_b64 s[6:7], s[6:7], s[8:9]
	s_cmp_lt_i32 s4, 2
	s_cselect_b64 s[8:9], -1, 0
	s_and_b64 s[6:7], s[6:7], s[8:9]
	s_andn2_b64 vcc, exec, s[6:7]
	s_cbranch_vccnz .LBB0_2047
	s_waitcnt lgkmcnt(0)
	v_mov_b32_e32 v0, v183
	v_mov_b32_e32 v1, v161
	s_lshl_b32 s5, s5, 3
	v_add_u32_e32 v1, 0, v1
	v_add_u32_e32 v1, 0x201c0, v1
	s_nop 0
	v_readfirstlane_b32 s6, v0
	s_ashr_i32 s6, s6, 6
	s_add_i32 s5, s5, s6
	s_add_i32 s14, s5, 0xffffff00
	s_waitcnt lgkmcnt(0)
	v_readlane_b32 s5, v251, 49
	s_cmpk_gt_i32 s14, 0x57f
	v_readlane_b32 s7, v251, 48
	s_cbranch_scc1 .LBB0_2047
	s_mul_i32 s8, s4, 0x2900000
	s_mul_hi_i32 s9, s4, 0x2900000
	s_add_u32 s8, s7, s8
	v_and_b32_e32 v1, 7, v0
	s_addc_u32 s9, s5, s9
	s_lshl_b32 s5, s6, 14
	s_mul_hi_i32 s15, s4, 0x1600000
	s_mul_i32 s16, s4, 0x1600000
	s_lshl_b32 s4, s4, 10
	v_bfe_u32 v71, v0, 3, 3
	v_lshlrev_b32_e32 v160, 4, v1
	s_add_i32 s6, s5, 0
	v_and_b32_e32 v2, 63, v0
	s_ashr_i32 s5, s4, 31
	v_mul_u32_u24_e32 v3, 0x410, v1
	v_lshl_add_u64 v[0:1], s[8:9], 0, v[160:161]
	s_mov_b64 s[8:9], 0x1500000
	v_lshlrev_b32_e32 v4, 2, v71
	v_lshl_add_u32 v70, v2, 2, s6
	v_lshl_add_u64 v[0:1], v[0:1], 0, s[8:9]
	v_add3_u32 v72, s6, v3, v4
	s_lshl_b32 s18, s14, 6
	s_lshl_b32 s19, s14, 5
	s_lshl_b64 s[6:7], s[4:5], 2
	v_lshlrev_b32_e32 v160, 2, v2
	s_branch .LBB0_1983

; #define LAS __attribute__((address_space(3)))
; #define PIN(i) ((const float*)ldq_(L, (i)))
; __device__ __forceinline__ unsigned pk2(float lo, float hi) { f32x2 v = {lo, hi}; bf16x2_t b = __builtin_convertvector(v, bf16x2_t); return __builtin_bit_cast(unsigned, b); }
; #define PREP_CONV(bit, SRC, Kd, Nd, DST, GK, MODE) if (mask & (bit)) { for (int it = gw; it < ((Kd) / 64) * ((Nd) / 64); it += NGW) transpose_item((SRC), (Kd), (Nd), (bf16_t*)(wl + (DST)), (GK), (MODE), scr, it, lane); }
; __device__ __forceinline__ void transpose_item(const float* W, int K, int N, bf16_t* WT, const float* gk, int mode, LAS float* scr_, int item, int lane) {
;     LAS unsigned* scr = (LAS unsigned*)scr_;
;     const int nblk = N / 64, kb = item / nblk, nb = item % nblk, k0 = 64 * kb, n0 = 64 * nb;
;     const int sc = (mode == 1) ? (((n0 >> 7) & 1) * DFF + (n0 >> 8) * 128 + (n0 & 127)) : n0;
;     const float* src = W + (size_t)k0 * N + sc + lane;
;     float va[32], vb[32];
; #pragma unroll
;     for (int kp = 0; kp < 32; ++kp) { va[kp] = src[(size_t)(2 * kp) * N]; vb[kp] = src[(size_t)(2 * kp + 1) * N]; }
; #pragma unroll
;     for (int kp = 0; kp < 32; ++kp) {
;         float a = va[kp], b = vb[kp];
;         if (gk) { a *= gk[k0 + 2 * kp]; b *= gk[k0 + 2 * kp + 1]; }
;         scr[kp * 65 + lane] = pk2(a, b);
; __device__ __forceinline__ void prep(const Params& p, LAS unsigned char* L, int wv, int vb, int nvb, int l, int mask) {
;     ...
;     PREP_CONV(PM_FFB_IN, PIN(I_WFFB_IN) + (size_t)l * DM * NFF2, DM, NFF2, WL_FFB_IN, PIN(I_NFFB) + l * DM, 1)
.LBB0_1983:
	v_mov_b32_e32 v2, v161
	s_mul_hi_i32 s8, s14, 0x2e8ba2e9
	v_add_u32_e32 v2, 0, v2
	v_add_u32_e32 v2, 0x20198, v2
	ds_read_b64 v[2:3], v2
	s_waitcnt lgkmcnt(0)
	v_readfirstlane_b32 s5, v2
	v_mov_b32_e32 v2, v161
	v_readfirstlane_b32 s4, v3
	v_add_u32_e32 v2, 0, v2
	v_add_u32_e32 v2, 0x20190, v2
	s_nop 0
	s_add_u32 s11, s5, s16
	s_addc_u32 s12, s4, s15
	s_waitcnt lgkmcnt(0)
	v_readlane_b32 s4, v251, 36
	v_readlane_b32 s5, v251, 37
	s_add_u32 s25, s4, s6
	s_addc_u32 s29, s5, s7
	s_lshr_b32 s9, s8, 31
	s_ashr_i32 s8, s8, 4
	s_add_i32 s13, s8, s9
	s_mul_i32 s9, s13, 0xffffea00
	s_mul_i32 s10, s13, 0xfffff500
	s_add_i32 s24, s18, s9
	s_bfe_i32 s9, s14, 0x10001
	s_add_i32 s10, s19, s10
	s_and_b32 s9, s9, 0xb00
	s_and_b32 s10, s10, 0xffffff80
	s_lshl_b32 s8, s13, 6
	s_add_i32 s9, s9, s10
	s_and_b32 s10, s24, 64
	s_or_b32 s10, s9, s10
	s_ashr_i32 s9, s8, 31
	s_mul_i32 s13, s13, 0x160000
	s_mul_hi_i32 s21, s8, 0x5800
	s_add_u32 s13, s11, s13
	s_addc_u32 s12, s12, s21
	s_ashr_i32 s11, s10, 31
	s_lshl_b64 s[10:11], s[10:11], 2
	s_add_u32 s10, s13, s10
	s_addc_u32 s11, s12, s11
	s_waitcnt vmcnt(9)
	v_lshl_add_u64 v[66:67], s[10:11], 0, v[160:161]
	global_load_dword v62, v160, s[10:11]
	s_movk_i32 s10, 0x5000
	v_add_co_u32_e32 v2, vcc, s10, v66
	s_mov_b32 s10, 0xb000
	s_nop 0
	v_addc_co_u32_e32 v3, vcc, 0, v67, vcc
	global_load_dword v63, v[2:3], off offset:2048
	v_add_co_u32_e32 v2, vcc, s10, v66
	s_mov_b32 s10, 0x1b000
	s_nop 0
	v_addc_co_u32_e32 v3, vcc, 0, v67, vcc
	global_load_dword v64, v[2:3], off
	v_add_co_u32_e32 v2, vcc, s37, v66
	s_cmp_lg_u64 s[4:5], 0
	s_nop 0
	v_addc_co_u32_e32 v3, vcc, 0, v67, vcc
	global_load_dword v65, v[2:3], off offset:2048
	v_add_co_u32_e32 v2, vcc, s47, v66
	s_mov_b64 s[12:13], -1
	s_nop 0
	v_addc_co_u32_e32 v3, vcc, 0, v67, vcc
	global_load_dword v54, v[2:3], off
	v_add_co_u32_e32 v2, vcc, s10, v66
	s_mov_b32 s10, 0x21000
	s_nop 0
	v_addc_co_u32_e32 v3, vcc, 0, v67, vcc
	global_load_dword v55, v[2:3], off offset:2048
	v_add_co_u32_e32 v2, vcc, s10, v66
	s_mov_b32 s10, 0x31000
	s_nop 0
	v_addc_co_u32_e32 v3, vcc, 0, v67, vcc
	global_load_dword v60, v[2:3], off
	v_add_co_u32_e32 v2, vcc, s73, v66
	s_nop 1
	v_addc_co_u32_e32 v3, vcc, 0, v67, vcc
	global_load_dword v61, v[2:3], off offset:2048
	v_add_co_u32_e32 v2, vcc, s82, v66
	s_nop 1
	v_addc_co_u32_e32 v3, vcc, 0, v67, vcc
	global_load_dword v56, v[2:3], off
	v_add_co_u32_e32 v2, vcc, s10, v66
	s_mov_b32 s10, 0x37000
	s_nop 0
	v_addc_co_u32_e32 v3, vcc, 0, v67, vcc
	global_load_dword v57, v[2:3], off offset:2048
	v_add_co_u32_e32 v2, vcc, s10, v66
	s_mov_b32 s10, 0x47000
	s_nop 0
	v_addc_co_u32_e32 v3, vcc, 0, v67, vcc
	global_load_dword v58, v[2:3], off
	v_add_co_u32_e32 v2, vcc, s90, v66
	s_nop 1
	v_addc_co_u32_e32 v3, vcc, 0, v67, vcc
	global_load_dword v59, v[2:3], off offset:2048
	v_add_co_u32_e32 v2, vcc, s93, v66
	s_nop 1
	v_addc_co_u32_e32 v3, vcc, 0, v67, vcc
	global_load_dword v44, v[2:3], off
	v_add_co_u32_e32 v2, vcc, s10, v66
	s_mov_b32 s10, 0x4d000
	s_nop 0
	v_addc_co_u32_e32 v3, vcc, 0, v67, vcc
	global_load_dword v45, v[2:3], off offset:2048
	v_add_co_u32_e32 v2, vcc, s10, v66
	s_mov_b32 s10, 0x52000
	s_nop 0
	v_addc_co_u32_e32 v3, vcc, 0, v67, vcc
	global_load_dword v50, v[2:3], off
	v_add_co_u32_e32 v2, vcc, s10, v66
	s_mov_b32 s10, 0x58000
	s_nop 0
	v_addc_co_u32_e32 v3, vcc, 0, v67, vcc
	global_load_dword v51, v[2:3], off offset:2048
	v_add_co_u32_e32 v2, vcc, s10, v66
	s_mov_b32 s10, 0x5d000
	s_nop 0
	v_addc_co_u32_e32 v3, vcc, 0, v67, vcc
	global_load_dword v48, v[2:3], off
	v_add_co_u32_e32 v2, vcc, s10, v66
	s_mov_b32 s10, 0x63000
	s_nop 0
	v_addc_co_u32_e32 v3, vcc, 0, v67, vcc
	global_load_dword v49, v[2:3], off offset:2048
	v_add_co_u32_e32 v2, vcc, s10, v66
	s_mov_b32 s10, 0x68000
	s_nop 0
	v_addc_co_u32_e32 v3, vcc, 0, v67, vcc
	global_load_dword v52, v[2:3], off
	v_add_co_u32_e32 v2, vcc, s10, v66
	s_mov_b32 s10, 0x6e000
	s_nop 0
	v_addc_co_u32_e32 v3, vcc, 0, v67, vcc
	global_load_dword v53, v[2:3], off offset:2048
	v_add_co_u32_e32 v2, vcc, s10, v66
	s_mov_b32 s10, 0x73000
	s_nop 0
	v_addc_co_u32_e32 v3, vcc, 0, v67, vcc
	global_load_dword v38, v[2:3], off
	v_add_co_u32_e32 v2, vcc, s10, v66
	s_mov_b32 s10, 0x79000
	s_nop 0
	v_addc_co_u32_e32 v3, vcc, 0, v67, vcc
	global_load_dword v39, v[2:3], off offset:2048
	v_add_co_u32_e32 v2, vcc, s10, v66
	s_mov_b32 s10, 0x7e000
	s_nop 0
	v_addc_co_u32_e32 v3, vcc, 0, v67, vcc
	global_load_dword v42, v[2:3], off
	v_add_co_u32_e32 v2, vcc, s10, v66
	s_mov_b32 s10, 0x84000
	s_nop 0
	v_addc_co_u32_e32 v3, vcc, 0, v67, vcc
	global_load_dword v43, v[2:3], off offset:2048
	v_add_co_u32_e32 v2, vcc, s10, v66
	s_mov_b32 s10, 0x89000
	s_nop 0
	v_addc_co_u32_e32 v3, vcc, 0, v67, vcc
	global_load_dword v40, v[2:3], off
	v_add_co_u32_e32 v2, vcc, s10, v66
	s_mov_b32 s10, 0x8f000
	s_nop 0
	v_addc_co_u32_e32 v3, vcc, 0, v67, vcc
	global_load_dword v41, v[2:3], off offset:2048
	v_add_co_u32_e32 v2, vcc, s10, v66
	s_mov_b32 s10, 0x94000
	s_nop 0
	v_addc_co_u32_e32 v3, vcc, 0, v67, vcc
	global_load_dword v46, v[2:3], off
	v_add_co_u32_e32 v2, vcc, s10, v66
	s_mov_b32 s10, 0x9a000
	s_nop 0
	v_addc_co_u32_e32 v3, vcc, 0, v67, vcc
	global_load_dword v47, v[2:3], off offset:2048
	v_add_co_u32_e32 v2, vcc, s10, v66
	s_mov_b32 s10, 0x9f000
	s_nop 0
	v_addc_co_u32_e32 v3, vcc, 0, v67, vcc
	global_load_dword v30, v[2:3], off
	v_add_co_u32_e32 v2, vcc, s10, v66
	s_mov_b32 s10, 0xa5000
	s_nop 0
; __device__ __forceinline__ void transpose_item(const float* W, int K, int N, bf16_t* WT, const float* gk, int mode, LAS float* scr_, int item, int lane) {
;     ...
;     for (int kp = 0; kp < 32; ++kp) { va[kp] = src[(size_t)(2 * kp) * N]; vb[kp] = src[(size_t)(2 * kp + 1) * N]; }
; #pragma unroll
;     for (int kp = 0; kp < 32; ++kp) {
;         float a = va[kp], b = vb[kp];
;         if (gk) { a *= gk[k0 + 2 * kp]; b *= gk[k0 + 2 * kp + 1]; }
	v_addc_co_u32_e32 v3, vcc, 0, v67, vcc
	global_load_dword v31, v[2:3], off offset:2048
	v_add_co_u32_e32 v2, vcc, s10, v66
	s_mov_b32 s10, 0xaa000
	s_nop 0
	v_addc_co_u32_e32 v3, vcc, 0, v67, vcc
	global_load_dword v36, v[2:3], off
	v_add_co_u32_e32 v2, vcc, s10, v66
	s_mov_b32 s10, 0xb5000
	s_nop 0
	v_addc_co_u32_e32 v3, vcc, 0, v67, vcc
	global_load_dword v37, v[2:3], off offset:2048
	v_add_co_u32_e32 v2, vcc, s95, v66
	s_nop 1
	v_addc_co_u32_e32 v3, vcc, 0, v67, vcc
	global_load_dword v32, v[2:3], off
	v_add_co_u32_e32 v2, vcc, s10, v66
	s_mov_b32 s10, 0xbb000
	s_nop 0
	v_addc_co_u32_e32 v3, vcc, 0, v67, vcc
	global_load_dword v33, v[2:3], off offset:2048
	v_add_co_u32_e32 v2, vcc, s10, v66
	s_mov_b32 s10, 0xc0000
	s_nop 0
	v_addc_co_u32_e32 v3, vcc, 0, v67, vcc
	global_load_dword v34, v[2:3], off
	v_add_co_u32_e32 v2, vcc, s10, v66
	s_mov_b32 s10, 0xcb000
	s_nop 0
	v_addc_co_u32_e32 v3, vcc, 0, v67, vcc
	global_load_dword v35, v[2:3], off offset:2048
	v_add_co_u32_e32 v2, vcc, s89, v66
	s_nop 1
	v_addc_co_u32_e32 v3, vcc, 0, v67, vcc
	global_load_dword v20, v[2:3], off
	v_add_co_u32_e32 v2, vcc, s10, v66
	s_mov_b32 s10, 0xd1000
	s_nop 0
	v_addc_co_u32_e32 v3, vcc, 0, v67, vcc
	global_load_dword v21, v[2:3], off offset:2048
	v_add_co_u32_e32 v2, vcc, s10, v66
	s_mov_b32 s10, 0xd6000
	s_nop 0
	v_addc_co_u32_e32 v3, vcc, 0, v67, vcc
	global_load_dword v26, v[2:3], off
	v_add_co_u32_e32 v2, vcc, s10, v66
	s_mov_b32 s10, 0xdc000
	s_nop 0
	v_addc_co_u32_e32 v3, vcc, 0, v67, vcc
	global_load_dword v27, v[2:3], off offset:2048
	v_add_co_u32_e32 v2, vcc, s10, v66
	s_mov_b32 s10, 0xe1000
	s_nop 0
	v_addc_co_u32_e32 v3, vcc, 0, v67, vcc
	global_load_dword v24, v[2:3], off
	v_add_co_u32_e32 v2, vcc, s10, v66
	s_mov_b32 s10, 0xe7000
	s_nop 0
	v_addc_co_u32_e32 v3, vcc, 0, v67, vcc
	global_load_dword v25, v[2:3], off offset:2048
	v_add_co_u32_e32 v2, vcc, s10, v66
	s_mov_b32 s10, 0xec000
	s_nop 0
	v_addc_co_u32_e32 v3, vcc, 0, v67, vcc
	global_load_dword v28, v[2:3], off
	v_add_co_u32_e32 v2, vcc, s10, v66
	s_mov_b32 s10, 0xf2000
	s_nop 0
	v_addc_co_u32_e32 v3, vcc, 0, v67, vcc
	global_load_dword v29, v[2:3], off offset:2048
	v_add_co_u32_e32 v2, vcc, s10, v66
	s_mov_b32 s10, 0xf7000
	s_nop 0
	v_addc_co_u32_e32 v3, vcc, 0, v67, vcc
	global_load_dword v12, v[2:3], off
	v_add_co_u32_e32 v2, vcc, s10, v66
	s_mov_b32 s10, 0xfd000
	s_nop 0
	v_addc_co_u32_e32 v3, vcc, 0, v67, vcc
	global_load_dword v13, v[2:3], off offset:2048
	v_add_co_u32_e32 v2, vcc, s10, v66
	s_mov_b32 s10, 0x102000
	s_nop 0
	v_addc_co_u32_e32 v3, vcc, 0, v67, vcc
	global_load_dword v18, v[2:3], off
	v_add_co_u32_e32 v2, vcc, s10, v66
	s_mov_b32 s10, 0x108000
	s_nop 0
	v_addc_co_u32_e32 v3, vcc, 0, v67, vcc
	global_load_dword v19, v[2:3], off offset:2048
	v_add_co_u32_e32 v2, vcc, s10, v66
	s_mov_b32 s10, 0x10d000
	s_nop 0
	v_addc_co_u32_e32 v3, vcc, 0, v67, vcc
	global_load_dword v16, v[2:3], off
	v_add_co_u32_e32 v2, vcc, s10, v66
	s_mov_b32 s10, 0x113000
	s_nop 0
	v_addc_co_u32_e32 v3, vcc, 0, v67, vcc
	global_load_dword v17, v[2:3], off offset:2048
	v_add_co_u32_e32 v2, vcc, s10, v66
	s_mov_b32 s10, 0x118000
	s_nop 0
	v_addc_co_u32_e32 v3, vcc, 0, v67, vcc
	global_load_dword v22, v[2:3], off
	v_add_co_u32_e32 v2, vcc, s10, v66
	s_mov_b32 s10, 0x11e000
	s_nop 0
	v_addc_co_u32_e32 v3, vcc, 0, v67, vcc
	global_load_dword v23, v[2:3], off offset:2048
	v_add_co_u32_e32 v2, vcc, s10, v66
	s_mov_b32 s10, 0x123000
	s_nop 0
	v_addc_co_u32_e32 v3, vcc, 0, v67, vcc
	global_load_dword v4, v[2:3], off
	v_add_co_u32_e32 v2, vcc, s10, v66
	s_mov_b32 s10, 0x129000
	s_nop 0
	v_addc_co_u32_e32 v3, vcc, 0, v67, vcc
	global_load_dword v5, v[2:3], off offset:2048
	v_add_co_u32_e32 v2, vcc, s10, v66
	s_mov_b32 s10, 0x12e000
	s_nop 0
	v_addc_co_u32_e32 v3, vcc, 0, v67, vcc
	global_load_dword v10, v[2:3], off
	v_add_co_u32_e32 v2, vcc, s10, v66
	s_mov_b32 s10, 0x134000
	s_nop 0
	v_addc_co_u32_e32 v3, vcc, 0, v67, vcc
	global_load_dword v11, v[2:3], off offset:2048
	v_add_co_u32_e32 v2, vcc, s10, v66
	s_mov_b32 s10, 0x139000
	s_nop 0
	v_addc_co_u32_e32 v3, vcc, 0, v67, vcc
	global_load_dword v6, v[2:3], off
	v_add_co_u32_e32 v2, vcc, s10, v66
	s_mov_b32 s10, 0x13f000
	s_nop 0
	v_addc_co_u32_e32 v3, vcc, 0, v67, vcc
	global_load_dword v7, v[2:3], off offset:2048
	v_add_co_u32_e32 v2, vcc, s10, v66
	s_mov_b32 s10, 0x144000
	s_nop 0
	v_addc_co_u32_e32 v3, vcc, 0, v67, vcc
	global_load_dword v14, v[2:3], off
	v_add_co_u32_e32 v2, vcc, s10, v66
	s_mov_b32 s10, 0x14a000
	s_nop 0
	v_addc_co_u32_e32 v3, vcc, 0, v67, vcc
	global_load_dword v15, v[2:3], off offset:2048
	v_add_co_u32_e32 v2, vcc, s10, v66
	s_mov_b32 s10, 0x14f000
	s_nop 0
	v_addc_co_u32_e32 v3, vcc, 0, v67, vcc
	v_add_co_u32_e32 v8, vcc, s10, v66
	global_load_dword v2, v[2:3], off
	s_nop 0
	v_addc_co_u32_e32 v9, vcc, 0, v67, vcc
	global_load_dword v3, v[8:9], off offset:2048
	v_add_co_u32_e32 v8, vcc, 0x155000, v66
	s_cselect_b64 s[10:11], -1, 0
	s_nop 0
	v_addc_co_u32_e32 v9, vcc, 0, v67, vcc
	v_add_co_u32_e32 v66, vcc, 0x15a000, v66
	global_load_dword v8, v[8:9], off
	s_nop 0
	v_addc_co_u32_e32 v67, vcc, 0, v67, vcc
	global_load_dword v9, v[66:67], off offset:2048
	s_cmp_eq_u64 s[4:5], 0
	s_cbranch_scc1 .LBB0_1985
	s_lshl_b64 s[4:5], s[8:9], 2
	s_add_u32 s4, s25, s4
	s_addc_u32 s5, s29, s5
	global_load_dwordx4 v[66:69], v161, s[4:5]
	s_mov_b64 s[12:13], 0
	s_waitcnt vmcnt(0)
	v_pk_mul_f32 v[66:67], v[62:63], v[66:67]
	v_pk_mul_f32 v[68:69], v[64:65], v[68:69]

; __device__ __forceinline__ unsigned xb_ld(unsigned* p)              { return __hip_atomic_load(p, __ATOMIC_RELAXED, __HIP_MEMORY_SCOPE_AGENT); }
; __device__ __forceinline__ void xcd_barrier_complete(unsigned* bar, unsigned x, unsigned& nloc, unsigned& nx) {
;     const unsigned G = gridDim.x * gridDim.y * gridDim.z;
;     unsigned sum, cnt, mine, sp = 0u;
;     for (;;) {
;         sum = 0u; cnt = 0u; mine = 0u;
; #pragma unroll
;         for (unsigned j = 0; j < 16; ++j) { const unsigned c = xb_ld(&bar[XB_XCNT(j)]); sum += c; cnt += (c > 0u) ? 1u : 0u; mine = (j == x) ? c : mine; }
; __device__ __forceinline__ void xcd_barrier(const XcdBarrier& b, bool t0) {
;     asm volatile("s_waitcnt vmcnt(0)" ::: "memory");
;     __syncthreads();
;     if (t0) {
;         unsigned* bar = b.bar;
;         __builtin_amdgcn_s_waitcnt(0);
;         unsigned nloc = b.st[0], nx = b.st[1];
;         if (nloc == 0u) { xcd_barrier_complete(bar, b.x, nloc, nx); b.st[0] = nloc; b.st[1] = nx; }
.LBB0_2047:
	s_waitcnt lgkmcnt(0)
	v_mov_b32_e32 v0, v161
	v_mov_b32_e32 v2, v183
	v_add_u32_e32 v0, 0, v0
	v_add_u32_e32 v0, 0x201c0, v0
	s_nop 0
	s_getreg_b32 s8, hwreg(HW_REG_XCC_ID, 0, 4)
	s_waitcnt vmcnt(0)
	s_waitcnt lgkmcnt(0)
	v_readlane_b32 s7, v251, 49
	v_readlane_b32 s6, v251, 48
	v_cmp_eq_u32_e32 vcc, 0, v2
	s_barrier
	s_and_saveexec_b64 s[4:5], vcc
	s_cbranch_execz .LBB0_2099
	v_readlane_b32 s9, v250, 17
	s_waitcnt vmcnt(0) expcnt(0) lgkmcnt(0)
	s_and_b32 s14, s8, 15
	v_mov_b32_e32 v0, s9
	ds_read_b32 v2, v0
	v_readlane_b32 s9, v250, 18
	s_waitcnt lgkmcnt(0)
	v_cmp_ne_u32_e32 vcc, 0, v2
	v_mov_b32_e32 v0, s9
	ds_read_b32 v0, v0
	s_cbranch_vccnz .LBB0_2063
	s_add_u32 s8, s6, 0x28680200
	s_addc_u32 s9, s7, 0
	s_add_u32 s10, s6, 0x28680400
	s_addc_u32 s11, s7, 0
	s_add_u32 s12, s6, 0x28680500
	s_addc_u32 s13, s7, 0
	s_add_u32 s18, s6, 0x28680600
	s_addc_u32 s19, s7, 0
	s_add_u32 s34, s6, 0x28680700
	s_addc_u32 s35, s7, 0
	s_add_u32 s40, s6, 0x28680800
	s_addc_u32 s41, s7, 0
	s_add_u32 s42, s6, 0x28680900
	s_addc_u32 s43, s7, 0
	s_add_u32 s44, s6, 0x28680a00
	s_addc_u32 s45, s7, 0
	s_add_u32 s48, s6, 0x28680b00
	s_addc_u32 s49, s7, 0
	s_add_u32 s50, s6, 0x28680c00
	s_addc_u32 s51, s7, 0
	s_add_u32 s52, s6, 0x28680d00
	s_addc_u32 s53, s7, 0
	s_add_u32 s56, s6, 0x28680e00
	s_addc_u32 s57, s7, 0
	s_add_u32 s60, s6, 0x28680f00
	s_addc_u32 s61, s7, 0
	s_add_u32 s62, s6, 0x28681000
	s_addc_u32 s63, s7, 0
	s_add_u32 s64, s6, 0x28681100
	s_addc_u32 s65, s7, 0
	s_add_u32 s66, s6, 0x28681200
	s_addc_u32 s67, s7, 0
	s_add_u32 s24, s6, 0x28681300
	s_addc_u32 s25, s7, 0
	s_mov_b32 s15, 1
	s_branch .LBB0_2051

; __device__ __forceinline__ unsigned xb_ld(unsigned* p)              { return __hip_atomic_load(p, __ATOMIC_RELAXED, __HIP_MEMORY_SCOPE_AGENT); }
; __device__ __forceinline__ void xcd_barrier_complete(unsigned* bar, unsigned x, unsigned& nloc, unsigned& nx) {
;     const unsigned G = gridDim.x * gridDim.y * gridDim.z;
;     unsigned sum, cnt, mine, sp = 0u;
;     for (;;) {
;         sum = 0u; cnt = 0u; mine = 0u;
; #pragma unroll
;         for (unsigned j = 0; j < 16; ++j) { const unsigned c = xb_ld(&bar[XB_XCNT(j)]); sum += c; cnt += (c > 0u) ? 1u : 0u; mine = (j == x) ? c : mine; }
; __device__ __forceinline__ void xcd_barrier(const XcdBarrier& b, bool t0) {
;     asm volatile("s_waitcnt vmcnt(0)" ::: "memory");
;     __syncthreads();
;     if (t0) {
;         unsigned* bar = b.bar;
;         __builtin_amdgcn_s_waitcnt(0);
;         unsigned nloc = b.st[0], nx = b.st[1];
;         if (nloc == 0u) { xcd_barrier_complete(bar, b.x, nloc, nx); b.st[0] = nloc; b.st[1] = nx; }
.LBB0_2220:
	s_waitcnt lgkmcnt(0)
	v_mov_b32_e32 v0, v161
	v_mov_b32_e32 v2, v183
	v_add_u32_e32 v0, 0, v0
	v_add_u32_e32 v0, 0x201c0, v0
	s_nop 0
	s_getreg_b32 s8, hwreg(HW_REG_XCC_ID, 0, 4)
	s_waitcnt vmcnt(0)
	s_waitcnt vmcnt(0) lgkmcnt(0)
	v_readlane_b32 s7, v251, 49
	v_readlane_b32 s6, v251, 48
	v_cmp_eq_u32_e32 vcc, 0, v2
	s_barrier
	s_and_saveexec_b64 s[4:5], vcc
	s_cbranch_execz .LBB0_2272
	v_readlane_b32 s9, v250, 17
	s_waitcnt vmcnt(0) expcnt(0) lgkmcnt(0)
	s_and_b32 s14, s8, 15
	v_mov_b32_e32 v0, s9
	ds_read_b32 v2, v0
	v_readlane_b32 s9, v250, 18
	s_waitcnt lgkmcnt(0)
	v_cmp_ne_u32_e32 vcc, 0, v2
	v_mov_b32_e32 v0, s9
	ds_read_b32 v0, v0
	s_cbranch_vccnz .LBB0_2236
	s_add_u32 s8, s6, 0x28680200
	s_addc_u32 s9, s7, 0
	s_add_u32 s10, s6, 0x28680400
	s_addc_u32 s11, s7, 0
	s_add_u32 s12, s6, 0x28680500
	s_addc_u32 s13, s7, 0
	s_add_u32 s18, s6, 0x28680600
	s_addc_u32 s19, s7, 0
	s_add_u32 s34, s6, 0x28680700
	s_addc_u32 s35, s7, 0
	s_add_u32 s40, s6, 0x28680800
	s_addc_u32 s41, s7, 0
	s_add_u32 s42, s6, 0x28680900
	s_addc_u32 s43, s7, 0
	s_add_u32 s44, s6, 0x28680a00
	s_addc_u32 s45, s7, 0
	s_add_u32 s48, s6, 0x28680b00
	s_addc_u32 s49, s7, 0
	s_add_u32 s50, s6, 0x28680c00
	s_addc_u32 s51, s7, 0
	s_add_u32 s52, s6, 0x28680d00
	s_addc_u32 s53, s7, 0
	s_add_u32 s56, s6, 0x28680e00
	s_addc_u32 s57, s7, 0
	s_add_u32 s60, s6, 0x28680f00
	s_addc_u32 s61, s7, 0
	s_add_u32 s62, s6, 0x28681000
	s_addc_u32 s63, s7, 0
	s_add_u32 s64, s6, 0x28681100
	s_addc_u32 s65, s7, 0
	s_add_u32 s66, s6, 0x28681200
	s_addc_u32 s67, s7, 0
	s_add_u32 s24, s6, 0x28681300
	s_addc_u32 s25, s7, 0
	s_mov_b32 s15, 1
	s_branch .LBB0_2224

; __device__ __forceinline__ int tid_of(int wv) { return wv * 64 + (int)__builtin_amdgcn_mbcnt_hi(~0u, __builtin_amdgcn_mbcnt_lo(~0u, 0u)); }
; template <class Epi, class Sched, bool ALIGN_EPI = false, bool SP2 = false>
; __device__ __forceinline__ void gemm_phase(PG8_LAS unsigned char* lds, const Gemm g, const Sched& S, const Epi& E, int wv) {
;     int tid_ = tid_of(wv); asm volatile("" : "+v"(tid_));
;     const int tid = tid_, wid = __builtin_amdgcn_readfirstlane(tid >> 6), lane = tid & 63, wr = wid >> 2, wc = wid & 3, fr = lane & 15, fq = lane >> 4;
;     const int K = g.K, nt = K / BK;
;     unsigned voffA[2], voffB[2];
; #pragma unroll
;     for (int i = 0; i < 2; ++i) { int R, C; stage_rc(tid * 16 + i * 8192, R, C); const int Rb = Epi::PERM ? ((R & ~31) + perm32(R & 31)) : R;
;         voffA[i] = (unsigned)(R * K + C) * 2u; voffB[i] = (unsigned)(Rb * K + C) * 2u; }
;     const size_t kstep = (size_t)(BK * 2);
;     const size_t hstep = (size_t)HALF * K * 2;
;     const size_t tstep = 2 * hstep;
;     const unsigned ldsw = (unsigned)wid * 1024u;
;     const int aoff = lds_byte(wr * 64 + fr, fq * 8), boff = lds_byte(wc * 32 + fr, fq * 8);
;     ...
;     Unit cur, nxt; int ui = 0;
;     if (!S.next(0, cur)) return;
;     f32x4 acc[2][2][4][2];
; #pragma unroll
;     for (int a = 0; a < 2; ++a)
; #pragma unroll
;         for (int b = 0; b < 2; ++b)
; #pragma unroll
;             for (int m = 0; m < 4; ++m)
; #pragma unroll
;                 for (int n = 0; n < 2; ++n) acc[a][b][m][n] = (f32x4){0.f, 0.f, 0.f, 0.f};
;     bf16x8 At[4][2], B0[2][2], B1[2][2];
;     const char* cA = (const char*)g.A + (size_t)cur.pm * tstep; const char* cB = (const char*)g.Bt + (size_t)cur.pn * tstep;
;     S.a_ready(cur);
;     if constexpr (SP2) {
;         PG8_STAGE(PG8_SB(0, 0), cB, voffB); PG8_STAGE(PG8_SB(0, 1), cB + hstep, voffB); PG8_STAGE(PG8_SA(0, 0), cA, voffA); PG8_STAGE(PG8_SA(0, 1), cA + hstep, voffA);
;         if (wr == 1) PG8_BAR;
; __global__ void __launch_bounds__(512, 2) hymba_fwd(Params p) {
;     ...
;         { PHASE_VARS pg8::Gemm g{xb, (const bf16_t*)(wl + WL_PEG), MT, DM, DM}; pg8::StaticOrder S; S.init(MT, DM, G, c);
;           EpiResid<1> E{xb, (bf16_t*)(ws + WS_XB2), ly + 1 < NLAYER ? nullptr : xres, sq + 4 * MT, 1.0f, (const bf16_t*)(ws + WS_U2), sq + 3 * MT};
;           pg8::gemm_phase<EpiResid<1>, pg8::StaticOrder, true, true>(L, g, S, E, wv); }
.LBB0_2272:
	s_or_b64 exec, exec, s[4:5]
	s_mov_b64 s[4:5], 0
	v_readlane_b32 s14, v250, 0
	s_waitcnt lgkmcnt(0)
	v_mov_b32_e32 v0, v161
	s_barrier
	v_mov_b32_e32 v2, v161
	v_add_u32_e32 v0, 0, v0
	v_add_u32_e32 v0, 0x201c0, v0
	s_nop 0
	v_readlane_b32 s8, v250, 42
	v_add_u32_e32 v2, 0, v2
	v_add_u32_e32 v2, 0x201c8, v2
	s_nop 0
	v_mov_b32_e32 v14, v183
	v_readlane_b32 s9, v250, 43
	s_waitcnt lgkmcnt(1)
	v_readlane_b32 s6, v251, 49
	v_readlane_b32 s7, v251, 48
	s_waitcnt lgkmcnt(0)
	v_readlane_b32 s18, v251, 51
	v_readlane_b32 s24, v251, 50
	s_and_b64 vcc, exec, s[8:9]
	v_readfirstlane_b32 s8, v14
	s_cbranch_vccnz .LBB0_2384
	v_lshlrev_b32_e32 v0, 4, v14
	v_add_u32_e32 v1, 0x2000, v0
	v_ashrrev_i32_e32 v2, 31, v1
	v_lshrrev_b32_e32 v2, 22, v2
	v_add_u32_e32 v2, v1, v2
	v_ashrrev_i32_e32 v8, 10, v2
	v_mul_i32_i24_e32 v2, 0x400, v8
	v_sub_u32_e32 v1, v1, v2
	s_add_u32 s25, s7, s4
	v_lshrrev_b32_e32 v2, 4, v1
	s_addc_u32 s26, s6, s5
	v_bitop3_b32 v1, v2, v1, 32 bitop3:0x6c
	s_add_u32 s10, s25, 0x5200000
	v_ashrrev_i32_e32 v2, 31, v1
	s_addc_u32 s11, s26, 0
	s_mul_i32 s5, s14, 0x2900000
	v_lshrrev_b32_e32 v2, 26, v2
	s_mul_hi_i32 s4, s14, 0x2900000
	s_add_u32 s5, s25, s5
	v_add_u32_e32 v2, v1, v2
	v_lshlrev_b32_e32 v3, 3, v8
	s_addc_u32 s4, s26, s4
	v_ashrrev_i32_e32 v9, 6, v2
	v_and_b32_e32 v3, -16, v3
	s_add_u32 s16, s5, 0x2580000
	v_add_u32_e32 v3, v9, v3
	s_addc_u32 s30, s4, 0
	v_and_b32_e32 v4, 3, v9
	s_mov_b32 s4, 0x1fffe0
	v_lshrrev_b32_e32 v5, 2, v3
	v_lshlrev_b32_e32 v6, 1, v3
	v_and_b32_e32 v2, 0xc0, v2
	v_and_or_b32 v4, v3, s4, v4
	v_and_b32_e32 v5, 4, v5
	v_and_b32_e32 v6, 24, v6
	v_sub_u32_e32 v1, v1, v2
	v_or3_b32 v4, v4, v5, v6
	v_lshlrev_b32_e32 v5, 5, v8
	v_ashrrev_i16_sdwa v1, v193, sext(v1) dst_sel:DWORD dst_unused:UNUSED_PAD src0_sel:DWORD src1_sel:BYTE_0
	v_and_b32_e32 v5, 32, v5
	v_bfe_i32 v10, v1, 0, 16
	v_add_lshl_u32 v1, v5, v10, 1
	v_lshl_add_u32 v162, v4, 11, v1
	v_lshl_add_u32 v164, v3, 11, v1
	v_bfe_i32 v1, v14, 27, 1
	v_lshrrev_b32_e32 v1, 22, v1
	v_add_u32_e32 v1, v0, v1
	v_and_b32_e32 v1, 0xfffffc00, v1
	v_sub_u32_e32 v0, v0, v1
	v_lshrrev_b32_e32 v1, 4, v0
	v_ashrrev_i32_e32 v2, 31, v14
	v_bitop3_b32 v0, v1, v0, 32 bitop3:0x6c
	v_lshrrev_b32_e32 v2, 26, v2
	v_ashrrev_i32_e32 v1, 31, v0
	v_add_u32_e32 v2, v14, v2
	v_lshrrev_b32_e32 v1, 26, v1
	v_ashrrev_i32_e32 v12, 6, v2
	v_add_u32_e32 v1, v0, v1
	v_lshlrev_b32_e32 v2, 3, v12
	v_ashrrev_i32_e32 v11, 6, v1
	v_and_b32_e32 v2, -16, v2
	v_add_u32_e32 v2, v11, v2
	v_and_b32_e32 v3, 3, v11
	v_lshrrev_b32_e32 v4, 2, v2
	v_lshlrev_b32_e32 v5, 1, v2
	v_and_b32_e32 v1, 0xc0, v1
	s_ashr_i32 s9, s8, 6
	v_and_or_b32 v3, v2, s4, v3
	v_and_b32_e32 v4, 4, v4
	v_and_b32_e32 v5, 24, v5
	v_sub_u32_e32 v0, v0, v1
	s_ashr_i32 s21, s8, 8
	s_lshl_b32 s31, s9, 10
	v_or3_b32 v3, v3, v4, v5
	v_lshlrev_b32_e32 v4, 5, v12
	v_ashrrev_i16_sdwa v0, v193, sext(v0) dst_sel:DWORD dst_unused:UNUSED_PAD src0_sel:DWORD src1_sel:BYTE_0
	v_readlane_b32 s4, v250, 15
	v_and_b32_e32 v4, 32, v4
	v_bfe_i32 v13, v0, 0, 16
	v_readlane_b32 s5, v250, 16
	s_add_u32 s6, s16, s4
	v_add_lshl_u32 v0, v4, v13, 1
	s_addc_u32 s7, s30, s5
	s_add_i32 s66, s31, 0
	v_lshl_add_u32 v160, v3, 11, v0
	s_add_i32 m0, s66, 0x10000
	v_lshl_add_u32 v166, v2, 11, v0
	global_load_lds_dwordx4 v160, s[6:7]
	s_add_i32 m0, s66, 0x12000
	s_add_u32 s4, s6, 0x40000
	global_load_lds_dwordx4 v162, s[6:7]
	s_addc_u32 s5, s7, 0
	s_add_i32 m0, s66, 0x14000
	v_mov_b32_e32 v163, v161
	global_load_lds_dwordx4 v160, s[4:5]
	s_add_i32 m0, s66, 0x16000
	v_mov_b32_e32 v167, v161
	global_load_lds_dwordx4 v162, s[4:5]
	v_readlane_b32 s4, v250, 29
	v_readlane_b32 s5, v250, 30
	s_add_u32 s4, s10, s4
	s_addc_u32 s5, s11, s5
	s_add_i32 s67, s66, 0x2000
	s_mov_b32 m0, s66
	s_add_u32 s12, s4, 0x40000
	global_load_lds_dwordx4 v166, s[4:5]
	s_mov_b32 m0, s67
	s_addc_u32 s13, s5, 0
	s_add_i32 s76, s66, 0x4000
	global_load_lds_dwordx4 v164, s[4:5]
	s_mov_b32 m0, s76
	s_add_i32 s77, s66, 0x6000
	global_load_lds_dwordx4 v166, s[12:13]
	s_mov_b32 m0, s77
	v_mov_b32_e32 v165, v161
	global_load_lds_dwordx4 v164, s[12:13]
	s_cmp_eq_u32 s21, 1
	v_lshl_add_u64 v[6:7], s[6:7], 0, v[160:161]
	v_lshl_add_u64 v[4:5], s[6:7], 0, v[162:163]
	v_lshl_add_u64 v[0:1], s[4:5], 0, v[166:167]
	s_cselect_b64 s[12:13], -1, 0
	s_cmp_lg_u32 s21, 1
	v_lshl_add_u64 v[2:3], s[4:5], 0, v[164:165]
	s_mov_b32 s19, s14
	s_cbranch_scc1 .LBB0_2275
	s_barrier

; #define LAS __attribute__((address_space(3)))
; __device__ __forceinline__ unsigned pk2(float lo, float hi) { f32x2 v = {lo, hi}; bf16x2_t b = __builtin_convertvector(v, bf16x2_t); return __builtin_bit_cast(unsigned, b); }
; __device__ __forceinline__ void transpose_item(const float* W, int K, int N, bf16_t* WT, const float* gk, int mode, LAS float* scr_, int item, int lane) {
;     LAS unsigned* scr = (LAS unsigned*)scr_;
;     const int nblk = N / 64, kb = item / nblk, nb = item % nblk, k0 = 64 * kb, n0 = 64 * nb;
;     const int sc = (mode == 1) ? (((n0 >> 7) & 1) * DFF + (n0 >> 8) * 128 + (n0 & 127)) : n0;
;     const float* src = W + (size_t)k0 * N + sc + lane;
;     float va[32], vb[32];
; #pragma unroll
;     for (int kp = 0; kp < 32; ++kp) { va[kp] = src[(size_t)(2 * kp) * N]; vb[kp] = src[(size_t)(2 * kp + 1) * N]; }
; #pragma unroll
;     for (int kp = 0; kp < 32; ++kp) {
;         float a = va[kp], b = vb[kp];
;         if (gk) { a *= gk[k0 + 2 * kp]; b *= gk[k0 + 2 * kp + 1]; }
;         scr[kp * 65 + lane] = pk2(a, b);
;     }
;     asm volatile("s_waitcnt lgkmcnt(0)" ::: "memory");
;     const int c = lane & 7;
; #pragma unroll
;     for (int j = 0; j < 8; ++j) { const int r = (lane >> 3) + 8 * j; const LAS unsigned* q = scr + (4 * c) * 65 + r;
;         u32x4 o; o.x = q[0]; o.y = q[65]; o.z = q[130]; o.w = q[195];
;         *(u32x4*)(WT + (size_t)(n0 + r) * K + k0 + 8 * c) = o; }
;     asm volatile("s_waitcnt lgkmcnt(0)" ::: "memory");
.LBB0_2384:
	s_mov_b32 s5, s20
	s_mov_b32 s4, s2
	s_cmpk_eq_i32 s5, 0x100
	s_cselect_b64 s[6:7], -1, 0
	s_cmp_gt_i32 s4, 31
	s_cselect_b64 s[8:9], -1, 0
	s_and_b64 s[6:7], s[6:7], s[8:9]
	s_cmp_lt_i32 s60, 2
	s_cselect_b64 s[8:9], -1, 0
	s_and_b64 s[6:7], s[6:7], s[8:9]
	s_andn2_b64 vcc, exec, s[6:7]
	s_mov_b32 s0, 0x24000
	s_cbranch_vccnz .LBB0_2461
	s_waitcnt lgkmcnt(0)
	v_mov_b32_e32 v1, v183
	v_mov_b32_e32 v2, v161
	s_lshl_b32 s4, s4, 3
	v_add_u32_e32 v2, 0, v2
	v_add_u32_e32 v2, 0x201c0, v2
	s_nop 0
	v_readfirstlane_b32 s5, v1
	s_ashr_i32 s5, s5, 6
	s_add_i32 s4, s4, s5
	s_add_i32 s16, s4, 0xffffff00
	s_lshl_b32 s4, s5, 14
	s_add_i32 s24, s4, 0
	s_waitcnt lgkmcnt(0)
	v_readlane_b32 s5, v251, 48
	s_ashr_i32 s61, s60, 31
	s_mul_i32 s6, s60, 0x2900000
	v_readlane_b32 s4, v251, 49
	s_mul_hi_i32 s7, s60, 0x2900000
	s_add_u32 s6, s5, s6
	v_and_b32_e32 v0, 63, v1
	s_addc_u32 s7, s4, s7
	s_cmpk_lt_i32 s16, 0x100
	v_and_b32_e32 v2, 7, v1
	v_lshrrev_b32_e32 v74, 3, v0
	s_cselect_b64 s[4:5], -1, 0
	s_cmpk_gt_i32 s16, 0xff
	v_lshl_add_u32 v75, v0, 2, s24
	v_mul_u32_u24_e32 v1, 0x410, v2
	v_lshlrev_b32_e32 v2, 4, v2
	v_lshlrev_b32_e32 v76, 2, v74
	s_cbranch_scc1 .LBB0_2388
	v_mov_b32_e32 v3, v161
	v_lshl_add_u64 v[4:5], s[6:7], 0, v[2:3]
	s_mov_b64 s[10:11], 0x1300000
	s_lshl_b64 s[8:9], s[60:61], 22
	v_lshl_add_u64 v[4:5], v[4:5], 0, s[10:11]
	v_add3_u32 v3, s24, v1, v76
	s_lshl_b32 s14, s16, 6
	v_lshlrev_b32_e32 v160, 2, v0
	s_mov_b32 s15, s16
.LBB0_2387:
	v_mov_b32_e32 v6, v161
	v_add_u32_e32 v77, 0x400, v75
	v_add_u32_e32 v6, 0, v6
	v_add_u32_e32 v6, 0x20188, v6
	s_nop 0
	v_add_u32_e32 v90, 0x800, v75
	v_add_u32_e32 v91, 0xc00, v75
	v_add_u32_e32 v92, 0x1000, v75
	v_add_u32_e32 v93, 0x1400, v75
	s_waitcnt lgkmcnt(0)
	v_readlane_b32 s11, v251, 34
	v_readlane_b32 s10, v251, 35
	s_add_u32 s11, s11, s8
	s_addc_u32 s21, s10, s9
	s_ashr_i32 s10, s15, 31
	s_lshr_b32 s10, s10, 28
	s_add_i32 s10, s15, s10
	s_ashr_i32 s10, s10, 4
	s_lshl_b32 s18, s10, 6
	s_lshl_b32 s10, s10, 10
	s_ashr_i32 s19, s18, 31
	s_sub_i32 s10, s14, s10
	s_lshl_b64 s[12:13], s[18:19], 12
	s_add_u32 s12, s11, s12
	v_add_u32_e32 v6, s10, v74
	s_addc_u32 s13, s21, s13
	s_ashr_i32 s11, s10, 31
	v_add_u32_e32 v8, 8, v6
	v_add_u32_e32 v10, 16, v6
	v_add_u32_e32 v12, 24, v6
	v_add_u32_e32 v14, 32, v6
	v_add_u32_e32 v16, 40, v6
	v_add_u32_e32 v18, 48, v6
	v_add_u32_e32 v22, 56, v6
	s_lshl_b64 s[10:11], s[10:11], 2
	v_ashrrev_i32_e32 v7, 31, v6
	v_ashrrev_i32_e32 v9, 31, v8
	v_ashrrev_i32_e32 v11, 31, v10
	v_ashrrev_i32_e32 v13, 31, v12
	v_ashrrev_i32_e32 v15, 31, v14
	v_ashrrev_i32_e32 v17, 31, v16
	v_ashrrev_i32_e32 v19, 31, v18
	v_ashrrev_i32_e32 v23, 31, v22
	s_add_u32 s12, s12, s10
	v_lshl_add_u64 v[20:21], s[18:19], 1, v[4:5]
	v_lshlrev_b64 v[6:7], 11, v[6:7]
	v_lshlrev_b64 v[8:9], 11, v[8:9]
	v_lshlrev_b64 v[10:11], 11, v[10:11]
	v_lshlrev_b64 v[12:13], 11, v[12:13]
	v_lshlrev_b64 v[14:15], 11, v[14:15]
	v_lshlrev_b64 v[16:17], 11, v[16:17]
	v_lshlrev_b64 v[18:19], 11, v[18:19]
	v_lshlrev_b64 v[22:23], 11, v[22:23]
	s_addc_u32 s13, s13, s11
	v_lshl_add_u64 v[6:7], v[20:21], 0, v[6:7]
	v_lshl_add_u64 v[8:9], v[20:21], 0, v[8:9]
	v_lshl_add_u64 v[10:11], v[20:21], 0, v[10:11]
	v_lshl_add_u64 v[12:13], v[20:21], 0, v[12:13]
	v_lshl_add_u64 v[14:15], v[20:21], 0, v[14:15]
	v_lshl_add_u64 v[16:17], v[20:21], 0, v[16:17]
	v_lshl_add_u64 v[18:19], v[20:21], 0, v[18:19]
	v_lshl_add_u64 v[20:21], v[20:21], 0, v[22:23]
	v_lshl_add_u64 v[22:23], s[12:13], 0, v[160:161]
	v_add_co_u32_e32 v24, vcc, s79, v22
	global_load_dword v96, v160, s[12:13]
	s_nop 0
	v_addc_co_u32_e32 v25, vcc, 0, v23, vcc
	v_add_co_u32_e32 v26, vcc, s88, v22
	v_add_u32_e32 v94, 0x1800, v75
	s_nop 0
	v_addc_co_u32_e32 v27, vcc, 0, v23, vcc
	v_add_co_u32_e32 v28, vcc, s80, v22
	v_add_u32_e32 v95, 0x1c00, v75
	s_nop 0
	v_addc_co_u32_e32 v29, vcc, 0, v23, vcc
	v_add_co_u32_e32 v30, vcc, s70, v22
	s_add_i32 s10, s15, 0x700
	s_nop 0
	v_addc_co_u32_e32 v31, vcc, 0, v23, vcc
	v_add_co_u32_e32 v32, vcc, s71, v22
	s_add_i32 s14, s14, 0x1c000
	s_nop 0
	v_addc_co_u32_e32 v33, vcc, 0, v23, vcc
	v_add_co_u32_e32 v34, vcc, s91, v22
	s_cmpk_lt_i32 s15, 0xfa00
	s_nop 0
	v_addc_co_u32_e32 v35, vcc, 0, v23, vcc
	v_add_co_u32_e32 v36, vcc, s92, v22
	s_mov_b32 s15, s10
	s_nop 0
	v_addc_co_u32_e32 v37, vcc, 0, v23, vcc
	v_add_co_u32_e32 v38, vcc, s37, v22
	s_nop 1
	v_addc_co_u32_e32 v39, vcc, 0, v23, vcc
	v_add_co_u32_e32 v40, vcc, s94, v22
	s_nop 1
	v_addc_co_u32_e32 v41, vcc, 0, v23, vcc
	v_add_co_u32_e32 v42, vcc, s46, v22
	s_nop 1
	v_addc_co_u32_e32 v43, vcc, 0, v23, vcc
	v_add_co_u32_e32 v44, vcc, s47, v22
	s_nop 1
	v_addc_co_u32_e32 v45, vcc, 0, v23, vcc
	v_add_co_u32_e32 v46, vcc, s59, v22
	s_nop 1
	v_addc_co_u32_e32 v47, vcc, 0, v23, vcc
	v_add_co_u32_e32 v48, vcc, s81, v22
	s_nop 1
	v_addc_co_u32_e32 v49, vcc, 0, v23, vcc
	v_add_co_u32_e32 v50, vcc, s83, v22
	s_nop 1
	v_addc_co_u32_e32 v51, vcc, 0, v23, vcc
	v_add_co_u32_e32 v52, vcc, s27, v22
	s_nop 1
	v_addc_co_u32_e32 v53, vcc, 0, v23, vcc
	v_add_co_u32_e32 v54, vcc, s50, v22
	s_nop 1
	v_addc_co_u32_e32 v55, vcc, 0, v23, vcc
	v_add_co_u32_e32 v56, vcc, s53, v22
	s_nop 1
	v_addc_co_u32_e32 v57, vcc, 0, v23, vcc
	v_add_co_u32_e32 v58, vcc, s0, v22
	s_nop 1
	v_addc_co_u32_e32 v59, vcc, 0, v23, vcc
	v_add_co_u32_e32 v60, vcc, s73, v22
	s_nop 1
	v_addc_co_u32_e32 v61, vcc, 0, v23, vcc
	v_add_co_u32_e32 v62, vcc, s1, v22
	s_nop 1
	v_addc_co_u32_e32 v63, vcc, 0, v23, vcc
	v_add_co_u32_e32 v64, vcc, s72, v22
	s_nop 1
	v_addc_co_u32_e32 v65, vcc, 0, v23, vcc
	v_add_co_u32_e32 v66, vcc, s82, v22
	s_nop 1
	v_addc_co_u32_e32 v67, vcc, 0, v23, vcc
	v_add_co_u32_e32 v68, vcc, s33, v22
	s_nop 1
; __device__ __forceinline__ unsigned pk2(float lo, float hi) { f32x2 v = {lo, hi}; bf16x2_t b = __builtin_convertvector(v, bf16x2_t); return __builtin_bit_cast(unsigned, b); }
; __device__ __forceinline__ void transpose_item(const float* W, int K, int N, bf16_t* WT, const float* gk, int mode, LAS float* scr_, int item, int lane) {
;     ...
;     for (int kp = 0; kp < 32; ++kp) { va[kp] = src[(size_t)(2 * kp) * N]; vb[kp] = src[(size_t)(2 * kp + 1) * N]; }
; #pragma unroll
;     for (int kp = 0; kp < 32; ++kp) {
;         float a = va[kp], b = vb[kp];
;         if (gk) { a *= gk[k0 + 2 * kp]; b *= gk[k0 + 2 * kp + 1]; }
;         scr[kp * 65 + lane] = pk2(a, b);
	v_addc_co_u32_e32 v69, vcc, 0, v23, vcc
	v_add_co_u32_e32 v70, vcc, s22, v22
	s_nop 1
	v_addc_co_u32_e32 v71, vcc, 0, v23, vcc
	v_add_co_u32_e32 v72, vcc, s38, v22
	s_nop 1
	v_addc_co_u32_e32 v73, vcc, 0, v23, vcc
	v_add_co_u32_e32 v78, vcc, s39, v22
	s_nop 1
	v_addc_co_u32_e32 v79, vcc, 0, v23, vcc
	v_add_co_u32_e32 v80, vcc, s56, v22
	s_nop 1
	v_addc_co_u32_e32 v81, vcc, 0, v23, vcc
	v_add_co_u32_e32 v82, vcc, s69, v22
	s_nop 1
	v_addc_co_u32_e32 v83, vcc, 0, v23, vcc
	v_add_co_u32_e32 v84, vcc, s87, v22
	s_nop 1
	v_addc_co_u32_e32 v85, vcc, 0, v23, vcc
	v_add_co_u32_e32 v86, vcc, s90, v22
	s_nop 1
	v_addc_co_u32_e32 v87, vcc, 0, v23, vcc
	v_add_co_u32_e32 v88, vcc, s51, v22
	s_nop 1
	v_addc_co_u32_e32 v89, vcc, 0, v23, vcc
	v_add_co_u32_e32 v22, vcc, s52, v22
	s_nop 1
	v_addc_co_u32_e32 v23, vcc, 0, v23, vcc
	global_load_dword v97, v[24:25], off offset:-4096
	s_nop 0
	global_load_dword v24, v[24:25], off
	s_nop 0
	global_load_dword v25, v[26:27], off offset:-4096
	s_nop 0
	global_load_dword v26, v[26:27], off
	s_nop 0
	global_load_dword v27, v[28:29], off offset:-4096
	s_nop 0
	global_load_dword v28, v[28:29], off
	s_nop 0
	global_load_dword v29, v[30:31], off offset:-4096
	s_nop 0
	global_load_dword v30, v[30:31], off
	s_nop 0
	global_load_dword v31, v[32:33], off offset:-4096
	s_nop 0
	global_load_dword v32, v[32:33], off
	s_nop 0
	global_load_dword v33, v[34:35], off offset:-4096
	s_nop 0
	global_load_dword v34, v[34:35], off
	s_nop 0
	global_load_dword v35, v[36:37], off offset:-4096
	s_nop 0
	global_load_dword v36, v[36:37], off
	s_nop 0
	global_load_dword v37, v[38:39], off offset:-4096
	s_nop 0
	global_load_dword v38, v[38:39], off
	s_nop 0
	global_load_dword v39, v[40:41], off offset:-4096
	s_nop 0
	global_load_dword v40, v[40:41], off
	s_nop 0
	global_load_dword v41, v[42:43], off offset:-4096
	s_nop 0
	global_load_dword v42, v[42:43], off
	s_nop 0
	global_load_dword v43, v[44:45], off offset:-4096
	s_nop 0
	global_load_dword v44, v[44:45], off
	s_nop 0
	global_load_dword v45, v[46:47], off offset:-4096
	s_nop 0
	global_load_dword v46, v[46:47], off
	s_nop 0
	global_load_dword v47, v[48:49], off offset:-4096
	s_nop 0
	global_load_dword v48, v[48:49], off
	s_nop 0
	global_load_dword v49, v[50:51], off offset:-4096
	s_nop 0
	global_load_dword v50, v[50:51], off
	s_nop 0
	global_load_dword v51, v[52:53], off offset:-4096
	s_nop 0
	global_load_dword v52, v[52:53], off
	s_nop 0
	global_load_dword v53, v[54:55], off offset:-4096
	s_nop 0
	global_load_dword v54, v[54:55], off
	s_nop 0
	global_load_dword v55, v[56:57], off offset:-4096
	s_nop 0
	global_load_dword v56, v[56:57], off
	s_nop 0
	global_load_dword v57, v[58:59], off offset:-4096
	s_nop 0
	global_load_dword v58, v[58:59], off
	s_nop 0
	global_load_dword v59, v[60:61], off offset:-4096
	s_nop 0
	global_load_dword v60, v[60:61], off
	s_nop 0
	global_load_dword v61, v[62:63], off offset:-4096
	s_nop 0
	global_load_dword v62, v[62:63], off
	s_nop 0
	global_load_dword v63, v[64:65], off offset:-4096
	s_nop 0
	global_load_dword v64, v[64:65], off
	s_nop 0
	global_load_dword v65, v[66:67], off offset:-4096
	s_nop 0
	global_load_dword v66, v[66:67], off
	s_nop 0
	global_load_dword v67, v[68:69], off offset:-4096
	s_nop 0
	global_load_dword v68, v[68:69], off
	s_nop 0
	global_load_dword v69, v[70:71], off offset:-4096
	s_nop 0
	global_load_dword v70, v[70:71], off
	s_nop 0
	global_load_dword v71, v[72:73], off offset:-4096
	s_nop 0
	global_load_dword v72, v[72:73], off
	s_nop 0
	global_load_dword v73, v[78:79], off offset:-4096
	s_nop 0
	global_load_dword v78, v[78:79], off
	s_nop 0
	global_load_dword v79, v[80:81], off offset:-4096
	s_nop 0
	global_load_dword v80, v[80:81], off
	s_nop 0
	global_load_dword v81, v[82:83], off offset:-4096
	s_nop 0
	global_load_dword v82, v[82:83], off
	s_nop 0
	global_load_dword v83, v[84:85], off offset:-4096
	s_nop 0
	global_load_dword v84, v[84:85], off
	s_nop 0
	global_load_dword v85, v[86:87], off offset:-4096
	s_nop 0
	global_load_dword v86, v[86:87], off
	s_nop 0
	global_load_dword v87, v[88:89], off offset:-4096
	s_nop 0
	global_load_dword v88, v[88:89], off
	s_nop 0
	global_load_dword v22, v[22:23], off
	s_waitcnt vmcnt(62)
	v_cvt_pk_bf16_f32 v23, v96, v97
	s_waitcnt vmcnt(60)
	v_cvt_pk_bf16_f32 v24, v24, v25
	s_waitcnt vmcnt(58)
	v_cvt_pk_bf16_f32 v25, v26, v27
	s_waitcnt vmcnt(56)
; #define LAS __attribute__((address_space(3)))
; __device__ __forceinline__ unsigned pk2(float lo, float hi) { f32x2 v = {lo, hi}; bf16x2_t b = __builtin_convertvector(v, bf16x2_t); return __builtin_bit_cast(unsigned, b); }
; __device__ __forceinline__ void transpose_item(const float* W, int K, int N, bf16_t* WT, const float* gk, int mode, LAS float* scr_, int item, int lane) {
;     ...
;     for (int kp = 0; kp < 32; ++kp) {
;         float a = va[kp], b = vb[kp];
;         if (gk) { a *= gk[k0 + 2 * kp]; b *= gk[k0 + 2 * kp + 1]; }
;         scr[kp * 65 + lane] = pk2(a, b);
;     }
;     asm volatile("s_waitcnt lgkmcnt(0)" ::: "memory");
;     const int c = lane & 7;
; #pragma unroll
;     for (int j = 0; j < 8; ++j) { const int r = (lane >> 3) + 8 * j; const LAS unsigned* q = scr + (4 * c) * 65 + r;
;         u32x4 o; o.x = q[0]; o.y = q[65]; o.z = q[130]; o.w = q[195];
;         *(u32x4*)(WT + (size_t)(n0 + r) * K + k0 + 8 * c) = o; }
;     asm volatile("s_waitcnt lgkmcnt(0)" ::: "memory");
	v_cvt_pk_bf16_f32 v26, v28, v29
	s_waitcnt vmcnt(54)
	v_cvt_pk_bf16_f32 v27, v30, v31
	s_waitcnt vmcnt(52)
	v_cvt_pk_bf16_f32 v28, v32, v33
	s_waitcnt vmcnt(50)
	v_cvt_pk_bf16_f32 v29, v34, v35
	s_waitcnt vmcnt(48)
	v_cvt_pk_bf16_f32 v30, v36, v37
	s_waitcnt vmcnt(46)
	v_cvt_pk_bf16_f32 v31, v38, v39
	s_waitcnt vmcnt(44)
	v_cvt_pk_bf16_f32 v32, v40, v41
	s_waitcnt vmcnt(42)
	v_cvt_pk_bf16_f32 v33, v42, v43
	s_waitcnt vmcnt(40)
	v_cvt_pk_bf16_f32 v34, v44, v45
	s_waitcnt vmcnt(38)
	v_cvt_pk_bf16_f32 v35, v46, v47
	s_waitcnt vmcnt(36)
	v_cvt_pk_bf16_f32 v36, v48, v49
	s_waitcnt vmcnt(34)
	v_cvt_pk_bf16_f32 v37, v50, v51
	s_waitcnt vmcnt(32)
	v_cvt_pk_bf16_f32 v38, v52, v53
	s_waitcnt vmcnt(30)
	v_cvt_pk_bf16_f32 v39, v54, v55
	s_waitcnt vmcnt(28)
	v_cvt_pk_bf16_f32 v40, v56, v57
	s_waitcnt vmcnt(26)
	v_cvt_pk_bf16_f32 v41, v58, v59
	s_waitcnt vmcnt(24)
	v_cvt_pk_bf16_f32 v42, v60, v61
	s_waitcnt vmcnt(22)
	v_cvt_pk_bf16_f32 v43, v62, v63
	s_waitcnt vmcnt(20)
	v_cvt_pk_bf16_f32 v44, v64, v65
	s_waitcnt vmcnt(18)
	v_cvt_pk_bf16_f32 v45, v66, v67
	s_waitcnt vmcnt(16)
	v_cvt_pk_bf16_f32 v46, v68, v69
	s_waitcnt vmcnt(14)
	v_cvt_pk_bf16_f32 v47, v70, v71
	s_waitcnt vmcnt(12)
	v_cvt_pk_bf16_f32 v48, v72, v73
	s_waitcnt vmcnt(10)
	v_cvt_pk_bf16_f32 v49, v78, v79
	s_waitcnt vmcnt(8)
	v_cvt_pk_bf16_f32 v50, v80, v81
	s_waitcnt vmcnt(6)
	v_cvt_pk_bf16_f32 v51, v82, v83
	s_waitcnt vmcnt(4)
	v_cvt_pk_bf16_f32 v52, v84, v85
	s_waitcnt vmcnt(2)
	v_cvt_pk_bf16_f32 v53, v86, v87
	s_waitcnt vmcnt(0)
	v_cvt_pk_bf16_f32 v22, v88, v22
	ds_write2_b32 v75, v23, v24 offset1:65
	ds_write2_b32 v75, v25, v26 offset0:130 offset1:195
	ds_write2_b32 v77, v27, v28 offset0:4 offset1:69
	ds_write2_b32 v77, v29, v30 offset0:134 offset1:199
	ds_write2_b32 v90, v31, v32 offset0:8 offset1:73
	ds_write2_b32 v90, v33, v34 offset0:138 offset1:203
	ds_write2_b32 v91, v35, v36 offset0:12 offset1:77
	ds_write2_b32 v91, v37, v38 offset0:142 offset1:207
	ds_write2_b32 v92, v39, v40 offset0:16 offset1:81
	ds_write2_b32 v92, v41, v42 offset0:146 offset1:211
	ds_write2_b32 v93, v43, v44 offset0:20 offset1:85
	ds_write2_b32 v93, v45, v46 offset0:150 offset1:215
	ds_write2_b32 v94, v47, v48 offset0:24 offset1:89
	ds_write2_b32 v94, v49, v50 offset0:154 offset1:219
	ds_write2_b32 v95, v51, v52 offset0:28 offset1:93
	ds_write2_b32 v95, v53, v22 offset0:158 offset1:223
	s_waitcnt lgkmcnt(0)
	ds_read2_b32 v[22:23], v3 offset0:65 offset1:73
	ds_read2_b32 v[42:43], v3 offset0:130 offset1:138
	ds_read2_b32 v[24:25], v3 offset0:195 offset1:203
	ds_read2_b32 v[44:45], v3 offset1:8
	ds_read2_b32 v[46:47], v3 offset0:16 offset1:24
	ds_read2_b32 v[26:27], v3 offset0:81 offset1:89
	ds_read2_b32 v[48:49], v3 offset0:146 offset1:154
	ds_read2_b32 v[28:29], v3 offset0:211 offset1:219
	ds_read2_b32 v[30:31], v3 offset0:97 offset1:105
	ds_read2_b32 v[50:51], v3 offset0:162 offset1:170
	ds_read2_b32 v[32:33], v3 offset0:227 offset1:235
	ds_read2_b32 v[52:53], v3 offset0:32 offset1:40
	ds_read2_b32 v[54:55], v3 offset0:48 offset1:56
	ds_read2_b32 v[34:35], v3 offset0:113 offset1:121
	ds_read2_b32 v[56:57], v3 offset0:178 offset1:186
	ds_read2_b32 v[36:37], v3 offset0:243 offset1:251
	s_waitcnt lgkmcnt(12)
	v_mov_b32_e32 v38, v44
	v_mov_b32_e32 v39, v22
	v_mov_b32_e32 v40, v42
	v_mov_b32_e32 v41, v24
	v_mov_b32_e32 v22, v45
	v_mov_b32_e32 v24, v43
	s_waitcnt lgkmcnt(11)
	v_mov_b32_e32 v42, v46
	s_waitcnt lgkmcnt(10)
	v_mov_b32_e32 v43, v26
	s_waitcnt lgkmcnt(9)
	v_mov_b32_e32 v44, v48
	s_waitcnt lgkmcnt(8)
	v_mov_b32_e32 v45, v28
	v_mov_b32_e32 v26, v47
	v_mov_b32_e32 v28, v49
	s_waitcnt lgkmcnt(4)
	v_mov_b32_e32 v46, v52
	v_mov_b32_e32 v47, v30
	v_mov_b32_e32 v48, v50
	v_mov_b32_e32 v49, v32
	v_mov_b32_e32 v30, v53
	v_mov_b32_e32 v32, v51
	s_waitcnt lgkmcnt(3)
	v_mov_b32_e32 v50, v54
	s_waitcnt lgkmcnt(2)
	v_mov_b32_e32 v51, v34
	s_waitcnt lgkmcnt(1)
	v_mov_b32_e32 v52, v56
	s_waitcnt lgkmcnt(0)
	v_mov_b32_e32 v53, v36
	v_mov_b32_e32 v34, v55
	v_mov_b32_e32 v36, v57
	global_store_dwordx4 v[6:7], v[38:41], off
	global_store_dwordx4 v[8:9], v[22:25], off
	global_store_dwordx4 v[10:11], v[42:45], off
	global_store_dwordx4 v[12:13], v[26:29], off
	global_store_dwordx4 v[14:15], v[46:49], off
	global_store_dwordx4 v[16:17], v[30:33], off
	global_store_dwordx4 v[18:19], v[50:53], off
	global_store_dwordx4 v[20:21], v[34:37], off
	s_waitcnt lgkmcnt(0)
	s_cbranch_scc1 .LBB0_2387

; #define LAS __attribute__((address_space(3)))
; #define PIN(i) ((const float*)ldq_(L, (i)))
; __device__ __forceinline__ unsigned pk2(float lo, float hi) { f32x2 v = {lo, hi}; bf16x2_t b = __builtin_convertvector(v, bf16x2_t); return __builtin_bit_cast(unsigned, b); }
; #define PREP_CONV(bit, SRC, Kd, Nd, DST, GK, MODE) if (mask & (bit)) { for (int it = gw; it < ((Kd) / 64) * ((Nd) / 64); it += NGW) transpose_item((SRC), (Kd), (Nd), (bf16_t*)(wl + (DST)), (GK), (MODE), scr, it, lane); }
; __device__ __forceinline__ void transpose_item(const float* W, int K, int N, bf16_t* WT, const float* gk, int mode, LAS float* scr_, int item, int lane) {
;     LAS unsigned* scr = (LAS unsigned*)scr_;
;     const int nblk = N / 64, kb = item / nblk, nb = item % nblk, k0 = 64 * kb, n0 = 64 * nb;
;     const int sc = (mode == 1) ? (((n0 >> 7) & 1) * DFF + (n0 >> 8) * 128 + (n0 & 127)) : n0;
;     const float* src = W + (size_t)k0 * N + sc + lane;
;     float va[32], vb[32];
; #pragma unroll
;     for (int kp = 0; kp < 32; ++kp) { va[kp] = src[(size_t)(2 * kp) * N]; vb[kp] = src[(size_t)(2 * kp + 1) * N]; }
; #pragma unroll
;     for (int kp = 0; kp < 32; ++kp) {
;         float a = va[kp], b = vb[kp];
;         if (gk) { a *= gk[k0 + 2 * kp]; b *= gk[k0 + 2 * kp + 1]; }
;         scr[kp * 65 + lane] = pk2(a, b);
;     }
;     asm volatile("s_waitcnt lgkmcnt(0)" ::: "memory");
;     const int c = lane & 7;
; #pragma unroll
;     for (int j = 0; j < 8; ++j) { const int r = (lane >> 3) + 8 * j; const LAS unsigned* q = scr + (4 * c) * 65 + r;
;         u32x4 o; o.x = q[0]; o.y = q[65]; o.z = q[130]; o.w = q[195];
;         *(u32x4*)(WT + (size_t)(n0 + r) * K + k0 + 8 * c) = o; }
;     asm volatile("s_waitcnt lgkmcnt(0)" ::: "memory");
; __device__ __forceinline__ void prep(const Params& p, LAS unsigned char* L, int wv, int vb, int nvb, int l, int mask) {
;     ...
;     PREP_CONV(PM_FFB_OUT, PIN(I_WFFB_OUT) + (size_t)l * DFF * DM, DFF, DM, WL_FFB_OUT, nullptr, 0)
.LBB0_2390:
	v_mov_b32_e32 v6, v161
	s_mul_i32 s10, s60, 0xb00000
	v_add_u32_e32 v6, 0, v6
	v_add_u32_e32 v6, 0x201a0, v6
	s_nop 0
	v_add_u32_e32 v23, 0x400, v75
	v_add_u32_e32 v77, 0x800, v75
	v_add_u32_e32 v92, 0xc00, v75
	v_add_u32_e32 v93, 0x1000, v75
	s_waitcnt lgkmcnt(0)
	v_readlane_b32 s9, v251, 40
	v_readlane_b32 s8, v251, 41
	s_add_u32 s9, s9, s10
	s_mul_hi_i32 s10, s60, 0xb00000
	s_addc_u32 s18, s8, s10
	s_ashr_i32 s8, s13, 31
	s_lshr_b32 s8, s8, 28
	s_add_i32 s8, s13, s8
	s_ashr_i32 s8, s8, 4
	s_lshl_b32 s10, s8, 6
	s_lshl_b32 s11, s8, 10
	s_mul_i32 s14, s8, 0xffd40000
	s_sub_i32 s8, s12, s11
	s_ashr_i32 s11, s10, 31
	v_add_u32_e32 v6, s14, v22
	s_lshl_b64 s[14:15], s[10:11], 12
	v_lshl_add_u64 v[20:21], s[10:11], 1, v[4:5]
	s_add_u32 s10, s9, s14
	s_addc_u32 s11, s18, s15
	s_ashr_i32 s9, s8, 31
	s_lshl_b64 s[8:9], s[8:9], 2
	v_add_u32_e32 v8, 0x5800, v6
	v_add_u32_e32 v10, 0xb000, v6
	v_add_u32_e32 v12, 0x10800, v6
	v_add_u32_e32 v14, 0x16000, v6
	v_add_u32_e32 v16, 0x1b800, v6
	v_add_u32_e32 v18, 0x21000, v6
	v_add_u32_e32 v24, 0x26800, v6
	s_add_u32 s10, s10, s8
	v_ashrrev_i32_e32 v7, 31, v6
	v_ashrrev_i32_e32 v9, 31, v8
	v_ashrrev_i32_e32 v11, 31, v10
	v_ashrrev_i32_e32 v13, 31, v12
	v_ashrrev_i32_e32 v15, 31, v14
	v_ashrrev_i32_e32 v17, 31, v16
	v_ashrrev_i32_e32 v19, 31, v18
	v_ashrrev_i32_e32 v25, 31, v24
	s_addc_u32 s11, s11, s9
	v_lshl_add_u64 v[6:7], v[6:7], 1, v[20:21]
	v_lshl_add_u64 v[8:9], v[8:9], 1, v[20:21]
	v_lshl_add_u64 v[10:11], v[10:11], 1, v[20:21]
	v_lshl_add_u64 v[12:13], v[12:13], 1, v[20:21]
	v_lshl_add_u64 v[14:15], v[14:15], 1, v[20:21]
	v_lshl_add_u64 v[16:17], v[16:17], 1, v[20:21]
	v_lshl_add_u64 v[18:19], v[18:19], 1, v[20:21]
	v_lshl_add_u64 v[20:21], v[24:25], 1, v[20:21]
	v_lshl_add_u64 v[24:25], s[10:11], 0, v[160:161]
	v_add_co_u32_e32 v26, vcc, s79, v24
	global_load_dword v97, v160, s[10:11]
	s_nop 0
	v_addc_co_u32_e32 v27, vcc, 0, v25, vcc
	v_add_co_u32_e32 v28, vcc, s88, v24
	v_add_u32_e32 v94, 0x1400, v75
	s_nop 0
	v_addc_co_u32_e32 v29, vcc, 0, v25, vcc
	v_add_co_u32_e32 v30, vcc, s80, v24
	v_add_u32_e32 v95, 0x1800, v75
	s_nop 0
	v_addc_co_u32_e32 v31, vcc, 0, v25, vcc
	v_add_co_u32_e32 v32, vcc, s70, v24
	v_add_u32_e32 v96, 0x1c00, v75
	s_nop 0
	v_addc_co_u32_e32 v33, vcc, 0, v25, vcc
	v_add_co_u32_e32 v34, vcc, s71, v24
	s_add_i32 s8, s13, 0x700
	s_nop 0
	v_addc_co_u32_e32 v35, vcc, 0, v25, vcc
	v_add_co_u32_e32 v36, vcc, s91, v24
	s_add_i32 s12, s12, 0x1c000
	s_nop 0
	v_addc_co_u32_e32 v37, vcc, 0, v25, vcc
	v_add_co_u32_e32 v38, vcc, s92, v24
	v_add_u32_e32 v22, 0x13400000, v22
	s_nop 0
	v_addc_co_u32_e32 v39, vcc, 0, v25, vcc
	v_add_co_u32_e32 v40, vcc, s37, v24
	s_cmpk_lt_i32 s13, 0xfbc0
	s_nop 0
	v_addc_co_u32_e32 v41, vcc, 0, v25, vcc
	v_add_co_u32_e32 v42, vcc, s94, v24
	s_mov_b32 s13, s8
	s_nop 0
	v_addc_co_u32_e32 v43, vcc, 0, v25, vcc
	v_add_co_u32_e32 v44, vcc, s46, v24
	s_nop 1
	v_addc_co_u32_e32 v45, vcc, 0, v25, vcc
	v_add_co_u32_e32 v46, vcc, s47, v24
	s_nop 1
	v_addc_co_u32_e32 v47, vcc, 0, v25, vcc
	v_add_co_u32_e32 v48, vcc, s59, v24
	s_nop 1
	v_addc_co_u32_e32 v49, vcc, 0, v25, vcc
	v_add_co_u32_e32 v50, vcc, s81, v24
	s_nop 1
	v_addc_co_u32_e32 v51, vcc, 0, v25, vcc
	v_add_co_u32_e32 v52, vcc, s83, v24
	s_nop 1
	v_addc_co_u32_e32 v53, vcc, 0, v25, vcc
	v_add_co_u32_e32 v54, vcc, s27, v24
	s_nop 1
	v_addc_co_u32_e32 v55, vcc, 0, v25, vcc
	v_add_co_u32_e32 v56, vcc, s50, v24
	s_nop 1
	v_addc_co_u32_e32 v57, vcc, 0, v25, vcc
	v_add_co_u32_e32 v58, vcc, s53, v24
	s_nop 1
	v_addc_co_u32_e32 v59, vcc, 0, v25, vcc
	v_add_co_u32_e32 v60, vcc, s0, v24
	s_nop 1
	v_addc_co_u32_e32 v61, vcc, 0, v25, vcc
	v_add_co_u32_e32 v62, vcc, s73, v24
	s_nop 1
	v_addc_co_u32_e32 v63, vcc, 0, v25, vcc
	v_add_co_u32_e32 v64, vcc, s1, v24
	s_nop 1
	v_addc_co_u32_e32 v65, vcc, 0, v25, vcc
	v_add_co_u32_e32 v66, vcc, s72, v24
	s_nop 1
	v_addc_co_u32_e32 v67, vcc, 0, v25, vcc
	v_add_co_u32_e32 v68, vcc, s82, v24
	s_nop 1
	v_addc_co_u32_e32 v69, vcc, 0, v25, vcc
	v_add_co_u32_e32 v70, vcc, s33, v24
	s_nop 1
	v_addc_co_u32_e32 v71, vcc, 0, v25, vcc
	v_add_co_u32_e32 v72, vcc, s22, v24
	s_nop 1
	v_addc_co_u32_e32 v73, vcc, 0, v25, vcc
	v_add_co_u32_e32 v78, vcc, s38, v24
	s_nop 1
	v_addc_co_u32_e32 v79, vcc, 0, v25, vcc
	v_add_co_u32_e32 v80, vcc, s39, v24
	s_nop 1
	v_addc_co_u32_e32 v81, vcc, 0, v25, vcc
	v_add_co_u32_e32 v82, vcc, s56, v24
	s_nop 1
	v_addc_co_u32_e32 v83, vcc, 0, v25, vcc
	v_add_co_u32_e32 v84, vcc, s69, v24
	s_nop 1
	v_addc_co_u32_e32 v85, vcc, 0, v25, vcc
	v_add_co_u32_e32 v86, vcc, s87, v24
	s_nop 1
	v_addc_co_u32_e32 v87, vcc, 0, v25, vcc
	v_add_co_u32_e32 v88, vcc, s90, v24
	s_nop 1
	v_addc_co_u32_e32 v89, vcc, 0, v25, vcc
	v_add_co_u32_e32 v90, vcc, s51, v24
	s_nop 1
	v_addc_co_u32_e32 v91, vcc, 0, v25, vcc
	v_add_co_u32_e32 v24, vcc, s52, v24
	s_nop 1
	v_addc_co_u32_e32 v25, vcc, 0, v25, vcc
	global_load_dword v98, v[26:27], off offset:-4096
	s_nop 0
	global_load_dword v26, v[26:27], off
	s_nop 0
	global_load_dword v27, v[28:29], off offset:-4096
	s_nop 0
	global_load_dword v28, v[28:29], off
	s_nop 0
	global_load_dword v29, v[30:31], off offset:-4096
	s_nop 0
	global_load_dword v30, v[30:31], off
	s_nop 0
	global_load_dword v31, v[32:33], off offset:-4096
	s_nop 0
	global_load_dword v32, v[32:33], off
	s_nop 0
	global_load_dword v33, v[34:35], off offset:-4096
	s_nop 0
	global_load_dword v34, v[34:35], off
	s_nop 0
	global_load_dword v35, v[36:37], off offset:-4096
	s_nop 0
	global_load_dword v36, v[36:37], off
	s_nop 0
	global_load_dword v37, v[38:39], off offset:-4096
	s_nop 0
	global_load_dword v38, v[38:39], off
	s_nop 0
	global_load_dword v39, v[40:41], off offset:-4096
; __device__ __forceinline__ unsigned pk2(float lo, float hi) { f32x2 v = {lo, hi}; bf16x2_t b = __builtin_convertvector(v, bf16x2_t); return __builtin_bit_cast(unsigned, b); }
; __device__ __forceinline__ void transpose_item(const float* W, int K, int N, bf16_t* WT, const float* gk, int mode, LAS float* scr_, int item, int lane) {
;     ...
;     for (int kp = 0; kp < 32; ++kp) { va[kp] = src[(size_t)(2 * kp) * N]; vb[kp] = src[(size_t)(2 * kp + 1) * N]; }
; #pragma unroll
;     for (int kp = 0; kp < 32; ++kp) {
;         float a = va[kp], b = vb[kp];
;         if (gk) { a *= gk[k0 + 2 * kp]; b *= gk[k0 + 2 * kp + 1]; }
;         scr[kp * 65 + lane] = pk2(a, b);
	s_nop 0
	global_load_dword v40, v[40:41], off
	s_nop 0
	global_load_dword v41, v[42:43], off offset:-4096
	s_nop 0
	global_load_dword v42, v[42:43], off
	s_nop 0
	global_load_dword v43, v[44:45], off offset:-4096
	s_nop 0
	global_load_dword v44, v[44:45], off
	s_nop 0
	global_load_dword v45, v[46:47], off offset:-4096
	s_nop 0
	global_load_dword v46, v[46:47], off
	s_nop 0
	global_load_dword v47, v[48:49], off offset:-4096
	s_nop 0
	global_load_dword v48, v[48:49], off
	s_nop 0
	global_load_dword v49, v[50:51], off offset:-4096
	s_nop 0
	global_load_dword v50, v[50:51], off
	s_nop 0
	global_load_dword v51, v[52:53], off offset:-4096
	s_nop 0
	global_load_dword v52, v[52:53], off
	s_nop 0
	global_load_dword v53, v[54:55], off offset:-4096
	s_nop 0
	global_load_dword v54, v[54:55], off
	s_nop 0
	global_load_dword v55, v[56:57], off offset:-4096
	s_nop 0
	global_load_dword v56, v[56:57], off
	s_nop 0
	global_load_dword v57, v[58:59], off offset:-4096
	s_nop 0
	global_load_dword v58, v[58:59], off
	s_nop 0
	global_load_dword v59, v[60:61], off offset:-4096
	s_nop 0
	global_load_dword v60, v[60:61], off
	s_nop 0
	global_load_dword v61, v[62:63], off offset:-4096
	s_nop 0
	global_load_dword v62, v[62:63], off
	s_nop 0
	global_load_dword v63, v[64:65], off offset:-4096
	s_nop 0
	global_load_dword v64, v[64:65], off
	s_nop 0
	global_load_dword v65, v[66:67], off offset:-4096
	s_nop 0
	global_load_dword v66, v[66:67], off
	s_nop 0
	global_load_dword v67, v[68:69], off offset:-4096
	s_nop 0
	global_load_dword v68, v[68:69], off
	s_nop 0
	global_load_dword v69, v[70:71], off offset:-4096
	s_nop 0
	global_load_dword v70, v[70:71], off
	s_nop 0
	global_load_dword v71, v[72:73], off offset:-4096
	s_nop 0
	global_load_dword v72, v[72:73], off
	s_nop 0
	global_load_dword v73, v[78:79], off offset:-4096
	s_nop 0
	global_load_dword v78, v[78:79], off
	s_nop 0
	global_load_dword v79, v[80:81], off offset:-4096
	s_nop 0
	global_load_dword v80, v[80:81], off
	s_nop 0
	global_load_dword v81, v[82:83], off offset:-4096
	s_nop 0
	global_load_dword v82, v[82:83], off
	s_nop 0
	global_load_dword v83, v[84:85], off offset:-4096
	s_nop 0
	global_load_dword v84, v[84:85], off
	s_nop 0
	global_load_dword v85, v[86:87], off offset:-4096
	s_nop 0
	global_load_dword v86, v[86:87], off
	s_nop 0
	global_load_dword v87, v[88:89], off offset:-4096
	s_nop 0
	global_load_dword v88, v[88:89], off
	s_nop 0
	global_load_dword v89, v[90:91], off offset:-4096
	s_nop 0
	global_load_dword v90, v[90:91], off
	s_nop 0
	global_load_dword v24, v[24:25], off
	s_waitcnt vmcnt(62)
	v_cvt_pk_bf16_f32 v25, v97, v98
	s_waitcnt vmcnt(60)
	v_cvt_pk_bf16_f32 v26, v26, v27
	s_waitcnt vmcnt(58)
	v_cvt_pk_bf16_f32 v27, v28, v29
	s_waitcnt vmcnt(56)
	v_cvt_pk_bf16_f32 v28, v30, v31
	s_waitcnt vmcnt(54)
	v_cvt_pk_bf16_f32 v29, v32, v33
	s_waitcnt vmcnt(52)
	v_cvt_pk_bf16_f32 v30, v34, v35
	s_waitcnt vmcnt(50)
	v_cvt_pk_bf16_f32 v31, v36, v37
	s_waitcnt vmcnt(48)
	v_cvt_pk_bf16_f32 v32, v38, v39
	s_waitcnt vmcnt(46)
	v_cvt_pk_bf16_f32 v33, v40, v41
	s_waitcnt vmcnt(44)
	v_cvt_pk_bf16_f32 v34, v42, v43
	s_waitcnt vmcnt(42)
	v_cvt_pk_bf16_f32 v35, v44, v45
	s_waitcnt vmcnt(40)
	v_cvt_pk_bf16_f32 v36, v46, v47
	s_waitcnt vmcnt(38)
	v_cvt_pk_bf16_f32 v37, v48, v49
	s_waitcnt vmcnt(36)
	v_cvt_pk_bf16_f32 v38, v50, v51
	s_waitcnt vmcnt(34)
	v_cvt_pk_bf16_f32 v39, v52, v53
	s_waitcnt vmcnt(32)
	v_cvt_pk_bf16_f32 v40, v54, v55
	s_waitcnt vmcnt(30)
	v_cvt_pk_bf16_f32 v41, v56, v57
	s_waitcnt vmcnt(28)
	v_cvt_pk_bf16_f32 v42, v58, v59
	s_waitcnt vmcnt(26)
; #define LAS __attribute__((address_space(3)))
; __device__ __forceinline__ unsigned pk2(float lo, float hi) { f32x2 v = {lo, hi}; bf16x2_t b = __builtin_convertvector(v, bf16x2_t); return __builtin_bit_cast(unsigned, b); }
; __device__ __forceinline__ void transpose_item(const float* W, int K, int N, bf16_t* WT, const float* gk, int mode, LAS float* scr_, int item, int lane) {
;     ...
;     for (int kp = 0; kp < 32; ++kp) {
;         float a = va[kp], b = vb[kp];
;         if (gk) { a *= gk[k0 + 2 * kp]; b *= gk[k0 + 2 * kp + 1]; }
;         scr[kp * 65 + lane] = pk2(a, b);
;     }
;     asm volatile("s_waitcnt lgkmcnt(0)" ::: "memory");
;     const int c = lane & 7;
; #pragma unroll
;     for (int j = 0; j < 8; ++j) { const int r = (lane >> 3) + 8 * j; const LAS unsigned* q = scr + (4 * c) * 65 + r;
;         u32x4 o; o.x = q[0]; o.y = q[65]; o.z = q[130]; o.w = q[195];
;         *(u32x4*)(WT + (size_t)(n0 + r) * K + k0 + 8 * c) = o; }
;     asm volatile("s_waitcnt lgkmcnt(0)" ::: "memory");
	v_cvt_pk_bf16_f32 v43, v60, v61
	s_waitcnt vmcnt(24)
	v_cvt_pk_bf16_f32 v44, v62, v63
	s_waitcnt vmcnt(22)
	v_cvt_pk_bf16_f32 v45, v64, v65
	s_waitcnt vmcnt(20)
	v_cvt_pk_bf16_f32 v46, v66, v67
	s_waitcnt vmcnt(18)
	v_cvt_pk_bf16_f32 v47, v68, v69
	s_waitcnt vmcnt(16)
	v_cvt_pk_bf16_f32 v48, v70, v71
	s_waitcnt vmcnt(14)
	v_cvt_pk_bf16_f32 v49, v72, v73
	s_waitcnt vmcnt(12)
	v_cvt_pk_bf16_f32 v50, v78, v79
	s_waitcnt vmcnt(10)
	v_cvt_pk_bf16_f32 v51, v80, v81
	s_waitcnt vmcnt(8)
	v_cvt_pk_bf16_f32 v52, v82, v83
	s_waitcnt vmcnt(6)
	v_cvt_pk_bf16_f32 v53, v84, v85
	s_waitcnt vmcnt(4)
	v_cvt_pk_bf16_f32 v54, v86, v87
	s_waitcnt vmcnt(2)
	v_cvt_pk_bf16_f32 v55, v88, v89
	s_waitcnt vmcnt(0)
	v_cvt_pk_bf16_f32 v24, v90, v24
	ds_write2_b32 v75, v25, v26 offset1:65
	ds_write2_b32 v75, v27, v28 offset0:130 offset1:195
	ds_write2_b32 v23, v29, v30 offset0:4 offset1:69
	ds_write2_b32 v23, v31, v32 offset0:134 offset1:199
	ds_write2_b32 v77, v33, v34 offset0:8 offset1:73
	ds_write2_b32 v77, v35, v36 offset0:138 offset1:203
	ds_write2_b32 v92, v37, v38 offset0:12 offset1:77
	ds_write2_b32 v92, v39, v40 offset0:142 offset1:207
	ds_write2_b32 v93, v41, v42 offset0:16 offset1:81
	ds_write2_b32 v93, v43, v44 offset0:146 offset1:211
	ds_write2_b32 v94, v45, v46 offset0:20 offset1:85
	ds_write2_b32 v94, v47, v48 offset0:150 offset1:215
	ds_write2_b32 v95, v49, v50 offset0:24 offset1:89
	ds_write2_b32 v95, v51, v52 offset0:154 offset1:219
	ds_write2_b32 v96, v53, v54 offset0:28 offset1:93
	ds_write2_b32 v96, v55, v24 offset0:158 offset1:223
	s_waitcnt lgkmcnt(0)
	ds_read2_b32 v[24:25], v3 offset0:65 offset1:73
	ds_read2_b32 v[44:45], v3 offset0:130 offset1:138
	ds_read2_b32 v[26:27], v3 offset0:195 offset1:203
	ds_read2_b32 v[46:47], v3 offset1:8
	ds_read2_b32 v[48:49], v3 offset0:16 offset1:24
	ds_read2_b32 v[28:29], v3 offset0:81 offset1:89
	ds_read2_b32 v[50:51], v3 offset0:146 offset1:154
	ds_read2_b32 v[30:31], v3 offset0:211 offset1:219
	ds_read2_b32 v[32:33], v3 offset0:97 offset1:105
	ds_read2_b32 v[52:53], v3 offset0:162 offset1:170
	ds_read2_b32 v[34:35], v3 offset0:227 offset1:235
	ds_read2_b32 v[54:55], v3 offset0:32 offset1:40
	ds_read2_b32 v[56:57], v3 offset0:48 offset1:56
	ds_read2_b32 v[36:37], v3 offset0:113 offset1:121
	ds_read2_b32 v[58:59], v3 offset0:178 offset1:186
	ds_read2_b32 v[38:39], v3 offset0:243 offset1:251
	s_waitcnt lgkmcnt(12)
	v_mov_b32_e32 v40, v46
	v_mov_b32_e32 v41, v24
	v_mov_b32_e32 v42, v44
	v_mov_b32_e32 v43, v26
	v_mov_b32_e32 v24, v47
	v_mov_b32_e32 v26, v45
	s_waitcnt lgkmcnt(11)
	v_mov_b32_e32 v44, v48
	s_waitcnt lgkmcnt(10)
	v_mov_b32_e32 v45, v28
	s_waitcnt lgkmcnt(9)
	v_mov_b32_e32 v46, v50
	s_waitcnt lgkmcnt(8)
	v_mov_b32_e32 v47, v30
	v_mov_b32_e32 v28, v49
	v_mov_b32_e32 v30, v51
	s_waitcnt lgkmcnt(4)
	v_mov_b32_e32 v48, v54
	v_mov_b32_e32 v49, v32
	v_mov_b32_e32 v50, v52
	v_mov_b32_e32 v51, v34
	v_mov_b32_e32 v32, v55
	v_mov_b32_e32 v34, v53
	s_waitcnt lgkmcnt(3)
	v_mov_b32_e32 v52, v56
	s_waitcnt lgkmcnt(2)
	v_mov_b32_e32 v53, v36
	s_waitcnt lgkmcnt(1)
	v_mov_b32_e32 v54, v58
	s_waitcnt lgkmcnt(0)
	v_mov_b32_e32 v55, v38
	v_mov_b32_e32 v36, v57
	v_mov_b32_e32 v38, v59
	global_store_dwordx4 v[6:7], v[40:43], off
	global_store_dwordx4 v[8:9], v[24:27], off
	global_store_dwordx4 v[10:11], v[44:47], off
	global_store_dwordx4 v[12:13], v[28:31], off
	global_store_dwordx4 v[14:15], v[48:51], off
	global_store_dwordx4 v[16:17], v[32:35], off
	global_store_dwordx4 v[18:19], v[52:55], off
	global_store_dwordx4 v[20:21], v[36:39], off
	s_waitcnt lgkmcnt(0)
	s_cbranch_scc1 .LBB0_2390

; #define LAS __attribute__((address_space(3)))
; #define PIN(i) ((const float*)ldq_(L, (i)))
; __device__ __forceinline__ unsigned pk2(float lo, float hi) { f32x2 v = {lo, hi}; bf16x2_t b = __builtin_convertvector(v, bf16x2_t); return __builtin_bit_cast(unsigned, b); }
; #define PREP_CONV(bit, SRC, Kd, Nd, DST, GK, MODE) if (mask & (bit)) { for (int it = gw; it < ((Kd) / 64) * ((Nd) / 64); it += NGW) transpose_item((SRC), (Kd), (Nd), (bf16_t*)(wl + (DST)), (GK), (MODE), scr, it, lane); }
; __device__ __forceinline__ void transpose_item(const float* W, int K, int N, bf16_t* WT, const float* gk, int mode, LAS float* scr_, int item, int lane) {
;     LAS unsigned* scr = (LAS unsigned*)scr_;
;     const int nblk = N / 64, kb = item / nblk, nb = item % nblk, k0 = 64 * kb, n0 = 64 * nb;
;     const int sc = (mode == 1) ? (((n0 >> 7) & 1) * DFF + (n0 >> 8) * 128 + (n0 & 127)) : n0;
;     const float* src = W + (size_t)k0 * N + sc + lane;
;     float va[32], vb[32];
; #pragma unroll
;     for (int kp = 0; kp < 32; ++kp) { va[kp] = src[(size_t)(2 * kp) * N]; vb[kp] = src[(size_t)(2 * kp + 1) * N]; }
; #pragma unroll
;     for (int kp = 0; kp < 32; ++kp) {
;         float a = va[kp], b = vb[kp];
;         if (gk) { a *= gk[k0 + 2 * kp]; b *= gk[k0 + 2 * kp + 1]; }
;         scr[kp * 65 + lane] = pk2(a, b);
; __device__ __forceinline__ void prep(const Params& p, LAS unsigned char* L, int wv, int vb, int nvb, int l, int mask) {
;     ...
;     PREP_CONV(PM_PEG, PIN(I_WPEG) + (size_t)l * DM * DM, DM, DM, WL_PEG, PIN(I_NPE) + l * DM, 0)
.LBB0_2394:
	v_mov_b32_e32 v6, v161
	s_nop 0
	v_add_u32_e32 v6, 0, v6
	v_add_u32_e32 v6, 0x201b0, v6
	ds_read_b64 v[6:7], v6
	s_waitcnt lgkmcnt(0)
	v_readfirstlane_b32 s5, v6
	v_mov_b32_e32 v6, v161
	v_readfirstlane_b32 s4, v7
	v_add_u32_e32 v6, 0, v6
	v_add_u32_e32 v6, 0x201a8, v6
	s_nop 0
	s_add_u32 s15, s5, s8
	s_addc_u32 s21, s4, s9
	s_waitcnt lgkmcnt(0)
	v_readlane_b32 s4, v251, 42
	v_readlane_b32 s5, v251, 43
	s_add_u32 s30, s4, s10
	s_addc_u32 s31, s5, s11
	s_ashr_i32 s12, s28, 31
	s_lshr_b32 s12, s12, 28
	s_add_i32 s12, s28, s12
	s_ashr_i32 s13, s12, 4
	s_lshl_b32 s12, s13, 6
	s_lshl_b32 s29, s13, 10
	s_ashr_i32 s13, s12, 31
	s_sub_i32 s14, s25, s29
	s_lshl_b64 s[18:19], s[12:13], 12
	s_add_u32 s18, s15, s18
	s_addc_u32 s19, s21, s19
	s_ashr_i32 s15, s14, 31
	s_lshl_b64 s[14:15], s[14:15], 2
	s_add_u32 s14, s18, s14
	s_addc_u32 s15, s19, s15
	v_lshl_add_u64 v[70:71], s[14:15], 0, v[160:161]
	v_add_co_u32_e32 v6, vcc, s79, v70
	global_load_dword v66, v160, s[14:15]
	s_nop 0
	v_addc_co_u32_e32 v7, vcc, 0, v71, vcc
	global_load_dword v67, v[6:7], off offset:-4096
	global_load_dword v68, v[6:7], off
	v_add_co_u32_e32 v6, vcc, s88, v70
	s_mov_b32 s14, 0x3d000
	s_nop 0
	v_addc_co_u32_e32 v7, vcc, 0, v71, vcc
	global_load_dword v69, v[6:7], off offset:-4096
	global_load_dword v62, v[6:7], off
	v_add_co_u32_e32 v6, vcc, s80, v70
	s_cmp_lg_u64 s[4:5], 0
	s_nop 0
	v_addc_co_u32_e32 v7, vcc, 0, v71, vcc
	global_load_dword v63, v[6:7], off offset:-4096
	global_load_dword v64, v[6:7], off
	v_add_co_u32_e32 v6, vcc, s70, v70
	s_mov_b64 s[18:19], -1
	s_nop 0
	v_addc_co_u32_e32 v7, vcc, 0, v71, vcc
	global_load_dword v65, v[6:7], off offset:-4096
	global_load_dword v58, v[6:7], off
	v_add_co_u32_e32 v6, vcc, s71, v70
	s_nop 1
	v_addc_co_u32_e32 v7, vcc, 0, v71, vcc
	global_load_dword v59, v[6:7], off offset:-4096
	global_load_dword v60, v[6:7], off
	v_add_co_u32_e32 v6, vcc, s91, v70
	s_nop 1
	v_addc_co_u32_e32 v7, vcc, 0, v71, vcc
	global_load_dword v61, v[6:7], off offset:-4096
	global_load_dword v54, v[6:7], off
	v_add_co_u32_e32 v6, vcc, s92, v70
	s_nop 1
	v_addc_co_u32_e32 v7, vcc, 0, v71, vcc
	global_load_dword v55, v[6:7], off offset:-4096
	global_load_dword v56, v[6:7], off
	v_add_co_u32_e32 v6, vcc, s37, v70
	s_nop 1
	v_addc_co_u32_e32 v7, vcc, 0, v71, vcc
	global_load_dword v57, v[6:7], off offset:-4096
	global_load_dword v50, v[6:7], off
	v_add_co_u32_e32 v6, vcc, s94, v70
	s_nop 1
	v_addc_co_u32_e32 v7, vcc, 0, v71, vcc
	global_load_dword v51, v[6:7], off offset:-4096
	global_load_dword v52, v[6:7], off
	v_add_co_u32_e32 v6, vcc, s46, v70
	s_nop 1
	v_addc_co_u32_e32 v7, vcc, 0, v71, vcc
	global_load_dword v53, v[6:7], off offset:-4096
	global_load_dword v46, v[6:7], off
	v_add_co_u32_e32 v6, vcc, s47, v70
	s_nop 1
	v_addc_co_u32_e32 v7, vcc, 0, v71, vcc
	global_load_dword v47, v[6:7], off offset:-4096
	global_load_dword v48, v[6:7], off
	v_add_co_u32_e32 v6, vcc, s59, v70
	s_nop 1
	v_addc_co_u32_e32 v7, vcc, 0, v71, vcc
	global_load_dword v49, v[6:7], off offset:-4096
	global_load_dword v42, v[6:7], off
	v_add_co_u32_e32 v6, vcc, s81, v70
	s_nop 1
	v_addc_co_u32_e32 v7, vcc, 0, v71, vcc
	global_load_dword v43, v[6:7], off offset:-4096
	global_load_dword v44, v[6:7], off
	v_add_co_u32_e32 v6, vcc, s83, v70
	s_nop 1
	v_addc_co_u32_e32 v7, vcc, 0, v71, vcc
	global_load_dword v45, v[6:7], off offset:-4096
	global_load_dword v38, v[6:7], off
	v_add_co_u32_e32 v6, vcc, s27, v70
	s_nop 1
	v_addc_co_u32_e32 v7, vcc, 0, v71, vcc
	global_load_dword v39, v[6:7], off offset:-4096
	global_load_dword v40, v[6:7], off
	v_add_co_u32_e32 v6, vcc, s50, v70
	s_nop 1
	v_addc_co_u32_e32 v7, vcc, 0, v71, vcc
	global_load_dword v41, v[6:7], off offset:-4096
	global_load_dword v34, v[6:7], off
	v_add_co_u32_e32 v6, vcc, s53, v70
	s_nop 1
	v_addc_co_u32_e32 v7, vcc, 0, v71, vcc
	global_load_dword v35, v[6:7], off offset:-4096
	global_load_dword v36, v[6:7], off
	v_add_co_u32_e32 v6, vcc, s0, v70
	s_nop 1
	v_addc_co_u32_e32 v7, vcc, 0, v71, vcc
	global_load_dword v37, v[6:7], off offset:-4096
	global_load_dword v30, v[6:7], off
	v_add_co_u32_e32 v6, vcc, s73, v70
	s_nop 1
	v_addc_co_u32_e32 v7, vcc, 0, v71, vcc
	global_load_dword v31, v[6:7], off offset:-4096
	global_load_dword v32, v[6:7], off
	v_add_co_u32_e32 v6, vcc, s1, v70
	s_nop 1
	v_addc_co_u32_e32 v7, vcc, 0, v71, vcc
	global_load_dword v33, v[6:7], off offset:-4096
	global_load_dword v26, v[6:7], off
	v_add_co_u32_e32 v6, vcc, s72, v70
	s_nop 1
	v_addc_co_u32_e32 v7, vcc, 0, v71, vcc
	global_load_dword v27, v[6:7], off offset:-4096
	global_load_dword v28, v[6:7], off
	v_add_co_u32_e32 v6, vcc, s82, v70
	s_nop 1
	v_addc_co_u32_e32 v7, vcc, 0, v71, vcc
	global_load_dword v29, v[6:7], off offset:-4096
	global_load_dword v22, v[6:7], off
	v_add_co_u32_e32 v6, vcc, s33, v70
	s_nop 1
	v_addc_co_u32_e32 v7, vcc, 0, v71, vcc
	global_load_dword v23, v[6:7], off offset:-4096
	global_load_dword v24, v[6:7], off
	v_add_co_u32_e32 v6, vcc, s22, v70
	s_nop 1
	v_addc_co_u32_e32 v7, vcc, 0, v71, vcc
	global_load_dword v25, v[6:7], off offset:-4096
	global_load_dword v18, v[6:7], off
	v_add_co_u32_e32 v6, vcc, s38, v70
	s_nop 1
	v_addc_co_u32_e32 v7, vcc, 0, v71, vcc
	global_load_dword v19, v[6:7], off offset:-4096
	global_load_dword v20, v[6:7], off
	v_add_co_u32_e32 v6, vcc, s39, v70
	s_nop 1
	v_addc_co_u32_e32 v7, vcc, 0, v71, vcc
	global_load_dword v21, v[6:7], off offset:-4096
	global_load_dword v14, v[6:7], off
	v_add_co_u32_e32 v6, vcc, s56, v70
	s_nop 1
	v_addc_co_u32_e32 v7, vcc, 0, v71, vcc
	global_load_dword v15, v[6:7], off offset:-4096
	global_load_dword v16, v[6:7], off
	v_add_co_u32_e32 v6, vcc, s69, v70
	s_nop 1
	v_addc_co_u32_e32 v7, vcc, 0, v71, vcc
	v_add_co_u32_e32 v8, vcc, s87, v70
	global_load_dword v17, v[6:7], off offset:-4096
	s_nop 0
	global_load_dword v6, v[6:7], off
	v_addc_co_u32_e32 v9, vcc, 0, v71, vcc
	global_load_dword v7, v[8:9], off offset:-4096
	global_load_dword v12, v[8:9], off
	v_add_co_u32_e32 v8, vcc, 0x3b000, v70
	s_nop 1
	v_addc_co_u32_e32 v9, vcc, 0, v71, vcc
	v_add_co_u32_e32 v10, vcc, s14, v70
	global_load_dword v13, v[8:9], off
	s_nop 0
	v_addc_co_u32_e32 v11, vcc, 0, v71, vcc
	global_load_dword v8, v[10:11], off offset:-4096
	global_load_dword v9, v[10:11], off
	v_add_co_u32_e32 v10, vcc, 0x3e000, v70
	s_cselect_b64 s[14:15], -1, 0
	s_nop 0
	v_addc_co_u32_e32 v11, vcc, 0, v71, vcc
	v_add_co_u32_e32 v70, vcc, 0x3f000, v70
	global_load_dword v10, v[10:11], off
	s_nop 0
	v_addc_co_u32_e32 v71, vcc, 0, v71, vcc
	global_load_dword v11, v[70:71], off
	s_cmp_eq_u64 s[4:5], 0
	s_cbranch_scc1 .LBB0_2396
	s_lshl_b64 s[4:5], s[12:13], 2
	s_add_u32 s4, s30, s4
	s_addc_u32 s5, s31, s5
	global_load_dwordx4 v[70:73], v161, s[4:5]
	s_mov_b64 s[18:19], 0
	s_waitcnt vmcnt(0)
	v_pk_mul_f32 v[70:71], v[66:67], v[70:71]
	v_pk_mul_f32 v[72:73], v[68:69], v[72:73]

; #define LAS __attribute__((address_space(3)))
; #define PIN(i) ((const float*)ldq_(L, (i)))
; __device__ __forceinline__ unsigned pk2(float lo, float hi) { f32x2 v = {lo, hi}; bf16x2_t b = __builtin_convertvector(v, bf16x2_t); return __builtin_bit_cast(unsigned, b); }
; #define PREP_CONV(bit, SRC, Kd, Nd, DST, GK, MODE) if (mask & (bit)) { for (int it = gw; it < ((Kd) / 64) * ((Nd) / 64); it += NGW) transpose_item((SRC), (Kd), (Nd), (bf16_t*)(wl + (DST)), (GK), (MODE), scr, it, lane); }
; __device__ __forceinline__ void transpose_item(const float* W, int K, int N, bf16_t* WT, const float* gk, int mode, LAS float* scr_, int item, int lane) {
;     LAS unsigned* scr = (LAS unsigned*)scr_;
;     const int nblk = N / 64, kb = item / nblk, nb = item % nblk, k0 = 64 * kb, n0 = 64 * nb;
;     const int sc = (mode == 1) ? (((n0 >> 7) & 1) * DFF + (n0 >> 8) * 128 + (n0 & 127)) : n0;
;     const float* src = W + (size_t)k0 * N + sc + lane;
;     float va[32], vb[32];
; #pragma unroll
;     for (int kp = 0; kp < 32; ++kp) { va[kp] = src[(size_t)(2 * kp) * N]; vb[kp] = src[(size_t)(2 * kp + 1) * N]; }
; #pragma unroll
;     for (int kp = 0; kp < 32; ++kp) {
;         float a = va[kp], b = vb[kp];
;         if (gk) { a *= gk[k0 + 2 * kp]; b *= gk[k0 + 2 * kp + 1]; }
;         scr[kp * 65 + lane] = pk2(a, b);
;     }
;     asm volatile("s_waitcnt lgkmcnt(0)" ::: "memory");
;     const int c = lane & 7;
; #pragma unroll
;     for (int j = 0; j < 8; ++j) { const int r = (lane >> 3) + 8 * j; const LAS unsigned* q = scr + (4 * c) * 65 + r;
;         u32x4 o; o.x = q[0]; o.y = q[65]; o.z = q[130]; o.w = q[195];
;         *(u32x4*)(WT + (size_t)(n0 + r) * K + k0 + 8 * c) = o; }
;     asm volatile("s_waitcnt lgkmcnt(0)" ::: "memory");
; __device__ __forceinline__ void prep(const Params& p, LAS unsigned char* L, int wv, int vb, int nvb, int l, int mask) {
;     ...
;     PREP_CONV(PM_PEU, PIN(I_WPEU) + (size_t)l * PED * DM, PED, DM, WL_PEU, nullptr, 0)
.LBB0_2460:
	v_mov_b32_e32 v0, v161
	s_nop 0
	v_add_u32_e32 v0, 0, v0
	v_add_u32_e32 v0, 0x201b8, v0
	s_nop 0
	s_waitcnt lgkmcnt(0)
	v_readlane_b32 s7, v251, 46
	v_readlane_b32 s6, v251, 47
	s_add_u32 s7, s7, s4
	s_addc_u32 s11, s6, s5
	s_ashr_i32 s6, s16, 31
	s_lshr_b32 s6, s6, 28
	s_add_i32 s6, s16, s6
	s_ashr_i32 s6, s6, 4
	s_lshl_b32 s8, s6, 6
	s_lshl_b32 s6, s6, 10
	s_ashr_i32 s9, s8, 31
	s_sub_i32 s6, s10, s6
	s_lshl_b64 s[12:13], s[8:9], 12
	s_add_u32 s14, s7, s12
	s_addc_u32 s11, s11, s13
	s_ashr_i32 s7, s6, 31
	s_lshl_b64 s[12:13], s[6:7], 2
	s_add_u32 s12, s14, s12
	s_addc_u32 s13, s11, s13
	v_lshl_add_u64 v[56:57], s[12:13], 0, v[160:161]
	v_add_co_u32_e32 v0, vcc, s79, v56
	global_load_dword v55, v160, s[12:13]
	s_nop 0
	v_addc_co_u32_e32 v1, vcc, 0, v57, vcc
	global_load_dword v58, v[0:1], off offset:-4096
	global_load_dword v59, v[0:1], off
	v_add_co_u32_e32 v0, vcc, s88, v56
	s_add_i32 s10, s10, 0x1c000
	s_nop 0
	v_addc_co_u32_e32 v1, vcc, 0, v57, vcc
	global_load_dword v60, v[0:1], off offset:-4096
	global_load_dword v61, v[0:1], off
	v_add_co_u32_e32 v0, vcc, s80, v56
	s_waitcnt vmcnt(3)
	v_cvt_pk_bf16_f32 v55, v55, v58
	v_addc_co_u32_e32 v1, vcc, 0, v57, vcc
	global_load_dword v62, v[0:1], off offset:-4096
	global_load_dword v63, v[0:1], off
	v_add_co_u32_e32 v0, vcc, s70, v56
	s_nop 1
	v_addc_co_u32_e32 v1, vcc, 0, v57, vcc
	global_load_dword v64, v[0:1], off offset:-4096
	global_load_dword v65, v[0:1], off
	v_add_co_u32_e32 v0, vcc, s71, v56
	s_nop 1
	v_addc_co_u32_e32 v1, vcc, 0, v57, vcc
	global_load_dword v66, v[0:1], off offset:-4096
	global_load_dword v67, v[0:1], off
	v_add_co_u32_e32 v0, vcc, s91, v56
	s_nop 1
	v_addc_co_u32_e32 v1, vcc, 0, v57, vcc
	global_load_dword v68, v[0:1], off offset:-4096
	global_load_dword v47, v[0:1], off
	v_add_co_u32_e32 v0, vcc, s92, v56
	s_nop 1
	v_addc_co_u32_e32 v1, vcc, 0, v57, vcc
	global_load_dword v48, v[0:1], off offset:-4096
	global_load_dword v49, v[0:1], off
	v_add_co_u32_e32 v0, vcc, s37, v56
	s_waitcnt vmcnt(1)
	v_cvt_pk_bf16_f32 v47, v47, v48
	v_addc_co_u32_e32 v1, vcc, 0, v57, vcc
	global_load_dword v51, v[0:1], off offset:-4096
	global_load_dword v50, v[0:1], off
	v_add_co_u32_e32 v0, vcc, s94, v56
	s_waitcnt vmcnt(1)
	v_cvt_pk_bf16_f32 v48, v49, v51
	v_addc_co_u32_e32 v1, vcc, 0, v57, vcc
	global_load_dword v52, v[0:1], off offset:-4096
	global_load_dword v53, v[0:1], off
	v_add_co_u32_e32 v0, vcc, s46, v56
	v_add_u32_e32 v49, 0x800, v75
	s_nop 0
	v_addc_co_u32_e32 v1, vcc, 0, v57, vcc
	global_load_dword v54, v[0:1], off offset:-4096
	global_load_dword v39, v[0:1], off
	v_add_co_u32_e32 v0, vcc, s47, v56
	s_nop 1
	v_addc_co_u32_e32 v1, vcc, 0, v57, vcc
	global_load_dword v40, v[0:1], off offset:-4096
	global_load_dword v41, v[0:1], off
	v_add_co_u32_e32 v0, vcc, s59, v56
	s_waitcnt vmcnt(1)
	v_cvt_pk_bf16_f32 v39, v39, v40
	v_addc_co_u32_e32 v1, vcc, 0, v57, vcc
	global_load_dword v43, v[0:1], off offset:-4096
	global_load_dword v42, v[0:1], off
	v_add_co_u32_e32 v0, vcc, s81, v56
	s_waitcnt vmcnt(1)
	v_cvt_pk_bf16_f32 v40, v41, v43
	v_addc_co_u32_e32 v1, vcc, 0, v57, vcc
	global_load_dword v44, v[0:1], off offset:-4096
	global_load_dword v45, v[0:1], off
	v_add_co_u32_e32 v0, vcc, s83, v56
	v_add_u32_e32 v41, 0xc00, v75
	s_nop 0
	v_addc_co_u32_e32 v1, vcc, 0, v57, vcc
	global_load_dword v46, v[0:1], off offset:-4096
	global_load_dword v31, v[0:1], off
	v_add_co_u32_e32 v0, vcc, s27, v56
	s_nop 1
	v_addc_co_u32_e32 v1, vcc, 0, v57, vcc
	global_load_dword v32, v[0:1], off offset:-4096
	global_load_dword v33, v[0:1], off
	v_add_co_u32_e32 v0, vcc, s50, v56
	s_waitcnt vmcnt(1)
	v_cvt_pk_bf16_f32 v31, v31, v32
	v_addc_co_u32_e32 v1, vcc, 0, v57, vcc
	global_load_dword v35, v[0:1], off offset:-4096
	global_load_dword v34, v[0:1], off
	v_add_co_u32_e32 v0, vcc, s53, v56
	s_waitcnt vmcnt(1)
	v_cvt_pk_bf16_f32 v32, v33, v35
	v_addc_co_u32_e32 v1, vcc, 0, v57, vcc
	global_load_dword v36, v[0:1], off offset:-4096
	global_load_dword v37, v[0:1], off
	v_add_co_u32_e32 v0, vcc, s0, v56
	v_add_u32_e32 v33, 0x1000, v75
	s_nop 0
	v_addc_co_u32_e32 v1, vcc, 0, v57, vcc
	global_load_dword v38, v[0:1], off offset:-4096
	global_load_dword v23, v[0:1], off
	v_add_co_u32_e32 v0, vcc, s73, v56
	s_nop 1
	v_addc_co_u32_e32 v1, vcc, 0, v57, vcc
	global_load_dword v24, v[0:1], off offset:-4096
	global_load_dword v25, v[0:1], off
	v_add_co_u32_e32 v0, vcc, s1, v56
	s_waitcnt vmcnt(1)
	v_cvt_pk_bf16_f32 v23, v23, v24
	v_addc_co_u32_e32 v1, vcc, 0, v57, vcc
	global_load_dword v27, v[0:1], off offset:-4096
	global_load_dword v26, v[0:1], off
	v_add_co_u32_e32 v0, vcc, s72, v56
	s_waitcnt vmcnt(1)
	v_cvt_pk_bf16_f32 v24, v25, v27
	v_addc_co_u32_e32 v1, vcc, 0, v57, vcc
	global_load_dword v28, v[0:1], off offset:-4096
	global_load_dword v29, v[0:1], off
	v_add_co_u32_e32 v0, vcc, s82, v56
	v_add_u32_e32 v25, 0x1400, v75
	s_nop 0
	v_addc_co_u32_e32 v1, vcc, 0, v57, vcc
	global_load_dword v30, v[0:1], off offset:-4096
	global_load_dword v15, v[0:1], off
	v_add_co_u32_e32 v0, vcc, s33, v56
	s_nop 1
	v_addc_co_u32_e32 v1, vcc, 0, v57, vcc
	global_load_dword v16, v[0:1], off offset:-4096
	global_load_dword v17, v[0:1], off
	v_add_co_u32_e32 v0, vcc, s22, v56
	s_waitcnt vmcnt(1)
	v_cvt_pk_bf16_f32 v15, v15, v16
	v_addc_co_u32_e32 v1, vcc, 0, v57, vcc
	global_load_dword v19, v[0:1], off offset:-4096
	global_load_dword v18, v[0:1], off
	v_add_co_u32_e32 v0, vcc, s38, v56
	s_waitcnt vmcnt(1)
; #define LAS __attribute__((address_space(3)))
; __device__ __forceinline__ unsigned pk2(float lo, float hi) { f32x2 v = {lo, hi}; bf16x2_t b = __builtin_convertvector(v, bf16x2_t); return __builtin_bit_cast(unsigned, b); }
; __device__ __forceinline__ void transpose_item(const float* W, int K, int N, bf16_t* WT, const float* gk, int mode, LAS float* scr_, int item, int lane) {
;     ...
;     for (int kp = 0; kp < 32; ++kp) { va[kp] = src[(size_t)(2 * kp) * N]; vb[kp] = src[(size_t)(2 * kp + 1) * N]; }
; #pragma unroll
;     for (int kp = 0; kp < 32; ++kp) {
;         float a = va[kp], b = vb[kp];
;         if (gk) { a *= gk[k0 + 2 * kp]; b *= gk[k0 + 2 * kp + 1]; }
;         scr[kp * 65 + lane] = pk2(a, b);
;     }
;     asm volatile("s_waitcnt lgkmcnt(0)" ::: "memory");
;     const int c = lane & 7;
; #pragma unroll
;     for (int j = 0; j < 8; ++j) { const int r = (lane >> 3) + 8 * j; const LAS unsigned* q = scr + (4 * c) * 65 + r;
;         u32x4 o; o.x = q[0]; o.y = q[65]; o.z = q[130]; o.w = q[195];
;         *(u32x4*)(WT + (size_t)(n0 + r) * K + k0 + 8 * c) = o; }
;     asm volatile("s_waitcnt lgkmcnt(0)" ::: "memory");
	v_cvt_pk_bf16_f32 v16, v17, v19
	v_addc_co_u32_e32 v1, vcc, 0, v57, vcc
	global_load_dword v20, v[0:1], off offset:-4096
	global_load_dword v21, v[0:1], off
	v_add_co_u32_e32 v0, vcc, s39, v56
	v_add_u32_e32 v17, 0x1800, v75
	s_nop 0
	v_addc_co_u32_e32 v1, vcc, 0, v57, vcc
	global_load_dword v22, v[0:1], off offset:-4096
	global_load_dword v7, v[0:1], off
	v_add_co_u32_e32 v0, vcc, s56, v56
	s_nop 1
	v_addc_co_u32_e32 v1, vcc, 0, v57, vcc
	global_load_dword v8, v[0:1], off offset:-4096
	global_load_dword v9, v[0:1], off
	v_add_co_u32_e32 v0, vcc, s69, v56
	s_waitcnt vmcnt(1)
	v_cvt_pk_bf16_f32 v7, v7, v8
	v_addc_co_u32_e32 v1, vcc, 0, v57, vcc
	global_load_dword v11, v[0:1], off offset:-4096
	global_load_dword v10, v[0:1], off
	v_add_co_u32_e32 v0, vcc, s87, v56
	s_waitcnt vmcnt(1)
	v_cvt_pk_bf16_f32 v8, v9, v11
	v_addc_co_u32_e32 v1, vcc, 0, v57, vcc
	global_load_dword v12, v[0:1], off offset:-4096
	global_load_dword v13, v[0:1], off
	v_add_co_u32_e32 v0, vcc, s90, v56
	v_add_u32_e32 v9, 0x1c00, v75
	s_nop 0
	v_addc_co_u32_e32 v1, vcc, 0, v57, vcc
	v_add_co_u32_e32 v4, vcc, s51, v56
	global_load_dword v14, v[0:1], off offset:-4096
	s_nop 0
	global_load_dword v0, v[0:1], off
	v_addc_co_u32_e32 v5, vcc, 0, v57, vcc
	v_add_co_u32_e32 v56, vcc, s52, v56
	global_load_dword v1, v[4:5], off offset:-4096
	s_nop 0
	global_load_dword v4, v[4:5], off
	v_addc_co_u32_e32 v57, vcc, 0, v57, vcc
	global_load_dword v5, v[56:57], off
	v_cvt_pk_bf16_f32 v56, v59, v60
	ds_write2_b32 v75, v55, v56 offset1:65
	v_cvt_pk_bf16_f32 v55, v61, v62
	v_cvt_pk_bf16_f32 v56, v63, v64
	v_add_u32_e32 v57, 0x400, v75
	ds_write2_b32 v75, v55, v56 offset0:130 offset1:195
	v_cvt_pk_bf16_f32 v55, v65, v66
	v_cvt_pk_bf16_f32 v56, v67, v68
	ds_write2_b32 v57, v47, v48 offset0:134 offset1:199
	v_cvt_pk_bf16_f32 v47, v50, v52
	v_cvt_pk_bf16_f32 v48, v53, v54
	ds_write2_b32 v49, v39, v40 offset0:138 offset1:203
	v_cvt_pk_bf16_f32 v39, v42, v44
	v_cvt_pk_bf16_f32 v40, v45, v46
	ds_write2_b32 v41, v31, v32 offset0:142 offset1:207
	v_cvt_pk_bf16_f32 v31, v34, v36
	v_cvt_pk_bf16_f32 v32, v37, v38
	ds_write2_b32 v33, v23, v24 offset0:146 offset1:211
	v_cvt_pk_bf16_f32 v23, v26, v28
	v_cvt_pk_bf16_f32 v24, v29, v30
	ds_write2_b32 v25, v15, v16 offset0:150 offset1:215
	v_cvt_pk_bf16_f32 v15, v18, v20
	v_cvt_pk_bf16_f32 v16, v21, v22
	ds_write2_b32 v17, v7, v8 offset0:154 offset1:219
	ds_write2_b32 v57, v55, v56 offset0:4 offset1:69
	ds_write2_b32 v49, v47, v48 offset0:8 offset1:73
	ds_write2_b32 v41, v39, v40 offset0:12 offset1:77
	ds_write2_b32 v33, v31, v32 offset0:16 offset1:81
	ds_write2_b32 v25, v23, v24 offset0:20 offset1:85
	ds_write2_b32 v17, v15, v16 offset0:24 offset1:89
	s_waitcnt vmcnt(6)
	v_cvt_pk_bf16_f32 v7, v10, v12
	s_waitcnt vmcnt(4)
	v_cvt_pk_bf16_f32 v8, v13, v14
	ds_write2_b32 v9, v7, v8 offset0:28 offset1:93
	s_waitcnt vmcnt(2)
	v_cvt_pk_bf16_f32 v0, v0, v1
	s_waitcnt vmcnt(0)
	v_cvt_pk_bf16_f32 v1, v4, v5
	ds_write2_b32 v9, v0, v1 offset0:158 offset1:223
	s_waitcnt lgkmcnt(0)
	ds_read2_b32 v[8:9], v6 offset0:65 offset1:73
	ds_read2_b32 v[16:17], v6 offset0:130 offset1:138
	ds_read2_b32 v[10:11], v6 offset0:195 offset1:203
	ds_read2_b32 v[18:19], v6 offset1:8
	v_add_u32_e32 v4, s6, v74
	v_ashrrev_i32_e32 v5, 31, v4
	v_lshl_add_u64 v[0:1], s[8:9], 1, v[2:3]
	v_lshlrev_b64 v[20:21], 9, v[4:5]
	s_waitcnt lgkmcnt(0)
	v_mov_b32_e32 v12, v18
	v_mov_b32_e32 v13, v8
	v_mov_b32_e32 v14, v16
	v_mov_b32_e32 v15, v10
	v_lshl_add_u64 v[20:21], v[0:1], 0, v[20:21]
	global_store_dwordx4 v[20:21], v[12:15], off
	v_mov_b32_e32 v8, v19
	v_mov_b32_e32 v10, v17
	v_add_u32_e32 v12, 8, v4
	v_ashrrev_i32_e32 v13, 31, v12
	v_lshlrev_b64 v[12:13], 9, v[12:13]
	v_lshl_add_u64 v[12:13], v[0:1], 0, v[12:13]
	global_store_dwordx4 v[12:13], v[8:11], off
	ds_read2_b32 v[16:17], v6 offset0:16 offset1:24
	ds_read2_b32 v[8:9], v6 offset0:81 offset1:89
	ds_read2_b32 v[18:19], v6 offset0:146 offset1:154
	ds_read2_b32 v[10:11], v6 offset0:211 offset1:219
	v_add_u32_e32 v20, 16, v4
	v_ashrrev_i32_e32 v21, 31, v20
	v_lshlrev_b64 v[20:21], 9, v[20:21]
	s_waitcnt lgkmcnt(3)
	v_mov_b32_e32 v12, v16
	s_waitcnt lgkmcnt(2)
	v_mov_b32_e32 v13, v8
	s_waitcnt lgkmcnt(1)
	v_mov_b32_e32 v14, v18
	s_waitcnt lgkmcnt(0)
	v_mov_b32_e32 v15, v10
	v_lshl_add_u64 v[20:21], v[0:1], 0, v[20:21]
	global_store_dwordx4 v[20:21], v[12:15], off
	v_mov_b32_e32 v8, v17
	v_mov_b32_e32 v10, v19
	v_add_u32_e32 v12, 24, v4
	v_ashrrev_i32_e32 v13, 31, v12
	v_lshlrev_b64 v[12:13], 9, v[12:13]
	v_lshl_add_u64 v[12:13], v[0:1], 0, v[12:13]
	global_store_dwordx4 v[12:13], v[8:11], off
	ds_read2_b32 v[8:9], v6 offset0:97 offset1:105
	ds_read2_b32 v[16:17], v6 offset0:162 offset1:170
	ds_read2_b32 v[10:11], v6 offset0:227 offset1:235
	ds_read2_b32 v[18:19], v6 offset0:32 offset1:40
	v_add_u32_e32 v20, 32, v4
	v_ashrrev_i32_e32 v21, 31, v20
	v_lshlrev_b64 v[20:21], 9, v[20:21]
	s_waitcnt lgkmcnt(3)
	v_mov_b32_e32 v13, v8
	s_waitcnt lgkmcnt(0)
	v_mov_b32_e32 v12, v18
	v_mov_b32_e32 v14, v16
	v_mov_b32_e32 v15, v10
	v_lshl_add_u64 v[20:21], v[0:1], 0, v[20:21]
	global_store_dwordx4 v[20:21], v[12:15], off
	v_mov_b32_e32 v8, v19
	v_mov_b32_e32 v10, v17
	v_add_u32_e32 v12, 40, v4
	v_ashrrev_i32_e32 v13, 31, v12
	v_lshlrev_b64 v[12:13], 9, v[12:13]
	v_lshl_add_u64 v[12:13], v[0:1], 0, v[12:13]
	global_store_dwordx4 v[12:13], v[8:11], off
	ds_read2_b32 v[16:17], v6 offset0:48 offset1:56
	ds_read2_b32 v[8:9], v6 offset0:113 offset1:121
	ds_read2_b32 v[18:19], v6 offset0:178 offset1:186
	ds_read2_b32 v[10:11], v6 offset0:243 offset1:251
	v_add_u32_e32 v20, 48, v4
	v_add_u32_e32 v4, 56, v4
	v_ashrrev_i32_e32 v21, 31, v20
	v_ashrrev_i32_e32 v5, 31, v4
	v_lshlrev_b64 v[20:21], 9, v[20:21]
	v_lshlrev_b64 v[4:5], 9, v[4:5]
	s_waitcnt lgkmcnt(3)
	v_mov_b32_e32 v12, v16
	s_waitcnt lgkmcnt(2)
	v_mov_b32_e32 v13, v8
	s_waitcnt lgkmcnt(1)
	v_mov_b32_e32 v14, v18
	s_waitcnt lgkmcnt(0)
	v_mov_b32_e32 v15, v10
	v_lshl_add_u64 v[20:21], v[0:1], 0, v[20:21]
	v_mov_b32_e32 v8, v17
	v_mov_b32_e32 v10, v19
	v_lshl_add_u64 v[0:1], v[0:1], 0, v[4:5]
	global_store_dwordx4 v[20:21], v[12:15], off
	global_store_dwordx4 v[0:1], v[8:11], off
	s_waitcnt lgkmcnt(0)
	s_add_i32 s6, s16, 0x700
	s_cmpk_lt_i32 s16, 0xf940
	s_mov_b32 s16, s6
	s_cbranch_scc1 .LBB0_2460

; #define XBAR() do { XcdBarrier bar_; bar_.bar = (unsigned*)(PWS + WS_BAR); bar_.x = xb_xcc_id(); bar_.st = (volatile LAS unsigned*)(L + 131072 + 64); int t_ = tid_of(wv); asm volatile("" : "+v"(t_)); xcd_barrier(bar_, t_ == 0); } while (0)
; __device__ __forceinline__ void xcd_barrier(const XcdBarrier& b, bool t0) {
;     asm volatile("s_waitcnt vmcnt(0)" ::: "memory");
;     __syncthreads();
;     if (t0) {
;         unsigned* bar = b.bar;
;         __builtin_amdgcn_s_waitcnt(0);
;         unsigned nloc = b.st[0], nx = b.st[1];
;         if (nloc == 0u) { xcd_barrier_complete(bar, b.x, nloc, nx); b.st[0] = nloc; b.st[1] = nx; }
; __global__ void __launch_bounds__(512, 2) hymba_fwd(Params p) {
;     ...
;         if (layer + 1 < NLAYER) XBAR();
.LBB0_2462:
	v_mov_b32_e32 v0, v161
	v_mov_b32_e32 v2, v183
	v_add_u32_e32 v0, 0, v0
	v_add_u32_e32 v0, 0x201c0, v0
	s_waitcnt lgkmcnt(0)
	s_nop 0
	s_getreg_b32 s8, hwreg(HW_REG_XCC_ID, 0, 4)
	s_waitcnt vmcnt(0)
	s_waitcnt lgkmcnt(0)
	v_readlane_b32 s7, v251, 49
	v_readlane_b32 s6, v251, 48
	v_cmp_eq_u32_e32 vcc, 0, v2
	s_barrier
	s_and_saveexec_b64 s[4:5], vcc
	s_cbranch_execnz .LBB0_2463
	s_getpc_b64 s[98:99]

; __global__ void __launch_bounds__(512, 2) hymba_fwd(Params p) {
	.amdhsa_kernel _Z9hymba_fwd6Params
		.amdhsa_group_segment_fixed_size 0
		.amdhsa_private_segment_fixed_size 0
		.amdhsa_kernarg_size 464
		.amdhsa_user_sgpr_count 2
		.amdhsa_user_sgpr_dispatch_ptr 0
		.amdhsa_user_sgpr_queue_ptr 0
		.amdhsa_user_sgpr_kernarg_segment_ptr 1
		.amdhsa_user_sgpr_dispatch_id 0
		.amdhsa_user_sgpr_kernarg_preload_length 0
		.amdhsa_user_sgpr_kernarg_preload_offset 0
		.amdhsa_user_sgpr_private_segment_size 0
		.amdhsa_uses_dynamic_stack 0
		.amdhsa_enable_private_segment 0
		.amdhsa_system_sgpr_workgroup_id_x 1
		.amdhsa_system_sgpr_workgroup_id_y 0
		.amdhsa_system_sgpr_workgroup_id_z 0
		.amdhsa_system_sgpr_workgroup_info 0
		.amdhsa_system_vgpr_workitem_id 2
		.amdhsa_next_free_vgpr 256
		.amdhsa_next_free_sgpr 100
		.amdhsa_accum_offset 256
		.amdhsa_reserve_vcc 1
		.amdhsa_float_round_mode_32 0
		.amdhsa_float_round_mode_16_64 0
		.amdhsa_float_denorm_mode_32 3
		.amdhsa_float_denorm_mode_16_64 3
		.amdhsa_dx10_clamp 1
		.amdhsa_ieee_mode 1
		.amdhsa_fp16_overflow 0
		.amdhsa_tg_split 0
		.amdhsa_exception_fp_ieee_invalid_op 0
		.amdhsa_exception_fp_denorm_src 0
		.amdhsa_exception_fp_ieee_div_zero 0
		.amdhsa_exception_fp_ieee_overflow 0
		.amdhsa_exception_fp_ieee_underflow 0
		.amdhsa_exception_fp_ieee_inexact 0
		.amdhsa_exception_int_div_zero 0
	.end_amdhsa_kernel

; __global__ void __launch_bounds__(512, 2) hymba_fwd(Params p) {
amdhsa.kernels:
  - .agpr_count:     0
    .args:
      - .offset:         0
        .size:           208
        .value_kind:     by_value
      - .offset:         208
        .size:           4
        .value_kind:     hidden_block_count_x
      - .offset:         212
        .size:           4
        .value_kind:     hidden_block_count_y
      - .offset:         216
        .size:           4
        .value_kind:     hidden_block_count_z
      - .offset:         220
        .size:           2
        .value_kind:     hidden_group_size_x
      - .offset:         222
        .size:           2
        .value_kind:     hidden_group_size_y
      - .offset:         224
        .size:           2
        .value_kind:     hidden_group_size_z
      - .offset:         226
        .size:           2
        .value_kind:     hidden_remainder_x
      - .offset:         228
        .size:           2
        .value_kind:     hidden_remainder_y
      - .offset:         230
        .size:           2
        .value_kind:     hidden_remainder_z
      - .offset:         248
        .size:           8
        .value_kind:     hidden_global_offset_x
      - .offset:         256
        .size:           8
        .value_kind:     hidden_global_offset_y
      - .offset:         264
        .size:           8
        .value_kind:     hidden_global_offset_z
      - .offset:         272
        .size:           2
        .value_kind:     hidden_grid_dims
      - .offset:         296
        .size:           8
        .value_kind:     hidden_multigrid_sync_arg
      - .offset:         328
        .size:           4
        .value_kind:     hidden_dynamic_lds_size
    .group_segment_fixed_size: 0
    .kernarg_segment_align: 8
    .kernarg_segment_size: 464
    .language:       OpenCL C
    .language_version:
      - 2
      - 0
    .max_flat_workgroup_size: 512
    .name:           _Z9hymba_fwd6Params
    .private_segment_fixed_size: 0
    .sgpr_count:     106
    .sgpr_spill_count: 53
    .symbol:         _Z9hymba_fwd6Params.kd
    .uniform_work_group_size: 1
    .uses_dynamic_stack: false
    .vgpr_count:     256
    .vgpr_spill_count: 0
    .wavefront_size: 64
